# all flat_load/flat_store (global memory only) converted to global_load/global_store: VMEM no longer counts on lgkmcnt, LDS waits stop covering prefetches
# speedup vs baseline: 1.0079x; 1.0079x over previous
; __device__ __forceinline__ unsigned xb_ld(unsigned* p)              { return __hip_atomic_load(p, __ATOMIC_RELAXED, __HIP_MEMORY_SCOPE_AGENT); }
; __device__ __forceinline__ void xcd_barrier_complete(unsigned* bar, unsigned x, unsigned& nloc, unsigned& nx) {
;     const unsigned G = gridDim.x * gridDim.y * gridDim.z;
;     unsigned sum, cnt, mine, sp = 0u;
;     for (;;) {
;         sum = 0u; cnt = 0u; mine = 0u;
; #pragma unroll
;         for (unsigned j = 0; j < 16; ++j) { const unsigned c = xb_ld(&bar[XB_XCNT(j)]); sum += c; cnt += (c > 0u) ? 1u : 0u; mine = (j == x) ? c : mine; }
;         if (sum == G) break;
;         __builtin_amdgcn_s_sleep(1);
;         if ((++sp & 255u) == 0u) { if (xb_ld(&bar[XB_TMO])) break; if (sp > XB_SPIN_CAP) { atomicAdd(&bar[XB_TMO], 1u); break; } }
;     }
;     nloc = mine > 0u ? mine : 1u; nx = cnt > 0u ? cnt : 1u;
.LBB0_80:
	global_load_dword v25, v[0:1], off offset:1024 sc1
	global_load_dword v10, v[0:1], off offset:1280 sc1
	global_load_dword v11, v[0:1], off offset:1536 sc1
	global_load_dword v12, v[0:1], off offset:1792 sc1
	global_load_dword v13, v[0:1], off offset:2048 sc1
	global_load_dword v14, v[0:1], off offset:2304 sc1
	global_load_dword v15, v[0:1], off offset:2560 sc1
	global_load_dword v16, v[0:1], off offset:2816 sc1
	global_load_dword v17, v[0:1], off offset:3072 sc1
	global_load_dword v18, v[0:1], off offset:3328 sc1
	global_load_dword v19, v[0:1], off offset:3584 sc1
	global_load_dword v20, v[0:1], off offset:3840 sc1
	global_load_dword v21, v[2:3], off sc1
	global_load_dword v22, v[4:5], off sc1
	global_load_dword v23, v[6:7], off sc1
	global_load_dword v24, v[8:9], off sc1
	s_or_b64 s[8:9], s[8:9], exec
	s_or_b64 s[6:7], s[6:7], exec
	s_waitcnt vmcnt(0) lgkmcnt(0)
	v_add_u32_e32 v26, v10, v25
	v_add_u32_e32 v26, v26, v11
	v_add_u32_e32 v26, v26, v12
	v_add_u32_e32 v26, v26, v13
	v_add_u32_e32 v26, v26, v14
	v_add_u32_e32 v26, v26, v15
	v_add_u32_e32 v26, v26, v16
	v_add_u32_e32 v26, v26, v17
	v_add_u32_e32 v26, v26, v18
	v_add_u32_e32 v26, v26, v19
	v_add_u32_e32 v26, v26, v20
	v_add_u32_e32 v26, v26, v21
	v_add_u32_e32 v26, v26, v22
	v_add_u32_e32 v26, v26, v23
	v_add_u32_e32 v26, v26, v24
	v_cmp_ne_u32_e32 vcc, s20, v26
	s_and_saveexec_b64 s[10:11], vcc
	s_cbranch_execz .LBB0_79
	s_and_b32 s14, s21, 0xff
	s_mov_b64 s[12:13], -1
	s_cmp_eq_u32 s14, 0
	s_mov_b64 s[16:17], -1
	s_mov_b64 s[14:15], -1
	s_sleep 1
	s_cbranch_scc1 .LBB0_83
	s_and_saveexec_b64 s[18:19], s[16:17]
	s_cbranch_execz .LBB0_78
	s_branch .LBB0_86
.LBB0_83:
	global_load_dword v26, v[0:1], off offset:512 sc1
	s_mov_b64 s[16:17], 0
	s_waitcnt vmcnt(0) lgkmcnt(0)
	v_cmp_eq_u32_e32 vcc, 0, v26
	s_and_saveexec_b64 s[18:19], vcc
	s_cmp_lt_u32 s21, 0x40001
	s_cselect_b64 s[16:17], -1, 0
	s_xor_b64 s[14:15], exec, -1
	s_and_b64 s[16:17], s[16:17], exec
	s_or_b64 exec, exec, s[18:19]
	s_and_saveexec_b64 s[18:19], s[16:17]
	s_cbranch_execz .LBB0_78

; __device__ __forceinline__ unsigned xb_ld(unsigned* p)              { return __hip_atomic_load(p, __ATOMIC_RELAXED, __HIP_MEMORY_SCOPE_AGENT); }
; __device__ __forceinline__ unsigned xb_add(unsigned* p, unsigned v) { return __hip_atomic_fetch_add(p, v, __ATOMIC_RELAXED, __HIP_MEMORY_SCOPE_AGENT); }
; #define XB_SPIN(cond, bar) do { unsigned _sp = 0; while (cond) { __builtin_amdgcn_s_sleep(1); \
;     if ((++_sp & 255u) == 0u) { if (xb_ld(&(bar)[XB_TMO])) break; if (_sp > XB_SPIN_CAP) { atomicAdd(&(bar)[XB_TMO], 1u); break; } } } } while (0)
; __device__ __forceinline__ void xcd_barrier(const XcdBarrier& b, int tid) {
;     ...
;         const unsigned old = xb_add(&bar[XB_XSUB(bx_)], 1u);
;         const unsigned gen = old / nloc;
;         if (old + 1u == (gen + 1u) * nloc) {
;             __builtin_amdgcn_fence(__ATOMIC_RELEASE, "agent");
;             asm volatile("s_waitcnt vmcnt(0)" ::: "memory");
;             const unsigned og = xb_add(&bar[XB_TOP], 1u);
;             const unsigned tg = og / nx;
;             if (og + 1u == (tg + 1u) * nx) xb_add(&bar[XB_TOPGEN], 1u);
;             else XB_SPIN(xb_ld(&bar[XB_TOPGEN]) == tg, bar);
;             __builtin_amdgcn_fence(__ATOMIC_ACQUIRE, "agent");
;             xb_add(&bar[XB_XGEN(bx_)], 1u);
;             asm volatile("s_waitcnt vmcnt(0)" ::: "memory");
;         } else {
;             XB_SPIN(xb_ld(&bar[XB_XGEN(bx_)]) == gen, bar);
.LBB0_90:
	s_lshl_b32 s24, s33, 6
	s_add_i32 s4, s24, 0x500
	s_mov_b32 s5, 0
	s_lshl_b64 s[0:1], s[4:5], 2
	s_add_u32 s0, s34, s0
	s_addc_u32 s1, s35, s1
	v_mov_b32_e32 v1, 1
	v_mov_b64_e32 v[4:5], s[0:1]
	flat_atomic_add v1, v[4:5], v1 sc0
	v_cvt_f32_u32_e32 v3, v2
	v_sub_u32_e32 v4, 0, v2
	v_rcp_iflag_f32_e32 v3, v3
	s_nop 0
	v_mul_f32_e32 v3, 0x4f7ffffe, v3
	v_cvt_u32_f32_e32 v3, v3
	v_mul_lo_u32 v4, v4, v3
	v_mul_hi_u32 v4, v3, v4
	v_add_u32_e32 v3, v3, v4
	s_waitcnt vmcnt(0) lgkmcnt(0)
	v_mul_hi_u32 v3, v1, v3
	v_mul_lo_u32 v5, v3, v2
	v_add_u32_e32 v4, 1, v1
	v_sub_u32_e32 v1, v1, v5
	v_add_u32_e32 v6, 1, v3
	v_cmp_ge_u32_e32 vcc, v1, v2
	v_sub_u32_e32 v5, v1, v2
	s_nop 0
	v_cndmask_b32_e32 v3, v3, v6, vcc
	v_cndmask_b32_e32 v1, v1, v5, vcc
	v_add_u32_e32 v5, 1, v3
	v_cmp_ge_u32_e32 vcc, v1, v2
	s_nop 1
	v_cndmask_b32_e32 v1, v3, v5, vcc
	v_mad_u64_u32 v[2:3], s[0:1], v2, v1, v[2:3]
	v_cmp_ne_u32_e32 vcc, v4, v2
	s_and_saveexec_b64 s[0:1], vcc
	s_xor_b64 s[0:1], exec, s[0:1]
	s_cbranch_execz .LBB0_103
	s_add_i32 s4, s24, 0x900
	s_lshl_b64 s[4:5], s[4:5], 2
	s_add_u32 s6, s34, s4
	s_addc_u32 s7, s35, s5
	v_mov_b64_e32 v[2:3], s[6:7]
	global_load_dword v0, v[2:3], off sc1
	s_waitcnt vmcnt(0) lgkmcnt(0)
	v_cmp_eq_u32_e32 vcc, v0, v1
	s_and_saveexec_b64 s[4:5], vcc
	s_cbranch_execz .LBB0_102
	s_mov_b32 s22, 1
	s_mov_b64 s[8:9], 0
	s_branch .LBB0_94

; __device__ __forceinline__ unsigned xb_ld(unsigned* p)              { return __hip_atomic_load(p, __ATOMIC_RELAXED, __HIP_MEMORY_SCOPE_AGENT); }
; #define XB_SPIN(cond, bar) do { unsigned _sp = 0; while (cond) { __builtin_amdgcn_s_sleep(1); \
;     if ((++_sp & 255u) == 0u) { if (xb_ld(&(bar)[XB_TMO])) break; if (_sp > XB_SPIN_CAP) { atomicAdd(&(bar)[XB_TMO], 1u); break; } } } } while (0)
; __device__ __forceinline__ void xcd_barrier(const XcdBarrier& b, int tid) {
;     ...
;             XB_SPIN(xb_ld(&bar[XB_XGEN(bx_)]) == gen, bar);
.LBB0_94:
	s_and_b32 s16, s22, 0xff
	s_mov_b64 s[14:15], -1
	s_cmp_lg_u32 s16, 0
	s_mov_b64 s[16:17], -1
	s_sleep 1
	s_cbranch_scc1 .LBB0_98
	v_mov_b64_e32 v[2:3], s[34:35]
	global_load_dword v0, v[2:3], off offset:512 sc1
	s_mov_b64 s[16:17], 0
	s_mov_b64 s[18:19], -1
	s_waitcnt vmcnt(0) lgkmcnt(0)
	v_cmp_eq_u32_e32 vcc, 0, v0
	s_and_saveexec_b64 s[20:21], vcc
	s_cmp_lt_u32 s22, 0x40001
	s_cselect_b64 s[16:17], -1, 0
	s_xor_b64 s[18:19], exec, -1
	s_and_b64 s[16:17], s[16:17], exec
	s_or_b64 exec, exec, s[20:21]
.LBB0_98:
	s_andn2_b64 s[12:13], s[12:13], exec
	s_and_b64 s[18:19], s[18:19], exec
	s_or_b64 s[12:13], s[12:13], s[18:19]
	s_and_saveexec_b64 s[18:19], s[16:17]
	s_cbranch_execz .LBB0_93
	v_mov_b64_e32 v[2:3], s[6:7]
	global_load_dword v0, v[2:3], off sc1
	s_add_i32 s22, s22, 1
	s_or_b64 s[12:13], s[12:13], exec
	s_waitcnt vmcnt(0) lgkmcnt(0)
	v_cmp_ne_u32_e32 vcc, v0, v1
	s_orn2_b64 s[14:15], vcc, exec
	s_branch .LBB0_93

; __device__ __forceinline__ unsigned xb_ld(unsigned* p)              { return __hip_atomic_load(p, __ATOMIC_RELAXED, __HIP_MEMORY_SCOPE_AGENT); }
; __device__ __forceinline__ unsigned xb_add(unsigned* p, unsigned v) { return __hip_atomic_fetch_add(p, v, __ATOMIC_RELAXED, __HIP_MEMORY_SCOPE_AGENT); }
; #define XB_SPIN(cond, bar) do { unsigned _sp = 0; while (cond) { __builtin_amdgcn_s_sleep(1); \
;     if ((++_sp & 255u) == 0u) { if (xb_ld(&(bar)[XB_TMO])) break; if (_sp > XB_SPIN_CAP) { atomicAdd(&(bar)[XB_TMO], 1u); break; } } } } while (0)
; __device__ __forceinline__ void xcd_barrier(const XcdBarrier& b, int tid) {
;     ...
;         if (old + 1u == (gen + 1u) * nloc) {
;             __builtin_amdgcn_fence(__ATOMIC_RELEASE, "agent");
;             asm volatile("s_waitcnt vmcnt(0)" ::: "memory");
;             const unsigned og = xb_add(&bar[XB_TOP], 1u);
;             const unsigned tg = og / nx;
;             if (og + 1u == (tg + 1u) * nx) xb_add(&bar[XB_TOPGEN], 1u);
;             else XB_SPIN(xb_ld(&bar[XB_TOPGEN]) == tg, bar);
.LBB0_103:
	s_andn2_saveexec_b64 s[0:1], s[0:1]
	s_cbranch_execz .LBB0_119
	v_mov_b32_e32 v1, s34
	v_add_co_u32_e32 v2, vcc, 0x3000, v1
	v_mov_b32_e32 v1, s35
	buffer_wbl2 sc1
	s_waitcnt vmcnt(0)
	v_addc_co_u32_e32 v3, vcc, 0, v1, vcc
	v_mov_b32_e32 v1, 1
	flat_atomic_add v1, v[2:3], v1 offset:1024 sc0
	v_cvt_f32_u32_e32 v2, v0
	v_sub_u32_e32 v3, 0, v0
	s_add_u32 s4, s34, 0x3500
	s_addc_u32 s5, s35, 0
	v_rcp_iflag_f32_e32 v2, v2
	s_mov_b64 s[8:9], -1
	v_mul_f32_e32 v2, 0x4f7ffffe, v2
	v_cvt_u32_f32_e32 v2, v2
	v_mul_lo_u32 v3, v3, v2
	v_mul_hi_u32 v3, v2, v3
	v_add_u32_e32 v2, v2, v3
	s_waitcnt vmcnt(0) lgkmcnt(0)
	v_mul_hi_u32 v2, v1, v2
	v_mul_lo_u32 v4, v2, v0
	v_add_u32_e32 v3, 1, v1
	v_sub_u32_e32 v1, v1, v4
	v_add_u32_e32 v5, 1, v2
	v_cmp_ge_u32_e32 vcc, v1, v0
	v_sub_u32_e32 v4, v1, v0
	s_nop 0
	v_cndmask_b32_e32 v2, v2, v5, vcc
	v_cndmask_b32_e32 v1, v1, v4, vcc
	v_add_u32_e32 v4, 1, v2
	v_cmp_ge_u32_e32 vcc, v1, v0
	s_nop 1
	v_cndmask_b32_e32 v2, v2, v4, vcc
	v_mad_u64_u32 v[0:1], s[6:7], v0, v2, v[0:1]
	v_cmp_ne_u32_e32 vcc, v3, v0
	v_mov_b64_e32 v[0:1], s[4:5]
	s_and_saveexec_b64 s[6:7], vcc
	s_cbranch_execz .LBB0_116
	v_mov_b64_e32 v[0:1], s[4:5]
	global_load_dword v0, v[0:1], off sc1
	s_mov_b64 s[12:13], 0
	s_waitcnt vmcnt(0) lgkmcnt(0)
	v_cmp_eq_u32_e32 vcc, v0, v2
	s_and_saveexec_b64 s[10:11], vcc
	s_cbranch_execz .LBB0_115
	s_add_u32 s8, s34, 0x200
	s_addc_u32 s9, s35, 0
	s_mov_b32 s25, 1
	s_branch .LBB0_108

; __device__ __forceinline__ unsigned xb_ld(unsigned* p)              { return __hip_atomic_load(p, __ATOMIC_RELAXED, __HIP_MEMORY_SCOPE_AGENT); }
; #define XB_SPIN(cond, bar) do { unsigned _sp = 0; while (cond) { __builtin_amdgcn_s_sleep(1); \
;     if ((++_sp & 255u) == 0u) { if (xb_ld(&(bar)[XB_TMO])) break; if (_sp > XB_SPIN_CAP) { atomicAdd(&(bar)[XB_TMO], 1u); break; } } } } while (0)
; __device__ __forceinline__ void xcd_barrier(const XcdBarrier& b, int tid) {
;     ...
;             else XB_SPIN(xb_ld(&bar[XB_TOPGEN]) == tg, bar);
.LBB0_110:
	v_mov_b64_e32 v[0:1], s[8:9]
	global_load_dword v0, v[0:1], off sc1
	s_mov_b64 s[18:19], 0
	s_mov_b64 s[16:17], -1
	s_waitcnt vmcnt(0) lgkmcnt(0)
	v_cmp_eq_u32_e32 vcc, 0, v0
	s_and_saveexec_b64 s[20:21], vcc
	s_cmp_lt_u32 s25, 0x40001
	s_cselect_b64 s[18:19], -1, 0
	s_xor_b64 s[16:17], exec, -1
	s_and_b64 s[18:19], s[18:19], exec
	s_or_b64 exec, exec, s[20:21]
	s_mov_b64 s[20:21], -1
	s_and_saveexec_b64 s[22:23], s[18:19]
	s_cbranch_execz .LBB0_107
.LBB0_113:
	v_mov_b64_e32 v[0:1], s[4:5]
	global_load_dword v0, v[0:1], off sc1
	s_add_i32 s25, s25, 1
	s_or_b64 s[16:17], s[16:17], exec
	s_waitcnt vmcnt(0) lgkmcnt(0)
	v_cmp_ne_u32_e32 vcc, v0, v2
	s_orn2_b64 s[20:21], vcc, exec
	s_branch .LBB0_107

;     __device__ __forceinline__ void operator()(const f32x4 (&acc)[2][2][4][2], const Unit& u, int wr, int wc, int fr, int fq) const {
;         const int row0 = u.pm * BM + wr * 64 + fr, col0 = u.pn * BM + wc * 32 + 4 * fq;
;         f32x4 bv[2][2];
; #pragma unroll
;         for (int bj = 0; bj < 2; ++bj)
; #pragma unroll
;             for (int n = 0; n < 2; ++n) bv[bj][n] = *(const f32x4*)(bias + col0 + bj * HALF + n * 16);
; #pragma unroll
;         for (int ai = 0; ai < 2; ++ai)
; #pragma unroll
;             for (int m = 0; m < 4; ++m) { float* rowp = C + (size_t)(row0 + ai * HALF + m * 16) * ldc + col0;
; #pragma unroll
;                 for (int bj = 0; bj < 2; ++bj)
; #pragma unroll
;                     for (int n = 0; n < 2; ++n) *(f32x4*)(rowp + bj * HALF + n * 16) = acc[ai][bj][m][n] + bv[bj][n]; }
;     }
.LBB0_132:
	v_lshl_or_b32 v128, s44, 8, v162
	v_ashrrev_i32_e32 v129, 31, v128
	v_lshlrev_b64 v[156:157], 2, v[128:129]
	v_lshl_add_u64 v[128:129], s[56:57], 0, v[156:157]
	global_load_dwordx4 v[140:143], v[128:129], off
	global_load_dwordx4 v[136:139], v[128:129], off offset:64
	global_load_dwordx4 v[132:135], v[128:129], off offset:512
	s_nop 0
	global_load_dwordx4 v[128:131], v[128:129], off offset:576
	v_lshl_add_u32 v176, s18, 8, v160
	v_mov_b64_e32 v[158:159], s[4:5]
	v_add_u32_e32 v174, 0x80, v176
	v_mad_i64_i32 v[166:167], s[20:21], v176, s39, v[158:159]
	v_or_b32_e32 v168, 16, v176
	v_or_b32_e32 v170, 32, v176
	v_or_b32_e32 v172, 48, v176
	v_mad_i64_i32 v[174:175], s[20:21], v174, s39, v[158:159]
	v_mad_i64_i32 v[168:169], s[20:21], v168, s39, v[158:159]
	v_mad_i64_i32 v[170:171], s[20:21], v170, s39, v[158:159]
	v_mad_i64_i32 v[172:173], s[20:21], v172, s39, v[158:159]
	v_lshl_add_u64 v[166:167], v[166:167], 0, v[156:157]
	v_lshl_add_u64 v[174:175], v[174:175], 0, v[156:157]
	v_lshl_add_u64 v[168:169], v[168:169], 0, v[156:157]
	v_lshl_add_u64 v[170:171], v[170:171], 0, v[156:157]
	v_lshl_add_u64 v[172:173], v[172:173], 0, v[156:157]
	s_andn2_b64 vcc, exec, s[0:1]
	s_mov_b64 s[0:1], -1
	s_waitcnt vmcnt(0)
	v_pk_add_f32 v[126:127], v[126:127], v[142:143]
	v_pk_add_f32 v[124:125], v[124:125], v[140:141]
	v_pk_add_f32 v[122:123], v[122:123], v[138:139]
	v_pk_add_f32 v[42:43], v[42:43], v[130:131]
	v_pk_add_f32 v[40:41], v[40:41], v[128:129]
	v_pk_add_f32 v[120:121], v[120:121], v[136:137]
	v_pk_add_f32 v[106:107], v[106:107], v[134:135]
	v_pk_add_f32 v[104:105], v[104:105], v[132:133]
	v_pk_add_f32 v[98:99], v[98:99], v[130:131]
	v_pk_add_f32 v[96:97], v[96:97], v[128:129]
	v_pk_add_f32 v[118:119], v[118:119], v[142:143]
	v_pk_add_f32 v[116:117], v[116:117], v[140:141]
	v_pk_add_f32 v[114:115], v[114:115], v[138:139]
	v_pk_add_f32 v[112:113], v[112:113], v[136:137]
	v_pk_add_f32 v[90:91], v[90:91], v[134:135]
	v_pk_add_f32 v[88:89], v[88:89], v[132:133]
	v_pk_add_f32 v[82:83], v[82:83], v[130:131]
	v_pk_add_f32 v[80:81], v[80:81], v[128:129]
	v_pk_add_f32 v[110:111], v[110:111], v[142:143]
	v_pk_add_f32 v[108:109], v[108:109], v[140:141]
	v_pk_add_f32 v[102:103], v[102:103], v[138:139]
	v_pk_add_f32 v[100:101], v[100:101], v[136:137]
	v_pk_add_f32 v[78:79], v[78:79], v[134:135]
	v_pk_add_f32 v[76:77], v[76:77], v[132:133]
	v_pk_add_f32 v[74:75], v[74:75], v[130:131]
	v_pk_add_f32 v[72:73], v[72:73], v[128:129]
	v_pk_add_f32 v[94:95], v[94:95], v[142:143]
	v_pk_add_f32 v[92:93], v[92:93], v[140:141]
	v_pk_add_f32 v[86:87], v[86:87], v[138:139]
	v_pk_add_f32 v[84:85], v[84:85], v[136:137]
	v_pk_add_f32 v[70:71], v[70:71], v[134:135]
	v_pk_add_f32 v[68:69], v[68:69], v[132:133]
	v_pk_add_f32 v[66:67], v[66:67], v[130:131]
	v_pk_add_f32 v[64:65], v[64:65], v[128:129]
	v_pk_add_f32 v[62:63], v[62:63], v[142:143]
	v_pk_add_f32 v[60:61], v[60:61], v[140:141]
	v_pk_add_f32 v[58:59], v[58:59], v[138:139]
	v_pk_add_f32 v[56:57], v[56:57], v[136:137]
	v_pk_add_f32 v[54:55], v[54:55], v[134:135]
	v_pk_add_f32 v[52:53], v[52:53], v[132:133]
	global_store_dwordx4 v[166:167], v[124:127], off
	global_store_dwordx4 v[166:167], v[120:123], off offset:64
	global_store_dwordx4 v[166:167], v[104:107], off offset:512
	global_store_dwordx4 v[166:167], v[96:99], off offset:576
	global_store_dwordx4 v[168:169], v[116:119], off
	global_store_dwordx4 v[168:169], v[112:115], off offset:64
	global_store_dwordx4 v[168:169], v[88:91], off offset:512
	global_store_dwordx4 v[168:169], v[80:83], off offset:576
	global_store_dwordx4 v[170:171], v[108:111], off
	global_store_dwordx4 v[170:171], v[100:103], off offset:64
	global_store_dwordx4 v[170:171], v[76:79], off offset:512
	global_store_dwordx4 v[170:171], v[72:75], off offset:576
	global_store_dwordx4 v[172:173], v[92:95], off
	global_store_dwordx4 v[172:173], v[84:87], off offset:64
	global_store_dwordx4 v[172:173], v[68:71], off offset:512
	global_store_dwordx4 v[172:173], v[64:67], off offset:576
	global_store_dwordx4 v[174:175], v[60:63], off
	global_store_dwordx4 v[174:175], v[56:59], off offset:64
	global_store_dwordx4 v[174:175], v[52:55], off offset:512
	global_store_dwordx4 v[174:175], v[40:43], off offset:576
	v_pk_add_f32 v[26:27], v[26:27], v[130:131]
	v_pk_add_f32 v[24:25], v[24:25], v[128:129]
	v_add_u32_e32 v40, 0x90, v176
	v_mad_i64_i32 v[40:41], s[20:21], v40, s39, v[158:159]
	v_lshl_add_u64 v[52:53], v[40:41], 0, v[156:157]
	global_store_dwordx4 v[52:53], v[24:27], off offset:576
	v_pk_add_f32 v[34:35], v[34:35], v[134:135]
	v_pk_add_f32 v[32:33], v[32:33], v[132:133]
	v_add_u32_e32 v24, 0xa0, v176
	v_mad_i64_i32 v[24:25], s[20:21], v24, s39, v[158:159]
	global_store_dwordx4 v[52:53], v[32:35], off offset:512
	v_pk_add_f32 v[10:11], v[10:11], v[130:131]
	v_pk_add_f32 v[8:9], v[8:9], v[128:129]
	v_lshl_add_u64 v[32:33], v[24:25], 0, v[156:157]
	global_store_dwordx4 v[32:33], v[8:11], off offset:576
	v_pk_add_f32 v[18:19], v[18:19], v[134:135]
	v_pk_add_f32 v[16:17], v[16:17], v[132:133]
	v_add_u32_e32 v8, 0xb0, v176
	v_mad_i64_i32 v[8:9], s[20:21], v8, s39, v[158:159]
	v_pk_add_f32 v[42:43], v[50:51], v[142:143]
	v_pk_add_f32 v[40:41], v[48:49], v[140:141]
	v_pk_add_f32 v[26:27], v[38:39], v[142:143]
	v_pk_add_f32 v[24:25], v[36:37], v[140:141]
	global_store_dwordx4 v[32:33], v[16:19], off offset:512
	v_pk_add_f32 v[10:11], v[22:23], v[142:143]
	global_store_dwordx4 v[52:53], v[40:43], off
	v_lshl_add_u64 v[16:17], v[8:9], 0, v[156:157]
	v_pk_add_f32 v[8:9], v[20:21], v[140:141]
	v_pk_add_f32 v[42:43], v[46:47], v[138:139]
	v_pk_add_f32 v[40:41], v[44:45], v[136:137]
	global_store_dwordx4 v[32:33], v[24:27], off
	global_store_dwordx4 v[16:17], v[8:11], off
	v_pk_add_f32 v[6:7], v[6:7], v[134:135]
	v_pk_add_f32 v[26:27], v[30:31], v[138:139]
	v_pk_add_f32 v[24:25], v[28:29], v[136:137]
	v_pk_add_f32 v[10:11], v[14:15], v[138:139]
	v_pk_add_f32 v[8:9], v[12:13], v[136:137]
	v_pk_add_f32 v[4:5], v[4:5], v[132:133]
	v_pk_add_f32 v[2:3], v[2:3], v[130:131]
	v_pk_add_f32 v[0:1], v[0:1], v[128:129]
	global_store_dwordx4 v[52:53], v[40:43], off offset:64
	global_store_dwordx4 v[32:33], v[24:27], off offset:64
	global_store_dwordx4 v[16:17], v[8:11], off offset:64
	global_store_dwordx4 v[16:17], v[4:7], off offset:512
	global_store_dwordx4 v[16:17], v[0:3], off offset:576
	s_cbranch_vccnz .LBB0_125
	s_andn2_b64 vcc, exec, s[2:3]
	s_cbranch_vccnz .LBB0_124
	s_barrier
	s_branch .LBB0_124

; __device__ __forceinline__ unsigned xb_ld(unsigned* p)              { return __hip_atomic_load(p, __ATOMIC_RELAXED, __HIP_MEMORY_SCOPE_AGENT); }
; __device__ __forceinline__ unsigned xb_add(unsigned* p, unsigned v) { return __hip_atomic_fetch_add(p, v, __ATOMIC_RELAXED, __HIP_MEMORY_SCOPE_AGENT); }
; #define XB_SPIN(cond, bar) do { unsigned _sp = 0; while (cond) { __builtin_amdgcn_s_sleep(1); \
;     if ((++_sp & 255u) == 0u) { if (xb_ld(&(bar)[XB_TMO])) break; if (_sp > XB_SPIN_CAP) { atomicAdd(&(bar)[XB_TMO], 1u); break; } } } } while (0)
; __device__ __forceinline__ void xcd_barrier(const XcdBarrier& b, int tid) {
;     ...
;         const unsigned old = xb_add(&bar[XB_XSUB(bx_)], 1u);
;         const unsigned gen = old / nloc;
;         if (old + 1u == (gen + 1u) * nloc) {
;             __builtin_amdgcn_fence(__ATOMIC_RELEASE, "agent");
;             asm volatile("s_waitcnt vmcnt(0)" ::: "memory");
;             const unsigned og = xb_add(&bar[XB_TOP], 1u);
;             const unsigned tg = og / nx;
;             if (og + 1u == (tg + 1u) * nx) xb_add(&bar[XB_TOPGEN], 1u);
;             else XB_SPIN(xb_ld(&bar[XB_TOPGEN]) == tg, bar);
;             __builtin_amdgcn_fence(__ATOMIC_ACQUIRE, "agent");
;             xb_add(&bar[XB_XGEN(bx_)], 1u);
;             asm volatile("s_waitcnt vmcnt(0)" ::: "memory");
;         } else {
;             XB_SPIN(xb_ld(&bar[XB_XGEN(bx_)]) == gen, bar);
.LBB0_151:
	s_lshl_b32 s22, s33, 6
	s_add_i32 s4, s22, 0x500
	s_mov_b32 s5, 0
	s_lshl_b64 s[0:1], s[4:5], 2
	s_add_u32 s0, s34, s0
	s_addc_u32 s1, s35, s1
	v_mov_b32_e32 v1, 1
	v_mov_b64_e32 v[4:5], s[0:1]
	flat_atomic_add v1, v[4:5], v1 sc0
	v_cvt_f32_u32_e32 v3, v2
	v_sub_u32_e32 v4, 0, v2
	v_rcp_iflag_f32_e32 v3, v3
	s_nop 0
	v_mul_f32_e32 v3, 0x4f7ffffe, v3
	v_cvt_u32_f32_e32 v3, v3
	v_mul_lo_u32 v4, v4, v3
	v_mul_hi_u32 v4, v3, v4
	v_add_u32_e32 v3, v3, v4
	s_waitcnt vmcnt(0) lgkmcnt(0)
	v_mul_hi_u32 v3, v1, v3
	v_mul_lo_u32 v5, v3, v2
	v_add_u32_e32 v4, 1, v1
	v_sub_u32_e32 v1, v1, v5
	v_add_u32_e32 v6, 1, v3
	v_cmp_ge_u32_e32 vcc, v1, v2
	v_sub_u32_e32 v5, v1, v2
	s_nop 0
	v_cndmask_b32_e32 v3, v3, v6, vcc
	v_cndmask_b32_e32 v1, v1, v5, vcc
	v_add_u32_e32 v5, 1, v3
	v_cmp_ge_u32_e32 vcc, v1, v2
	s_nop 1
	v_cndmask_b32_e32 v1, v3, v5, vcc
	v_mad_u64_u32 v[2:3], s[0:1], v2, v1, v[2:3]
	v_cmp_ne_u32_e32 vcc, v4, v2
	s_and_saveexec_b64 s[0:1], vcc
	s_xor_b64 s[0:1], exec, s[0:1]
	s_cbranch_execz .LBB0_164
	s_add_i32 s4, s22, 0x900
	s_lshl_b64 s[4:5], s[4:5], 2
	s_add_u32 s6, s34, s4
	s_addc_u32 s7, s35, s5
	v_mov_b64_e32 v[2:3], s[6:7]
	global_load_dword v0, v[2:3], off sc1
	s_waitcnt vmcnt(0) lgkmcnt(0)
	v_cmp_eq_u32_e32 vcc, v0, v1
	s_and_saveexec_b64 s[4:5], vcc
	s_cbranch_execz .LBB0_163
	s_mov_b32 s23, 1
	s_mov_b64 s[8:9], 0
	s_branch .LBB0_155

; __device__ __forceinline__ unsigned xb_ld(unsigned* p)              { return __hip_atomic_load(p, __ATOMIC_RELAXED, __HIP_MEMORY_SCOPE_AGENT); }
; #define XB_SPIN(cond, bar) do { unsigned _sp = 0; while (cond) { __builtin_amdgcn_s_sleep(1); \
;     if ((++_sp & 255u) == 0u) { if (xb_ld(&(bar)[XB_TMO])) break; if (_sp > XB_SPIN_CAP) { atomicAdd(&(bar)[XB_TMO], 1u); break; } } } } while (0)
; __device__ __forceinline__ void xcd_barrier(const XcdBarrier& b, int tid) {
;     ...
;             XB_SPIN(xb_ld(&bar[XB_XGEN(bx_)]) == gen, bar);
.LBB0_155:
	s_and_b32 s16, s23, 0xff
	s_mov_b64 s[14:15], -1
	s_cmp_lg_u32 s16, 0
	s_mov_b64 s[16:17], -1
	s_sleep 1
	s_cbranch_scc1 .LBB0_159
	v_mov_b64_e32 v[2:3], s[34:35]
	global_load_dword v0, v[2:3], off offset:512 sc1
	s_mov_b64 s[16:17], 0
	s_mov_b64 s[18:19], -1
	s_waitcnt vmcnt(0) lgkmcnt(0)
	v_cmp_eq_u32_e32 vcc, 0, v0
	s_and_saveexec_b64 s[20:21], vcc
	s_cmp_lt_u32 s23, 0x40001
	s_cselect_b64 s[16:17], -1, 0
	s_xor_b64 s[18:19], exec, -1
	s_and_b64 s[16:17], s[16:17], exec
	s_or_b64 exec, exec, s[20:21]
.LBB0_159:
	s_andn2_b64 s[12:13], s[12:13], exec
	s_and_b64 s[18:19], s[18:19], exec
	s_or_b64 s[12:13], s[12:13], s[18:19]
	s_and_saveexec_b64 s[18:19], s[16:17]
	s_cbranch_execz .LBB0_154
	v_mov_b64_e32 v[2:3], s[6:7]
	global_load_dword v0, v[2:3], off sc1
	s_add_i32 s23, s23, 1
	s_or_b64 s[12:13], s[12:13], exec
	s_waitcnt vmcnt(0) lgkmcnt(0)
	v_cmp_ne_u32_e32 vcc, v0, v1
	s_orn2_b64 s[14:15], vcc, exec
	s_branch .LBB0_154

; __device__ __forceinline__ unsigned xb_ld(unsigned* p)              { return __hip_atomic_load(p, __ATOMIC_RELAXED, __HIP_MEMORY_SCOPE_AGENT); }
; __device__ __forceinline__ unsigned xb_add(unsigned* p, unsigned v) { return __hip_atomic_fetch_add(p, v, __ATOMIC_RELAXED, __HIP_MEMORY_SCOPE_AGENT); }
; #define XB_SPIN(cond, bar) do { unsigned _sp = 0; while (cond) { __builtin_amdgcn_s_sleep(1); \
;     if ((++_sp & 255u) == 0u) { if (xb_ld(&(bar)[XB_TMO])) break; if (_sp > XB_SPIN_CAP) { atomicAdd(&(bar)[XB_TMO], 1u); break; } } } } while (0)
; __device__ __forceinline__ void xcd_barrier(const XcdBarrier& b, int tid) {
;     ...
;         if (old + 1u == (gen + 1u) * nloc) {
;             __builtin_amdgcn_fence(__ATOMIC_RELEASE, "agent");
;             asm volatile("s_waitcnt vmcnt(0)" ::: "memory");
;             const unsigned og = xb_add(&bar[XB_TOP], 1u);
;             const unsigned tg = og / nx;
;             if (og + 1u == (tg + 1u) * nx) xb_add(&bar[XB_TOPGEN], 1u);
;             else XB_SPIN(xb_ld(&bar[XB_TOPGEN]) == tg, bar);
.LBB0_164:
	s_andn2_saveexec_b64 s[0:1], s[0:1]
	s_cbranch_execz .LBB0_180
	v_mov_b32_e32 v1, s34
	v_add_co_u32_e32 v2, vcc, 0x3000, v1
	v_mov_b32_e32 v1, s35
	buffer_wbl2 sc1
	s_waitcnt vmcnt(0)
	v_addc_co_u32_e32 v3, vcc, 0, v1, vcc
	v_mov_b32_e32 v1, 1
	flat_atomic_add v1, v[2:3], v1 offset:1024 sc0
	v_cvt_f32_u32_e32 v2, v0
	v_sub_u32_e32 v3, 0, v0
	s_add_u32 s0, s34, 0x3500
	s_addc_u32 s1, s35, 0
	v_rcp_iflag_f32_e32 v2, v2
	s_mov_b64 s[6:7], -1
	v_mul_f32_e32 v2, 0x4f7ffffe, v2
	v_cvt_u32_f32_e32 v2, v2
	v_mul_lo_u32 v3, v3, v2
	v_mul_hi_u32 v3, v2, v3
	v_add_u32_e32 v2, v2, v3
	s_waitcnt vmcnt(0) lgkmcnt(0)
	v_mul_hi_u32 v2, v1, v2
	v_mul_lo_u32 v4, v2, v0
	v_add_u32_e32 v3, 1, v1
	v_sub_u32_e32 v1, v1, v4
	v_add_u32_e32 v5, 1, v2
	v_cmp_ge_u32_e32 vcc, v1, v0
	v_sub_u32_e32 v4, v1, v0
	s_nop 0
	v_cndmask_b32_e32 v2, v2, v5, vcc
	v_cndmask_b32_e32 v1, v1, v4, vcc
	v_add_u32_e32 v4, 1, v2
	v_cmp_ge_u32_e32 vcc, v1, v0
	s_nop 1
	v_cndmask_b32_e32 v2, v2, v4, vcc
	v_mad_u64_u32 v[0:1], s[4:5], v0, v2, v[0:1]
	v_cmp_ne_u32_e32 vcc, v3, v0
	v_mov_b64_e32 v[0:1], s[0:1]
	s_and_saveexec_b64 s[4:5], vcc
	s_cbranch_execz .LBB0_177
	v_mov_b64_e32 v[0:1], s[0:1]
	global_load_dword v0, v[0:1], off sc1
	s_mov_b64 s[10:11], 0
	s_waitcnt vmcnt(0) lgkmcnt(0)
	v_cmp_eq_u32_e32 vcc, v0, v2
	s_and_saveexec_b64 s[8:9], vcc
	s_cbranch_execz .LBB0_176
	s_add_u32 s6, s34, 0x200
	s_addc_u32 s7, s35, 0
	s_mov_b32 s23, 1
	s_branch .LBB0_169

; __device__ __forceinline__ unsigned xb_ld(unsigned* p)              { return __hip_atomic_load(p, __ATOMIC_RELAXED, __HIP_MEMORY_SCOPE_AGENT); }
; #define XB_SPIN(cond, bar) do { unsigned _sp = 0; while (cond) { __builtin_amdgcn_s_sleep(1); \
;     if ((++_sp & 255u) == 0u) { if (xb_ld(&(bar)[XB_TMO])) break; if (_sp > XB_SPIN_CAP) { atomicAdd(&(bar)[XB_TMO], 1u); break; } } } } while (0)
; __device__ __forceinline__ void xcd_barrier(const XcdBarrier& b, int tid) {
;     ...
;             else XB_SPIN(xb_ld(&bar[XB_TOPGEN]) == tg, bar);
.LBB0_171:
	v_mov_b64_e32 v[0:1], s[6:7]
	global_load_dword v0, v[0:1], off sc1
	s_mov_b64 s[16:17], 0
	s_mov_b64 s[14:15], -1
	s_waitcnt vmcnt(0) lgkmcnt(0)
	v_cmp_eq_u32_e32 vcc, 0, v0
	s_and_saveexec_b64 s[18:19], vcc
	s_cmp_lt_u32 s23, 0x40001
	s_cselect_b64 s[16:17], -1, 0
	s_xor_b64 s[14:15], exec, -1
	s_and_b64 s[16:17], s[16:17], exec
	s_or_b64 exec, exec, s[18:19]
	s_mov_b64 s[18:19], -1
	s_and_saveexec_b64 s[20:21], s[16:17]
	s_cbranch_execz .LBB0_168
.LBB0_174:
	v_mov_b64_e32 v[0:1], s[0:1]
	global_load_dword v0, v[0:1], off sc1
	s_add_i32 s23, s23, 1
	s_or_b64 s[14:15], s[14:15], exec
	s_waitcnt vmcnt(0) lgkmcnt(0)
	v_cmp_ne_u32_e32 vcc, v0, v2
	s_orn2_b64 s[18:19], vcc, exec
	s_branch .LBB0_168

; template <int NR> __device__ __forceinline__ void norm_load(unsigned long long (&raw)[NR][4], const bf16* X, int lane) {
; #pragma unroll
;     for (int r = 0; r < NR; ++r) { const unsigned long long* xr = (const unsigned long long*)(X + (size_t)r * D) + lane;
; #pragma unroll
;         for (int j = 0; j < 4; ++j) raw[r][j] = xr[64 * j]; }
; }
; template <int MODE>
; __device__ __forceinline__ void phase_norm(const float* Xp32, const float* Xs32, bf16* X, bf16* H, const float* nw, const float* mod_sh, const float* mod_sc, int gw, int NGW, int lane) {
;     ...
;     for (int b = gw; b < MP / 8; b += NGW) {
;         const int ci = b >> 8; f32x4 mul[4], sh[4];
;         const size_t ro = (size_t)b * 8 * D;
;         const f32x4* shp = (const f32x4*)(mod_sh + (size_t)ci * MODLD) + lane; const f32x4* scp = (const f32x4*)(mod_sc + (size_t)ci * MODLD) + lane;
;         if constexpr (MODE == 1) {
; #pragma unroll
;             for (int j = 0; j < 4; ++j) { sh[j] = shp[64 * j]; mul[j] = w4[j] * (scp[64 * j] + 1.0f); }
;             norm_rows<MODE, 4>(Xp32 + ro, X + ro, H + ro, nullptr, mul, sh, lane);
;             norm_rows<MODE, 4>(Xp32 + ro + 4 * D, X + ro + 4 * D, H + ro + 4 * D, nullptr, mul, sh, lane);
;         } else {
;             unsigned long long raw[8][4]; norm_load<8>(raw, X + ro, lane); asm volatile("" ::: "memory");
; #pragma unroll
;             for (int j = 0; j < 4; ++j) { sh[j] = shp[64 * j]; mul[j] = w4[j] * (scp[64 * j] + 1.0f); }
;             norm_finish<MODE, 8>(raw, H + ro, nullptr, mul, sh, lane);
.LBB0_186:
	v_add_co_u32_e32 v20, vcc, 0xfbefc200, v38
	s_ashr_i32 s9, s1, 8
	s_nop 0
	v_addc_co_u32_e32 v21, vcc, -1, v39, vcc
	global_load_dwordx2 v[112:113], v[20:21], off
	v_add_co_u32_e32 v20, vcc, 0xfbefc400, v38
	v_mad_i64_i32 v[32:33], s[2:3], s9, v132, v[8:9]
	s_nop 0
	v_addc_co_u32_e32 v21, vcc, -1, v39, vcc
	global_load_dwordx2 v[114:115], v[20:21], off
	v_add_co_u32_e32 v20, vcc, 0xfbefc600, v38
	v_mad_i64_i32 v[52:53], s[2:3], s9, v132, v[36:37]
	s_nop 0
	v_addc_co_u32_e32 v21, vcc, -1, v39, vcc
	global_load_dwordx2 v[116:117], v[20:21], off
	v_add_co_u32_e32 v20, vcc, 0xfbefc800, v38
	s_add_i32 s1, s1, s96
	s_nop 0
	v_addc_co_u32_e32 v21, vcc, -1, v39, vcc
	global_load_dwordx2 v[118:119], v[20:21], off
	v_add_co_u32_e32 v20, vcc, 0xfbefca00, v38
	s_cmpk_gt_i32 s1, 0x7ff
	s_nop 0
	v_addc_co_u32_e32 v21, vcc, -1, v39, vcc
	global_load_dwordx2 v[104:105], v[20:21], off
	v_add_co_u32_e32 v20, vcc, 0xfbefcc00, v38
	s_waitcnt vmcnt(0) lgkmcnt(0)
	v_and_b32_e32 v125, 0xffff0000, v114
	v_addc_co_u32_e32 v21, vcc, -1, v39, vcc
	global_load_dwordx2 v[106:107], v[20:21], off
	v_add_co_u32_e32 v20, vcc, 0xfbefce00, v38
	v_mul_f32_e32 v126, v125, v125
	s_nop 0
	v_addc_co_u32_e32 v21, vcc, -1, v39, vcc
	global_load_dwordx2 v[108:109], v[20:21], off
	v_add_co_u32_e32 v20, vcc, 0xfbefd000, v38
	s_nop 1
	v_addc_co_u32_e32 v21, vcc, -1, v39, vcc
	global_load_dwordx2 v[110:111], v[20:21], off
	v_add_co_u32_e32 v20, vcc, 0xfbefd200, v38
	s_nop 1
	v_addc_co_u32_e32 v21, vcc, -1, v39, vcc
	global_load_dwordx2 v[96:97], v[20:21], off
	v_add_co_u32_e32 v20, vcc, 0xfbefd400, v38
	s_nop 1
	v_addc_co_u32_e32 v21, vcc, -1, v39, vcc
	global_load_dwordx2 v[98:99], v[20:21], off
	v_add_co_u32_e32 v20, vcc, 0xfbefd600, v38
	s_nop 1
	v_addc_co_u32_e32 v21, vcc, -1, v39, vcc
	global_load_dwordx2 v[100:101], v[20:21], off
	v_add_co_u32_e32 v20, vcc, 0xfbefd800, v38
	s_nop 1
	v_addc_co_u32_e32 v21, vcc, -1, v39, vcc
	global_load_dwordx2 v[102:103], v[20:21], off
	v_add_co_u32_e32 v20, vcc, 0xfbefda00, v38
	s_nop 1
	v_addc_co_u32_e32 v21, vcc, -1, v39, vcc
	global_load_dwordx2 v[88:89], v[20:21], off
	v_add_co_u32_e32 v20, vcc, 0xfbefdc00, v38
	s_nop 1
	v_addc_co_u32_e32 v21, vcc, -1, v39, vcc
	global_load_dwordx2 v[90:91], v[20:21], off
	v_add_co_u32_e32 v20, vcc, 0xfbefde00, v38
	s_nop 1
	v_addc_co_u32_e32 v21, vcc, -1, v39, vcc
	global_load_dwordx2 v[92:93], v[20:21], off
	v_add_co_u32_e32 v20, vcc, 0xfbefe000, v38
	s_nop 1
	v_addc_co_u32_e32 v21, vcc, -1, v39, vcc
	global_load_dwordx2 v[94:95], v[20:21], off
	v_add_co_u32_e32 v20, vcc, 0xfbefe200, v38
	s_nop 1
	v_addc_co_u32_e32 v21, vcc, -1, v39, vcc
	global_load_dwordx2 v[80:81], v[20:21], off
	v_add_co_u32_e32 v20, vcc, 0xfbefe400, v38
	s_nop 1
	v_addc_co_u32_e32 v21, vcc, -1, v39, vcc
	global_load_dwordx2 v[82:83], v[20:21], off
	v_add_co_u32_e32 v20, vcc, 0xfbefe600, v38
	s_nop 1
	v_addc_co_u32_e32 v21, vcc, -1, v39, vcc
	global_load_dwordx2 v[84:85], v[20:21], off
	v_add_co_u32_e32 v20, vcc, 0xfbefe800, v38
	s_nop 1
	v_addc_co_u32_e32 v21, vcc, -1, v39, vcc
	global_load_dwordx2 v[86:87], v[20:21], off
	v_add_co_u32_e32 v20, vcc, 0xfbefea00, v38
	s_nop 1
	v_addc_co_u32_e32 v21, vcc, -1, v39, vcc
	global_load_dwordx2 v[72:73], v[20:21], off
	v_add_co_u32_e32 v20, vcc, 0xfbefec00, v38
	s_nop 1
	v_addc_co_u32_e32 v21, vcc, -1, v39, vcc
	global_load_dwordx2 v[74:75], v[20:21], off
	v_add_co_u32_e32 v20, vcc, 0xfbefee00, v38
	s_nop 1
	v_addc_co_u32_e32 v21, vcc, -1, v39, vcc
	global_load_dwordx2 v[76:77], v[20:21], off
	v_add_co_u32_e32 v20, vcc, 0xfbeff000, v38
	s_nop 1
	v_addc_co_u32_e32 v21, vcc, -1, v39, vcc
	global_load_dwordx2 v[78:79], v[20:21], off
	v_add_co_u32_e32 v20, vcc, 0xfbeff200, v38
	s_nop 1
	v_addc_co_u32_e32 v21, vcc, -1, v39, vcc
	global_load_dwordx2 v[64:65], v[20:21], off
	v_add_co_u32_e32 v20, vcc, 0xfbeff400, v38
	s_nop 1
	v_addc_co_u32_e32 v21, vcc, -1, v39, vcc
	global_load_dwordx2 v[66:67], v[20:21], off
	v_add_co_u32_e32 v20, vcc, 0xfbeff600, v38
	s_nop 1
	v_addc_co_u32_e32 v21, vcc, -1, v39, vcc
	global_load_dwordx2 v[68:69], v[20:21], off
	v_add_co_u32_e32 v20, vcc, 0xfbeff800, v38
	s_nop 1
	v_addc_co_u32_e32 v21, vcc, -1, v39, vcc
	global_load_dwordx2 v[70:71], v[20:21], off
	v_add_co_u32_e32 v20, vcc, 0xfbeffa00, v38
	s_nop 1
	v_addc_co_u32_e32 v21, vcc, -1, v39, vcc
	global_load_dwordx2 v[56:57], v[20:21], off
	v_add_co_u32_e32 v20, vcc, 0xfbeffc00, v38
	s_nop 1
	v_addc_co_u32_e32 v21, vcc, -1, v39, vcc
	global_load_dwordx2 v[58:59], v[20:21], off
	v_add_co_u32_e32 v20, vcc, 0xfbeffe00, v38
	s_nop 1
	v_addc_co_u32_e32 v21, vcc, -1, v39, vcc
	global_load_dwordx2 v[60:61], v[20:21], off
	v_add_co_u32_e32 v20, vcc, 0xfbf00000, v38
	s_nop 1
	v_addc_co_u32_e32 v21, vcc, -1, v39, vcc
	global_load_dwordx2 v[62:63], v[20:21], off
	global_load_dwordx4 v[28:31], v[32:33], off
	global_load_dwordx4 v[20:23], v[52:53], off
	s_waitcnt vmcnt(0) lgkmcnt(0)
	v_pk_add_f32 v[22:23], v[22:23], 1.0 op_sel_hi:[1,0]
	v_pk_add_f32 v[20:21], v[20:21], 1.0 op_sel_hi:[1,0]
	v_pk_mul_f32 v[40:41], v[2:3], v[22:23]
	v_pk_mul_f32 v[42:43], v[0:1], v[20:21]
	global_load_dwordx4 v[20:23], v[32:33], off offset:1024
	global_load_dwordx4 v[24:27], v[52:53], off offset:1024
	s_waitcnt vmcnt(0) lgkmcnt(0)
	v_pk_add_f32 v[26:27], v[26:27], 1.0 op_sel_hi:[1,0]
	v_pk_add_f32 v[24:25], v[24:25], 1.0 op_sel_hi:[1,0]
	v_pk_mul_f32 v[44:45], v[6:7], v[26:27]
	v_pk_mul_f32 v[46:47], v[4:5], v[24:25]
	global_load_dwordx4 v[24:27], v[32:33], off offset:2048
	global_load_dwordx4 v[48:51], v[52:53], off offset:2048
	s_waitcnt vmcnt(0) lgkmcnt(0)
; __device__ __forceinline__ unsigned pk2(float lo, float hi) { unsigned r; asm("v_cvt_pk_bf16_f32 %0, %1, %2" : "=v"(r) : "v"(lo), "v"(hi)); return r; }
; __device__ __forceinline__ f32x4 unpack4(unsigned long long w) { const unsigned lo = (unsigned)w, hi = (unsigned)(w >> 32); return (f32x4){__uint_as_float(lo << 16), __uint_as_float(lo & 0xffff0000u), __uint_as_float(hi << 16), __uint_as_float(hi & 0xffff0000u)}; }
; template <int MODE, int NR>
; __device__ __forceinline__ void norm_finish(const unsigned long long (&raw)[NR][4], bf16* H, float* out32, const f32x4 (&mul)[4], const f32x4 (&sh)[4], int lane) {
; #pragma unroll
;     for (int r = 0; r < NR; ++r) { f32x4 v[4]; float s = 0.f;
; #pragma unroll
;         for (int j = 0; j < 4; ++j) { v[j] = unpack4(raw[r][j]); s += (v[j].x * v[j].x + v[j].y * v[j].y) + (v[j].z * v[j].z + v[j].w * v[j].w); }
;         const float rstd = rsqrtf(wave_sum(s) * (1.f / D) + EPS);
;         if constexpr (MODE == 2) { f32x4* o = (f32x4*)(out32 + (size_t)r * D) + lane;
; #pragma unroll
;             for (int j = 0; j < 4; ++j) o[64 * j] = v[j] * rstd * mul[j];
;         } else { unsigned long long* o8 = (unsigned long long*)(H + (size_t)r * D) + lane;
; #pragma unroll
;             for (int j = 0; j < 4; ++j) { const f32x4 y = v[j] * rstd * mul[j] + sh[j]; o8[64 * j] = (unsigned long long)pk2(y.x, y.y) | ((unsigned long long)pk2(y.z, y.w) << 32); } } }
; }
	v_pk_add_f32 v[34:35], v[50:51], 1.0 op_sel_hi:[1,0]
	v_pk_add_f32 v[50:51], v[48:49], 1.0 op_sel_hi:[1,0]
	v_pk_mul_f32 v[48:49], v[14:15], v[34:35]
	global_load_dwordx4 v[32:35], v[32:33], off offset:3072
	s_nop 0
	global_load_dwordx4 v[52:55], v[52:53], off offset:3072
	v_pk_mul_f32 v[50:51], v[12:13], v[50:51]
	s_waitcnt vmcnt(0) lgkmcnt(0)
	v_pk_add_f32 v[54:55], v[54:55], 1.0 op_sel_hi:[1,0]
	v_pk_add_f32 v[122:123], v[52:53], 1.0 op_sel_hi:[1,0]
	v_pk_mul_f32 v[52:53], v[18:19], v[54:55]
	v_pk_mul_f32 v[54:55], v[16:17], v[122:123]
	v_lshlrev_b32_e32 v122, 16, v112
	v_and_b32_e32 v123, 0xffff0000, v112
	v_lshlrev_b32_e32 v112, 16, v113
	v_and_b32_e32 v113, 0xffff0000, v113
	v_mul_f32_e32 v121, v123, v123
	v_mul_f32_e32 v124, v113, v113
	v_fmac_f32_e32 v121, v122, v122
	v_fmac_f32_e32 v124, v112, v112
	v_add_f32_e32 v121, v121, v124
	v_lshlrev_b32_e32 v124, 16, v114
	v_lshlrev_b32_e32 v114, 16, v115
	v_and_b32_e32 v115, 0xffff0000, v115
	v_mul_f32_e32 v127, v115, v115
	v_fmac_f32_e32 v126, v124, v124
	v_fmac_f32_e32 v127, v114, v114
	v_add_f32_e32 v126, v126, v127
	v_add_f32_e32 v121, v121, v126
	v_lshlrev_b32_e32 v126, 16, v116
	v_and_b32_e32 v127, 0xffff0000, v116
	v_lshlrev_b32_e32 v116, 16, v117
	v_and_b32_e32 v117, 0xffff0000, v117
	v_mul_f32_e32 v128, v127, v127
	v_mul_f32_e32 v129, v117, v117
	v_fmac_f32_e32 v128, v126, v126
	v_fmac_f32_e32 v129, v116, v116
	v_add_f32_e32 v128, v128, v129
	v_add_f32_e32 v121, v121, v128
	v_lshlrev_b32_e32 v128, 16, v118
	v_and_b32_e32 v129, 0xffff0000, v118
	v_lshlrev_b32_e32 v118, 16, v119
	v_and_b32_e32 v119, 0xffff0000, v119
	v_mul_f32_e32 v130, v129, v129
	v_mul_f32_e32 v131, v119, v119
	v_fmac_f32_e32 v130, v128, v128
	v_fmac_f32_e32 v131, v118, v118
	v_add_f32_e32 v130, v130, v131
	v_add_f32_e32 v121, v121, v130
	ds_swizzle_b32 v130, v121 offset:swizzle(SWAP,1)
	s_waitcnt lgkmcnt(0)
	v_add_f32_e32 v121, v121, v130
	ds_swizzle_b32 v130, v121 offset:swizzle(SWAP,2)
	s_waitcnt lgkmcnt(0)
	v_add_f32_e32 v121, v121, v130
	ds_swizzle_b32 v130, v121 offset:swizzle(SWAP,4)
	s_waitcnt lgkmcnt(0)
	v_add_f32_e32 v121, v121, v130
	ds_swizzle_b32 v130, v121 offset:swizzle(SWAP,8)
	s_waitcnt lgkmcnt(0)
	v_add_f32_e32 v121, v121, v130
	ds_swizzle_b32 v130, v121 offset:swizzle(SWAP,16)
	s_waitcnt lgkmcnt(0)
	v_add_f32_e32 v121, v121, v130
	v_mov_b32_e32 v130, v121
	s_nop 1
	v_permlane32_swap_b32_e32 v121, v130
	v_add_f32_e32 v121, v121, v130
	v_fmamk_f32 v121, v121, 0x3a800000, v176
	v_cmp_gt_f32_e32 vcc, s33, v121
	v_mul_f32_e32 v130, 0x4b800000, v121
	s_nop 0
	v_cndmask_b32_e32 v121, v121, v130, vcc
	v_rsq_f32_e32 v121, v121
	s_nop 0
	v_mul_f32_e32 v130, 0x45800000, v121
	v_cndmask_b32_e32 v130, v121, v130, vcc
	v_pk_mul_f32 v[122:123], v[122:123], v[130:131] op_sel_hi:[1,0]
	v_pk_mul_f32 v[112:113], v[112:113], v[130:131] op_sel_hi:[1,0]
	v_pk_fma_f32 v[122:123], v[42:43], v[122:123], v[28:29]
	v_pk_fma_f32 v[112:113], v[40:41], v[112:113], v[30:31]
	v_cvt_pk_bf16_f32 v122, v122, v123
	v_pk_mul_f32 v[114:115], v[114:115], v[130:131] op_sel_hi:[1,0]
	v_cvt_pk_bf16_f32 v123, v112, v113
	v_add_co_u32_e32 v112, vcc, s10, v38
	v_pk_fma_f32 v[114:115], v[44:45], v[114:115], v[22:23]
	s_nop 0
	v_addc_co_u32_e32 v113, vcc, -1, v39, vcc
	global_store_dwordx2 v[112:113], v[122:123], off
	v_pk_mul_f32 v[112:113], v[124:125], v[130:131] op_sel_hi:[1,0]
	s_nop 0
	v_pk_fma_f32 v[112:113], v[46:47], v[112:113], v[20:21]
	s_nop 0
	v_cvt_pk_bf16_f32 v112, v112, v113
	v_cvt_pk_bf16_f32 v113, v114, v115
	v_add_co_u32_e32 v114, vcc, s11, v38
	s_nop 1
	v_addc_co_u32_e32 v115, vcc, -1, v39, vcc
	global_store_dwordx2 v[114:115], v[112:113], off
	v_pk_mul_f32 v[112:113], v[126:127], v[130:131] op_sel_hi:[1,0]
	v_pk_mul_f32 v[114:115], v[116:117], v[130:131] op_sel_hi:[1,0]
	v_pk_fma_f32 v[112:113], v[50:51], v[112:113], v[24:25]
	v_pk_fma_f32 v[114:115], v[48:49], v[114:115], v[26:27]
	v_cvt_pk_bf16_f32 v112, v112, v113
	s_nop 0
	v_cvt_pk_bf16_f32 v113, v114, v115
	v_add_co_u32_e32 v114, vcc, s12, v38
	s_nop 1
	v_addc_co_u32_e32 v115, vcc, -1, v39, vcc
	global_store_dwordx2 v[114:115], v[112:113], off
	v_pk_mul_f32 v[112:113], v[128:129], v[130:131] op_sel_hi:[1,0]
	v_pk_mul_f32 v[114:115], v[118:119], v[130:131] op_sel_hi:[1,0]
	v_pk_fma_f32 v[112:113], v[54:55], v[112:113], v[32:33]
	v_pk_fma_f32 v[114:115], v[52:53], v[114:115], v[34:35]
	v_cvt_pk_bf16_f32 v112, v112, v113
	s_nop 0
	v_cvt_pk_bf16_f32 v113, v114, v115
	v_add_co_u32_e32 v114, vcc, s13, v38
	s_nop 1
	v_addc_co_u32_e32 v115, vcc, -1, v39, vcc
	global_store_dwordx2 v[114:115], v[112:113], off
	v_lshlrev_b32_e32 v112, 16, v104
	v_and_b32_e32 v113, 0xffff0000, v104
	v_lshlrev_b32_e32 v104, 16, v105
	v_and_b32_e32 v105, 0xffff0000, v105
	v_mul_f32_e32 v114, v113, v113
	v_mul_f32_e32 v115, v105, v105
	v_fmac_f32_e32 v114, v112, v112
	v_fmac_f32_e32 v115, v104, v104
	v_add_f32_e32 v116, v114, v115
	v_lshlrev_b32_e32 v114, 16, v106
	v_and_b32_e32 v115, 0xffff0000, v106
	v_lshlrev_b32_e32 v106, 16, v107
	v_and_b32_e32 v107, 0xffff0000, v107
	v_mul_f32_e32 v117, v115, v115
	v_mul_f32_e32 v118, v107, v107
	v_fmac_f32_e32 v117, v114, v114
	v_fmac_f32_e32 v118, v106, v106
	v_add_f32_e32 v117, v117, v118
	v_add_f32_e32 v118, v116, v117
	v_lshlrev_b32_e32 v116, 16, v108
	v_and_b32_e32 v117, 0xffff0000, v108
	v_lshlrev_b32_e32 v108, 16, v109
	v_and_b32_e32 v109, 0xffff0000, v109
	v_mul_f32_e32 v119, v117, v117
	v_mul_f32_e32 v121, v109, v109
	v_fmac_f32_e32 v119, v116, v116
	v_fmac_f32_e32 v121, v108, v108
	v_add_f32_e32 v119, v119, v121
	v_add_f32_e32 v121, v118, v119
	v_lshlrev_b32_e32 v118, 16, v110
	v_and_b32_e32 v119, 0xffff0000, v110
	v_lshlrev_b32_e32 v110, 16, v111
	v_and_b32_e32 v111, 0xffff0000, v111
	v_mul_f32_e32 v122, v119, v119
	v_mul_f32_e32 v123, v111, v111
	v_fmac_f32_e32 v122, v118, v118
	v_fmac_f32_e32 v123, v110, v110
	v_add_f32_e32 v122, v122, v123
	v_add_f32_e32 v121, v121, v122
	ds_swizzle_b32 v122, v121 offset:swizzle(SWAP,1)
	s_waitcnt lgkmcnt(0)
; __device__ __forceinline__ unsigned pk2(float lo, float hi) { unsigned r; asm("v_cvt_pk_bf16_f32 %0, %1, %2" : "=v"(r) : "v"(lo), "v"(hi)); return r; }
; __device__ __forceinline__ f32x4 unpack4(unsigned long long w) { const unsigned lo = (unsigned)w, hi = (unsigned)(w >> 32); return (f32x4){__uint_as_float(lo << 16), __uint_as_float(lo & 0xffff0000u), __uint_as_float(hi << 16), __uint_as_float(hi & 0xffff0000u)}; }
; template <int MODE, int NR>
; __device__ __forceinline__ void norm_finish(const unsigned long long (&raw)[NR][4], bf16* H, float* out32, const f32x4 (&mul)[4], const f32x4 (&sh)[4], int lane) {
; #pragma unroll
;     for (int r = 0; r < NR; ++r) { f32x4 v[4]; float s = 0.f;
; #pragma unroll
;         for (int j = 0; j < 4; ++j) { v[j] = unpack4(raw[r][j]); s += (v[j].x * v[j].x + v[j].y * v[j].y) + (v[j].z * v[j].z + v[j].w * v[j].w); }
;         const float rstd = rsqrtf(wave_sum(s) * (1.f / D) + EPS);
;         if constexpr (MODE == 2) { f32x4* o = (f32x4*)(out32 + (size_t)r * D) + lane;
; #pragma unroll
;             for (int j = 0; j < 4; ++j) o[64 * j] = v[j] * rstd * mul[j];
;         } else { unsigned long long* o8 = (unsigned long long*)(H + (size_t)r * D) + lane;
; #pragma unroll
;             for (int j = 0; j < 4; ++j) { const f32x4 y = v[j] * rstd * mul[j] + sh[j]; o8[64 * j] = (unsigned long long)pk2(y.x, y.y) | ((unsigned long long)pk2(y.z, y.w) << 32); } } }
; }
	v_add_f32_e32 v121, v121, v122
	ds_swizzle_b32 v122, v121 offset:swizzle(SWAP,2)
	s_waitcnt lgkmcnt(0)
	v_add_f32_e32 v121, v121, v122
	ds_swizzle_b32 v122, v121 offset:swizzle(SWAP,4)
	s_waitcnt lgkmcnt(0)
	v_add_f32_e32 v121, v121, v122
	ds_swizzle_b32 v122, v121 offset:swizzle(SWAP,8)
	s_waitcnt lgkmcnt(0)
	v_add_f32_e32 v121, v121, v122
	ds_swizzle_b32 v122, v121 offset:swizzle(SWAP,16)
	s_waitcnt lgkmcnt(0)
	v_add_f32_e32 v121, v121, v122
	v_mov_b32_e32 v122, v121
	s_nop 1
	v_permlane32_swap_b32_e32 v121, v122
	v_add_f32_e32 v121, v121, v122
	v_fmamk_f32 v121, v121, 0x3a800000, v176
	v_cmp_gt_f32_e32 vcc, s33, v121
	v_mul_f32_e32 v122, 0x4b800000, v121
	s_nop 0
	v_cndmask_b32_e32 v121, v121, v122, vcc
	v_rsq_f32_e32 v121, v121
	s_nop 0
	v_mul_f32_e32 v122, 0x45800000, v121
	v_cndmask_b32_e32 v122, v121, v122, vcc
	v_pk_mul_f32 v[112:113], v[112:113], v[122:123] op_sel_hi:[1,0]
	v_pk_mul_f32 v[104:105], v[104:105], v[122:123] op_sel_hi:[1,0]
	v_pk_fma_f32 v[112:113], v[42:43], v[112:113], v[28:29]
	v_pk_fma_f32 v[104:105], v[40:41], v[104:105], v[30:31]
	v_cvt_pk_bf16_f32 v112, v112, v113
	v_pk_mul_f32 v[106:107], v[106:107], v[122:123] op_sel_hi:[1,0]
	v_cvt_pk_bf16_f32 v113, v104, v105
	v_add_co_u32_e32 v104, vcc, s14, v38
	v_pk_fma_f32 v[106:107], v[44:45], v[106:107], v[22:23]
	s_nop 0
	v_addc_co_u32_e32 v105, vcc, -1, v39, vcc
	global_store_dwordx2 v[104:105], v[112:113], off
	v_pk_mul_f32 v[104:105], v[114:115], v[122:123] op_sel_hi:[1,0]
	s_nop 0
	v_pk_fma_f32 v[104:105], v[46:47], v[104:105], v[20:21]
	s_nop 0
	v_cvt_pk_bf16_f32 v104, v104, v105
	v_cvt_pk_bf16_f32 v105, v106, v107
	v_add_co_u32_e32 v106, vcc, s15, v38
	s_nop 1
	v_addc_co_u32_e32 v107, vcc, -1, v39, vcc
	global_store_dwordx2 v[106:107], v[104:105], off
	v_pk_mul_f32 v[104:105], v[116:117], v[122:123] op_sel_hi:[1,0]
	v_pk_mul_f32 v[106:107], v[108:109], v[122:123] op_sel_hi:[1,0]
	v_pk_fma_f32 v[104:105], v[50:51], v[104:105], v[24:25]
	v_pk_fma_f32 v[106:107], v[48:49], v[106:107], v[26:27]
	v_cvt_pk_bf16_f32 v104, v104, v105
	s_nop 0
	v_cvt_pk_bf16_f32 v105, v106, v107
	v_add_co_u32_e32 v106, vcc, s16, v38
	s_nop 1
	v_addc_co_u32_e32 v107, vcc, -1, v39, vcc
	global_store_dwordx2 v[106:107], v[104:105], off
	v_pk_mul_f32 v[104:105], v[118:119], v[122:123] op_sel_hi:[1,0]
	v_pk_mul_f32 v[106:107], v[110:111], v[122:123] op_sel_hi:[1,0]
	v_pk_fma_f32 v[104:105], v[54:55], v[104:105], v[32:33]
	v_pk_fma_f32 v[106:107], v[52:53], v[106:107], v[34:35]
	v_cvt_pk_bf16_f32 v104, v104, v105
	s_nop 0
	v_cvt_pk_bf16_f32 v105, v106, v107
	v_add_co_u32_e32 v106, vcc, s17, v38
	s_nop 1
	v_addc_co_u32_e32 v107, vcc, -1, v39, vcc
	global_store_dwordx2 v[106:107], v[104:105], off
	v_lshlrev_b32_e32 v104, 16, v96
	v_and_b32_e32 v105, 0xffff0000, v96
	v_lshlrev_b32_e32 v96, 16, v97
	v_and_b32_e32 v97, 0xffff0000, v97
	v_mul_f32_e32 v106, v105, v105
	v_mul_f32_e32 v107, v97, v97
	v_fmac_f32_e32 v106, v104, v104
	v_fmac_f32_e32 v107, v96, v96
	v_add_f32_e32 v108, v106, v107
	v_lshlrev_b32_e32 v106, 16, v98
	v_and_b32_e32 v107, 0xffff0000, v98
	v_lshlrev_b32_e32 v98, 16, v99
	v_and_b32_e32 v99, 0xffff0000, v99
	v_mul_f32_e32 v109, v107, v107
	v_mul_f32_e32 v110, v99, v99
	v_fmac_f32_e32 v109, v106, v106
	v_fmac_f32_e32 v110, v98, v98
	v_add_f32_e32 v109, v109, v110
	v_add_f32_e32 v110, v108, v109
	v_lshlrev_b32_e32 v108, 16, v100
	v_and_b32_e32 v109, 0xffff0000, v100
	v_lshlrev_b32_e32 v100, 16, v101
	v_and_b32_e32 v101, 0xffff0000, v101
	v_mul_f32_e32 v111, v109, v109
	v_mul_f32_e32 v112, v101, v101
	v_fmac_f32_e32 v111, v108, v108
	v_fmac_f32_e32 v112, v100, v100
	v_add_f32_e32 v111, v111, v112
	v_add_f32_e32 v112, v110, v111
	v_lshlrev_b32_e32 v110, 16, v102
	v_and_b32_e32 v111, 0xffff0000, v102
	v_lshlrev_b32_e32 v102, 16, v103
	v_and_b32_e32 v103, 0xffff0000, v103
	v_mul_f32_e32 v113, v111, v111
	v_mul_f32_e32 v114, v103, v103
	v_fmac_f32_e32 v113, v110, v110
	v_fmac_f32_e32 v114, v102, v102
	v_add_f32_e32 v113, v113, v114
	v_add_f32_e32 v112, v112, v113
	ds_swizzle_b32 v113, v112 offset:swizzle(SWAP,1)
	s_waitcnt lgkmcnt(0)
	v_add_f32_e32 v112, v112, v113
	ds_swizzle_b32 v113, v112 offset:swizzle(SWAP,2)
	s_waitcnt lgkmcnt(0)
	v_add_f32_e32 v112, v112, v113
	ds_swizzle_b32 v113, v112 offset:swizzle(SWAP,4)
	s_waitcnt lgkmcnt(0)
	v_add_f32_e32 v112, v112, v113
	ds_swizzle_b32 v113, v112 offset:swizzle(SWAP,8)
	s_waitcnt lgkmcnt(0)
	v_add_f32_e32 v112, v112, v113
	ds_swizzle_b32 v113, v112 offset:swizzle(SWAP,16)
	s_waitcnt lgkmcnt(0)
; __device__ __forceinline__ unsigned pk2(float lo, float hi) { unsigned r; asm("v_cvt_pk_bf16_f32 %0, %1, %2" : "=v"(r) : "v"(lo), "v"(hi)); return r; }
; __device__ __forceinline__ f32x4 unpack4(unsigned long long w) { const unsigned lo = (unsigned)w, hi = (unsigned)(w >> 32); return (f32x4){__uint_as_float(lo << 16), __uint_as_float(lo & 0xffff0000u), __uint_as_float(hi << 16), __uint_as_float(hi & 0xffff0000u)}; }
; template <int MODE, int NR>
; __device__ __forceinline__ void norm_finish(const unsigned long long (&raw)[NR][4], bf16* H, float* out32, const f32x4 (&mul)[4], const f32x4 (&sh)[4], int lane) {
; #pragma unroll
;     for (int r = 0; r < NR; ++r) { f32x4 v[4]; float s = 0.f;
; #pragma unroll
;         for (int j = 0; j < 4; ++j) { v[j] = unpack4(raw[r][j]); s += (v[j].x * v[j].x + v[j].y * v[j].y) + (v[j].z * v[j].z + v[j].w * v[j].w); }
;         const float rstd = rsqrtf(wave_sum(s) * (1.f / D) + EPS);
;         if constexpr (MODE == 2) { f32x4* o = (f32x4*)(out32 + (size_t)r * D) + lane;
; #pragma unroll
;             for (int j = 0; j < 4; ++j) o[64 * j] = v[j] * rstd * mul[j];
;         } else { unsigned long long* o8 = (unsigned long long*)(H + (size_t)r * D) + lane;
; #pragma unroll
;             for (int j = 0; j < 4; ++j) { const f32x4 y = v[j] * rstd * mul[j] + sh[j]; o8[64 * j] = (unsigned long long)pk2(y.x, y.y) | ((unsigned long long)pk2(y.z, y.w) << 32); } } }
; }
	v_add_f32_e32 v112, v112, v113
	v_mov_b32_e32 v113, v112
	s_nop 1
	v_permlane32_swap_b32_e32 v112, v113
	v_add_f32_e32 v112, v112, v113
	v_fmamk_f32 v112, v112, 0x3a800000, v176
	v_cmp_gt_f32_e32 vcc, s33, v112
	v_mul_f32_e32 v113, 0x4b800000, v112
	s_nop 0
	v_cndmask_b32_e32 v112, v112, v113, vcc
	v_rsq_f32_e32 v112, v112
	s_nop 0
	v_mul_f32_e32 v113, 0x45800000, v112
	v_cndmask_b32_e32 v112, v112, v113, vcc
	v_pk_mul_f32 v[104:105], v[104:105], v[112:113] op_sel_hi:[1,0]
	v_pk_mul_f32 v[96:97], v[96:97], v[112:113] op_sel_hi:[1,0]
	v_pk_fma_f32 v[104:105], v[42:43], v[104:105], v[28:29]
	v_pk_fma_f32 v[96:97], v[40:41], v[96:97], v[30:31]
	v_cvt_pk_bf16_f32 v104, v104, v105
	v_pk_mul_f32 v[98:99], v[98:99], v[112:113] op_sel_hi:[1,0]
	v_cvt_pk_bf16_f32 v105, v96, v97
	v_add_co_u32_e32 v96, vcc, s18, v38
	v_pk_fma_f32 v[98:99], v[44:45], v[98:99], v[22:23]
	s_nop 0
	v_addc_co_u32_e32 v97, vcc, -1, v39, vcc
	global_store_dwordx2 v[96:97], v[104:105], off
	v_pk_mul_f32 v[96:97], v[106:107], v[112:113] op_sel_hi:[1,0]
	s_nop 0
	v_pk_fma_f32 v[96:97], v[46:47], v[96:97], v[20:21]
	s_nop 0
	v_cvt_pk_bf16_f32 v96, v96, v97
	v_cvt_pk_bf16_f32 v97, v98, v99
	v_add_co_u32_e32 v98, vcc, s19, v38
	s_nop 1
	v_addc_co_u32_e32 v99, vcc, -1, v39, vcc
	global_store_dwordx2 v[98:99], v[96:97], off
	v_pk_mul_f32 v[96:97], v[108:109], v[112:113] op_sel_hi:[1,0]
	v_pk_mul_f32 v[98:99], v[100:101], v[112:113] op_sel_hi:[1,0]
	v_pk_fma_f32 v[96:97], v[50:51], v[96:97], v[24:25]
	v_pk_fma_f32 v[98:99], v[48:49], v[98:99], v[26:27]
	v_cvt_pk_bf16_f32 v96, v96, v97
	s_nop 0
	v_cvt_pk_bf16_f32 v97, v98, v99
	v_add_co_u32_e32 v98, vcc, s20, v38
	s_nop 1
	v_addc_co_u32_e32 v99, vcc, -1, v39, vcc
	global_store_dwordx2 v[98:99], v[96:97], off
	v_pk_mul_f32 v[96:97], v[110:111], v[112:113] op_sel_hi:[1,0]
	v_pk_mul_f32 v[98:99], v[102:103], v[112:113] op_sel_hi:[1,0]
	v_pk_fma_f32 v[96:97], v[54:55], v[96:97], v[32:33]
	v_pk_fma_f32 v[98:99], v[52:53], v[98:99], v[34:35]
	v_cvt_pk_bf16_f32 v96, v96, v97
	s_nop 0
	v_cvt_pk_bf16_f32 v97, v98, v99
	v_add_co_u32_e32 v98, vcc, s21, v38
	s_nop 1
	v_addc_co_u32_e32 v99, vcc, -1, v39, vcc
	global_store_dwordx2 v[98:99], v[96:97], off
	v_lshlrev_b32_e32 v96, 16, v88
	v_and_b32_e32 v97, 0xffff0000, v88
	v_lshlrev_b32_e32 v88, 16, v89
	v_and_b32_e32 v89, 0xffff0000, v89
	v_mul_f32_e32 v98, v97, v97
	v_mul_f32_e32 v99, v89, v89
	v_fmac_f32_e32 v98, v96, v96
	v_fmac_f32_e32 v99, v88, v88
	v_add_f32_e32 v100, v98, v99
	v_lshlrev_b32_e32 v98, 16, v90
	v_and_b32_e32 v99, 0xffff0000, v90
	v_lshlrev_b32_e32 v90, 16, v91
	v_and_b32_e32 v91, 0xffff0000, v91
	v_mul_f32_e32 v101, v99, v99
	v_mul_f32_e32 v102, v91, v91
	v_fmac_f32_e32 v101, v98, v98
	v_fmac_f32_e32 v102, v90, v90
	v_add_f32_e32 v101, v101, v102
	v_add_f32_e32 v102, v100, v101
	v_lshlrev_b32_e32 v100, 16, v92
	v_and_b32_e32 v101, 0xffff0000, v92
	v_lshlrev_b32_e32 v92, 16, v93
	v_and_b32_e32 v93, 0xffff0000, v93
	v_mul_f32_e32 v103, v101, v101
	v_mul_f32_e32 v104, v93, v93
	v_fmac_f32_e32 v103, v100, v100
	v_fmac_f32_e32 v104, v92, v92
	v_add_f32_e32 v103, v103, v104
	v_add_f32_e32 v104, v102, v103
	v_lshlrev_b32_e32 v102, 16, v94
	v_and_b32_e32 v103, 0xffff0000, v94
	v_lshlrev_b32_e32 v94, 16, v95
	v_and_b32_e32 v95, 0xffff0000, v95
	v_mul_f32_e32 v105, v103, v103
	v_mul_f32_e32 v106, v95, v95
	v_fmac_f32_e32 v105, v102, v102
	v_fmac_f32_e32 v106, v94, v94
	v_add_f32_e32 v105, v105, v106
	v_add_f32_e32 v104, v104, v105
	ds_swizzle_b32 v105, v104 offset:swizzle(SWAP,1)
	s_waitcnt lgkmcnt(0)
	v_add_f32_e32 v104, v104, v105
	ds_swizzle_b32 v105, v104 offset:swizzle(SWAP,2)
	s_waitcnt lgkmcnt(0)
	v_add_f32_e32 v104, v104, v105
	ds_swizzle_b32 v105, v104 offset:swizzle(SWAP,4)
	s_waitcnt lgkmcnt(0)
	v_add_f32_e32 v104, v104, v105
	ds_swizzle_b32 v105, v104 offset:swizzle(SWAP,8)
	s_waitcnt lgkmcnt(0)
	v_add_f32_e32 v104, v104, v105
	ds_swizzle_b32 v105, v104 offset:swizzle(SWAP,16)
	s_waitcnt lgkmcnt(0)
	v_add_f32_e32 v104, v104, v105
	v_mov_b32_e32 v105, v104
	s_nop 1
	v_permlane32_swap_b32_e32 v104, v105
	v_add_f32_e32 v104, v104, v105
	v_fmamk_f32 v104, v104, 0x3a800000, v176
	v_cmp_gt_f32_e32 vcc, s33, v104
	v_mul_f32_e32 v105, 0x4b800000, v104
	s_nop 0
	v_cndmask_b32_e32 v104, v104, v105, vcc
	v_rsq_f32_e32 v104, v104
	s_nop 0
	v_mul_f32_e32 v105, 0x45800000, v104
	v_cndmask_b32_e32 v104, v104, v105, vcc
	v_pk_mul_f32 v[96:97], v[96:97], v[104:105] op_sel_hi:[1,0]
	v_pk_mul_f32 v[88:89], v[88:89], v[104:105] op_sel_hi:[1,0]
	v_pk_fma_f32 v[96:97], v[42:43], v[96:97], v[28:29]
	v_pk_fma_f32 v[88:89], v[40:41], v[88:89], v[30:31]
	v_cvt_pk_bf16_f32 v96, v96, v97
	v_pk_mul_f32 v[90:91], v[90:91], v[104:105] op_sel_hi:[1,0]
	v_cvt_pk_bf16_f32 v97, v88, v89
	v_add_co_u32_e32 v88, vcc, s22, v38
	v_pk_fma_f32 v[90:91], v[44:45], v[90:91], v[22:23]
	s_nop 0
	v_addc_co_u32_e32 v89, vcc, -1, v39, vcc
	global_store_dwordx2 v[88:89], v[96:97], off
	v_pk_mul_f32 v[88:89], v[98:99], v[104:105] op_sel_hi:[1,0]
	s_nop 0
	v_pk_fma_f32 v[88:89], v[46:47], v[88:89], v[20:21]
	s_nop 0
	v_cvt_pk_bf16_f32 v88, v88, v89
	v_cvt_pk_bf16_f32 v89, v90, v91
	v_add_co_u32_e32 v90, vcc, s23, v38
	s_nop 1
	v_addc_co_u32_e32 v91, vcc, -1, v39, vcc
	global_store_dwordx2 v[90:91], v[88:89], off
	v_pk_mul_f32 v[88:89], v[100:101], v[104:105] op_sel_hi:[1,0]
	v_pk_mul_f32 v[90:91], v[92:93], v[104:105] op_sel_hi:[1,0]
	v_pk_fma_f32 v[88:89], v[50:51], v[88:89], v[24:25]
	v_pk_fma_f32 v[90:91], v[48:49], v[90:91], v[26:27]
	v_cvt_pk_bf16_f32 v88, v88, v89
	s_nop 0
	v_cvt_pk_bf16_f32 v89, v90, v91
	v_add_co_u32_e32 v90, vcc, s24, v38
	s_nop 1
	v_addc_co_u32_e32 v91, vcc, -1, v39, vcc
; __device__ __forceinline__ unsigned pk2(float lo, float hi) { unsigned r; asm("v_cvt_pk_bf16_f32 %0, %1, %2" : "=v"(r) : "v"(lo), "v"(hi)); return r; }
; __device__ __forceinline__ f32x4 unpack4(unsigned long long w) { const unsigned lo = (unsigned)w, hi = (unsigned)(w >> 32); return (f32x4){__uint_as_float(lo << 16), __uint_as_float(lo & 0xffff0000u), __uint_as_float(hi << 16), __uint_as_float(hi & 0xffff0000u)}; }
; template <int MODE, int NR>
; __device__ __forceinline__ void norm_finish(const unsigned long long (&raw)[NR][4], bf16* H, float* out32, const f32x4 (&mul)[4], const f32x4 (&sh)[4], int lane) {
; #pragma unroll
;     for (int r = 0; r < NR; ++r) { f32x4 v[4]; float s = 0.f;
; #pragma unroll
;         for (int j = 0; j < 4; ++j) { v[j] = unpack4(raw[r][j]); s += (v[j].x * v[j].x + v[j].y * v[j].y) + (v[j].z * v[j].z + v[j].w * v[j].w); }
;         const float rstd = rsqrtf(wave_sum(s) * (1.f / D) + EPS);
;         if constexpr (MODE == 2) { f32x4* o = (f32x4*)(out32 + (size_t)r * D) + lane;
; #pragma unroll
;             for (int j = 0; j < 4; ++j) o[64 * j] = v[j] * rstd * mul[j];
;         } else { unsigned long long* o8 = (unsigned long long*)(H + (size_t)r * D) + lane;
; #pragma unroll
;             for (int j = 0; j < 4; ++j) { const f32x4 y = v[j] * rstd * mul[j] + sh[j]; o8[64 * j] = (unsigned long long)pk2(y.x, y.y) | ((unsigned long long)pk2(y.z, y.w) << 32); } } }
; }
	global_store_dwordx2 v[90:91], v[88:89], off
	v_pk_mul_f32 v[88:89], v[102:103], v[104:105] op_sel_hi:[1,0]
	v_pk_mul_f32 v[90:91], v[94:95], v[104:105] op_sel_hi:[1,0]
	v_pk_fma_f32 v[88:89], v[54:55], v[88:89], v[32:33]
	v_pk_fma_f32 v[90:91], v[52:53], v[90:91], v[34:35]
	v_cvt_pk_bf16_f32 v88, v88, v89
	s_nop 0
	v_cvt_pk_bf16_f32 v89, v90, v91
	v_add_co_u32_e32 v90, vcc, s25, v38
	s_nop 1
	v_addc_co_u32_e32 v91, vcc, -1, v39, vcc
	global_store_dwordx2 v[90:91], v[88:89], off
	v_lshlrev_b32_e32 v88, 16, v80
	v_and_b32_e32 v89, 0xffff0000, v80
	v_lshlrev_b32_e32 v80, 16, v81
	v_and_b32_e32 v81, 0xffff0000, v81
	v_mul_f32_e32 v90, v89, v89
	v_mul_f32_e32 v91, v81, v81
	v_fmac_f32_e32 v90, v88, v88
	v_fmac_f32_e32 v91, v80, v80
	v_add_f32_e32 v92, v90, v91
	v_lshlrev_b32_e32 v90, 16, v82
	v_and_b32_e32 v91, 0xffff0000, v82
	v_lshlrev_b32_e32 v82, 16, v83
	v_and_b32_e32 v83, 0xffff0000, v83
	v_mul_f32_e32 v93, v91, v91
	v_mul_f32_e32 v94, v83, v83
	v_fmac_f32_e32 v93, v90, v90
	v_fmac_f32_e32 v94, v82, v82
	v_add_f32_e32 v93, v93, v94
	v_add_f32_e32 v94, v92, v93
	v_lshlrev_b32_e32 v92, 16, v84
	v_and_b32_e32 v93, 0xffff0000, v84
	v_lshlrev_b32_e32 v84, 16, v85
	v_and_b32_e32 v85, 0xffff0000, v85
	v_mul_f32_e32 v95, v93, v93
	v_mul_f32_e32 v96, v85, v85
	v_fmac_f32_e32 v95, v92, v92
	v_fmac_f32_e32 v96, v84, v84
	v_add_f32_e32 v95, v95, v96
	v_add_f32_e32 v96, v94, v95
	v_lshlrev_b32_e32 v94, 16, v86
	v_and_b32_e32 v95, 0xffff0000, v86
	v_lshlrev_b32_e32 v86, 16, v87
	v_and_b32_e32 v87, 0xffff0000, v87
	v_mul_f32_e32 v97, v95, v95
	v_mul_f32_e32 v98, v87, v87
	v_fmac_f32_e32 v97, v94, v94
	v_fmac_f32_e32 v98, v86, v86
	v_add_f32_e32 v97, v97, v98
	v_add_f32_e32 v96, v96, v97
	ds_swizzle_b32 v97, v96 offset:swizzle(SWAP,1)
	s_waitcnt lgkmcnt(0)
	v_add_f32_e32 v96, v96, v97
	ds_swizzle_b32 v97, v96 offset:swizzle(SWAP,2)
	s_waitcnt lgkmcnt(0)
	v_add_f32_e32 v96, v96, v97
	ds_swizzle_b32 v97, v96 offset:swizzle(SWAP,4)
	s_waitcnt lgkmcnt(0)
	v_add_f32_e32 v96, v96, v97
	ds_swizzle_b32 v97, v96 offset:swizzle(SWAP,8)
	s_waitcnt lgkmcnt(0)
	v_add_f32_e32 v96, v96, v97
	ds_swizzle_b32 v97, v96 offset:swizzle(SWAP,16)
	s_waitcnt lgkmcnt(0)
	v_add_f32_e32 v96, v96, v97
	v_mov_b32_e32 v97, v96
	s_nop 1
	v_permlane32_swap_b32_e32 v96, v97
	v_add_f32_e32 v96, v96, v97
	v_fmamk_f32 v96, v96, 0x3a800000, v176
	v_cmp_gt_f32_e32 vcc, s33, v96
	v_mul_f32_e32 v97, 0x4b800000, v96
	s_nop 0
	v_cndmask_b32_e32 v96, v96, v97, vcc
	v_rsq_f32_e32 v96, v96
	s_nop 0
	v_mul_f32_e32 v97, 0x45800000, v96
	v_cndmask_b32_e32 v96, v96, v97, vcc
	v_pk_mul_f32 v[88:89], v[88:89], v[96:97] op_sel_hi:[1,0]
	v_pk_mul_f32 v[80:81], v[80:81], v[96:97] op_sel_hi:[1,0]
	v_pk_fma_f32 v[88:89], v[42:43], v[88:89], v[28:29]
	v_pk_fma_f32 v[80:81], v[40:41], v[80:81], v[30:31]
	v_cvt_pk_bf16_f32 v88, v88, v89
	v_pk_mul_f32 v[82:83], v[82:83], v[96:97] op_sel_hi:[1,0]
	v_cvt_pk_bf16_f32 v89, v80, v81
	v_add_co_u32_e32 v80, vcc, s26, v38
	v_pk_fma_f32 v[82:83], v[44:45], v[82:83], v[22:23]
	s_nop 0
	v_addc_co_u32_e32 v81, vcc, -1, v39, vcc
	global_store_dwordx2 v[80:81], v[88:89], off
	v_pk_mul_f32 v[80:81], v[90:91], v[96:97] op_sel_hi:[1,0]
	s_nop 0
	v_pk_fma_f32 v[80:81], v[46:47], v[80:81], v[20:21]
	s_nop 0
	v_cvt_pk_bf16_f32 v80, v80, v81
	v_cvt_pk_bf16_f32 v81, v82, v83
	v_add_co_u32_e32 v82, vcc, s27, v38
	s_nop 1
	v_addc_co_u32_e32 v83, vcc, -1, v39, vcc
	global_store_dwordx2 v[82:83], v[80:81], off
	v_pk_mul_f32 v[80:81], v[92:93], v[96:97] op_sel_hi:[1,0]
	v_pk_mul_f32 v[82:83], v[84:85], v[96:97] op_sel_hi:[1,0]
	v_pk_fma_f32 v[80:81], v[50:51], v[80:81], v[24:25]
	v_pk_fma_f32 v[82:83], v[48:49], v[82:83], v[26:27]
	v_cvt_pk_bf16_f32 v80, v80, v81
	s_nop 0
	v_cvt_pk_bf16_f32 v81, v82, v83
	v_add_co_u32_e32 v82, vcc, s28, v38
	s_nop 1
	v_addc_co_u32_e32 v83, vcc, -1, v39, vcc
	global_store_dwordx2 v[82:83], v[80:81], off
	v_pk_mul_f32 v[80:81], v[94:95], v[96:97] op_sel_hi:[1,0]
	v_pk_mul_f32 v[82:83], v[86:87], v[96:97] op_sel_hi:[1,0]
	v_pk_fma_f32 v[80:81], v[54:55], v[80:81], v[32:33]
	v_pk_fma_f32 v[82:83], v[52:53], v[82:83], v[34:35]
	v_cvt_pk_bf16_f32 v80, v80, v81
	s_nop 0
	v_cvt_pk_bf16_f32 v81, v82, v83
	v_add_co_u32_e32 v82, vcc, s29, v38
	s_nop 1
	v_addc_co_u32_e32 v83, vcc, -1, v39, vcc
	global_store_dwordx2 v[82:83], v[80:81], off
	v_lshlrev_b32_e32 v80, 16, v72
	v_and_b32_e32 v81, 0xffff0000, v72
	v_lshlrev_b32_e32 v72, 16, v73
	v_and_b32_e32 v73, 0xffff0000, v73
	v_mul_f32_e32 v82, v81, v81
	v_mul_f32_e32 v83, v73, v73
	v_fmac_f32_e32 v82, v80, v80
	v_fmac_f32_e32 v83, v72, v72
	v_add_f32_e32 v84, v82, v83
	v_lshlrev_b32_e32 v82, 16, v74
	v_and_b32_e32 v83, 0xffff0000, v74
	v_lshlrev_b32_e32 v74, 16, v75
	v_and_b32_e32 v75, 0xffff0000, v75
	v_mul_f32_e32 v85, v83, v83
	v_mul_f32_e32 v86, v75, v75
	v_fmac_f32_e32 v85, v82, v82
	v_fmac_f32_e32 v86, v74, v74
	v_add_f32_e32 v85, v85, v86
	v_add_f32_e32 v86, v84, v85
	v_lshlrev_b32_e32 v84, 16, v76
	v_and_b32_e32 v85, 0xffff0000, v76
	v_lshlrev_b32_e32 v76, 16, v77
	v_and_b32_e32 v77, 0xffff0000, v77
	v_mul_f32_e32 v87, v85, v85
	v_mul_f32_e32 v88, v77, v77
	v_fmac_f32_e32 v87, v84, v84
	v_fmac_f32_e32 v88, v76, v76
	v_add_f32_e32 v87, v87, v88
	v_add_f32_e32 v88, v86, v87
	v_lshlrev_b32_e32 v86, 16, v78
	v_and_b32_e32 v87, 0xffff0000, v78
	v_lshlrev_b32_e32 v78, 16, v79
	v_and_b32_e32 v79, 0xffff0000, v79
	v_mul_f32_e32 v89, v87, v87
	v_mul_f32_e32 v90, v79, v79
	v_fmac_f32_e32 v89, v86, v86
	v_fmac_f32_e32 v90, v78, v78
	v_add_f32_e32 v89, v89, v90
	v_add_f32_e32 v88, v88, v89
	ds_swizzle_b32 v89, v88 offset:swizzle(SWAP,1)
	s_waitcnt lgkmcnt(0)
	v_add_f32_e32 v88, v88, v89
	ds_swizzle_b32 v89, v88 offset:swizzle(SWAP,2)
	s_waitcnt lgkmcnt(0)
; __device__ __forceinline__ unsigned pk2(float lo, float hi) { unsigned r; asm("v_cvt_pk_bf16_f32 %0, %1, %2" : "=v"(r) : "v"(lo), "v"(hi)); return r; }
; __device__ __forceinline__ f32x4 unpack4(unsigned long long w) { const unsigned lo = (unsigned)w, hi = (unsigned)(w >> 32); return (f32x4){__uint_as_float(lo << 16), __uint_as_float(lo & 0xffff0000u), __uint_as_float(hi << 16), __uint_as_float(hi & 0xffff0000u)}; }
; template <int MODE, int NR>
; __device__ __forceinline__ void norm_finish(const unsigned long long (&raw)[NR][4], bf16* H, float* out32, const f32x4 (&mul)[4], const f32x4 (&sh)[4], int lane) {
; #pragma unroll
;     for (int r = 0; r < NR; ++r) { f32x4 v[4]; float s = 0.f;
; #pragma unroll
;         for (int j = 0; j < 4; ++j) { v[j] = unpack4(raw[r][j]); s += (v[j].x * v[j].x + v[j].y * v[j].y) + (v[j].z * v[j].z + v[j].w * v[j].w); }
;         const float rstd = rsqrtf(wave_sum(s) * (1.f / D) + EPS);
;         if constexpr (MODE == 2) { f32x4* o = (f32x4*)(out32 + (size_t)r * D) + lane;
; #pragma unroll
;             for (int j = 0; j < 4; ++j) o[64 * j] = v[j] * rstd * mul[j];
;         } else { unsigned long long* o8 = (unsigned long long*)(H + (size_t)r * D) + lane;
; #pragma unroll
;             for (int j = 0; j < 4; ++j) { const f32x4 y = v[j] * rstd * mul[j] + sh[j]; o8[64 * j] = (unsigned long long)pk2(y.x, y.y) | ((unsigned long long)pk2(y.z, y.w) << 32); } } }
; }
	v_add_f32_e32 v88, v88, v89
	ds_swizzle_b32 v89, v88 offset:swizzle(SWAP,4)
	s_waitcnt lgkmcnt(0)
	v_add_f32_e32 v88, v88, v89
	ds_swizzle_b32 v89, v88 offset:swizzle(SWAP,8)
	s_waitcnt lgkmcnt(0)
	v_add_f32_e32 v88, v88, v89
	ds_swizzle_b32 v89, v88 offset:swizzle(SWAP,16)
	s_waitcnt lgkmcnt(0)
	v_add_f32_e32 v88, v88, v89
	v_mov_b32_e32 v89, v88
	s_nop 1
	v_permlane32_swap_b32_e32 v88, v89
	v_add_f32_e32 v88, v88, v89
	v_fmamk_f32 v88, v88, 0x3a800000, v176
	v_cmp_gt_f32_e32 vcc, s33, v88
	v_mul_f32_e32 v89, 0x4b800000, v88
	s_nop 0
	v_cndmask_b32_e32 v88, v88, v89, vcc
	v_rsq_f32_e32 v88, v88
	s_nop 0
	v_mul_f32_e32 v89, 0x45800000, v88
	v_cndmask_b32_e32 v88, v88, v89, vcc
	v_pk_mul_f32 v[80:81], v[80:81], v[88:89] op_sel_hi:[1,0]
	v_pk_mul_f32 v[72:73], v[72:73], v[88:89] op_sel_hi:[1,0]
	v_pk_fma_f32 v[80:81], v[42:43], v[80:81], v[28:29]
	v_pk_fma_f32 v[72:73], v[40:41], v[72:73], v[30:31]
	v_cvt_pk_bf16_f32 v80, v80, v81
	v_pk_mul_f32 v[74:75], v[74:75], v[88:89] op_sel_hi:[1,0]
	v_cvt_pk_bf16_f32 v81, v72, v73
	v_add_co_u32_e32 v72, vcc, s30, v38
	v_pk_fma_f32 v[74:75], v[44:45], v[74:75], v[22:23]
	s_nop 0
	v_addc_co_u32_e32 v73, vcc, -1, v39, vcc
	global_store_dwordx2 v[72:73], v[80:81], off
	v_pk_mul_f32 v[72:73], v[82:83], v[88:89] op_sel_hi:[1,0]
	s_nop 0
	v_pk_fma_f32 v[72:73], v[46:47], v[72:73], v[20:21]
	s_nop 0
	v_cvt_pk_bf16_f32 v72, v72, v73
	v_cvt_pk_bf16_f32 v73, v74, v75
	v_add_co_u32_e32 v74, vcc, s31, v38
	s_nop 1
	v_addc_co_u32_e32 v75, vcc, -1, v39, vcc
	global_store_dwordx2 v[74:75], v[72:73], off
	v_pk_mul_f32 v[72:73], v[84:85], v[88:89] op_sel_hi:[1,0]
	v_pk_mul_f32 v[74:75], v[76:77], v[88:89] op_sel_hi:[1,0]
	v_pk_fma_f32 v[72:73], v[50:51], v[72:73], v[24:25]
	v_pk_fma_f32 v[74:75], v[48:49], v[74:75], v[26:27]
	v_cvt_pk_bf16_f32 v72, v72, v73
	s_nop 0
	v_cvt_pk_bf16_f32 v73, v74, v75
	v_add_co_u32_e32 v74, vcc, s34, v38
	s_nop 1
	v_addc_co_u32_e32 v75, vcc, -1, v39, vcc
	global_store_dwordx2 v[74:75], v[72:73], off
	v_pk_mul_f32 v[72:73], v[86:87], v[88:89] op_sel_hi:[1,0]
	v_pk_mul_f32 v[74:75], v[78:79], v[88:89] op_sel_hi:[1,0]
	v_pk_fma_f32 v[72:73], v[54:55], v[72:73], v[32:33]
	v_pk_fma_f32 v[74:75], v[52:53], v[74:75], v[34:35]
	v_cvt_pk_bf16_f32 v72, v72, v73
	s_nop 0
	v_cvt_pk_bf16_f32 v73, v74, v75
	v_add_co_u32_e32 v74, vcc, s8, v38
	s_nop 1
	v_addc_co_u32_e32 v75, vcc, -1, v39, vcc
	global_store_dwordx2 v[74:75], v[72:73], off
	v_lshlrev_b32_e32 v72, 16, v64
	v_and_b32_e32 v73, 0xffff0000, v64
	v_lshlrev_b32_e32 v64, 16, v65
	v_and_b32_e32 v65, 0xffff0000, v65
	v_mul_f32_e32 v74, v73, v73
	v_mul_f32_e32 v75, v65, v65
	v_fmac_f32_e32 v74, v72, v72
	v_fmac_f32_e32 v75, v64, v64
	v_add_f32_e32 v76, v74, v75
	v_lshlrev_b32_e32 v74, 16, v66
	v_and_b32_e32 v75, 0xffff0000, v66
	v_lshlrev_b32_e32 v66, 16, v67
	v_and_b32_e32 v67, 0xffff0000, v67
	v_mul_f32_e32 v77, v75, v75
	v_mul_f32_e32 v78, v67, v67
	v_fmac_f32_e32 v77, v74, v74
	v_fmac_f32_e32 v78, v66, v66
	v_add_f32_e32 v77, v77, v78
	v_add_f32_e32 v78, v76, v77
	v_lshlrev_b32_e32 v76, 16, v68
	v_and_b32_e32 v77, 0xffff0000, v68
	v_lshlrev_b32_e32 v68, 16, v69
	v_and_b32_e32 v69, 0xffff0000, v69
	v_mul_f32_e32 v79, v77, v77
	v_mul_f32_e32 v80, v69, v69
	v_fmac_f32_e32 v79, v76, v76
	v_fmac_f32_e32 v80, v68, v68
	v_add_f32_e32 v79, v79, v80
	v_add_f32_e32 v80, v78, v79
	v_lshlrev_b32_e32 v78, 16, v70
	v_and_b32_e32 v79, 0xffff0000, v70
	v_lshlrev_b32_e32 v70, 16, v71
	v_and_b32_e32 v71, 0xffff0000, v71
	v_mul_f32_e32 v81, v79, v79
	v_mul_f32_e32 v82, v71, v71
	v_fmac_f32_e32 v81, v78, v78
	v_fmac_f32_e32 v82, v70, v70
	v_add_f32_e32 v81, v81, v82
	v_add_f32_e32 v80, v80, v81
	ds_swizzle_b32 v81, v80 offset:swizzle(SWAP,1)
	s_waitcnt lgkmcnt(0)
	v_add_f32_e32 v80, v80, v81
	ds_swizzle_b32 v81, v80 offset:swizzle(SWAP,2)
	s_waitcnt lgkmcnt(0)
	v_add_f32_e32 v80, v80, v81
	ds_swizzle_b32 v81, v80 offset:swizzle(SWAP,4)
	s_waitcnt lgkmcnt(0)
	v_add_f32_e32 v80, v80, v81
	ds_swizzle_b32 v81, v80 offset:swizzle(SWAP,8)
	s_waitcnt lgkmcnt(0)
	v_add_f32_e32 v80, v80, v81
	ds_swizzle_b32 v81, v80 offset:swizzle(SWAP,16)
	s_waitcnt lgkmcnt(0)
; __device__ __forceinline__ unsigned pk2(float lo, float hi) { unsigned r; asm("v_cvt_pk_bf16_f32 %0, %1, %2" : "=v"(r) : "v"(lo), "v"(hi)); return r; }
; __device__ __forceinline__ f32x4 unpack4(unsigned long long w) { const unsigned lo = (unsigned)w, hi = (unsigned)(w >> 32); return (f32x4){__uint_as_float(lo << 16), __uint_as_float(lo & 0xffff0000u), __uint_as_float(hi << 16), __uint_as_float(hi & 0xffff0000u)}; }
; template <int MODE, int NR>
; __device__ __forceinline__ void norm_finish(const unsigned long long (&raw)[NR][4], bf16* H, float* out32, const f32x4 (&mul)[4], const f32x4 (&sh)[4], int lane) {
; #pragma unroll
;     for (int r = 0; r < NR; ++r) { f32x4 v[4]; float s = 0.f;
; #pragma unroll
;         for (int j = 0; j < 4; ++j) { v[j] = unpack4(raw[r][j]); s += (v[j].x * v[j].x + v[j].y * v[j].y) + (v[j].z * v[j].z + v[j].w * v[j].w); }
;         const float rstd = rsqrtf(wave_sum(s) * (1.f / D) + EPS);
;         if constexpr (MODE == 2) { f32x4* o = (f32x4*)(out32 + (size_t)r * D) + lane;
; #pragma unroll
;             for (int j = 0; j < 4; ++j) o[64 * j] = v[j] * rstd * mul[j];
;         } else { unsigned long long* o8 = (unsigned long long*)(H + (size_t)r * D) + lane;
; #pragma unroll
;             for (int j = 0; j < 4; ++j) { const f32x4 y = v[j] * rstd * mul[j] + sh[j]; o8[64 * j] = (unsigned long long)pk2(y.x, y.y) | ((unsigned long long)pk2(y.z, y.w) << 32); } } }
; }
	v_add_f32_e32 v80, v80, v81
	v_mov_b32_e32 v81, v80
	s_nop 1
	v_permlane32_swap_b32_e32 v80, v81
	v_add_f32_e32 v80, v80, v81
	v_fmamk_f32 v80, v80, 0x3a800000, v176
	v_cmp_gt_f32_e32 vcc, s33, v80
	v_mul_f32_e32 v81, 0x4b800000, v80
	s_nop 0
	v_cndmask_b32_e32 v80, v80, v81, vcc
	v_rsq_f32_e32 v80, v80
	s_nop 0
	v_mul_f32_e32 v81, 0x45800000, v80
	v_cndmask_b32_e32 v80, v80, v81, vcc
	v_pk_mul_f32 v[72:73], v[72:73], v[80:81] op_sel_hi:[1,0]
	v_pk_mul_f32 v[64:65], v[64:65], v[80:81] op_sel_hi:[1,0]
	v_pk_fma_f32 v[72:73], v[42:43], v[72:73], v[28:29]
	v_pk_fma_f32 v[64:65], v[40:41], v[64:65], v[30:31]
	v_cvt_pk_bf16_f32 v72, v72, v73
	v_pk_mul_f32 v[66:67], v[66:67], v[80:81] op_sel_hi:[1,0]
	v_cvt_pk_bf16_f32 v73, v64, v65
	v_add_co_u32_e32 v64, vcc, s35, v38
	v_pk_fma_f32 v[66:67], v[44:45], v[66:67], v[22:23]
	s_nop 0
	v_addc_co_u32_e32 v65, vcc, -1, v39, vcc
	global_store_dwordx2 v[64:65], v[72:73], off
	v_pk_mul_f32 v[64:65], v[74:75], v[80:81] op_sel_hi:[1,0]
	s_nop 0
	v_pk_fma_f32 v[64:65], v[46:47], v[64:65], v[20:21]
	s_nop 0
	v_cvt_pk_bf16_f32 v64, v64, v65
	v_cvt_pk_bf16_f32 v65, v66, v67
	v_add_co_u32_e32 v66, vcc, s36, v38
	s_nop 1
	v_addc_co_u32_e32 v67, vcc, -1, v39, vcc
	global_store_dwordx2 v[66:67], v[64:65], off
	v_pk_mul_f32 v[64:65], v[76:77], v[80:81] op_sel_hi:[1,0]
	v_pk_mul_f32 v[66:67], v[68:69], v[80:81] op_sel_hi:[1,0]
	v_pk_fma_f32 v[64:65], v[50:51], v[64:65], v[24:25]
	v_pk_fma_f32 v[66:67], v[48:49], v[66:67], v[26:27]
	v_cvt_pk_bf16_f32 v64, v64, v65
	s_nop 0
	v_cvt_pk_bf16_f32 v65, v66, v67
	v_add_co_u32_e32 v66, vcc, s37, v38
	s_nop 1
	v_addc_co_u32_e32 v67, vcc, -1, v39, vcc
	global_store_dwordx2 v[66:67], v[64:65], off
	v_pk_mul_f32 v[64:65], v[78:79], v[80:81] op_sel_hi:[1,0]
	v_pk_mul_f32 v[66:67], v[70:71], v[80:81] op_sel_hi:[1,0]
	v_pk_fma_f32 v[64:65], v[54:55], v[64:65], v[32:33]
	v_pk_fma_f32 v[66:67], v[52:53], v[66:67], v[34:35]
	v_cvt_pk_bf16_f32 v64, v64, v65
	s_nop 0
	v_cvt_pk_bf16_f32 v65, v66, v67
	v_add_co_u32_e32 v66, vcc, s50, v38
	s_nop 1
	v_addc_co_u32_e32 v67, vcc, -1, v39, vcc
	global_store_dwordx2 v[66:67], v[64:65], off
	v_lshlrev_b32_e32 v64, 16, v56
	v_and_b32_e32 v65, 0xffff0000, v56
	v_lshlrev_b32_e32 v56, 16, v57
	v_and_b32_e32 v57, 0xffff0000, v57
	v_mul_f32_e32 v66, v65, v65
	v_mul_f32_e32 v67, v57, v57
	v_fmac_f32_e32 v66, v64, v64
	v_fmac_f32_e32 v67, v56, v56
	v_add_f32_e32 v68, v66, v67
	v_lshlrev_b32_e32 v66, 16, v58
	v_and_b32_e32 v67, 0xffff0000, v58
	v_lshlrev_b32_e32 v58, 16, v59
	v_and_b32_e32 v59, 0xffff0000, v59
	v_mul_f32_e32 v69, v67, v67
	v_mul_f32_e32 v70, v59, v59
	v_fmac_f32_e32 v69, v66, v66
	v_fmac_f32_e32 v70, v58, v58
	v_add_f32_e32 v69, v69, v70
	v_add_f32_e32 v70, v68, v69
	v_lshlrev_b32_e32 v68, 16, v60
	v_and_b32_e32 v69, 0xffff0000, v60
	v_lshlrev_b32_e32 v60, 16, v61
	v_and_b32_e32 v61, 0xffff0000, v61
	v_mul_f32_e32 v71, v69, v69
	v_mul_f32_e32 v72, v61, v61
	v_fmac_f32_e32 v71, v68, v68
	v_fmac_f32_e32 v72, v60, v60
	v_add_f32_e32 v71, v71, v72
	v_add_f32_e32 v72, v70, v71
	v_lshlrev_b32_e32 v70, 16, v62
	v_and_b32_e32 v71, 0xffff0000, v62
	v_lshlrev_b32_e32 v62, 16, v63
	v_and_b32_e32 v63, 0xffff0000, v63
	v_mul_f32_e32 v73, v71, v71
	v_mul_f32_e32 v74, v63, v63
	v_fmac_f32_e32 v73, v70, v70
	v_fmac_f32_e32 v74, v62, v62
	v_add_f32_e32 v73, v73, v74
	v_add_f32_e32 v72, v72, v73
	ds_swizzle_b32 v73, v72 offset:swizzle(SWAP,1)
	s_waitcnt lgkmcnt(0)
	v_add_f32_e32 v72, v72, v73
	ds_swizzle_b32 v73, v72 offset:swizzle(SWAP,2)
	s_waitcnt lgkmcnt(0)
	v_add_f32_e32 v72, v72, v73
	ds_swizzle_b32 v73, v72 offset:swizzle(SWAP,4)
	s_waitcnt lgkmcnt(0)
	v_add_f32_e32 v72, v72, v73
	ds_swizzle_b32 v73, v72 offset:swizzle(SWAP,8)
	s_waitcnt lgkmcnt(0)
	v_add_f32_e32 v72, v72, v73
	ds_swizzle_b32 v73, v72 offset:swizzle(SWAP,16)
	s_waitcnt lgkmcnt(0)
	v_add_f32_e32 v72, v72, v73
	v_mov_b32_e32 v73, v72
	s_nop 1
	v_permlane32_swap_b32_e32 v72, v73
	v_add_f32_e32 v72, v72, v73
	v_fmamk_f32 v72, v72, 0x3a800000, v176
	v_cmp_gt_f32_e32 vcc, s33, v72
	v_mul_f32_e32 v73, 0x4b800000, v72
	s_nop 0
	v_cndmask_b32_e32 v72, v72, v73, vcc
	v_rsq_f32_e32 v72, v72
	s_nop 0
	v_mul_f32_e32 v73, 0x45800000, v72
	v_cndmask_b32_e32 v72, v72, v73, vcc
	v_pk_mul_f32 v[64:65], v[64:65], v[72:73] op_sel_hi:[1,0]
	v_pk_mul_f32 v[56:57], v[56:57], v[72:73] op_sel_hi:[1,0]
	v_pk_fma_f32 v[28:29], v[42:43], v[64:65], v[28:29]
	v_pk_fma_f32 v[30:31], v[40:41], v[56:57], v[30:31]
	v_cvt_pk_bf16_f32 v28, v28, v29
	s_nop 0
	v_cvt_pk_bf16_f32 v29, v30, v31
	v_add_co_u32_e32 v30, vcc, s58, v38
	s_nop 1
	v_addc_co_u32_e32 v31, vcc, -1, v39, vcc
	global_store_dwordx2 v[30:31], v[28:29], off
	v_pk_mul_f32 v[28:29], v[66:67], v[72:73] op_sel_hi:[1,0]
	v_pk_mul_f32 v[30:31], v[58:59], v[72:73] op_sel_hi:[1,0]
	v_pk_fma_f32 v[20:21], v[46:47], v[28:29], v[20:21]
	v_pk_fma_f32 v[22:23], v[44:45], v[30:31], v[22:23]
	v_cvt_pk_bf16_f32 v20, v20, v21
	s_nop 0
	v_cvt_pk_bf16_f32 v21, v22, v23
	v_add_co_u32_e32 v22, vcc, s59, v38
	s_nop 1
	v_addc_co_u32_e32 v23, vcc, -1, v39, vcc
	global_store_dwordx2 v[22:23], v[20:21], off
	v_pk_mul_f32 v[20:21], v[68:69], v[72:73] op_sel_hi:[1,0]
	v_pk_mul_f32 v[22:23], v[60:61], v[72:73] op_sel_hi:[1,0]
	v_pk_fma_f32 v[20:21], v[50:51], v[20:21], v[24:25]
	v_pk_fma_f32 v[22:23], v[48:49], v[22:23], v[26:27]
	v_cvt_pk_bf16_f32 v20, v20, v21
	s_nop 0
	v_cvt_pk_bf16_f32 v21, v22, v23
	v_add_co_u32_e32 v22, vcc, s62, v38
	s_nop 1
	v_addc_co_u32_e32 v23, vcc, -1, v39, vcc
	global_store_dwordx2 v[22:23], v[20:21], off
	v_pk_mul_f32 v[20:21], v[70:71], v[72:73] op_sel_hi:[1,0]
	v_pk_mul_f32 v[22:23], v[62:63], v[72:73] op_sel_hi:[1,0]
	v_pk_fma_f32 v[20:21], v[54:55], v[20:21], v[32:33]
	v_pk_fma_f32 v[22:23], v[52:53], v[22:23], v[34:35]
	v_cvt_pk_bf16_f32 v20, v20, v21
	s_nop 0
	v_cvt_pk_bf16_f32 v21, v22, v23
	global_store_dwordx2 v[38:39], v[20:21], off
	v_lshl_add_u64 v[38:39], v[38:39], 0, s[78:79]
	s_cbranch_scc0 .LBB0_186

; __device__ __forceinline__ unsigned pk2(float lo, float hi) { unsigned r; asm("v_cvt_pk_bf16_f32 %0, %1, %2" : "=v"(r) : "v"(lo), "v"(hi)); return r; }
; template <int MODE, int NR>
; __device__ __forceinline__ void norm_rows(const float* X32, bf16* X, bf16* H, float* out32, const f32x4 (&mul)[4], const f32x4 (&sh)[4], int lane) {
;     ...
;     } else {
;         unsigned long long raw[NR][4];
; #pragma unroll
;         for (int r = 0; r < NR; ++r) { const unsigned long long* xr = (const unsigned long long*)(X + (size_t)r * D) + lane;
; #pragma unroll
;             for (int j = 0; j < 4; ++j) raw[r][j] = xr[64 * j]; }
; #pragma unroll
;         for (int r = 0; r < NR; ++r) { f32x4 v[4]; float s = 0.f;
; #pragma unroll
;             for (int j = 0; j < 4; ++j) { v[j] = unpack4(raw[r][j]); s += (v[j].x * v[j].x + v[j].y * v[j].y) + (v[j].z * v[j].z + v[j].w * v[j].w); }
;             const float rstd = rsqrtf(wave_sum(s) * (1.f / D) + EPS);
;             if constexpr (MODE == 2) { f32x4* o = (f32x4*)(out32 + (size_t)r * D) + lane;
; #pragma unroll
;                 for (int j = 0; j < 4; ++j) o[64 * j] = v[j] * rstd * mul[j];
;             } else { unsigned long long* o8 = (unsigned long long*)(H + (size_t)r * D) + lane;
; #pragma unroll
;                 for (int j = 0; j < 4; ++j) { const f32x4 y = v[j] * rstd * mul[j] + sh[j]; o8[64 * j] = (unsigned long long)pk2(y.x, y.y) | ((unsigned long long)pk2(y.z, y.w) << 32); } } }
; template <int MODE>
; __device__ __forceinline__ void phase_norm(const float* Xp32, const float* Xs32, bf16* X, bf16* H, const float* nw, const float* mod_sh, const float* mod_sc, int gw, int NGW, int lane) {
;     ...
;     for (int sr = gw; sr < MS; sr += NGW) {
;         const int ci = NB + sr; f32x4 mul[4], sh[4];
;         const f32x4* shp = (const f32x4*)(mod_sh + (size_t)ci * MODLD) + lane; const f32x4* scp = (const f32x4*)(mod_sc + (size_t)ci * MODLD) + lane;
; #pragma unroll
;         for (int j = 0; j < 4; ++j) { sh[j] = shp[64 * j]; mul[j] = w4[j] * (scp[64 * j] + 1.0f); }
;         const size_t ro = (size_t)(MP + sr) * D;
;         norm_rows<MODE, 1>(MODE == 1 ? Xs32 + (size_t)sr * D : nullptr, X + ro, H + ro, nullptr, mul, sh, lane);
;     }
.LBB0_189:
	v_lshl_add_u64 v[26:27], s[4:5], 0, v[20:21]
	v_add_co_u32_e32 v38, vcc, 0x300000, v26
	v_lshl_add_u64 v[54:55], s[4:5], 0, v[8:9]
	s_nop 0
	v_addc_co_u32_e32 v39, vcc, 0, v27, vcc
	v_add_co_u32_e32 v40, vcc, 0x301000, v26
	global_load_dwordx4 v[22:25], v[38:39], off
	s_nop 0
	v_addc_co_u32_e32 v41, vcc, 0, v27, vcc
	global_load_dwordx4 v[26:29], v[40:41], off
	v_add_co_u32_e32 v56, vcc, s8, v54
	s_add_i32 s1, s1, s96
	s_nop 0
	v_addc_co_u32_e32 v57, vcc, 0, v55, vcc
	v_lshl_add_u64 v[8:9], v[8:9], 0, s[10:11]
	v_lshl_add_u64 v[20:21], v[20:21], 0, s[60:61]
	s_cmpk_lt_i32 s1, 0x80
	s_waitcnt vmcnt(0) lgkmcnt(0)
	v_pk_add_f32 v[28:29], v[28:29], 1.0 op_sel_hi:[1,0]
	v_pk_add_f32 v[26:27], v[26:27], 1.0 op_sel_hi:[1,0]
	v_pk_mul_f32 v[42:43], v[2:3], v[28:29]
	v_pk_mul_f32 v[44:45], v[0:1], v[26:27]
	global_load_dwordx4 v[26:29], v[38:39], off offset:1024
	global_load_dwordx4 v[30:33], v[40:41], off offset:1024
	s_waitcnt vmcnt(0) lgkmcnt(0)
	v_pk_add_f32 v[32:33], v[32:33], 1.0 op_sel_hi:[1,0]
	v_pk_add_f32 v[30:31], v[30:31], 1.0 op_sel_hi:[1,0]
	v_pk_mul_f32 v[46:47], v[6:7], v[32:33]
	v_pk_mul_f32 v[48:49], v[4:5], v[30:31]
	global_load_dwordx4 v[30:33], v[38:39], off offset:2048
	global_load_dwordx4 v[34:37], v[40:41], off offset:2048
	s_waitcnt vmcnt(0) lgkmcnt(0)
	v_pk_add_f32 v[36:37], v[36:37], 1.0 op_sel_hi:[1,0]
	v_pk_add_f32 v[34:35], v[34:35], 1.0 op_sel_hi:[1,0]
	v_pk_mul_f32 v[50:51], v[14:15], v[36:37]
	v_pk_mul_f32 v[52:53], v[12:13], v[34:35]
	global_load_dwordx4 v[34:37], v[38:39], off offset:3072
	s_nop 0
	global_load_dwordx4 v[38:41], v[40:41], off offset:3072
	s_nop 0
	global_load_dwordx2 v[58:59], v[56:57], off
	global_load_dwordx2 v[60:61], v[56:57], off offset:512
	global_load_dwordx2 v[62:63], v[56:57], off offset:1024
	s_nop 0
	global_load_dwordx2 v[56:57], v[56:57], off offset:1536
	s_waitcnt vmcnt(0) lgkmcnt(0)
	v_lshlrev_b32_e32 v64, 16, v58
	v_and_b32_e32 v65, 0xffff0000, v58
	v_lshlrev_b32_e32 v58, 16, v59
	v_and_b32_e32 v59, 0xffff0000, v59
	v_mul_f32_e32 v66, v65, v65
	v_mul_f32_e32 v67, v59, v59
	v_fmac_f32_e32 v66, v64, v64
	v_fmac_f32_e32 v67, v58, v58
	v_add_f32_e32 v68, v66, v67
	v_lshlrev_b32_e32 v66, 16, v60
	v_and_b32_e32 v67, 0xffff0000, v60
	v_lshlrev_b32_e32 v60, 16, v61
	v_and_b32_e32 v61, 0xffff0000, v61
	v_mul_f32_e32 v69, v67, v67
	v_mul_f32_e32 v70, v61, v61
	v_fmac_f32_e32 v69, v66, v66
	v_fmac_f32_e32 v70, v60, v60
	v_add_f32_e32 v69, v69, v70
	v_add_f32_e32 v70, v68, v69
	v_lshlrev_b32_e32 v68, 16, v62
	v_and_b32_e32 v69, 0xffff0000, v62
	v_lshlrev_b32_e32 v62, 16, v63
	v_and_b32_e32 v63, 0xffff0000, v63
	v_mul_f32_e32 v71, v69, v69
	v_mul_f32_e32 v72, v63, v63
	v_fmac_f32_e32 v71, v68, v68
	v_fmac_f32_e32 v72, v62, v62
	v_add_f32_e32 v71, v71, v72
	v_add_f32_e32 v72, v70, v71
	v_lshlrev_b32_e32 v70, 16, v56
	v_and_b32_e32 v71, 0xffff0000, v56
	v_lshlrev_b32_e32 v56, 16, v57
	v_and_b32_e32 v57, 0xffff0000, v57
	v_mul_f32_e32 v73, v71, v71
	v_mul_f32_e32 v74, v57, v57
	v_fmac_f32_e32 v73, v70, v70
	v_fmac_f32_e32 v74, v56, v56
	v_add_f32_e32 v73, v73, v74
	v_add_f32_e32 v72, v72, v73
	ds_swizzle_b32 v73, v72 offset:swizzle(SWAP,1)
	v_pk_add_f32 v[38:39], v[38:39], 1.0 op_sel_hi:[1,0]
	v_pk_add_f32 v[40:41], v[40:41], 1.0 op_sel_hi:[1,0]
	v_pk_mul_f32 v[38:39], v[16:17], v[38:39]
	v_pk_mul_f32 v[40:41], v[18:19], v[40:41]
	s_waitcnt lgkmcnt(0)
	v_add_f32_e32 v72, v72, v73
	ds_swizzle_b32 v73, v72 offset:swizzle(SWAP,2)
	s_waitcnt lgkmcnt(0)
	v_add_f32_e32 v72, v72, v73
	ds_swizzle_b32 v73, v72 offset:swizzle(SWAP,4)
	s_waitcnt lgkmcnt(0)
	v_add_f32_e32 v72, v72, v73
	ds_swizzle_b32 v73, v72 offset:swizzle(SWAP,8)
	s_waitcnt lgkmcnt(0)
	v_add_f32_e32 v72, v72, v73
	ds_swizzle_b32 v73, v72 offset:swizzle(SWAP,16)
	s_waitcnt lgkmcnt(0)
	v_add_f32_e32 v72, v72, v73
	v_mov_b32_e32 v73, v72
	s_nop 1
	v_permlane32_swap_b32_e32 v72, v73
	v_add_f32_e32 v72, v72, v73
	v_fmamk_f32 v72, v72, 0x3a800000, v176
	v_cmp_gt_f32_e32 vcc, s33, v72
	v_mul_f32_e32 v73, 0x4b800000, v72
	s_nop 0
	v_cndmask_b32_e32 v72, v72, v73, vcc
	v_rsq_f32_e32 v72, v72
	s_nop 0
	v_mul_f32_e32 v73, 0x45800000, v72
	v_cndmask_b32_e32 v72, v72, v73, vcc
	v_pk_mul_f32 v[64:65], v[64:65], v[72:73] op_sel_hi:[1,0]
	v_pk_mul_f32 v[58:59], v[58:59], v[72:73] op_sel_hi:[1,0]
	v_pk_fma_f32 v[22:23], v[44:45], v[64:65], v[22:23]
	v_pk_fma_f32 v[24:25], v[42:43], v[58:59], v[24:25]
	v_cvt_pk_bf16_f32 v22, v22, v23
	v_pk_mul_f32 v[42:43], v[60:61], v[72:73] op_sel_hi:[1,0]
	v_cvt_pk_bf16_f32 v23, v24, v25
	v_add_co_u32_e32 v24, vcc, s9, v54
	v_pk_fma_f32 v[28:29], v[46:47], v[42:43], v[28:29]
	s_nop 0
	v_addc_co_u32_e32 v25, vcc, 0, v55, vcc
	global_store_dwordx2 v[24:25], v[22:23], off
	v_pk_mul_f32 v[22:23], v[66:67], v[72:73] op_sel_hi:[1,0]
	s_nop 0
	v_pk_fma_f32 v[22:23], v[48:49], v[22:23], v[26:27]
	v_pk_mul_f32 v[26:27], v[62:63], v[72:73] op_sel_hi:[1,0]
	v_cvt_pk_bf16_f32 v22, v22, v23
	v_cvt_pk_bf16_f32 v23, v28, v29
	global_store_dwordx2 v[24:25], v[22:23], off offset:512
	v_pk_mul_f32 v[22:23], v[68:69], v[72:73] op_sel_hi:[1,0]
	v_pk_fma_f32 v[26:27], v[50:51], v[26:27], v[32:33]
	v_pk_fma_f32 v[22:23], v[52:53], v[22:23], v[30:31]
	s_nop 0
	v_cvt_pk_bf16_f32 v22, v22, v23
	v_cvt_pk_bf16_f32 v23, v26, v27
	global_store_dwordx2 v[24:25], v[22:23], off offset:1024
	v_pk_mul_f32 v[22:23], v[70:71], v[72:73] op_sel_hi:[1,0]
	v_pk_mul_f32 v[26:27], v[56:57], v[72:73] op_sel_hi:[1,0]
	v_pk_fma_f32 v[22:23], v[38:39], v[22:23], v[34:35]
	v_pk_fma_f32 v[26:27], v[40:41], v[26:27], v[36:37]
	v_cvt_pk_bf16_f32 v22, v22, v23
	s_nop 0
	v_cvt_pk_bf16_f32 v23, v26, v27
	global_store_dwordx2 v[24:25], v[22:23], off offset:1536
	s_cbranch_scc1 .LBB0_189

; __device__ __forceinline__ unsigned pk2(float lo, float hi) { unsigned r; asm("v_cvt_pk_bf16_f32 %0, %1, %2" : "=v"(r) : "v"(lo), "v"(hi)); return r; }
; template <int MODE, int NR>
; __device__ __forceinline__ void norm_rows(const float* X32, bf16* X, bf16* H, float* out32, const f32x4 (&mul)[4], const f32x4 (&sh)[4], int lane) {
;     if constexpr (MODE == 1) {
;         f32x4 v[NR][4];
; #pragma unroll
;         for (int r = 0; r < NR; ++r) { const f32x4* xr = (const f32x4*)(X32 + (size_t)r * D) + lane;
; #pragma unroll
;             for (int j = 0; j < 4; ++j) v[r][j] = xr[64 * j]; }
; #pragma unroll
;         for (int r = 0; r < NR; ++r) { float s = 0.f;
; #pragma unroll
;             for (int j = 0; j < 4; ++j) s += (v[r][j].x * v[r][j].x + v[r][j].y * v[r][j].y) + (v[r][j].z * v[r][j].z + v[r][j].w * v[r][j].w);
;             const float rstd = rsqrtf(wave_sum(s) * (1.f / D) + EPS);
;             unsigned long long* o8 = (unsigned long long*)(H + (size_t)r * D) + lane; unsigned long long* x8 = (unsigned long long*)(X + (size_t)r * D) + lane;
; #pragma unroll
;             for (int j = 0; j < 4; ++j) { const f32x4 y = v[r][j] * rstd * mul[j] + sh[j];
;                 x8[64 * j] = (unsigned long long)pk2(v[r][j].x, v[r][j].y) | ((unsigned long long)pk2(v[r][j].z, v[r][j].w) << 32);
;                 o8[64 * j] = (unsigned long long)pk2(y.x, y.y) | ((unsigned long long)pk2(y.z, y.w) << 32); } }
; template <int MODE>
; __device__ __forceinline__ void phase_norm(const float* Xp32, const float* Xs32, bf16* X, bf16* H, const float* nw, const float* mod_sh, const float* mod_sc, int gw, int NGW, int lane) {
;     ...
;     for (int b = gw; b < MP / 8; b += NGW) {
;         const int ci = b >> 8; f32x4 mul[4], sh[4];
;         const size_t ro = (size_t)b * 8 * D;
;         const f32x4* shp = (const f32x4*)(mod_sh + (size_t)ci * MODLD) + lane; const f32x4* scp = (const f32x4*)(mod_sc + (size_t)ci * MODLD) + lane;
;         if constexpr (MODE == 1) {
; #pragma unroll
;             for (int j = 0; j < 4; ++j) { sh[j] = shp[64 * j]; mul[j] = w4[j] * (scp[64 * j] + 1.0f); }
;             norm_rows<MODE, 4>(Xp32 + ro, X + ro, H + ro, nullptr, mul, sh, lane);
;             norm_rows<MODE, 4>(Xp32 + ro + 4 * D, X + ro + 4 * D, H + ro + 4 * D, nullptr, mul, sh, lane);
.LBB0_194:
	s_ashr_i32 s6, s1, 8
	v_mad_i64_i32 v[36:37], s[2:3], s6, v132, v[96:97]
	v_mad_i64_i32 v[38:39], s[2:3], s6, v132, v[98:99]
	global_load_dwordx4 v[32:35], v[36:37], off
	global_load_dwordx4 v[20:23], v[38:39], off
	s_movk_i32 s2, 0x2000
	s_add_i32 s1, s1, s96
	s_cmpk_gt_i32 s1, 0x7ff
	s_waitcnt vmcnt(0) lgkmcnt(0)
	v_pk_add_f32 v[22:23], v[22:23], 1.0 op_sel_hi:[1,0]
	v_pk_add_f32 v[20:21], v[20:21], 1.0 op_sel_hi:[1,0]
	v_pk_mul_f32 v[116:117], v[2:3], v[22:23]
	v_pk_mul_f32 v[118:119], v[0:1], v[20:21]
	global_load_dwordx4 v[28:31], v[36:37], off offset:1024
	global_load_dwordx4 v[20:23], v[38:39], off offset:1024
	s_waitcnt vmcnt(0) lgkmcnt(0)
	v_pk_add_f32 v[22:23], v[22:23], 1.0 op_sel_hi:[1,0]
	v_pk_add_f32 v[20:21], v[20:21], 1.0 op_sel_hi:[1,0]
	v_pk_mul_f32 v[112:113], v[6:7], v[22:23]
	v_pk_mul_f32 v[114:115], v[4:5], v[20:21]
	global_load_dwordx4 v[24:27], v[36:37], off offset:2048
	global_load_dwordx4 v[20:23], v[38:39], off offset:2048
	s_waitcnt vmcnt(0) lgkmcnt(0)
	v_pk_add_f32 v[22:23], v[22:23], 1.0 op_sel_hi:[1,0]
	v_pk_add_f32 v[20:21], v[20:21], 1.0 op_sel_hi:[1,0]
	v_pk_mul_f32 v[108:109], v[14:15], v[22:23]
	v_pk_mul_f32 v[110:111], v[12:13], v[20:21]
	global_load_dwordx4 v[20:23], v[36:37], off offset:3072
	s_nop 0
	global_load_dwordx4 v[36:39], v[38:39], off offset:3072
	s_nop 0
	global_load_dwordx4 v[124:127], v[100:101], off
	global_load_dwordx4 v[92:95], v[100:101], off offset:1024
	global_load_dwordx4 v[88:91], v[100:101], off offset:2048
	global_load_dwordx4 v[84:87], v[100:101], off offset:3072
	s_waitcnt vmcnt(0)
	v_mul_f32_e32 v9, v125, v125
	v_mul_f32_e32 v122, v127, v127
	s_waitcnt lgkmcnt(0)
	v_pk_add_f32 v[36:37], v[36:37], 1.0 op_sel_hi:[1,0]
	v_pk_add_f32 v[38:39], v[38:39], 1.0 op_sel_hi:[1,0]
	v_pk_mul_f32 v[106:107], v[16:17], v[36:37]
	v_add_co_u32_e32 v36, vcc, s35, v100
	v_pk_mul_f32 v[104:105], v[18:19], v[38:39]
	s_nop 0
	v_addc_co_u32_e32 v37, vcc, 0, v101, vcc
	v_add_co_u32_e32 v38, vcc, s2, v100
	v_fmac_f32_e32 v9, v124, v124
	s_nop 0
	v_addc_co_u32_e32 v39, vcc, 0, v101, vcc
	global_load_dwordx4 v[80:83], v[38:39], off offset:-4096
	global_load_dwordx4 v[76:79], v[36:37], off offset:1024
	global_load_dwordx4 v[72:75], v[36:37], off offset:2048
	global_load_dwordx4 v[68:71], v[36:37], off offset:3072
	global_load_dwordx4 v[64:67], v[38:39], off
	global_load_dwordx4 v[60:63], v[38:39], off offset:1024
	global_load_dwordx4 v[56:59], v[38:39], off offset:2048
	global_load_dwordx4 v[52:55], v[38:39], off offset:3072
	v_fmac_f32_e32 v122, v126, v126
	v_add_f32_e32 v9, v9, v122
	v_mul_f32_e32 v122, v93, v93
	v_mul_f32_e32 v123, v95, v95
	v_fmac_f32_e32 v122, v92, v92
	v_fmac_f32_e32 v123, v94, v94
	v_add_f32_e32 v122, v122, v123
	v_add_f32_e32 v9, v9, v122
	v_mul_f32_e32 v122, v89, v89
	v_mul_f32_e32 v123, v91, v91
	v_fmac_f32_e32 v122, v88, v88
	v_fmac_f32_e32 v123, v90, v90
	v_add_f32_e32 v122, v122, v123
	v_add_f32_e32 v9, v9, v122
	v_mul_f32_e32 v122, v85, v85
	v_mul_f32_e32 v123, v87, v87
	v_fmac_f32_e32 v122, v84, v84
	v_fmac_f32_e32 v123, v86, v86
	v_add_f32_e32 v122, v122, v123
	v_add_f32_e32 v9, v9, v122
	ds_swizzle_b32 v122, v9 offset:swizzle(SWAP,1)
	v_add_co_u32_e32 v36, vcc, s36, v100
	s_mov_b32 s2, 0xfbefc200
	s_nop 0
	v_addc_co_u32_e32 v37, vcc, 0, v101, vcc
	s_waitcnt lgkmcnt(0)
	v_add_f32_e32 v9, v9, v122
	ds_swizzle_b32 v122, v9 offset:swizzle(SWAP,2)
	v_add_co_u32_e32 v120, vcc, s51, v100
	s_waitcnt lgkmcnt(0)
	v_add_f32_e32 v9, v9, v122
	ds_swizzle_b32 v122, v9 offset:swizzle(SWAP,4)
	v_addc_co_u32_e32 v121, vcc, 0, v101, vcc
	global_load_dwordx4 v[48:51], v[120:121], off offset:-4096
	global_load_dwordx4 v[44:47], v[36:37], off offset:1024
	global_load_dwordx4 v[40:43], v[36:37], off offset:2048
	s_nop 0
	global_load_dwordx4 v[36:39], v[36:37], off offset:3072
	s_waitcnt lgkmcnt(0)
	v_add_f32_e32 v9, v9, v122
	ds_swizzle_b32 v122, v9 offset:swizzle(SWAP,8)
	s_waitcnt lgkmcnt(0)
	v_add_f32_e32 v9, v9, v122
	ds_swizzle_b32 v122, v9 offset:swizzle(SWAP,16)
	s_waitcnt lgkmcnt(0)
	v_add_f32_e32 v9, v9, v122
	v_mov_b32_e32 v122, v9
	s_nop 1
	v_permlane32_swap_b32_e32 v9, v122
	v_add_f32_e32 v9, v9, v122
	v_fmamk_f32 v9, v9, 0x3a800000, v176
	v_cmp_gt_f32_e32 vcc, s33, v9
	v_mul_f32_e32 v122, 0x4b800000, v9
	s_nop 0
	v_cndmask_b32_e32 v9, v9, v122, vcc
	v_rsq_f32_e32 v9, v9
	s_nop 0
	v_mul_f32_e32 v122, 0x45800000, v9
	v_cndmask_b32_e32 v122, v9, v122, vcc
	v_pk_mul_f32 v[128:129], v[124:125], v[122:123] op_sel_hi:[1,0]
	v_pk_mul_f32 v[130:131], v[126:127], v[122:123] op_sel_hi:[1,0]
	v_cvt_pk_bf16_f32 v124, v124, v125
	v_cvt_pk_bf16_f32 v125, v126, v127
	v_add_co_u32_e32 v126, vcc, s2, v102
	v_pk_fma_f32 v[130:131], v[116:117], v[130:131], v[34:35]
	s_nop 0
	v_addc_co_u32_e32 v127, vcc, -1, v103, vcc
	global_store_dwordx2 v[126:127], v[124:125], off
	v_add_co_u32_e32 v126, vcc, s7, v102
	v_pk_fma_f32 v[128:129], v[118:119], v[128:129], v[32:33]
	v_cvt_pk_bf16_f32 v125, v130, v131
	s_nop 0
	v_addc_co_u32_e32 v127, vcc, -1, v103, vcc
	v_cvt_pk_bf16_f32 v124, v128, v129
	s_mov_b32 s2, 0xfbefc400
	global_store_dwordx2 v[126:127], v[124:125], off
	v_pk_mul_f32 v[124:125], v[92:93], v[122:123] op_sel_hi:[1,0]
	v_pk_mul_f32 v[126:127], v[94:95], v[122:123] op_sel_hi:[1,0]
	v_cvt_pk_bf16_f32 v92, v92, v93
	v_cvt_pk_bf16_f32 v93, v94, v95
	v_add_co_u32_e32 v94, vcc, s2, v102
	v_pk_fma_f32 v[126:127], v[112:113], v[126:127], v[30:31]
	s_nop 0
	v_addc_co_u32_e32 v95, vcc, -1, v103, vcc
	global_store_dwordx2 v[94:95], v[92:93], off
	v_add_co_u32_e32 v94, vcc, s12, v102
	v_pk_fma_f32 v[124:125], v[114:115], v[124:125], v[28:29]
	v_cvt_pk_bf16_f32 v93, v126, v127
	s_nop 0
; __device__ __forceinline__ unsigned pk2(float lo, float hi) { unsigned r; asm("v_cvt_pk_bf16_f32 %0, %1, %2" : "=v"(r) : "v"(lo), "v"(hi)); return r; }
; template <int MODE, int NR>
; __device__ __forceinline__ void norm_rows(const float* X32, bf16* X, bf16* H, float* out32, const f32x4 (&mul)[4], const f32x4 (&sh)[4], int lane) {
;     if constexpr (MODE == 1) {
;         f32x4 v[NR][4];
; #pragma unroll
;         for (int r = 0; r < NR; ++r) { const f32x4* xr = (const f32x4*)(X32 + (size_t)r * D) + lane;
; #pragma unroll
;             for (int j = 0; j < 4; ++j) v[r][j] = xr[64 * j]; }
; #pragma unroll
;         for (int r = 0; r < NR; ++r) { float s = 0.f;
; #pragma unroll
;             for (int j = 0; j < 4; ++j) s += (v[r][j].x * v[r][j].x + v[r][j].y * v[r][j].y) + (v[r][j].z * v[r][j].z + v[r][j].w * v[r][j].w);
;             const float rstd = rsqrtf(wave_sum(s) * (1.f / D) + EPS);
;             unsigned long long* o8 = (unsigned long long*)(H + (size_t)r * D) + lane; unsigned long long* x8 = (unsigned long long*)(X + (size_t)r * D) + lane;
; #pragma unroll
;             for (int j = 0; j < 4; ++j) { const f32x4 y = v[r][j] * rstd * mul[j] + sh[j];
;                 x8[64 * j] = (unsigned long long)pk2(v[r][j].x, v[r][j].y) | ((unsigned long long)pk2(v[r][j].z, v[r][j].w) << 32);
;                 o8[64 * j] = (unsigned long long)pk2(y.x, y.y) | ((unsigned long long)pk2(y.z, y.w) << 32); } }
	v_addc_co_u32_e32 v95, vcc, -1, v103, vcc
	v_cvt_pk_bf16_f32 v92, v124, v125
	s_mov_b32 s2, 0xfbefc600
	global_store_dwordx2 v[94:95], v[92:93], off
	v_pk_mul_f32 v[92:93], v[88:89], v[122:123] op_sel_hi:[1,0]
	v_pk_mul_f32 v[94:95], v[90:91], v[122:123] op_sel_hi:[1,0]
	v_cvt_pk_bf16_f32 v88, v88, v89
	v_cvt_pk_bf16_f32 v89, v90, v91
	v_add_co_u32_e32 v90, vcc, s2, v102
	v_pk_fma_f32 v[94:95], v[108:109], v[94:95], v[26:27]
	s_nop 0
	v_addc_co_u32_e32 v91, vcc, -1, v103, vcc
	global_store_dwordx2 v[90:91], v[88:89], off
	v_add_co_u32_e32 v90, vcc, s13, v102
	v_pk_fma_f32 v[92:93], v[110:111], v[92:93], v[24:25]
	v_cvt_pk_bf16_f32 v89, v94, v95
	s_nop 0
	v_addc_co_u32_e32 v91, vcc, -1, v103, vcc
	v_cvt_pk_bf16_f32 v88, v92, v93
	s_mov_b32 s2, 0xfbefc800
	global_store_dwordx2 v[90:91], v[88:89], off
	v_pk_mul_f32 v[88:89], v[84:85], v[122:123] op_sel_hi:[1,0]
	v_pk_mul_f32 v[90:91], v[86:87], v[122:123] op_sel_hi:[1,0]
	v_cvt_pk_bf16_f32 v84, v84, v85
	v_cvt_pk_bf16_f32 v85, v86, v87
	v_add_co_u32_e32 v86, vcc, s2, v102
	v_pk_fma_f32 v[88:89], v[106:107], v[88:89], v[20:21]
	s_nop 0
	v_addc_co_u32_e32 v87, vcc, -1, v103, vcc
	global_store_dwordx2 v[86:87], v[84:85], off
	v_add_co_u32_e32 v86, vcc, s14, v102
	v_cvt_pk_bf16_f32 v84, v88, v89
	v_pk_fma_f32 v[90:91], v[104:105], v[90:91], v[22:23]
	s_nop 0
	v_addc_co_u32_e32 v87, vcc, -1, v103, vcc
	v_cvt_pk_bf16_f32 v85, v90, v91
	global_store_dwordx2 v[86:87], v[84:85], off
	s_waitcnt vmcnt(0)
	v_mul_f32_e32 v9, v81, v81
	v_mul_f32_e32 v84, v83, v83
	v_fmac_f32_e32 v9, v80, v80
	v_fmac_f32_e32 v84, v82, v82
	v_add_f32_e32 v9, v9, v84
	v_mul_f32_e32 v84, v77, v77
	v_mul_f32_e32 v85, v79, v79
	v_fmac_f32_e32 v84, v76, v76
	v_fmac_f32_e32 v85, v78, v78
	v_add_f32_e32 v84, v84, v85
	v_add_f32_e32 v9, v9, v84
	v_mul_f32_e32 v84, v73, v73
	v_mul_f32_e32 v85, v75, v75
	v_fmac_f32_e32 v84, v72, v72
	v_fmac_f32_e32 v85, v74, v74
	v_add_f32_e32 v84, v84, v85
	v_add_f32_e32 v9, v9, v84
	v_mul_f32_e32 v84, v69, v69
	v_mul_f32_e32 v85, v71, v71
	v_fmac_f32_e32 v84, v68, v68
	v_fmac_f32_e32 v85, v70, v70
	v_add_f32_e32 v84, v84, v85
	v_add_f32_e32 v9, v9, v84
	ds_swizzle_b32 v84, v9 offset:swizzle(SWAP,1)
	s_mov_b32 s2, 0xfbefca00
	s_waitcnt lgkmcnt(0)
	v_add_f32_e32 v9, v9, v84
	ds_swizzle_b32 v84, v9 offset:swizzle(SWAP,2)
	s_waitcnt lgkmcnt(0)
	v_add_f32_e32 v9, v9, v84
	ds_swizzle_b32 v84, v9 offset:swizzle(SWAP,4)
	s_waitcnt lgkmcnt(0)
	v_add_f32_e32 v9, v9, v84
	ds_swizzle_b32 v84, v9 offset:swizzle(SWAP,8)
	s_waitcnt lgkmcnt(0)
	v_add_f32_e32 v9, v9, v84
	ds_swizzle_b32 v84, v9 offset:swizzle(SWAP,16)
	s_waitcnt lgkmcnt(0)
	v_add_f32_e32 v9, v9, v84
	v_mov_b32_e32 v84, v9
	s_nop 1
	v_permlane32_swap_b32_e32 v9, v84
	v_add_f32_e32 v9, v9, v84
	v_fmamk_f32 v9, v9, 0x3a800000, v176
	v_cmp_gt_f32_e32 vcc, s33, v9
	v_mul_f32_e32 v84, 0x4b800000, v9
	s_nop 0
	v_cndmask_b32_e32 v9, v9, v84, vcc
	v_rsq_f32_e32 v9, v9
	s_nop 0
	v_mul_f32_e32 v84, 0x45800000, v9
	v_cndmask_b32_e32 v84, v9, v84, vcc
	v_pk_mul_f32 v[86:87], v[80:81], v[84:85] op_sel_hi:[1,0]
	v_pk_mul_f32 v[88:89], v[82:83], v[84:85] op_sel_hi:[1,0]
	v_cvt_pk_bf16_f32 v80, v80, v81
	v_cvt_pk_bf16_f32 v81, v82, v83
	v_add_co_u32_e32 v82, vcc, s2, v102
	v_pk_fma_f32 v[88:89], v[116:117], v[88:89], v[34:35]
	s_nop 0
	v_addc_co_u32_e32 v83, vcc, -1, v103, vcc
	global_store_dwordx2 v[82:83], v[80:81], off
	v_add_co_u32_e32 v82, vcc, s15, v102
	v_pk_fma_f32 v[86:87], v[118:119], v[86:87], v[32:33]
	v_cvt_pk_bf16_f32 v81, v88, v89
	s_nop 0
	v_addc_co_u32_e32 v83, vcc, -1, v103, vcc
	v_cvt_pk_bf16_f32 v80, v86, v87
	s_mov_b32 s2, 0xfbefcc00
	global_store_dwordx2 v[82:83], v[80:81], off
	v_pk_mul_f32 v[80:81], v[76:77], v[84:85] op_sel_hi:[1,0]
	v_pk_mul_f32 v[82:83], v[78:79], v[84:85] op_sel_hi:[1,0]
	v_cvt_pk_bf16_f32 v76, v76, v77
	v_cvt_pk_bf16_f32 v77, v78, v79
	v_add_co_u32_e32 v78, vcc, s2, v102
	v_pk_fma_f32 v[82:83], v[112:113], v[82:83], v[30:31]
	s_nop 0
	v_addc_co_u32_e32 v79, vcc, -1, v103, vcc
	global_store_dwordx2 v[78:79], v[76:77], off
	v_add_co_u32_e32 v78, vcc, s16, v102
	v_pk_fma_f32 v[80:81], v[114:115], v[80:81], v[28:29]
	v_cvt_pk_bf16_f32 v77, v82, v83
	s_nop 0
	v_addc_co_u32_e32 v79, vcc, -1, v103, vcc
	v_cvt_pk_bf16_f32 v76, v80, v81
	s_mov_b32 s2, 0xfbefce00
	global_store_dwordx2 v[78:79], v[76:77], off
	v_pk_mul_f32 v[76:77], v[72:73], v[84:85] op_sel_hi:[1,0]
	v_pk_mul_f32 v[78:79], v[74:75], v[84:85] op_sel_hi:[1,0]
	v_cvt_pk_bf16_f32 v72, v72, v73
	v_cvt_pk_bf16_f32 v73, v74, v75
	v_add_co_u32_e32 v74, vcc, s2, v102
	v_pk_fma_f32 v[78:79], v[108:109], v[78:79], v[26:27]
	s_nop 0
	v_addc_co_u32_e32 v75, vcc, -1, v103, vcc
	global_store_dwordx2 v[74:75], v[72:73], off
	v_add_co_u32_e32 v74, vcc, s17, v102
	v_pk_fma_f32 v[76:77], v[110:111], v[76:77], v[24:25]
	v_cvt_pk_bf16_f32 v73, v78, v79
	s_nop 0
	v_addc_co_u32_e32 v75, vcc, -1, v103, vcc
	v_cvt_pk_bf16_f32 v72, v76, v77
	s_mov_b32 s2, 0xfbefd000
	global_store_dwordx2 v[74:75], v[72:73], off
	v_pk_mul_f32 v[72:73], v[68:69], v[84:85] op_sel_hi:[1,0]
	v_pk_mul_f32 v[74:75], v[70:71], v[84:85] op_sel_hi:[1,0]
	v_cvt_pk_bf16_f32 v68, v68, v69
	v_cvt_pk_bf16_f32 v69, v70, v71
	v_add_co_u32_e32 v70, vcc, s2, v102
	v_pk_fma_f32 v[72:73], v[106:107], v[72:73], v[20:21]
	s_nop 0
	v_addc_co_u32_e32 v71, vcc, -1, v103, vcc
	global_store_dwordx2 v[70:71], v[68:69], off
	v_add_co_u32_e32 v70, vcc, s18, v102
	v_cvt_pk_bf16_f32 v68, v72, v73
	v_pk_fma_f32 v[74:75], v[104:105], v[74:75], v[22:23]
	s_nop 0
	v_addc_co_u32_e32 v71, vcc, -1, v103, vcc
	v_cvt_pk_bf16_f32 v69, v74, v75
	global_store_dwordx2 v[70:71], v[68:69], off
	v_mul_f32_e32 v9, v65, v65
	v_mul_f32_e32 v68, v67, v67
	v_fmac_f32_e32 v9, v64, v64
	v_fmac_f32_e32 v68, v66, v66
	v_add_f32_e32 v9, v9, v68
	v_mul_f32_e32 v68, v61, v61
	v_mul_f32_e32 v69, v63, v63
	v_fmac_f32_e32 v68, v60, v60
	v_fmac_f32_e32 v69, v62, v62
	v_add_f32_e32 v68, v68, v69
	v_add_f32_e32 v9, v9, v68
	v_mul_f32_e32 v68, v57, v57
	v_mul_f32_e32 v69, v59, v59
	v_fmac_f32_e32 v68, v56, v56
	v_fmac_f32_e32 v69, v58, v58
	v_add_f32_e32 v68, v68, v69
	v_add_f32_e32 v9, v9, v68
	v_mul_f32_e32 v68, v53, v53
	v_mul_f32_e32 v69, v55, v55
	v_fmac_f32_e32 v68, v52, v52
	v_fmac_f32_e32 v69, v54, v54
	v_add_f32_e32 v68, v68, v69
	v_add_f32_e32 v9, v9, v68
	ds_swizzle_b32 v68, v9 offset:swizzle(SWAP,1)
	s_mov_b32 s2, 0xfbefd200
	s_waitcnt lgkmcnt(0)
; __device__ __forceinline__ unsigned pk2(float lo, float hi) { unsigned r; asm("v_cvt_pk_bf16_f32 %0, %1, %2" : "=v"(r) : "v"(lo), "v"(hi)); return r; }
; template <int MODE, int NR>
; __device__ __forceinline__ void norm_rows(const float* X32, bf16* X, bf16* H, float* out32, const f32x4 (&mul)[4], const f32x4 (&sh)[4], int lane) {
;     if constexpr (MODE == 1) {
;         f32x4 v[NR][4];
; #pragma unroll
;         for (int r = 0; r < NR; ++r) { const f32x4* xr = (const f32x4*)(X32 + (size_t)r * D) + lane;
; #pragma unroll
;             for (int j = 0; j < 4; ++j) v[r][j] = xr[64 * j]; }
; #pragma unroll
;         for (int r = 0; r < NR; ++r) { float s = 0.f;
; #pragma unroll
;             for (int j = 0; j < 4; ++j) s += (v[r][j].x * v[r][j].x + v[r][j].y * v[r][j].y) + (v[r][j].z * v[r][j].z + v[r][j].w * v[r][j].w);
;             const float rstd = rsqrtf(wave_sum(s) * (1.f / D) + EPS);
;             unsigned long long* o8 = (unsigned long long*)(H + (size_t)r * D) + lane; unsigned long long* x8 = (unsigned long long*)(X + (size_t)r * D) + lane;
; #pragma unroll
;             for (int j = 0; j < 4; ++j) { const f32x4 y = v[r][j] * rstd * mul[j] + sh[j];
;                 x8[64 * j] = (unsigned long long)pk2(v[r][j].x, v[r][j].y) | ((unsigned long long)pk2(v[r][j].z, v[r][j].w) << 32);
;                 o8[64 * j] = (unsigned long long)pk2(y.x, y.y) | ((unsigned long long)pk2(y.z, y.w) << 32); } }
	v_add_f32_e32 v9, v9, v68
	ds_swizzle_b32 v68, v9 offset:swizzle(SWAP,2)
	s_waitcnt lgkmcnt(0)
	v_add_f32_e32 v9, v9, v68
	ds_swizzle_b32 v68, v9 offset:swizzle(SWAP,4)
	s_waitcnt lgkmcnt(0)
	v_add_f32_e32 v9, v9, v68
	ds_swizzle_b32 v68, v9 offset:swizzle(SWAP,8)
	s_waitcnt lgkmcnt(0)
	v_add_f32_e32 v9, v9, v68
	ds_swizzle_b32 v68, v9 offset:swizzle(SWAP,16)
	s_waitcnt lgkmcnt(0)
	v_add_f32_e32 v9, v9, v68
	v_mov_b32_e32 v68, v9
	s_nop 1
	v_permlane32_swap_b32_e32 v9, v68
	v_add_f32_e32 v9, v9, v68
	v_fmamk_f32 v9, v9, 0x3a800000, v176
	v_cmp_gt_f32_e32 vcc, s33, v9
	v_mul_f32_e32 v68, 0x4b800000, v9
	s_nop 0
	v_cndmask_b32_e32 v9, v9, v68, vcc
	v_rsq_f32_e32 v9, v9
	s_nop 0
	v_mul_f32_e32 v68, 0x45800000, v9
	v_cndmask_b32_e32 v68, v9, v68, vcc
	v_pk_mul_f32 v[70:71], v[64:65], v[68:69] op_sel_hi:[1,0]
	v_pk_mul_f32 v[72:73], v[66:67], v[68:69] op_sel_hi:[1,0]
	v_cvt_pk_bf16_f32 v64, v64, v65
	v_cvt_pk_bf16_f32 v65, v66, v67
	v_add_co_u32_e32 v66, vcc, s2, v102
	v_pk_fma_f32 v[72:73], v[116:117], v[72:73], v[34:35]
	s_nop 0
	v_addc_co_u32_e32 v67, vcc, -1, v103, vcc
	global_store_dwordx2 v[66:67], v[64:65], off
	v_add_co_u32_e32 v66, vcc, s37, v102
	v_pk_fma_f32 v[70:71], v[118:119], v[70:71], v[32:33]
	v_cvt_pk_bf16_f32 v65, v72, v73
	s_nop 0
	v_addc_co_u32_e32 v67, vcc, -1, v103, vcc
	v_cvt_pk_bf16_f32 v64, v70, v71
	s_mov_b32 s2, 0xfbefd400
	global_store_dwordx2 v[66:67], v[64:65], off
	v_pk_mul_f32 v[64:65], v[60:61], v[68:69] op_sel_hi:[1,0]
	v_pk_mul_f32 v[66:67], v[62:63], v[68:69] op_sel_hi:[1,0]
	v_cvt_pk_bf16_f32 v60, v60, v61
	v_cvt_pk_bf16_f32 v61, v62, v63
	v_add_co_u32_e32 v62, vcc, s2, v102
	v_pk_fma_f32 v[66:67], v[112:113], v[66:67], v[30:31]
	s_nop 0
	v_addc_co_u32_e32 v63, vcc, -1, v103, vcc
	global_store_dwordx2 v[62:63], v[60:61], off
	v_add_co_u32_e32 v62, vcc, s50, v102
	v_pk_fma_f32 v[64:65], v[114:115], v[64:65], v[28:29]
	v_cvt_pk_bf16_f32 v61, v66, v67
	s_nop 0
	v_addc_co_u32_e32 v63, vcc, -1, v103, vcc
	v_cvt_pk_bf16_f32 v60, v64, v65
	s_mov_b32 s2, 0xfbefd600
	global_store_dwordx2 v[62:63], v[60:61], off
	v_pk_mul_f32 v[60:61], v[56:57], v[68:69] op_sel_hi:[1,0]
	v_pk_mul_f32 v[62:63], v[58:59], v[68:69] op_sel_hi:[1,0]
	v_cvt_pk_bf16_f32 v56, v56, v57
	v_cvt_pk_bf16_f32 v57, v58, v59
	v_add_co_u32_e32 v58, vcc, s2, v102
	v_pk_fma_f32 v[62:63], v[108:109], v[62:63], v[26:27]
	s_nop 0
	v_addc_co_u32_e32 v59, vcc, -1, v103, vcc
	global_store_dwordx2 v[58:59], v[56:57], off
	v_add_co_u32_e32 v58, vcc, s58, v102
	v_pk_fma_f32 v[60:61], v[110:111], v[60:61], v[24:25]
	v_cvt_pk_bf16_f32 v57, v62, v63
	s_nop 0
	v_addc_co_u32_e32 v59, vcc, -1, v103, vcc
	v_cvt_pk_bf16_f32 v56, v60, v61
	s_mov_b32 s2, 0xfbefd800
	global_store_dwordx2 v[58:59], v[56:57], off
	v_pk_mul_f32 v[56:57], v[52:53], v[68:69] op_sel_hi:[1,0]
	v_pk_mul_f32 v[58:59], v[54:55], v[68:69] op_sel_hi:[1,0]
	v_cvt_pk_bf16_f32 v52, v52, v53
	v_cvt_pk_bf16_f32 v53, v54, v55
	v_add_co_u32_e32 v54, vcc, s2, v102
	v_pk_fma_f32 v[56:57], v[106:107], v[56:57], v[20:21]
	s_nop 0
	v_addc_co_u32_e32 v55, vcc, -1, v103, vcc
	global_store_dwordx2 v[54:55], v[52:53], off
	v_add_co_u32_e32 v54, vcc, s59, v102
	v_cvt_pk_bf16_f32 v52, v56, v57
	v_pk_fma_f32 v[58:59], v[104:105], v[58:59], v[22:23]
	s_nop 0
	v_addc_co_u32_e32 v55, vcc, -1, v103, vcc
	v_cvt_pk_bf16_f32 v53, v58, v59
	global_store_dwordx2 v[54:55], v[52:53], off
	v_mul_f32_e32 v9, v49, v49
	v_mul_f32_e32 v52, v51, v51
	v_fmac_f32_e32 v9, v48, v48
	v_fmac_f32_e32 v52, v50, v50
	v_add_f32_e32 v9, v9, v52
	v_mul_f32_e32 v52, v45, v45
	v_mul_f32_e32 v53, v47, v47
	v_fmac_f32_e32 v52, v44, v44
	v_fmac_f32_e32 v53, v46, v46
	v_add_f32_e32 v52, v52, v53
	v_add_f32_e32 v9, v9, v52
	v_mul_f32_e32 v52, v41, v41
	v_mul_f32_e32 v53, v43, v43
	v_fmac_f32_e32 v52, v40, v40
	v_fmac_f32_e32 v53, v42, v42
	v_add_f32_e32 v52, v52, v53
	v_add_f32_e32 v9, v9, v52
	v_mul_f32_e32 v52, v37, v37
	v_mul_f32_e32 v53, v39, v39
	v_fmac_f32_e32 v52, v36, v36
	v_fmac_f32_e32 v53, v38, v38
	v_add_f32_e32 v52, v52, v53
	v_add_f32_e32 v9, v9, v52
	ds_swizzle_b32 v52, v9 offset:swizzle(SWAP,1)
	s_mov_b32 s2, 0xfbefda00
	s_waitcnt lgkmcnt(0)
	v_add_f32_e32 v9, v9, v52
	ds_swizzle_b32 v52, v9 offset:swizzle(SWAP,2)
	s_waitcnt lgkmcnt(0)
	v_add_f32_e32 v9, v9, v52
	ds_swizzle_b32 v52, v9 offset:swizzle(SWAP,4)
	s_waitcnt lgkmcnt(0)
	v_add_f32_e32 v9, v9, v52
	ds_swizzle_b32 v52, v9 offset:swizzle(SWAP,8)
	s_waitcnt lgkmcnt(0)
	v_add_f32_e32 v9, v9, v52
	ds_swizzle_b32 v52, v9 offset:swizzle(SWAP,16)
	s_waitcnt lgkmcnt(0)
; __device__ __forceinline__ unsigned pk2(float lo, float hi) { unsigned r; asm("v_cvt_pk_bf16_f32 %0, %1, %2" : "=v"(r) : "v"(lo), "v"(hi)); return r; }
; template <int MODE, int NR>
; __device__ __forceinline__ void norm_rows(const float* X32, bf16* X, bf16* H, float* out32, const f32x4 (&mul)[4], const f32x4 (&sh)[4], int lane) {
;     if constexpr (MODE == 1) {
;         f32x4 v[NR][4];
; #pragma unroll
;         for (int r = 0; r < NR; ++r) { const f32x4* xr = (const f32x4*)(X32 + (size_t)r * D) + lane;
; #pragma unroll
;             for (int j = 0; j < 4; ++j) v[r][j] = xr[64 * j]; }
; #pragma unroll
;         for (int r = 0; r < NR; ++r) { float s = 0.f;
; #pragma unroll
;             for (int j = 0; j < 4; ++j) s += (v[r][j].x * v[r][j].x + v[r][j].y * v[r][j].y) + (v[r][j].z * v[r][j].z + v[r][j].w * v[r][j].w);
;             const float rstd = rsqrtf(wave_sum(s) * (1.f / D) + EPS);
;             unsigned long long* o8 = (unsigned long long*)(H + (size_t)r * D) + lane; unsigned long long* x8 = (unsigned long long*)(X + (size_t)r * D) + lane;
; #pragma unroll
;             for (int j = 0; j < 4; ++j) { const f32x4 y = v[r][j] * rstd * mul[j] + sh[j];
;                 x8[64 * j] = (unsigned long long)pk2(v[r][j].x, v[r][j].y) | ((unsigned long long)pk2(v[r][j].z, v[r][j].w) << 32);
;                 o8[64 * j] = (unsigned long long)pk2(y.x, y.y) | ((unsigned long long)pk2(y.z, y.w) << 32); } }
	v_add_f32_e32 v9, v9, v52
	v_mov_b32_e32 v52, v9
	s_nop 1
	v_permlane32_swap_b32_e32 v9, v52
	v_add_f32_e32 v9, v9, v52
	v_fmamk_f32 v9, v9, 0x3a800000, v176
	v_cmp_gt_f32_e32 vcc, s33, v9
	v_mul_f32_e32 v52, 0x4b800000, v9
	s_nop 0
	v_cndmask_b32_e32 v9, v9, v52, vcc
	v_rsq_f32_e32 v9, v9
	s_nop 0
	v_mul_f32_e32 v52, 0x45800000, v9
	v_cndmask_b32_e32 v52, v9, v52, vcc
	v_pk_mul_f32 v[54:55], v[48:49], v[52:53] op_sel_hi:[1,0]
	v_pk_mul_f32 v[56:57], v[50:51], v[52:53] op_sel_hi:[1,0]
	v_cvt_pk_bf16_f32 v48, v48, v49
	v_cvt_pk_bf16_f32 v49, v50, v51
	v_add_co_u32_e32 v50, vcc, s2, v102
	v_pk_fma_f32 v[56:57], v[116:117], v[56:57], v[34:35]
	s_nop 0
	v_addc_co_u32_e32 v51, vcc, -1, v103, vcc
	global_store_dwordx2 v[50:51], v[48:49], off
	v_add_co_u32_e32 v50, vcc, s62, v102
	v_pk_fma_f32 v[54:55], v[118:119], v[54:55], v[32:33]
	v_cvt_pk_bf16_f32 v49, v56, v57
	s_nop 0
	v_addc_co_u32_e32 v51, vcc, -1, v103, vcc
	v_cvt_pk_bf16_f32 v48, v54, v55
	s_mov_b32 s2, 0xfbefdc00
	global_store_dwordx2 v[50:51], v[48:49], off
	v_pk_mul_f32 v[48:49], v[44:45], v[52:53] op_sel_hi:[1,0]
	v_pk_mul_f32 v[50:51], v[46:47], v[52:53] op_sel_hi:[1,0]
	v_cvt_pk_bf16_f32 v44, v44, v45
	v_cvt_pk_bf16_f32 v45, v46, v47
	v_add_co_u32_e32 v46, vcc, s2, v102
	v_pk_fma_f32 v[50:51], v[112:113], v[50:51], v[30:31]
	s_nop 0
	v_addc_co_u32_e32 v47, vcc, -1, v103, vcc
	global_store_dwordx2 v[46:47], v[44:45], off
	v_add_co_u32_e32 v46, vcc, s63, v102
	v_pk_fma_f32 v[48:49], v[114:115], v[48:49], v[28:29]
	v_cvt_pk_bf16_f32 v45, v50, v51
	s_nop 0
	v_addc_co_u32_e32 v47, vcc, -1, v103, vcc
	v_cvt_pk_bf16_f32 v44, v48, v49
	s_mov_b32 s2, 0xfbefde00
	global_store_dwordx2 v[46:47], v[44:45], off
	v_pk_mul_f32 v[44:45], v[40:41], v[52:53] op_sel_hi:[1,0]
	v_pk_mul_f32 v[46:47], v[42:43], v[52:53] op_sel_hi:[1,0]
	v_cvt_pk_bf16_f32 v40, v40, v41
	v_cvt_pk_bf16_f32 v41, v42, v43
	v_add_co_u32_e32 v42, vcc, s2, v102
	v_pk_fma_f32 v[46:47], v[108:109], v[46:47], v[26:27]
	s_nop 0
	v_addc_co_u32_e32 v43, vcc, -1, v103, vcc
	global_store_dwordx2 v[42:43], v[40:41], off
	v_add_co_u32_e32 v42, vcc, s64, v102
	v_pk_fma_f32 v[44:45], v[110:111], v[44:45], v[24:25]
	v_cvt_pk_bf16_f32 v41, v46, v47
	s_nop 0
	v_addc_co_u32_e32 v43, vcc, -1, v103, vcc
	v_cvt_pk_bf16_f32 v40, v44, v45
	s_mov_b32 s2, 0xfbefe000
	global_store_dwordx2 v[42:43], v[40:41], off
	v_pk_mul_f32 v[40:41], v[36:37], v[52:53] op_sel_hi:[1,0]
	v_pk_mul_f32 v[42:43], v[38:39], v[52:53] op_sel_hi:[1,0]
	v_cvt_pk_bf16_f32 v36, v36, v37
	v_cvt_pk_bf16_f32 v37, v38, v39
	v_add_co_u32_e32 v38, vcc, s2, v102
	v_pk_fma_f32 v[42:43], v[104:105], v[42:43], v[22:23]
	s_nop 0
	v_addc_co_u32_e32 v39, vcc, -1, v103, vcc
	global_store_dwordx2 v[38:39], v[36:37], off
	v_add_co_u32_e32 v38, vcc, s66, v102
	v_pk_fma_f32 v[40:41], v[106:107], v[40:41], v[20:21]
	s_nop 0
	v_addc_co_u32_e32 v39, vcc, -1, v103, vcc
	v_cvt_pk_bf16_f32 v36, v40, v41
	v_cvt_pk_bf16_f32 v37, v42, v43
	global_store_dwordx2 v[38:39], v[36:37], off
	global_load_dwordx4 v[122:125], v[120:121], off
	global_load_dwordx4 v[92:95], v[120:121], off offset:1024
	global_load_dwordx4 v[88:91], v[120:121], off offset:2048
	global_load_dwordx4 v[84:87], v[120:121], off offset:3072
	s_movk_i32 s2, 0x5000
	v_add_co_u32_e32 v36, vcc, s2, v100
	s_movk_i32 s2, 0x6000
	s_nop 0
	v_addc_co_u32_e32 v37, vcc, 0, v101, vcc
	v_add_co_u32_e32 v38, vcc, s2, v100
	s_movk_i32 s2, 0x7000
	s_nop 0
	v_addc_co_u32_e32 v39, vcc, 0, v101, vcc
	global_load_dwordx4 v[80:83], v[38:39], off offset:-4096
	global_load_dwordx4 v[76:79], v[36:37], off offset:1024
	global_load_dwordx4 v[72:75], v[36:37], off offset:2048
	global_load_dwordx4 v[68:71], v[36:37], off offset:3072
	global_load_dwordx4 v[64:67], v[38:39], off
	global_load_dwordx4 v[60:63], v[38:39], off offset:1024
	global_load_dwordx4 v[56:59], v[38:39], off offset:2048
	global_load_dwordx4 v[52:55], v[38:39], off offset:3072
	v_add_co_u32_e32 v36, vcc, s2, v100
	s_mov_b32 s2, 0xfbefe200
	s_nop 0
	v_addc_co_u32_e32 v37, vcc, 0, v101, vcc
	global_load_dwordx4 v[48:51], v[36:37], off
	global_load_dwordx4 v[44:47], v[36:37], off offset:1024
	global_load_dwordx4 v[40:43], v[36:37], off offset:2048
	s_nop 0
	global_load_dwordx4 v[36:39], v[36:37], off offset:3072
	v_lshl_add_u64 v[100:101], v[100:101], 0, s[10:11]
	s_waitcnt vmcnt(0)
	v_mul_f32_e32 v9, v123, v123
	v_mul_f32_e32 v120, v125, v125
	v_fmac_f32_e32 v9, v122, v122
	v_fmac_f32_e32 v120, v124, v124
	v_add_f32_e32 v9, v9, v120
	v_mul_f32_e32 v120, v93, v93
	v_mul_f32_e32 v121, v95, v95
	v_fmac_f32_e32 v120, v92, v92
	v_fmac_f32_e32 v121, v94, v94
	v_add_f32_e32 v120, v120, v121
	v_add_f32_e32 v9, v9, v120
	v_mul_f32_e32 v120, v89, v89
	v_mul_f32_e32 v121, v91, v91
	v_fmac_f32_e32 v120, v88, v88
	v_fmac_f32_e32 v121, v90, v90
	v_add_f32_e32 v120, v120, v121
	v_add_f32_e32 v9, v9, v120
	v_mul_f32_e32 v120, v85, v85
	v_mul_f32_e32 v121, v87, v87
	v_fmac_f32_e32 v120, v84, v84
	v_fmac_f32_e32 v121, v86, v86
	v_add_f32_e32 v120, v120, v121
	v_add_f32_e32 v9, v9, v120
	ds_swizzle_b32 v120, v9 offset:swizzle(SWAP,1)
	s_waitcnt lgkmcnt(0)
	v_add_f32_e32 v9, v9, v120
	ds_swizzle_b32 v120, v9 offset:swizzle(SWAP,2)
	s_waitcnt lgkmcnt(0)
	v_add_f32_e32 v9, v9, v120
	ds_swizzle_b32 v120, v9 offset:swizzle(SWAP,4)
	s_waitcnt lgkmcnt(0)
	v_add_f32_e32 v9, v9, v120
	ds_swizzle_b32 v120, v9 offset:swizzle(SWAP,8)
	s_waitcnt lgkmcnt(0)
	v_add_f32_e32 v9, v9, v120
	ds_swizzle_b32 v120, v9 offset:swizzle(SWAP,16)
	s_waitcnt lgkmcnt(0)
; __device__ __forceinline__ unsigned pk2(float lo, float hi) { unsigned r; asm("v_cvt_pk_bf16_f32 %0, %1, %2" : "=v"(r) : "v"(lo), "v"(hi)); return r; }
; template <int MODE, int NR>
; __device__ __forceinline__ void norm_rows(const float* X32, bf16* X, bf16* H, float* out32, const f32x4 (&mul)[4], const f32x4 (&sh)[4], int lane) {
;     if constexpr (MODE == 1) {
;         f32x4 v[NR][4];
; #pragma unroll
;         for (int r = 0; r < NR; ++r) { const f32x4* xr = (const f32x4*)(X32 + (size_t)r * D) + lane;
; #pragma unroll
;             for (int j = 0; j < 4; ++j) v[r][j] = xr[64 * j]; }
; #pragma unroll
;         for (int r = 0; r < NR; ++r) { float s = 0.f;
; #pragma unroll
;             for (int j = 0; j < 4; ++j) s += (v[r][j].x * v[r][j].x + v[r][j].y * v[r][j].y) + (v[r][j].z * v[r][j].z + v[r][j].w * v[r][j].w);
;             const float rstd = rsqrtf(wave_sum(s) * (1.f / D) + EPS);
;             unsigned long long* o8 = (unsigned long long*)(H + (size_t)r * D) + lane; unsigned long long* x8 = (unsigned long long*)(X + (size_t)r * D) + lane;
; #pragma unroll
;             for (int j = 0; j < 4; ++j) { const f32x4 y = v[r][j] * rstd * mul[j] + sh[j];
;                 x8[64 * j] = (unsigned long long)pk2(v[r][j].x, v[r][j].y) | ((unsigned long long)pk2(v[r][j].z, v[r][j].w) << 32);
;                 o8[64 * j] = (unsigned long long)pk2(y.x, y.y) | ((unsigned long long)pk2(y.z, y.w) << 32); } }
	v_add_f32_e32 v9, v9, v120
	v_mov_b32_e32 v120, v9
	s_nop 1
	v_permlane32_swap_b32_e32 v9, v120
	v_add_f32_e32 v9, v9, v120
	v_fmamk_f32 v9, v9, 0x3a800000, v176
	v_cmp_gt_f32_e32 vcc, s33, v9
	v_mul_f32_e32 v120, 0x4b800000, v9
	s_nop 0
	v_cndmask_b32_e32 v9, v9, v120, vcc
	v_rsq_f32_e32 v9, v9
	s_nop 0
	v_mul_f32_e32 v120, 0x45800000, v9
	v_cndmask_b32_e32 v120, v9, v120, vcc
	v_pk_mul_f32 v[126:127], v[122:123], v[120:121] op_sel_hi:[1,0]
	v_pk_mul_f32 v[128:129], v[124:125], v[120:121] op_sel_hi:[1,0]
	v_cvt_pk_bf16_f32 v122, v122, v123
	v_cvt_pk_bf16_f32 v123, v124, v125
	v_add_co_u32_e32 v124, vcc, s2, v102
	v_pk_fma_f32 v[128:129], v[116:117], v[128:129], v[34:35]
	s_nop 0
	v_addc_co_u32_e32 v125, vcc, -1, v103, vcc
	global_store_dwordx2 v[124:125], v[122:123], off
	v_add_co_u32_e32 v124, vcc, s67, v102
	v_pk_fma_f32 v[126:127], v[118:119], v[126:127], v[32:33]
	v_cvt_pk_bf16_f32 v123, v128, v129
	s_nop 0
	v_addc_co_u32_e32 v125, vcc, -1, v103, vcc
	v_cvt_pk_bf16_f32 v122, v126, v127
	s_mov_b32 s2, 0xfbefe400
	global_store_dwordx2 v[124:125], v[122:123], off
	v_pk_mul_f32 v[122:123], v[92:93], v[120:121] op_sel_hi:[1,0]
	v_pk_mul_f32 v[124:125], v[94:95], v[120:121] op_sel_hi:[1,0]
	v_cvt_pk_bf16_f32 v92, v92, v93
	v_cvt_pk_bf16_f32 v93, v94, v95
	v_add_co_u32_e32 v94, vcc, s2, v102
	v_pk_fma_f32 v[124:125], v[112:113], v[124:125], v[30:31]
	s_nop 0
	v_addc_co_u32_e32 v95, vcc, -1, v103, vcc
	global_store_dwordx2 v[94:95], v[92:93], off
	v_add_co_u32_e32 v94, vcc, s68, v102
	v_pk_fma_f32 v[122:123], v[114:115], v[122:123], v[28:29]
	v_cvt_pk_bf16_f32 v93, v124, v125
	s_nop 0
	v_addc_co_u32_e32 v95, vcc, -1, v103, vcc
	v_cvt_pk_bf16_f32 v92, v122, v123
	s_mov_b32 s2, 0xfbefe600
	global_store_dwordx2 v[94:95], v[92:93], off
	v_pk_mul_f32 v[92:93], v[88:89], v[120:121] op_sel_hi:[1,0]
	v_pk_mul_f32 v[94:95], v[90:91], v[120:121] op_sel_hi:[1,0]
	v_cvt_pk_bf16_f32 v88, v88, v89
	v_cvt_pk_bf16_f32 v89, v90, v91
	v_add_co_u32_e32 v90, vcc, s2, v102
	v_pk_fma_f32 v[94:95], v[108:109], v[94:95], v[26:27]
	s_nop 0
	v_addc_co_u32_e32 v91, vcc, -1, v103, vcc
	global_store_dwordx2 v[90:91], v[88:89], off
	v_add_co_u32_e32 v90, vcc, s69, v102
	v_pk_fma_f32 v[92:93], v[110:111], v[92:93], v[24:25]
	v_cvt_pk_bf16_f32 v89, v94, v95
	s_nop 0
	v_addc_co_u32_e32 v91, vcc, -1, v103, vcc
	v_cvt_pk_bf16_f32 v88, v92, v93
	s_mov_b32 s2, 0xfbefe800
	global_store_dwordx2 v[90:91], v[88:89], off
	v_pk_mul_f32 v[88:89], v[84:85], v[120:121] op_sel_hi:[1,0]
	v_pk_mul_f32 v[90:91], v[86:87], v[120:121] op_sel_hi:[1,0]
	v_cvt_pk_bf16_f32 v84, v84, v85
	v_cvt_pk_bf16_f32 v85, v86, v87
	v_add_co_u32_e32 v86, vcc, s2, v102
	v_pk_fma_f32 v[88:89], v[106:107], v[88:89], v[20:21]
	s_nop 0
	v_addc_co_u32_e32 v87, vcc, -1, v103, vcc
	global_store_dwordx2 v[86:87], v[84:85], off
	v_add_co_u32_e32 v86, vcc, s70, v102
	v_cvt_pk_bf16_f32 v84, v88, v89
	v_pk_fma_f32 v[90:91], v[104:105], v[90:91], v[22:23]
	s_nop 0
	v_addc_co_u32_e32 v87, vcc, -1, v103, vcc
	v_cvt_pk_bf16_f32 v85, v90, v91
	global_store_dwordx2 v[86:87], v[84:85], off
	v_mul_f32_e32 v9, v81, v81
	v_mul_f32_e32 v84, v83, v83
	v_fmac_f32_e32 v9, v80, v80
	v_fmac_f32_e32 v84, v82, v82
	v_add_f32_e32 v9, v9, v84
	v_mul_f32_e32 v84, v77, v77
	v_mul_f32_e32 v85, v79, v79
	v_fmac_f32_e32 v84, v76, v76
	v_fmac_f32_e32 v85, v78, v78
	v_add_f32_e32 v84, v84, v85
	v_add_f32_e32 v9, v9, v84
	v_mul_f32_e32 v84, v73, v73
	v_mul_f32_e32 v85, v75, v75
	v_fmac_f32_e32 v84, v72, v72
	v_fmac_f32_e32 v85, v74, v74
	v_add_f32_e32 v84, v84, v85
	v_add_f32_e32 v9, v9, v84
	v_mul_f32_e32 v84, v69, v69
	v_mul_f32_e32 v85, v71, v71
	v_fmac_f32_e32 v84, v68, v68
	v_fmac_f32_e32 v85, v70, v70
	v_add_f32_e32 v84, v84, v85
	v_add_f32_e32 v9, v9, v84
	ds_swizzle_b32 v84, v9 offset:swizzle(SWAP,1)
	s_mov_b32 s2, 0xfbefea00
	s_waitcnt lgkmcnt(0)
	v_add_f32_e32 v9, v9, v84
	ds_swizzle_b32 v84, v9 offset:swizzle(SWAP,2)
	s_waitcnt lgkmcnt(0)
	v_add_f32_e32 v9, v9, v84
	ds_swizzle_b32 v84, v9 offset:swizzle(SWAP,4)
	s_waitcnt lgkmcnt(0)
	v_add_f32_e32 v9, v9, v84
	ds_swizzle_b32 v84, v9 offset:swizzle(SWAP,8)
	s_waitcnt lgkmcnt(0)
	v_add_f32_e32 v9, v9, v84
	ds_swizzle_b32 v84, v9 offset:swizzle(SWAP,16)
	s_waitcnt lgkmcnt(0)
	v_add_f32_e32 v9, v9, v84
	v_mov_b32_e32 v84, v9
	s_nop 1
	v_permlane32_swap_b32_e32 v9, v84
	v_add_f32_e32 v9, v9, v84
	v_fmamk_f32 v9, v9, 0x3a800000, v176
	v_cmp_gt_f32_e32 vcc, s33, v9
	v_mul_f32_e32 v84, 0x4b800000, v9
	s_nop 0
	v_cndmask_b32_e32 v9, v9, v84, vcc
	v_rsq_f32_e32 v9, v9
	s_nop 0
	v_mul_f32_e32 v84, 0x45800000, v9
	v_cndmask_b32_e32 v84, v9, v84, vcc
	v_pk_mul_f32 v[86:87], v[80:81], v[84:85] op_sel_hi:[1,0]
	v_pk_mul_f32 v[88:89], v[82:83], v[84:85] op_sel_hi:[1,0]
	v_cvt_pk_bf16_f32 v80, v80, v81
	v_cvt_pk_bf16_f32 v81, v82, v83
	v_add_co_u32_e32 v82, vcc, s2, v102
	v_pk_fma_f32 v[88:89], v[116:117], v[88:89], v[34:35]
	s_nop 0
	v_addc_co_u32_e32 v83, vcc, -1, v103, vcc
	global_store_dwordx2 v[82:83], v[80:81], off
	v_add_co_u32_e32 v82, vcc, s71, v102
	v_pk_fma_f32 v[86:87], v[118:119], v[86:87], v[32:33]
	v_cvt_pk_bf16_f32 v81, v88, v89
	s_nop 0
	v_addc_co_u32_e32 v83, vcc, -1, v103, vcc
	v_cvt_pk_bf16_f32 v80, v86, v87
	s_mov_b32 s2, 0xfbefec00
	global_store_dwordx2 v[82:83], v[80:81], off
	v_pk_mul_f32 v[80:81], v[76:77], v[84:85] op_sel_hi:[1,0]
	v_pk_mul_f32 v[82:83], v[78:79], v[84:85] op_sel_hi:[1,0]
	v_cvt_pk_bf16_f32 v76, v76, v77
	v_cvt_pk_bf16_f32 v77, v78, v79
	v_add_co_u32_e32 v78, vcc, s2, v102
	v_pk_fma_f32 v[82:83], v[112:113], v[82:83], v[30:31]
	s_nop 0
	v_addc_co_u32_e32 v79, vcc, -1, v103, vcc
	global_store_dwordx2 v[78:79], v[76:77], off
	v_add_co_u32_e32 v78, vcc, s72, v102
; __device__ __forceinline__ unsigned pk2(float lo, float hi) { unsigned r; asm("v_cvt_pk_bf16_f32 %0, %1, %2" : "=v"(r) : "v"(lo), "v"(hi)); return r; }
; template <int MODE, int NR>
; __device__ __forceinline__ void norm_rows(const float* X32, bf16* X, bf16* H, float* out32, const f32x4 (&mul)[4], const f32x4 (&sh)[4], int lane) {
;     if constexpr (MODE == 1) {
;         f32x4 v[NR][4];
; #pragma unroll
;         for (int r = 0; r < NR; ++r) { const f32x4* xr = (const f32x4*)(X32 + (size_t)r * D) + lane;
; #pragma unroll
;             for (int j = 0; j < 4; ++j) v[r][j] = xr[64 * j]; }
; #pragma unroll
;         for (int r = 0; r < NR; ++r) { float s = 0.f;
; #pragma unroll
;             for (int j = 0; j < 4; ++j) s += (v[r][j].x * v[r][j].x + v[r][j].y * v[r][j].y) + (v[r][j].z * v[r][j].z + v[r][j].w * v[r][j].w);
;             const float rstd = rsqrtf(wave_sum(s) * (1.f / D) + EPS);
;             unsigned long long* o8 = (unsigned long long*)(H + (size_t)r * D) + lane; unsigned long long* x8 = (unsigned long long*)(X + (size_t)r * D) + lane;
; #pragma unroll
;             for (int j = 0; j < 4; ++j) { const f32x4 y = v[r][j] * rstd * mul[j] + sh[j];
;                 x8[64 * j] = (unsigned long long)pk2(v[r][j].x, v[r][j].y) | ((unsigned long long)pk2(v[r][j].z, v[r][j].w) << 32);
;                 o8[64 * j] = (unsigned long long)pk2(y.x, y.y) | ((unsigned long long)pk2(y.z, y.w) << 32); } }
	v_pk_fma_f32 v[80:81], v[114:115], v[80:81], v[28:29]
	v_cvt_pk_bf16_f32 v77, v82, v83
	s_nop 0
	v_addc_co_u32_e32 v79, vcc, -1, v103, vcc
	v_cvt_pk_bf16_f32 v76, v80, v81
	s_mov_b32 s2, 0xfbefee00
	global_store_dwordx2 v[78:79], v[76:77], off
	v_pk_mul_f32 v[76:77], v[72:73], v[84:85] op_sel_hi:[1,0]
	v_pk_mul_f32 v[78:79], v[74:75], v[84:85] op_sel_hi:[1,0]
	v_cvt_pk_bf16_f32 v72, v72, v73
	v_cvt_pk_bf16_f32 v73, v74, v75
	v_add_co_u32_e32 v74, vcc, s2, v102
	v_pk_fma_f32 v[78:79], v[108:109], v[78:79], v[26:27]
	s_nop 0
	v_addc_co_u32_e32 v75, vcc, -1, v103, vcc
	global_store_dwordx2 v[74:75], v[72:73], off
	v_add_co_u32_e32 v74, vcc, s73, v102
	v_pk_fma_f32 v[76:77], v[110:111], v[76:77], v[24:25]
	v_cvt_pk_bf16_f32 v73, v78, v79
	s_nop 0
	v_addc_co_u32_e32 v75, vcc, -1, v103, vcc
	v_cvt_pk_bf16_f32 v72, v76, v77
	s_mov_b32 s2, 0xfbeff000
	global_store_dwordx2 v[74:75], v[72:73], off
	v_pk_mul_f32 v[72:73], v[68:69], v[84:85] op_sel_hi:[1,0]
	v_pk_mul_f32 v[74:75], v[70:71], v[84:85] op_sel_hi:[1,0]
	v_cvt_pk_bf16_f32 v68, v68, v69
	v_cvt_pk_bf16_f32 v69, v70, v71
	v_add_co_u32_e32 v70, vcc, s2, v102
	v_pk_fma_f32 v[72:73], v[106:107], v[72:73], v[20:21]
	s_nop 0
	v_addc_co_u32_e32 v71, vcc, -1, v103, vcc
	global_store_dwordx2 v[70:71], v[68:69], off
	v_add_co_u32_e32 v70, vcc, s8, v102
	v_cvt_pk_bf16_f32 v68, v72, v73
	v_pk_fma_f32 v[74:75], v[104:105], v[74:75], v[22:23]
	s_nop 0
	v_addc_co_u32_e32 v71, vcc, -1, v103, vcc
	v_cvt_pk_bf16_f32 v69, v74, v75
	global_store_dwordx2 v[70:71], v[68:69], off
	v_mul_f32_e32 v9, v65, v65
	v_mul_f32_e32 v68, v67, v67
	v_fmac_f32_e32 v9, v64, v64
	v_fmac_f32_e32 v68, v66, v66
	v_add_f32_e32 v9, v9, v68
	v_mul_f32_e32 v68, v61, v61
	v_mul_f32_e32 v69, v63, v63
	v_fmac_f32_e32 v68, v60, v60
	v_fmac_f32_e32 v69, v62, v62
	v_add_f32_e32 v68, v68, v69
	v_add_f32_e32 v9, v9, v68
	v_mul_f32_e32 v68, v57, v57
	v_mul_f32_e32 v69, v59, v59
	v_fmac_f32_e32 v68, v56, v56
	v_fmac_f32_e32 v69, v58, v58
	v_add_f32_e32 v68, v68, v69
	v_add_f32_e32 v9, v9, v68
	v_mul_f32_e32 v68, v53, v53
	v_mul_f32_e32 v69, v55, v55
	v_fmac_f32_e32 v68, v52, v52
	v_fmac_f32_e32 v69, v54, v54
	v_add_f32_e32 v68, v68, v69
	v_add_f32_e32 v9, v9, v68
	ds_swizzle_b32 v68, v9 offset:swizzle(SWAP,1)
	s_mov_b32 s2, 0xfbeff200
	s_waitcnt lgkmcnt(0)
	v_add_f32_e32 v9, v9, v68
	ds_swizzle_b32 v68, v9 offset:swizzle(SWAP,2)
	s_waitcnt lgkmcnt(0)
	v_add_f32_e32 v9, v9, v68
	ds_swizzle_b32 v68, v9 offset:swizzle(SWAP,4)
	s_waitcnt lgkmcnt(0)
	v_add_f32_e32 v9, v9, v68
	ds_swizzle_b32 v68, v9 offset:swizzle(SWAP,8)
	s_waitcnt lgkmcnt(0)
	v_add_f32_e32 v9, v9, v68
	ds_swizzle_b32 v68, v9 offset:swizzle(SWAP,16)
	s_waitcnt lgkmcnt(0)
	v_add_f32_e32 v9, v9, v68
	v_mov_b32_e32 v68, v9
	s_nop 1
	v_permlane32_swap_b32_e32 v9, v68
	v_add_f32_e32 v9, v9, v68
	v_fmamk_f32 v9, v9, 0x3a800000, v176
	v_cmp_gt_f32_e32 vcc, s33, v9
	v_mul_f32_e32 v68, 0x4b800000, v9
	s_nop 0
	v_cndmask_b32_e32 v9, v9, v68, vcc
	v_rsq_f32_e32 v9, v9
	s_nop 0
	v_mul_f32_e32 v68, 0x45800000, v9
	v_cndmask_b32_e32 v68, v9, v68, vcc
	v_pk_mul_f32 v[70:71], v[64:65], v[68:69] op_sel_hi:[1,0]
	v_pk_mul_f32 v[72:73], v[66:67], v[68:69] op_sel_hi:[1,0]
	v_cvt_pk_bf16_f32 v64, v64, v65
	v_cvt_pk_bf16_f32 v65, v66, v67
	v_add_co_u32_e32 v66, vcc, s2, v102
	v_pk_fma_f32 v[72:73], v[116:117], v[72:73], v[34:35]
	s_nop 0
	v_addc_co_u32_e32 v67, vcc, -1, v103, vcc
	global_store_dwordx2 v[66:67], v[64:65], off
	v_add_co_u32_e32 v66, vcc, s97, v102
	v_pk_fma_f32 v[70:71], v[118:119], v[70:71], v[32:33]
	v_cvt_pk_bf16_f32 v65, v72, v73
	s_nop 0
	v_addc_co_u32_e32 v67, vcc, -1, v103, vcc
	v_cvt_pk_bf16_f32 v64, v70, v71
	s_mov_b32 s2, 0xfbeff400
	global_store_dwordx2 v[66:67], v[64:65], off
	v_pk_mul_f32 v[64:65], v[60:61], v[68:69] op_sel_hi:[1,0]
	v_pk_mul_f32 v[66:67], v[62:63], v[68:69] op_sel_hi:[1,0]
	v_cvt_pk_bf16_f32 v60, v60, v61
	v_cvt_pk_bf16_f32 v61, v62, v63
	v_add_co_u32_e32 v62, vcc, s2, v102
	v_pk_fma_f32 v[66:67], v[112:113], v[66:67], v[30:31]
	s_nop 0
	v_addc_co_u32_e32 v63, vcc, -1, v103, vcc
	global_store_dwordx2 v[62:63], v[60:61], off
	v_add_co_u32_e32 v62, vcc, s9, v102
	v_pk_fma_f32 v[64:65], v[114:115], v[64:65], v[28:29]
	v_cvt_pk_bf16_f32 v61, v66, v67
	s_nop 0
	v_addc_co_u32_e32 v63, vcc, -1, v103, vcc
	v_cvt_pk_bf16_f32 v60, v64, v65
	s_mov_b32 s2, 0xfbeff600
	global_store_dwordx2 v[62:63], v[60:61], off
	v_pk_mul_f32 v[60:61], v[56:57], v[68:69] op_sel_hi:[1,0]
	v_pk_mul_f32 v[62:63], v[58:59], v[68:69] op_sel_hi:[1,0]
	v_cvt_pk_bf16_f32 v56, v56, v57
	v_cvt_pk_bf16_f32 v57, v58, v59
	v_add_co_u32_e32 v58, vcc, s2, v102
	v_pk_fma_f32 v[62:63], v[108:109], v[62:63], v[26:27]
	s_nop 0
	v_addc_co_u32_e32 v59, vcc, -1, v103, vcc
	global_store_dwordx2 v[58:59], v[56:57], off
	v_add_co_u32_e32 v58, vcc, s28, v102
	v_pk_fma_f32 v[60:61], v[110:111], v[60:61], v[24:25]
	v_cvt_pk_bf16_f32 v57, v62, v63
	s_nop 0
	v_addc_co_u32_e32 v59, vcc, -1, v103, vcc
	v_cvt_pk_bf16_f32 v56, v60, v61
	s_mov_b32 s2, 0xfbeff800
	global_store_dwordx2 v[58:59], v[56:57], off
	v_pk_mul_f32 v[56:57], v[52:53], v[68:69] op_sel_hi:[1,0]
	v_pk_mul_f32 v[58:59], v[54:55], v[68:69] op_sel_hi:[1,0]
	v_cvt_pk_bf16_f32 v52, v52, v53
	v_cvt_pk_bf16_f32 v53, v54, v55
	v_add_co_u32_e32 v54, vcc, s2, v102
	v_pk_fma_f32 v[56:57], v[106:107], v[56:57], v[20:21]
	s_nop 0
	v_addc_co_u32_e32 v55, vcc, -1, v103, vcc
	global_store_dwordx2 v[54:55], v[52:53], off
	v_add_co_u32_e32 v54, vcc, s29, v102
	v_cvt_pk_bf16_f32 v52, v56, v57
	v_pk_fma_f32 v[58:59], v[104:105], v[58:59], v[22:23]
	s_nop 0
	v_addc_co_u32_e32 v55, vcc, -1, v103, vcc
	v_cvt_pk_bf16_f32 v53, v58, v59
	global_store_dwordx2 v[54:55], v[52:53], off
	v_mul_f32_e32 v9, v49, v49
	v_mul_f32_e32 v52, v51, v51
	v_fmac_f32_e32 v9, v48, v48
	v_fmac_f32_e32 v52, v50, v50
	v_add_f32_e32 v9, v9, v52
	v_mul_f32_e32 v52, v45, v45
	v_mul_f32_e32 v53, v47, v47
	v_fmac_f32_e32 v52, v44, v44
	v_fmac_f32_e32 v53, v46, v46
	v_add_f32_e32 v52, v52, v53
	v_add_f32_e32 v9, v9, v52
	v_mul_f32_e32 v52, v41, v41
	v_mul_f32_e32 v53, v43, v43
	v_fmac_f32_e32 v52, v40, v40
	v_fmac_f32_e32 v53, v42, v42
	v_add_f32_e32 v52, v52, v53
	v_add_f32_e32 v9, v9, v52
	v_mul_f32_e32 v52, v37, v37
	v_mul_f32_e32 v53, v39, v39
	v_fmac_f32_e32 v52, v36, v36
	v_fmac_f32_e32 v53, v38, v38
	v_add_f32_e32 v52, v52, v53
	v_add_f32_e32 v9, v9, v52
	ds_swizzle_b32 v52, v9 offset:swizzle(SWAP,1)
	s_mov_b32 s2, 0xfbeffa00
	s_waitcnt lgkmcnt(0)
; __device__ __forceinline__ unsigned pk2(float lo, float hi) { unsigned r; asm("v_cvt_pk_bf16_f32 %0, %1, %2" : "=v"(r) : "v"(lo), "v"(hi)); return r; }
; template <int MODE, int NR>
; __device__ __forceinline__ void norm_rows(const float* X32, bf16* X, bf16* H, float* out32, const f32x4 (&mul)[4], const f32x4 (&sh)[4], int lane) {
;     if constexpr (MODE == 1) {
;         f32x4 v[NR][4];
; #pragma unroll
;         for (int r = 0; r < NR; ++r) { const f32x4* xr = (const f32x4*)(X32 + (size_t)r * D) + lane;
; #pragma unroll
;             for (int j = 0; j < 4; ++j) v[r][j] = xr[64 * j]; }
; #pragma unroll
;         for (int r = 0; r < NR; ++r) { float s = 0.f;
; #pragma unroll
;             for (int j = 0; j < 4; ++j) s += (v[r][j].x * v[r][j].x + v[r][j].y * v[r][j].y) + (v[r][j].z * v[r][j].z + v[r][j].w * v[r][j].w);
;             const float rstd = rsqrtf(wave_sum(s) * (1.f / D) + EPS);
;             unsigned long long* o8 = (unsigned long long*)(H + (size_t)r * D) + lane; unsigned long long* x8 = (unsigned long long*)(X + (size_t)r * D) + lane;
; #pragma unroll
;             for (int j = 0; j < 4; ++j) { const f32x4 y = v[r][j] * rstd * mul[j] + sh[j];
;                 x8[64 * j] = (unsigned long long)pk2(v[r][j].x, v[r][j].y) | ((unsigned long long)pk2(v[r][j].z, v[r][j].w) << 32);
;                 o8[64 * j] = (unsigned long long)pk2(y.x, y.y) | ((unsigned long long)pk2(y.z, y.w) << 32); } }
	v_add_f32_e32 v9, v9, v52
	ds_swizzle_b32 v52, v9 offset:swizzle(SWAP,2)
	s_waitcnt lgkmcnt(0)
	v_add_f32_e32 v9, v9, v52
	ds_swizzle_b32 v52, v9 offset:swizzle(SWAP,4)
	s_waitcnt lgkmcnt(0)
	v_add_f32_e32 v9, v9, v52
	ds_swizzle_b32 v52, v9 offset:swizzle(SWAP,8)
	s_waitcnt lgkmcnt(0)
	v_add_f32_e32 v9, v9, v52
	ds_swizzle_b32 v52, v9 offset:swizzle(SWAP,16)
	s_waitcnt lgkmcnt(0)
	v_add_f32_e32 v9, v9, v52
	v_mov_b32_e32 v52, v9
	s_nop 1
	v_permlane32_swap_b32_e32 v9, v52
	v_add_f32_e32 v9, v9, v52
	v_fmamk_f32 v9, v9, 0x3a800000, v176
	v_cmp_gt_f32_e32 vcc, s33, v9
	v_mul_f32_e32 v52, 0x4b800000, v9
	s_nop 0
	v_cndmask_b32_e32 v9, v9, v52, vcc
	v_rsq_f32_e32 v9, v9
	s_nop 0
	v_mul_f32_e32 v52, 0x45800000, v9
	v_cndmask_b32_e32 v52, v9, v52, vcc
	v_pk_mul_f32 v[54:55], v[48:49], v[52:53] op_sel_hi:[1,0]
	v_pk_mul_f32 v[56:57], v[50:51], v[52:53] op_sel_hi:[1,0]
	v_cvt_pk_bf16_f32 v48, v48, v49
	v_cvt_pk_bf16_f32 v49, v50, v51
	v_add_co_u32_e32 v50, vcc, s2, v102
	v_pk_fma_f32 v[34:35], v[116:117], v[56:57], v[34:35]
	v_pk_fma_f32 v[32:33], v[118:119], v[54:55], v[32:33]
	v_addc_co_u32_e32 v51, vcc, -1, v103, vcc
	v_cvt_pk_bf16_f32 v32, v32, v33
	v_cvt_pk_bf16_f32 v33, v34, v35
	v_add_co_u32_e32 v34, vcc, s30, v102
	s_mov_b32 s2, 0xfbeffc00
	s_nop 0
	v_addc_co_u32_e32 v35, vcc, -1, v103, vcc
	global_store_dwordx2 v[34:35], v[32:33], off
	v_pk_mul_f32 v[34:35], v[46:47], v[52:53] op_sel_hi:[1,0]
	v_pk_mul_f32 v[32:33], v[44:45], v[52:53] op_sel_hi:[1,0]
	v_pk_fma_f32 v[30:31], v[112:113], v[34:35], v[30:31]
	v_add_co_u32_e32 v34, vcc, s2, v102
	v_pk_fma_f32 v[28:29], v[114:115], v[32:33], v[28:29]
	s_nop 0
	v_addc_co_u32_e32 v35, vcc, -1, v103, vcc
	v_cvt_pk_bf16_f32 v28, v28, v29
	v_cvt_pk_bf16_f32 v29, v30, v31
	v_add_co_u32_e32 v30, vcc, s31, v102
	s_mov_b32 s2, 0xfbeffe00
	s_nop 0
	v_addc_co_u32_e32 v31, vcc, -1, v103, vcc
	global_store_dwordx2 v[30:31], v[28:29], off
	v_pk_mul_f32 v[30:31], v[42:43], v[52:53] op_sel_hi:[1,0]
	v_pk_mul_f32 v[28:29], v[40:41], v[52:53] op_sel_hi:[1,0]
	v_pk_fma_f32 v[26:27], v[108:109], v[30:31], v[26:27]
	v_add_co_u32_e32 v30, vcc, s2, v102
	v_pk_fma_f32 v[24:25], v[110:111], v[28:29], v[24:25]
	s_nop 0
	v_addc_co_u32_e32 v31, vcc, -1, v103, vcc
	v_cvt_pk_bf16_f32 v24, v24, v25
	v_cvt_pk_bf16_f32 v25, v26, v27
	v_add_co_u32_e32 v26, vcc, s34, v102
	s_mov_b32 s2, 0xfbf00000
	s_nop 0
	v_addc_co_u32_e32 v27, vcc, -1, v103, vcc
	global_store_dwordx2 v[26:27], v[24:25], off
	v_pk_mul_f32 v[24:25], v[36:37], v[52:53] op_sel_hi:[1,0]
	v_pk_mul_f32 v[26:27], v[38:39], v[52:53] op_sel_hi:[1,0]
	v_pk_fma_f32 v[20:21], v[106:107], v[24:25], v[20:21]
	v_pk_fma_f32 v[22:23], v[104:105], v[26:27], v[22:23]
	v_add_co_u32_e32 v26, vcc, s2, v102
	v_cvt_pk_bf16_f32 v20, v20, v21
	v_cvt_pk_bf16_f32 v21, v22, v23
	global_store_dwordx2 v[102:103], v[20:21], off
	s_nop 0
	v_addc_co_u32_e32 v27, vcc, -1, v103, vcc
	v_lshl_add_u64 v[102:103], v[102:103], 0, s[78:79]
	global_store_dwordx2 v[50:51], v[48:49], off
	v_cvt_pk_bf16_f32 v32, v44, v45
	v_cvt_pk_bf16_f32 v33, v46, v47
	global_store_dwordx2 v[34:35], v[32:33], off
	v_cvt_pk_bf16_f32 v28, v40, v41
	v_cvt_pk_bf16_f32 v29, v42, v43
	global_store_dwordx2 v[30:31], v[28:29], off
	v_cvt_pk_bf16_f32 v24, v36, v37
	v_cvt_pk_bf16_f32 v25, v38, v39
	global_store_dwordx2 v[26:27], v[24:25], off
	s_cbranch_scc0 .LBB0_194

; __device__ __forceinline__ unsigned pk2(float lo, float hi) { unsigned r; asm("v_cvt_pk_bf16_f32 %0, %1, %2" : "=v"(r) : "v"(lo), "v"(hi)); return r; }
; template <int MODE, int NR>
; __device__ __forceinline__ void norm_rows(const float* X32, bf16* X, bf16* H, float* out32, const f32x4 (&mul)[4], const f32x4 (&sh)[4], int lane) {
;     if constexpr (MODE == 1) {
;         f32x4 v[NR][4];
; #pragma unroll
;         for (int r = 0; r < NR; ++r) { const f32x4* xr = (const f32x4*)(X32 + (size_t)r * D) + lane;
; #pragma unroll
;             for (int j = 0; j < 4; ++j) v[r][j] = xr[64 * j]; }
; #pragma unroll
;         for (int r = 0; r < NR; ++r) { float s = 0.f;
; #pragma unroll
;             for (int j = 0; j < 4; ++j) s += (v[r][j].x * v[r][j].x + v[r][j].y * v[r][j].y) + (v[r][j].z * v[r][j].z + v[r][j].w * v[r][j].w);
;             const float rstd = rsqrtf(wave_sum(s) * (1.f / D) + EPS);
;             unsigned long long* o8 = (unsigned long long*)(H + (size_t)r * D) + lane; unsigned long long* x8 = (unsigned long long*)(X + (size_t)r * D) + lane;
; #pragma unroll
;             for (int j = 0; j < 4; ++j) { const f32x4 y = v[r][j] * rstd * mul[j] + sh[j];
;                 x8[64 * j] = (unsigned long long)pk2(v[r][j].x, v[r][j].y) | ((unsigned long long)pk2(v[r][j].z, v[r][j].w) << 32);
;                 o8[64 * j] = (unsigned long long)pk2(y.x, y.y) | ((unsigned long long)pk2(y.z, y.w) << 32); } }
; template <int MODE>
; __device__ __forceinline__ void phase_norm(const float* Xp32, const float* Xs32, bf16* X, bf16* H, const float* nw, const float* mod_sh, const float* mod_sc, int gw, int NGW, int lane) {
;     ...
;     for (int sr = gw; sr < MS; sr += NGW) {
;         const int ci = NB + sr; f32x4 mul[4], sh[4];
;         const f32x4* shp = (const f32x4*)(mod_sh + (size_t)ci * MODLD) + lane; const f32x4* scp = (const f32x4*)(mod_sc + (size_t)ci * MODLD) + lane;
; #pragma unroll
;         for (int j = 0; j < 4; ++j) { sh[j] = shp[64 * j]; mul[j] = w4[j] * (scp[64 * j] + 1.0f); }
;         const size_t ro = (size_t)(MP + sr) * D;
;         norm_rows<MODE, 1>(MODE == 1 ? Xs32 + (size_t)sr * D : nullptr, X + ro, H + ro, nullptr, mul, sh, lane);
;     }
.LBB0_197:
	v_lshl_add_u64 v[26:27], s[2:3], 0, v[10:11]
	v_add_co_u32_e32 v38, vcc, 0x300000, v26
	v_lshl_add_u64 v[50:51], s[4:5], 0, v[10:11]
	s_nop 0
	v_addc_co_u32_e32 v39, vcc, 0, v27, vcc
	v_add_co_u32_e32 v40, vcc, 0x301000, v26
	global_load_dwordx4 v[22:25], v[38:39], off
	s_nop 0
	v_addc_co_u32_e32 v41, vcc, 0, v27, vcc
	global_load_dwordx4 v[26:29], v[40:41], off
	s_add_i32 s6, s0, 0x4000
	s_ashr_i32 s7, s6, 31
	s_lshl_b64 s[6:7], s[6:7], 11
	v_lshl_add_u64 v[70:71], v[8:9], 0, s[6:7]
	s_add_i32 s0, s0, s96
	s_add_u32 s2, s2, s60
	s_addc_u32 s3, s3, s61
	s_add_u32 s4, s4, s8
	s_addc_u32 s5, s5, s9
	s_cmpk_gt_i32 s0, 0x7f
	s_waitcnt vmcnt(0) lgkmcnt(0)
	v_pk_add_f32 v[28:29], v[28:29], 1.0 op_sel_hi:[1,0]
	v_pk_add_f32 v[26:27], v[26:27], 1.0 op_sel_hi:[1,0]
	v_pk_mul_f32 v[54:55], v[2:3], v[28:29]
	v_pk_mul_f32 v[56:57], v[0:1], v[26:27]
	global_load_dwordx4 v[26:29], v[38:39], off offset:1024
	global_load_dwordx4 v[30:33], v[40:41], off offset:1024
	s_waitcnt vmcnt(0) lgkmcnt(0)
	v_pk_add_f32 v[32:33], v[32:33], 1.0 op_sel_hi:[1,0]
	v_pk_add_f32 v[30:31], v[30:31], 1.0 op_sel_hi:[1,0]
	v_pk_mul_f32 v[58:59], v[6:7], v[32:33]
	v_pk_mul_f32 v[60:61], v[4:5], v[30:31]
	global_load_dwordx4 v[30:33], v[38:39], off offset:2048
	global_load_dwordx4 v[34:37], v[40:41], off offset:2048
	s_waitcnt vmcnt(0) lgkmcnt(0)
	v_pk_add_f32 v[36:37], v[36:37], 1.0 op_sel_hi:[1,0]
	v_pk_add_f32 v[34:35], v[34:35], 1.0 op_sel_hi:[1,0]
	v_pk_mul_f32 v[62:63], v[14:15], v[36:37]
	v_pk_mul_f32 v[64:65], v[12:13], v[34:35]
	global_load_dwordx4 v[34:37], v[38:39], off offset:3072
	s_nop 0
	global_load_dwordx4 v[38:41], v[40:41], off offset:3072
	s_waitcnt vmcnt(0) lgkmcnt(0)
	v_pk_add_f32 v[40:41], v[40:41], 1.0 op_sel_hi:[1,0]
	v_pk_add_f32 v[38:39], v[38:39], 1.0 op_sel_hi:[1,0]
	v_pk_mul_f32 v[66:67], v[18:19], v[40:41]
	v_pk_mul_f32 v[68:69], v[16:17], v[38:39]
	global_load_dwordx4 v[38:41], v[50:51], off
	global_load_dwordx4 v[42:45], v[50:51], off offset:1024
	global_load_dwordx4 v[46:49], v[50:51], off offset:2048
	s_nop 0
	global_load_dwordx4 v[50:53], v[50:51], off offset:3072
	s_waitcnt vmcnt(3)
	v_mul_f32_e32 v72, v39, v39
	v_mul_f32_e32 v73, v41, v41
	v_fmac_f32_e32 v72, v38, v38
	v_fmac_f32_e32 v73, v40, v40
	v_add_f32_e32 v72, v72, v73
	s_waitcnt vmcnt(2)
	v_mul_f32_e32 v73, v43, v43
	v_mul_f32_e32 v74, v45, v45
	v_fmac_f32_e32 v73, v42, v42
	v_fmac_f32_e32 v74, v44, v44
	v_add_f32_e32 v73, v73, v74
	v_add_f32_e32 v72, v72, v73
	s_waitcnt vmcnt(1)
	v_mul_f32_e32 v73, v47, v47
	v_mul_f32_e32 v74, v49, v49
	v_fmac_f32_e32 v73, v46, v46
	v_fmac_f32_e32 v74, v48, v48
	v_add_f32_e32 v73, v73, v74
	v_add_f32_e32 v72, v72, v73
	s_waitcnt vmcnt(0)
	v_mul_f32_e32 v73, v51, v51
	v_mul_f32_e32 v74, v53, v53
	v_fmac_f32_e32 v73, v50, v50
	v_fmac_f32_e32 v74, v52, v52
	v_add_f32_e32 v73, v73, v74
	v_add_f32_e32 v74, v72, v73
	ds_swizzle_b32 v75, v74 offset:swizzle(SWAP,1)
	v_lshl_add_u64 v[72:73], v[20:21], 0, s[6:7]
	s_waitcnt lgkmcnt(0)
	v_add_f32_e32 v74, v74, v75
	ds_swizzle_b32 v75, v74 offset:swizzle(SWAP,2)
	s_waitcnt lgkmcnt(0)
	v_add_f32_e32 v74, v74, v75
	ds_swizzle_b32 v75, v74 offset:swizzle(SWAP,4)
	s_waitcnt lgkmcnt(0)
	v_add_f32_e32 v74, v74, v75
	ds_swizzle_b32 v75, v74 offset:swizzle(SWAP,8)
	s_waitcnt lgkmcnt(0)
	v_add_f32_e32 v74, v74, v75
	ds_swizzle_b32 v75, v74 offset:swizzle(SWAP,16)
	s_waitcnt lgkmcnt(0)
	v_add_f32_e32 v74, v74, v75
	v_mov_b32_e32 v75, v74
	s_nop 1
	v_permlane32_swap_b32_e32 v74, v75
	v_add_f32_e32 v74, v74, v75
	v_fmamk_f32 v74, v74, 0x3a800000, v176
	v_cmp_gt_f32_e32 vcc, s33, v74
	v_mul_f32_e32 v75, 0x4b800000, v74
	s_nop 0
	v_cndmask_b32_e32 v74, v74, v75, vcc
	v_rsq_f32_e32 v74, v74
	s_nop 0
	v_mul_f32_e32 v75, 0x45800000, v74
	v_cndmask_b32_e32 v74, v74, v75, vcc
	v_pk_mul_f32 v[76:77], v[38:39], v[74:75] op_sel_hi:[1,0]
	v_pk_mul_f32 v[78:79], v[40:41], v[74:75] op_sel_hi:[1,0]
	v_pk_fma_f32 v[22:23], v[56:57], v[76:77], v[22:23]
	v_pk_fma_f32 v[24:25], v[54:55], v[78:79], v[24:25]
	v_cvt_pk_bf16_f32 v22, v22, v23
	v_cvt_pk_bf16_f32 v38, v38, v39
	v_cvt_pk_bf16_f32 v39, v40, v41
	global_store_dwordx2 v[72:73], v[38:39], off
	v_cvt_pk_bf16_f32 v23, v24, v25
	global_store_dwordx2 v[70:71], v[22:23], off
	v_pk_mul_f32 v[22:23], v[42:43], v[74:75] op_sel_hi:[1,0]
	v_pk_mul_f32 v[24:25], v[44:45], v[74:75] op_sel_hi:[1,0]
	v_pk_fma_f32 v[22:23], v[60:61], v[22:23], v[26:27]
	v_pk_fma_f32 v[24:25], v[58:59], v[24:25], v[28:29]
	v_cvt_pk_bf16_f32 v22, v22, v23
	v_cvt_pk_bf16_f32 v26, v42, v43
	v_cvt_pk_bf16_f32 v27, v44, v45
	global_store_dwordx2 v[72:73], v[26:27], off offset:512
	v_cvt_pk_bf16_f32 v23, v24, v25
	global_store_dwordx2 v[70:71], v[22:23], off offset:512
	v_pk_mul_f32 v[22:23], v[46:47], v[74:75] op_sel_hi:[1,0]
	v_pk_mul_f32 v[24:25], v[48:49], v[74:75] op_sel_hi:[1,0]
	v_pk_fma_f32 v[22:23], v[64:65], v[22:23], v[30:31]
	v_pk_fma_f32 v[24:25], v[62:63], v[24:25], v[32:33]
	v_cvt_pk_bf16_f32 v22, v22, v23
	v_cvt_pk_bf16_f32 v26, v46, v47
	v_cvt_pk_bf16_f32 v27, v48, v49
	global_store_dwordx2 v[72:73], v[26:27], off offset:1024
	v_cvt_pk_bf16_f32 v23, v24, v25
	global_store_dwordx2 v[70:71], v[22:23], off offset:1024
	v_pk_mul_f32 v[22:23], v[50:51], v[74:75] op_sel_hi:[1,0]
	v_pk_mul_f32 v[24:25], v[52:53], v[74:75] op_sel_hi:[1,0]
	v_pk_fma_f32 v[22:23], v[68:69], v[22:23], v[34:35]
	v_pk_fma_f32 v[24:25], v[66:67], v[24:25], v[36:37]
	v_cvt_pk_bf16_f32 v26, v50, v51
	v_cvt_pk_bf16_f32 v27, v52, v53
	global_store_dwordx2 v[72:73], v[26:27], off offset:1536
	v_cvt_pk_bf16_f32 v22, v22, v23
	v_cvt_pk_bf16_f32 v23, v24, v25
	global_store_dwordx2 v[70:71], v[22:23], off offset:1536
	s_cbranch_scc0 .LBB0_197

; __device__ __forceinline__ unsigned xb_ld(unsigned* p)              { return __hip_atomic_load(p, __ATOMIC_RELAXED, __HIP_MEMORY_SCOPE_AGENT); }
; __device__ __forceinline__ void xcd_barrier_complete(unsigned* bar, unsigned x, unsigned& nloc, unsigned& nx) {
;     const unsigned G = gridDim.x * gridDim.y * gridDim.z;
;     unsigned sum, cnt, mine, sp = 0u;
;     for (;;) {
;         sum = 0u; cnt = 0u; mine = 0u;
; #pragma unroll
;         for (unsigned j = 0; j < 16; ++j) { const unsigned c = xb_ld(&bar[XB_XCNT(j)]); sum += c; cnt += (c > 0u) ? 1u : 0u; mine = (j == x) ? c : mine; }
;         if (sum == G) break;
;         __builtin_amdgcn_s_sleep(1);
;         if ((++sp & 255u) == 0u) { if (xb_ld(&bar[XB_TMO])) break; if (sp > XB_SPIN_CAP) { atomicAdd(&bar[XB_TMO], 1u); break; } }
;     }
;     nloc = mine > 0u ? mine : 1u; nx = cnt > 0u ? cnt : 1u;
.LBB0_203:
	v_mov_b64_e32 v[12:13], s[34:35]
	global_load_dword v1, v[12:13], off offset:1024 sc1
	global_load_dword v0, v[12:13], off offset:1280 sc1
	global_load_dword v2, v[12:13], off offset:1536 sc1
	s_or_b64 s[16:17], s[16:17], exec
	s_or_b64 s[14:15], s[14:15], exec
	s_waitcnt vmcnt(0) lgkmcnt(0)
	v_add_u32_e32 v3, v0, v1
	v_add_u32_e32 v4, v3, v2
	global_load_dword v3, v[12:13], off offset:1792 sc1
	s_waitcnt vmcnt(0) lgkmcnt(0)
	v_add_u32_e32 v5, v4, v3
	global_load_dword v4, v[12:13], off offset:2048 sc1
	s_waitcnt vmcnt(0) lgkmcnt(0)
	v_add_u32_e32 v6, v5, v4
	global_load_dword v5, v[12:13], off offset:2304 sc1
	s_waitcnt vmcnt(0) lgkmcnt(0)
	v_add_u32_e32 v7, v6, v5
	global_load_dword v6, v[12:13], off offset:2560 sc1
	s_waitcnt vmcnt(0) lgkmcnt(0)
	v_add_u32_e32 v8, v7, v6
	global_load_dword v7, v[12:13], off offset:2816 sc1
	s_waitcnt vmcnt(0) lgkmcnt(0)
	v_add_u32_e32 v9, v8, v7
	global_load_dword v8, v[12:13], off offset:3072 sc1
	s_waitcnt vmcnt(0) lgkmcnt(0)
	v_add_u32_e32 v10, v9, v8
	global_load_dword v9, v[12:13], off offset:3328 sc1
	s_waitcnt vmcnt(0) lgkmcnt(0)
	v_add_u32_e32 v14, v10, v9
	global_load_dword v10, v[12:13], off offset:3584 sc1
	s_waitcnt vmcnt(0) lgkmcnt(0)
	v_add_u32_e32 v14, v14, v10
	global_load_dword v12, v[12:13], off offset:3840 sc1
	s_waitcnt vmcnt(0) lgkmcnt(0)
	v_add_u32_e32 v16, v14, v12
	v_mov_b64_e32 v[14:15], s[0:1]
	global_load_dword v13, v[14:15], off sc1
	v_mov_b64_e32 v[14:15], s[4:5]
	global_load_dword v14, v[14:15], off sc1
	s_waitcnt vmcnt(0) lgkmcnt(0)
	v_add_u32_e32 v16, v16, v13
	v_add_u32_e32 v18, v16, v14
	v_mov_b64_e32 v[16:17], s[6:7]
	global_load_dword v15, v[16:17], off sc1
	v_mov_b64_e32 v[16:17], s[8:9]
	global_load_dword v16, v[16:17], off sc1
	s_waitcnt vmcnt(0) lgkmcnt(0)
	v_add_u32_e32 v18, v18, v15
	v_add_u32_e32 v17, v18, v16
	v_cmp_ne_u32_e32 vcc, s28, v17
	s_and_saveexec_b64 s[18:19], vcc
	s_cbranch_execz .LBB0_202
	s_and_b32 s22, s29, 0xff
	s_mov_b64 s[20:21], -1
	s_cmp_eq_u32 s22, 0
	s_mov_b64 s[24:25], -1
	s_mov_b64 s[22:23], -1
	s_sleep 1
	s_cbranch_scc1 .LBB0_206
	s_and_saveexec_b64 s[26:27], s[24:25]
	s_cbranch_execz .LBB0_201
	s_branch .LBB0_209
.LBB0_206:
	v_mov_b64_e32 v[18:19], s[34:35]
	global_load_dword v17, v[18:19], off offset:512 sc1
	s_mov_b64 s[24:25], 0
	s_waitcnt vmcnt(0) lgkmcnt(0)
	v_cmp_eq_u32_e32 vcc, 0, v17
	s_and_saveexec_b64 s[26:27], vcc
	s_cmp_lt_u32 s29, 0x40001
	s_cselect_b64 s[24:25], -1, 0
	s_xor_b64 s[22:23], exec, -1
	s_and_b64 s[24:25], s[24:25], exec
	s_or_b64 exec, exec, s[26:27]
	s_and_saveexec_b64 s[26:27], s[24:25]
	s_cbranch_execz .LBB0_201

; __device__ __forceinline__ unsigned xb_ld(unsigned* p)              { return __hip_atomic_load(p, __ATOMIC_RELAXED, __HIP_MEMORY_SCOPE_AGENT); }
; __device__ __forceinline__ unsigned xb_add(unsigned* p, unsigned v) { return __hip_atomic_fetch_add(p, v, __ATOMIC_RELAXED, __HIP_MEMORY_SCOPE_AGENT); }
; #define XB_SPIN(cond, bar) do { unsigned _sp = 0; while (cond) { __builtin_amdgcn_s_sleep(1); \
;     if ((++_sp & 255u) == 0u) { if (xb_ld(&(bar)[XB_TMO])) break; if (_sp > XB_SPIN_CAP) { atomicAdd(&(bar)[XB_TMO], 1u); break; } } } } while (0)
; __device__ __forceinline__ void xcd_barrier(const XcdBarrier& b, int tid) {
;     ...
;         const unsigned old = xb_add(&bar[XB_XSUB(bx_)], 1u);
;         const unsigned gen = old / nloc;
;         if (old + 1u == (gen + 1u) * nloc) {
;             __builtin_amdgcn_fence(__ATOMIC_RELEASE, "agent");
;             asm volatile("s_waitcnt vmcnt(0)" ::: "memory");
;             const unsigned og = xb_add(&bar[XB_TOP], 1u);
;             const unsigned tg = og / nx;
;             if (og + 1u == (tg + 1u) * nx) xb_add(&bar[XB_TOPGEN], 1u);
;             else XB_SPIN(xb_ld(&bar[XB_TOPGEN]) == tg, bar);
;             __builtin_amdgcn_fence(__ATOMIC_ACQUIRE, "agent");
;             xb_add(&bar[XB_XGEN(bx_)], 1u);
;             asm volatile("s_waitcnt vmcnt(0)" ::: "memory");
;         } else {
;             XB_SPIN(xb_ld(&bar[XB_XGEN(bx_)]) == gen, bar);
.LBB0_213:
	s_lshl_b32 s24, s36, 6
	s_add_i32 s64, s24, 0x500
	s_lshl_b64 s[0:1], s[64:65], 2
	s_add_u32 s0, s34, s0
	s_addc_u32 s1, s35, s1
	v_mov_b64_e32 v[4:5], s[0:1]
	v_mov_b32_e32 v1, 1
	flat_atomic_add v3, v[4:5], v1 sc0
	v_cvt_f32_u32_e32 v1, v2
	v_sub_u32_e32 v4, 0, v2
	v_rcp_iflag_f32_e32 v1, v1
	s_nop 0
	v_mul_f32_e32 v1, 0x4f7ffffe, v1
	v_cvt_u32_f32_e32 v1, v1
	v_mul_lo_u32 v4, v4, v1
	v_mul_hi_u32 v4, v1, v4
	v_add_u32_e32 v1, v1, v4
	s_waitcnt vmcnt(0) lgkmcnt(0)
	v_mul_hi_u32 v1, v3, v1
	v_mul_lo_u32 v4, v1, v2
	v_sub_u32_e32 v4, v3, v4
	v_cmp_ge_u32_e32 vcc, v4, v2
	v_add_u32_e32 v5, 1, v1
	s_nop 0
	v_cndmask_b32_e32 v1, v1, v5, vcc
	v_sub_u32_e32 v5, v4, v2
	v_cndmask_b32_e32 v4, v4, v5, vcc
	v_cmp_ge_u32_e32 vcc, v4, v2
	v_add_u32_e32 v4, 1, v1
	s_nop 0
	v_cndmask_b32_e32 v1, v1, v4, vcc
	v_add_u32_e32 v4, 1, v3
	v_mad_u64_u32 v[2:3], s[0:1], v2, v1, v[2:3]
	v_cmp_ne_u32_e32 vcc, v4, v2
	s_and_saveexec_b64 s[0:1], vcc
	s_xor_b64 s[0:1], exec, s[0:1]
	s_cbranch_execz .LBB0_226
	s_add_i32 s64, s24, 0x900
	s_lshl_b64 s[4:5], s[64:65], 2
	s_add_u32 s6, s34, s4
	s_addc_u32 s7, s35, s5
	v_mov_b64_e32 v[2:3], s[6:7]
	global_load_dword v0, v[2:3], off sc1
	s_waitcnt vmcnt(0) lgkmcnt(0)
	v_cmp_eq_u32_e32 vcc, v0, v1
	s_and_saveexec_b64 s[4:5], vcc
	s_cbranch_execz .LBB0_225
	s_mov_b32 s22, 1
	s_mov_b64 s[8:9], 0
	s_branch .LBB0_217

; __device__ __forceinline__ unsigned xb_ld(unsigned* p)              { return __hip_atomic_load(p, __ATOMIC_RELAXED, __HIP_MEMORY_SCOPE_AGENT); }
; __device__ __forceinline__ unsigned xb_add(unsigned* p, unsigned v) { return __hip_atomic_fetch_add(p, v, __ATOMIC_RELAXED, __HIP_MEMORY_SCOPE_AGENT); }
; #define XB_SPIN(cond, bar) do { unsigned _sp = 0; while (cond) { __builtin_amdgcn_s_sleep(1); \
;     if ((++_sp & 255u) == 0u) { if (xb_ld(&(bar)[XB_TMO])) break; if (_sp > XB_SPIN_CAP) { atomicAdd(&(bar)[XB_TMO], 1u); break; } } } } while (0)
; __device__ __forceinline__ void xcd_barrier(const XcdBarrier& b, int tid) {
;     ...
;         if (old + 1u == (gen + 1u) * nloc) {
;             __builtin_amdgcn_fence(__ATOMIC_RELEASE, "agent");
;             asm volatile("s_waitcnt vmcnt(0)" ::: "memory");
;             const unsigned og = xb_add(&bar[XB_TOP], 1u);
;             const unsigned tg = og / nx;
;             if (og + 1u == (tg + 1u) * nx) xb_add(&bar[XB_TOPGEN], 1u);
;             else XB_SPIN(xb_ld(&bar[XB_TOPGEN]) == tg, bar);
;             __builtin_amdgcn_fence(__ATOMIC_ACQUIRE, "agent");
;             xb_add(&bar[XB_XGEN(bx_)], 1u);
.LBB0_226:
	s_andn2_saveexec_b64 s[0:1], s[0:1]
	s_cbranch_execz .LBB0_242
	v_mov_b32_e32 v1, s34
	v_add_co_u32_e32 v2, vcc, 0x3000, v1
	v_mov_b32_e32 v1, s35
	buffer_wbl2 sc1
	s_waitcnt vmcnt(0)
	v_addc_co_u32_e32 v3, vcc, 0, v1, vcc
	v_mov_b32_e32 v1, 1
	flat_atomic_add v1, v[2:3], v1 offset:1024 sc0
	v_cvt_f32_u32_e32 v2, v0
	v_sub_u32_e32 v3, 0, v0
	s_mov_b64 s[8:9], -1
	v_rcp_iflag_f32_e32 v2, v2
	s_nop 0
	v_mul_f32_e32 v2, 0x4f7ffffe, v2
	v_cvt_u32_f32_e32 v2, v2
	v_mul_lo_u32 v3, v3, v2
	v_mul_hi_u32 v3, v2, v3
	v_add_u32_e32 v2, v2, v3
	s_waitcnt vmcnt(0) lgkmcnt(0)
	v_mul_hi_u32 v2, v1, v2
	v_mul_lo_u32 v3, v2, v0
	v_sub_u32_e32 v3, v1, v3
	v_cmp_ge_u32_e32 vcc, v3, v0
	v_add_u32_e32 v4, 1, v2
	s_nop 0
	v_cndmask_b32_e32 v2, v2, v4, vcc
	v_sub_u32_e32 v4, v3, v0
	v_cndmask_b32_e32 v3, v3, v4, vcc
	v_cmp_ge_u32_e32 vcc, v3, v0
	v_add_u32_e32 v3, 1, v2
	s_nop 0
	v_cndmask_b32_e32 v2, v2, v3, vcc
	v_add_u32_e32 v3, 1, v1
	v_mad_u64_u32 v[0:1], s[4:5], v0, v2, v[0:1]
	s_add_u32 s4, s34, 0x3500
	s_addc_u32 s5, s35, 0
	v_cmp_ne_u32_e32 vcc, v3, v0
	v_mov_b64_e32 v[0:1], s[4:5]
	s_and_saveexec_b64 s[6:7], vcc
	s_cbranch_execz .LBB0_239
	v_mov_b64_e32 v[0:1], s[4:5]
	global_load_dword v0, v[0:1], off sc1
	s_mov_b64 s[12:13], 0
	s_waitcnt vmcnt(0) lgkmcnt(0)
	v_cmp_eq_u32_e32 vcc, v0, v2
	s_and_saveexec_b64 s[10:11], vcc
	s_cbranch_execz .LBB0_238
	s_add_u32 s8, s34, 0x200
	s_addc_u32 s9, s35, 0
	s_mov_b32 s25, 1
	s_branch .LBB0_231

; __device__ __forceinline__ unsigned xb_ld(unsigned* p)              { return __hip_atomic_load(p, __ATOMIC_RELAXED, __HIP_MEMORY_SCOPE_AGENT); }
; #define XB_SPIN(cond, bar) do { unsigned _sp = 0; while (cond) { __builtin_amdgcn_s_sleep(1); \
;     if ((++_sp & 255u) == 0u) { if (xb_ld(&(bar)[XB_TMO])) break; if (_sp > XB_SPIN_CAP) { atomicAdd(&(bar)[XB_TMO], 1u); break; } } } } while (0)
; __device__ __forceinline__ void xcd_barrier(const XcdBarrier& b, int tid) {
;     ...
;             else XB_SPIN(xb_ld(&bar[XB_TOPGEN]) == tg, bar);
.LBB0_233:
	v_mov_b64_e32 v[0:1], s[8:9]
	global_load_dword v0, v[0:1], off sc1
	s_mov_b64 s[20:21], 0
	s_mov_b64 s[18:19], -1
	s_waitcnt vmcnt(0) lgkmcnt(0)
	v_cmp_eq_u32_e32 vcc, 0, v0
	s_and_saveexec_b64 s[22:23], vcc
	s_cmp_lt_u32 s25, 0x40001
	s_cselect_b64 s[20:21], -1, 0
	s_xor_b64 s[18:19], exec, -1
	s_and_b64 s[20:21], s[20:21], exec
	s_or_b64 exec, exec, s[22:23]
	s_and_saveexec_b64 s[22:23], s[20:21]
	s_cbranch_execz .LBB0_230
.LBB0_236:
	v_mov_b64_e32 v[0:1], s[4:5]
	global_load_dword v0, v[0:1], off sc1
	s_add_i32 s25, s25, 1
	s_or_b64 s[18:19], s[18:19], exec
	s_waitcnt vmcnt(0) lgkmcnt(0)
	v_cmp_ne_u32_e32 vcc, v0, v2
	s_orn2_b64 s[16:17], vcc, exec
	s_branch .LBB0_230

; __device__ __forceinline__ unsigned cvt_pk_bf16(float lo, float hi) { unsigned r; asm volatile("v_cvt_pk_bf16_f32 %0, %1, %2" : "=v"(r) : "v"(lo), "v"(hi)); return r; }
;     __device__ __forceinline__ void operator()(const f32x4 (&acc)[2][2][4][2], const Unit& u, int wr, int wc, int fr, int fq) const {
;         const int lane = fr + 16 * fq, r2 = lane >> 2, q2 = lane & 3;
;         const int src4 = (r2 + 16 * q2) << 2;
;         const int row0 = u.pm * BM + wr * 64 + r2; const int col0 = u.pn * BM + wc * 32 + 8 * q2;
; #pragma unroll
;         for (int ai = 0; ai < 2; ++ai)
; #pragma unroll
;             for (int m = 0; m < 4; ++m) { bf16_t* rowp = O + (size_t)(row0 + ai * HALF + m * 16) * ldc + col0;
; #pragma unroll
;                 for (int bj = 0; bj < 2; ++bj) { f32x4 v0 = acc[ai][bj][m][0], v1 = acc[ai][bj][m][1];
;                     if (ACT == 1) {
; #pragma unroll
;                         for (int j = 0; j < 4; ++j) { const float a = fmaxf(v0[j], 0.f), b = fmaxf(v1[j], 0.f); v0[j] = a * a; v1[j] = b * b; } }
;                     u32x4 w; w.x = cvt_pk_bf16(v0[0], v0[1]); w.y = cvt_pk_bf16(v0[2], v0[3]); w.z = cvt_pk_bf16(v1[0], v1[1]); w.w = cvt_pk_bf16(v1[2], v1[3]);
;                     w.x = (unsigned)__builtin_amdgcn_ds_bpermute(src4, (int)w.x); w.y = (unsigned)__builtin_amdgcn_ds_bpermute(src4, (int)w.y);
;                     w.z = (unsigned)__builtin_amdgcn_ds_bpermute(src4, (int)w.z); w.w = (unsigned)__builtin_amdgcn_ds_bpermute(src4, (int)w.w);
;                     *(u32x4*)(rowp + bj * HALF) = w; } }
;     }
.LBB0_255:
	v_cvt_pk_bf16_f32 v128, v128, v129
	v_cvt_pk_bf16_f32 v129, v130, v131
	v_cvt_pk_bf16_f32 v124, v124, v125
	v_cvt_pk_bf16_f32 v125, v126, v127
	ds_bpermute_b32 v126, v143, v128
	ds_bpermute_b32 v127, v143, v129
	ds_bpermute_b32 v128, v143, v124
	ds_bpermute_b32 v129, v143, v125
	v_lshl_or_b32 v156, s50, 8, v145
	v_lshl_add_u32 v147, s51, 8, v144
	v_ashrrev_i32_e32 v157, 31, v156
	v_mov_b64_e32 v[140:141], s[8:9]
	v_mad_i64_i32 v[130:131], s[20:21], v147, s77, v[140:141]
	v_lshlrev_b64 v[124:125], 1, v[156:157]
	v_lshl_add_u64 v[130:131], v[130:131], 0, v[124:125]
	s_waitcnt lgkmcnt(0)
	global_store_dwordx4 v[130:131], v[126:129], off
	v_cvt_pk_bf16_f32 v116, v116, v117
	v_cvt_pk_bf16_f32 v117, v118, v119
	v_cvt_pk_bf16_f32 v118, v108, v109
	v_cvt_pk_bf16_f32 v111, v110, v111
	ds_bpermute_b32 v108, v143, v116
	ds_bpermute_b32 v109, v143, v117
	ds_bpermute_b32 v110, v143, v118
	ds_bpermute_b32 v111, v143, v111
	s_andn2_b64 vcc, exec, s[0:1]
	s_mov_b64 s[0:1], -1
	s_waitcnt lgkmcnt(0)
	global_store_dwordx4 v[130:131], v[108:111], off offset:256
	s_nop 1
	v_cvt_pk_bf16_f32 v108, v120, v121
	v_cvt_pk_bf16_f32 v109, v122, v123
	v_cvt_pk_bf16_f32 v110, v112, v113
	v_cvt_pk_bf16_f32 v111, v114, v115
	ds_bpermute_b32 v108, v143, v108
	ds_bpermute_b32 v109, v143, v109
	ds_bpermute_b32 v110, v143, v110
	ds_bpermute_b32 v111, v143, v111
	v_or_b32_e32 v112, 16, v147
	v_mad_i64_i32 v[112:113], s[20:21], v112, s77, v[140:141]
	v_lshl_add_u64 v[112:113], v[112:113], 0, v[124:125]
	s_waitcnt lgkmcnt(0)
	global_store_dwordx4 v[112:113], v[108:111], off
	v_cvt_pk_bf16_f32 v100, v100, v101
	v_cvt_pk_bf16_f32 v101, v102, v103
	v_cvt_pk_bf16_f32 v102, v92, v93
	v_cvt_pk_bf16_f32 v95, v94, v95
	ds_bpermute_b32 v92, v143, v100
	ds_bpermute_b32 v93, v143, v101
	ds_bpermute_b32 v94, v143, v102
	ds_bpermute_b32 v95, v143, v95
	s_waitcnt lgkmcnt(0)
	global_store_dwordx4 v[112:113], v[92:95], off offset:256
	s_nop 1
	v_cvt_pk_bf16_f32 v92, v104, v105
	v_cvt_pk_bf16_f32 v93, v106, v107
	v_cvt_pk_bf16_f32 v94, v96, v97
	v_cvt_pk_bf16_f32 v95, v98, v99
	ds_bpermute_b32 v92, v143, v92
	ds_bpermute_b32 v93, v143, v93
	ds_bpermute_b32 v94, v143, v94
	ds_bpermute_b32 v95, v143, v95
	v_or_b32_e32 v96, 32, v147
	v_mad_i64_i32 v[96:97], s[20:21], v96, s77, v[140:141]
	v_lshl_add_u64 v[96:97], v[96:97], 0, v[124:125]
	s_waitcnt lgkmcnt(0)
	global_store_dwordx4 v[96:97], v[92:95], off
	v_cvt_pk_bf16_f32 v84, v84, v85
	v_cvt_pk_bf16_f32 v85, v86, v87
	v_cvt_pk_bf16_f32 v86, v76, v77
	v_cvt_pk_bf16_f32 v79, v78, v79
	ds_bpermute_b32 v76, v143, v84
	ds_bpermute_b32 v77, v143, v85
	ds_bpermute_b32 v78, v143, v86
	ds_bpermute_b32 v79, v143, v79
	s_waitcnt lgkmcnt(0)
	global_store_dwordx4 v[96:97], v[76:79], off offset:256
	s_nop 1
	v_cvt_pk_bf16_f32 v76, v88, v89
	v_cvt_pk_bf16_f32 v77, v90, v91
	v_cvt_pk_bf16_f32 v78, v80, v81
	v_cvt_pk_bf16_f32 v79, v82, v83
	ds_bpermute_b32 v76, v143, v76
	ds_bpermute_b32 v77, v143, v77
	ds_bpermute_b32 v78, v143, v78
	ds_bpermute_b32 v79, v143, v79
	v_or_b32_e32 v80, 48, v147
	v_mad_i64_i32 v[80:81], s[20:21], v80, s77, v[140:141]
	v_lshl_add_u64 v[80:81], v[80:81], 0, v[124:125]
	s_waitcnt lgkmcnt(0)
	global_store_dwordx4 v[80:81], v[76:79], off
	v_cvt_pk_bf16_f32 v72, v72, v73
	v_cvt_pk_bf16_f32 v73, v74, v75
	v_cvt_pk_bf16_f32 v74, v68, v69
	v_cvt_pk_bf16_f32 v71, v70, v71
	ds_bpermute_b32 v68, v143, v72
	ds_bpermute_b32 v69, v143, v73
	ds_bpermute_b32 v70, v143, v74
	ds_bpermute_b32 v71, v143, v71
	s_waitcnt lgkmcnt(0)
	global_store_dwordx4 v[80:81], v[68:71], off offset:256
	v_cvt_pk_bf16_f32 v64, v64, v65
	v_cvt_pk_bf16_f32 v65, v66, v67
	v_cvt_pk_bf16_f32 v66, v60, v61
	v_cvt_pk_bf16_f32 v63, v62, v63
	ds_bpermute_b32 v60, v143, v64
	ds_bpermute_b32 v61, v143, v65
	ds_bpermute_b32 v62, v143, v66
	ds_bpermute_b32 v63, v143, v63
	v_add_u32_e32 v64, 0x80, v147
	v_mad_i64_i32 v[64:65], s[20:21], v64, s77, v[140:141]
	v_lshl_add_u64 v[64:65], v[64:65], 0, v[124:125]
	s_waitcnt lgkmcnt(0)
	global_store_dwordx4 v[64:65], v[60:63], off
	v_cvt_pk_bf16_f32 v52, v52, v53
	v_cvt_pk_bf16_f32 v53, v54, v55
	v_cvt_pk_bf16_f32 v54, v44, v45
	v_cvt_pk_bf16_f32 v47, v46, v47
	ds_bpermute_b32 v44, v143, v52
	ds_bpermute_b32 v45, v143, v53
	ds_bpermute_b32 v46, v143, v54
	ds_bpermute_b32 v47, v143, v47
	s_waitcnt lgkmcnt(0)
	global_store_dwordx4 v[64:65], v[44:47], off offset:256
	s_nop 1
	v_cvt_pk_bf16_f32 v44, v56, v57
	v_cvt_pk_bf16_f32 v45, v58, v59
	v_cvt_pk_bf16_f32 v46, v48, v49
	v_cvt_pk_bf16_f32 v47, v50, v51
	ds_bpermute_b32 v44, v143, v44
	ds_bpermute_b32 v45, v143, v45
	ds_bpermute_b32 v46, v143, v46
	ds_bpermute_b32 v47, v143, v47
	v_add_u32_e32 v48, 0x90, v147
	v_mad_i64_i32 v[48:49], s[20:21], v48, s77, v[140:141]
	v_lshl_add_u64 v[48:49], v[48:49], 0, v[124:125]
	s_waitcnt lgkmcnt(0)
	global_store_dwordx4 v[48:49], v[44:47], off
	v_cvt_pk_bf16_f32 v36, v36, v37
	v_cvt_pk_bf16_f32 v37, v38, v39
	v_cvt_pk_bf16_f32 v38, v28, v29
	v_cvt_pk_bf16_f32 v31, v30, v31
	ds_bpermute_b32 v28, v143, v36
	ds_bpermute_b32 v29, v143, v37
	ds_bpermute_b32 v30, v143, v38
	ds_bpermute_b32 v31, v143, v31
	s_waitcnt lgkmcnt(0)
	global_store_dwordx4 v[48:49], v[28:31], off offset:256
	s_nop 1
	v_cvt_pk_bf16_f32 v28, v40, v41
	v_cvt_pk_bf16_f32 v29, v42, v43
	v_cvt_pk_bf16_f32 v30, v32, v33
	v_cvt_pk_bf16_f32 v31, v34, v35
	ds_bpermute_b32 v28, v143, v28
	ds_bpermute_b32 v29, v143, v29
	ds_bpermute_b32 v30, v143, v30
	ds_bpermute_b32 v31, v143, v31
	v_add_u32_e32 v32, 0xa0, v147
	v_mad_i64_i32 v[32:33], s[20:21], v32, s77, v[140:141]
	v_lshl_add_u64 v[32:33], v[32:33], 0, v[124:125]
	s_waitcnt lgkmcnt(0)
	global_store_dwordx4 v[32:33], v[28:31], off
	v_cvt_pk_bf16_f32 v20, v20, v21
	v_cvt_pk_bf16_f32 v21, v22, v23
	v_cvt_pk_bf16_f32 v22, v12, v13
	v_cvt_pk_bf16_f32 v15, v14, v15
	ds_bpermute_b32 v12, v143, v20
	ds_bpermute_b32 v13, v143, v21
	ds_bpermute_b32 v14, v143, v22
	ds_bpermute_b32 v15, v143, v15
	s_waitcnt lgkmcnt(0)
	global_store_dwordx4 v[32:33], v[12:15], off offset:256
	s_nop 1
	v_cvt_pk_bf16_f32 v12, v24, v25
	v_cvt_pk_bf16_f32 v13, v26, v27
	v_cvt_pk_bf16_f32 v14, v16, v17
	v_cvt_pk_bf16_f32 v15, v18, v19
	ds_bpermute_b32 v12, v143, v12
	ds_bpermute_b32 v13, v143, v13
	ds_bpermute_b32 v14, v143, v14
	ds_bpermute_b32 v15, v143, v15
	v_add_u32_e32 v16, 0xb0, v147
	v_mad_i64_i32 v[16:17], s[20:21], v16, s77, v[140:141]
	v_lshl_add_u64 v[16:17], v[16:17], 0, v[124:125]
	s_waitcnt lgkmcnt(0)
	global_store_dwordx4 v[16:17], v[12:15], off
	v_cvt_pk_bf16_f32 v4, v4, v5
	v_cvt_pk_bf16_f32 v5, v6, v7
	v_cvt_pk_bf16_f32 v6, v0, v1
	v_cvt_pk_bf16_f32 v3, v2, v3
	ds_bpermute_b32 v0, v143, v4
	ds_bpermute_b32 v1, v143, v5
	ds_bpermute_b32 v2, v143, v6
	ds_bpermute_b32 v3, v143, v3
	s_waitcnt lgkmcnt(0)
	global_store_dwordx4 v[16:17], v[0:3], off offset:256
	s_cbranch_vccnz .LBB0_248
	s_andn2_b64 vcc, exec, s[6:7]
	s_cbranch_vccnz .LBB0_247
	s_barrier
	s_branch .LBB0_247

; __device__ __forceinline__ f32x4 mfma16(bf16x8 a, bf16x8 b, f32x4 c) { return __builtin_amdgcn_mfma_f32_16x16x32_bf16(a, b, c, 0, 0, 0); }
; template <int RT, class Epi>
; __device__ __forceinline__ void skinny_gemm(const bf16* A, size_t lda, const bf16* Bt, int K, int N, const Epi& epi, int wg, int wg_first, int wg_count, int tid, LAS unsigned char* lds) {
;     ...
;     for (int s = me; s < nunit; s += wg_count) {
;         const int n0 = 32 * (s / NRG), r0 = (s % NRG) * (16 * RT);
;         f32x4 acc[RT][2];
; #pragma unroll
;         for (int rt = 0; rt < RT; ++rt) { acc[rt][0] = (f32x4){0.f, 0.f, 0.f, 0.f}; acc[rt][1] = (f32x4){0.f, 0.f, 0.f, 0.f}; }
;         const bf16* ap = A + (size_t)(r0 + c) * lda + (size_t)w * (K / 8) + 8 * g;
;         const bf16* bp = Bt + (size_t)(n0 + c) * K + (size_t)w * (K / 8) + 8 * g;
; #pragma unroll 4
;         for (int ks = 0; ks < ksteps; ++ks) {
;             bf16x8 af[RT], bfr[2];
; #pragma unroll
;             for (int rt = 0; rt < RT; ++rt) af[rt] = *(const bf16x8*)(ap + (size_t)(16 * rt) * lda + 32 * ks);
;             bfr[0] = *(const bf16x8*)(bp + 32 * ks); bfr[1] = *(const bf16x8*)(bp + (size_t)16 * K + 32 * ks);
; #pragma unroll
;             for (int rt = 0; rt < RT; ++rt) { acc[rt][0] = mfma16(af[rt], bfr[0], acc[rt][0]); acc[rt][1] = mfma16(af[rt], bfr[1], acc[rt][1]); }
;         }
.LBB0_261:
	v_add_u32_e32 v10, s0, v149
	global_load_dwordx4 v[0:3], v[8:9], off
	global_load_dwordx4 v[4:7], v[90:91], off
	v_lshlrev_b64 v[12:13], 11, v[10:11]
	global_load_dwordx4 v[16:19], v[92:93], off
	global_load_dwordx4 v[20:23], v[94:95], off
	global_load_dwordx4 v[24:27], v[96:97], off
	global_load_dwordx4 v[28:31], v[98:99], off
	global_load_dwordx4 v[58:61], v[100:101], off
	global_load_dwordx4 v[66:69], v[102:103], off
	v_lshl_add_u64 v[32:33], v[88:89], 0, v[12:13]
	v_add_co_u32_e32 v56, vcc, 0x8000, v32
	global_load_dwordx4 v[12:15], v[32:33], off
	s_nop 0
	v_addc_co_u32_e32 v57, vcc, 0, v33, vcc
	global_load_dwordx4 v[78:81], v[56:57], off
	global_load_dwordx4 v[82:85], v[104:105], off
	global_load_dwordx4 v[168:171], v[106:107], off
	global_load_dwordx4 v[172:175], v[108:109], off
	global_load_dwordx4 v[188:191], v[110:111], off
	global_load_dwordx4 v[192:195], v[112:113], off
	global_load_dwordx4 v[196:199], v[114:115], off
	global_load_dwordx4 v[200:203], v[116:117], off
	global_load_dwordx4 v[208:211], v[130:131], off
	v_add_u32_e32 v150, 0x3800, v158
	s_add_i32 s1, s1, s2
	v_add_u32_e32 v10, s0, v156
	s_add_i32 s0, s0, s3
	s_cmpk_lt_i32 s1, 0x188
	s_waitcnt vmcnt(0) lgkmcnt(0)
	v_mfma_f32_16x16x32_bf16 v[34:37], v[0:3], v[12:15], 0
	global_load_dwordx4 v[212:215], v[56:57], off offset:128
	v_mfma_f32_16x16x32_bf16 v[38:41], v[4:7], v[12:15], 0
	v_mfma_f32_16x16x32_bf16 v[42:45], v[16:19], v[12:15], 0
	v_mfma_f32_16x16x32_bf16 v[46:49], v[20:23], v[12:15], 0
	v_mfma_f32_16x16x32_bf16 v[50:53], v[24:27], v[12:15], 0
	v_mfma_f32_16x16x32_bf16 v[62:65], v[28:31], v[12:15], 0
	v_mfma_f32_16x16x32_bf16 v[70:73], v[58:61], v[12:15], 0
	v_mfma_f32_16x16x32_bf16 v[74:77], v[66:69], v[12:15], 0
	v_mfma_f32_16x16x32_bf16 v[12:15], v[16:19], v[78:81], 0
	v_mfma_f32_16x16x32_bf16 v[16:19], v[20:23], v[78:81], 0
	v_mfma_f32_16x16x32_bf16 v[20:23], v[24:27], v[78:81], 0
	v_mfma_f32_16x16x32_bf16 v[24:27], v[28:31], v[78:81], 0
	v_mfma_f32_16x16x32_bf16 v[28:31], v[58:61], v[78:81], 0
	global_load_dwordx4 v[58:61], v[8:9], off offset:64
	v_mfma_f32_16x16x32_bf16 v[0:3], v[0:3], v[78:81], 0
	v_mfma_f32_16x16x32_bf16 v[4:7], v[4:7], v[78:81], 0
	v_mfma_f32_16x16x32_bf16 v[66:69], v[66:69], v[78:81], 0
	global_load_dwordx4 v[78:81], v[32:33], off offset:64
	s_waitcnt vmcnt(0) lgkmcnt(0)
	v_mfma_f32_16x16x32_bf16 v[34:37], v[58:61], v[78:81], v[34:37]
	v_mfma_f32_16x16x32_bf16 v[38:41], v[82:85], v[78:81], v[38:41]
	v_mfma_f32_16x16x32_bf16 v[42:45], v[168:171], v[78:81], v[42:45]
	v_mfma_f32_16x16x32_bf16 v[46:49], v[172:175], v[78:81], v[46:49]
	v_mfma_f32_16x16x32_bf16 v[50:53], v[188:191], v[78:81], v[50:53]
	v_mfma_f32_16x16x32_bf16 v[62:65], v[192:195], v[78:81], v[62:65]
	v_mfma_f32_16x16x32_bf16 v[70:73], v[196:199], v[78:81], v[70:73]
	v_mfma_f32_16x16x32_bf16 v[74:77], v[200:203], v[78:81], v[74:77]
	global_load_dwordx4 v[78:81], v[56:57], off offset:64
	s_waitcnt vmcnt(0) lgkmcnt(0)
	v_mfma_f32_16x16x32_bf16 v[0:3], v[58:61], v[78:81], v[0:3]
	global_load_dwordx4 v[58:61], v[8:9], off offset:128
	v_mfma_f32_16x16x32_bf16 v[4:7], v[82:85], v[78:81], v[4:7]
	v_mfma_f32_16x16x32_bf16 v[12:15], v[168:171], v[78:81], v[12:15]
	global_load_dwordx4 v[168:171], v[120:121], off
	v_mfma_f32_16x16x32_bf16 v[16:19], v[172:175], v[78:81], v[16:19]
	v_mfma_f32_16x16x32_bf16 v[20:23], v[188:191], v[78:81], v[20:23]
	global_load_dwordx4 v[188:191], v[124:125], off
	v_mfma_f32_16x16x32_bf16 v[24:27], v[192:195], v[78:81], v[24:27]
	v_mfma_f32_16x16x32_bf16 v[28:31], v[196:199], v[78:81], v[28:31]
	v_mfma_f32_16x16x32_bf16 v[84:87], v[200:203], v[78:81], v[66:69]
	global_load_dwordx4 v[78:81], v[118:119], off
	global_load_dwordx4 v[200:203], v[128:129], off
	s_nop 0
	global_load_dwordx4 v[66:69], v[32:33], off offset:128
	s_waitcnt vmcnt(0) lgkmcnt(0)
	v_mfma_f32_16x16x32_bf16 v[172:175], v[168:171], v[66:69], v[42:45]
	s_nop 2
	global_load_dwordx4 v[42:45], v[122:123], off
	v_mfma_f32_16x16x32_bf16 v[192:195], v[188:191], v[66:69], v[50:53]
	s_nop 2
	global_load_dwordx4 v[50:53], v[126:127], off
	v_mfma_f32_16x16x32_bf16 v[34:37], v[58:61], v[66:69], v[34:37]
	v_mfma_f32_16x16x32_bf16 v[38:41], v[78:81], v[66:69], v[38:41]
	s_waitcnt vmcnt(0) lgkmcnt(0)
	v_mfma_f32_16x16x32_bf16 v[46:49], v[42:45], v[66:69], v[46:49]
	v_mfma_f32_16x16x32_bf16 v[196:199], v[50:53], v[66:69], v[62:65]
	v_mfma_f32_16x16x32_bf16 v[204:207], v[200:203], v[66:69], v[70:73]
	v_mfma_f32_16x16x32_bf16 v[72:75], v[208:211], v[66:69], v[74:77]
	v_mfma_f32_16x16x32_bf16 v[64:67], v[58:61], v[212:215], v[0:3]
	global_load_dwordx4 v[56:59], v[56:57], off offset:192
	v_mfma_f32_16x16x32_bf16 v[68:71], v[78:81], v[212:215], v[4:7]
	v_mfma_f32_16x16x32_bf16 v[76:79], v[168:171], v[212:215], v[12:15]
	global_load_dwordx4 v[168:171], v[8:9], off offset:192
	v_mfma_f32_16x16x32_bf16 v[60:63], v[188:191], v[212:215], v[20:23]
	global_load_dwordx4 v[188:191], v[132:133], off
	v_mfma_f32_16x16x32_bf16 v[0:3], v[200:203], v[212:215], v[28:31]
	global_load_dwordx4 v[200:203], v[134:135], off
	v_mfma_f32_16x16x32_bf16 v[80:83], v[42:45], v[212:215], v[16:19]
	s_nop 2
	global_load_dwordx4 v[16:19], v[32:33], off offset:192
	v_mfma_f32_16x16x32_bf16 v[4:7], v[208:211], v[212:215], v[84:87]
	global_load_dwordx4 v[208:211], v[138:139], off
	s_waitcnt vmcnt(0) lgkmcnt(0)
; #define LAS __attribute__((address_space(3)))
; __device__ __forceinline__ f32x4 mfma16(bf16x8 a, bf16x8 b, f32x4 c) { return __builtin_amdgcn_mfma_f32_16x16x32_bf16(a, b, c, 0, 0, 0); }
; __device__ __forceinline__ void sync_threads() { __syncthreads(); }
; template <int RT, class Epi>
; __device__ __forceinline__ void skinny_gemm(const bf16* A, size_t lda, const bf16* Bt, int K, int N, const Epi& epi, int wg, int wg_first, int wg_count, int tid, LAS unsigned char* lds) {
;     ...
;             for (int rt = 0; rt < RT; ++rt) { acc[rt][0] = mfma16(af[rt], bfr[0], acc[rt][0]); acc[rt][1] = mfma16(af[rt], bfr[1], acc[rt][1]); }
;         }
;         LAS float* part = (LAS float*)(lds + w * SK_PART);
; #pragma unroll
;         for (int rt = 0; rt < RT; ++rt)
; #pragma unroll
;             for (int nt = 0; nt < 2; ++nt)
; #pragma unroll
;                 for (int r = 0; r < 4; ++r) part[(16 * rt + 4 * g + r) * 32 + 16 * nt + c] = acc[rt][nt][r];
;         sync_threads();
;         if (RT == 8 || tid < 64 * RT) {
;             const int row = tid >> 2, c8 = (tid & 3) * 8;
;             f32x4 v0 = (f32x4){0.f, 0.f, 0.f, 0.f}, v1 = (f32x4){0.f, 0.f, 0.f, 0.f};
; #pragma unroll
;             for (int ww = 0; ww < 8; ++ww) { const LAS float* pp = (const LAS float*)(lds + ww * SK_PART) + row * 32 + c8; v0 = v0 + *(const LAS f32x4*)pp; v1 = v1 + *(const LAS f32x4*)(pp + 4); }
;             epi(r0 + row, n0 + c8, v0, v1);
;         }
;         sync_threads();
;     }
; }
	v_mfma_f32_16x16x32_bf16 v[12:15], v[168:171], v[16:19], v[34:37]
	v_mfma_f32_16x16x32_bf16 v[40:43], v[188:191], v[16:19], v[38:41]
	v_mfma_f32_16x16x32_bf16 v[36:39], v[200:203], v[16:19], v[172:175]
	s_nop 2
	global_load_dwordx4 v[172:175], v[136:137], off
	v_mfma_f32_16x16x32_bf16 v[52:55], v[50:53], v[212:215], v[24:27]
	v_mfma_f32_16x16x32_bf16 v[28:31], v[208:211], v[16:19], v[192:195]
	s_nop 2
	global_load_dwordx4 v[192:195], v[140:141], off
	s_waitcnt vmcnt(0) lgkmcnt(0)
	v_mfma_f32_16x16x32_bf16 v[32:35], v[172:175], v[16:19], v[46:49]
	s_nop 2
	global_load_dwordx4 v[48:51], v[142:143], off
	global_load_dwordx4 v[44:47], v[144:145], off
	v_mfma_f32_16x16x32_bf16 v[84:87], v[168:171], v[56:59], v[64:67]
	v_mfma_f32_16x16x32_bf16 v[24:27], v[192:195], v[16:19], v[196:199]
	s_waitcnt vmcnt(0) lgkmcnt(0)
	v_mfma_f32_16x16x32_bf16 v[20:23], v[48:51], v[16:19], v[204:207]
	v_mfma_f32_16x16x32_bf16 v[16:19], v[44:47], v[16:19], v[72:75]
	v_mfma_f32_16x16x32_bf16 v[64:67], v[172:175], v[56:59], v[80:83]
	v_mfma_f32_16x16x32_bf16 v[60:63], v[208:211], v[56:59], v[60:63]
	s_nop 1
	v_add_u32_e32 v80, 0x1800, v158
	v_add_u32_e32 v81, 0x2000, v158
	v_add_u32_e32 v82, 0x2800, v158
	v_mfma_f32_16x16x32_bf16 v[52:55], v[192:195], v[56:59], v[52:55]
	v_add_u32_e32 v83, 0x3000, v158
	v_mfma_f32_16x16x32_bf16 v[0:3], v[48:51], v[56:59], v[0:3]
	v_mfma_f32_16x16x32_bf16 v[4:7], v[44:47], v[56:59], v[4:7]
	v_mfma_f32_16x16x32_bf16 v[72:75], v[188:191], v[56:59], v[68:71]
	v_mfma_f32_16x16x32_bf16 v[68:71], v[200:203], v[56:59], v[76:79]
	s_nop 2
	v_add_u32_e32 v78, 0x800, v158
	v_add_u32_e32 v79, 0x1000, v158
	ds_write2_b32 v158, v12, v84 offset1:16
	ds_write2_b32 v158, v13, v85 offset0:32 offset1:48
	ds_write2_b32 v158, v14, v86 offset0:64 offset1:80
	ds_write2_b32 v158, v15, v87 offset0:96 offset1:112
	ds_write2_b32 v78, v40, v72 offset1:16
	ds_write2_b32 v78, v41, v73 offset0:32 offset1:48
	ds_write2_b32 v78, v42, v74 offset0:64 offset1:80
	ds_write2_b32 v78, v43, v75 offset0:96 offset1:112
	ds_write2_b32 v79, v36, v68 offset1:16
	ds_write2_b32 v79, v37, v69 offset0:32 offset1:48
	ds_write2_b32 v79, v38, v70 offset0:64 offset1:80
	ds_write2_b32 v79, v39, v71 offset0:96 offset1:112
	ds_write2_b32 v80, v32, v64 offset1:16
	ds_write2_b32 v80, v33, v65 offset0:32 offset1:48
	ds_write2_b32 v80, v34, v66 offset0:64 offset1:80
	ds_write2_b32 v80, v35, v67 offset0:96 offset1:112
	ds_write2_b32 v81, v28, v60 offset1:16
	ds_write2_b32 v81, v29, v61 offset0:32 offset1:48
	ds_write2_b32 v81, v30, v62 offset0:64 offset1:80
	ds_write2_b32 v81, v31, v63 offset0:96 offset1:112
	ds_write2_b32 v82, v24, v52 offset1:16
	ds_write2_b32 v82, v25, v53 offset0:32 offset1:48
	ds_write2_b32 v82, v26, v54 offset0:64 offset1:80
	ds_write2_b32 v82, v27, v55 offset0:96 offset1:112
	ds_write2_b32 v83, v20, v0 offset1:16
	ds_write2_b32 v83, v21, v1 offset0:32 offset1:48
	ds_write2_b32 v83, v22, v2 offset0:64 offset1:80
	ds_write2_b32 v83, v23, v3 offset0:96 offset1:112
	ds_write2_b32 v150, v16, v4 offset1:16
	ds_write2_b32 v150, v17, v5 offset0:32 offset1:48
	ds_write2_b32 v150, v18, v6 offset0:64 offset1:80
	ds_write2_b32 v150, v19, v7 offset0:96 offset1:112
	s_waitcnt lgkmcnt(0)
	s_barrier
	ds_read_b128 v[0:3], v157
	ds_read_b128 v[4:7], v157 offset:16
	ds_read_b128 v[12:15], v157 offset:16384
	ds_read_b128 v[16:19], v157 offset:16400
	ds_read_b128 v[20:23], v157 offset:32768
	ds_read_b128 v[24:27], v157 offset:32784
	ds_read_b128 v[28:31], v157 offset:49152
	ds_read_b128 v[32:35], v157 offset:49168
	ds_read_b128 v[36:39], v159
	ds_read_b128 v[40:43], v160
	ds_read_b128 v[44:47], v161
	ds_read_b128 v[48:51], v162
	ds_read_b128 v[52:55], v163
	ds_read_b128 v[56:59], v164
	ds_read_b128 v[60:63], v165
	ds_read_b128 v[64:67], v166
	s_waitcnt lgkmcnt(14)
	v_pk_add_f32 v[2:3], v[2:3], 0 op_sel_hi:[1,0]
	v_pk_add_f32 v[0:1], v[0:1], 0 op_sel_hi:[1,0]
	v_pk_add_f32 v[6:7], v[6:7], 0 op_sel_hi:[1,0]
	v_pk_add_f32 v[4:5], v[4:5], 0 op_sel_hi:[1,0]
	s_waitcnt lgkmcnt(13)
	v_pk_add_f32 v[2:3], v[2:3], v[14:15]
	v_pk_add_f32 v[0:1], v[0:1], v[12:13]
	s_waitcnt lgkmcnt(12)
	v_pk_add_f32 v[6:7], v[6:7], v[18:19]
	v_pk_add_f32 v[4:5], v[4:5], v[16:17]
	s_waitcnt lgkmcnt(11)
	v_pk_add_f32 v[2:3], v[2:3], v[22:23]
	v_pk_add_f32 v[0:1], v[0:1], v[20:21]
	s_waitcnt lgkmcnt(10)
	v_pk_add_f32 v[6:7], v[6:7], v[26:27]
	v_pk_add_f32 v[4:5], v[4:5], v[24:25]
	s_waitcnt lgkmcnt(9)
	v_pk_add_f32 v[2:3], v[2:3], v[30:31]
	v_pk_add_f32 v[0:1], v[0:1], v[28:29]
	s_waitcnt lgkmcnt(8)
	v_pk_add_f32 v[6:7], v[6:7], v[34:35]
	v_pk_add_f32 v[4:5], v[4:5], v[32:33]
	s_waitcnt lgkmcnt(7)
	v_pk_add_f32 v[2:3], v[2:3], v[38:39]
	v_pk_add_f32 v[0:1], v[0:1], v[36:37]
	s_waitcnt lgkmcnt(6)
	v_pk_add_f32 v[6:7], v[6:7], v[42:43]
	v_pk_add_f32 v[4:5], v[4:5], v[40:41]
	s_waitcnt lgkmcnt(5)
	v_pk_add_f32 v[2:3], v[2:3], v[46:47]
	v_pk_add_f32 v[0:1], v[0:1], v[44:45]
	s_waitcnt lgkmcnt(4)
	v_pk_add_f32 v[6:7], v[6:7], v[50:51]
	v_pk_add_f32 v[4:5], v[4:5], v[48:49]
	s_waitcnt lgkmcnt(3)
	v_pk_add_f32 v[2:3], v[2:3], v[54:55]
	v_pk_add_f32 v[0:1], v[0:1], v[52:53]
	v_lshl_add_u64 v[76:77], v[10:11], 1, v[146:147]
	s_waitcnt lgkmcnt(2)
	v_pk_add_f32 v[6:7], v[6:7], v[58:59]
	v_pk_add_f32 v[4:5], v[4:5], v[56:57]
	s_waitcnt lgkmcnt(1)
	v_pk_add_f32 v[2:3], v[2:3], v[62:63]
	v_pk_add_f32 v[0:1], v[0:1], v[60:61]
	s_waitcnt lgkmcnt(0)
	v_pk_add_f32 v[6:7], v[6:7], v[66:67]
	v_pk_add_f32 v[4:5], v[4:5], v[64:65]
	v_cvt_pk_bf16_f32 v0, v0, v1
	v_cvt_pk_bf16_f32 v1, v2, v3
	v_cvt_pk_bf16_f32 v3, v6, v7
	s_nop 0
	v_cvt_pk_bf16_f32 v2, v4, v5
	global_store_dwordx4 v[76:77], v[0:3], off
	s_waitcnt lgkmcnt(0)
	s_barrier
	s_cbranch_scc1 .LBB0_261

; #define LAS __attribute__((address_space(3)))
; __device__ __forceinline__ void ssd_pass1(const RecurBufs& rb, const float* conv_w, const float* conv_b, const float* dt_bias, const float* a_log, float* conv_out_l, int u, int tid, LAS unsigned char* lds) {
;     const int b = u >> 5, grp = (u >> 2) & 7, seg = u & 3, lane = tid & 63, w = tid >> 6;
;     LAS unsigned char* T = lds + SD_T; LAS float* sDt = (LAS float*)(lds + SD_DT); LAS float* sCum = (LAS float*)(lds + SD_CUM); LAS unsigned char* RH = lds + SD_RH;
;     const int cp = tid & 255, half = tid >> 8, t0c = 2 * cp;
;     const int chx = t0c < 256 ? (grp * 256 + t0c) : (t0c < 384 ? (2048 + grp * 128 + (t0c - 256)) : (3072 + grp * 128 + (t0c - 384)));
;     const int xcol = (t0c & ~63) + 16 * (t0c & 3) + ((t0c & 63) >> 2);
;     const f32x2r w0 = (f32x2r){conv_w[chx], conv_w[chx + 1]}, w1 = (f32x2r){conv_w[4096 + chx], conv_w[4096 + chx + 1]}, w2 = (f32x2r){conv_w[8192 + chx], conv_w[8192 + chx + 1]},
;                  w3 = (f32x2r){conv_w[12288 + chx], conv_w[12288 + chx + 1]}, cb = (f32x2r){conv_b[chx], conv_b[chx + 1]};
;     const size_t rowS = (size_t)b * SEQ + seg * SEGLEN;
;     if (half == 0) {
; #pragma unroll
;         for (int j = 0; j < 3; ++j) { unsigned v = 0u; if (seg > 0) v = *(const unsigned*)(rb.proj + (rowS - 3 + j) * LDP + PC_XBC + chx); *(LAS unsigned*)(RH + j * 1024 + cp * 4) = v; } }
.LBB0_317:
	s_andn2_saveexec_b64 s[4:5], s[4:5]
	v_lshl_or_b32 v10, s3, 8, v0
	s_or_b64 exec, exec, s[4:5]
	v_lshlrev_b64 v[0:1], 2, v[10:11]
	v_lshl_add_u64 v[2:3], s[30:31], 0, v[0:1]
	s_mov_b32 s4, 0xc000
	v_add_u32_e32 v8, 0x1000, v10
	v_mov_b32_e32 v9, v11
	v_add_u32_e32 v100, 0x2000, v10
	v_mov_b32_e32 v101, v11
	v_add_co_u32_e32 v12, vcc, s4, v2
	v_lshl_add_u64 v[4:5], v[8:9], 2, s[30:31]
	v_lshl_add_u64 v[6:7], v[100:101], 2, s[30:31]
	v_addc_co_u32_e32 v13, vcc, 0, v3, vcc
	global_load_dwordx2 v[102:103], v[2:3], off
	global_load_dwordx2 v[104:105], v[4:5], off
	global_load_dwordx2 v[106:107], v[6:7], off
	global_load_dwordx2 v[108:109], v[12:13], off
	v_lshl_add_u64 v[0:1], s[34:35], 0, v[0:1]
	global_load_dwordx2 v[112:113], v[0:1], off
	s_ashr_i32 s58, s2, 5
	s_and_b32 s22, s2, 3
	s_ashr_i32 s59, s58, 31
	s_lshl_b64 s[66:67], s[58:59], 11
	s_lshl_b32 s4, s22, 9
	s_or_b32 s66, s66, s4
	s_movk_i32 s4, 0x100
	v_cmp_gt_u32_e64 s[6:7], s4, v139
	v_lshlrev_b32_e32 v110, 2, v139
	s_and_saveexec_b64 s[4:5], s[6:7]
	s_cbranch_execz .LBB0_328
	s_cmp_lg_u32 s22, 0
	v_add_u32_e32 v0, 0, v110
	s_cselect_b64 s[8:9], -1, 0
	s_cmp_eq_u32 s22, 0
	s_mul_hi_u32 s12, s66, 0x6200
	s_mul_i32 s13, s66, 0x6200
	v_add_u32_e32 v0, 0x18800, v0
	s_cbranch_scc1 .LBB0_325
	s_mul_i32 s10, s67, 0x6200
	s_add_i32 s11, s12, s10
	s_add_u32 s10, s78, s13
	s_addc_u32 s11, s79, s11
	v_lshl_add_u64 v[2:3], v[10:11], 1, s[10:11]
	v_add_co_u32_e32 v4, vcc, 0xffff0a00, v2
	s_nop 1
	v_addc_co_u32_e32 v5, vcc, -1, v3, vcc
	global_load_dword v1, v[4:5], off
	v_add_co_u32_e32 v2, vcc, 0xffff6c00, v2
	s_waitcnt vmcnt(0) lgkmcnt(0)
	ds_write_b32 v0, v1
	v_addc_co_u32_e32 v3, vcc, -1, v3, vcc
	global_load_dword v1, v[2:3], off
	s_cbranch_execnz .LBB0_323

; #define LAS __attribute__((address_space(3)))
; __device__ __forceinline__ void ssd_pass1(const RecurBufs& rb, const float* conv_w, const float* conv_b, const float* dt_bias, const float* a_log, float* conv_out_l, int u, int tid, LAS unsigned char* lds) {
;     ...
;     if (half == 0) {
; #pragma unroll
;         for (int j = 0; j < 3; ++j) { unsigned v = 0u; if (seg > 0) v = *(const unsigned*)(rb.proj + (rowS - 3 + j) * LDP + PC_XBC + chx); *(LAS unsigned*)(RH + j * 1024 + cp * 4) = v; } }
.LBB0_323:
	s_add_i32 s10, 0, 0x18800
	v_add_u32_e32 v0, s10, v110
	s_andn2_b64 vcc, exec, s[8:9]
	s_waitcnt vmcnt(0) lgkmcnt(0)
	ds_write_b32 v0, v1 offset:1024
	s_cbranch_vccnz .LBB0_326
	s_mul_i32 s8, s67, 0x6200
	s_add_i32 s12, s12, s8
	s_add_u32 s8, s78, s13
	s_addc_u32 s9, s79, s12
	v_lshl_add_u64 v[2:3], v[10:11], 1, s[8:9]
	v_add_co_u32_e32 v2, vcc, 0xffffce00, v2
	s_nop 1
	v_addc_co_u32_e32 v3, vcc, -1, v3, vcc
	global_load_dword v1, v[2:3], off
	s_branch .LBB0_327

; #define LAS __attribute__((address_space(3)))
; #define LAUNDER_PTR(p) do {} while (0)
; #define LAUNDER_PTR(p) asm volatile("" : "+v"(p))
; __device__ __forceinline__ void ssd_pass1(const RecurBufs& rb, const float* conv_w, const float* conv_b, const float* dt_bias, const float* a_log, float* conv_out_l, int u, int tid, LAS unsigned char* lds) {
;     ...
;     const int ch16 = tid & 63, rr = tid >> 6;
;     const int gcol = ssd_gcol(grp, ch16);
;     LAS unsigned char* XO = lds + SD_XO;
;     v4u raw[8];
;     {   const bf16* gp = rb.proj + (rowS + rr) * LDP + PC_XBC + gcol;
; #pragma unroll
;         for (int i = 0; i < 8; ++i) { LAUNDER_PTR(gp); raw[i] = *(const v4u*)gp; gp += 8 * (size_t)LDP; } }
;     bf16 dtn = 0;
;     if (w < 4) dtn = rb.proj[(rowS + lane) * LDP + PC_DT + grp * 4 + w];
.LBB0_334:
	s_andn2_saveexec_b64 s[8:9], s[8:9]
	s_lshl_b32 s10, s3, 8
	v_lshl_or_b32 v114, v111, 3, s10
	s_or_b64 exec, exec, s[8:9]
	v_ashrrev_i32_e32 v116, 6, v139
	v_ashrrev_i32_e32 v117, 31, v116
	v_lshl_add_u64 v[0:1], s[66:67], 0, v[116:117]
	v_mov_b64_e32 v[2:3], s[78:79]
	v_mad_u64_u32 v[2:3], s[8:9], v0, s77, v[2:3]
	v_mov_b32_e32 v0, v3
	v_mad_u64_u32 v[0:1], s[8:9], v1, s77, v[0:1]
	v_mov_b32_e32 v3, v0
	v_mov_b32_e32 v115, v11
	v_lshl_add_u64 v[0:1], v[114:115], 1, v[2:3]
	v_lshl_add_u64 v[4:5], v[0:1], 0, s[92:93]
	global_load_dwordx4 v[0:3], v[4:5], off
	v_lshl_add_u64 v[12:13], v[4:5], 0, s[84:85]
	global_load_dwordx4 v[4:7], v[12:13], off
	v_lshl_add_u64 v[16:17], v[12:13], 0, s[84:85]
	global_load_dwordx4 v[12:15], v[16:17], off
	v_lshl_add_u64 v[20:21], v[16:17], 0, s[84:85]
	global_load_dwordx4 v[16:19], v[20:21], off
	v_lshl_add_u64 v[24:25], v[20:21], 0, s[84:85]
	global_load_dwordx4 v[20:23], v[24:25], off
	v_lshl_add_u64 v[28:29], v[24:25], 0, s[84:85]
	global_load_dwordx4 v[24:27], v[28:29], off
	v_lshl_add_u64 v[32:33], v[28:29], 0, s[84:85]
	global_load_dwordx4 v[28:31], v[32:33], off
	v_lshl_add_u64 v[32:33], v[32:33], 0, s[84:85]
	global_load_dwordx4 v[32:35], v[32:33], off
	v_cmp_gt_i32_e64 s[8:9], 4, v116
	v_cmp_lt_i32_e32 vcc, 3, v116
	s_and_saveexec_b64 s[10:11], vcc
	s_xor_b64 s[10:11], exec, s[10:11]
	s_lshl_b32 s12, s3, 2
	s_or_saveexec_b64 s[10:11], s[10:11]
	v_mov_b32_e32 v140, 0
	v_mov_b32_e32 v36, s12
	v_mov_b32_e32 v142, 0
	s_xor_b64 exec, exec, s[10:11]
	s_cbranch_execz .LBB0_340
	v_or_b32_e32 v38, s66, v111
	v_mov_b64_e32 v[36:37], s[78:79]
	s_mul_i32 s14, s67, 0x6200
	v_mad_u64_u32 v[36:37], s[12:13], v38, s77, v[36:37]
	v_add_u32_e32 v37, s14, v37
	s_lshl_b32 s64, s3, 3
	v_lshl_add_u64 v[36:37], v[36:37], 0, s[64:65]
	v_lshl_add_u64 v[36:37], v[116:117], 1, v[36:37]
	v_add_co_u32_e32 v36, vcc, 0x6000, v36
	s_lshl_b32 s3, s3, 2
	s_nop 0
	v_addc_co_u32_e32 v37, vcc, 0, v37, vcc
	global_load_ushort v142, v[36:37], off
	v_mov_b32_e32 v36, s3

; #define LAS __attribute__((address_space(3)))
; __device__ __forceinline__ void ssd_state_update(f32x4 (&H)[4][4], LAS unsigned char* Xi, int xp, LAS unsigned char* Bi, int bp, const LAS float* sDt, const LAS float* sCum, int w, int lane) {
;     const int g = lane >> 4, k = w >> 1, nh = w & 1;
;     const float tot = sCum[63 * 4 + k]; const float et = __expf(tot);
; #pragma unroll
;     for (int nt = 0; nt < 4; ++nt)
; #pragma unroll
;         for (int pt = 0; pt < 4; ++pt) H[nt][pt] = H[nt][pt] * et;
; #pragma unroll
;     for (int ks = 0; ks < 2; ++ks) {
;         float wg[8];
; #pragma unroll
;         for (int j = 0; j < 8; ++j) wg[j] = __expf(tot - sCum[(32 * ks + 8 * g + j) * 4 + k]) * sDt[(32 * ks + 8 * g + j) * 4 + k];
;         bf16x8 Bx[4];
; #pragma unroll
;         for (int pt = 0; pt < 4; ++pt) Bx[pt] = scale_frag8(frag_tr(Xi, xp, 32 * ks + 8 * g, 32 * ks + 8 * g + 4, 64 * k + 16 * pt, lane), wg);
; #pragma unroll
.LBB0_341:
	s_or_b64 exec, exec, s[50:51]
	s_waitcnt lgkmcnt(0)
	s_barrier
	ds_read_b32 v128, v157 offset:1008
	ds_read_b32 v132, v163
	ds_read_b32 v136, v171
	s_add_i32 s3, s3, 1
	ds_read_b32 v134, v167
	s_waitcnt lgkmcnt(0)
	v_mul_f32_e32 v129, 0x3fb8aa3b, v128
	v_exp_f32_e32 v130, v129
	ds_read_b32 v129, v158
	ds_read_b32 v133, v165
	ds_read_b32 v135, v169
	v_pk_mul_f32 v[98:99], v[98:99], v[130:131] op_sel_hi:[1,0]
	v_pk_mul_f32 v[96:97], v[96:97], v[130:131] op_sel_hi:[1,0]
	v_pk_mul_f32 v[94:95], v[94:95], v[130:131] op_sel_hi:[1,0]
	v_pk_mul_f32 v[92:93], v[92:93], v[130:131] op_sel_hi:[1,0]
	v_pk_mul_f32 v[90:91], v[90:91], v[130:131] op_sel_hi:[1,0]
	v_pk_mul_f32 v[88:89], v[88:89], v[130:131] op_sel_hi:[1,0]
	v_pk_mul_f32 v[86:87], v[86:87], v[130:131] op_sel_hi:[1,0]
	v_pk_mul_f32 v[84:85], v[84:85], v[130:131] op_sel_hi:[1,0]
	v_pk_mul_f32 v[70:71], v[70:71], v[130:131] op_sel_hi:[1,0]
	v_pk_mul_f32 v[68:69], v[68:69], v[130:131] op_sel_hi:[1,0]
	v_pk_mul_f32 v[74:75], v[74:75], v[130:131] op_sel_hi:[1,0]
	v_pk_mul_f32 v[72:73], v[72:73], v[130:131] op_sel_hi:[1,0]
	v_pk_mul_f32 v[78:79], v[78:79], v[130:131] op_sel_hi:[1,0]
	v_pk_mul_f32 v[76:77], v[76:77], v[130:131] op_sel_hi:[1,0]
	v_pk_mul_f32 v[82:83], v[82:83], v[130:131] op_sel_hi:[1,0]
	v_pk_mul_f32 v[80:81], v[80:81], v[130:131] op_sel_hi:[1,0]
	v_pk_mul_f32 v[62:63], v[62:63], v[130:131] op_sel_hi:[1,0]
	v_pk_mul_f32 v[60:61], v[60:61], v[130:131] op_sel_hi:[1,0]
	v_pk_mul_f32 v[66:67], v[66:67], v[130:131] op_sel_hi:[1,0]
	v_pk_mul_f32 v[64:65], v[64:65], v[130:131] op_sel_hi:[1,0]
	v_pk_mul_f32 v[58:59], v[58:59], v[130:131] op_sel_hi:[1,0]
	v_pk_mul_f32 v[56:57], v[56:57], v[130:131] op_sel_hi:[1,0]
	v_pk_mul_f32 v[54:55], v[54:55], v[130:131] op_sel_hi:[1,0]
	v_pk_mul_f32 v[52:53], v[52:53], v[130:131] op_sel_hi:[1,0]
	v_pk_mul_f32 v[50:51], v[50:51], v[130:131] op_sel_hi:[1,0]
	v_pk_mul_f32 v[48:49], v[48:49], v[130:131] op_sel_hi:[1,0]
	v_pk_mul_f32 v[46:47], v[46:47], v[130:131] op_sel_hi:[1,0]
	v_pk_mul_f32 v[44:45], v[44:45], v[130:131] op_sel_hi:[1,0]
	v_pk_mul_f32 v[42:43], v[42:43], v[130:131] op_sel_hi:[1,0]
	v_pk_mul_f32 v[40:41], v[40:41], v[130:131] op_sel_hi:[1,0]
	v_pk_mul_f32 v[38:39], v[38:39], v[130:131] op_sel_hi:[1,0]
	v_pk_mul_f32 v[36:37], v[36:37], v[130:131] op_sel_hi:[1,0]
	ds_read_b32 v130, v159
	ds_read_b32 v131, v161
	s_waitcnt lgkmcnt(0)
	v_sub_f32_e32 v129, v128, v129
	v_mul_f32_e32 v129, 0x3fb8aa3b, v129
	v_exp_f32_e32 v129, v129
	s_nop 0
	v_mul_f32_e32 v129, v130, v129
	ds_read_b32 v130, v160
	s_waitcnt lgkmcnt(0)
	v_sub_f32_e32 v130, v128, v130
	v_mul_f32_e32 v130, 0x3fb8aa3b, v130
	v_exp_f32_e32 v130, v130
	s_nop 0
	v_mul_f32_e32 v130, v131, v130
	ds_read_b32 v131, v162
	s_waitcnt lgkmcnt(0)
	v_sub_f32_e32 v131, v128, v131
	v_mul_f32_e32 v131, 0x3fb8aa3b, v131
	v_exp_f32_e32 v131, v131
	s_nop 0
	v_mul_f32_e32 v131, v132, v131
	ds_read_b32 v132, v164
	s_waitcnt lgkmcnt(0)
	v_sub_f32_e32 v132, v128, v132
	v_mul_f32_e32 v132, 0x3fb8aa3b, v132
	v_exp_f32_e32 v132, v132
	s_nop 0
	v_mul_f32_e32 v132, v133, v132
	ds_read_b32 v133, v166
	s_waitcnt lgkmcnt(0)
	v_sub_f32_e32 v133, v128, v133
	v_mul_f32_e32 v133, 0x3fb8aa3b, v133
	v_exp_f32_e32 v133, v133
	s_nop 0
	v_mul_f32_e32 v133, v134, v133
	ds_read_b32 v134, v168
	s_waitcnt lgkmcnt(0)
	v_sub_f32_e32 v134, v128, v134
	v_mul_f32_e32 v134, 0x3fb8aa3b, v134
	v_exp_f32_e32 v134, v134
	s_nop 0
	v_mul_f32_e32 v134, v135, v134
	ds_read_b32 v135, v170
	s_waitcnt lgkmcnt(0)
	v_sub_f32_e32 v135, v128, v135
	v_mul_f32_e32 v135, 0x3fb8aa3b, v135
	v_exp_f32_e32 v135, v135
	s_nop 0
	v_mul_f32_e32 v226, v136, v135
	ds_read_b32 v135, v172
	ds_read_b32 v136, v173
	ds_read_b64_tr_b16 v[230:231], v219 offset:2112
	ds_read_b64_tr_b16 v[228:229], v219
	ds_read_b64_tr_b16 v[236:237], v219 offset:32
	ds_read_b64_tr_b16 v[238:239], v219 offset:2144
	ds_read_b64_tr_b16 v[242:243], v219 offset:64
	ds_read_b64_tr_b16 v[244:245], v219 offset:2176
	s_waitcnt lgkmcnt(0)
	v_sub_f32_e32 v135, v128, v135
	v_mul_f32_e32 v135, 0x3fb8aa3b, v135
	v_exp_f32_e32 v135, v135
	v_and_b32_e32 v150, 0xffff0000, v229
	v_mul_f32_e32 v150, v132, v150
	v_cvt_pk_bf16_f32 v227, v150, v150
	v_lshlrev_b32_e32 v150, 16, v230
	v_mul_f32_e32 v150, v133, v150
	v_mul_f32_e32 v240, v136, v135
	v_lshlrev_b32_e32 v135, 16, v228
	v_and_b32_e32 v136, 0xffff0000, v228
	v_cvt_pk_bf16_f32 v228, v150, v150
	v_and_b32_e32 v150, 0xffff0000, v230
	v_mul_f32_e32 v150, v134, v150
	v_cvt_pk_bf16_f32 v230, v150, v150
	v_lshlrev_b32_e32 v150, 16, v231
	v_mul_f32_e32 v150, v226, v150
	v_cvt_pk_bf16_f32 v232, v150, v150
	v_and_b32_e32 v150, 0xffff0000, v231
	v_mul_f32_e32 v150, v240, v150
	v_cvt_pk_bf16_f32 v234, v150, v150
	v_lshlrev_b32_e32 v150, 16, v236
	v_mul_f32_e32 v150, v129, v150
	v_lshlrev_b32_e32 v137, 16, v229
	v_cvt_pk_bf16_f32 v229, v150, v150
	v_and_b32_e32 v150, 0xffff0000, v236
	v_mul_f32_e32 v150, v130, v150
	v_cvt_pk_bf16_f32 v231, v150, v150
	v_lshlrev_b32_e32 v150, 16, v237
	v_mul_f32_e32 v150, v131, v150
	v_cvt_pk_bf16_f32 v233, v150, v150
	v_and_b32_e32 v150, 0xffff0000, v237
	v_mul_f32_e32 v150, v132, v150
	v_cvt_pk_bf16_f32 v235, v150, v150
	v_lshlrev_b32_e32 v150, 16, v238
	v_mul_f32_e32 v150, v133, v150
	v_cvt_pk_bf16_f32 v236, v150, v150
	v_and_b32_e32 v150, 0xffff0000, v238
	v_mul_f32_e32 v150, v134, v150
	v_cvt_pk_bf16_f32 v237, v150, v150
	v_lshlrev_b32_e32 v150, 16, v239
	v_mul_f32_e32 v150, v226, v150
	v_cvt_pk_bf16_f32 v238, v150, v150
	v_and_b32_e32 v150, 0xffff0000, v239
	v_mul_f32_e32 v150, v240, v150
	v_cvt_pk_bf16_f32 v239, v150, v150
	v_lshlrev_b32_e32 v150, 16, v242
	v_and_b32_e32 v151, 0xffff0000, v242
	v_lshlrev_b32_e32 v152, 16, v243
	v_and_b32_e32 v153, 0xffff0000, v243
	v_lshlrev_b32_e32 v154, 16, v244
	v_and_b32_e32 v155, 0xffff0000, v244
	v_lshlrev_b32_e32 v177, 16, v245
	v_and_b32_e32 v179, 0xffff0000, v245
	ds_read_b64_tr_b16 v[242:243], v219 offset:96
	ds_read_b64_tr_b16 v[244:245], v219 offset:2208
	v_mul_f32_e32 v135, v129, v135
	v_mul_f32_e32 v150, v129, v150
	v_mul_f32_e32 v136, v130, v136
	s_waitcnt lgkmcnt(0)
; __device__ __forceinline__ f32x4 mfma16(bf16x8 a, bf16x8 b, f32x4 c) { return __builtin_amdgcn_mfma_f32_16x16x32_bf16(a, b, c, 0, 0, 0); }
; #define SCHED_FENCE() do {} while (0)
; #define SCHED_FENCE() __builtin_amdgcn_sched_barrier(0)
; __device__ __forceinline__ void ssd_state_update(f32x4 (&H)[4][4], LAS unsigned char* Xi, int xp, LAS unsigned char* Bi, int bp, const LAS float* sDt, const LAS float* sCum, int w, int lane) {
;     ...
;     for (int ks = 0; ks < 2; ++ks) {
;         float wg[8];
; #pragma unroll
;         for (int j = 0; j < 8; ++j) wg[j] = __expf(tot - sCum[(32 * ks + 8 * g + j) * 4 + k]) * sDt[(32 * ks + 8 * g + j) * 4 + k];
;         bf16x8 Bx[4];
; #pragma unroll
;         for (int pt = 0; pt < 4; ++pt) Bx[pt] = scale_frag8(frag_tr(Xi, xp, 32 * ks + 8 * g, 32 * ks + 8 * g + 4, 64 * k + 16 * pt, lane), wg);
; #pragma unroll
;         for (int nt = 0; nt < 4; ++nt) { const bf16x8 A = frag_tr(Bi, bp, 32 * ks + 8 * g, 32 * ks + 8 * g + 4, 16 * (4 * nh + nt), lane);
; #pragma unroll
;             for (int pt = 0; pt < 4; ++pt) H[nt][pt] = mfma16(A, Bx[pt], H[nt][pt]);
;             SCHED_FENCE(); }
;     }
	v_lshlrev_b32_e32 v180, 16, v242
	v_mul_f32_e32 v129, v129, v180
	v_and_b32_e32 v180, 0xffff0000, v242
	v_mul_f32_e32 v151, v130, v151
	v_mul_f32_e32 v130, v130, v180
	v_cvt_pk_bf16_f32 v180, v130, v130
	v_lshlrev_b32_e32 v130, 16, v243
	v_mul_f32_e32 v130, v131, v130
	v_cvt_pk_bf16_f32 v181, v130, v130
	v_and_b32_e32 v130, 0xffff0000, v243
	v_mul_f32_e32 v130, v132, v130
	v_cvt_pk_bf16_f32 v182, v130, v130
	v_lshlrev_b32_e32 v130, 16, v244
	v_mul_f32_e32 v130, v133, v130
	v_cvt_pk_bf16_f32 v246, v130, v130
	v_and_b32_e32 v130, 0xffff0000, v244
	v_mul_f32_e32 v130, v134, v130
	v_cvt_pk_bf16_f32 v244, v130, v130
	v_lshlrev_b32_e32 v130, 16, v245
	v_mul_f32_e32 v130, v226, v130
	v_cvt_pk_bf16_f32 v247, v130, v130
	v_and_b32_e32 v130, 0xffff0000, v245
	v_mul_f32_e32 v130, v240, v130
	v_mul_f32_e32 v137, v131, v137
	v_mul_f32_e32 v152, v131, v152
	v_mul_f32_e32 v153, v132, v153
	v_mul_f32_e32 v154, v133, v154
	v_cvt_pk_bf16_f32 v245, v130, v130
	ds_read_b64_tr_b16 v[130:131], v220 offset:512
	ds_read_b64_tr_b16 v[132:133], v220 offset:4672
	v_cvt_pk_bf16_f32 v135, v135, v135
	v_cvt_pk_bf16_f32 v136, v136, v136
	v_cvt_pk_bf16_f32 v137, v137, v137
	v_mul_f32_e32 v155, v134, v155
	v_mul_f32_e32 v177, v226, v177
	v_mul_f32_e32 v179, v240, v179
	v_cvt_pk_bf16_f32 v150, v150, v150
	v_cvt_pk_bf16_f32 v151, v151, v151
	v_cvt_pk_bf16_f32 v152, v152, v152
	v_cvt_pk_bf16_f32 v153, v153, v153
	v_cvt_pk_bf16_f32 v154, v154, v154
	v_cvt_pk_bf16_f32 v155, v155, v155
	v_cvt_pk_bf16_f32 v177, v177, v177
	v_cvt_pk_bf16_f32 v179, v179, v179
	v_cvt_pk_bf16_f32 v129, v129, v129
	v_perm_b32 v243, v234, v232, s75
	v_perm_b32 v242, v230, v228, s75
	v_perm_b32 v241, v227, v137, s75
	v_perm_b32 v240, v136, v135, s75
	v_perm_b32 v137, v239, v238, s75
	v_perm_b32 v136, v237, v236, s75
	v_perm_b32 v135, v235, v233, s75
	v_perm_b32 v134, v231, v229, s75
	v_perm_b32 v229, v179, v177, s75
	v_perm_b32 v228, v155, v154, s75
	v_perm_b32 v227, v153, v152, s75
	v_perm_b32 v226, v151, v150, s75
	v_perm_b32 v233, v245, v247, s75
	v_perm_b32 v232, v244, v246, s75
	v_perm_b32 v231, v182, v181, s75
	v_perm_b32 v230, v180, v129, s75
	s_waitcnt lgkmcnt(0)
	v_mfma_f32_16x16x32_bf16 v[96:99], v[130:133], v[240:243], v[96:99]
	v_mfma_f32_16x16x32_bf16 v[92:95], v[130:133], v[134:137], v[92:95]
	v_mfma_f32_16x16x32_bf16 v[88:91], v[130:133], v[226:229], v[88:91]
	v_mfma_f32_16x16x32_bf16 v[84:87], v[130:133], v[230:233], v[84:87]
	ds_read_b64_tr_b16 v[130:131], v220 offset:544
	ds_read_b64_tr_b16 v[132:133], v220 offset:4704
	s_waitcnt lgkmcnt(0)
	v_mfma_f32_16x16x32_bf16 v[68:71], v[130:133], v[240:243], v[68:71]
	v_mfma_f32_16x16x32_bf16 v[72:75], v[130:133], v[134:137], v[72:75]
	v_mfma_f32_16x16x32_bf16 v[76:79], v[130:133], v[226:229], v[76:79]
	v_mfma_f32_16x16x32_bf16 v[80:83], v[130:133], v[230:233], v[80:83]
	ds_read_b64_tr_b16 v[130:131], v220 offset:576
	ds_read_b64_tr_b16 v[132:133], v220 offset:4736
	s_waitcnt lgkmcnt(0)
	v_mfma_f32_16x16x32_bf16 v[60:63], v[130:133], v[240:243], v[60:63]
	v_mfma_f32_16x16x32_bf16 v[64:67], v[130:133], v[134:137], v[64:67]
	v_mfma_f32_16x16x32_bf16 v[56:59], v[130:133], v[226:229], v[56:59]
	v_mfma_f32_16x16x32_bf16 v[52:55], v[130:133], v[230:233], v[52:55]
	ds_read_b64_tr_b16 v[130:131], v220 offset:608
	ds_read_b64_tr_b16 v[132:133], v220 offset:4768
	s_waitcnt lgkmcnt(0)
	v_mfma_f32_16x16x32_bf16 v[48:51], v[130:133], v[240:243], v[48:51]
	v_mfma_f32_16x16x32_bf16 v[44:47], v[130:133], v[134:137], v[44:47]
	v_mfma_f32_16x16x32_bf16 v[40:43], v[130:133], v[226:229], v[40:43]
	v_mfma_f32_16x16x32_bf16 v[36:39], v[130:133], v[230:233], v[36:39]
	ds_read_b32 v129, v174
	ds_read_b32 v130, v175
	ds_read_b32 v131, v188
	ds_read_b32 v132, v189
	ds_read_b32 v133, v190
	ds_read_b32 v134, v191
	ds_read_b32 v135, v192
	ds_read_b32 v136, v193
	s_waitcnt lgkmcnt(0)
	v_sub_f32_e32 v129, v128, v129
	v_sub_f32_e32 v131, v128, v131
	v_sub_f32_e32 v133, v128, v133
	v_sub_f32_e32 v135, v128, v135
	v_mul_f32_e32 v129, 0x3fb8aa3b, v129
	v_mul_f32_e32 v131, 0x3fb8aa3b, v131
	v_mul_f32_e32 v133, 0x3fb8aa3b, v133
	v_mul_f32_e32 v135, 0x3fb8aa3b, v135
	v_exp_f32_e32 v129, v129
	v_exp_f32_e32 v131, v131
	v_exp_f32_e32 v133, v133
	v_exp_f32_e32 v135, v135
	v_mul_f32_e32 v129, v130, v129
	v_mul_f32_e32 v150, v132, v131
	v_mul_f32_e32 v151, v134, v133
	v_mul_f32_e32 v152, v136, v135
	ds_read_b32 v130, v194
	ds_read_b32 v131, v195
	ds_read_b32 v132, v196
	ds_read_b32 v133, v197
	ds_read_b32 v134, v198
	ds_read_b32 v135, v199
	ds_read_b32 v136, v200
	ds_read_b32 v137, v201
	s_waitcnt lgkmcnt(0)
	v_sub_f32_e32 v130, v128, v130
	v_sub_f32_e32 v132, v128, v132
	v_sub_f32_e32 v134, v128, v134
	v_sub_f32_e32 v136, v128, v136
	v_mul_f32_e32 v130, 0x3fb8aa3b, v130
	v_mul_f32_e32 v132, 0x3fb8aa3b, v132
	v_mul_f32_e32 v134, 0x3fb8aa3b, v134
	v_mul_f32_e32 v136, 0x3fb8aa3b, v136
	v_exp_f32_e32 v130, v130
	v_exp_f32_e32 v132, v132
	v_exp_f32_e32 v134, v134
	v_exp_f32_e32 v136, v136
	v_mul_f32_e32 v153, v131, v130
	v_mul_f32_e32 v154, v133, v132
	v_mul_f32_e32 v155, v135, v134
	v_mul_f32_e32 v177, v137, v136
	ds_read_b64_tr_b16 v[130:131], v221
	ds_read_b64_tr_b16 v[132:133], v221 offset:2112
	ds_read_b64_tr_b16 v[134:135], v221 offset:32
	ds_read_b64_tr_b16 v[136:137], v221 offset:64
	ds_read_b64_tr_b16 v[226:227], v221 offset:96
	s_waitcnt lgkmcnt(0)
; __device__ __forceinline__ void ssd_state_update(f32x4 (&H)[4][4], LAS unsigned char* Xi, int xp, LAS unsigned char* Bi, int bp, const LAS float* sDt, const LAS float* sCum, int w, int lane) {
;     ...
;     for (int ks = 0; ks < 2; ++ks) {
;         float wg[8];
; #pragma unroll
;         for (int j = 0; j < 8; ++j) wg[j] = __expf(tot - sCum[(32 * ks + 8 * g + j) * 4 + k]) * sDt[(32 * ks + 8 * g + j) * 4 + k];
;         bf16x8 Bx[4];
; #pragma unroll
;         for (int pt = 0; pt < 4; ++pt) Bx[pt] = scale_frag8(frag_tr(Xi, xp, 32 * ks + 8 * g, 32 * ks + 8 * g + 4, 64 * k + 16 * pt, lane), wg);
; #pragma unroll
;         for (int nt = 0; nt < 4; ++nt) { const bf16x8 A = frag_tr(Bi, bp, 32 * ks + 8 * g, 32 * ks + 8 * g + 4, 16 * (4 * nh + nt), lane);
	v_lshlrev_b32_e32 v179, 16, v130
	v_lshlrev_b32_e32 v232, 16, v132
	v_and_b32_e32 v132, 0xffff0000, v132
	v_mul_f32_e32 v132, v154, v132
	v_cvt_pk_bf16_f32 v233, v132, v132
	v_lshlrev_b32_e32 v132, 16, v133
	v_mul_f32_e32 v132, v155, v132
	v_cvt_pk_bf16_f32 v234, v132, v132
	v_and_b32_e32 v132, 0xffff0000, v133
	v_and_b32_e32 v130, 0xffff0000, v130
	v_mul_f32_e32 v132, v177, v132
	v_mul_f32_e32 v130, v150, v130
	v_cvt_pk_bf16_f32 v235, v132, v132
	v_lshlrev_b32_e32 v132, 16, v134
	v_cvt_pk_bf16_f32 v180, v130, v130
	v_lshlrev_b32_e32 v130, 16, v131
	v_mul_f32_e32 v132, v129, v132
	v_mul_f32_e32 v130, v151, v130
	v_cvt_pk_bf16_f32 v236, v132, v132
	v_and_b32_e32 v132, 0xffff0000, v134
	v_cvt_pk_bf16_f32 v181, v130, v130
	v_and_b32_e32 v130, 0xffff0000, v131
	v_mul_f32_e32 v132, v150, v132
	v_mul_f32_e32 v130, v152, v130
	v_cvt_pk_bf16_f32 v237, v132, v132
	v_lshlrev_b32_e32 v132, 16, v135
	v_cvt_pk_bf16_f32 v182, v130, v130
	ds_read_b64_tr_b16 v[130:131], v221 offset:2144
	ds_read_b64_tr_b16 v[228:229], v221 offset:2176
	ds_read_b64_tr_b16 v[230:231], v221 offset:2208
	v_mul_f32_e32 v132, v151, v132
	v_cvt_pk_bf16_f32 v238, v132, v132
	v_and_b32_e32 v132, 0xffff0000, v135
	v_mul_f32_e32 v132, v152, v132
	v_cvt_pk_bf16_f32 v239, v132, v132
	s_waitcnt lgkmcnt(0)
	v_lshlrev_b32_e32 v132, 16, v130
	v_and_b32_e32 v130, 0xffff0000, v130
	v_mul_f32_e32 v130, v154, v130
	v_cvt_pk_bf16_f32 v241, v130, v130
	v_lshlrev_b32_e32 v130, 16, v131
	v_mul_f32_e32 v130, v155, v130
	v_cvt_pk_bf16_f32 v242, v130, v130
	v_and_b32_e32 v130, 0xffff0000, v131
	v_mul_f32_e32 v130, v177, v130
	v_cvt_pk_bf16_f32 v243, v130, v130
	v_lshlrev_b32_e32 v130, 16, v136
	v_mul_f32_e32 v130, v129, v130
	v_cvt_pk_bf16_f32 v244, v130, v130
	v_and_b32_e32 v130, 0xffff0000, v136
	v_mul_f32_e32 v130, v150, v130
	v_cvt_pk_bf16_f32 v245, v130, v130
	v_lshlrev_b32_e32 v130, 16, v137
	v_mul_f32_e32 v130, v151, v130
	v_cvt_pk_bf16_f32 v246, v130, v130
	v_and_b32_e32 v130, 0xffff0000, v137
	v_mul_f32_e32 v130, v152, v130
	v_cvt_pk_bf16_f32 v247, v130, v130
	v_lshlrev_b32_e32 v130, 16, v228
	v_mul_f32_e32 v130, v153, v130
	v_cvt_pk_bf16_f32 v248, v130, v130
	v_and_b32_e32 v130, 0xffff0000, v228
	v_mul_f32_e32 v130, v154, v130
	v_cvt_pk_bf16_f32 v249, v130, v130
	v_lshlrev_b32_e32 v130, 16, v229
	v_mul_f32_e32 v130, v155, v130
	v_cvt_pk_bf16_f32 v250, v130, v130
	v_and_b32_e32 v130, 0xffff0000, v229
	v_mul_f32_e32 v130, v177, v130
	v_cvt_pk_bf16_f32 v251, v130, v130
	v_lshlrev_b32_e32 v130, 16, v226
	v_mul_f32_e32 v179, v129, v179
	v_mul_f32_e32 v129, v129, v130
	v_and_b32_e32 v130, 0xffff0000, v226
	v_mul_f32_e32 v130, v150, v130
	v_cvt_pk_bf16_f32 v150, v130, v130
	v_lshlrev_b32_e32 v130, 16, v227
	v_mul_f32_e32 v130, v151, v130
	v_cvt_pk_bf16_f32 v151, v130, v130
	v_and_b32_e32 v130, 0xffff0000, v227
	v_mul_f32_e32 v130, v152, v130
	v_cvt_pk_bf16_f32 v152, v130, v130
	v_lshlrev_b32_e32 v130, 16, v230
	v_mul_f32_e32 v130, v153, v130
	v_mul_f32_e32 v232, v153, v232
	v_mul_f32_e32 v132, v153, v132
	v_cvt_pk_bf16_f32 v153, v130, v130
	v_and_b32_e32 v130, 0xffff0000, v230
	v_mul_f32_e32 v130, v154, v130
	v_cvt_pk_bf16_f32 v154, v130, v130
	v_lshlrev_b32_e32 v130, 16, v231
	v_cvt_pk_bf16_f32 v240, v132, v132
	v_mul_f32_e32 v134, v155, v130
	ds_read_b64_tr_b16 v[130:131], v222 offset:512
	ds_read_b64_tr_b16 v[132:133], v222 offset:4672
	v_cvt_pk_bf16_f32 v155, v134, v134
	v_and_b32_e32 v134, 0xffff0000, v231
	v_cvt_pk_bf16_f32 v232, v232, v232
	v_mul_f32_e32 v134, v177, v134
	v_cvt_pk_bf16_f32 v179, v179, v179
	v_cvt_pk_bf16_f32 v129, v129, v129
	v_cvt_pk_bf16_f32 v177, v134, v134
	v_perm_b32 v137, v235, v234, s75
	v_perm_b32 v136, v233, v232, s75
	v_perm_b32 v135, v182, v181, s75
	v_perm_b32 v134, v180, v179, s75
	v_perm_b32 v229, v243, v242, s75
	v_perm_b32 v228, v241, v240, s75
	v_perm_b32 v227, v239, v238, s75
	v_perm_b32 v226, v237, v236, s75
	v_perm_b32 v233, v251, v250, s75
	v_perm_b32 v232, v249, v248, s75
	v_perm_b32 v231, v247, v246, s75
	v_perm_b32 v230, v245, v244, s75
	v_perm_b32 v237, v177, v155, s75
	v_perm_b32 v236, v154, v153, s75
	v_perm_b32 v235, v152, v151, s75
	v_perm_b32 v234, v150, v129, s75
	s_waitcnt lgkmcnt(0)
; #define LAS __attribute__((address_space(3)))
; __device__ __forceinline__ f32x4 mfma16(bf16x8 a, bf16x8 b, f32x4 c) { return __builtin_amdgcn_mfma_f32_16x16x32_bf16(a, b, c, 0, 0, 0); }
; __device__ __forceinline__ void sync_threads() { __syncthreads(); }
; #define SCHED_FENCE() do {} while (0)
; #define LAUNDER_PTR(p) do {} while (0)
; #define LAUNDER_PTR(p) asm volatile("" : "+v"(p))
; #define SCHED_FENCE() __builtin_amdgcn_sched_barrier(0)
; __device__ __forceinline__ void ssd_state_update(f32x4 (&H)[4][4], LAS unsigned char* Xi, int xp, LAS unsigned char* Bi, int bp, const LAS float* sDt, const LAS float* sCum, int w, int lane) {
;     ...
;         for (int nt = 0; nt < 4; ++nt) { const bf16x8 A = frag_tr(Bi, bp, 32 * ks + 8 * g, 32 * ks + 8 * g + 4, 16 * (4 * nh + nt), lane);
; #pragma unroll
;             for (int pt = 0; pt < 4; ++pt) H[nt][pt] = mfma16(A, Bx[pt], H[nt][pt]);
;             SCHED_FENCE(); }
;     }
; __device__ __forceinline__ void ssd_pass1(const RecurBufs& rb, const float* conv_w, const float* conv_b, const float* dt_bias, const float* a_log, float* conv_out_l, int u, int tid, LAS unsigned char* lds) {
;     ...
;         tsum += sCum[63 * 4 + (w >> 1)];
;         ssd_state_update(H, XO, PX, T + 512, PR, sDt, sCum, w, lane);
;         {   bf16* gp = rb.xbcc + (row0 + rr) * 4096 + gcol;
;             const LAS unsigned char* src = ch16 < 32 ? (XO + ch16 * 16) : (T + ch16 * 16); const int spitch = ch16 < 32 ? PX : PR;
; #pragma unroll
;             for (int i = 0; i < 8; ++i) { LAUNDER_PTR(gp); *(v4u*)gp = *(const LAS v4u*)(src + (rr + 8 * i) * spitch); gp += 8 * 4096; } }
;         sync_threads();
	v_mfma_f32_16x16x32_bf16 v[96:99], v[130:133], v[134:137], v[96:99]
	v_mfma_f32_16x16x32_bf16 v[92:95], v[130:133], v[226:229], v[92:95]
	v_mfma_f32_16x16x32_bf16 v[88:91], v[130:133], v[230:233], v[88:91]
	v_mfma_f32_16x16x32_bf16 v[84:87], v[130:133], v[234:237], v[84:87]
	ds_read_b64_tr_b16 v[130:131], v222 offset:544
	ds_read_b64_tr_b16 v[132:133], v222 offset:4704
	s_waitcnt lgkmcnt(0)
	v_mfma_f32_16x16x32_bf16 v[68:71], v[130:133], v[134:137], v[68:71]
	v_mfma_f32_16x16x32_bf16 v[72:75], v[130:133], v[226:229], v[72:75]
	v_mfma_f32_16x16x32_bf16 v[76:79], v[130:133], v[230:233], v[76:79]
	v_mfma_f32_16x16x32_bf16 v[80:83], v[130:133], v[234:237], v[80:83]
	ds_read_b64_tr_b16 v[130:131], v222 offset:576
	ds_read_b64_tr_b16 v[132:133], v222 offset:4736
	s_waitcnt lgkmcnt(0)
	v_mfma_f32_16x16x32_bf16 v[60:63], v[130:133], v[134:137], v[60:63]
	v_mfma_f32_16x16x32_bf16 v[64:67], v[130:133], v[226:229], v[64:67]
	v_mfma_f32_16x16x32_bf16 v[56:59], v[130:133], v[230:233], v[56:59]
	v_mfma_f32_16x16x32_bf16 v[52:55], v[130:133], v[234:237], v[52:55]
	ds_read_b64_tr_b16 v[130:131], v222 offset:608
	ds_read_b64_tr_b16 v[132:133], v222 offset:4768
	s_waitcnt lgkmcnt(0)
	v_mfma_f32_16x16x32_bf16 v[48:51], v[130:133], v[134:137], v[48:51]
	v_mfma_f32_16x16x32_bf16 v[44:47], v[130:133], v[226:229], v[44:47]
	v_mfma_f32_16x16x32_bf16 v[40:43], v[130:133], v[230:233], v[40:43]
	v_mfma_f32_16x16x32_bf16 v[36:39], v[130:133], v[234:237], v[36:39]
	v_lshl_add_u64 v[130:131], s[68:69], 0, v[116:117]
	v_lshlrev_b64 v[130:131], 13, v[130:131]
	v_lshl_add_u64 v[134:135], v[126:127], 0, v[130:131]
	v_add_u32_e32 v129, v202, v209
	ds_read_b128 v[130:133], v129
	v_add_u32_e32 v129, v202, v210
	v_add_f32_e32 v140, v140, v128
	s_cmp_eq_u32 s3, 8
	s_waitcnt lgkmcnt(0)
	global_store_dwordx4 v[134:135], v[130:133], off
	v_lshl_add_u64 v[134:135], v[134:135], 0, s[42:43]
	ds_read_b128 v[130:133], v129
	v_add_u32_e32 v129, v202, v211
	s_waitcnt lgkmcnt(0)
	global_store_dwordx4 v[134:135], v[130:133], off
	v_lshl_add_u64 v[134:135], v[134:135], 0, s[42:43]
	ds_read_b128 v[130:133], v129
	v_add_u32_e32 v129, v202, v212
	s_waitcnt lgkmcnt(0)
	global_store_dwordx4 v[134:135], v[130:133], off
	v_lshl_add_u64 v[134:135], v[134:135], 0, s[42:43]
	ds_read_b128 v[130:133], v129
	v_add_u32_e32 v129, v202, v213
	s_waitcnt lgkmcnt(0)
	global_store_dwordx4 v[134:135], v[130:133], off
	v_lshl_add_u64 v[134:135], v[134:135], 0, s[42:43]
	ds_read_b128 v[130:133], v129
	v_add_u32_e32 v129, v202, v214
	s_waitcnt lgkmcnt(0)
	global_store_dwordx4 v[134:135], v[130:133], off
	v_lshl_add_u64 v[134:135], v[134:135], 0, s[42:43]
	ds_read_b128 v[130:133], v129
	v_add_u32_e32 v129, v202, v215
	s_waitcnt lgkmcnt(0)
	global_store_dwordx4 v[134:135], v[130:133], off
	v_lshl_add_u64 v[134:135], v[134:135], 0, s[42:43]
	ds_read_b128 v[130:133], v129
	s_waitcnt lgkmcnt(0)
	global_store_dwordx4 v[134:135], v[130:133], off
	v_lshl_add_u64 v[134:135], v[134:135], 0, s[42:43]
	ds_read_b128 v[130:133], v223
	s_waitcnt lgkmcnt(0)
	global_store_dwordx4 v[134:135], v[130:133], off
	s_waitcnt lgkmcnt(0)
	s_barrier
	s_cbranch_scc1 .LBB0_386

; __device__ __forceinline__ float bf2f(bf16 v) { return __uint_as_float(((unsigned)v) << 16); }
; __device__ __forceinline__ float softplusf_(float x) { return x > 20.f ? x : log1pf(__expf(x)); }
; #define LAS __attribute__((address_space(3)))
; __device__ __forceinline__ float shfl_up_f(float v, int o, int lane) { return __int_as_float(__builtin_amdgcn_ds_bpermute((lane >= o ? lane - o : lane) << 2, __float_as_int(v))); }
; #define LAUNDER_PTR(p) do {} while (0)
; #define LAUNDER_PTR(p) asm volatile("" : "+v"(p))
; __device__ __forceinline__ void ssd_pass1(const RecurBufs& rb, const float* conv_w, const float* conv_b, const float* dt_bias, const float* a_log, float* conv_out_l, int u, int tid, LAS unsigned char* lds) {
;     ...
;         if (w < 4) {
;             const int head = grp * 4 + w; const size_t row = row0 + lane;
;             const float dv = softplusf_(bf2f(dtn) + dt_bias[head]);
;             if (ch + 1 < NCH) dtn = rb.proj[(row + RC) * LDP + PC_DT + head];
;             float la = dv * (-__expf(a_log[head]));
; #pragma unroll
;             for (int o = 1; o < 64; o <<= 1) { const float t = shfl_up_f(la, o, lane); if (lane >= o) la += t; }
;             sDt[lane * 4 + w] = dv; sCum[lane * 4 + w] = la; rb.dtv[row * 32 + head] = dv; rb.cum[row * 32 + head] = la;
;         }
; #pragma unroll
;         for (int i = 0; i < 8; ++i) *(LAS v4u*)(T + (rr + 8 * i) * PR + ch16 * 16) = raw[i];
;         if (ch + 1 < NCH) { const bf16* gp = rb.proj + (row0 + RC + rr) * LDP + PC_XBC + gcol;
; #pragma unroll
;             for (int i = 0; i < 8; ++i) { LAUNDER_PTR(gp); raw[i] = *(const v4u*)gp; gp += 8 * (size_t)LDP; } }
.LBB0_345:
	s_or_b64 exec, exec, s[50:51]
	v_mov_b32_e32 v129, s69
	s_cmp_eq_u32 s3, 7
	v_or_b32_e32 v128, s68, v111
	s_cbranch_scc1 .LBB0_347
	v_mov_b64_e32 v[132:133], s[78:79]
	v_mad_u64_u32 v[132:133], s[50:51], v128, s77, v[132:133]
	v_mov_b32_e32 v134, v133
	v_mad_u64_u32 v[134:135], s[50:51], v129, s77, v[134:135]
	v_mov_b32_e32 v133, v134
	v_lshl_add_u64 v[132:133], v[118:119], 1, v[132:133]
	v_add_co_u32_e32 v132, vcc, 0x18e000, v132
	s_nop 1
	v_addc_co_u32_e32 v133, vcc, 0, v133, vcc
	global_load_ushort v142, v[132:133], off
.LBB0_347:
	global_load_dword v131, v[122:123], off
	v_lshlrev_b64 v[128:129], 5, v[128:129]
	v_lshl_add_u64 v[128:129], v[128:129], 0, v[118:119]
	v_lshlrev_b64 v[128:129], 2, v[128:129]
	s_waitcnt vmcnt(0)
	v_mul_f32_e32 v131, 0x3fb8aa3b, v131
	v_exp_f32_e32 v131, v131
	s_nop 0
	v_mul_f32_e64 v132, v130, -v131
	ds_bpermute_b32 v133, v203, v132
	s_waitcnt lgkmcnt(0)
	v_fma_f32 v131, v130, -v131, v133
	v_cndmask_b32_e64 v131, v132, v131, s[10:11]
	ds_bpermute_b32 v132, v204, v131
	s_waitcnt lgkmcnt(0)
	v_add_f32_e32 v132, v131, v132
	v_cndmask_b32_e64 v131, v132, v131, s[12:13]
	ds_bpermute_b32 v132, v205, v131
	s_waitcnt lgkmcnt(0)
	v_add_f32_e32 v132, v131, v132
	v_cndmask_b32_e64 v131, v132, v131, s[14:15]
	ds_bpermute_b32 v132, v206, v131
	s_waitcnt lgkmcnt(0)
	v_add_f32_e32 v132, v131, v132
	v_cndmask_b32_e64 v131, v132, v131, s[16:17]
	ds_bpermute_b32 v132, v207, v131
	s_waitcnt lgkmcnt(0)
	v_add_f32_e32 v132, v131, v132
	v_cndmask_b32_e64 v131, v132, v131, s[18:19]
	ds_bpermute_b32 v132, v208, v131
	s_waitcnt lgkmcnt(0)
	v_add_f32_e32 v132, v131, v132
	v_cndmask_b32_e64 v131, v132, v131, s[4:5]
	v_lshl_add_u64 v[132:133], s[24:25], 0, v[128:129]
	v_lshl_add_u64 v[128:129], s[26:27], 0, v[128:129]
	ds_write_b32 v143, v130
	ds_write_b32 v144, v131
	global_store_dword v[132:133], v130, off
	global_store_dword v[128:129], v131, off
.LBB0_348:
	s_or_b64 exec, exec, s[70:71]
	s_cmp_eq_u32 s3, 7
	s_waitcnt vmcnt(0) lgkmcnt(0)
	ds_write_b128 v218, v[0:3]
	ds_write_b128 v218, v[4:7] offset:8320
	ds_write_b128 v218, v[12:15] offset:16640
	ds_write_b128 v218, v[16:19] offset:24960
	ds_write_b128 v218, v[20:23] offset:33280
	ds_write_b128 v218, v[24:27] offset:41600
	ds_write_b128 v218, v[28:31] offset:49920
	ds_write_b128 v218, v[32:35] offset:58240
	s_cbranch_scc1 .LBB0_350
	v_lshl_add_u64 v[0:1], v[124:125], 0, s[68:69]
	v_mov_b64_e32 v[2:3], s[78:79]
	v_mad_u64_u32 v[2:3], s[50:51], v0, s77, v[2:3]
	v_mov_b32_e32 v0, v3
	v_mad_u64_u32 v[0:1], s[50:51], v1, s77, v[0:1]
	v_mov_b32_e32 v3, v0
	v_lshl_add_u64 v[0:1], v[114:115], 1, v[2:3]
	v_lshl_add_u64 v[4:5], v[0:1], 0, s[92:93]
	global_load_dwordx4 v[0:3], v[4:5], off
	v_lshl_add_u64 v[12:13], v[4:5], 0, s[84:85]
	global_load_dwordx4 v[4:7], v[12:13], off
	v_lshl_add_u64 v[16:17], v[12:13], 0, s[84:85]
	global_load_dwordx4 v[12:15], v[16:17], off
	v_lshl_add_u64 v[20:21], v[16:17], 0, s[84:85]
	global_load_dwordx4 v[16:19], v[20:21], off
	v_lshl_add_u64 v[24:25], v[20:21], 0, s[84:85]
	global_load_dwordx4 v[20:23], v[24:25], off
	v_lshl_add_u64 v[28:29], v[24:25], 0, s[84:85]
	global_load_dwordx4 v[24:27], v[28:29], off
	v_lshl_add_u64 v[32:33], v[28:29], 0, s[84:85]
	global_load_dwordx4 v[28:31], v[32:33], off
	v_lshl_add_u64 v[32:33], v[32:33], 0, s[84:85]
	global_load_dwordx4 v[32:35], v[32:33], off

; #define LAUNDER_PTR(p) do {} while (0)
; #define LAUNDER_PTR(p) asm volatile("" : "+v"(p))
; __device__ __forceinline__ void ssd_pass1(const RecurBufs& rb, const float* conv_w, const float* conv_b, const float* dt_bias, const float* a_log, float* conv_out_l, int u, int tid, LAS unsigned char* lds) {
;     ...
;     float* hp = rb.hseg + (size_t)u * 32768 + tid * 4;
; #pragma unroll
;     for (int nt = 0; nt < 4; ++nt)
; #pragma unroll
;         for (int pt = 0; pt < 4; ++pt) { LAUNDER_PTR(hp); *(f32x4*)hp = H[nt][pt]; hp += 2048; }
;     if ((tid & 127) == 0) rb.tseg[u * 4 + (w >> 1)] = tsum;
.LBB0_386:
	s_ashr_i32 s3, s2, 31
	s_lshl_b64 s[4:5], s[2:3], 17
	v_readlane_b32 s3, v255, 43
	s_add_u32 s4, s3, s4
	v_readlane_b32 s3, v255, 44
	s_addc_u32 s5, s3, s5
	v_ashrrev_i32_e32 v111, 31, v110
	s_waitcnt vmcnt(0)
	v_lshl_add_u64 v[0:1], v[110:111], 2, s[4:5]
	global_store_dwordx4 v[0:1], v[96:99], off
	v_lshl_add_u64 v[0:1], v[0:1], 0, s[44:45]
	global_store_dwordx4 v[0:1], v[92:95], off
	v_lshl_add_u64 v[0:1], v[0:1], 0, s[44:45]
	global_store_dwordx4 v[0:1], v[88:91], off
	v_lshl_add_u64 v[0:1], v[0:1], 0, s[44:45]
	global_store_dwordx4 v[0:1], v[84:87], off
	v_lshl_add_u64 v[0:1], v[0:1], 0, s[44:45]
	global_store_dwordx4 v[0:1], v[68:71], off
	v_lshl_add_u64 v[0:1], v[0:1], 0, s[44:45]
	global_store_dwordx4 v[0:1], v[72:75], off
	v_lshl_add_u64 v[0:1], v[0:1], 0, s[44:45]
	global_store_dwordx4 v[0:1], v[76:79], off
	v_lshl_add_u64 v[0:1], v[0:1], 0, s[44:45]
	global_store_dwordx4 v[0:1], v[80:83], off
	v_lshl_add_u64 v[0:1], v[0:1], 0, s[44:45]
	global_store_dwordx4 v[0:1], v[60:63], off
	v_lshl_add_u64 v[0:1], v[0:1], 0, s[44:45]
	global_store_dwordx4 v[0:1], v[64:67], off
	v_lshl_add_u64 v[0:1], v[0:1], 0, s[44:45]
	global_store_dwordx4 v[0:1], v[56:59], off
	v_lshl_add_u64 v[0:1], v[0:1], 0, s[44:45]
	global_store_dwordx4 v[0:1], v[52:55], off
	v_lshl_add_u64 v[0:1], v[0:1], 0, s[44:45]
	global_store_dwordx4 v[0:1], v[48:51], off
	v_lshl_add_u64 v[0:1], v[0:1], 0, s[44:45]
	global_store_dwordx4 v[0:1], v[44:47], off
	v_lshl_add_u64 v[0:1], v[0:1], 0, s[44:45]
	global_store_dwordx4 v[0:1], v[40:43], off
	v_lshl_add_u64 v[0:1], v[0:1], 0, s[44:45]
	global_store_dwordx4 v[0:1], v[36:39], off
	v_and_b32_e32 v0, 0x7f, v139
	v_cmp_eq_u32_e32 vcc, 0, v0
	s_and_saveexec_b64 s[4:5], vcc
	s_cbranch_execz .LBB0_388
	v_lshl_add_u32 v0, s2, 2, v141
	v_readlane_b32 s8, v255, 45
	v_ashrrev_i32_e32 v1, 31, v0
	v_readlane_b32 s9, v255, 46
	s_nop 1
	v_lshl_add_u64 v[0:1], v[0:1], 2, s[8:9]
	global_store_dword v[0:1], v140, off

; #define LAS __attribute__((address_space(3)))
; __device__ __forceinline__ void hgrn_pass1(const RecurBufs& rb, const float* lbs_l, int u, int tid, LAS unsigned char* lds) {
;     const int b = u >> 5, h = (u >> 2) & 7, seg = u & 3, lane = tid & 63, w = tid >> 6;
;     const int d = tid & 127, jq = tid >> 7;
;     LAS unsigned char* Qt = lds + HG_QT; LAS unsigned char* Kt = lds + HG_KT; LAS unsigned char* V = lds + HG_V; LAS float* part = (LAS float*)(lds + HG_PART); LAS float* vec = (LAS float*)(lds + HG_VEC1);
;     const float lb = lbs_l[h * 128 + d];
;     f32x4 S[8];
; #pragma unroll
;     for (int et = 0; et < 8; ++et) S[et] = (f32x4){0.f, 0.f, 0.f, 0.f};
;     float dprod = 1.f;
;     const int sr = tid >> 4, sc16 = tid & 15;
;     v4u pre[6];
;     {   const bf16* gq = rb.proj + ((size_t)b * SEQ + seg * SEGLEN + sr) * LDP + PC_Q + h * 128 + sc16 * 8;
;         pre[0] = *(const v4u*)gq; pre[1] = *(const v4u*)(gq + 32 * (size_t)LDP); pre[2] = *(const v4u*)(gq + PC_F); pre[3] = *(const v4u*)(gq + 32 * (size_t)LDP + PC_F);
;         pre[4] = *(const v4u*)(gq + PC_I); pre[5] = *(const v4u*)(gq + 32 * (size_t)LDP + PC_I); }
;     ...
;         *(v4u*)gq = *(const LAS v4u*)(Qt + sr * PQ + sc16 * 16); *(v4u*)(gq + 32 * (size_t)LDP) = *(const LAS v4u*)(Qt + (sr + 32) * PQ + sc16 * 16);
;         *(v4u*)(gq + PC_F) = *(const LAS v4u*)(Kt + sr * PQ + sc16 * 16); *(v4u*)(gq + 32 * (size_t)LDP + PC_F) = *(const LAS v4u*)(Kt + (sr + 32) * PQ + sc16 * 16);
;         hgrn_state_update(S, Kt, V, vec + 128, vec + 256, w, lane);
.LBB0_391:
	s_bfe_u32 s4, s16, 0x30002
	v_mov_b32_e32 v97, v138
	s_lshl_b32 s17, s4, 7
	v_and_b32_e32 v92, 0x7f, v97
	s_and_b32 s3, s18, 3
	s_ashr_i32 s2, s16, 5
	v_or_b32_e32 v0, s17, v92
	s_and_b32 s19, s16, 3
	s_lshl_b32 s14, s3, 3
	s_lshl_b32 s23, s3, 9
	s_ashr_i32 s3, s2, 31
	v_lshlrev_b32_e32 v10, 2, v0
	s_lshl_b32 s5, s19, 9
	s_lshl_b32 s9, s2, 8
	v_ashrrev_i32_e32 v2, 4, v97
	s_lshl_b64 s[2:3], s[2:3], 11
	v_lshl_add_u64 v[0:1], s[96:97], 0, v[10:11]
	s_lshl_b32 s8, s4, 5
	s_lshl_b32 s64, s4, 8
	s_or_b32 s4, s2, s5
	s_mov_b32 s5, s3
	v_ashrrev_i32_e32 v3, 31, v2
	global_load_dword v93, v[0:1], off
	v_mov_b64_e32 v[0:1], s[78:79]
	v_lshl_add_u64 v[4:5], s[4:5], 0, v[2:3]
	v_mad_u64_u32 v[94:95], s[4:5], v4, s77, v[0:1]
	v_and_b32_e32 v12, 15, v97
	v_mad_i32_i24 v95, v5, s77, v95
	v_lshlrev_b32_e32 v10, 4, v12
	v_lshl_add_u64 v[0:1], v[94:95], 0, s[64:65]
	v_lshl_add_u64 v[0:1], v[0:1], 0, v[10:11]
	s_mov_b32 s4, 0xc4000
	v_add_co_u32_e32 v4, vcc, s4, v0
	s_movk_i32 s4, 0x1000
	s_nop 0
	v_addc_co_u32_e32 v5, vcc, 0, v1, vcc
	v_add_co_u32_e32 v6, vcc, s4, v0
	s_mov_b32 s4, 0xc5000
	s_nop 0
	v_addc_co_u32_e32 v7, vcc, 0, v1, vcc
	v_add_co_u32_e32 v8, vcc, s4, v0
	global_load_dwordx4 v[36:39], v[0:1], off
	s_nop 0
	v_addc_co_u32_e32 v9, vcc, 0, v1, vcc
	global_load_dwordx4 v[44:47], v[4:5], off
	global_load_dwordx4 v[40:43], v[0:1], off offset:2048
	global_load_dwordx4 v[48:51], v[4:5], off offset:2048
	global_load_dwordx4 v[52:55], v[6:7], off
	global_load_dwordx4 v[56:59], v[8:9], off
	v_lshlrev_b32_e32 v8, 2, v97
	v_ashrrev_i32_e32 v1, 2, v97
	s_or_b32 s28, s9, s8
	s_movk_i32 s15, 0x110
	v_lshrrev_b32_e32 v5, 1, v97
	v_bfe_u32 v6, v97, 2, 2
	v_mul_lo_u32 v7, v2, s15
	v_lshlrev_b32_e32 v112, 1, v92
	v_and_b32_e32 v1, -16, v1
	v_and_b32_e32 v9, 12, v8
	s_or_b32 s14, s28, s14
	v_mov_b32_e32 v101, 1.0
	v_ashrrev_i32_e32 v0, 7, v97
	v_and_or_b32 v5, v5, 24, v6
	v_add_u32_e32 v6, 0, v7
	v_add_u32_e32 v100, 0, v112
	v_lshl_add_u32 v7, v1, 2, 0
	v_or_b32_e32 v1, v9, v1
	s_mul_hi_i32 s29, s14, 0x600
	s_mul_i32 s50, s14, 0x600
	s_movk_i32 s14, 0x1100
	s_or_b32 s2, s2, s23
	v_lshlrev_b32_e32 v96, 3, v12
	v_cmp_lt_i32_e64 s[10:11], 0, v0
	v_cmp_lt_i32_e64 s[12:13], 1, v0
	v_cmp_lt_i32_e64 s[8:9], 2, v0
	v_mul_u32_u24_e32 v13, 0x110, v5
	v_mad_u32_u24 v5, v5, s15, 0
	v_lshl_add_u32 v106, v12, 2, v7
	v_lshl_add_u32 v12, v1, 1, 0
	v_mad_u64_u32 v[98:99], s[14:15], v0, s14, v[100:101]
	v_lshl_add_u64 v[0:1], s[2:3], 0, v[2:3]
	v_mov_b64_e32 v[2:3], s[64:65]
	s_movk_i32 s4, 0x80
	s_movk_i32 s6, 0x7f
	v_and_b32_e32 v4, 48, v97
	v_lshlrev_b32_e32 v9, 1, v9
	v_mad_u64_u32 v[2:3], s[2:3], v0, s77, v[2:3]
	v_mov_b32_e32 v0, 0
	s_mov_b32 s22, 7
	v_cmp_gt_u32_e64 s[4:5], s4, v97
	v_cmp_lt_u32_e64 s[6:7], s6, v97
	v_add_u32_e32 v109, 0, v8
	v_lshl_or_b32 v102, v92, 2, s50
	v_mov_b32_e32 v103, s29
	v_mad_i32_i24 v105, v1, s77, v3
	v_or_b32_e32 v104, v2, v10
	v_add_u32_e32 v108, v6, v10
	v_add_u32_e32 v107, v7, v4
	v_add_u32_e32 v99, v12, v13
	v_add_u32_e32 v9, v5, v9
	s_waitcnt vmcnt(0) lgkmcnt(0)
	v_sub_f32_e32 v110, 1.0, v93
	v_mov_b32_e32 v1, v0
	v_mov_b32_e32 v2, v0
	v_mov_b32_e32 v3, v0
	v_mov_b32_e32 v4, v0
	v_mov_b32_e32 v5, v0
	v_mov_b32_e32 v6, v0
	v_mov_b32_e32 v7, v0
	v_mov_b32_e32 v12, v0
	v_mov_b32_e32 v13, v0
	v_mov_b32_e32 v14, v0
	v_mov_b32_e32 v15, v0
	v_mov_b32_e32 v16, v0
	v_mov_b32_e32 v17, v0
	v_mov_b32_e32 v18, v0
	v_mov_b32_e32 v19, v0
	v_mov_b32_e32 v20, v0
	v_mov_b32_e32 v21, v0
	v_mov_b32_e32 v22, v0
	v_mov_b32_e32 v23, v0
	v_mov_b32_e32 v24, v0
	v_mov_b32_e32 v25, v0
	v_mov_b32_e32 v26, v0
	v_mov_b32_e32 v27, v0
	v_mov_b32_e32 v28, v0
	v_mov_b32_e32 v29, v0
	v_mov_b32_e32 v30, v0
	v_mov_b32_e32 v31, v0
	v_mov_b32_e32 v32, v0
	v_mov_b32_e32 v33, v0
	v_mov_b32_e32 v34, v0
	v_mov_b32_e32 v35, v0
	s_branch .LBB0_393
.LBB0_392:
	s_or_b64 exec, exec, s[2:3]
	s_waitcnt lgkmcnt(0)
	s_barrier
	ds_read_b128 v[62:65], v108
	v_add_co_u32_e32 v66, vcc, 0x17600000, v60
	v_mul_f32_e32 v101, v101, v10
	s_nop 0
	v_addc_co_u32_e32 v67, vcc, 0, v61, vcc
	s_waitcnt lgkmcnt(0)
	global_store_dwordx4 v[66:67], v[62:65], off
	ds_read_b128 v[62:65], v108 offset:8704
	v_add_co_u32_e32 v68, vcc, 0x176c4000, v60
	s_nop 1
	v_addc_co_u32_e32 v69, vcc, 0, v61, vcc
	s_waitcnt lgkmcnt(0)
	global_store_dwordx4 v[68:69], v[62:65], off
	ds_read_b128 v[60:63], v108 offset:17408
	s_waitcnt lgkmcnt(0)
	global_store_dwordx4 v[66:67], v[60:63], off offset:2048
	ds_read_b128 v[60:63], v108 offset:26112
	s_waitcnt lgkmcnt(0)
	global_store_dwordx4 v[68:69], v[60:63], off offset:2048
	ds_read_b128 v[60:63], v107 offset:55296
	s_waitcnt lgkmcnt(0)
	v_pk_mul_f32 v[84:85], v[4:5], v[60:61]
	v_pk_mul_f32 v[86:87], v[6:7], v[62:63]
	ds_read_b32 v10, v106 offset:54784
	ds_read_b64_tr_b16 v[4:5], v99 offset:17408
	ds_read_b64_tr_b16 v[6:7], v99 offset:18496
	v_pk_mul_f32 v[80:81], v[12:13], v[60:61]
	v_pk_mul_f32 v[82:83], v[14:15], v[62:63]
	v_pk_mul_f32 v[88:89], v[0:1], v[60:61]
	s_waitcnt lgkmcnt(0)
; #define LAS __attribute__((address_space(3)))
; __device__ __forceinline__ f32x4 mfma16(bf16x8 a, bf16x8 b, f32x4 c) { return __builtin_amdgcn_mfma_f32_16x16x32_bf16(a, b, c, 0, 0, 0); }
; #define SCHED_FENCE() do {} while (0)
; #define SCHED_FENCE() __builtin_amdgcn_sched_barrier(0)
; __device__ __forceinline__ void hgrn_state_update(f32x4 (&S)[8], LAS unsigned char* Kt, LAS unsigned char* V, const LAS float* escale, const LAS float* edec, int w, int lane) {
;     const int c = lane & 15, g = lane >> 4;
;     const f32x4 dc = *(const LAS f32x4*)(edec + 16 * w + 4 * g);
; #pragma unroll
;     for (int et = 0; et < 8; ++et) S[et] = S[et] * dc;
;     const float es = escale[16 * w + c];
; #pragma unroll
;     for (int ks = 0; ks < 2; ++ks) {
;         const bf16x8 A = scale_frag(frag_tr(Kt, PQ, 32 * ks + 8 * g, 32 * ks + 8 * g + 4, 16 * w, lane), es);
; #pragma unroll
;         for (int et = 0; et < 8; ++et) { const bf16x8 B = frag_tr(V, PQ, 32 * ks + 8 * g, 32 * ks + 8 * g + 4, 16 * et, lane); S[et] = mfma16(A, B, S[et]); }
;         SCHED_FENCE();
;     }
; }
	v_lshlrev_b32_e32 v12, 16, v4
	v_and_b32_e32 v4, 0xffff0000, v4
	v_lshlrev_b32_e32 v13, 16, v5
	v_and_b32_e32 v5, 0xffff0000, v5
	v_lshlrev_b32_e32 v14, 16, v6
	v_and_b32_e32 v6, 0xffff0000, v6
	v_lshlrev_b32_e32 v15, 16, v7
	v_and_b32_e32 v7, 0xffff0000, v7
	v_mul_f32_e32 v12, v10, v12
	v_mul_f32_e32 v4, v10, v4
	v_mul_f32_e32 v13, v10, v13
	v_mul_f32_e32 v5, v10, v5
	v_mul_f32_e32 v14, v10, v14
	v_mul_f32_e32 v6, v10, v6
	v_mul_f32_e32 v15, v10, v15
	v_mul_f32_e32 v7, v10, v7
	v_cvt_pk_bf16_f32 v12, v12, v12
	v_cvt_pk_bf16_f32 v4, v4, v4
	v_cvt_pk_bf16_f32 v13, v13, v13
	v_cvt_pk_bf16_f32 v5, v5, v5
	v_cvt_pk_bf16_f32 v14, v14, v14
	v_cvt_pk_bf16_f32 v6, v6, v6
	v_cvt_pk_bf16_f32 v15, v15, v15
	v_cvt_pk_bf16_f32 v7, v7, v7
	v_pk_mul_f32 v[90:91], v[2:3], v[62:63]
	v_pk_mul_f32 v[76:77], v[16:17], v[60:61]
	v_pk_mul_f32 v[78:79], v[18:19], v[62:63]
	v_pk_mul_f32 v[72:73], v[20:21], v[60:61]
	v_pk_mul_f32 v[74:75], v[22:23], v[62:63]
	v_pk_mul_f32 v[68:69], v[24:25], v[60:61]
	v_pk_mul_f32 v[70:71], v[26:27], v[62:63]
	v_pk_mul_f32 v[64:65], v[28:29], v[60:61]
	v_pk_mul_f32 v[66:67], v[30:31], v[62:63]
	v_pk_mul_f32 v[0:1], v[32:33], v[60:61]
	v_pk_mul_f32 v[2:3], v[34:35], v[62:63]
	v_perm_b32 v63, v7, v15, s75
	v_perm_b32 v62, v6, v14, s75
	v_perm_b32 v61, v5, v13, s75
	v_perm_b32 v60, v4, v12, s75
	ds_read_b64_tr_b16 v[6:7], v9 offset:35904
	ds_read_b64_tr_b16 v[4:5], v9 offset:34816
	ds_read_b64_tr_b16 v[12:13], v9 offset:34848
	ds_read_b64_tr_b16 v[14:15], v9 offset:35936
	ds_read_b64_tr_b16 v[16:17], v9 offset:34880
	ds_read_b64_tr_b16 v[18:19], v9 offset:35968
	ds_read_b64_tr_b16 v[20:21], v9 offset:34912
	ds_read_b64_tr_b16 v[22:23], v9 offset:36000
	ds_read_b64_tr_b16 v[24:25], v9 offset:34944
	ds_read_b64_tr_b16 v[26:27], v9 offset:36032
	ds_read_b64_tr_b16 v[28:29], v9 offset:34976
	ds_read_b64_tr_b16 v[30:31], v9 offset:36064
	ds_read_b64_tr_b16 v[32:33], v9 offset:35008
	ds_read_b64_tr_b16 v[34:35], v9 offset:36096
	s_waitcnt lgkmcnt(0)
	v_mfma_f32_16x16x32_bf16 v[32:35], v[60:63], v[32:35], v[64:67]
	s_nop 2
	ds_read_b64_tr_b16 v[64:65], v9 offset:35040
	ds_read_b64_tr_b16 v[66:67], v9 offset:36128
	v_mfma_f32_16x16x32_bf16 v[4:7], v[60:63], v[4:7], v[88:91]
	v_mfma_f32_16x16x32_bf16 v[12:15], v[60:63], v[12:15], v[84:87]
	v_mfma_f32_16x16x32_bf16 v[16:19], v[60:63], v[16:19], v[80:83]
	v_mfma_f32_16x16x32_bf16 v[20:23], v[60:63], v[20:23], v[76:79]
	v_mfma_f32_16x16x32_bf16 v[24:27], v[60:63], v[24:27], v[72:75]
	v_mfma_f32_16x16x32_bf16 v[28:31], v[60:63], v[28:31], v[68:71]
	s_waitcnt lgkmcnt(0)
	v_mfma_f32_16x16x32_bf16 v[60:63], v[60:63], v[64:67], v[0:3]
	s_nop 2
	ds_read_b64_tr_b16 v[0:1], v99 offset:26112
	ds_read_b64_tr_b16 v[2:3], v99 offset:27200
	s_waitcnt lgkmcnt(0)
	v_lshlrev_b32_e32 v64, 16, v0
	v_and_b32_e32 v0, 0xffff0000, v0
	v_lshlrev_b32_e32 v65, 16, v1
	v_and_b32_e32 v1, 0xffff0000, v1
	v_lshlrev_b32_e32 v66, 16, v2
	v_and_b32_e32 v2, 0xffff0000, v2
	v_lshlrev_b32_e32 v67, 16, v3
	v_and_b32_e32 v3, 0xffff0000, v3
	v_mul_f32_e32 v64, v10, v64
	v_mul_f32_e32 v0, v10, v0
	v_mul_f32_e32 v65, v10, v65
	v_mul_f32_e32 v1, v10, v1
	v_mul_f32_e32 v66, v10, v66
	v_mul_f32_e32 v2, v10, v2
	v_mul_f32_e32 v67, v10, v67
	v_mul_f32_e32 v3, v10, v3
	v_cvt_pk_bf16_f32 v64, v64, v64
	v_cvt_pk_bf16_f32 v0, v0, v0
	v_cvt_pk_bf16_f32 v65, v65, v65
	v_cvt_pk_bf16_f32 v1, v1, v1
	v_cvt_pk_bf16_f32 v66, v66, v66
	v_cvt_pk_bf16_f32 v2, v2, v2
	v_cvt_pk_bf16_f32 v67, v67, v67
	v_cvt_pk_bf16_f32 v3, v3, v3
	s_nop 0
	v_perm_b32 v64, v0, v64, s75
	v_perm_b32 v67, v3, v67, s75
	v_perm_b32 v66, v2, v66, s75
	v_perm_b32 v65, v1, v65, s75
	ds_read_b64_tr_b16 v[2:3], v9 offset:44608
	ds_read_b64_tr_b16 v[0:1], v9 offset:43520
	ds_read_b64_tr_b16 v[68:69], v9 offset:43552
	ds_read_b64_tr_b16 v[70:71], v9 offset:44640
	s_waitcnt lgkmcnt(0)
	v_mfma_f32_16x16x32_bf16 v[0:3], v[64:67], v[0:3], v[4:7]
	v_mfma_f32_16x16x32_bf16 v[4:7], v[64:67], v[68:71], v[12:15]
	s_nop 2
	ds_read_b64_tr_b16 v[12:13], v9 offset:43584
	ds_read_b64_tr_b16 v[14:15], v9 offset:44672
	s_waitcnt lgkmcnt(0)
	v_mfma_f32_16x16x32_bf16 v[12:15], v[64:67], v[12:15], v[16:19]
	s_nop 2
	ds_read_b64_tr_b16 v[16:17], v9 offset:43616
	ds_read_b64_tr_b16 v[18:19], v9 offset:44704
	s_waitcnt lgkmcnt(0)
	v_mfma_f32_16x16x32_bf16 v[16:19], v[64:67], v[16:19], v[20:23]
	s_nop 2
	ds_read_b64_tr_b16 v[20:21], v9 offset:43648
	ds_read_b64_tr_b16 v[22:23], v9 offset:44736
	s_waitcnt lgkmcnt(0)
	v_mfma_f32_16x16x32_bf16 v[20:23], v[64:67], v[20:23], v[24:27]
	s_nop 2
	ds_read_b64_tr_b16 v[24:25], v9 offset:43680
	ds_read_b64_tr_b16 v[26:27], v9 offset:44768
	s_waitcnt lgkmcnt(0)
	v_mfma_f32_16x16x32_bf16 v[24:27], v[64:67], v[24:27], v[28:31]
	s_nop 2
	ds_read_b64_tr_b16 v[28:29], v9 offset:43712
	ds_read_b64_tr_b16 v[30:31], v9 offset:44800
	s_waitcnt lgkmcnt(0)
	v_mfma_f32_16x16x32_bf16 v[28:31], v[64:67], v[28:31], v[32:35]
	s_nop 2
	ds_read_b64_tr_b16 v[32:33], v9 offset:43744
	ds_read_b64_tr_b16 v[34:35], v9 offset:44832
	s_waitcnt lgkmcnt(0)
	v_mfma_f32_16x16x32_bf16 v[32:35], v[64:67], v[32:35], v[60:63]
	s_add_i32 s22, s22, -1
	v_lshl_add_u64 v[102:103], v[102:103], 0, s[46:47]
	s_cmp_eq_u32 s22, 0
	v_lshl_add_u64 v[104:105], v[104:105], 0, s[48:49]
	s_barrier
	s_cbranch_scc1 .LBB0_397
; __device__ __forceinline__ float bf2f(bf16 v) { return __uint_as_float(((unsigned)v) << 16); }
; __device__ __forceinline__ float sigmoidf_(float x) { return frcp_(1.0f + __expf(-x)); }
; __device__ __forceinline__ float siluf_(float x) { return x * frcp_(1.0f + __expf(-x)); }
; #define LAS __attribute__((address_space(3)))
; __device__ __forceinline__ void sync_threads() { __syncthreads(); }
; __device__ __forceinline__ void hgrn_pass1(const RecurBufs& rb, const float* lbs_l, int u, int tid, LAS unsigned char* lds) {
;     ...
;         *(LAS v4u*)(Qt + sr * PQ + sc16 * 16) = pre[0]; *(LAS v4u*)(Qt + (sr + 32) * PQ + sc16 * 16) = pre[1];
;         *(LAS v4u*)(Kt + sr * PQ + sc16 * 16) = pre[2]; *(LAS v4u*)(Kt + (sr + 32) * PQ + sc16 * 16) = pre[3];
;         *(LAS v4u*)(V + sr * PQ + sc16 * 16) = pre[4]; *(LAS v4u*)(V + (sr + 32) * PQ + sc16 * 16) = pre[5];
;         if (ch + 1 < NCH) { const bf16* gn = gq + RC * (size_t)LDP;
;             pre[0] = *(const v4u*)gn; pre[1] = *(const v4u*)(gn + 32 * (size_t)LDP); pre[2] = *(const v4u*)(gn + PC_F); pre[3] = *(const v4u*)(gn + 32 * (size_t)LDP + PC_F);
;             pre[4] = *(const v4u*)(gn + PC_I); pre[5] = *(const v4u*)(gn + 32 * (size_t)LDP + PC_I); }
;         sync_threads();
;         float qq[16], kk[16], lg[16];
; #pragma unroll
;         for (int j = 0; j < 16; ++j) { const float q = bf2f(*(const LAS bf16*)(Qt + (16 * jq + j) * PQ + d * 2)), f = bf2f(*(const LAS bf16*)(Kt + (16 * jq + j) * PQ + d * 2));
;             const float fg = lb + (1.f - lb) * sigmoidf_(f);
;             qq[j] = siluf_(q) * 0.08838834764831845f; kk[j] = 1.f - fg; lg[j] = __logf(fg); }
.LBB0_393:
	v_lshl_add_u64 v[60:61], s[72:73], 0, v[104:105]
	s_waitcnt vmcnt(0)
	ds_write_b128 v108, v[36:39]
	ds_write_b128 v108, v[44:47] offset:8704
	ds_write_b128 v108, v[40:43] offset:17408
	ds_write_b128 v108, v[48:51] offset:26112
	ds_write_b128 v108, v[52:55] offset:34816
	ds_write_b128 v108, v[56:59] offset:43520
	v_add_co_u32_e32 v40, vcc, s38, v60
	s_nop 1
	v_addc_co_u32_e32 v41, vcc, 0, v61, vcc
	v_add_co_u32_e32 v48, vcc, s39, v60
	s_nop 1
	v_addc_co_u32_e32 v49, vcc, 0, v61, vcc
	v_add_co_u32_e32 v52, vcc, s55, v60
	global_load_dwordx4 v[36:39], v[40:41], off
	s_nop 0
	global_load_dwordx4 v[40:43], v[40:41], off offset:2048
	s_nop 0
	global_load_dwordx4 v[44:47], v[48:49], off
	s_nop 0
	global_load_dwordx4 v[48:51], v[48:49], off offset:2048
	v_addc_co_u32_e32 v53, vcc, 0, v61, vcc
	v_add_co_u32_e32 v56, vcc, s80, v60
	s_nop 1
	v_addc_co_u32_e32 v57, vcc, 0, v61, vcc
	global_load_dwordx4 v[52:55], v[52:53], off
	s_nop 0
	global_load_dwordx4 v[56:59], v[56:57], off
	s_waitcnt lgkmcnt(0)
	s_barrier
	ds_read_u16 v10, v98 offset:17408
	ds_read_u16 v62, v98 offset:17680
	ds_read_u16 v64, v98 offset:17952
	ds_read_u16 v66, v98 offset:18224
	ds_read_u16 v68, v98 offset:18496
	ds_read_u16 v71, v98 offset:18768
	ds_read_u16 v73, v98 offset:19040
	ds_read_u16 v76, v98 offset:19312
	s_waitcnt lgkmcnt(0)
	v_lshlrev_b32_e32 v10, 16, v10
	v_mul_f32_e32 v10, 0xbfb8aa3b, v10
	v_exp_f32_e32 v10, v10
	ds_read_u16 v63, v98
	ds_read_u16 v65, v98 offset:272
	ds_read_u16 v67, v98 offset:544
	ds_read_u16 v70, v98 offset:816
	ds_read_u16 v72, v98 offset:1088
	ds_read_u16 v74, v98 offset:1360
	ds_read_u16 v75, v98 offset:1632
	ds_read_u16 v77, v98 offset:1904
	s_waitcnt lgkmcnt(0)
	v_lshlrev_b32_e32 v63, 16, v63
	v_mul_f32_e32 v69, 0xbfb8aa3b, v63
	v_add_f32_e32 v10, 1.0, v10
	v_rcp_f32_e32 v10, v10
	v_exp_f32_e32 v69, v69
	v_lshlrev_b32_e32 v62, 16, v62
	v_mul_f32_e32 v62, 0xbfb8aa3b, v62
	v_fma_f32 v10, v110, v10, v93
	v_cmp_gt_f32_e32 vcc, s33, v10
	v_add_f32_e32 v69, 1.0, v69
	v_rcp_f32_e32 v69, v69
	v_cndmask_b32_e64 v78, 0, 32, vcc
	v_ldexp_f32 v78, v10, v78
	v_log_f32_e32 v78, v78
	v_exp_f32_e32 v62, v62
	v_mul_f32_e32 v63, v69, v63
	v_lshlrev_b32_e32 v65, 16, v65
	v_mul_f32_e32 v69, 0x3f317217, v78
	v_fma_f32 v69, v78, s74, -v69
	v_add_f32_e32 v62, 1.0, v62
	v_fmac_f32_e32 v69, 0x3377d1cf, v78
	v_rcp_f32_e32 v62, v62
	v_fmac_f32_e32 v69, 0x3f317217, v78
	v_cmp_lt_f32_e64 s[14:15], |v78|, s81
	v_cndmask_b32_e32 v79, 0, v186, vcc
	v_fma_f32 v62, v110, v62, v93
	v_cndmask_b32_e64 v69, v78, v69, s[14:15]
	v_mul_f32_e32 v78, 0xbfb8aa3b, v65
	v_exp_f32_e32 v78, v78
	v_cmp_gt_f32_e32 vcc, s33, v62
	v_sub_f32_e32 v69, v69, v79
	v_lshlrev_b32_e32 v64, 16, v64
	v_cndmask_b32_e64 v79, 0, 32, vcc
	v_add_f32_e32 v78, 1.0, v78
	v_ldexp_f32 v79, v62, v79
	v_rcp_f32_e32 v78, v78
	v_log_f32_e32 v79, v79
	v_mul_f32_e32 v64, 0xbfb8aa3b, v64
	v_exp_f32_e32 v64, v64
	v_mul_f32_e32 v65, v78, v65
	v_mul_f32_e32 v78, 0x3f317217, v79
	v_fma_f32 v78, v79, s74, -v78
	v_add_f32_e32 v64, 1.0, v64
	v_fmac_f32_e32 v78, 0x3377d1cf, v79
	v_rcp_f32_e32 v64, v64
	v_fmac_f32_e32 v78, 0x3f317217, v79
	v_cmp_lt_f32_e64 s[14:15], |v79|, s81
	v_lshlrev_b32_e32 v67, 16, v67
	v_fma_f32 v64, v110, v64, v93
	v_cndmask_b32_e64 v78, v79, v78, s[14:15]
	v_mul_f32_e32 v79, 0xbfb8aa3b, v67
	v_exp_f32_e32 v79, v79
	v_cndmask_b32_e32 v80, 0, v186, vcc
	v_cmp_gt_f32_e32 vcc, s33, v64
	v_sub_f32_e32 v78, v78, v80
	v_add_f32_e32 v79, 1.0, v79
	v_cndmask_b32_e64 v80, 0, 32, vcc
	v_ldexp_f32 v80, v64, v80
	v_lshlrev_b32_e32 v66, 16, v66
	v_rcp_f32_e32 v79, v79
	v_log_f32_e32 v80, v80
	v_mul_f32_e32 v66, 0xbfb8aa3b, v66
	v_exp_f32_e32 v66, v66
	v_mul_f32_e32 v67, v79, v67
	v_mul_f32_e32 v79, 0x3f317217, v80
	v_fma_f32 v79, v80, s74, -v79
	v_add_f32_e32 v66, 1.0, v66
	v_fmac_f32_e32 v79, 0x3377d1cf, v80
	v_rcp_f32_e32 v66, v66
	v_fmac_f32_e32 v79, 0x3f317217, v80
	v_cmp_lt_f32_e64 s[14:15], |v80|, s81
	v_lshlrev_b32_e32 v70, 16, v70
	v_fma_f32 v66, v110, v66, v93
	v_cndmask_b32_e64 v79, v80, v79, s[14:15]
	v_mul_f32_e32 v80, 0xbfb8aa3b, v70
	v_exp_f32_e32 v80, v80
	v_cndmask_b32_e32 v81, 0, v186, vcc
	v_cmp_gt_f32_e32 vcc, s33, v66
	v_sub_f32_e32 v79, v79, v81
	v_add_f32_e32 v80, 1.0, v80
	v_cndmask_b32_e64 v81, 0, 32, vcc
	v_ldexp_f32 v81, v66, v81
	v_lshlrev_b32_e32 v68, 16, v68
	v_rcp_f32_e32 v80, v80
	v_log_f32_e32 v81, v81
	v_mul_f32_e32 v68, 0xbfb8aa3b, v68
	v_exp_f32_e32 v68, v68
	v_mul_f32_e32 v70, v80, v70
	v_mul_f32_e32 v80, 0x3f317217, v81
	v_fma_f32 v80, v81, s74, -v80
	v_add_f32_e32 v68, 1.0, v68
	v_fmac_f32_e32 v80, 0x3377d1cf, v81
	v_rcp_f32_e32 v68, v68
	v_fmac_f32_e32 v80, 0x3f317217, v81
	v_cmp_lt_f32_e64 s[14:15], |v81|, s81
	v_lshlrev_b32_e32 v72, 16, v72
	v_fma_f32 v68, v110, v68, v93
	v_cndmask_b32_e64 v80, v81, v80, s[14:15]
	v_mul_f32_e32 v81, 0xbfb8aa3b, v72
	v_exp_f32_e32 v81, v81
	v_cndmask_b32_e32 v82, 0, v186, vcc
	v_cmp_gt_f32_e32 vcc, s33, v68
	v_sub_f32_e32 v80, v80, v82
	v_add_f32_e32 v81, 1.0, v81
	v_cndmask_b32_e64 v82, 0, 32, vcc
	v_ldexp_f32 v82, v68, v82
	v_lshlrev_b32_e32 v71, 16, v71
	v_rcp_f32_e32 v81, v81
	v_log_f32_e32 v82, v82
	v_mul_f32_e32 v71, 0xbfb8aa3b, v71
	v_exp_f32_e32 v71, v71
	v_mul_f32_e32 v72, v81, v72
	v_mul_f32_e32 v81, 0x3f317217, v82
	v_fma_f32 v81, v82, s74, -v81
	v_add_f32_e32 v71, 1.0, v71
	v_fmac_f32_e32 v81, 0x3377d1cf, v82
	v_rcp_f32_e32 v71, v71
	v_fmac_f32_e32 v81, 0x3f317217, v82
	v_cmp_lt_f32_e64 s[14:15], |v82|, s81
	v_lshlrev_b32_e32 v74, 16, v74
	v_fma_f32 v71, v110, v71, v93
	v_cndmask_b32_e64 v81, v82, v81, s[14:15]
	v_mul_f32_e32 v82, 0xbfb8aa3b, v74
	v_exp_f32_e32 v82, v82
	v_cndmask_b32_e32 v83, 0, v186, vcc
; __device__ __forceinline__ float bf2f(bf16 v) { return __uint_as_float(((unsigned)v) << 16); }
; __device__ __forceinline__ float sigmoidf_(float x) { return frcp_(1.0f + __expf(-x)); }
; __device__ __forceinline__ float siluf_(float x) { return x * frcp_(1.0f + __expf(-x)); }
; #define LAS __attribute__((address_space(3)))
; __device__ __forceinline__ void hgrn_pass1(const RecurBufs& rb, const float* lbs_l, int u, int tid, LAS unsigned char* lds) {
;     ...
; #pragma unroll
;         for (int j = 0; j < 16; ++j) { const float q = bf2f(*(const LAS bf16*)(Qt + (16 * jq + j) * PQ + d * 2)), f = bf2f(*(const LAS bf16*)(Kt + (16 * jq + j) * PQ + d * 2));
;             const float fg = lb + (1.f - lb) * sigmoidf_(f);
;             qq[j] = siluf_(q) * 0.08838834764831845f; kk[j] = 1.f - fg; lg[j] = __logf(fg); }
	v_cmp_gt_f32_e32 vcc, s33, v71
	v_sub_f32_e32 v81, v81, v83
	v_add_f32_e32 v82, 1.0, v82
	v_cndmask_b32_e64 v83, 0, 32, vcc
	v_ldexp_f32 v83, v71, v83
	v_lshlrev_b32_e32 v73, 16, v73
	v_rcp_f32_e32 v82, v82
	v_log_f32_e32 v83, v83
	v_mul_f32_e32 v73, 0xbfb8aa3b, v73
	v_exp_f32_e32 v73, v73
	v_mul_f32_e32 v74, v82, v74
	v_mul_f32_e32 v82, 0x3f317217, v83
	v_fma_f32 v82, v83, s74, -v82
	v_add_f32_e32 v73, 1.0, v73
	v_fmac_f32_e32 v82, 0x3377d1cf, v83
	v_rcp_f32_e32 v73, v73
	v_fmac_f32_e32 v82, 0x3f317217, v83
	v_cmp_lt_f32_e64 s[14:15], |v83|, s81
	v_lshlrev_b32_e32 v75, 16, v75
	v_fma_f32 v73, v110, v73, v93
	v_cndmask_b32_e64 v82, v83, v82, s[14:15]
	v_mul_f32_e32 v83, 0xbfb8aa3b, v75
	v_exp_f32_e32 v83, v83
	v_cndmask_b32_e32 v84, 0, v186, vcc
	v_cmp_gt_f32_e32 vcc, s33, v73
	v_sub_f32_e32 v82, v82, v84
	v_add_f32_e32 v83, 1.0, v83
	v_cndmask_b32_e64 v84, 0, 32, vcc
	v_ldexp_f32 v84, v73, v84
	v_lshlrev_b32_e32 v76, 16, v76
	v_rcp_f32_e32 v83, v83
	v_log_f32_e32 v84, v84
	v_mul_f32_e32 v76, 0xbfb8aa3b, v76
	v_exp_f32_e32 v76, v76
	v_mul_f32_e32 v75, v83, v75
	v_mul_f32_e32 v83, 0x3f317217, v84
	v_fma_f32 v83, v84, s74, -v83
	v_add_f32_e32 v76, 1.0, v76
	v_fmac_f32_e32 v83, 0x3377d1cf, v84
	v_rcp_f32_e32 v76, v76
	v_fmac_f32_e32 v83, 0x3f317217, v84
	v_cmp_lt_f32_e64 s[14:15], |v84|, s81
	v_lshlrev_b32_e32 v77, 16, v77
	v_fma_f32 v76, v110, v76, v93
	v_cndmask_b32_e64 v83, v84, v83, s[14:15]
	v_mul_f32_e32 v84, 0xbfb8aa3b, v77
	v_exp_f32_e32 v84, v84
	v_cndmask_b32_e32 v85, 0, v186, vcc
	v_cmp_gt_f32_e32 vcc, s33, v76
	v_sub_f32_e32 v83, v83, v85
	v_add_f32_e32 v84, 1.0, v84
	v_cndmask_b32_e64 v85, 0, 32, vcc
	v_ldexp_f32 v85, v76, v85
	v_rcp_f32_e32 v84, v84
	v_log_f32_e32 v85, v85
	v_cndmask_b32_e32 v122, 0, v186, vcc
	v_mul_f32_e32 v63, 0x3db504f3, v63
	v_mul_f32_e32 v77, v84, v77
	v_mul_f32_e32 v84, 0x3f317217, v85
	v_fma_f32 v84, v85, s74, -v84
	v_fmac_f32_e32 v84, 0x3377d1cf, v85
	v_fmac_f32_e32 v84, 0x3f317217, v85
	v_cmp_lt_f32_e64 s[14:15], |v85|, s81
	v_sub_f32_e32 v10, 1.0, v10
	v_mul_f32_e32 v65, 0x3db504f3, v65
	v_cndmask_b32_e64 v84, v85, v84, s[14:15]
	ds_read_u16 v85, v98 offset:19584
	ds_read_u16 v86, v98 offset:19856
	ds_read_u16 v87, v98 offset:20128
	ds_read_u16 v88, v98 offset:20400
	ds_read_u16 v89, v98 offset:20672
	ds_read_u16 v90, v98 offset:20944
	ds_read_u16 v91, v98 offset:21216
	ds_read_u16 v111, v98 offset:21488
	s_waitcnt lgkmcnt(0)
	v_lshlrev_b32_e32 v85, 16, v85
	v_mul_f32_e32 v85, 0xbfb8aa3b, v85
	v_exp_f32_e32 v85, v85
	ds_read_u16 v113, v98 offset:2176
	ds_read_u16 v114, v98 offset:2448
	ds_read_u16 v115, v98 offset:2720
	ds_read_u16 v116, v98 offset:2992
	ds_read_u16 v117, v98 offset:3264
	ds_read_u16 v118, v98 offset:3536
	ds_read_u16 v119, v98 offset:3808
	ds_read_u16 v120, v98 offset:4080
	s_waitcnt lgkmcnt(0)
	v_lshlrev_b32_e32 v113, 16, v113
	v_mul_f32_e32 v121, 0xbfb8aa3b, v113
	v_add_f32_e32 v85, 1.0, v85
	v_rcp_f32_e32 v85, v85
	v_exp_f32_e32 v121, v121
	v_sub_f32_e32 v84, v84, v122
	v_lshlrev_b32_e32 v86, 16, v86
	v_fma_f32 v85, v110, v85, v93
	v_cmp_gt_f32_e32 vcc, s33, v85
	v_add_f32_e32 v121, 1.0, v121
	v_rcp_f32_e32 v121, v121
	v_cndmask_b32_e64 v122, 0, 32, vcc
	v_ldexp_f32 v122, v85, v122
	v_log_f32_e32 v122, v122
	v_mul_f32_e32 v86, 0xbfb8aa3b, v86
	v_exp_f32_e32 v86, v86
	v_mul_f32_e32 v113, v121, v113
	v_mul_f32_e32 v121, 0x3f317217, v122
	v_fma_f32 v121, v122, s74, -v121
	v_add_f32_e32 v86, 1.0, v86
	v_fmac_f32_e32 v121, 0x3377d1cf, v122
	v_rcp_f32_e32 v86, v86
	v_fmac_f32_e32 v121, 0x3f317217, v122
	v_cmp_lt_f32_e64 s[14:15], |v122|, s81
	v_lshlrev_b32_e32 v114, 16, v114
	v_fma_f32 v86, v110, v86, v93
	v_cndmask_b32_e64 v121, v122, v121, s[14:15]
	v_mul_f32_e32 v122, 0xbfb8aa3b, v114
	v_exp_f32_e32 v122, v122
	v_cndmask_b32_e32 v123, 0, v186, vcc
	v_cmp_gt_f32_e32 vcc, s33, v86
	v_sub_f32_e32 v121, v121, v123
	v_add_f32_e32 v122, 1.0, v122
	v_cndmask_b32_e64 v123, 0, 32, vcc
	v_ldexp_f32 v123, v86, v123
	v_lshlrev_b32_e32 v87, 16, v87
	v_rcp_f32_e32 v122, v122
	v_log_f32_e32 v123, v123
	v_mul_f32_e32 v87, 0xbfb8aa3b, v87
	v_exp_f32_e32 v87, v87
	v_mul_f32_e32 v114, v122, v114
	v_mul_f32_e32 v122, 0x3f317217, v123
	v_fma_f32 v122, v123, s74, -v122
	v_add_f32_e32 v87, 1.0, v87
	v_fmac_f32_e32 v122, 0x3377d1cf, v123
	v_rcp_f32_e32 v87, v87
	v_fmac_f32_e32 v122, 0x3f317217, v123
	v_cmp_lt_f32_e64 s[14:15], |v123|, s81
	v_lshlrev_b32_e32 v115, 16, v115
	v_fma_f32 v87, v110, v87, v93
	v_cndmask_b32_e64 v122, v123, v122, s[14:15]
	v_mul_f32_e32 v123, 0xbfb8aa3b, v115
	v_exp_f32_e32 v123, v123
	v_cndmask_b32_e32 v124, 0, v186, vcc
	v_cmp_gt_f32_e32 vcc, s33, v87
	v_sub_f32_e32 v122, v122, v124
	v_add_f32_e32 v123, 1.0, v123
	v_cndmask_b32_e64 v124, 0, 32, vcc
	v_ldexp_f32 v124, v87, v124
	v_lshlrev_b32_e32 v88, 16, v88
	v_rcp_f32_e32 v123, v123
	v_log_f32_e32 v124, v124
	v_mul_f32_e32 v88, 0xbfb8aa3b, v88
	v_exp_f32_e32 v88, v88
	v_mul_f32_e32 v115, v123, v115
	v_mul_f32_e32 v123, 0x3f317217, v124
	v_fma_f32 v123, v124, s74, -v123
	v_add_f32_e32 v88, 1.0, v88
	v_fmac_f32_e32 v123, 0x3377d1cf, v124
	v_rcp_f32_e32 v88, v88
	v_fmac_f32_e32 v123, 0x3f317217, v124
	v_cmp_lt_f32_e64 s[14:15], |v124|, s81
	v_lshlrev_b32_e32 v116, 16, v116
	v_fma_f32 v88, v110, v88, v93
	v_cndmask_b32_e64 v123, v124, v123, s[14:15]
	v_mul_f32_e32 v124, 0xbfb8aa3b, v116
	v_exp_f32_e32 v124, v124
	v_cndmask_b32_e32 v125, 0, v186, vcc
	v_cmp_gt_f32_e32 vcc, s33, v88
	v_sub_f32_e32 v123, v123, v125
	v_add_f32_e32 v124, 1.0, v124
	v_cndmask_b32_e64 v125, 0, 32, vcc
	v_ldexp_f32 v125, v88, v125
	v_lshlrev_b32_e32 v89, 16, v89
	v_rcp_f32_e32 v124, v124
	v_log_f32_e32 v125, v125
	v_mul_f32_e32 v89, 0xbfb8aa3b, v89
; __device__ __forceinline__ float bf2f(bf16 v) { return __uint_as_float(((unsigned)v) << 16); }
; __device__ __forceinline__ float sigmoidf_(float x) { return frcp_(1.0f + __expf(-x)); }
; __device__ __forceinline__ float siluf_(float x) { return x * frcp_(1.0f + __expf(-x)); }
; #define LAS __attribute__((address_space(3)))
; __device__ __forceinline__ void sync_threads() { __syncthreads(); }
; __device__ __forceinline__ void hgrn_pass1(const RecurBufs& rb, const float* lbs_l, int u, int tid, LAS unsigned char* lds) {
;     ...
; #pragma unroll
;         for (int j = 0; j < 16; ++j) { const float q = bf2f(*(const LAS bf16*)(Qt + (16 * jq + j) * PQ + d * 2)), f = bf2f(*(const LAS bf16*)(Kt + (16 * jq + j) * PQ + d * 2));
;             const float fg = lb + (1.f - lb) * sigmoidf_(f);
;             qq[j] = siluf_(q) * 0.08838834764831845f; kk[j] = 1.f - fg; lg[j] = __logf(fg); }
; #pragma unroll
;         for (int j = 1; j < 16; ++j) lg[j] += lg[j - 1];
;         part[jq * 128 + d] = lg[15];
;         sync_threads();
;         const float p0 = part[d], p1 = part[128 + d], p2 = part[256 + d], p3 = part[384 + d];
	v_exp_f32_e32 v89, v89
	v_mul_f32_e32 v116, v124, v116
	v_mul_f32_e32 v124, 0x3f317217, v125
	v_fma_f32 v124, v125, s74, -v124
	v_add_f32_e32 v89, 1.0, v89
	v_fmac_f32_e32 v124, 0x3377d1cf, v125
	v_rcp_f32_e32 v89, v89
	v_fmac_f32_e32 v124, 0x3f317217, v125
	v_cmp_lt_f32_e64 s[14:15], |v125|, s81
	v_lshlrev_b32_e32 v117, 16, v117
	v_fma_f32 v89, v110, v89, v93
	v_cndmask_b32_e64 v124, v125, v124, s[14:15]
	v_mul_f32_e32 v125, 0xbfb8aa3b, v117
	v_exp_f32_e32 v125, v125
	v_cndmask_b32_e32 v126, 0, v186, vcc
	v_cmp_gt_f32_e32 vcc, s33, v89
	v_sub_f32_e32 v124, v124, v126
	v_add_f32_e32 v125, 1.0, v125
	v_cndmask_b32_e64 v126, 0, 32, vcc
	v_ldexp_f32 v126, v89, v126
	v_lshlrev_b32_e32 v90, 16, v90
	v_rcp_f32_e32 v125, v125
	v_log_f32_e32 v126, v126
	v_mul_f32_e32 v90, 0xbfb8aa3b, v90
	v_exp_f32_e32 v90, v90
	v_mul_f32_e32 v117, v125, v117
	v_mul_f32_e32 v125, 0x3f317217, v126
	v_fma_f32 v125, v126, s74, -v125
	v_add_f32_e32 v90, 1.0, v90
	v_fmac_f32_e32 v125, 0x3377d1cf, v126
	v_rcp_f32_e32 v90, v90
	v_fmac_f32_e32 v125, 0x3f317217, v126
	v_cmp_lt_f32_e64 s[14:15], |v126|, s81
	v_lshlrev_b32_e32 v118, 16, v118
	v_fma_f32 v90, v110, v90, v93
	v_cndmask_b32_e64 v125, v126, v125, s[14:15]
	v_mul_f32_e32 v126, 0xbfb8aa3b, v118
	v_exp_f32_e32 v126, v126
	v_lshlrev_b32_e32 v91, 16, v91
	v_cndmask_b32_e32 v127, 0, v186, vcc
	v_cmp_gt_f32_e32 vcc, s33, v90
	v_mul_f32_e32 v91, 0xbfb8aa3b, v91
	v_sub_f32_e32 v125, v125, v127
	v_cndmask_b32_e64 v127, 0, 32, vcc
	v_exp_f32_e32 v91, v91
	v_add_f32_e32 v126, 1.0, v126
	v_ldexp_f32 v127, v90, v127
	v_rcp_f32_e32 v126, v126
	v_log_f32_e32 v127, v127
	v_add_f32_e32 v91, 1.0, v91
	v_lshlrev_b32_e32 v119, 16, v119
	v_rcp_f32_e32 v91, v91
	v_mul_f32_e32 v118, v126, v118
	v_mul_f32_e32 v126, 0x3f317217, v127
	v_mul_f32_e32 v128, 0xbfb8aa3b, v119
	v_fma_f32 v126, v127, s74, -v126
	v_exp_f32_e32 v128, v128
	v_fmac_f32_e32 v126, 0x3377d1cf, v127
	v_fmac_f32_e32 v126, 0x3f317217, v127
	v_cmp_lt_f32_e64 s[14:15], |v127|, s81
	v_fma_f32 v91, v110, v91, v93
	v_lshlrev_b32_e32 v111, 16, v111
	v_cndmask_b32_e64 v126, v127, v126, s[14:15]
	v_cmp_gt_f32_e64 s[14:15], s33, v91
	v_mul_f32_e32 v111, 0xbfb8aa3b, v111
	v_add_f32_e32 v127, 1.0, v128
	v_cndmask_b32_e64 v128, 0, 32, s[14:15]
	v_exp_f32_e32 v111, v111
	v_ldexp_f32 v128, v91, v128
	v_rcp_f32_e32 v127, v127
	v_log_f32_e32 v128, v128
	v_add_f32_e32 v111, 1.0, v111
	v_rcp_f32_e32 v111, v111
	v_mul_f32_e32 v119, v127, v119
	v_mul_f32_e32 v127, 0x3f317217, v128
	v_fma_f32 v127, v128, s74, -v127
	v_cndmask_b32_e32 v129, 0, v186, vcc
	v_fmac_f32_e32 v127, 0x3377d1cf, v128
	v_sub_f32_e32 v126, v126, v129
	v_fmac_f32_e32 v127, 0x3f317217, v128
	v_cmp_lt_f32_e64 vcc, |v128|, s81
	v_fma_f32 v129, v110, v111, v93
	v_lshlrev_b32_e32 v120, 16, v120
	v_cndmask_b32_e32 v127, v128, v127, vcc
	v_cmp_gt_f32_e32 vcc, s33, v129
	v_mul_f32_e32 v111, 0xbfb8aa3b, v120
	v_exp_f32_e32 v111, v111
	v_cndmask_b32_e64 v130, 0, 32, vcc
	v_ldexp_f32 v130, v129, v130
	v_log_f32_e32 v130, v130
	v_cndmask_b32_e64 v128, 0, v186, s[14:15]
	v_add_f32_e32 v111, 1.0, v111
	v_sub_f32_e32 v127, v127, v128
	v_rcp_f32_e32 v128, v111
	v_mul_f32_e32 v111, 0x3f317217, v130
	v_fma_f32 v111, v130, s74, -v111
	v_fmac_f32_e32 v111, 0x3377d1cf, v130
	v_fmac_f32_e32 v111, 0x3f317217, v130
	v_cmp_lt_f32_e64 s[14:15], |v130|, s81
	v_mul_f32_e32 v120, v128, v120
	v_sub_f32_e32 v62, 1.0, v62
	v_cndmask_b32_e64 v111, v130, v111, s[14:15]
	v_cndmask_b32_e32 v130, 0, v186, vcc
	v_sub_f32_e32 v111, v111, v130
	v_add_f32_e32 v130, v69, v78
	v_add_f32_e32 v131, v130, v79
	v_add_f32_e32 v132, v131, v80
	v_add_f32_e32 v133, v132, v81
	v_add_f32_e32 v82, v133, v82
	v_add_f32_e32 v83, v82, v83
	v_add_f32_e32 v84, v83, v84
	v_add_f32_e32 v121, v84, v121
	v_add_f32_e32 v122, v121, v122
	v_add_f32_e32 v123, v122, v123
	v_add_f32_e32 v124, v123, v124
	v_add_f32_e32 v125, v124, v125
	v_add_f32_e32 v126, v125, v126
	v_add_f32_e32 v127, v126, v127
	v_add_f32_e32 v134, v127, v111
	v_add_u32_e32 v111, v100, v112
	ds_write_b32 v109, v134 offset:52224
	s_waitcnt lgkmcnt(0)
	s_barrier
	ds_read2st64_b32 v[78:79], v111 offset0:204 offset1:206
	ds_read2st64_b32 v[80:81], v111 offset0:208 offset1:210
	v_mul_f32_e32 v67, 0x3db504f3, v67
	v_sub_f32_e32 v64, 1.0, v64
	v_mul_f32_e32 v70, 0x3db504f3, v70
	s_waitcnt lgkmcnt(0)
; __device__ __forceinline__ bf16 f2bf(float f) { return (bf16)pk2(f, f); }
; __device__ __forceinline__ float frcp_(float x) { return __builtin_amdgcn_rcpf(x); }
; #define LAS __attribute__((address_space(3)))
; __device__ __forceinline__ void hgrn_pass1(const RecurBufs& rb, const float* lbs_l, int u, int tid, LAS unsigned char* lds) {
;     ...
;         const float p0 = part[d], p1 = part[128 + d], p2 = part[256 + d], p3 = part[384 + d];
;         const float off = (jq > 0 ? p0 : 0.f) + (jq > 1 ? p1 : 0.f) + (jq > 2 ? p2 : 0.f);
;         const float bref = p0 + p1, bend = (p0 + p1) + (p2 + p3);
; #pragma unroll
;         for (int j = 0; j < 16; ++j) { const float e1 = __expf(fminf(fmaxf(off + lg[j] - bref, -80.f), 80.f));
;             *(LAS bf16*)(Qt + (16 * jq + j) * PQ + d * 2) = f2bf(qq[j] * e1); *(LAS bf16*)(Kt + (16 * jq + j) * PQ + d * 2) = f2bf(kk[j] * frcp_(e1)); }
	v_cndmask_b32_e64 v128, 0, v78, s[10:11]
	v_cndmask_b32_e64 v135, 0, v79, s[12:13]
	v_add_f32_e32 v128, v128, v135
	v_cndmask_b32_e64 v135, 0, v80, s[8:9]
	v_add_f32_e32 v128, v128, v135
	v_add_f32_e32 v78, v78, v79
	v_add_f32_e32 v69, v69, v128
	v_sub_f32_e32 v69, v69, v78
	v_med3_f32 v69, v69, s86, v187
	v_mul_f32_e32 v69, 0x3fb8aa3b, v69
	v_exp_f32_e32 v69, v69
	v_sub_f32_e32 v66, 1.0, v66
	v_mul_f32_e32 v72, 0x3db504f3, v72
	v_sub_f32_e32 v68, 1.0, v68
	v_mul_f32_e32 v63, v63, v69
	v_cvt_pk_bf16_f32 v63, v63, v63
	ds_write_b16 v98, v63
	v_rcp_f32_e32 v63, v69
	v_add_f32_e32 v69, v130, v128
	v_sub_f32_e32 v69, v69, v78
	v_med3_f32 v69, v69, s86, v187
	v_mul_f32_e32 v69, 0x3fb8aa3b, v69
	v_exp_f32_e32 v69, v69
	v_mul_f32_e32 v10, v10, v63
	v_cvt_pk_bf16_f32 v10, v10, v10
	ds_write_b16 v98, v10 offset:17408
	v_mul_f32_e32 v10, v65, v69
	v_add_f32_e32 v63, v131, v128
	v_cvt_pk_bf16_f32 v10, v10, v10
	v_sub_f32_e32 v63, v63, v78
	ds_write_b16 v98, v10 offset:272
	v_rcp_f32_e32 v10, v69
	v_med3_f32 v63, v63, s86, v187
	v_mul_f32_e32 v63, 0x3fb8aa3b, v63
	v_exp_f32_e32 v63, v63
	v_mul_f32_e32 v10, v62, v10
	v_cvt_pk_bf16_f32 v10, v10, v10
	ds_write_b16 v98, v10 offset:17680
	v_mul_f32_e32 v10, v67, v63
	v_add_f32_e32 v62, v132, v128
	v_cvt_pk_bf16_f32 v10, v10, v10
	v_sub_f32_e32 v62, v62, v78
	ds_write_b16 v98, v10 offset:544
	v_rcp_f32_e32 v10, v63
	v_med3_f32 v62, v62, s86, v187
	v_mul_f32_e32 v62, 0x3fb8aa3b, v62
	v_exp_f32_e32 v62, v62
	v_mul_f32_e32 v10, v64, v10
	v_cvt_pk_bf16_f32 v10, v10, v10
	ds_write_b16 v98, v10 offset:17952
	v_mul_f32_e32 v10, v70, v62
	v_cvt_pk_bf16_f32 v10, v10, v10
	ds_write_b16 v98, v10 offset:816
	v_rcp_f32_e32 v10, v62
	v_add_f32_e32 v62, v133, v128
	v_sub_f32_e32 v62, v62, v78
	v_med3_f32 v62, v62, s86, v187
	v_mul_f32_e32 v62, 0x3fb8aa3b, v62
	v_exp_f32_e32 v62, v62
	v_mul_f32_e32 v10, v66, v10
	v_cvt_pk_bf16_f32 v10, v10, v10
	ds_write_b16 v98, v10 offset:18224
	v_mul_f32_e32 v10, v72, v62
	v_cvt_pk_bf16_f32 v10, v10, v10
	ds_write_b16 v98, v10 offset:1088
	v_rcp_f32_e32 v10, v62
	v_add_f32_e32 v62, v82, v128
	v_sub_f32_e32 v62, v62, v78
	v_med3_f32 v62, v62, s86, v187
	v_mul_f32_e32 v62, 0x3fb8aa3b, v62
	v_exp_f32_e32 v62, v62
	v_mul_f32_e32 v10, v68, v10
	v_mul_f32_e32 v74, 0x3db504f3, v74
	v_cvt_pk_bf16_f32 v10, v10, v10
	ds_write_b16 v98, v10 offset:18496
	v_mul_f32_e32 v10, v74, v62
	v_cvt_pk_bf16_f32 v10, v10, v10
	ds_write_b16 v98, v10 offset:1360
	v_rcp_f32_e32 v10, v62
	v_add_f32_e32 v62, v83, v128
	v_sub_f32_e32 v62, v62, v78
	v_med3_f32 v62, v62, s86, v187
	v_mul_f32_e32 v62, 0x3fb8aa3b, v62
	v_exp_f32_e32 v62, v62
	v_sub_f32_e32 v71, 1.0, v71
	v_mul_f32_e32 v10, v71, v10
	v_mul_f32_e32 v75, 0x3db504f3, v75
	v_cvt_pk_bf16_f32 v10, v10, v10
	ds_write_b16 v98, v10 offset:18768
	v_mul_f32_e32 v10, v75, v62
	v_cvt_pk_bf16_f32 v10, v10, v10
	ds_write_b16 v98, v10 offset:1632
	v_rcp_f32_e32 v10, v62
	v_add_f32_e32 v62, v84, v128
	v_sub_f32_e32 v62, v62, v78
	v_med3_f32 v62, v62, s86, v187
	v_mul_f32_e32 v62, 0x3fb8aa3b, v62
	v_exp_f32_e32 v62, v62
	v_sub_f32_e32 v73, 1.0, v73
	v_mul_f32_e32 v10, v73, v10
	v_mul_f32_e32 v77, 0x3db504f3, v77
	v_cvt_pk_bf16_f32 v10, v10, v10
	ds_write_b16 v98, v10 offset:19040
	v_mul_f32_e32 v10, v77, v62
	v_cvt_pk_bf16_f32 v10, v10, v10
	ds_write_b16 v98, v10 offset:1904
	v_rcp_f32_e32 v10, v62
	v_add_f32_e32 v62, v121, v128
	v_sub_f32_e32 v62, v62, v78
	v_med3_f32 v62, v62, s86, v187
	v_mul_f32_e32 v62, 0x3fb8aa3b, v62
	v_exp_f32_e32 v62, v62
	v_sub_f32_e32 v76, 1.0, v76
	v_mul_f32_e32 v10, v76, v10
	v_mul_f32_e32 v113, 0x3db504f3, v113
	v_cvt_pk_bf16_f32 v10, v10, v10
	ds_write_b16 v98, v10 offset:19312
	v_mul_f32_e32 v10, v113, v62
	v_cvt_pk_bf16_f32 v10, v10, v10
	ds_write_b16 v98, v10 offset:2176
	v_rcp_f32_e32 v10, v62
	v_add_f32_e32 v62, v122, v128
	v_sub_f32_e32 v62, v62, v78
	v_med3_f32 v62, v62, s86, v187
	v_mul_f32_e32 v62, 0x3fb8aa3b, v62
	v_exp_f32_e32 v62, v62
	v_sub_f32_e32 v85, 1.0, v85
	v_mul_f32_e32 v10, v85, v10
	v_mul_f32_e32 v114, 0x3db504f3, v114
	v_cvt_pk_bf16_f32 v10, v10, v10
	ds_write_b16 v98, v10 offset:19584
	v_mul_f32_e32 v10, v114, v62
	v_cvt_pk_bf16_f32 v10, v10, v10
	ds_write_b16 v98, v10 offset:2448
	v_rcp_f32_e32 v10, v62
	v_add_f32_e32 v62, v123, v128
	v_sub_f32_e32 v62, v62, v78
	v_med3_f32 v62, v62, s86, v187
	v_mul_f32_e32 v62, 0x3fb8aa3b, v62
	v_exp_f32_e32 v62, v62
	v_sub_f32_e32 v86, 1.0, v86
	v_mul_f32_e32 v10, v86, v10
	v_mul_f32_e32 v115, 0x3db504f3, v115
	v_cvt_pk_bf16_f32 v10, v10, v10
	ds_write_b16 v98, v10 offset:19856
	v_mul_f32_e32 v10, v115, v62
	v_cvt_pk_bf16_f32 v10, v10, v10
	ds_write_b16 v98, v10 offset:2720
	v_rcp_f32_e32 v10, v62
	v_add_f32_e32 v62, v124, v128
	v_sub_f32_e32 v62, v62, v78
	v_med3_f32 v62, v62, s86, v187
	v_mul_f32_e32 v62, 0x3fb8aa3b, v62
	v_exp_f32_e32 v62, v62
	v_sub_f32_e32 v87, 1.0, v87
	v_mul_f32_e32 v10, v87, v10
	v_mul_f32_e32 v116, 0x3db504f3, v116
	v_cvt_pk_bf16_f32 v10, v10, v10
	ds_write_b16 v98, v10 offset:20128
	v_mul_f32_e32 v10, v116, v62
	v_cvt_pk_bf16_f32 v10, v10, v10
	ds_write_b16 v98, v10 offset:2992
	v_rcp_f32_e32 v10, v62
	v_add_f32_e32 v62, v125, v128
	v_sub_f32_e32 v62, v62, v78
	v_med3_f32 v62, v62, s86, v187
	v_mul_f32_e32 v62, 0x3fb8aa3b, v62
	v_exp_f32_e32 v62, v62
	v_sub_f32_e32 v88, 1.0, v88
	v_mul_f32_e32 v10, v88, v10
	v_mul_f32_e32 v117, 0x3db504f3, v117
	v_cvt_pk_bf16_f32 v10, v10, v10
	ds_write_b16 v98, v10 offset:20400
	v_mul_f32_e32 v10, v117, v62
	v_cvt_pk_bf16_f32 v10, v10, v10
	ds_write_b16 v98, v10 offset:3264
	v_rcp_f32_e32 v10, v62
	v_add_f32_e32 v62, v126, v128
	v_sub_f32_e32 v62, v62, v78
	v_med3_f32 v62, v62, s86, v187
	v_mul_f32_e32 v62, 0x3fb8aa3b, v62
; __device__ __forceinline__ float bf2f(bf16 v) { return __uint_as_float(((unsigned)v) << 16); }
; __device__ __forceinline__ bf16 f2bf(float f) { return (bf16)pk2(f, f); }
; __device__ __forceinline__ float frcp_(float x) { return __builtin_amdgcn_rcpf(x); }
; __device__ __forceinline__ float sigmoidf_(float x) { return frcp_(1.0f + __expf(-x)); }
; __device__ __forceinline__ float siluf_(float x) { return x * frcp_(1.0f + __expf(-x)); }
; #define LAS __attribute__((address_space(3)))
; __device__ __forceinline__ void sync_threads() { __syncthreads(); }
; __device__ __forceinline__ void hgrn_pass1(const RecurBufs& rb, const float* lbs_l, int u, int tid, LAS unsigned char* lds) {
;     ...
;         *(LAS v4u*)(Qt + sr * PQ + sc16 * 16) = pre[0]; *(LAS v4u*)(Qt + (sr + 32) * PQ + sc16 * 16) = pre[1];
;         *(LAS v4u*)(Kt + sr * PQ + sc16 * 16) = pre[2]; *(LAS v4u*)(Kt + (sr + 32) * PQ + sc16 * 16) = pre[3];
;         *(LAS v4u*)(V + sr * PQ + sc16 * 16) = pre[4]; *(LAS v4u*)(V + (sr + 32) * PQ + sc16 * 16) = pre[5];
;         if (ch + 1 < NCH) { const bf16* gn = gq + RC * (size_t)LDP;
;             pre[0] = *(const v4u*)gn; pre[1] = *(const v4u*)(gn + 32 * (size_t)LDP); pre[2] = *(const v4u*)(gn + PC_F); pre[3] = *(const v4u*)(gn + 32 * (size_t)LDP + PC_F);
;             pre[4] = *(const v4u*)(gn + PC_I); pre[5] = *(const v4u*)(gn + 32 * (size_t)LDP + PC_I); }
;         sync_threads();
;         float qq[16], kk[16], lg[16];
; #pragma unroll
;         for (int j = 0; j < 16; ++j) { const float q = bf2f(*(const LAS bf16*)(Qt + (16 * jq + j) * PQ + d * 2)), f = bf2f(*(const LAS bf16*)(Kt + (16 * jq + j) * PQ + d * 2));
;             const float fg = lb + (1.f - lb) * sigmoidf_(f);
;             qq[j] = siluf_(q) * 0.08838834764831845f; kk[j] = 1.f - fg; lg[j] = __logf(fg); }
;     ...
;         for (int j = 0; j < 16; ++j) { const float e1 = __expf(fminf(fmaxf(off + lg[j] - bref, -80.f), 80.f));
;             *(LAS bf16*)(Qt + (16 * jq + j) * PQ + d * 2) = f2bf(qq[j] * e1); *(LAS bf16*)(Kt + (16 * jq + j) * PQ + d * 2) = f2bf(kk[j] * frcp_(e1)); }
;         if (jq == 0) { const float eref = __expf(bref), esc = __expf(bend - bref), edc = __expf(bend);
;             float* cvp = rb.cv + ((size_t)((b * 8 + h) * 32 + seg * NCH + ch) * 3) * 128;
;             cvp[d] = eref; cvp[128 + d] = esc; cvp[256 + d] = edc; vec[128 + d] = esc; vec[256 + d] = edc; }
	v_exp_f32_e32 v62, v62
	v_sub_f32_e32 v89, 1.0, v89
	v_mul_f32_e32 v10, v89, v10
	v_mul_f32_e32 v118, 0x3db504f3, v118
	v_cvt_pk_bf16_f32 v10, v10, v10
	ds_write_b16 v98, v10 offset:20672
	v_mul_f32_e32 v10, v118, v62
	v_cvt_pk_bf16_f32 v10, v10, v10
	ds_write_b16 v98, v10 offset:3536
	v_rcp_f32_e32 v10, v62
	v_add_f32_e32 v62, v128, v127
	v_sub_f32_e32 v62, v62, v78
	v_med3_f32 v62, v62, s86, v187
	v_mul_f32_e32 v62, 0x3fb8aa3b, v62
	v_exp_f32_e32 v62, v62
	v_sub_f32_e32 v90, 1.0, v90
	v_mul_f32_e32 v10, v90, v10
	v_mul_f32_e32 v119, 0x3db504f3, v119
	v_cvt_pk_bf16_f32 v10, v10, v10
	ds_write_b16 v98, v10 offset:20944
	v_mul_f32_e32 v10, v119, v62
	v_cvt_pk_bf16_f32 v10, v10, v10
	ds_write_b16 v98, v10 offset:3808
	v_rcp_f32_e32 v10, v62
	v_add_f32_e32 v62, v128, v134
	v_sub_f32_e32 v62, v62, v78
	v_med3_f32 v62, v62, s86, v187
	v_mul_f32_e32 v62, 0x3fb8aa3b, v62
	v_exp_f32_e32 v62, v62
	v_sub_f32_e32 v91, 1.0, v91
	v_mul_f32_e32 v10, v91, v10
	v_mul_f32_e32 v79, 0x3db504f3, v120
	v_add_f32_e32 v80, v80, v81
	v_cvt_pk_bf16_f32 v10, v10, v10
	ds_write_b16 v98, v10 offset:21216
	v_mul_f32_e32 v10, v79, v62
	v_rcp_f32_e32 v64, v62
	v_add_f32_e32 v62, v78, v80
	v_cvt_pk_bf16_f32 v10, v10, v10
	v_mul_f32_e32 v63, 0x3fb8aa3b, v62
	ds_write_b16 v98, v10 offset:4080
	v_exp_f32_e32 v10, v63
	v_sub_f32_e32 v120, 1.0, v129
	v_mul_f32_e32 v64, v120, v64
	v_cvt_pk_bf16_f32 v64, v64, v64
	ds_write_b16 v98, v64 offset:21488
	s_and_saveexec_b64 s[2:3], s[6:7]
	s_xor_b64 s[2:3], exec, s[2:3]
	v_exp_f32_e32 v10, v63
	s_andn2_saveexec_b64 s[2:3], s[2:3]
	s_cbranch_execz .LBB0_392
	v_sub_f32_e32 v62, v62, v78
	v_mul_f32_e32 v63, 0x3fb8aa3b, v78
	v_mul_f32_e32 v62, 0x3fb8aa3b, v62
	v_exp_f32_e32 v64, v63
	v_exp_f32_e32 v65, v62
	v_lshl_add_u64 v[62:63], s[72:73], 0, v[102:103]
	v_add_co_u32_e32 v62, vcc, 0x4d200000, v62
	s_nop 1
	v_addc_co_u32_e32 v63, vcc, 0, v63, vcc
	global_store_dword v[62:63], v64, off
	global_store_dword v[62:63], v65, off offset:512
	global_store_dword v[62:63], v10, off offset:1024
	ds_write2st64_b32 v111, v65, v10 offset0:214 offset1:216
	s_branch .LBB0_392
.LBB0_397:
	s_waitcnt vmcnt(0)
	ds_write_b128 v108, v[36:39]
	ds_write_b128 v108, v[44:47] offset:8704
	ds_write_b128 v108, v[40:43] offset:17408
	ds_write_b128 v108, v[48:51] offset:26112
	ds_write_b128 v108, v[52:55] offset:34816
	ds_write_b128 v108, v[56:59] offset:43520
	s_waitcnt lgkmcnt(0)
	s_barrier
	ds_read_u16 v10, v98 offset:17408
	ds_read_u16 v36, v98 offset:17680
	ds_read_u16 v38, v98 offset:17952
	ds_read_u16 v40, v98 offset:18224
	ds_read_u16 v42, v98 offset:18496
	ds_read_u16 v45, v98 offset:18768
	ds_read_u16 v47, v98 offset:19040
	ds_read_u16 v50, v98 offset:19312
	s_waitcnt lgkmcnt(7)
	v_lshlrev_b32_e32 v10, 16, v10
	v_mul_f32_e32 v10, 0xbfb8aa3b, v10
	v_exp_f32_e32 v10, v10
	ds_read_u16 v37, v98
	ds_read_u16 v39, v98 offset:272
	ds_read_u16 v41, v98 offset:544
	ds_read_u16 v44, v98 offset:816
	ds_read_u16 v46, v98 offset:1088
	ds_read_u16 v48, v98 offset:1360
	ds_read_u16 v49, v98 offset:1632
	ds_read_u16 v51, v98 offset:1904
	s_waitcnt lgkmcnt(7)
	v_lshlrev_b32_e32 v37, 16, v37
	v_mul_f32_e32 v43, 0xbfb8aa3b, v37
	v_add_f32_e32 v10, 1.0, v10
	v_rcp_f32_e32 v10, v10
	v_exp_f32_e32 v43, v43
	v_lshlrev_b32_e32 v36, 16, v36
	v_mul_f32_e32 v36, 0xbfb8aa3b, v36
	v_fma_f32 v10, v110, v10, v93
	v_cmp_gt_f32_e32 vcc, s33, v10
	v_add_f32_e32 v43, 1.0, v43
	v_rcp_f32_e32 v43, v43
	v_cndmask_b32_e64 v52, 0, 32, vcc
	v_ldexp_f32 v52, v10, v52
	v_log_f32_e32 v52, v52
	v_exp_f32_e32 v36, v36
	v_mul_f32_e32 v37, v43, v37
	s_waitcnt lgkmcnt(6)
	v_lshlrev_b32_e32 v39, 16, v39
	v_mul_f32_e32 v43, 0x3f317217, v52
	v_fma_f32 v43, v52, s74, -v43
	v_add_f32_e32 v36, 1.0, v36
	v_fmac_f32_e32 v43, 0x3377d1cf, v52
	v_rcp_f32_e32 v36, v36
	v_fmac_f32_e32 v43, 0x3f317217, v52
	v_cmp_lt_f32_e64 s[14:15], |v52|, s81
	v_cndmask_b32_e32 v53, 0, v186, vcc
	v_fma_f32 v36, v110, v36, v93
	v_cndmask_b32_e64 v43, v52, v43, s[14:15]
	v_mul_f32_e32 v52, 0xbfb8aa3b, v39
	v_exp_f32_e32 v52, v52
	v_cmp_gt_f32_e32 vcc, s33, v36
	v_sub_f32_e32 v43, v43, v53
	v_lshlrev_b32_e32 v38, 16, v38
	v_cndmask_b32_e64 v53, 0, 32, vcc
	v_add_f32_e32 v52, 1.0, v52
	v_ldexp_f32 v53, v36, v53
	v_rcp_f32_e32 v52, v52
	v_log_f32_e32 v53, v53
	v_mul_f32_e32 v38, 0xbfb8aa3b, v38
	v_exp_f32_e32 v38, v38
	v_mul_f32_e32 v39, v52, v39
	v_mul_f32_e32 v52, 0x3f317217, v53
	v_fma_f32 v52, v53, s74, -v52
	v_add_f32_e32 v38, 1.0, v38
	v_fmac_f32_e32 v52, 0x3377d1cf, v53
	v_rcp_f32_e32 v38, v38
	v_fmac_f32_e32 v52, 0x3f317217, v53
	v_cmp_lt_f32_e64 s[14:15], |v53|, s81
	s_waitcnt lgkmcnt(5)
	v_lshlrev_b32_e32 v41, 16, v41
	v_fma_f32 v38, v110, v38, v93
	v_cndmask_b32_e64 v52, v53, v52, s[14:15]
	v_mul_f32_e32 v53, 0xbfb8aa3b, v41
	v_exp_f32_e32 v53, v53
	v_cndmask_b32_e32 v54, 0, v186, vcc
	v_cmp_gt_f32_e32 vcc, s33, v38
	v_sub_f32_e32 v52, v52, v54
	v_add_f32_e32 v53, 1.0, v53
	v_cndmask_b32_e64 v54, 0, 32, vcc
	v_ldexp_f32 v54, v38, v54
	v_lshlrev_b32_e32 v40, 16, v40
	v_rcp_f32_e32 v53, v53
	v_log_f32_e32 v54, v54
	v_mul_f32_e32 v40, 0xbfb8aa3b, v40
	v_exp_f32_e32 v40, v40
	v_mul_f32_e32 v41, v53, v41
	v_mul_f32_e32 v53, 0x3f317217, v54
	v_fma_f32 v53, v54, s74, -v53
	v_add_f32_e32 v40, 1.0, v40
	v_fmac_f32_e32 v53, 0x3377d1cf, v54
	v_rcp_f32_e32 v40, v40
	v_fmac_f32_e32 v53, 0x3f317217, v54
	v_cmp_lt_f32_e64 s[14:15], |v54|, s81
	s_waitcnt lgkmcnt(4)
; __device__ __forceinline__ float bf2f(bf16 v) { return __uint_as_float(((unsigned)v) << 16); }
; __device__ __forceinline__ float sigmoidf_(float x) { return frcp_(1.0f + __expf(-x)); }
; __device__ __forceinline__ float siluf_(float x) { return x * frcp_(1.0f + __expf(-x)); }
; #define LAS __attribute__((address_space(3)))
; __device__ __forceinline__ void hgrn_pass1(const RecurBufs& rb, const float* lbs_l, int u, int tid, LAS unsigned char* lds) {
;     ...
; #pragma unroll
;         for (int j = 0; j < 16; ++j) { const float q = bf2f(*(const LAS bf16*)(Qt + (16 * jq + j) * PQ + d * 2)), f = bf2f(*(const LAS bf16*)(Kt + (16 * jq + j) * PQ + d * 2));
;             const float fg = lb + (1.f - lb) * sigmoidf_(f);
;             qq[j] = siluf_(q) * 0.08838834764831845f; kk[j] = 1.f - fg; lg[j] = __logf(fg); }
	v_lshlrev_b32_e32 v44, 16, v44
	v_fma_f32 v40, v110, v40, v93
	v_cndmask_b32_e64 v53, v54, v53, s[14:15]
	v_mul_f32_e32 v54, 0xbfb8aa3b, v44
	v_exp_f32_e32 v54, v54
	v_cndmask_b32_e32 v55, 0, v186, vcc
	v_cmp_gt_f32_e32 vcc, s33, v40
	v_sub_f32_e32 v53, v53, v55
	v_add_f32_e32 v54, 1.0, v54
	v_cndmask_b32_e64 v55, 0, 32, vcc
	v_ldexp_f32 v55, v40, v55
	v_lshlrev_b32_e32 v42, 16, v42
	v_rcp_f32_e32 v54, v54
	v_log_f32_e32 v55, v55
	v_mul_f32_e32 v42, 0xbfb8aa3b, v42
	v_exp_f32_e32 v42, v42
	v_mul_f32_e32 v44, v54, v44
	v_mul_f32_e32 v54, 0x3f317217, v55
	v_fma_f32 v54, v55, s74, -v54
	v_add_f32_e32 v42, 1.0, v42
	v_fmac_f32_e32 v54, 0x3377d1cf, v55
	v_rcp_f32_e32 v42, v42
	v_fmac_f32_e32 v54, 0x3f317217, v55
	v_cmp_lt_f32_e64 s[14:15], |v55|, s81
	s_waitcnt lgkmcnt(3)
	v_lshlrev_b32_e32 v46, 16, v46
	v_fma_f32 v42, v110, v42, v93
	v_cndmask_b32_e64 v54, v55, v54, s[14:15]
	v_mul_f32_e32 v55, 0xbfb8aa3b, v46
	v_exp_f32_e32 v55, v55
	v_cndmask_b32_e32 v56, 0, v186, vcc
	v_cmp_gt_f32_e32 vcc, s33, v42
	v_sub_f32_e32 v54, v54, v56
	v_add_f32_e32 v55, 1.0, v55
	v_cndmask_b32_e64 v56, 0, 32, vcc
	v_ldexp_f32 v56, v42, v56
	v_lshlrev_b32_e32 v45, 16, v45
	v_rcp_f32_e32 v55, v55
	v_log_f32_e32 v56, v56
	v_mul_f32_e32 v45, 0xbfb8aa3b, v45
	v_exp_f32_e32 v45, v45
	v_mul_f32_e32 v46, v55, v46
	v_mul_f32_e32 v55, 0x3f317217, v56
	v_fma_f32 v55, v56, s74, -v55
	v_add_f32_e32 v45, 1.0, v45
	v_fmac_f32_e32 v55, 0x3377d1cf, v56
	v_rcp_f32_e32 v45, v45
	v_fmac_f32_e32 v55, 0x3f317217, v56
	v_cmp_lt_f32_e64 s[14:15], |v56|, s81
	s_waitcnt lgkmcnt(2)
	v_lshlrev_b32_e32 v48, 16, v48
	v_fma_f32 v45, v110, v45, v93
	v_cndmask_b32_e64 v55, v56, v55, s[14:15]
	v_mul_f32_e32 v56, 0xbfb8aa3b, v48
	v_exp_f32_e32 v56, v56
	v_cndmask_b32_e32 v57, 0, v186, vcc
	v_cmp_gt_f32_e32 vcc, s33, v45
	v_sub_f32_e32 v55, v55, v57
	v_add_f32_e32 v56, 1.0, v56
	v_cndmask_b32_e64 v57, 0, 32, vcc
	v_ldexp_f32 v57, v45, v57
	v_lshlrev_b32_e32 v47, 16, v47
	v_rcp_f32_e32 v56, v56
	v_log_f32_e32 v57, v57
	v_mul_f32_e32 v47, 0xbfb8aa3b, v47
	v_exp_f32_e32 v47, v47
	v_mul_f32_e32 v48, v56, v48
	v_mul_f32_e32 v56, 0x3f317217, v57
	v_fma_f32 v56, v57, s74, -v56
	v_add_f32_e32 v47, 1.0, v47
	v_fmac_f32_e32 v56, 0x3377d1cf, v57
	v_rcp_f32_e32 v47, v47
	v_fmac_f32_e32 v56, 0x3f317217, v57
	v_cmp_lt_f32_e64 s[14:15], |v57|, s81
	s_waitcnt lgkmcnt(1)
	v_lshlrev_b32_e32 v49, 16, v49
	v_fma_f32 v47, v110, v47, v93
	v_cndmask_b32_e64 v56, v57, v56, s[14:15]
	v_mul_f32_e32 v57, 0xbfb8aa3b, v49
	v_exp_f32_e32 v57, v57
	v_cndmask_b32_e32 v58, 0, v186, vcc
	v_cmp_gt_f32_e32 vcc, s33, v47
	v_sub_f32_e32 v56, v56, v58
	v_add_f32_e32 v57, 1.0, v57
	v_cndmask_b32_e64 v58, 0, 32, vcc
	v_ldexp_f32 v58, v47, v58
	v_lshlrev_b32_e32 v50, 16, v50
	v_rcp_f32_e32 v57, v57
	v_log_f32_e32 v58, v58
	v_mul_f32_e32 v50, 0xbfb8aa3b, v50
	v_exp_f32_e32 v50, v50
	v_mul_f32_e32 v49, v57, v49
	v_mul_f32_e32 v57, 0x3f317217, v58
	v_fma_f32 v57, v58, s74, -v57
	v_add_f32_e32 v50, 1.0, v50
	v_fmac_f32_e32 v57, 0x3377d1cf, v58
	v_rcp_f32_e32 v50, v50
	v_fmac_f32_e32 v57, 0x3f317217, v58
	v_cmp_lt_f32_e64 s[14:15], |v58|, s81
	s_waitcnt lgkmcnt(0)
	v_lshlrev_b32_e32 v51, 16, v51
	v_fma_f32 v50, v110, v50, v93
	v_cndmask_b32_e64 v57, v58, v57, s[14:15]
	v_mul_f32_e32 v58, 0xbfb8aa3b, v51
	v_exp_f32_e32 v58, v58
	v_cndmask_b32_e32 v59, 0, v186, vcc
	v_cmp_gt_f32_e32 vcc, s33, v50
	v_sub_f32_e32 v57, v57, v59
	v_add_f32_e32 v58, 1.0, v58
	v_cndmask_b32_e64 v59, 0, 32, vcc
	v_ldexp_f32 v59, v50, v59
	v_rcp_f32_e32 v58, v58
	v_log_f32_e32 v59, v59
	v_cndmask_b32_e32 v76, 0, v186, vcc
	v_mul_f32_e32 v37, 0x3db504f3, v37
	v_mul_f32_e32 v51, v58, v51
	v_mul_f32_e32 v58, 0x3f317217, v59
	v_fma_f32 v58, v59, s74, -v58
	v_fmac_f32_e32 v58, 0x3377d1cf, v59
	v_fmac_f32_e32 v58, 0x3f317217, v59
	v_cmp_lt_f32_e64 s[14:15], |v59|, s81
	v_sub_f32_e32 v10, 1.0, v10
	v_mul_f32_e32 v39, 0x3db504f3, v39
	v_cndmask_b32_e64 v58, v59, v58, s[14:15]
	ds_read_u16 v59, v98 offset:19584
	ds_read_u16 v60, v98 offset:19856
	ds_read_u16 v61, v98 offset:20128
	ds_read_u16 v62, v98 offset:20400
	ds_read_u16 v63, v98 offset:20672
	ds_read_u16 v64, v98 offset:20944
	ds_read_u16 v65, v98 offset:21216
	ds_read_u16 v66, v98 offset:21488
	s_waitcnt lgkmcnt(7)
	v_lshlrev_b32_e32 v59, 16, v59
	v_mul_f32_e32 v59, 0xbfb8aa3b, v59
	v_exp_f32_e32 v59, v59
	ds_read_u16 v67, v98 offset:2176
	ds_read_u16 v68, v98 offset:2448
	ds_read_u16 v69, v98 offset:2720
	ds_read_u16 v70, v98 offset:2992
	ds_read_u16 v71, v98 offset:3264
	ds_read_u16 v72, v98 offset:3536
	ds_read_u16 v73, v98 offset:3808
	ds_read_u16 v74, v98 offset:4080
	s_waitcnt lgkmcnt(7)
	v_lshlrev_b32_e32 v67, 16, v67
	v_mul_f32_e32 v75, 0xbfb8aa3b, v67
	v_add_f32_e32 v59, 1.0, v59
	v_rcp_f32_e32 v59, v59
	v_exp_f32_e32 v75, v75
	v_sub_f32_e32 v58, v58, v76
	v_lshlrev_b32_e32 v60, 16, v60
	v_fma_f32 v59, v110, v59, v93
	v_cmp_gt_f32_e32 vcc, s33, v59
	v_add_f32_e32 v75, 1.0, v75
	v_rcp_f32_e32 v75, v75
	v_cndmask_b32_e64 v76, 0, 32, vcc
	v_ldexp_f32 v76, v59, v76
	v_log_f32_e32 v76, v76
	v_mul_f32_e32 v60, 0xbfb8aa3b, v60
	v_exp_f32_e32 v60, v60
	v_mul_f32_e32 v67, v75, v67
	v_mul_f32_e32 v75, 0x3f317217, v76
	v_fma_f32 v75, v76, s74, -v75
	v_add_f32_e32 v60, 1.0, v60
	v_fmac_f32_e32 v75, 0x3377d1cf, v76
	v_rcp_f32_e32 v60, v60
	v_fmac_f32_e32 v75, 0x3f317217, v76
	v_cmp_lt_f32_e64 s[14:15], |v76|, s81
	s_waitcnt lgkmcnt(6)
; __device__ __forceinline__ float bf2f(bf16 v) { return __uint_as_float(((unsigned)v) << 16); }
; __device__ __forceinline__ float sigmoidf_(float x) { return frcp_(1.0f + __expf(-x)); }
; __device__ __forceinline__ float siluf_(float x) { return x * frcp_(1.0f + __expf(-x)); }
; #define LAS __attribute__((address_space(3)))
; __device__ __forceinline__ void sync_threads() { __syncthreads(); }
; __device__ __forceinline__ void hgrn_pass1(const RecurBufs& rb, const float* lbs_l, int u, int tid, LAS unsigned char* lds) {
;     ...
; #pragma unroll
;         for (int j = 0; j < 16; ++j) { const float q = bf2f(*(const LAS bf16*)(Qt + (16 * jq + j) * PQ + d * 2)), f = bf2f(*(const LAS bf16*)(Kt + (16 * jq + j) * PQ + d * 2));
;             const float fg = lb + (1.f - lb) * sigmoidf_(f);
;             qq[j] = siluf_(q) * 0.08838834764831845f; kk[j] = 1.f - fg; lg[j] = __logf(fg); }
; #pragma unroll
;         for (int j = 1; j < 16; ++j) lg[j] += lg[j - 1];
;         part[jq * 128 + d] = lg[15];
;         sync_threads();
	v_lshlrev_b32_e32 v68, 16, v68
	v_fma_f32 v60, v110, v60, v93
	v_cndmask_b32_e64 v75, v76, v75, s[14:15]
	v_mul_f32_e32 v76, 0xbfb8aa3b, v68
	v_exp_f32_e32 v76, v76
	v_cndmask_b32_e32 v77, 0, v186, vcc
	v_cmp_gt_f32_e32 vcc, s33, v60
	v_sub_f32_e32 v75, v75, v77
	v_add_f32_e32 v76, 1.0, v76
	v_cndmask_b32_e64 v77, 0, 32, vcc
	v_ldexp_f32 v77, v60, v77
	v_lshlrev_b32_e32 v61, 16, v61
	v_rcp_f32_e32 v76, v76
	v_log_f32_e32 v77, v77
	v_mul_f32_e32 v61, 0xbfb8aa3b, v61
	v_exp_f32_e32 v61, v61
	v_mul_f32_e32 v68, v76, v68
	v_mul_f32_e32 v76, 0x3f317217, v77
	v_fma_f32 v76, v77, s74, -v76
	v_add_f32_e32 v61, 1.0, v61
	v_fmac_f32_e32 v76, 0x3377d1cf, v77
	v_rcp_f32_e32 v61, v61
	v_fmac_f32_e32 v76, 0x3f317217, v77
	v_cmp_lt_f32_e64 s[14:15], |v77|, s81
	s_waitcnt lgkmcnt(5)
	v_lshlrev_b32_e32 v69, 16, v69
	v_fma_f32 v61, v110, v61, v93
	v_cndmask_b32_e64 v76, v77, v76, s[14:15]
	v_mul_f32_e32 v77, 0xbfb8aa3b, v69
	v_exp_f32_e32 v77, v77
	v_cndmask_b32_e32 v78, 0, v186, vcc
	v_cmp_gt_f32_e32 vcc, s33, v61
	v_sub_f32_e32 v76, v76, v78
	v_add_f32_e32 v77, 1.0, v77
	v_cndmask_b32_e64 v78, 0, 32, vcc
	v_ldexp_f32 v78, v61, v78
	v_lshlrev_b32_e32 v62, 16, v62
	v_rcp_f32_e32 v77, v77
	v_log_f32_e32 v78, v78
	v_mul_f32_e32 v62, 0xbfb8aa3b, v62
	v_exp_f32_e32 v62, v62
	v_mul_f32_e32 v69, v77, v69
	v_mul_f32_e32 v77, 0x3f317217, v78
	v_fma_f32 v77, v78, s74, -v77
	v_add_f32_e32 v62, 1.0, v62
	v_fmac_f32_e32 v77, 0x3377d1cf, v78
	v_rcp_f32_e32 v62, v62
	v_fmac_f32_e32 v77, 0x3f317217, v78
	v_cmp_lt_f32_e64 s[14:15], |v78|, s81
	s_waitcnt lgkmcnt(4)
	v_lshlrev_b32_e32 v70, 16, v70
	v_fma_f32 v62, v110, v62, v93
	v_cndmask_b32_e64 v77, v78, v77, s[14:15]
	v_mul_f32_e32 v78, 0xbfb8aa3b, v70
	v_exp_f32_e32 v78, v78
	v_cndmask_b32_e32 v79, 0, v186, vcc
	v_cmp_gt_f32_e32 vcc, s33, v62
	v_sub_f32_e32 v77, v77, v79
	v_add_f32_e32 v78, 1.0, v78
	v_cndmask_b32_e64 v79, 0, 32, vcc
	v_ldexp_f32 v79, v62, v79
	v_lshlrev_b32_e32 v63, 16, v63
	v_rcp_f32_e32 v78, v78
	v_log_f32_e32 v79, v79
	v_mul_f32_e32 v63, 0xbfb8aa3b, v63
	v_exp_f32_e32 v63, v63
	v_mul_f32_e32 v70, v78, v70
	v_mul_f32_e32 v78, 0x3f317217, v79
	v_fma_f32 v78, v79, s74, -v78
	v_add_f32_e32 v63, 1.0, v63
	v_fmac_f32_e32 v78, 0x3377d1cf, v79
	v_rcp_f32_e32 v63, v63
	v_fmac_f32_e32 v78, 0x3f317217, v79
	v_cmp_lt_f32_e64 s[14:15], |v79|, s81
	s_waitcnt lgkmcnt(3)
	v_lshlrev_b32_e32 v71, 16, v71
	v_fma_f32 v63, v110, v63, v93
	v_cndmask_b32_e64 v78, v79, v78, s[14:15]
	v_mul_f32_e32 v79, 0xbfb8aa3b, v71
	v_exp_f32_e32 v79, v79
	v_cndmask_b32_e32 v80, 0, v186, vcc
	v_cmp_gt_f32_e32 vcc, s33, v63
	v_sub_f32_e32 v78, v78, v80
	v_add_f32_e32 v79, 1.0, v79
	v_cndmask_b32_e64 v80, 0, 32, vcc
	v_ldexp_f32 v80, v63, v80
	v_lshlrev_b32_e32 v64, 16, v64
	v_rcp_f32_e32 v79, v79
	v_log_f32_e32 v80, v80
	v_mul_f32_e32 v64, 0xbfb8aa3b, v64
	v_exp_f32_e32 v64, v64
	v_mul_f32_e32 v71, v79, v71
	v_mul_f32_e32 v79, 0x3f317217, v80
	v_fma_f32 v79, v80, s74, -v79
	v_add_f32_e32 v64, 1.0, v64
	v_fmac_f32_e32 v79, 0x3377d1cf, v80
	v_rcp_f32_e32 v64, v64
	v_fmac_f32_e32 v79, 0x3f317217, v80
	v_cmp_lt_f32_e64 s[14:15], |v80|, s81
	s_waitcnt lgkmcnt(2)
	v_lshlrev_b32_e32 v72, 16, v72
	v_fma_f32 v64, v110, v64, v93
	v_cndmask_b32_e64 v79, v80, v79, s[14:15]
	v_mul_f32_e32 v80, 0xbfb8aa3b, v72
	v_exp_f32_e32 v80, v80
	v_lshlrev_b32_e32 v65, 16, v65
	v_cndmask_b32_e32 v81, 0, v186, vcc
	v_cmp_gt_f32_e32 vcc, s33, v64
	v_mul_f32_e32 v65, 0xbfb8aa3b, v65
	v_sub_f32_e32 v79, v79, v81
	v_cndmask_b32_e64 v81, 0, 32, vcc
	v_exp_f32_e32 v65, v65
	v_add_f32_e32 v80, 1.0, v80
	v_ldexp_f32 v81, v64, v81
	v_rcp_f32_e32 v80, v80
	v_log_f32_e32 v81, v81
	v_add_f32_e32 v65, 1.0, v65
	s_waitcnt lgkmcnt(1)
	v_lshlrev_b32_e32 v73, 16, v73
	v_rcp_f32_e32 v65, v65
	v_mul_f32_e32 v72, v80, v72
	v_mul_f32_e32 v80, 0x3f317217, v81
	v_mul_f32_e32 v82, 0xbfb8aa3b, v73
	v_fma_f32 v80, v81, s74, -v80
	v_exp_f32_e32 v82, v82
	v_fmac_f32_e32 v80, 0x3377d1cf, v81
	v_fmac_f32_e32 v80, 0x3f317217, v81
	v_cmp_lt_f32_e64 s[14:15], |v81|, s81
	v_fma_f32 v65, v110, v65, v93
	v_lshlrev_b32_e32 v66, 16, v66
	v_cndmask_b32_e64 v80, v81, v80, s[14:15]
	v_cmp_gt_f32_e64 s[14:15], s33, v65
	v_mul_f32_e32 v66, 0xbfb8aa3b, v66
	v_add_f32_e32 v81, 1.0, v82
	v_cndmask_b32_e64 v82, 0, 32, s[14:15]
	v_exp_f32_e32 v66, v66
	v_ldexp_f32 v82, v65, v82
	v_rcp_f32_e32 v81, v81
	v_log_f32_e32 v82, v82
	v_add_f32_e32 v66, 1.0, v66
	v_rcp_f32_e32 v66, v66
	v_mul_f32_e32 v73, v81, v73
	v_mul_f32_e32 v81, 0x3f317217, v82
	v_fma_f32 v81, v82, s74, -v81
	v_fmac_f32_e32 v81, 0x3377d1cf, v82
	v_cndmask_b32_e32 v83, 0, v186, vcc
	v_fmac_f32_e32 v81, 0x3f317217, v82
	v_cmp_lt_f32_e64 vcc, |v82|, s81
	v_fmac_f32_e32 v93, v110, v66
	v_sub_f32_e32 v80, v80, v83
	v_cndmask_b32_e32 v81, v82, v81, vcc
	v_cmp_gt_f32_e32 vcc, s33, v93
	v_cndmask_b32_e64 v82, 0, v186, s[14:15]
	v_sub_f32_e32 v81, v81, v82
	v_cndmask_b32_e64 v83, 0, 32, vcc
	v_ldexp_f32 v83, v93, v83
	v_log_f32_e32 v83, v83
	s_waitcnt lgkmcnt(0)
	v_lshlrev_b32_e32 v74, 16, v74
	v_mul_f32_e32 v66, 0xbfb8aa3b, v74
	v_exp_f32_e32 v66, v66
	v_mul_f32_e32 v82, 0x3f317217, v83
	v_fma_f32 v82, v83, s74, -v82
	v_fmac_f32_e32 v82, 0x3377d1cf, v83
	v_fmac_f32_e32 v82, 0x3f317217, v83
	v_cmp_lt_f32_e64 s[14:15], |v83|, s81
	v_add_f32_e32 v66, 1.0, v66
	v_rcp_f32_e32 v66, v66
	v_cndmask_b32_e64 v82, v83, v82, s[14:15]
	v_cndmask_b32_e32 v83, 0, v186, vcc
	v_sub_f32_e32 v82, v82, v83
	v_add_f32_e32 v83, v43, v52
	v_add_f32_e32 v84, v83, v53
	v_add_f32_e32 v85, v84, v54
	v_add_f32_e32 v86, v85, v55
	v_add_f32_e32 v56, v86, v56
	v_add_f32_e32 v57, v56, v57
	v_add_f32_e32 v58, v57, v58
	v_add_f32_e32 v75, v58, v75
	v_add_f32_e32 v76, v75, v76
	v_add_f32_e32 v77, v76, v77
	v_add_f32_e32 v78, v77, v78
	v_add_f32_e32 v79, v78, v79
	v_add_f32_e32 v80, v79, v80
	v_add_f32_e32 v81, v80, v81
	v_add_f32_e32 v82, v81, v82
	ds_write_b32 v109, v82 offset:52224
	s_waitcnt lgkmcnt(0)
	s_barrier
; __device__ __forceinline__ bf16 f2bf(float f) { return (bf16)pk2(f, f); }
; __device__ __forceinline__ float frcp_(float x) { return __builtin_amdgcn_rcpf(x); }
; #define LAS __attribute__((address_space(3)))
; __device__ __forceinline__ void hgrn_pass1(const RecurBufs& rb, const float* lbs_l, int u, int tid, LAS unsigned char* lds) {
;     ...
;         const float p0 = part[d], p1 = part[128 + d], p2 = part[256 + d], p3 = part[384 + d];
;         const float off = (jq > 0 ? p0 : 0.f) + (jq > 1 ? p1 : 0.f) + (jq > 2 ? p2 : 0.f);
;         const float bref = p0 + p1, bend = (p0 + p1) + (p2 + p3);
; #pragma unroll
;         for (int j = 0; j < 16; ++j) { const float e1 = __expf(fminf(fmaxf(off + lg[j] - bref, -80.f), 80.f));
;             *(LAS bf16*)(Qt + (16 * jq + j) * PQ + d * 2) = f2bf(qq[j] * e1); *(LAS bf16*)(Kt + (16 * jq + j) * PQ + d * 2) = f2bf(kk[j] * frcp_(e1)); }
	ds_read2st64_b32 v[52:53], v111 offset0:204 offset1:206
	ds_read2st64_b32 v[54:55], v111 offset0:208 offset1:210
	v_mul_f32_e32 v66, v66, v74
	v_sub_f32_e32 v36, 1.0, v36
	v_mul_f32_e32 v41, 0x3db504f3, v41
	s_waitcnt lgkmcnt(1)
	v_cndmask_b32_e64 v74, 0, v52, s[10:11]
	v_cndmask_b32_e64 v87, 0, v53, s[12:13]
	v_add_f32_e32 v74, v74, v87
	s_waitcnt lgkmcnt(0)
	v_cndmask_b32_e64 v87, 0, v54, s[8:9]
	v_add_f32_e32 v74, v74, v87
	v_add_f32_e32 v52, v52, v53
	v_add_f32_e32 v43, v43, v74
	v_sub_f32_e32 v43, v43, v52
	v_med3_f32 v43, v43, s86, v187
	v_mul_f32_e32 v43, 0x3fb8aa3b, v43
	v_exp_f32_e32 v43, v43
	v_sub_f32_e32 v38, 1.0, v38
	v_mul_f32_e32 v44, 0x3db504f3, v44
	v_sub_f32_e32 v40, 1.0, v40
	v_mul_f32_e32 v37, v37, v43
	v_cvt_pk_bf16_f32 v37, v37, v37
	ds_write_b16 v98, v37
	v_rcp_f32_e32 v37, v43
	v_add_f32_e32 v43, v83, v74
	v_sub_f32_e32 v43, v43, v52
	v_med3_f32 v43, v43, s86, v187
	v_mul_f32_e32 v43, 0x3fb8aa3b, v43
	v_exp_f32_e32 v43, v43
	v_mul_f32_e32 v10, v10, v37
	v_cvt_pk_bf16_f32 v10, v10, v10
	ds_write_b16 v98, v10 offset:17408
	v_mul_f32_e32 v10, v39, v43
	v_add_f32_e32 v37, v84, v74
	v_cvt_pk_bf16_f32 v10, v10, v10
	v_sub_f32_e32 v37, v37, v52
	ds_write_b16 v98, v10 offset:272
	v_rcp_f32_e32 v10, v43
	v_med3_f32 v37, v37, s86, v187
	v_mul_f32_e32 v37, 0x3fb8aa3b, v37
	v_exp_f32_e32 v37, v37
	v_mul_f32_e32 v10, v36, v10
	v_cvt_pk_bf16_f32 v10, v10, v10
	ds_write_b16 v98, v10 offset:17680
	v_mul_f32_e32 v10, v41, v37
	v_add_f32_e32 v36, v85, v74
	v_cvt_pk_bf16_f32 v10, v10, v10
	v_sub_f32_e32 v36, v36, v52
	ds_write_b16 v98, v10 offset:544
	v_rcp_f32_e32 v10, v37
	v_med3_f32 v36, v36, s86, v187
	v_mul_f32_e32 v36, 0x3fb8aa3b, v36
	v_exp_f32_e32 v36, v36
	v_mul_f32_e32 v10, v38, v10
	v_cvt_pk_bf16_f32 v10, v10, v10
	ds_write_b16 v98, v10 offset:17952
	v_mul_f32_e32 v10, v44, v36
	v_cvt_pk_bf16_f32 v10, v10, v10
	ds_write_b16 v98, v10 offset:816
	v_rcp_f32_e32 v10, v36
	v_add_f32_e32 v36, v86, v74
	v_sub_f32_e32 v36, v36, v52
	v_med3_f32 v36, v36, s86, v187
	v_mul_f32_e32 v36, 0x3fb8aa3b, v36
	v_exp_f32_e32 v36, v36
	v_mul_f32_e32 v10, v40, v10
	v_mul_f32_e32 v46, 0x3db504f3, v46
	v_cvt_pk_bf16_f32 v10, v10, v10
	ds_write_b16 v98, v10 offset:18224
	v_mul_f32_e32 v10, v46, v36
	v_cvt_pk_bf16_f32 v10, v10, v10
	ds_write_b16 v98, v10 offset:1088
	v_rcp_f32_e32 v10, v36
	v_add_f32_e32 v36, v56, v74
	v_sub_f32_e32 v36, v36, v52
	v_med3_f32 v36, v36, s86, v187
	v_mul_f32_e32 v36, 0x3fb8aa3b, v36
	v_exp_f32_e32 v36, v36
	v_sub_f32_e32 v42, 1.0, v42
	v_mul_f32_e32 v10, v42, v10
	v_mul_f32_e32 v48, 0x3db504f3, v48
	v_cvt_pk_bf16_f32 v10, v10, v10
	ds_write_b16 v98, v10 offset:18496
	v_mul_f32_e32 v10, v48, v36
	v_cvt_pk_bf16_f32 v10, v10, v10
	ds_write_b16 v98, v10 offset:1360
	v_rcp_f32_e32 v10, v36
	v_add_f32_e32 v36, v57, v74
	v_sub_f32_e32 v36, v36, v52
	v_med3_f32 v36, v36, s86, v187
	v_mul_f32_e32 v36, 0x3fb8aa3b, v36
	v_exp_f32_e32 v36, v36
	v_sub_f32_e32 v45, 1.0, v45
	v_mul_f32_e32 v10, v45, v10
	v_mul_f32_e32 v49, 0x3db504f3, v49
	v_cvt_pk_bf16_f32 v10, v10, v10
	ds_write_b16 v98, v10 offset:18768
	v_mul_f32_e32 v10, v49, v36
	v_cvt_pk_bf16_f32 v10, v10, v10
	ds_write_b16 v98, v10 offset:1632
	v_rcp_f32_e32 v10, v36
	v_add_f32_e32 v36, v58, v74
	v_sub_f32_e32 v36, v36, v52
	v_med3_f32 v36, v36, s86, v187
	v_mul_f32_e32 v36, 0x3fb8aa3b, v36
	v_exp_f32_e32 v36, v36
	v_sub_f32_e32 v47, 1.0, v47
	v_mul_f32_e32 v10, v47, v10
	v_mul_f32_e32 v51, 0x3db504f3, v51
	v_cvt_pk_bf16_f32 v10, v10, v10
	ds_write_b16 v98, v10 offset:19040
	v_mul_f32_e32 v10, v51, v36
	v_cvt_pk_bf16_f32 v10, v10, v10
	ds_write_b16 v98, v10 offset:1904
	v_rcp_f32_e32 v10, v36
	v_add_f32_e32 v36, v75, v74
	v_sub_f32_e32 v36, v36, v52
	v_med3_f32 v36, v36, s86, v187
	v_mul_f32_e32 v36, 0x3fb8aa3b, v36
	v_exp_f32_e32 v36, v36
	v_sub_f32_e32 v50, 1.0, v50
	v_mul_f32_e32 v10, v50, v10
	v_mul_f32_e32 v67, 0x3db504f3, v67
	v_cvt_pk_bf16_f32 v10, v10, v10
	ds_write_b16 v98, v10 offset:19312
	v_mul_f32_e32 v10, v67, v36
	v_cvt_pk_bf16_f32 v10, v10, v10
	ds_write_b16 v98, v10 offset:2176
	v_rcp_f32_e32 v10, v36
	v_add_f32_e32 v36, v76, v74
	v_sub_f32_e32 v36, v36, v52
	v_med3_f32 v36, v36, s86, v187
	v_mul_f32_e32 v36, 0x3fb8aa3b, v36
	v_exp_f32_e32 v36, v36
	v_sub_f32_e32 v59, 1.0, v59
	v_mul_f32_e32 v10, v59, v10
	v_mul_f32_e32 v68, 0x3db504f3, v68
	v_cvt_pk_bf16_f32 v10, v10, v10
	ds_write_b16 v98, v10 offset:19584
	v_mul_f32_e32 v10, v68, v36
	v_cvt_pk_bf16_f32 v10, v10, v10
	ds_write_b16 v98, v10 offset:2448
	v_rcp_f32_e32 v10, v36
	v_add_f32_e32 v36, v77, v74
	v_sub_f32_e32 v36, v36, v52
	v_med3_f32 v36, v36, s86, v187
	v_mul_f32_e32 v36, 0x3fb8aa3b, v36
	v_exp_f32_e32 v36, v36
	v_sub_f32_e32 v60, 1.0, v60
	v_mul_f32_e32 v10, v60, v10
	v_mul_f32_e32 v69, 0x3db504f3, v69
	v_cvt_pk_bf16_f32 v10, v10, v10
	ds_write_b16 v98, v10 offset:19856
	v_mul_f32_e32 v10, v69, v36
	v_cvt_pk_bf16_f32 v10, v10, v10
	ds_write_b16 v98, v10 offset:2720
	v_rcp_f32_e32 v10, v36
	v_add_f32_e32 v36, v78, v74
	v_sub_f32_e32 v36, v36, v52
	v_med3_f32 v36, v36, s86, v187
	v_mul_f32_e32 v36, 0x3fb8aa3b, v36
	v_exp_f32_e32 v36, v36
	v_sub_f32_e32 v61, 1.0, v61
	v_mul_f32_e32 v10, v61, v10
	v_mul_f32_e32 v70, 0x3db504f3, v70
	v_cvt_pk_bf16_f32 v10, v10, v10
	ds_write_b16 v98, v10 offset:20128
	v_mul_f32_e32 v10, v70, v36
	v_cvt_pk_bf16_f32 v10, v10, v10
	ds_write_b16 v98, v10 offset:2992
	v_rcp_f32_e32 v10, v36
	v_add_f32_e32 v36, v79, v74
	v_sub_f32_e32 v36, v36, v52
	v_med3_f32 v36, v36, s86, v187
	v_mul_f32_e32 v36, 0x3fb8aa3b, v36
	v_exp_f32_e32 v36, v36
	v_sub_f32_e32 v62, 1.0, v62
	v_mul_f32_e32 v10, v62, v10
	v_mul_f32_e32 v71, 0x3db504f3, v71
	v_cvt_pk_bf16_f32 v10, v10, v10
; __device__ __forceinline__ bf16 f2bf(float f) { return (bf16)pk2(f, f); }
; __device__ __forceinline__ float frcp_(float x) { return __builtin_amdgcn_rcpf(x); }
; #define LAS __attribute__((address_space(3)))
; __device__ __forceinline__ void sync_threads() { __syncthreads(); }
; __device__ __forceinline__ void hgrn_pass1(const RecurBufs& rb, const float* lbs_l, int u, int tid, LAS unsigned char* lds) {
;     ...
;         for (int j = 0; j < 16; ++j) { const float e1 = __expf(fminf(fmaxf(off + lg[j] - bref, -80.f), 80.f));
;             *(LAS bf16*)(Qt + (16 * jq + j) * PQ + d * 2) = f2bf(qq[j] * e1); *(LAS bf16*)(Kt + (16 * jq + j) * PQ + d * 2) = f2bf(kk[j] * frcp_(e1)); }
;         if (jq == 0) { const float eref = __expf(bref), esc = __expf(bend - bref), edc = __expf(bend);
;             float* cvp = rb.cv + ((size_t)((b * 8 + h) * 32 + seg * NCH + ch) * 3) * 128;
;             cvp[d] = eref; cvp[128 + d] = esc; cvp[256 + d] = edc; vec[128 + d] = esc; vec[256 + d] = edc; }
;         dprod *= __expf(bend);
;         sync_threads();
;         *(v4u*)gq = *(const LAS v4u*)(Qt + sr * PQ + sc16 * 16); *(v4u*)(gq + 32 * (size_t)LDP) = *(const LAS v4u*)(Qt + (sr + 32) * PQ + sc16 * 16);
;         *(v4u*)(gq + PC_F) = *(const LAS v4u*)(Kt + sr * PQ + sc16 * 16); *(v4u*)(gq + 32 * (size_t)LDP + PC_F) = *(const LAS v4u*)(Kt + (sr + 32) * PQ + sc16 * 16);
;         hgrn_state_update(S, Kt, V, vec + 128, vec + 256, w, lane);
	ds_write_b16 v98, v10 offset:20400
	v_mul_f32_e32 v10, v71, v36
	v_cvt_pk_bf16_f32 v10, v10, v10
	ds_write_b16 v98, v10 offset:3264
	v_rcp_f32_e32 v10, v36
	v_add_f32_e32 v36, v80, v74
	v_sub_f32_e32 v36, v36, v52
	v_med3_f32 v36, v36, s86, v187
	v_mul_f32_e32 v36, 0x3fb8aa3b, v36
	v_exp_f32_e32 v36, v36
	v_sub_f32_e32 v63, 1.0, v63
	v_mul_f32_e32 v10, v63, v10
	v_mul_f32_e32 v72, 0x3db504f3, v72
	v_cvt_pk_bf16_f32 v10, v10, v10
	ds_write_b16 v98, v10 offset:20672
	v_mul_f32_e32 v10, v72, v36
	v_cvt_pk_bf16_f32 v10, v10, v10
	ds_write_b16 v98, v10 offset:3536
	v_rcp_f32_e32 v10, v36
	v_add_f32_e32 v36, v74, v81
	v_sub_f32_e32 v36, v36, v52
	v_med3_f32 v36, v36, s86, v187
	v_mul_f32_e32 v36, 0x3fb8aa3b, v36
	v_exp_f32_e32 v36, v36
	v_sub_f32_e32 v64, 1.0, v64
	v_mul_f32_e32 v10, v64, v10
	v_mul_f32_e32 v73, 0x3db504f3, v73
	v_cvt_pk_bf16_f32 v10, v10, v10
	ds_write_b16 v98, v10 offset:20944
	v_mul_f32_e32 v10, v73, v36
	v_cvt_pk_bf16_f32 v10, v10, v10
	ds_write_b16 v98, v10 offset:3808
	v_rcp_f32_e32 v10, v36
	v_add_f32_e32 v36, v74, v82
	v_sub_f32_e32 v36, v36, v52
	v_med3_f32 v36, v36, s86, v187
	v_mul_f32_e32 v36, 0x3fb8aa3b, v36
	v_exp_f32_e32 v36, v36
	v_sub_f32_e32 v65, 1.0, v65
	v_mul_f32_e32 v10, v65, v10
	v_mul_f32_e32 v53, 0x3db504f3, v66
	v_cvt_pk_bf16_f32 v10, v10, v10
	ds_write_b16 v98, v10 offset:21216
	v_mul_f32_e32 v10, v53, v36
	v_add_f32_e32 v54, v54, v55
	v_cvt_pk_bf16_f32 v10, v10, v10
	ds_write_b16 v98, v10 offset:4080
	v_add_f32_e32 v10, v52, v54
	v_rcp_f32_e32 v37, v36
	v_mul_f32_e32 v36, 0x3fb8aa3b, v10
	v_exp_f32_e32 v68, v36
	v_sub_f32_e32 v66, 1.0, v93
	v_mul_f32_e32 v37, v66, v37
	v_cvt_pk_bf16_f32 v37, v37, v37
	ds_write_b16 v98, v37 offset:21488
	s_and_saveexec_b64 s[2:3], s[6:7]
	s_xor_b64 s[2:3], exec, s[2:3]
	v_exp_f32_e32 v68, v36
	s_andn2_saveexec_b64 s[2:3], s[2:3]
	s_cbranch_execz .LBB0_401
	s_lshl_b32 s6, s19, 3
	s_or_b32 s6, s28, s6
	v_sub_f32_e32 v10, v10, v52
	v_mul_f32_e32 v36, 0x3fb8aa3b, v52
	v_mul_f32_e32 v10, 0x3fb8aa3b, v10
	s_or_b32 s6, s6, 7
	v_exp_f32_e32 v38, v36
	v_exp_f32_e32 v39, v10
	s_mul_hi_i32 s7, s6, 0x600
	s_mulk_i32 s6, 0x600
	v_readlane_b32 s8, v255, 39
	s_add_u32 s6, s8, s6
	v_readlane_b32 s8, v255, 40
	s_addc_u32 s7, s8, s7
	v_lshlrev_b32_e32 v10, 2, v92
	v_lshl_add_u64 v[36:37], s[6:7], 0, v[10:11]
	global_store_dword v[36:37], v38, off
	global_store_dword v[36:37], v39, off offset:512
	global_store_dword v[36:37], v68, off offset:1024
	ds_write2st64_b32 v111, v39, v68 offset0:214 offset1:216
.LBB0_401:
	s_or_b64 exec, exec, s[2:3]
	s_lshl_b32 s64, s17, 1
	v_lshl_add_u64 v[36:37], v[94:95], 0, s[64:65]
	v_lshlrev_b32_e32 v10, 1, v96
	v_lshl_add_u64 v[40:41], v[36:37], 0, v[10:11]
	s_waitcnt lgkmcnt(0)
	s_barrier
	ds_read_b128 v[36:39], v108
	v_add_co_u32_e32 v44, vcc, 0xab8000, v40
	s_mov_b64 s[2:3], 0xab8000
	s_nop 0
	v_addc_co_u32_e32 v45, vcc, 0, v41, vcc
	s_waitcnt lgkmcnt(0)
	global_store_dwordx4 v[44:45], v[36:39], off
	ds_read_b128 v[36:39], v108 offset:8704
	v_lshl_add_u64 v[42:43], v[40:41], 0, s[2:3]
	v_add_co_u32_e32 v40, vcc, 0xb7c000, v40
	s_nop 1
	v_addc_co_u32_e32 v41, vcc, 0, v41, vcc
	s_waitcnt lgkmcnt(0)
	global_store_dwordx4 v[40:41], v[36:39], off
	ds_read_b128 v[36:39], v108 offset:17408
	s_waitcnt lgkmcnt(0)
	global_store_dwordx4 v[42:43], v[36:39], off offset:2048
	ds_read_b128 v[36:39], v108 offset:26112
	s_waitcnt lgkmcnt(0)
	global_store_dwordx4 v[40:41], v[36:39], off offset:2048
	ds_read_b128 v[36:39], v107 offset:55296
	s_waitcnt lgkmcnt(0)
	v_pk_mul_f32 v[62:63], v[6:7], v[38:39]
	v_pk_mul_f32 v[60:61], v[4:5], v[36:37]
	ds_read_b32 v10, v106 offset:54784
	ds_read_b64_tr_b16 v[4:5], v99 offset:17408
	ds_read_b64_tr_b16 v[6:7], v99 offset:18496
	v_pk_mul_f32 v[58:59], v[14:15], v[38:39]
	v_pk_mul_f32 v[56:57], v[12:13], v[36:37]
	v_pk_mul_f32 v[66:67], v[2:3], v[38:39]
	s_waitcnt lgkmcnt(0)
	v_lshlrev_b32_e32 v12, 16, v4
	v_and_b32_e32 v4, 0xffff0000, v4
	v_lshlrev_b32_e32 v13, 16, v5
	v_and_b32_e32 v5, 0xffff0000, v5
	v_lshlrev_b32_e32 v14, 16, v6
	v_and_b32_e32 v6, 0xffff0000, v6
	v_lshlrev_b32_e32 v15, 16, v7
	v_and_b32_e32 v7, 0xffff0000, v7
	v_mul_f32_e32 v12, v10, v12
	v_mul_f32_e32 v4, v10, v4
	v_mul_f32_e32 v13, v10, v13
	v_mul_f32_e32 v5, v10, v5
	v_mul_f32_e32 v14, v10, v14
	v_mul_f32_e32 v6, v10, v6
	v_mul_f32_e32 v15, v10, v15
	v_mul_f32_e32 v7, v10, v7
	v_cvt_pk_bf16_f32 v12, v12, v12
	v_cvt_pk_bf16_f32 v4, v4, v4
	v_cvt_pk_bf16_f32 v13, v13, v13
	v_cvt_pk_bf16_f32 v5, v5, v5
	v_cvt_pk_bf16_f32 v14, v14, v14
	v_cvt_pk_bf16_f32 v6, v6, v6
	v_cvt_pk_bf16_f32 v15, v15, v15
	v_cvt_pk_bf16_f32 v7, v7, v7
	v_pk_mul_f32 v[64:65], v[0:1], v[36:37]
	v_pk_mul_f32 v[54:55], v[18:19], v[38:39]
	v_pk_mul_f32 v[52:53], v[16:17], v[36:37]
	v_pk_mul_f32 v[50:51], v[22:23], v[38:39]
	v_pk_mul_f32 v[48:49], v[20:21], v[36:37]
	v_pk_mul_f32 v[46:47], v[26:27], v[38:39]
	v_pk_mul_f32 v[44:45], v[24:25], v[36:37]
	v_pk_mul_f32 v[42:43], v[30:31], v[38:39]
	v_pk_mul_f32 v[40:41], v[28:29], v[36:37]
	v_pk_mul_f32 v[2:3], v[34:35], v[38:39]
	v_pk_mul_f32 v[0:1], v[32:33], v[36:37]
	v_perm_b32 v39, v7, v15, s75
	v_perm_b32 v38, v6, v14, s75
	v_perm_b32 v37, v5, v13, s75
	v_perm_b32 v36, v4, v12, s75
	ds_read_b64_tr_b16 v[6:7], v9 offset:35904
	ds_read_b64_tr_b16 v[4:5], v9 offset:34816
	ds_read_b64_tr_b16 v[12:13], v9 offset:34848
	ds_read_b64_tr_b16 v[14:15], v9 offset:35936
	ds_read_b64_tr_b16 v[16:17], v9 offset:34880
	ds_read_b64_tr_b16 v[18:19], v9 offset:35968
	ds_read_b64_tr_b16 v[20:21], v9 offset:34912
	ds_read_b64_tr_b16 v[22:23], v9 offset:36000
	ds_read_b64_tr_b16 v[24:25], v9 offset:34944
	ds_read_b64_tr_b16 v[26:27], v9 offset:36032
	ds_read_b64_tr_b16 v[28:29], v9 offset:34976
	ds_read_b64_tr_b16 v[30:31], v9 offset:36064
	ds_read_b64_tr_b16 v[32:33], v9 offset:35008
	ds_read_b64_tr_b16 v[34:35], v9 offset:36096
	s_waitcnt lgkmcnt(0)
; __device__ __forceinline__ f32x4 mfma16(bf16x8 a, bf16x8 b, f32x4 c) { return __builtin_amdgcn_mfma_f32_16x16x32_bf16(a, b, c, 0, 0, 0); }
; #define SCHED_FENCE() do {} while (0)
; #define LAUNDER_PTR(p) do {} while (0)
; #define LAUNDER_PTR(p) asm volatile("" : "+v"(p))
; #define SCHED_FENCE() __builtin_amdgcn_sched_barrier(0)
; __device__ __forceinline__ void hgrn_state_update(f32x4 (&S)[8], LAS unsigned char* Kt, LAS unsigned char* V, const LAS float* escale, const LAS float* edec, int w, int lane) {
;     ...
;     for (int et = 0; et < 8; ++et) S[et] = S[et] * dc;
;     const float es = escale[16 * w + c];
; #pragma unroll
;     for (int ks = 0; ks < 2; ++ks) {
;         const bf16x8 A = scale_frag(frag_tr(Kt, PQ, 32 * ks + 8 * g, 32 * ks + 8 * g + 4, 16 * w, lane), es);
; #pragma unroll
;         for (int et = 0; et < 8; ++et) { const bf16x8 B = frag_tr(V, PQ, 32 * ks + 8 * g, 32 * ks + 8 * g + 4, 16 * et, lane); S[et] = mfma16(A, B, S[et]); }
;         SCHED_FENCE();
;     }
; }
; __device__ __forceinline__ void hgrn_pass1(const RecurBufs& rb, const float* lbs_l, int u, int tid, LAS unsigned char* lds) {
;     ...
;     float* sp = rb.sseg + (size_t)u * 16384 + tid * 4;
; #pragma unroll
;     for (int et = 0; et < 8; ++et) { LAUNDER_PTR(sp); *(f32x4*)sp = S[et]; sp += 2048; }
;     if (jq == 0) rb.dseg[u * 128 + d] = dprod;
	v_mfma_f32_16x16x32_bf16 v[32:35], v[36:39], v[32:35], v[40:43]
	s_nop 2
	ds_read_b64_tr_b16 v[40:41], v9 offset:35040
	ds_read_b64_tr_b16 v[42:43], v9 offset:36128
	v_mfma_f32_16x16x32_bf16 v[4:7], v[36:39], v[4:7], v[64:67]
	v_mfma_f32_16x16x32_bf16 v[12:15], v[36:39], v[12:15], v[60:63]
	v_mfma_f32_16x16x32_bf16 v[16:19], v[36:39], v[16:19], v[56:59]
	v_mfma_f32_16x16x32_bf16 v[20:23], v[36:39], v[20:23], v[52:55]
	v_mfma_f32_16x16x32_bf16 v[24:27], v[36:39], v[24:27], v[48:51]
	v_mfma_f32_16x16x32_bf16 v[28:31], v[36:39], v[28:31], v[44:47]
	s_waitcnt lgkmcnt(0)
	v_mfma_f32_16x16x32_bf16 v[0:3], v[36:39], v[40:43], v[0:3]
	ds_read_b64_tr_b16 v[36:37], v99 offset:26112
	ds_read_b64_tr_b16 v[38:39], v99 offset:27200
	s_waitcnt lgkmcnt(0)
	v_lshlrev_b32_e32 v40, 16, v36
	v_and_b32_e32 v36, 0xffff0000, v36
	v_lshlrev_b32_e32 v41, 16, v37
	v_and_b32_e32 v37, 0xffff0000, v37
	v_lshlrev_b32_e32 v42, 16, v38
	v_and_b32_e32 v38, 0xffff0000, v38
	v_mul_f32_e32 v36, v10, v36
	v_mul_f32_e32 v37, v10, v37
	v_mul_f32_e32 v38, v10, v38
	v_lshlrev_b32_e32 v43, 16, v39
	v_and_b32_e32 v39, 0xffff0000, v39
	v_mul_f32_e32 v40, v10, v40
	v_cvt_pk_bf16_f32 v36, v36, v36
	v_mul_f32_e32 v41, v10, v41
	v_cvt_pk_bf16_f32 v37, v37, v37
	v_mul_f32_e32 v42, v10, v42
	v_cvt_pk_bf16_f32 v38, v38, v38
	v_mul_f32_e32 v43, v10, v43
	v_mul_f32_e32 v10, v10, v39
	v_cvt_pk_bf16_f32 v40, v40, v40
	v_cvt_pk_bf16_f32 v41, v41, v41
	v_cvt_pk_bf16_f32 v42, v42, v42
	v_cvt_pk_bf16_f32 v43, v43, v43
	v_cvt_pk_bf16_f32 v10, v10, v10
	s_nop 0
	v_perm_b32 v39, v10, v43, s75
	v_perm_b32 v38, v38, v42, s75
	v_perm_b32 v37, v37, v41, s75
	v_perm_b32 v36, v36, v40, s75
	ds_read_b64_tr_b16 v[42:43], v9 offset:44608
	ds_read_b64_tr_b16 v[40:41], v9 offset:43520
	ds_read_b64_tr_b16 v[44:45], v9 offset:43552
	s_waitcnt lgkmcnt(0)
	v_mfma_f32_16x16x32_bf16 v[4:7], v[36:39], v[40:43], v[4:7]
	ds_read_b64_tr_b16 v[46:47], v9 offset:44640
	ds_read_b64_tr_b16 v[40:41], v9 offset:43584
	ds_read_b64_tr_b16 v[42:43], v9 offset:44672
	s_waitcnt lgkmcnt(0)
	v_mfma_f32_16x16x32_bf16 v[16:19], v[36:39], v[40:43], v[16:19]
	ds_read_b64_tr_b16 v[40:41], v9 offset:43616
	ds_read_b64_tr_b16 v[42:43], v9 offset:44704
	s_waitcnt lgkmcnt(0)
	v_mfma_f32_16x16x32_bf16 v[20:23], v[36:39], v[40:43], v[20:23]
	ds_read_b64_tr_b16 v[40:41], v9 offset:43648
	ds_read_b64_tr_b16 v[42:43], v9 offset:44736
	s_waitcnt lgkmcnt(0)
	v_mfma_f32_16x16x32_bf16 v[24:27], v[36:39], v[40:43], v[24:27]
	ds_read_b64_tr_b16 v[40:41], v9 offset:43680
	ds_read_b64_tr_b16 v[42:43], v9 offset:44768
	s_waitcnt lgkmcnt(0)
	v_mfma_f32_16x16x32_bf16 v[28:31], v[36:39], v[40:43], v[28:31]
	ds_read_b64_tr_b16 v[40:41], v9 offset:43712
	ds_read_b64_tr_b16 v[42:43], v9 offset:44800
	s_waitcnt lgkmcnt(0)
	v_mfma_f32_16x16x32_bf16 v[32:35], v[36:39], v[40:43], v[32:35]
	ds_read_b64_tr_b16 v[40:41], v9 offset:43744
	ds_read_b64_tr_b16 v[42:43], v9 offset:44832
	v_mfma_f32_16x16x32_bf16 v[12:15], v[36:39], v[44:47], v[12:15]
	s_waitcnt lgkmcnt(0)
	v_mfma_f32_16x16x32_bf16 v[0:3], v[36:39], v[40:43], v[0:3]
	s_ashr_i32 s17, s16, 31
	s_lshl_b64 s[2:3], s[16:17], 16
	s_add_u32 s2, s0, s2
	s_addc_u32 s3, s1, s3
	v_ashrrev_i32_e32 v9, 31, v8
	v_lshl_add_u64 v[8:9], v[8:9], 2, s[2:3]
	s_barrier
	global_store_dwordx4 v[8:9], v[4:7], off
	s_nop 1
	v_lshl_add_u64 v[4:5], v[8:9], 0, s[44:45]
	global_store_dwordx4 v[4:5], v[12:15], off
	v_lshl_add_u64 v[4:5], v[4:5], 0, s[44:45]
	global_store_dwordx4 v[4:5], v[16:19], off
	v_lshl_add_u64 v[4:5], v[4:5], 0, s[44:45]
	global_store_dwordx4 v[4:5], v[20:23], off
	v_lshl_add_u64 v[4:5], v[4:5], 0, s[44:45]
	global_store_dwordx4 v[4:5], v[24:27], off
	v_lshl_add_u64 v[4:5], v[4:5], 0, s[44:45]
	global_store_dwordx4 v[4:5], v[28:31], off
	v_lshl_add_u64 v[4:5], v[4:5], 0, s[44:45]
	global_store_dwordx4 v[4:5], v[32:35], off
	v_lshl_add_u64 v[4:5], v[4:5], 0, s[44:45]
	global_store_dwordx4 v[4:5], v[0:3], off
	s_and_saveexec_b64 s[2:3], s[4:5]
	s_cbranch_execz .LBB0_390
	v_lshl_or_b32 v0, s16, 7, v97
	v_readlane_b32 s4, v255, 41
	v_ashrrev_i32_e32 v1, 31, v0
	v_readlane_b32 s5, v255, 42
	v_mul_f32_e32 v2, v101, v68
	s_nop 0
	v_lshl_add_u64 v[0:1], v[0:1], 2, s[4:5]
	global_store_dword v[0:1], v2, off
	s_branch .LBB0_390
.LBB0_403:
	v_readlane_b32 s2, v255, 34
	v_readlane_b32 s4, v253, 15
	v_readlane_b32 s3, v255, 35
	v_readlane_b32 s5, v253, 16
	s_lshl_b64 s[2:3], s[2:3], 26
	v_readlane_b32 s8, v253, 19
	v_readlane_b32 s16, v253, 27
	v_readlane_b32 s4, v254, 11
	v_readlane_b32 s9, v253, 20
	v_readlane_b32 s17, v253, 28
	s_add_u32 s16, s8, s2
	v_readlane_b32 s5, v254, 12
	s_addc_u32 s17, s9, s3
	s_and_b64 vcc, exec, s[4:5]
	v_readlane_b32 s6, v253, 17
	v_readlane_b32 s7, v253, 18
	v_readlane_b32 s10, v253, 21
	v_readlane_b32 s11, v253, 22
	v_readlane_b32 s12, v253, 23
	v_readlane_b32 s13, v253, 24
	v_readlane_b32 s14, v253, 25
	v_readlane_b32 s15, v253, 26
	v_readlane_b32 s18, v253, 29
	v_readlane_b32 s19, v253, 30
	s_cbranch_vccz .LBB0_405
	v_mov_b32_e32 v0, v138
	v_readlane_b32 s4, v255, 4
	v_readlane_b32 s5, v255, 5
	s_add_u32 s4, s16, s4
	v_lshlrev_b32_e32 v0, 2, v0
	s_addc_u32 s5, s17, s5
	v_ashrrev_i32_e32 v1, 31, v0
	v_lshl_add_u64 v[4:5], v[0:1], 2, s[4:5]
	global_load_dwordx4 v[0:3], v[4:5], off
	v_lshl_add_u64 v[8:9], v[4:5], 0, s[44:45]
	global_load_dwordx4 v[4:7], v[8:9], off
	v_lshl_add_u64 v[8:9], v[8:9], 0, s[44:45]
	global_load_dwordx4 v[12:15], v[8:9], off
	v_lshl_add_u64 v[8:9], v[8:9], 0, s[44:45]
	global_load_dwordx4 v[16:19], v[8:9], off
	v_lshl_add_u64 v[8:9], v[8:9], 0, s[44:45]
	global_load_dwordx4 v[20:23], v[8:9], off
	v_lshl_add_u64 v[8:9], v[8:9], 0, s[44:45]
	global_load_dwordx4 v[24:27], v[8:9], off
	v_lshl_add_u64 v[8:9], v[8:9], 0, s[44:45]
	global_load_dwordx4 v[28:31], v[8:9], off
	v_lshl_add_u64 v[8:9], v[8:9], 0, s[44:45]
	global_load_dwordx4 v[32:35], v[8:9], off

; __device__ __forceinline__ float bf2f(bf16 v) { return __uint_as_float(((unsigned)v) << 16); }
; __device__ __forceinline__ float sigmoidf_(float x) { return frcp_(1.0f + __expf(-x)); }
; __device__ __forceinline__ float siluf_(float x) { return x * frcp_(1.0f + __expf(-x)); }
; __host__ __device__ __forceinline__ int hg_vpos(int e) { return (e & 64) + 16 * (e & 3) + ((e & 63) >> 2); }
; #define LAS __attribute__((address_space(3)))
; __device__ __forceinline__ void hgrn_sample_step(const bf16* proj, const float* lbs_l, const float* hgn_l, const float* state_in, float* state_out, bf16* ohg, int bh, int tid, LAS unsigned char* lds,
;                                                  f32x4 (&st)[8], int bh_next) {
;     const int b = bh >> 3, h = bh & 7, lane = tid & 63, w = tid >> 6;
;     LAS float* sq = (LAS float*)lds; LAS float* sg = sq + 128; LAS float* sk = sq + 256; LAS float* sv = sq + 384; LAS float* so = (LAS float*)(lds + 8192); LAS float* sred = (LAS float*)(lds + 16384);
;     const size_t row = (size_t)MP + b;
;     float ogv = 0.f, q_ = 0.f, f_ = 0.f, v_ = 0.f, lb_ = 0.f;
;     if (tid < 128) { const bf16* pr = proj + row * LDP + h * 128; q_ = bf2f(pr[PC_Q + tid]); f_ = bf2f(pr[PC_F + tid]); lb_ = lbs_l[h * 128 + tid]; v_ = bf2f(pr[PC_I + hg_vpos(tid)]); ogv = bf2f(pr[PC_OG + tid]); }
;     if (tid < 128) { const float fg = lb_ + (1.f - lb_) * sigmoidf_(f_);
;         sq[tid] = siluf_(q_) * 0.08838834764831845f; sg[tid] = fg; sk[tid] = 1.f - fg; sv[tid] = v_; }
.LBB0_408:
	s_ashr_i32 s6, s22, 3
	v_mov_b32_e32 v8, v138
	s_add_i32 s10, s6, 0x4000
	s_movk_i32 s6, 0x80
	s_and_b32 s18, s22, 7
	s_ashr_i32 s11, s10, 31
	v_cmp_gt_i32_e64 s[6:7], s6, v8
	v_bfrev_b32_e32 v38, 1
	v_mov_b32_e32 v36, 0
	v_ashrrev_i32_e32 v9, 31, v8
	v_mov_b32_e32 v68, 0
	v_mov_b32_e32 v10, 0
	v_mov_b32_e32 v37, 0
	s_and_saveexec_b64 s[8:9], s[6:7]
	s_cbranch_execz .LBB0_410
	s_mul_i32 s13, s10, 0x6200
	s_mul_hi_i32 s12, s10, 0x6200
	s_add_u32 s13, s78, s13
	s_addc_u32 s14, s79, s12
	s_lshl_b32 s12, s18, 8
	s_add_u32 s12, s13, s12
	s_addc_u32 s13, s14, 0
	v_lshl_add_u64 v[38:39], v[8:9], 1, s[12:13]
	global_load_ushort v10, v[38:39], off offset:2048
	v_lshl_add_u32 v36, s18, 7, v8
	v_ashrrev_i32_e32 v37, 31, v36
	v_lshl_add_u64 v[36:37], v[36:37], 2, s[96:97]
	global_load_dword v36, v[36:37], off
	v_lshlrev_b32_e32 v37, 4, v8
	v_and_b32_e32 v37, 48, v37
	v_bfe_u32 v40, v8, 2, 4
	s_waitcnt vmcnt(0) lgkmcnt(0)
	v_lshlrev_b32_e32 v42, 16, v10
	v_and_b32_e32 v10, 64, v8
	v_or3_b32 v10, v37, v10, v40
	v_lshlrev_b32_e32 v10, 1, v10
	v_lshl_add_u64 v[40:41], s[12:13], 0, v[10:11]
	s_movk_i32 s12, 0x1000
	v_add_co_u32_e32 v40, vcc, s12, v40
	s_nop 1
	v_addc_co_u32_e32 v41, vcc, 0, v41, vcc
	global_load_ushort v10, v[40:41], off
	global_load_ushort v37, v[38:39], off
	v_add_co_u32_e32 v38, vcc, 0x1000, v38
	s_waitcnt vmcnt(0) lgkmcnt(0)
	v_lshlrev_b32_e32 v10, 16, v10
	v_addc_co_u32_e32 v39, vcc, 0, v39, vcc
	global_load_ushort v38, v[38:39], off offset:2048
	v_lshlrev_b32_e32 v37, 16, v37
	s_waitcnt vmcnt(0) lgkmcnt(0)
	v_lshlrev_b32_e32 v68, 16, v38
	v_mul_f32_e32 v38, 0xbfb8aa3b, v42

; #define LAS __attribute__((address_space(3)))
; #define LAUNDER_PTR(p) do {} while (0)
; #define LAUNDER_PTR(p) asm volatile("" : "+v"(p))
; __device__ __forceinline__ void hgrn_sample_step(const bf16* proj, const float* lbs_l, const float* hgn_l, const float* state_in, float* state_out, bf16* ohg, int bh, int tid, LAS unsigned char* lds,
;                                                  f32x4 (&st)[8], int bh_next) {
;     ...
;     const int dv4 = tid & 31, rg = tid >> 5;
;     const f32x4 vv = *(const LAS f32x4*)(sv + 4 * dv4);
;     f32x4 oacc = (f32x4){0.f, 0.f, 0.f, 0.f};
;     float* op = state_out + (size_t)bh * 16384 + tid * 4;
;     const float* np = state_in + (size_t)(bh_next >= 0 ? bh_next : bh) * 16384 + tid * 4;
; #pragma unroll
;     for (int it = 0; it < 8; ++it) { const int dk = it * 16 + rg; const f32x4 sn = st[it] * sg[dk] + vv * sk[dk]; LAUNDER_PTR(op); *(f32x4*)op = sn; op += 2048; oacc = oacc + sn * sq[dk];
;         LAUNDER_PTR(np); if (bh_next >= 0) st[it] = *(const f32x4*)np; np += 2048; }
.LBB0_412:
	s_or_b64 exec, exec, s[8:9]
	v_lshlrev_b32_e32 v40, 2, v8
	v_and_b32_e32 v73, 0x7c, v40
	v_ashrrev_i32_e32 v71, 5, v8
	v_lshl_add_u32 v10, v73, 2, 0
	s_waitcnt lgkmcnt(0)
	s_barrier
	ds_read_b128 v[36:39], v10 offset:1536
	v_lshl_add_u32 v10, v71, 2, 0
	ds_read2st64_b32 v[42:43], v10 offset0:2 offset1:4
	s_add_i32 s19, s22, s90
	s_cmpk_gt_i32 s19, 0x3ff
	s_cselect_b64 s[12:13], -1, 0
	s_cmpk_lt_i32 s19, 0x400
	s_cselect_b32 s8, s19, -1
	v_ashrrev_i32_e32 v41, 31, v40
	v_lshlrev_b64 v[46:47], 2, v[40:41]
	s_cmp_gt_i32 s8, -1
	s_waitcnt lgkmcnt(0)
	v_mov_b32_e32 v40, v43
	s_cselect_b64 s[14:15], -1, 0
	v_pk_mul_f32 v[48:49], v[38:39], v[40:41] op_sel_hi:[1,0]
	v_pk_mul_f32 v[40:41], v[36:37], v[40:41] op_sel_hi:[1,0]
	v_lshl_add_u64 v[44:45], s[2:3], 0, v[46:47]
	s_and_b64 vcc, s[14:15], exec
	s_waitcnt vmcnt(0)
	v_pk_fma_f32 v[40:41], v[0:1], v[42:43], v[40:41] op_sel_hi:[1,0,1]
	v_pk_fma_f32 v[42:43], v[2:3], v[42:43], v[48:49] op_sel_hi:[1,0,1]
	s_cselect_b32 s8, s8, s22
	global_store_dwordx4 v[44:45], v[40:43], off
	s_ashr_i32 s9, s8, 31
	ds_read_b32 v70, v10
	s_lshl_b64 s[8:9], s[8:9], 16
	s_add_u32 s8, s16, s8
	s_addc_u32 s9, s17, s9
	v_lshl_add_u64 v[46:47], s[8:9], 0, v[46:47]
	s_cbranch_vccz .LBB0_414
	global_load_dwordx4 v[0:3], v[46:47], off
.LBB0_414:
	v_add_u32_e32 v66, 64, v10
	ds_read2st64_b32 v[50:51], v66 offset0:2 offset1:4
	v_lshl_add_u64 v[48:49], v[44:45], 0, s[44:45]
	v_lshl_add_u64 v[52:53], v[46:47], 0, s[44:45]
	s_andn2_b64 vcc, exec, s[14:15]
	s_waitcnt lgkmcnt(0)
	v_mov_b32_e32 v44, v51
	v_pk_mul_f32 v[46:47], v[38:39], v[44:45] op_sel_hi:[1,0]
	v_pk_mul_f32 v[44:45], v[36:37], v[44:45] op_sel_hi:[1,0]
	v_pk_fma_f32 v[46:47], v[6:7], v[50:51], v[46:47] op_sel_hi:[1,0,1]
	v_pk_fma_f32 v[44:45], v[4:5], v[50:51], v[44:45] op_sel_hi:[1,0,1]
	global_store_dwordx4 v[48:49], v[44:47], off
	ds_read_b32 v72, v10 offset:64
	v_cndmask_b32_e64 v50, 0, 1, s[14:15]
	v_cmp_ne_u32_e64 s[8:9], 1, v50
	s_cbranch_vccnz .LBB0_416
	global_load_dwordx4 v[4:7], v[52:53], off
.LBB0_416:
	v_add_u32_e32 v75, 0x80, v10
	ds_read2st64_b32 v[56:57], v75 offset0:2 offset1:4
	v_lshl_add_u64 v[54:55], v[48:49], 0, s[44:45]
	s_and_b64 vcc, exec, s[8:9]
	s_waitcnt lgkmcnt(0)
	v_mov_b32_e32 v48, v57
	v_pk_mul_f32 v[50:51], v[38:39], v[48:49] op_sel_hi:[1,0]
	v_pk_mul_f32 v[48:49], v[36:37], v[48:49] op_sel_hi:[1,0]
	v_pk_fma_f32 v[50:51], v[14:15], v[56:57], v[50:51] op_sel_hi:[1,0,1]
	v_pk_fma_f32 v[48:49], v[12:13], v[56:57], v[48:49] op_sel_hi:[1,0,1]
	global_store_dwordx4 v[54:55], v[48:51], off
	ds_read_b32 v74, v10 offset:128
	v_lshl_add_u64 v[56:57], v[52:53], 0, s[44:45]
	s_cbranch_vccnz .LBB0_418
	global_load_dwordx4 v[12:15], v[56:57], off
.LBB0_418:
	v_add_u32_e32 v77, 0xc0, v10
	ds_read2st64_b32 v[52:53], v77 offset0:2 offset1:4
	v_lshl_add_u64 v[58:59], v[54:55], 0, s[44:45]
	s_and_b64 vcc, exec, s[8:9]
	s_waitcnt lgkmcnt(0)
	v_mov_b32_e32 v54, v53
	v_pk_mul_f32 v[60:61], v[38:39], v[54:55] op_sel_hi:[1,0]
	v_pk_mul_f32 v[62:63], v[36:37], v[54:55] op_sel_hi:[1,0]
	v_pk_fma_f32 v[54:55], v[18:19], v[52:53], v[60:61] op_sel_hi:[1,0,1]
	v_pk_fma_f32 v[52:53], v[16:17], v[52:53], v[62:63] op_sel_hi:[1,0,1]
	global_store_dwordx4 v[58:59], v[52:55], off
	ds_read_b32 v76, v10 offset:192
	v_lshl_add_u64 v[60:61], v[56:57], 0, s[44:45]
	s_cbranch_vccnz .LBB0_420
	global_load_dwordx4 v[16:19], v[60:61], off
.LBB0_420:
	ds_read2st64_b32 v[56:57], v10 offset0:3 offset1:5
	v_lshl_add_u64 v[62:63], v[58:59], 0, s[44:45]
	s_and_b64 vcc, exec, s[8:9]
	s_waitcnt lgkmcnt(0)
	v_mov_b32_e32 v58, v57
	v_pk_mul_f32 v[64:65], v[38:39], v[58:59] op_sel_hi:[1,0]
	v_pk_mul_f32 v[78:79], v[36:37], v[58:59] op_sel_hi:[1,0]
	v_pk_fma_f32 v[58:59], v[22:23], v[56:57], v[64:65] op_sel_hi:[1,0,1]
	v_pk_fma_f32 v[56:57], v[20:21], v[56:57], v[78:79] op_sel_hi:[1,0,1]
	global_store_dwordx4 v[62:63], v[56:59], off
	ds_read_b32 v78, v10 offset:256
	v_lshl_add_u64 v[64:65], v[60:61], 0, s[44:45]
	s_cbranch_vccnz .LBB0_422
	global_load_dwordx4 v[20:23], v[64:65], off
.LBB0_422:
	ds_read2st64_b32 v[60:61], v66 offset0:3 offset1:5
	v_lshl_add_u64 v[66:67], v[62:63], 0, s[44:45]
	v_lshl_add_u64 v[84:85], v[64:65], 0, s[44:45]
	s_and_b64 vcc, exec, s[8:9]
	s_waitcnt lgkmcnt(0)
	v_mov_b32_e32 v62, v61
	v_pk_mul_f32 v[80:81], v[38:39], v[62:63] op_sel_hi:[1,0]
	v_pk_mul_f32 v[82:83], v[36:37], v[62:63] op_sel_hi:[1,0]
	v_pk_fma_f32 v[62:63], v[26:27], v[60:61], v[80:81] op_sel_hi:[1,0,1]
	v_pk_fma_f32 v[60:61], v[24:25], v[60:61], v[82:83] op_sel_hi:[1,0,1]
	global_store_dwordx4 v[66:67], v[60:63], off
	ds_read_b32 v80, v10 offset:320
	s_cbranch_vccnz .LBB0_424
	global_load_dwordx4 v[24:27], v[84:85], off
.LBB0_424:
	ds_read2st64_b32 v[64:65], v75 offset0:3 offset1:5
	v_lshl_add_u64 v[86:87], v[66:67], 0, s[44:45]
	s_and_b64 vcc, exec, s[8:9]
	s_waitcnt lgkmcnt(0)
	v_mov_b32_e32 v66, v65
	v_pk_mul_f32 v[82:83], v[38:39], v[66:67] op_sel_hi:[1,0]
	v_pk_mul_f32 v[88:89], v[36:37], v[66:67] op_sel_hi:[1,0]
	v_pk_fma_f32 v[66:67], v[30:31], v[64:65], v[82:83] op_sel_hi:[1,0,1]
	v_pk_fma_f32 v[64:65], v[28:29], v[64:65], v[88:89] op_sel_hi:[1,0,1]
	global_store_dwordx4 v[86:87], v[64:67], off
	ds_read_b32 v82, v10 offset:384
	v_lshl_add_u64 v[88:89], v[84:85], 0, s[44:45]
	s_cbranch_vccnz .LBB0_426
	global_load_dwordx4 v[28:31], v[88:89], off
.LBB0_426:
	ds_read2st64_b32 v[84:85], v77 offset0:3 offset1:5
	v_lshl_add_u64 v[86:87], v[86:87], 0, s[44:45]
	s_and_b64 vcc, exec, s[8:9]
	s_waitcnt lgkmcnt(0)
	v_mov_b32_e32 v90, v85
	v_pk_mul_f32 v[38:39], v[38:39], v[90:91] op_sel_hi:[1,0]
	v_pk_mul_f32 v[36:37], v[36:37], v[90:91] op_sel_hi:[1,0]
	v_pk_fma_f32 v[38:39], v[34:35], v[84:85], v[38:39] op_sel_hi:[1,0,1]
	v_pk_fma_f32 v[36:37], v[32:33], v[84:85], v[36:37] op_sel_hi:[1,0,1]
	global_store_dwordx4 v[86:87], v[36:39], off
	ds_read_b32 v84, v10 offset:448
	v_lshl_add_u64 v[86:87], v[88:89], 0, s[44:45]
	s_cbranch_vccnz .LBB0_428
	global_load_dwordx4 v[32:35], v[86:87], off

; __device__ __forceinline__ bf16 f2bf(float f) { return (bf16)pk2(f, f); }
; __device__ __forceinline__ float siluf_(float x) { return x * frcp_(1.0f + __expf(-x)); }
; #define LAUNDER_PTR(p) do {} while (0)
; #define LAUNDER_PTR(p) asm volatile("" : "+v"(p))
; __device__ __forceinline__ void hgrn_sample_step(const bf16* proj, const float* lbs_l, const float* hgn_l, const float* state_in, float* state_out, bf16* ohg, int bh, int tid, LAS unsigned char* lds,
;                                                  f32x4 (&st)[8], int bh_next) {
;     ...
;     if (tid < 128) { const float rstd = rsqrtf(((sred[0] + sred[1]) + (sred[2] + sred[3])) * (1.f / 128.f) + EPS);
;         ohg[row * 1024 + h * 128 + tid] = f2bf(sq[tid] * rstd * hgn_l[tid] * siluf_(ogv)); }
; __device__ __forceinline__ void ssd_sample_load(f32x4 (&st)[16], const float* state_in, int bg, int tid) {
;     const float* sp = state_in + ((size_t)((bg >> 3) * 32 + (bg & 7) * 4)) * 8192 + tid * 4;
; #pragma unroll
;     for (int it = 0; it < 16; ++it) { LAUNDER_PTR(sp); st[it] = *(const f32x4*)sp; sp += 2048; }
; }
.LBB0_432:
	s_or_b64 exec, exec, s[8:9]
	s_waitcnt lgkmcnt(0)
	s_barrier
	s_and_saveexec_b64 s[8:9], s[6:7]
	s_cbranch_execz .LBB0_407
	ds_read_b128 v[36:39], v11 offset:16384
	v_readlane_b32 s6, v255, 53
	v_readlane_b32 s7, v255, 54
	s_waitcnt lgkmcnt(0)
	v_mov_b32_e32 v40, v37
	v_mov_b32_e32 v41, v38
	v_mov_b32_e32 v37, v39
	v_pk_add_f32 v[36:37], v[40:41], v[36:37]
	v_lshl_add_u64 v[38:39], v[8:9], 2, s[6:7]
	v_add_f32_e32 v10, v36, v37
	v_fmamk_f32 v10, v10, 0x3c000000, v176
	v_cmp_gt_f32_e32 vcc, s33, v10
	v_mul_f32_e32 v36, 0x4b800000, v10
	s_lshl_b64 s[6:7], s[10:11], 11
	v_cndmask_b32_e32 v10, v10, v36, vcc
	v_rsq_f32_e32 v10, v10
	v_readlane_b32 s10, v255, 47
	s_add_u32 s6, s10, s6
	v_readlane_b32 s10, v255, 48
	v_mul_f32_e32 v36, 0x45800000, v10
	v_cndmask_b32_e32 v10, v10, v36, vcc
	ds_read_b32 v36, v69
	global_load_dword v69, v[38:39], off
	s_addc_u32 s7, s10, s7
	s_lshl_b32 s10, s18, 8
	s_add_u32 s6, s6, s10
	s_waitcnt lgkmcnt(0)
	v_mul_f32_e32 v37, v36, v10
	v_mul_f32_e32 v10, 0xbfb8aa3b, v68
	v_exp_f32_e32 v10, v10
	s_addc_u32 s7, s7, 0
	v_lshl_add_u64 v[8:9], v[8:9], 1, s[6:7]
	v_add_f32_e32 v10, 1.0, v10
	v_rcp_f32_e32 v36, v10
	s_waitcnt vmcnt(0)
	v_pk_mul_f32 v[36:37], v[68:69], v[36:37]
	s_nop 0
	v_mul_f32_e32 v10, v36, v37
	v_cvt_pk_bf16_f32 v10, v10, v10
	global_store_short v[8:9], v10, off
	s_branch .LBB0_407
.LBB0_434:
	v_readlane_b32 s2, v255, 34
	v_readlane_b32 s3, v255, 35
	v_readlane_b32 s8, v253, 15
	s_lshl_b64 s[2:3], s[2:3], 27
	v_readlane_b32 s14, v253, 21
	v_readlane_b32 s20, v253, 27
	v_readlane_b32 s15, v253, 22
	v_readlane_b32 s21, v253, 28
	s_add_u32 s20, s14, s2
	s_addc_u32 s21, s15, s3
	v_readlane_b32 s2, v254, 11
	v_readlane_b32 s3, v254, 12
	s_and_b64 vcc, exec, s[2:3]
	v_readlane_b32 s9, v253, 16
	v_readlane_b32 s10, v253, 17
	v_readlane_b32 s11, v253, 18
	v_readlane_b32 s12, v253, 19
	v_readlane_b32 s13, v253, 20
	v_readlane_b32 s16, v253, 23
	v_readlane_b32 s17, v253, 24
	v_readlane_b32 s18, v253, 25
	v_readlane_b32 s19, v253, 26
	v_readlane_b32 s22, v253, 29
	v_readlane_b32 s23, v253, 30
	s_cbranch_vccz .LBB0_436
	s_waitcnt vmcnt(0) lgkmcnt(0)
	v_mov_b32_e32 v0, v138
	v_readlane_b32 s2, v254, 15
	v_readlane_b32 s3, v254, 16
	s_add_u32 s2, s20, s2
	v_lshlrev_b32_e32 v0, 2, v0
	s_addc_u32 s3, s21, s3
	v_ashrrev_i32_e32 v1, 31, v0
	v_lshl_add_u64 v[4:5], v[0:1], 2, s[2:3]
	global_load_dwordx4 v[0:3], v[4:5], off
	v_lshl_add_u64 v[8:9], v[4:5], 0, s[44:45]
	global_load_dwordx4 v[4:7], v[8:9], off
	v_lshl_add_u64 v[8:9], v[8:9], 0, s[44:45]
	global_load_dwordx4 v[12:15], v[8:9], off
	v_lshl_add_u64 v[8:9], v[8:9], 0, s[44:45]
	global_load_dwordx4 v[16:19], v[8:9], off
	v_lshl_add_u64 v[8:9], v[8:9], 0, s[44:45]
	global_load_dwordx4 v[20:23], v[8:9], off
	v_lshl_add_u64 v[8:9], v[8:9], 0, s[44:45]
	global_load_dwordx4 v[24:27], v[8:9], off
	v_lshl_add_u64 v[8:9], v[8:9], 0, s[44:45]
	global_load_dwordx4 v[28:31], v[8:9], off
	v_lshl_add_u64 v[8:9], v[8:9], 0, s[44:45]
	global_load_dwordx4 v[32:35], v[8:9], off
	v_lshl_add_u64 v[8:9], v[8:9], 0, s[44:45]
	global_load_dwordx4 v[36:39], v[8:9], off
	v_lshl_add_u64 v[8:9], v[8:9], 0, s[44:45]
	global_load_dwordx4 v[40:43], v[8:9], off
	v_lshl_add_u64 v[8:9], v[8:9], 0, s[44:45]
	global_load_dwordx4 v[44:47], v[8:9], off
	v_lshl_add_u64 v[8:9], v[8:9], 0, s[44:45]
	global_load_dwordx4 v[48:51], v[8:9], off
	v_lshl_add_u64 v[8:9], v[8:9], 0, s[44:45]
	global_load_dwordx4 v[52:55], v[8:9], off
	v_lshl_add_u64 v[8:9], v[8:9], 0, s[44:45]
	global_load_dwordx4 v[56:59], v[8:9], off
	v_lshl_add_u64 v[8:9], v[8:9], 0, s[44:45]
	global_load_dwordx4 v[60:63], v[8:9], off
	v_lshl_add_u64 v[8:9], v[8:9], 0, s[44:45]
	global_load_dwordx4 v[64:67], v[8:9], off

; __device__ __forceinline__ float bf2f(bf16 v) { return __uint_as_float(((unsigned)v) << 16); }
; __device__ __forceinline__ void ssd_sample_step(const bf16* proj, const float* conv_w, const float* conv_b, const float* dt_bias, const float* a_log, const float* d_skip, const float* ssm_norm, ...
;     ...
;         const int chx = tid < 256 ? (grp * 256 + tid) : (tid < 384 ? (2048 + grp * 128 + (tid - 256)) : (3072 + grp * 128 + (tid - 384)));
;         const float* ci = conv_in + (size_t)b * 3 * 4096; const float r0 = ci[chx], r1 = ci[4096 + chx], r2 = ci[8192 + chx];
;         const float cur = bf2f(proj[row * LDP + PC_XBC + chx]);
;         const float cw0 = conv_w[chx], cw1 = conv_w[4096 + chx], cw2 = conv_w[8192 + chx], cw3 = conv_w[12288 + chx], cbb = conv_b[chx];
;         float dtr = 0.f, dtbv = 0.f, alg = 0.f; if (tid < 4) { const int head = grp * 4 + tid; dtr = bf2f(proj[row * LDP + PC_DT + head]); dtbv = dt_bias[head]; alg = a_log[head]; }
.LBB0_445:
	s_or_saveexec_b64 s[2:3], s[2:3]
	v_lshl_add_u32 v80, s50, 8, v8
	s_xor_b64 exec, exec, s[2:3]
	v_mov_b32_e32 v68, v80
	s_or_b64 exec, exec, s[2:3]
	s_ashr_i32 s58, s59, 3
	s_ashr_i32 s3, s58, 31
	s_add_u32 s2, s58, 0x4000
	s_mul_hi_i32 s9, s58, 0x3000
	s_mul_i32 s8, s58, 0x3000
	s_addc_u32 s3, s3, 0
	s_lshl_b64 s[12:13], s[8:9], 2
	s_add_u32 s8, s28, s12
	v_ashrrev_i32_e32 v69, 31, v68
	s_addc_u32 s9, s29, s13
	v_lshlrev_b64 v[72:73], 2, v[68:69]
	v_lshl_add_u64 v[74:75], s[8:9], 0, v[72:73]
	s_movk_i32 s14, 0x4000
	v_add_co_u32_e32 v70, vcc, s14, v74
	s_mov_b32 s8, 0x8000
	s_nop 0
	v_addc_co_u32_e32 v71, vcc, 0, v75, vcc
	s_mul_i32 s9, s2, 0x6200
	global_load_dword v10, v[74:75], off
	s_add_u32 s10, s78, s9
	global_load_dword v70, v[70:71], off
	v_add_co_u32_e32 v74, vcc, s8, v74
	s_mul_hi_i32 s8, s2, 0x6200
	s_nop 0
	v_addc_co_u32_e32 v75, vcc, 0, v75, vcc
	s_addc_u32 s11, s79, s8
	global_load_dword v71, v[74:75], off
	v_lshl_add_u64 v[74:75], v[68:69], 1, s[10:11]
	s_movk_i32 s8, 0x3000
	v_add_co_u32_e32 v74, vcc, s8, v74
	v_lshl_add_u64 v[78:79], s[30:31], 0, v[72:73]
	s_nop 0
	v_addc_co_u32_e32 v75, vcc, 0, v75, vcc
	v_add_co_u32_e32 v76, vcc, s14, v78
	global_load_ushort v74, v[74:75], off
	s_nop 0
	v_addc_co_u32_e32 v77, vcc, 0, v79, vcc
	v_add_co_u32_e32 v82, vcc, 0x8000, v78
	global_load_dword v75, v[78:79], off
	s_nop 0
	v_addc_co_u32_e32 v83, vcc, 0, v79, vcc
	global_load_dword v76, v[76:77], off
	v_add_co_u32_e32 v78, vcc, 0xc000, v78
	v_lshl_add_u64 v[72:73], s[34:35], 0, v[72:73]
	s_nop 0
	v_addc_co_u32_e32 v79, vcc, 0, v79, vcc
	global_load_dword v77, v[82:83], off
	v_cmp_gt_i32_e64 s[8:9], 4, v8
	global_load_dword v79, v[78:79], off
	v_mov_b32_e32 v9, 0
	global_load_dword v78, v[72:73], off
	v_mov_b32_e32 v73, 0
	v_mov_b32_e32 v72, 0
	s_and_saveexec_b64 s[14:15], s[8:9]
	s_cbranch_execz .LBB0_449
	v_lshl_add_u32 v82, s50, 2, v8
	v_ashrrev_i32_e32 v83, 31, v82
	v_lshl_add_u64 v[72:73], v[82:83], 1, s[10:11]
	v_add_co_u32_e32 v72, vcc, 0x6000, v72
	v_lshlrev_b64 v[82:83], 2, v[82:83]
	s_nop 0
	v_addc_co_u32_e32 v73, vcc, 0, v73, vcc
	global_load_ushort v9, v[72:73], off
	v_lshl_add_u64 v[84:85], s[36:37], 0, v[82:83]
	v_lshl_add_u64 v[82:83], s[60:61], 0, v[82:83]
	global_load_dword v73, v[84:85], off
	s_waitcnt vmcnt(0) lgkmcnt(0)
	v_lshlrev_b32_e32 v72, 16, v9
	global_load_dword v9, v[82:83], off
	s_waitcnt vmcnt(0)
	v_mul_f32_e32 v9, 0x3fb8aa3b, v9

; #define LAS __attribute__((address_space(3)))
; #define LAUNDER_PTR(p) do {} while (0)
; #define LAUNDER_PTR(p) asm volatile("" : "+v"(p))
; __device__ __forceinline__ void ssd_sample_step(const bf16* proj, const float* conv_w, const float* conv_b, const float* dt_bias, const float* a_log, const float* d_skip, const float* ssm_norm, ...
;     ...
;     const int n4 = tid & 31, pr_ = tid >> 5;
;     const f32x4 Bv = *(const LAS f32x4*)(sB + 4 * n4), Cv = *(const LAS f32x4*)(sC + 4 * n4);
;     float* op = state_out + ((size_t)(b * 32 + grp * 4)) * 8192 + tid * 4;
;     const int bgn = bg_next >= 0 ? bg_next : bg; const float* np = state_in + ((size_t)((bgn >> 3) * 32 + (bgn & 7) * 4)) * 8192 + tid * 4;
; #pragma unroll
;     for (int it = 0; it < 16; ++it) { const int k = it >> 2, p = (it & 3) * 16 + pr_; const float xdt = sx[k * 64 + p] * sdt[k];
;         const f32x4 hn = st[it] * sdec[k] + Bv * xdt; LAUNDER_PTR(op); *(f32x4*)op = hn; op += 2048;
;         LAUNDER_PTR(np); if (bg_next >= 0) st[it] = *(const f32x4*)np; np += 2048;
.LBB0_461:
	s_or_b64 exec, exec, s[6:7]
	s_add_i32 s51, s59, s90
	s_cmpk_gt_i32 s51, 0x3ff
	s_cselect_b64 s[12:13], -1, 0
	s_cmpk_lt_i32 s51, 0x400
	s_cselect_b32 s8, s51, -1
	s_lshl_b32 s6, s58, 5
	s_lshl_b32 s58, s50, 2
	s_or_b32 s6, s6, s58
	s_ashr_i32 s7, s6, 31
	s_lshl_b64 s[6:7], s[6:7], 15
	s_add_u32 s6, s64, s6
	v_lshlrev_b32_e32 v72, 2, v8
	s_addc_u32 s7, s66, s7
	v_ashrrev_i32_e32 v73, 31, v72
	s_cmp_gt_i32 s8, -1
	v_lshlrev_b32_e32 v68, 4, v8
	v_lshlrev_b64 v[76:77], 2, v[72:73]
	s_cselect_b64 s[14:15], -1, 0
	v_ashrrev_i32_e32 v9, 5, v8
	v_and_b32_e32 v68, 0x1f0, v68
	v_lshl_add_u64 v[82:83], s[6:7], 0, v[76:77]
	s_and_b64 s[6:7], s[14:15], exec
	s_movk_i32 s9, 0x1000
	v_add_u32_e32 v74, 0, v68
	s_cselect_b32 s6, s8, s59
	v_lshl_add_u32 v81, v9, 2, 0
	v_add_u32_e64 v9, s9, 0
	s_waitcnt lgkmcnt(0)
	s_barrier
	ds_read_b128 v[68:71], v74 offset:3584
	s_lshl_b32 s6, s6, 2
	ds_read_b128 v[72:75], v74 offset:3072
	ds_read_b32 v86, v81 offset:2048
	ds_read2_b32 v[78:79], v9 offset1:4
	s_ashr_i32 s7, s6, 31
	s_lshl_b64 s[6:7], s[6:7], 15
	s_add_u32 s6, s20, s6
	s_addc_u32 s7, s21, s7
	v_lshl_add_u64 v[84:85], s[6:7], 0, v[76:77]
	s_waitcnt lgkmcnt(0)
	v_mov_b32_e32 v76, v79
	v_mul_f32_e32 v78, v86, v78
	v_pk_mul_f32 v[86:87], v[2:3], v[76:77] op_sel_hi:[1,0]
	v_pk_mul_f32 v[76:77], v[0:1], v[76:77] op_sel_hi:[1,0]
	s_cmp_lt_i32 s8, 0
	v_pk_fma_f32 v[76:77], v[72:73], v[78:79], v[76:77] op_sel_hi:[1,0,1]
	v_pk_fma_f32 v[78:79], v[74:75], v[78:79], v[86:87] op_sel_hi:[1,0,1]
	global_store_dwordx4 v[82:83], v[76:79], off
	s_cbranch_scc1 .LBB0_463
	global_load_dwordx4 v[0:3], v[84:85], off

; #define LAUNDER_PTR(p) do {} while (0)
; #define LAUNDER_PTR(p) asm volatile("" : "+v"(p))
; __device__ __forceinline__ float row32_sum(float s) { s += SHFL_XOR(s, 1); s += SHFL_XOR(s, 2); s += SHFL_XOR(s, 4); s += SHFL_XOR(s, 8); s += SHFL_XOR(s, 16); return s; }
; __device__ __forceinline__ void ssd_sample_step(const bf16* proj, const float* conv_w, const float* conv_b, const float* dt_bias, const float* a_log, const float* d_skip, const float* ssm_norm, ...
;     ...
; #pragma unroll
;     for (int it = 0; it < 16; ++it) { const int k = it >> 2, p = (it & 3) * 16 + pr_; const float xdt = sx[k * 64 + p] * sdt[k];
;         const f32x4 hn = st[it] * sdec[k] + Bv * xdt; LAUNDER_PTR(op); *(f32x4*)op = hn; op += 2048;
;         LAUNDER_PTR(np); if (bg_next >= 0) st[it] = *(const f32x4*)np; np += 2048;
;         const f32x4 t = hn * Cv; float y = (t[0] + t[1]) + (t[2] + t[3]); y = row32_sum(y);
;         if ((lane & 31) == 0) sy[k * 64 + p] = y; }
.LBB0_465:
	s_or_b64 exec, exec, s[8:9]
	ds_read_b32 v78, v81 offset:2112
	s_waitcnt lgkmcnt(0)
	ds_read2_b32 v[76:77], v9 offset1:4
	v_lshl_add_u64 v[84:85], v[84:85], 0, s[44:45]
	v_lshl_add_u64 v[82:83], v[82:83], 0, s[44:45]
	s_andn2_b64 vcc, exec, s[14:15]
	s_waitcnt lgkmcnt(0)
	v_mul_f32_e32 v76, v78, v76
	v_mov_b32_e32 v78, v77
	v_pk_mul_f32 v[86:87], v[6:7], v[78:79] op_sel_hi:[1,0]
	v_pk_mul_f32 v[88:89], v[4:5], v[78:79] op_sel_hi:[1,0]
	v_pk_fma_f32 v[78:79], v[74:75], v[76:77], v[86:87] op_sel_hi:[1,0,1]
	v_cndmask_b32_e64 v86, 0, 1, s[14:15]
	v_pk_fma_f32 v[76:77], v[72:73], v[76:77], v[88:89] op_sel_hi:[1,0,1]
	v_cmp_ne_u32_e64 s[8:9], 1, v86
	global_store_dwordx4 v[82:83], v[76:79], off
	s_cbranch_vccnz .LBB0_467
	global_load_dwordx4 v[4:7], v[84:85], off

; #define LAUNDER_PTR(p) do {} while (0)
; #define LAUNDER_PTR(p) asm volatile("" : "+v"(p))
; __device__ __forceinline__ float row32_sum(float s) { s += SHFL_XOR(s, 1); s += SHFL_XOR(s, 2); s += SHFL_XOR(s, 4); s += SHFL_XOR(s, 8); s += SHFL_XOR(s, 16); return s; }
; __device__ __forceinline__ void ssd_sample_step(const bf16* proj, const float* conv_w, const float* conv_b, const float* dt_bias, const float* a_log, const float* d_skip, const float* ssm_norm, ...
;     ...
; #pragma unroll
;     for (int it = 0; it < 16; ++it) { const int k = it >> 2, p = (it & 3) * 16 + pr_; const float xdt = sx[k * 64 + p] * sdt[k];
;         const f32x4 hn = st[it] * sdec[k] + Bv * xdt; LAUNDER_PTR(op); *(f32x4*)op = hn; op += 2048;
;         LAUNDER_PTR(np); if (bg_next >= 0) st[it] = *(const f32x4*)np; np += 2048;
;         const f32x4 t = hn * Cv; float y = (t[0] + t[1]) + (t[2] + t[3]); y = row32_sum(y);
;         if ((lane & 31) == 0) sy[k * 64 + p] = y; }
.LBB0_469:
	s_or_b64 exec, exec, s[14:15]
	ds_read_b32 v78, v81 offset:2176
	s_waitcnt lgkmcnt(0)
	ds_read2_b32 v[76:77], v9 offset1:4
	v_lshl_add_u64 v[84:85], v[84:85], 0, s[44:45]
	v_lshl_add_u64 v[82:83], v[82:83], 0, s[44:45]
	s_and_b64 vcc, exec, s[8:9]
	s_waitcnt lgkmcnt(0)
	v_mul_f32_e32 v76, v78, v76
	v_mov_b32_e32 v78, v77
	v_pk_mul_f32 v[86:87], v[14:15], v[78:79] op_sel_hi:[1,0]
	v_pk_mul_f32 v[88:89], v[12:13], v[78:79] op_sel_hi:[1,0]
	v_pk_fma_f32 v[78:79], v[74:75], v[76:77], v[86:87] op_sel_hi:[1,0,1]
	v_pk_fma_f32 v[76:77], v[72:73], v[76:77], v[88:89] op_sel_hi:[1,0,1]
	global_store_dwordx4 v[82:83], v[76:79], off
	s_cbranch_vccnz .LBB0_471
	global_load_dwordx4 v[12:15], v[84:85], off

; #define LAUNDER_PTR(p) do {} while (0)
; #define LAUNDER_PTR(p) asm volatile("" : "+v"(p))
; __device__ __forceinline__ float row32_sum(float s) { s += SHFL_XOR(s, 1); s += SHFL_XOR(s, 2); s += SHFL_XOR(s, 4); s += SHFL_XOR(s, 8); s += SHFL_XOR(s, 16); return s; }
; __device__ __forceinline__ void ssd_sample_step(const bf16* proj, const float* conv_w, const float* conv_b, const float* dt_bias, const float* a_log, const float* d_skip, const float* ssm_norm, ...
;     ...
; #pragma unroll
;     for (int it = 0; it < 16; ++it) { const int k = it >> 2, p = (it & 3) * 16 + pr_; const float xdt = sx[k * 64 + p] * sdt[k];
;         const f32x4 hn = st[it] * sdec[k] + Bv * xdt; LAUNDER_PTR(op); *(f32x4*)op = hn; op += 2048;
;         LAUNDER_PTR(np); if (bg_next >= 0) st[it] = *(const f32x4*)np; np += 2048;
;         const f32x4 t = hn * Cv; float y = (t[0] + t[1]) + (t[2] + t[3]); y = row32_sum(y);
;         if ((lane & 31) == 0) sy[k * 64 + p] = y; }
.LBB0_473:
	s_or_b64 exec, exec, s[14:15]
	ds_read_b32 v78, v81 offset:2240
	s_waitcnt lgkmcnt(0)
	ds_read2_b32 v[76:77], v9 offset1:4
	v_lshl_add_u64 v[84:85], v[84:85], 0, s[44:45]
	v_lshl_add_u64 v[82:83], v[82:83], 0, s[44:45]
	s_and_b64 vcc, exec, s[8:9]
	s_waitcnt lgkmcnt(0)
	v_mul_f32_e32 v76, v78, v76
	v_mov_b32_e32 v78, v77
	v_pk_mul_f32 v[86:87], v[18:19], v[78:79] op_sel_hi:[1,0]
	v_pk_mul_f32 v[88:89], v[16:17], v[78:79] op_sel_hi:[1,0]
	v_pk_fma_f32 v[78:79], v[74:75], v[76:77], v[86:87] op_sel_hi:[1,0,1]
	v_pk_fma_f32 v[76:77], v[72:73], v[76:77], v[88:89] op_sel_hi:[1,0,1]
	global_store_dwordx4 v[82:83], v[76:79], off
	s_cbranch_vccnz .LBB0_475
	global_load_dwordx4 v[16:19], v[84:85], off

; #define LAUNDER_PTR(p) do {} while (0)
; #define LAUNDER_PTR(p) asm volatile("" : "+v"(p))
; __device__ __forceinline__ float row32_sum(float s) { s += SHFL_XOR(s, 1); s += SHFL_XOR(s, 2); s += SHFL_XOR(s, 4); s += SHFL_XOR(s, 8); s += SHFL_XOR(s, 16); return s; }
; __device__ __forceinline__ void ssd_sample_step(const bf16* proj, const float* conv_w, const float* conv_b, const float* dt_bias, const float* a_log, const float* d_skip, const float* ssm_norm, ...
;     ...
; #pragma unroll
;     for (int it = 0; it < 16; ++it) { const int k = it >> 2, p = (it & 3) * 16 + pr_; const float xdt = sx[k * 64 + p] * sdt[k];
;         const f32x4 hn = st[it] * sdec[k] + Bv * xdt; LAUNDER_PTR(op); *(f32x4*)op = hn; op += 2048;
;         LAUNDER_PTR(np); if (bg_next >= 0) st[it] = *(const f32x4*)np; np += 2048;
;         const f32x4 t = hn * Cv; float y = (t[0] + t[1]) + (t[2] + t[3]); y = row32_sum(y);
;         if ((lane & 31) == 0) sy[k * 64 + p] = y; }
.LBB0_477:
	s_or_b64 exec, exec, s[14:15]
	ds_read_b32 v78, v81 offset:2304
	s_waitcnt lgkmcnt(0)
	ds_read2_b32 v[76:77], v9 offset0:1 offset1:5
	v_lshl_add_u64 v[84:85], v[84:85], 0, s[44:45]
	v_lshl_add_u64 v[82:83], v[82:83], 0, s[44:45]
	s_and_b64 vcc, exec, s[8:9]
	s_waitcnt lgkmcnt(0)
	v_mul_f32_e32 v76, v78, v76
	v_mov_b32_e32 v78, v77
	v_pk_mul_f32 v[86:87], v[22:23], v[78:79] op_sel_hi:[1,0]
	v_pk_mul_f32 v[88:89], v[20:21], v[78:79] op_sel_hi:[1,0]
	v_pk_fma_f32 v[78:79], v[74:75], v[76:77], v[86:87] op_sel_hi:[1,0,1]
	v_pk_fma_f32 v[76:77], v[72:73], v[76:77], v[88:89] op_sel_hi:[1,0,1]
	global_store_dwordx4 v[82:83], v[76:79], off
	s_cbranch_vccnz .LBB0_479
	global_load_dwordx4 v[20:23], v[84:85], off

; #define LAUNDER_PTR(p) do {} while (0)
; #define LAUNDER_PTR(p) asm volatile("" : "+v"(p))
; __device__ __forceinline__ float row32_sum(float s) { s += SHFL_XOR(s, 1); s += SHFL_XOR(s, 2); s += SHFL_XOR(s, 4); s += SHFL_XOR(s, 8); s += SHFL_XOR(s, 16); return s; }
; __device__ __forceinline__ void ssd_sample_step(const bf16* proj, const float* conv_w, const float* conv_b, const float* dt_bias, const float* a_log, const float* d_skip, const float* ssm_norm, ...
;     ...
; #pragma unroll
;     for (int it = 0; it < 16; ++it) { const int k = it >> 2, p = (it & 3) * 16 + pr_; const float xdt = sx[k * 64 + p] * sdt[k];
;         const f32x4 hn = st[it] * sdec[k] + Bv * xdt; LAUNDER_PTR(op); *(f32x4*)op = hn; op += 2048;
;         LAUNDER_PTR(np); if (bg_next >= 0) st[it] = *(const f32x4*)np; np += 2048;
;         const f32x4 t = hn * Cv; float y = (t[0] + t[1]) + (t[2] + t[3]); y = row32_sum(y);
;         if ((lane & 31) == 0) sy[k * 64 + p] = y; }
.LBB0_481:
	s_or_b64 exec, exec, s[14:15]
	ds_read_b32 v78, v81 offset:2368
	s_waitcnt lgkmcnt(0)
	ds_read2_b32 v[76:77], v9 offset0:1 offset1:5
	v_lshl_add_u64 v[84:85], v[84:85], 0, s[44:45]
	v_lshl_add_u64 v[82:83], v[82:83], 0, s[44:45]
	s_and_b64 vcc, exec, s[8:9]
	s_waitcnt lgkmcnt(0)
	v_mul_f32_e32 v76, v78, v76
	v_mov_b32_e32 v78, v77
	v_pk_mul_f32 v[86:87], v[26:27], v[78:79] op_sel_hi:[1,0]
	v_pk_mul_f32 v[88:89], v[24:25], v[78:79] op_sel_hi:[1,0]
	v_pk_fma_f32 v[78:79], v[74:75], v[76:77], v[86:87] op_sel_hi:[1,0,1]
	v_pk_fma_f32 v[76:77], v[72:73], v[76:77], v[88:89] op_sel_hi:[1,0,1]
	global_store_dwordx4 v[82:83], v[76:79], off
	s_cbranch_vccnz .LBB0_483
	global_load_dwordx4 v[24:27], v[84:85], off

; #define LAUNDER_PTR(p) do {} while (0)
; #define LAUNDER_PTR(p) asm volatile("" : "+v"(p))
; __device__ __forceinline__ float row32_sum(float s) { s += SHFL_XOR(s, 1); s += SHFL_XOR(s, 2); s += SHFL_XOR(s, 4); s += SHFL_XOR(s, 8); s += SHFL_XOR(s, 16); return s; }
; __device__ __forceinline__ void ssd_sample_step(const bf16* proj, const float* conv_w, const float* conv_b, const float* dt_bias, const float* a_log, const float* d_skip, const float* ssm_norm, ...
;     ...
; #pragma unroll
;     for (int it = 0; it < 16; ++it) { const int k = it >> 2, p = (it & 3) * 16 + pr_; const float xdt = sx[k * 64 + p] * sdt[k];
;         const f32x4 hn = st[it] * sdec[k] + Bv * xdt; LAUNDER_PTR(op); *(f32x4*)op = hn; op += 2048;
;         LAUNDER_PTR(np); if (bg_next >= 0) st[it] = *(const f32x4*)np; np += 2048;
;         const f32x4 t = hn * Cv; float y = (t[0] + t[1]) + (t[2] + t[3]); y = row32_sum(y);
;         if ((lane & 31) == 0) sy[k * 64 + p] = y; }
.LBB0_485:
	s_or_b64 exec, exec, s[14:15]
	ds_read_b32 v78, v81 offset:2432
	s_waitcnt lgkmcnt(0)
	ds_read2_b32 v[76:77], v9 offset0:1 offset1:5
	v_lshl_add_u64 v[84:85], v[84:85], 0, s[44:45]
	v_lshl_add_u64 v[82:83], v[82:83], 0, s[44:45]
	s_and_b64 vcc, exec, s[8:9]
	s_waitcnt lgkmcnt(0)
	v_mul_f32_e32 v76, v78, v76
	v_mov_b32_e32 v78, v77
	v_pk_mul_f32 v[86:87], v[30:31], v[78:79] op_sel_hi:[1,0]
	v_pk_mul_f32 v[88:89], v[28:29], v[78:79] op_sel_hi:[1,0]
	v_pk_fma_f32 v[78:79], v[74:75], v[76:77], v[86:87] op_sel_hi:[1,0,1]
	v_pk_fma_f32 v[76:77], v[72:73], v[76:77], v[88:89] op_sel_hi:[1,0,1]
	global_store_dwordx4 v[82:83], v[76:79], off
	s_cbranch_vccnz .LBB0_487
	global_load_dwordx4 v[28:31], v[84:85], off

; #define LAUNDER_PTR(p) do {} while (0)
; #define LAUNDER_PTR(p) asm volatile("" : "+v"(p))
; __device__ __forceinline__ float row32_sum(float s) { s += SHFL_XOR(s, 1); s += SHFL_XOR(s, 2); s += SHFL_XOR(s, 4); s += SHFL_XOR(s, 8); s += SHFL_XOR(s, 16); return s; }
; __device__ __forceinline__ void ssd_sample_step(const bf16* proj, const float* conv_w, const float* conv_b, const float* dt_bias, const float* a_log, const float* d_skip, const float* ssm_norm, ...
;     ...
; #pragma unroll
;     for (int it = 0; it < 16; ++it) { const int k = it >> 2, p = (it & 3) * 16 + pr_; const float xdt = sx[k * 64 + p] * sdt[k];
;         const f32x4 hn = st[it] * sdec[k] + Bv * xdt; LAUNDER_PTR(op); *(f32x4*)op = hn; op += 2048;
;         LAUNDER_PTR(np); if (bg_next >= 0) st[it] = *(const f32x4*)np; np += 2048;
;         const f32x4 t = hn * Cv; float y = (t[0] + t[1]) + (t[2] + t[3]); y = row32_sum(y);
;         if ((lane & 31) == 0) sy[k * 64 + p] = y; }
.LBB0_489:
	s_or_b64 exec, exec, s[14:15]
	ds_read_b32 v78, v81 offset:2496
	s_waitcnt lgkmcnt(0)
	ds_read2_b32 v[76:77], v9 offset0:1 offset1:5
	v_lshl_add_u64 v[84:85], v[84:85], 0, s[44:45]
	v_lshl_add_u64 v[82:83], v[82:83], 0, s[44:45]
	s_and_b64 vcc, exec, s[8:9]
	s_waitcnt lgkmcnt(0)
	v_mul_f32_e32 v76, v78, v76
	v_mov_b32_e32 v78, v77
	v_pk_mul_f32 v[86:87], v[34:35], v[78:79] op_sel_hi:[1,0]
	v_pk_mul_f32 v[88:89], v[32:33], v[78:79] op_sel_hi:[1,0]
	v_pk_fma_f32 v[78:79], v[74:75], v[76:77], v[86:87] op_sel_hi:[1,0,1]
	v_pk_fma_f32 v[76:77], v[72:73], v[76:77], v[88:89] op_sel_hi:[1,0,1]
	global_store_dwordx4 v[82:83], v[76:79], off
	s_cbranch_vccnz .LBB0_491
	global_load_dwordx4 v[32:35], v[84:85], off

; #define LAUNDER_PTR(p) do {} while (0)
; #define LAUNDER_PTR(p) asm volatile("" : "+v"(p))
; __device__ __forceinline__ float row32_sum(float s) { s += SHFL_XOR(s, 1); s += SHFL_XOR(s, 2); s += SHFL_XOR(s, 4); s += SHFL_XOR(s, 8); s += SHFL_XOR(s, 16); return s; }
; __device__ __forceinline__ void ssd_sample_step(const bf16* proj, const float* conv_w, const float* conv_b, const float* dt_bias, const float* a_log, const float* d_skip, const float* ssm_norm, ...
;     ...
; #pragma unroll
;     for (int it = 0; it < 16; ++it) { const int k = it >> 2, p = (it & 3) * 16 + pr_; const float xdt = sx[k * 64 + p] * sdt[k];
;         const f32x4 hn = st[it] * sdec[k] + Bv * xdt; LAUNDER_PTR(op); *(f32x4*)op = hn; op += 2048;
;         LAUNDER_PTR(np); if (bg_next >= 0) st[it] = *(const f32x4*)np; np += 2048;
;         const f32x4 t = hn * Cv; float y = (t[0] + t[1]) + (t[2] + t[3]); y = row32_sum(y);
;         if ((lane & 31) == 0) sy[k * 64 + p] = y; }
.LBB0_493:
	s_or_b64 exec, exec, s[14:15]
	ds_read_b32 v78, v81 offset:2560
	s_waitcnt lgkmcnt(0)
	ds_read2_b32 v[76:77], v9 offset0:2 offset1:6
	v_lshl_add_u64 v[84:85], v[84:85], 0, s[44:45]
	v_lshl_add_u64 v[82:83], v[82:83], 0, s[44:45]
	s_and_b64 vcc, exec, s[8:9]
	s_waitcnt lgkmcnt(0)
	v_mul_f32_e32 v76, v78, v76
	v_mov_b32_e32 v78, v77
	v_pk_mul_f32 v[86:87], v[38:39], v[78:79] op_sel_hi:[1,0]
	v_pk_mul_f32 v[88:89], v[36:37], v[78:79] op_sel_hi:[1,0]
	v_pk_fma_f32 v[78:79], v[74:75], v[76:77], v[86:87] op_sel_hi:[1,0,1]
	v_pk_fma_f32 v[76:77], v[72:73], v[76:77], v[88:89] op_sel_hi:[1,0,1]
	global_store_dwordx4 v[82:83], v[76:79], off
	s_cbranch_vccnz .LBB0_495
	global_load_dwordx4 v[36:39], v[84:85], off

; #define LAUNDER_PTR(p) do {} while (0)
; #define LAUNDER_PTR(p) asm volatile("" : "+v"(p))
; __device__ __forceinline__ float row32_sum(float s) { s += SHFL_XOR(s, 1); s += SHFL_XOR(s, 2); s += SHFL_XOR(s, 4); s += SHFL_XOR(s, 8); s += SHFL_XOR(s, 16); return s; }
; __device__ __forceinline__ void ssd_sample_step(const bf16* proj, const float* conv_w, const float* conv_b, const float* dt_bias, const float* a_log, const float* d_skip, const float* ssm_norm, ...
;     ...
; #pragma unroll
;     for (int it = 0; it < 16; ++it) { const int k = it >> 2, p = (it & 3) * 16 + pr_; const float xdt = sx[k * 64 + p] * sdt[k];
;         const f32x4 hn = st[it] * sdec[k] + Bv * xdt; LAUNDER_PTR(op); *(f32x4*)op = hn; op += 2048;
;         LAUNDER_PTR(np); if (bg_next >= 0) st[it] = *(const f32x4*)np; np += 2048;
;         const f32x4 t = hn * Cv; float y = (t[0] + t[1]) + (t[2] + t[3]); y = row32_sum(y);
;         if ((lane & 31) == 0) sy[k * 64 + p] = y; }
.LBB0_497:
	s_or_b64 exec, exec, s[14:15]
	ds_read_b32 v78, v81 offset:2624
	s_waitcnt lgkmcnt(0)
	ds_read2_b32 v[76:77], v9 offset0:2 offset1:6
	v_lshl_add_u64 v[84:85], v[84:85], 0, s[44:45]
	v_lshl_add_u64 v[82:83], v[82:83], 0, s[44:45]
	s_and_b64 vcc, exec, s[8:9]
	s_waitcnt lgkmcnt(0)
	v_mul_f32_e32 v76, v78, v76
	v_mov_b32_e32 v78, v77
	v_pk_mul_f32 v[86:87], v[42:43], v[78:79] op_sel_hi:[1,0]
	v_pk_mul_f32 v[88:89], v[40:41], v[78:79] op_sel_hi:[1,0]
	v_pk_fma_f32 v[78:79], v[74:75], v[76:77], v[86:87] op_sel_hi:[1,0,1]
	v_pk_fma_f32 v[76:77], v[72:73], v[76:77], v[88:89] op_sel_hi:[1,0,1]
	global_store_dwordx4 v[82:83], v[76:79], off
	s_cbranch_vccnz .LBB0_499
	global_load_dwordx4 v[40:43], v[84:85], off

; #define LAUNDER_PTR(p) do {} while (0)
; #define LAUNDER_PTR(p) asm volatile("" : "+v"(p))
; __device__ __forceinline__ float row32_sum(float s) { s += SHFL_XOR(s, 1); s += SHFL_XOR(s, 2); s += SHFL_XOR(s, 4); s += SHFL_XOR(s, 8); s += SHFL_XOR(s, 16); return s; }
; __device__ __forceinline__ void ssd_sample_step(const bf16* proj, const float* conv_w, const float* conv_b, const float* dt_bias, const float* a_log, const float* d_skip, const float* ssm_norm, ...
;     ...
; #pragma unroll
;     for (int it = 0; it < 16; ++it) { const int k = it >> 2, p = (it & 3) * 16 + pr_; const float xdt = sx[k * 64 + p] * sdt[k];
;         const f32x4 hn = st[it] * sdec[k] + Bv * xdt; LAUNDER_PTR(op); *(f32x4*)op = hn; op += 2048;
;         LAUNDER_PTR(np); if (bg_next >= 0) st[it] = *(const f32x4*)np; np += 2048;
;         const f32x4 t = hn * Cv; float y = (t[0] + t[1]) + (t[2] + t[3]); y = row32_sum(y);
;         if ((lane & 31) == 0) sy[k * 64 + p] = y; }
.LBB0_501:
	s_or_b64 exec, exec, s[14:15]
	ds_read_b32 v78, v81 offset:2688
	s_waitcnt lgkmcnt(0)
	ds_read2_b32 v[76:77], v9 offset0:2 offset1:6
	v_lshl_add_u64 v[84:85], v[84:85], 0, s[44:45]
	v_lshl_add_u64 v[82:83], v[82:83], 0, s[44:45]
	s_and_b64 vcc, exec, s[8:9]
	s_waitcnt lgkmcnt(0)
	v_mul_f32_e32 v76, v78, v76
	v_mov_b32_e32 v78, v77
	v_pk_mul_f32 v[86:87], v[46:47], v[78:79] op_sel_hi:[1,0]
	v_pk_mul_f32 v[88:89], v[44:45], v[78:79] op_sel_hi:[1,0]
	v_pk_fma_f32 v[78:79], v[74:75], v[76:77], v[86:87] op_sel_hi:[1,0,1]
	v_pk_fma_f32 v[76:77], v[72:73], v[76:77], v[88:89] op_sel_hi:[1,0,1]
	global_store_dwordx4 v[82:83], v[76:79], off
	s_cbranch_vccnz .LBB0_503
	global_load_dwordx4 v[44:47], v[84:85], off

; #define LAUNDER_PTR(p) do {} while (0)
; #define LAUNDER_PTR(p) asm volatile("" : "+v"(p))
; __device__ __forceinline__ float row32_sum(float s) { s += SHFL_XOR(s, 1); s += SHFL_XOR(s, 2); s += SHFL_XOR(s, 4); s += SHFL_XOR(s, 8); s += SHFL_XOR(s, 16); return s; }
; __device__ __forceinline__ void ssd_sample_step(const bf16* proj, const float* conv_w, const float* conv_b, const float* dt_bias, const float* a_log, const float* d_skip, const float* ssm_norm, ...
;     ...
; #pragma unroll
;     for (int it = 0; it < 16; ++it) { const int k = it >> 2, p = (it & 3) * 16 + pr_; const float xdt = sx[k * 64 + p] * sdt[k];
;         const f32x4 hn = st[it] * sdec[k] + Bv * xdt; LAUNDER_PTR(op); *(f32x4*)op = hn; op += 2048;
;         LAUNDER_PTR(np); if (bg_next >= 0) st[it] = *(const f32x4*)np; np += 2048;
;         const f32x4 t = hn * Cv; float y = (t[0] + t[1]) + (t[2] + t[3]); y = row32_sum(y);
;         if ((lane & 31) == 0) sy[k * 64 + p] = y; }
.LBB0_505:
	s_or_b64 exec, exec, s[14:15]
	ds_read_b32 v78, v81 offset:2752
	s_waitcnt lgkmcnt(0)
	ds_read2_b32 v[76:77], v9 offset0:2 offset1:6
	v_lshl_add_u64 v[84:85], v[84:85], 0, s[44:45]
	v_lshl_add_u64 v[82:83], v[82:83], 0, s[44:45]
	s_and_b64 vcc, exec, s[8:9]
	s_waitcnt lgkmcnt(0)
	v_mul_f32_e32 v76, v78, v76
	v_mov_b32_e32 v78, v77
	v_pk_mul_f32 v[86:87], v[50:51], v[78:79] op_sel_hi:[1,0]
	v_pk_mul_f32 v[88:89], v[48:49], v[78:79] op_sel_hi:[1,0]
	v_pk_fma_f32 v[78:79], v[74:75], v[76:77], v[86:87] op_sel_hi:[1,0,1]
	v_pk_fma_f32 v[76:77], v[72:73], v[76:77], v[88:89] op_sel_hi:[1,0,1]
	global_store_dwordx4 v[82:83], v[76:79], off
	s_cbranch_vccnz .LBB0_507
	global_load_dwordx4 v[48:51], v[84:85], off

; #define LAUNDER_PTR(p) do {} while (0)
; #define LAUNDER_PTR(p) asm volatile("" : "+v"(p))
; __device__ __forceinline__ float row32_sum(float s) { s += SHFL_XOR(s, 1); s += SHFL_XOR(s, 2); s += SHFL_XOR(s, 4); s += SHFL_XOR(s, 8); s += SHFL_XOR(s, 16); return s; }
; __device__ __forceinline__ void ssd_sample_step(const bf16* proj, const float* conv_w, const float* conv_b, const float* dt_bias, const float* a_log, const float* d_skip, const float* ssm_norm, ...
;     ...
; #pragma unroll
;     for (int it = 0; it < 16; ++it) { const int k = it >> 2, p = (it & 3) * 16 + pr_; const float xdt = sx[k * 64 + p] * sdt[k];
;         const f32x4 hn = st[it] * sdec[k] + Bv * xdt; LAUNDER_PTR(op); *(f32x4*)op = hn; op += 2048;
;         LAUNDER_PTR(np); if (bg_next >= 0) st[it] = *(const f32x4*)np; np += 2048;
;         const f32x4 t = hn * Cv; float y = (t[0] + t[1]) + (t[2] + t[3]); y = row32_sum(y);
;         if ((lane & 31) == 0) sy[k * 64 + p] = y; }
.LBB0_509:
	s_or_b64 exec, exec, s[14:15]
	ds_read_b32 v78, v81 offset:2816
	s_waitcnt lgkmcnt(0)
	ds_read2_b32 v[76:77], v9 offset0:3 offset1:7
	v_lshl_add_u64 v[84:85], v[84:85], 0, s[44:45]
	v_lshl_add_u64 v[82:83], v[82:83], 0, s[44:45]
	s_and_b64 vcc, exec, s[8:9]
	s_waitcnt lgkmcnt(0)
	v_mul_f32_e32 v76, v78, v76
	v_mov_b32_e32 v78, v77
	v_pk_mul_f32 v[86:87], v[54:55], v[78:79] op_sel_hi:[1,0]
	v_pk_mul_f32 v[88:89], v[52:53], v[78:79] op_sel_hi:[1,0]
	v_pk_fma_f32 v[78:79], v[74:75], v[76:77], v[86:87] op_sel_hi:[1,0,1]
	v_pk_fma_f32 v[76:77], v[72:73], v[76:77], v[88:89] op_sel_hi:[1,0,1]
	global_store_dwordx4 v[82:83], v[76:79], off
	s_cbranch_vccnz .LBB0_511
	global_load_dwordx4 v[52:55], v[84:85], off

; #define LAUNDER_PTR(p) do {} while (0)
; #define LAUNDER_PTR(p) asm volatile("" : "+v"(p))
; __device__ __forceinline__ float row32_sum(float s) { s += SHFL_XOR(s, 1); s += SHFL_XOR(s, 2); s += SHFL_XOR(s, 4); s += SHFL_XOR(s, 8); s += SHFL_XOR(s, 16); return s; }
; __device__ __forceinline__ void ssd_sample_step(const bf16* proj, const float* conv_w, const float* conv_b, const float* dt_bias, const float* a_log, const float* d_skip, const float* ssm_norm, ...
;     ...
; #pragma unroll
;     for (int it = 0; it < 16; ++it) { const int k = it >> 2, p = (it & 3) * 16 + pr_; const float xdt = sx[k * 64 + p] * sdt[k];
;         const f32x4 hn = st[it] * sdec[k] + Bv * xdt; LAUNDER_PTR(op); *(f32x4*)op = hn; op += 2048;
;         LAUNDER_PTR(np); if (bg_next >= 0) st[it] = *(const f32x4*)np; np += 2048;
;         const f32x4 t = hn * Cv; float y = (t[0] + t[1]) + (t[2] + t[3]); y = row32_sum(y);
;         if ((lane & 31) == 0) sy[k * 64 + p] = y; }
.LBB0_513:
	s_or_b64 exec, exec, s[14:15]
	ds_read_b32 v78, v81 offset:2880
	s_waitcnt lgkmcnt(0)
	ds_read2_b32 v[76:77], v9 offset0:3 offset1:7
	v_lshl_add_u64 v[84:85], v[84:85], 0, s[44:45]
	v_lshl_add_u64 v[82:83], v[82:83], 0, s[44:45]
	s_and_b64 vcc, exec, s[8:9]
	s_waitcnt lgkmcnt(0)
	v_mul_f32_e32 v76, v78, v76
	v_mov_b32_e32 v78, v77
	v_pk_mul_f32 v[86:87], v[58:59], v[78:79] op_sel_hi:[1,0]
	v_pk_mul_f32 v[88:89], v[56:57], v[78:79] op_sel_hi:[1,0]
	v_pk_fma_f32 v[78:79], v[74:75], v[76:77], v[86:87] op_sel_hi:[1,0,1]
	v_pk_fma_f32 v[76:77], v[72:73], v[76:77], v[88:89] op_sel_hi:[1,0,1]
	global_store_dwordx4 v[82:83], v[76:79], off
	s_cbranch_vccnz .LBB0_515
	global_load_dwordx4 v[56:59], v[84:85], off

; #define LAUNDER_PTR(p) do {} while (0)
; #define LAUNDER_PTR(p) asm volatile("" : "+v"(p))
; __device__ __forceinline__ float row32_sum(float s) { s += SHFL_XOR(s, 1); s += SHFL_XOR(s, 2); s += SHFL_XOR(s, 4); s += SHFL_XOR(s, 8); s += SHFL_XOR(s, 16); return s; }
; __device__ __forceinline__ void ssd_sample_step(const bf16* proj, const float* conv_w, const float* conv_b, const float* dt_bias, const float* a_log, const float* d_skip, const float* ssm_norm, ...
;     ...
; #pragma unroll
;     for (int it = 0; it < 16; ++it) { const int k = it >> 2, p = (it & 3) * 16 + pr_; const float xdt = sx[k * 64 + p] * sdt[k];
;         const f32x4 hn = st[it] * sdec[k] + Bv * xdt; LAUNDER_PTR(op); *(f32x4*)op = hn; op += 2048;
;         LAUNDER_PTR(np); if (bg_next >= 0) st[it] = *(const f32x4*)np; np += 2048;
;         const f32x4 t = hn * Cv; float y = (t[0] + t[1]) + (t[2] + t[3]); y = row32_sum(y);
;         if ((lane & 31) == 0) sy[k * 64 + p] = y; }
.LBB0_517:
	s_or_b64 exec, exec, s[14:15]
	ds_read_b32 v78, v81 offset:2944
	s_waitcnt lgkmcnt(0)
	ds_read2_b32 v[76:77], v9 offset0:3 offset1:7
	v_lshl_add_u64 v[84:85], v[84:85], 0, s[44:45]
	v_lshl_add_u64 v[82:83], v[82:83], 0, s[44:45]
	s_and_b64 vcc, exec, s[8:9]
	s_waitcnt lgkmcnt(0)
	v_mul_f32_e32 v76, v78, v76
	v_mov_b32_e32 v78, v77
	v_pk_mul_f32 v[86:87], v[62:63], v[78:79] op_sel_hi:[1,0]
	v_pk_mul_f32 v[88:89], v[60:61], v[78:79] op_sel_hi:[1,0]
	v_pk_fma_f32 v[78:79], v[74:75], v[76:77], v[86:87] op_sel_hi:[1,0,1]
	v_pk_fma_f32 v[76:77], v[72:73], v[76:77], v[88:89] op_sel_hi:[1,0,1]
	global_store_dwordx4 v[82:83], v[76:79], off
	s_cbranch_vccnz .LBB0_519
	global_load_dwordx4 v[60:63], v[84:85], off

; #define LAUNDER_PTR(p) do {} while (0)
; #define LAUNDER_PTR(p) asm volatile("" : "+v"(p))
; __device__ __forceinline__ float row32_sum(float s) { s += SHFL_XOR(s, 1); s += SHFL_XOR(s, 2); s += SHFL_XOR(s, 4); s += SHFL_XOR(s, 8); s += SHFL_XOR(s, 16); return s; }
; __device__ __forceinline__ void ssd_sample_step(const bf16* proj, const float* conv_w, const float* conv_b, const float* dt_bias, const float* a_log, const float* d_skip, const float* ssm_norm, ...
;     ...
; #pragma unroll
;     for (int it = 0; it < 16; ++it) { const int k = it >> 2, p = (it & 3) * 16 + pr_; const float xdt = sx[k * 64 + p] * sdt[k];
;         const f32x4 hn = st[it] * sdec[k] + Bv * xdt; LAUNDER_PTR(op); *(f32x4*)op = hn; op += 2048;
;         LAUNDER_PTR(np); if (bg_next >= 0) st[it] = *(const f32x4*)np; np += 2048;
;         const f32x4 t = hn * Cv; float y = (t[0] + t[1]) + (t[2] + t[3]); y = row32_sum(y);
;         if ((lane & 31) == 0) sy[k * 64 + p] = y; }
.LBB0_521:
	s_or_b64 exec, exec, s[14:15]
	ds_read_b32 v86, v81 offset:3008
	ds_read2_b32 v[78:79], v9 offset0:3 offset1:7
	s_waitcnt lgkmcnt(0)
	v_lshl_add_u64 v[76:77], v[84:85], 0, s[44:45]
	v_lshl_add_u64 v[82:83], v[82:83], 0, s[44:45]
	s_and_b64 vcc, exec, s[8:9]
	v_mov_b32_e32 v84, v79
	v_mul_f32_e32 v78, v86, v78
	v_pk_mul_f32 v[86:87], v[66:67], v[84:85] op_sel_hi:[1,0]
	v_pk_mul_f32 v[84:85], v[64:65], v[84:85] op_sel_hi:[1,0]
	v_pk_fma_f32 v[74:75], v[74:75], v[78:79], v[86:87] op_sel_hi:[1,0,1]
	v_pk_fma_f32 v[72:73], v[72:73], v[78:79], v[84:85] op_sel_hi:[1,0,1]
	global_store_dwordx4 v[82:83], v[72:75], off
	s_cbranch_vccnz .LBB0_523
	global_load_dwordx4 v[64:67], v[76:77], off

; __device__ __forceinline__ float bf2f(bf16 v) { return __uint_as_float(((unsigned)v) << 16); }
; __device__ __forceinline__ float siluf_(float x) { return x * frcp_(1.0f + __expf(-x)); }
; __device__ __forceinline__ float row32_sum(float s) { s += SHFL_XOR(s, 1); s += SHFL_XOR(s, 2); s += SHFL_XOR(s, 4); s += SHFL_XOR(s, 8); s += SHFL_XOR(s, 16); return s; }
; __device__ __forceinline__ void ssd_sample_step(const bf16* proj, const float* conv_w, const float* conv_b, const float* dt_bias, const float* a_log, const float* d_skip, const float* ssm_norm, ...
;     ...
;     float yv = 0.f;
;     if (tid < 256) { const int k = tid >> 6; const float z = bf2f(proj[row * LDP + PC_Z + grp * 256 + tid]);
;         yv = (sy[tid] + d_skip[grp * 4 + k] * sx[tid]) * siluf_(z);
;         float ss = yv * yv; ss = row32_sum(ss); if ((lane & 31) == 0) sred[tid >> 5] = ss; }
.LBB0_525:
	s_or_b64 exec, exec, s[8:9]
	s_waitcnt lgkmcnt(0)
	v_mov_b32_e32 v68, 0
	v_ashrrev_i32_e32 v9, 31, v8
	s_barrier
	s_and_saveexec_b64 s[8:9], s[4:5]
	s_cbranch_execz .LBB0_529
	s_lshl_b32 s14, s50, 9
	s_add_u32 s10, s10, s14
	s_addc_u32 s11, s11, 0
	v_lshl_add_u64 v[68:69], v[8:9], 1, s[10:11]
	v_add_co_u32_e32 v68, vcc, 0x2000, v68
	v_readlane_b32 s10, v255, 32
	s_nop 0
	v_addc_co_u32_e32 v69, vcc, 0, v69, vcc
	global_load_ushort v70, v[68:69], off
	v_ashrrev_i32_e32 v68, 6, v8
	v_add_u32_e32 v68, s58, v68
	v_ashrrev_i32_e32 v69, 31, v68
	v_readlane_b32 s11, v255, 33
	ds_read2st64_b32 v[72:73], v10 offset0:8 offset1:18
	s_waitcnt vmcnt(0) lgkmcnt(0)
	v_lshlrev_b32_e32 v71, 16, v70
	v_lshl_add_u64 v[68:69], v[68:69], 2, s[10:11]
	global_load_dword v68, v[68:69], off
	v_mul_f32_e32 v69, 0xbfb8aa3b, v71
	v_exp_f32_e32 v69, v69
	v_mov_b32_e32 v70, v72
	v_add_f32_e32 v10, 1.0, v69
	v_rcp_f32_e32 v69, v10
	s_waitcnt vmcnt(0)
	v_pk_mul_f32 v[68:69], v[68:69], v[70:71]
	s_nop 0
	v_add_f32_e32 v10, v73, v68
	v_mul_f32_e32 v68, v10, v69
	v_mul_f32_e32 v10, v68, v68
	ds_swizzle_b32 v10, v10 offset:swizzle(SWAP,1)
	s_waitcnt lgkmcnt(0)
	v_fmac_f32_e32 v10, v68, v68
	ds_swizzle_b32 v69, v10 offset:swizzle(SWAP,2)
	s_waitcnt lgkmcnt(0)
	v_add_f32_e32 v10, v10, v69
	ds_swizzle_b32 v69, v10 offset:swizzle(SWAP,4)
	s_waitcnt lgkmcnt(0)
	v_add_f32_e32 v10, v10, v69
	ds_swizzle_b32 v69, v10 offset:swizzle(SWAP,8)
	s_waitcnt lgkmcnt(0)
	v_add_f32_e32 v10, v10, v69
	ds_swizzle_b32 v69, v10 offset:swizzle(SWAP,16)
	s_and_saveexec_b64 s[10:11], s[6:7]
	s_cbranch_execz .LBB0_528
	s_waitcnt lgkmcnt(0)
	v_add_f32_e32 v10, v10, v69
	ds_write_b32 v81, v10 offset:16384

; __device__ __forceinline__ bf16 f2bf(float f) { return (bf16)pk2(f, f); }
; __device__ __forceinline__ void sync_threads() { __syncthreads(); }
; __device__ __forceinline__ void ssd_sample_step(const bf16* proj, const float* conv_w, const float* conv_b, const float* dt_bias, const float* a_log, const float* d_skip, const float* ssm_norm, ...
;     ...
;     sync_threads();
;     if (tid < 256) { float tot = 0.f;
; #pragma unroll
;         for (int r = 0; r < 8; ++r) tot += sred[r];
;         ybuf[row * 2048 + grp * 256 + tid] = f2bf(yv * rsqrtf(tot * (1.f / 256.f) + EPS) * ssm_norm[grp * 256 + tid]); }
.LBB0_529:
	s_or_b64 exec, exec, s[8:9]
	s_waitcnt lgkmcnt(0)
	s_barrier
	s_and_saveexec_b64 s[6:7], s[4:5]
	s_cbranch_execz .LBB0_438
	ds_read_b128 v[70:73], v11 offset:16384
	ds_read_b128 v[74:77], v11 offset:16400
	v_readlane_b32 s4, v255, 57
	v_ashrrev_i32_e32 v81, 31, v80
	v_readlane_b32 s5, v255, 58
	s_waitcnt lgkmcnt(0)
	v_add_f32_e32 v10, 0, v70
	v_add_f32_e32 v10, v10, v71
	v_add_f32_e32 v10, v10, v72
	v_add_f32_e32 v10, v10, v73
	v_add_f32_e32 v10, v10, v74
	v_add_f32_e32 v10, v10, v75
	v_add_f32_e32 v10, v10, v76
	v_add_f32_e32 v10, v10, v77
	v_fmamk_f32 v10, v10, 0x3b800000, v176
	v_cmp_gt_f32_e32 vcc, s33, v10
	v_mul_f32_e32 v69, 0x4b800000, v10
	s_lshl_b64 s[2:3], s[2:3], 12
	v_cndmask_b32_e32 v10, v10, v69, vcc
	v_rsq_f32_e32 v10, v10
	s_nop 0
	v_mul_f32_e32 v69, 0x45800000, v10
	v_cndmask_b32_e32 v10, v10, v69, vcc
	v_mul_f32_e32 v10, v68, v10
	v_lshl_add_u64 v[68:69], v[80:81], 2, s[4:5]
	global_load_dword v68, v[68:69], off
	v_readlane_b32 s4, v255, 49
	s_add_u32 s2, s4, s2
	v_readlane_b32 s4, v255, 50
	s_addc_u32 s3, s4, s3
	s_lshl_b32 s4, s50, 9
	s_add_u32 s2, s2, s4
	s_addc_u32 s3, s3, 0
	v_lshl_add_u64 v[8:9], v[8:9], 1, s[2:3]
	s_waitcnt vmcnt(0)
	v_mul_f32_e32 v10, v68, v10
	v_cvt_pk_bf16_f32 v10, v10, v10
	global_store_short v[8:9], v10, off
	s_branch .LBB0_438

; #define LAUNDER_PTR(p) do {} while (0)
; #define LAUNDER_PTR(p) asm volatile("" : "+v"(p))
; __device__ __forceinline__ void hgrn_sample_load(f32x4 (&st)[8], const float* state_in, int bh, int tid) {
;     const float* sp = state_in + (size_t)bh * 16384 + tid * 4;
; #pragma unroll
;     for (int it = 0; it < 8; ++it) { LAUNDER_PTR(sp); st[it] = *(const f32x4*)sp; sp += 2048; }
; }
.LBB0_534:
	v_readlane_b32 s0, v255, 34
	v_readlane_b32 s4, v253, 15
	v_readlane_b32 s1, v255, 35
	v_readlane_b32 s5, v253, 16
	s_lshl_b64 s[2:3], s[0:1], 26
	v_readlane_b32 s8, v253, 19
	v_readlane_b32 s4, v254, 11
	v_readlane_b32 s9, v253, 20
	s_add_u32 s0, s8, s2
	v_readlane_b32 s5, v254, 12
	s_addc_u32 s1, s9, s3
	s_and_b64 vcc, exec, s[4:5]
	v_readlane_b32 s6, v253, 17
	v_readlane_b32 s7, v253, 18
	v_readlane_b32 s10, v253, 21
	v_readlane_b32 s11, v253, 22
	v_readlane_b32 s12, v253, 23
	v_readlane_b32 s13, v253, 24
	v_readlane_b32 s14, v253, 25
	v_readlane_b32 s15, v253, 26
	v_readlane_b32 s16, v253, 27
	v_readlane_b32 s17, v253, 28
	v_readlane_b32 s18, v253, 29
	v_readlane_b32 s19, v253, 30
	s_cbranch_vccz .LBB0_536
	s_waitcnt vmcnt(0) lgkmcnt(0)
	v_mov_b32_e32 v0, v138
	v_readlane_b32 s4, v255, 4
	v_readlane_b32 s5, v255, 5
	s_add_u32 s4, s0, s4
	v_lshlrev_b32_e32 v0, 2, v0
	s_addc_u32 s5, s1, s5
	v_ashrrev_i32_e32 v1, 31, v0
	v_lshl_add_u64 v[4:5], v[0:1], 2, s[4:5]
	global_load_dwordx4 v[0:3], v[4:5], off
	v_lshl_add_u64 v[8:9], v[4:5], 0, s[44:45]
	global_load_dwordx4 v[4:7], v[8:9], off
	v_lshl_add_u64 v[8:9], v[8:9], 0, s[44:45]
	global_load_dwordx4 v[12:15], v[8:9], off
	v_lshl_add_u64 v[8:9], v[8:9], 0, s[44:45]
	global_load_dwordx4 v[16:19], v[8:9], off
	v_lshl_add_u64 v[8:9], v[8:9], 0, s[44:45]
	global_load_dwordx4 v[20:23], v[8:9], off
	v_lshl_add_u64 v[8:9], v[8:9], 0, s[44:45]
	global_load_dwordx4 v[24:27], v[8:9], off
	v_lshl_add_u64 v[8:9], v[8:9], 0, s[44:45]
	global_load_dwordx4 v[28:31], v[8:9], off
	v_lshl_add_u64 v[8:9], v[8:9], 0, s[44:45]
	global_load_dwordx4 v[32:35], v[8:9], off

; #define LAS __attribute__((address_space(3)))
; __device__ __forceinline__ void hgrn_pass1(const RecurBufs& rb, const float* lbs_l, int u, int tid, LAS unsigned char* lds) {
;     const int b = u >> 5, h = (u >> 2) & 7, seg = u & 3, lane = tid & 63, w = tid >> 6;
;     const int d = tid & 127, jq = tid >> 7;
;     LAS unsigned char* Qt = lds + HG_QT; LAS unsigned char* Kt = lds + HG_KT; LAS unsigned char* V = lds + HG_V; LAS float* part = (LAS float*)(lds + HG_PART); LAS float* vec = (LAS float*)(lds + HG_VEC1);
;     const float lb = lbs_l[h * 128 + d];
;     f32x4 S[8];
; #pragma unroll
;     for (int et = 0; et < 8; ++et) S[et] = (f32x4){0.f, 0.f, 0.f, 0.f};
;     float dprod = 1.f;
;     const int sr = tid >> 4, sc16 = tid & 15;
;     v4u pre[6];
;     {   const bf16* gq = rb.proj + ((size_t)b * SEQ + seg * SEGLEN + sr) * LDP + PC_Q + h * 128 + sc16 * 8;
;         pre[0] = *(const v4u*)gq; pre[1] = *(const v4u*)(gq + 32 * (size_t)LDP); pre[2] = *(const v4u*)(gq + PC_F); pre[3] = *(const v4u*)(gq + 32 * (size_t)LDP + PC_F);
;         pre[4] = *(const v4u*)(gq + PC_I); pre[5] = *(const v4u*)(gq + 32 * (size_t)LDP + PC_I); }
.LBB0_539:
	s_bfe_u32 s4, s16, 0x30002
	v_mov_b32_e32 v97, v138
	s_lshl_b32 s17, s4, 7
	v_and_b32_e32 v92, 0x7f, v97
	s_and_b32 s3, s18, 3
	s_ashr_i32 s2, s16, 5
	s_waitcnt vmcnt(0) lgkmcnt(0)
	v_or_b32_e32 v0, s17, v92
	s_and_b32 s19, s16, 3
	s_lshl_b32 s14, s3, 3
	s_lshl_b32 s23, s3, 9
	s_ashr_i32 s3, s2, 31
	v_lshlrev_b32_e32 v10, 2, v0
	s_lshl_b32 s5, s19, 9
	s_lshl_b32 s9, s2, 8
	v_ashrrev_i32_e32 v2, 4, v97
	s_lshl_b64 s[2:3], s[2:3], 11
	v_lshl_add_u64 v[0:1], s[96:97], 0, v[10:11]
	s_lshl_b32 s8, s4, 5
	s_lshl_b32 s64, s4, 8
	s_or_b32 s4, s2, s5
	s_mov_b32 s5, s3
	v_ashrrev_i32_e32 v3, 31, v2
	global_load_dword v93, v[0:1], off
	v_mov_b64_e32 v[0:1], s[78:79]
	v_lshl_add_u64 v[4:5], s[4:5], 0, v[2:3]
	v_mad_u64_u32 v[94:95], s[4:5], v4, s77, v[0:1]
	v_and_b32_e32 v12, 15, v97
	v_mad_i32_i24 v95, v5, s77, v95
	v_lshlrev_b32_e32 v10, 4, v12
	v_lshl_add_u64 v[0:1], v[94:95], 0, s[64:65]
	v_lshl_add_u64 v[0:1], v[0:1], 0, v[10:11]
	s_mov_b32 s4, 0xc4000
	v_add_co_u32_e32 v4, vcc, s4, v0
	s_movk_i32 s4, 0x1000
	s_nop 0
	v_addc_co_u32_e32 v5, vcc, 0, v1, vcc
	v_add_co_u32_e32 v6, vcc, s4, v0
	s_mov_b32 s4, 0xc5000
	s_nop 0
	v_addc_co_u32_e32 v7, vcc, 0, v1, vcc
	v_add_co_u32_e32 v8, vcc, s4, v0
	global_load_dwordx4 v[36:39], v[0:1], off
	s_nop 0
	v_addc_co_u32_e32 v9, vcc, 0, v1, vcc
	global_load_dwordx4 v[44:47], v[4:5], off
	global_load_dwordx4 v[40:43], v[0:1], off offset:2048
	global_load_dwordx4 v[48:51], v[4:5], off offset:2048
	global_load_dwordx4 v[52:55], v[6:7], off
	global_load_dwordx4 v[56:59], v[8:9], off
	v_lshlrev_b32_e32 v8, 2, v97
	v_ashrrev_i32_e32 v1, 2, v97
	s_or_b32 s28, s9, s8
	s_movk_i32 s15, 0x110
	v_lshrrev_b32_e32 v5, 1, v97
	v_bfe_u32 v6, v97, 2, 2
	v_mul_lo_u32 v7, v2, s15
	v_lshlrev_b32_e32 v112, 1, v92
	v_and_b32_e32 v1, -16, v1
	v_and_b32_e32 v9, 12, v8
	s_or_b32 s14, s28, s14
	v_mov_b32_e32 v101, 1.0
	v_ashrrev_i32_e32 v0, 7, v97
	v_and_or_b32 v5, v5, 24, v6
	v_add_u32_e32 v6, 0, v7
	v_add_u32_e32 v100, 0, v112
	v_lshl_add_u32 v7, v1, 2, 0
	v_or_b32_e32 v1, v9, v1
	s_mul_hi_i32 s29, s14, 0x600
	s_mul_i32 s50, s14, 0x600
	s_movk_i32 s14, 0x1100
	s_or_b32 s2, s2, s23
	v_lshlrev_b32_e32 v96, 3, v12
	v_cmp_lt_i32_e64 s[10:11], 0, v0
	v_cmp_lt_i32_e64 s[12:13], 1, v0
	v_cmp_lt_i32_e64 s[8:9], 2, v0
	v_mul_u32_u24_e32 v13, 0x110, v5
	v_mad_u32_u24 v5, v5, s15, 0
	v_lshl_add_u32 v106, v12, 2, v7
	v_lshl_add_u32 v12, v1, 1, 0
	v_mad_u64_u32 v[98:99], s[14:15], v0, s14, v[100:101]
	v_lshl_add_u64 v[0:1], s[2:3], 0, v[2:3]
	v_mov_b64_e32 v[2:3], s[64:65]
	s_movk_i32 s4, 0x80
	s_movk_i32 s6, 0x7f
	v_and_b32_e32 v4, 48, v97
	v_lshlrev_b32_e32 v9, 1, v9
	v_mad_u64_u32 v[2:3], s[2:3], v0, s77, v[2:3]
	v_mov_b32_e32 v0, 0
	s_mov_b32 s22, 7
	v_cmp_gt_u32_e64 s[4:5], s4, v97
	v_cmp_lt_u32_e64 s[6:7], s6, v97
	v_add_u32_e32 v109, 0, v8
	v_lshl_or_b32 v102, v92, 2, s50
	v_mov_b32_e32 v103, s29
	v_mad_i32_i24 v105, v1, s77, v3
	v_or_b32_e32 v104, v2, v10
	v_add_u32_e32 v108, v6, v10
	v_add_u32_e32 v107, v7, v4
	v_add_u32_e32 v99, v12, v13
	v_add_u32_e32 v9, v5, v9
	s_waitcnt vmcnt(0) lgkmcnt(0)
	v_sub_f32_e32 v110, 1.0, v93
	v_mov_b32_e32 v1, v0
	v_mov_b32_e32 v2, v0
	v_mov_b32_e32 v3, v0
	v_mov_b32_e32 v4, v0
	v_mov_b32_e32 v5, v0
	v_mov_b32_e32 v6, v0
	v_mov_b32_e32 v7, v0
	v_mov_b32_e32 v12, v0
	v_mov_b32_e32 v13, v0
	v_mov_b32_e32 v14, v0
	v_mov_b32_e32 v15, v0
	v_mov_b32_e32 v16, v0
	v_mov_b32_e32 v17, v0
	v_mov_b32_e32 v18, v0
	v_mov_b32_e32 v19, v0
	v_mov_b32_e32 v20, v0
	v_mov_b32_e32 v21, v0
	v_mov_b32_e32 v22, v0
	v_mov_b32_e32 v23, v0
	v_mov_b32_e32 v24, v0
	v_mov_b32_e32 v25, v0
	v_mov_b32_e32 v26, v0
	v_mov_b32_e32 v27, v0
	v_mov_b32_e32 v28, v0
	v_mov_b32_e32 v29, v0
	v_mov_b32_e32 v30, v0
	v_mov_b32_e32 v31, v0
	v_mov_b32_e32 v32, v0
	v_mov_b32_e32 v33, v0
	v_mov_b32_e32 v34, v0
	v_mov_b32_e32 v35, v0
	s_branch .LBB0_541

; __device__ __forceinline__ float bf2f(bf16 v) { return __uint_as_float(((unsigned)v) << 16); }
; __device__ __forceinline__ float sigmoidf_(float x) { return frcp_(1.0f + __expf(-x)); }
; __device__ __forceinline__ float siluf_(float x) { return x * frcp_(1.0f + __expf(-x)); }
; __host__ __device__ __forceinline__ int hg_vpos(int e) { return (e & 64) + 16 * (e & 3) + ((e & 63) >> 2); }
; __device__ __forceinline__ void hgrn_sample_step(const bf16* proj, const float* lbs_l, const float* hgn_l, const float* state_in, float* state_out, bf16* ohg, int bh, int tid, LAS unsigned char* lds,
;                                                  f32x4 (&st)[8], int bh_next) {
;     ...
;     const size_t row = (size_t)MP + b;
;     float ogv = 0.f, q_ = 0.f, f_ = 0.f, v_ = 0.f, lb_ = 0.f;
;     if (tid < 128) { const bf16* pr = proj + row * LDP + h * 128; q_ = bf2f(pr[PC_Q + tid]); f_ = bf2f(pr[PC_F + tid]); lb_ = lbs_l[h * 128 + tid]; v_ = bf2f(pr[PC_I + hg_vpos(tid)]); ogv = bf2f(pr[PC_OG + tid]); }
;     if (tid < 128) { const float fg = lb_ + (1.f - lb_) * sigmoidf_(f_);
;         sq[tid] = siluf_(q_) * 0.08838834764831845f; sg[tid] = fg; sk[tid] = 1.f - fg; sv[tid] = v_; }
.LBB0_552:
	s_ashr_i32 s6, s18, 3
	v_mov_b32_e32 v8, v138
	s_add_i32 s10, s6, 0x4000
	s_movk_i32 s6, 0x80
	s_and_b32 s16, s18, 7
	s_ashr_i32 s11, s10, 31
	v_cmp_gt_i32_e64 s[6:7], s6, v8
	s_waitcnt vmcnt(0) lgkmcnt(0)
	v_bfrev_b32_e32 v38, 1
	v_mov_b32_e32 v36, 0
	v_ashrrev_i32_e32 v9, 31, v8
	v_mov_b32_e32 v68, 0
	v_mov_b32_e32 v10, 0
	v_mov_b32_e32 v37, 0
	s_and_saveexec_b64 s[8:9], s[6:7]
	s_cbranch_execz .LBB0_554
	s_mul_i32 s13, s10, 0x6200
	s_mul_hi_i32 s12, s10, 0x6200
	s_add_u32 s13, s78, s13
	s_addc_u32 s14, s79, s12
	s_lshl_b32 s12, s16, 8
	s_add_u32 s12, s13, s12
	s_addc_u32 s13, s14, 0
	v_lshl_add_u64 v[38:39], v[8:9], 1, s[12:13]
	global_load_ushort v10, v[38:39], off offset:2048
	v_lshl_add_u32 v36, s16, 7, v8
	v_ashrrev_i32_e32 v37, 31, v36
	v_lshl_add_u64 v[36:37], v[36:37], 2, s[96:97]
	global_load_dword v36, v[36:37], off
	v_lshlrev_b32_e32 v37, 4, v8
	v_and_b32_e32 v37, 48, v37
	v_bfe_u32 v40, v8, 2, 4
	s_waitcnt vmcnt(0) lgkmcnt(0)
	v_lshlrev_b32_e32 v42, 16, v10
	v_and_b32_e32 v10, 64, v8
	v_or3_b32 v10, v37, v10, v40
	v_lshlrev_b32_e32 v10, 1, v10
	v_lshl_add_u64 v[40:41], s[12:13], 0, v[10:11]
	s_movk_i32 s12, 0x1000
	v_add_co_u32_e32 v40, vcc, s12, v40
	s_nop 1
	v_addc_co_u32_e32 v41, vcc, 0, v41, vcc
	global_load_ushort v10, v[40:41], off
	global_load_ushort v37, v[38:39], off
	v_add_co_u32_e32 v38, vcc, 0x1000, v38
	s_waitcnt vmcnt(0) lgkmcnt(0)
	v_lshlrev_b32_e32 v10, 16, v10
	v_addc_co_u32_e32 v39, vcc, 0, v39, vcc
	global_load_ushort v38, v[38:39], off offset:2048
	v_lshlrev_b32_e32 v37, 16, v37
	s_waitcnt vmcnt(0) lgkmcnt(0)
	v_lshlrev_b32_e32 v68, 16, v38
	v_mul_f32_e32 v38, 0xbfb8aa3b, v42

; #define LAS __attribute__((address_space(3)))
; #define LAUNDER_PTR(p) do {} while (0)
; #define LAUNDER_PTR(p) asm volatile("" : "+v"(p))
; __device__ __forceinline__ void hgrn_sample_step(const bf16* proj, const float* lbs_l, const float* hgn_l, const float* state_in, float* state_out, bf16* ohg, int bh, int tid, LAS unsigned char* lds,
;                                                  f32x4 (&st)[8], int bh_next) {
;     ...
;     const int dv4 = tid & 31, rg = tid >> 5;
;     const f32x4 vv = *(const LAS f32x4*)(sv + 4 * dv4);
;     f32x4 oacc = (f32x4){0.f, 0.f, 0.f, 0.f};
;     float* op = state_out + (size_t)bh * 16384 + tid * 4;
;     const float* np = state_in + (size_t)(bh_next >= 0 ? bh_next : bh) * 16384 + tid * 4;
; #pragma unroll
;     for (int it = 0; it < 8; ++it) { const int dk = it * 16 + rg; const f32x4 sn = st[it] * sg[dk] + vv * sk[dk]; LAUNDER_PTR(op); *(f32x4*)op = sn; op += 2048; oacc = oacc + sn * sq[dk];
;         LAUNDER_PTR(np); if (bh_next >= 0) st[it] = *(const f32x4*)np; np += 2048; }
.LBB0_556:
	s_or_b64 exec, exec, s[8:9]
	v_lshlrev_b32_e32 v40, 2, v8
	v_and_b32_e32 v73, 0x7c, v40
	v_ashrrev_i32_e32 v71, 5, v8
	v_lshl_add_u32 v10, v73, 2, 0
	s_waitcnt lgkmcnt(0)
	s_barrier
	ds_read_b128 v[36:39], v10 offset:1536
	v_lshl_add_u32 v10, v71, 2, 0
	ds_read2st64_b32 v[42:43], v10 offset0:2 offset1:4
	s_add_i32 s17, s18, s90
	s_cmpk_gt_i32 s17, 0x3ff
	s_cselect_b64 s[12:13], -1, 0
	s_cmpk_lt_i32 s17, 0x400
	s_cselect_b32 s8, s17, -1
	v_ashrrev_i32_e32 v41, 31, v40
	v_lshlrev_b64 v[46:47], 2, v[40:41]
	s_cmp_gt_i32 s8, -1
	s_waitcnt lgkmcnt(0)
	v_mov_b32_e32 v40, v43
	s_cselect_b64 s[14:15], -1, 0
	v_pk_mul_f32 v[48:49], v[38:39], v[40:41] op_sel_hi:[1,0]
	v_pk_mul_f32 v[40:41], v[36:37], v[40:41] op_sel_hi:[1,0]
	v_lshl_add_u64 v[44:45], s[2:3], 0, v[46:47]
	s_and_b64 vcc, s[14:15], exec
	v_pk_fma_f32 v[40:41], v[0:1], v[42:43], v[40:41] op_sel_hi:[1,0,1]
	v_pk_fma_f32 v[42:43], v[2:3], v[42:43], v[48:49] op_sel_hi:[1,0,1]
	s_cselect_b32 s8, s8, s18
	global_store_dwordx4 v[44:45], v[40:43], off
	s_ashr_i32 s9, s8, 31
	ds_read_b32 v70, v10
	s_lshl_b64 s[8:9], s[8:9], 16
	s_add_u32 s8, s0, s8
	s_addc_u32 s9, s1, s9
	v_lshl_add_u64 v[46:47], s[8:9], 0, v[46:47]
	s_cbranch_vccz .LBB0_558
	global_load_dwordx4 v[0:3], v[46:47], off

; __device__ __forceinline__ bf16 f2bf(float f) { return (bf16)pk2(f, f); }
; __device__ __forceinline__ float siluf_(float x) { return x * frcp_(1.0f + __expf(-x)); }
; #define LAUNDER_PTR(p) do {} while (0)
; #define LAUNDER_PTR(p) asm volatile("" : "+v"(p))
; __device__ __forceinline__ void hgrn_sample_step(const bf16* proj, const float* lbs_l, const float* hgn_l, const float* state_in, float* state_out, bf16* ohg, int bh, int tid, LAS unsigned char* lds,
;                                                  f32x4 (&st)[8], int bh_next) {
;     ...
;     if (tid < 128) { const float rstd = rsqrtf(((sred[0] + sred[1]) + (sred[2] + sred[3])) * (1.f / 128.f) + EPS);
;         ohg[row * 1024 + h * 128 + tid] = f2bf(sq[tid] * rstd * hgn_l[tid] * siluf_(ogv)); }
; __device__ __forceinline__ void ssd_sample_load(f32x4 (&st)[16], const float* state_in, int bg, int tid) {
;     const float* sp = state_in + ((size_t)((bg >> 3) * 32 + (bg & 7) * 4)) * 8192 + tid * 4;
; #pragma unroll
;     for (int it = 0; it < 16; ++it) { LAUNDER_PTR(sp); st[it] = *(const f32x4*)sp; sp += 2048; }
; }
.LBB0_576:
	s_or_b64 exec, exec, s[8:9]
	s_waitcnt lgkmcnt(0)
	s_barrier
	s_and_saveexec_b64 s[8:9], s[6:7]
	s_cbranch_execz .LBB0_551
	ds_read_b128 v[36:39], v11 offset:16384
	v_readlane_b32 s6, v255, 53
	v_readlane_b32 s7, v255, 54
	s_waitcnt lgkmcnt(0)
	v_mov_b32_e32 v40, v37
	v_mov_b32_e32 v41, v38
	v_mov_b32_e32 v37, v39
	v_pk_add_f32 v[36:37], v[40:41], v[36:37]
	v_lshl_add_u64 v[38:39], v[8:9], 2, s[6:7]
	v_add_f32_e32 v10, v36, v37
	v_fmamk_f32 v10, v10, 0x3c000000, v176
	v_cmp_gt_f32_e32 vcc, s33, v10
	v_mul_f32_e32 v36, 0x4b800000, v10
	s_lshl_b64 s[6:7], s[10:11], 11
	v_cndmask_b32_e32 v10, v10, v36, vcc
	v_rsq_f32_e32 v10, v10
	v_readlane_b32 s10, v255, 47
	s_add_u32 s6, s10, s6
	v_readlane_b32 s10, v255, 48
	v_mul_f32_e32 v36, 0x45800000, v10
	v_cndmask_b32_e32 v10, v10, v36, vcc
	ds_read_b32 v36, v69
	global_load_dword v69, v[38:39], off
	s_addc_u32 s7, s10, s7
	s_lshl_b32 s10, s16, 8
	s_add_u32 s6, s6, s10
	s_waitcnt lgkmcnt(0)
	v_mul_f32_e32 v37, v36, v10
	v_mul_f32_e32 v10, 0xbfb8aa3b, v68
	v_exp_f32_e32 v10, v10
	s_addc_u32 s7, s7, 0
	v_lshl_add_u64 v[8:9], v[8:9], 1, s[6:7]
	v_add_f32_e32 v10, 1.0, v10
	v_rcp_f32_e32 v36, v10
	s_waitcnt vmcnt(0)
	v_pk_mul_f32 v[36:37], v[68:69], v[36:37]
	s_nop 0
	v_mul_f32_e32 v10, v36, v37
	v_cvt_pk_bf16_f32 v10, v10, v10
	global_store_short v[8:9], v10, off
	s_branch .LBB0_551
.LBB0_578:
	v_readlane_b32 s0, v255, 34
	v_readlane_b32 s1, v255, 35
	v_readlane_b32 s8, v253, 15
	s_lshl_b64 s[0:1], s[0:1], 27
	v_readlane_b32 s14, v253, 21
	v_readlane_b32 s2, v254, 11
	v_readlane_b32 s15, v253, 22
	s_add_u32 s0, s14, s0
	v_readlane_b32 s3, v254, 12
	s_addc_u32 s1, s15, s1
	s_and_b64 vcc, exec, s[2:3]
	v_readlane_b32 s9, v253, 16
	v_readlane_b32 s10, v253, 17
	v_readlane_b32 s11, v253, 18
	v_readlane_b32 s12, v253, 19
	v_readlane_b32 s13, v253, 20
	v_readlane_b32 s16, v253, 23
	v_readlane_b32 s17, v253, 24
	v_readlane_b32 s18, v253, 25
	v_readlane_b32 s19, v253, 26
	v_readlane_b32 s20, v253, 27
	v_readlane_b32 s21, v253, 28
	v_readlane_b32 s22, v253, 29
	v_readlane_b32 s23, v253, 30
	s_cbranch_vccz .LBB0_580
	s_waitcnt vmcnt(0) lgkmcnt(0)
	v_mov_b32_e32 v0, v138
	v_readlane_b32 s2, v254, 15
	v_readlane_b32 s3, v254, 16
	s_add_u32 s2, s0, s2
	v_lshlrev_b32_e32 v0, 2, v0
	s_addc_u32 s3, s1, s3
	v_ashrrev_i32_e32 v1, 31, v0
	v_lshl_add_u64 v[4:5], v[0:1], 2, s[2:3]
	global_load_dwordx4 v[0:3], v[4:5], off
	v_lshl_add_u64 v[8:9], v[4:5], 0, s[44:45]
	global_load_dwordx4 v[4:7], v[8:9], off
	v_lshl_add_u64 v[8:9], v[8:9], 0, s[44:45]
	global_load_dwordx4 v[12:15], v[8:9], off
	v_lshl_add_u64 v[8:9], v[8:9], 0, s[44:45]
	global_load_dwordx4 v[16:19], v[8:9], off
	v_lshl_add_u64 v[8:9], v[8:9], 0, s[44:45]
	global_load_dwordx4 v[20:23], v[8:9], off
	v_lshl_add_u64 v[8:9], v[8:9], 0, s[44:45]
	global_load_dwordx4 v[24:27], v[8:9], off
	v_lshl_add_u64 v[8:9], v[8:9], 0, s[44:45]
	global_load_dwordx4 v[28:31], v[8:9], off
	v_lshl_add_u64 v[8:9], v[8:9], 0, s[44:45]
	global_load_dwordx4 v[32:35], v[8:9], off
	v_lshl_add_u64 v[8:9], v[8:9], 0, s[44:45]
	global_load_dwordx4 v[36:39], v[8:9], off
	v_lshl_add_u64 v[8:9], v[8:9], 0, s[44:45]
	global_load_dwordx4 v[40:43], v[8:9], off
	v_lshl_add_u64 v[8:9], v[8:9], 0, s[44:45]
	global_load_dwordx4 v[44:47], v[8:9], off
	v_lshl_add_u64 v[8:9], v[8:9], 0, s[44:45]
	global_load_dwordx4 v[48:51], v[8:9], off
	v_lshl_add_u64 v[8:9], v[8:9], 0, s[44:45]
	global_load_dwordx4 v[52:55], v[8:9], off
	v_lshl_add_u64 v[8:9], v[8:9], 0, s[44:45]
	global_load_dwordx4 v[56:59], v[8:9], off
	v_lshl_add_u64 v[8:9], v[8:9], 0, s[44:45]
	global_load_dwordx4 v[60:63], v[8:9], off
	v_lshl_add_u64 v[8:9], v[8:9], 0, s[44:45]
	global_load_dwordx4 v[64:67], v[8:9], off

; __device__ __forceinline__ float bf2f(bf16 v) { return __uint_as_float(((unsigned)v) << 16); }
; __device__ __forceinline__ void ssd_sample_step(const bf16* proj, const float* conv_w, const float* conv_b, const float* dt_bias, const float* a_log, const float* d_skip, const float* ssm_norm, ...
;     ...
;         const int chx = tid < 256 ? (grp * 256 + tid) : (tid < 384 ? (2048 + grp * 128 + (tid - 256)) : (3072 + grp * 128 + (tid - 384)));
;         const float* ci = conv_in + (size_t)b * 3 * 4096; const float r0 = ci[chx], r1 = ci[4096 + chx], r2 = ci[8192 + chx];
;         const float cur = bf2f(proj[row * LDP + PC_XBC + chx]);
;         const float cw0 = conv_w[chx], cw1 = conv_w[4096 + chx], cw2 = conv_w[8192 + chx], cw3 = conv_w[12288 + chx], cbb = conv_b[chx];
;         float dtr = 0.f, dtbv = 0.f, alg = 0.f; if (tid < 4) { const int head = grp * 4 + tid; dtr = bf2f(proj[row * LDP + PC_DT + head]); dtbv = dt_bias[head]; alg = a_log[head]; }
.LBB0_589:
	s_or_saveexec_b64 s[2:3], s[2:3]
	v_lshl_add_u32 v80, s28, 8, v8
	s_xor_b64 exec, exec, s[2:3]
	v_mov_b32_e32 v68, v80
	s_or_b64 exec, exec, s[2:3]
	s_ashr_i32 s50, s51, 3
	s_ashr_i32 s3, s50, 31
	s_add_u32 s2, s50, 0x4000
	s_mul_hi_i32 s9, s50, 0x3000
	s_mul_i32 s8, s50, 0x3000
	s_addc_u32 s3, s3, 0
	s_lshl_b64 s[12:13], s[8:9], 2
	s_add_u32 s8, s22, s12
	v_ashrrev_i32_e32 v69, 31, v68
	s_addc_u32 s9, s23, s13
	v_lshlrev_b64 v[72:73], 2, v[68:69]
	v_lshl_add_u64 v[74:75], s[8:9], 0, v[72:73]
	s_movk_i32 s14, 0x4000
	v_add_co_u32_e32 v70, vcc, s14, v74
	s_mov_b32 s8, 0x8000
	s_nop 0
	v_addc_co_u32_e32 v71, vcc, 0, v75, vcc
	s_mul_i32 s9, s2, 0x6200
	global_load_dword v10, v[74:75], off
	s_add_u32 s10, s78, s9
	global_load_dword v70, v[70:71], off
	v_add_co_u32_e32 v74, vcc, s8, v74
	s_mul_hi_i32 s8, s2, 0x6200
	s_nop 0
	v_addc_co_u32_e32 v75, vcc, 0, v75, vcc
	s_addc_u32 s11, s79, s8
	global_load_dword v71, v[74:75], off
	v_lshl_add_u64 v[74:75], v[68:69], 1, s[10:11]
	s_movk_i32 s8, 0x3000
	v_add_co_u32_e32 v74, vcc, s8, v74
	v_lshl_add_u64 v[78:79], s[30:31], 0, v[72:73]
	s_nop 0
	v_addc_co_u32_e32 v75, vcc, 0, v75, vcc
	v_add_co_u32_e32 v76, vcc, s14, v78
	global_load_ushort v74, v[74:75], off
	s_nop 0
	v_addc_co_u32_e32 v77, vcc, 0, v79, vcc
	v_add_co_u32_e32 v82, vcc, 0x8000, v78
	global_load_dword v75, v[78:79], off
	s_nop 0
	v_addc_co_u32_e32 v83, vcc, 0, v79, vcc
	global_load_dword v76, v[76:77], off
	v_add_co_u32_e32 v78, vcc, 0xc000, v78
	v_lshl_add_u64 v[72:73], s[34:35], 0, v[72:73]
	s_nop 0
	v_addc_co_u32_e32 v79, vcc, 0, v79, vcc
	global_load_dword v77, v[82:83], off
	v_cmp_gt_i32_e64 s[8:9], 4, v8
	global_load_dword v79, v[78:79], off
	v_mov_b32_e32 v9, 0
	global_load_dword v78, v[72:73], off
	v_mov_b32_e32 v73, 0
	v_mov_b32_e32 v72, 0
	s_and_saveexec_b64 s[14:15], s[8:9]
	s_cbranch_execz .LBB0_593
	v_lshl_add_u32 v82, s28, 2, v8
	v_ashrrev_i32_e32 v83, 31, v82
	v_lshl_add_u64 v[72:73], v[82:83], 1, s[10:11]
	v_add_co_u32_e32 v72, vcc, 0x6000, v72
	v_lshlrev_b64 v[82:83], 2, v[82:83]
	s_nop 0
	v_addc_co_u32_e32 v73, vcc, 0, v73, vcc
	global_load_ushort v9, v[72:73], off
	v_lshl_add_u64 v[84:85], s[36:37], 0, v[82:83]
	v_lshl_add_u64 v[82:83], s[60:61], 0, v[82:83]
	global_load_dword v73, v[84:85], off
	s_waitcnt vmcnt(0) lgkmcnt(0)
	v_lshlrev_b32_e32 v72, 16, v9
	global_load_dword v9, v[82:83], off
	s_waitcnt vmcnt(0)
	v_mul_f32_e32 v9, 0x3fb8aa3b, v9

; #define LAS __attribute__((address_space(3)))
; #define LAUNDER_PTR(p) do {} while (0)
; #define LAUNDER_PTR(p) asm volatile("" : "+v"(p))
; __device__ __forceinline__ void ssd_sample_step(const bf16* proj, const float* conv_w, const float* conv_b, const float* dt_bias, const float* a_log, const float* d_skip, const float* ssm_norm, ...
;     ...
;     const int n4 = tid & 31, pr_ = tid >> 5;
;     const f32x4 Bv = *(const LAS f32x4*)(sB + 4 * n4), Cv = *(const LAS f32x4*)(sC + 4 * n4);
;     float* op = state_out + ((size_t)(b * 32 + grp * 4)) * 8192 + tid * 4;
;     const int bgn = bg_next >= 0 ? bg_next : bg; const float* np = state_in + ((size_t)((bgn >> 3) * 32 + (bgn & 7) * 4)) * 8192 + tid * 4;
; #pragma unroll
;     for (int it = 0; it < 16; ++it) { const int k = it >> 2, p = (it & 3) * 16 + pr_; const float xdt = sx[k * 64 + p] * sdt[k];
;         const f32x4 hn = st[it] * sdec[k] + Bv * xdt; LAUNDER_PTR(op); *(f32x4*)op = hn; op += 2048;
;         LAUNDER_PTR(np); if (bg_next >= 0) st[it] = *(const f32x4*)np; np += 2048;
.LBB0_605:
	s_or_b64 exec, exec, s[6:7]
	s_add_i32 s29, s51, s90
	s_cmpk_gt_i32 s29, 0x3ff
	s_cselect_b64 s[12:13], -1, 0
	s_cmpk_lt_i32 s29, 0x400
	s_cselect_b32 s8, s29, -1
	s_lshl_b32 s6, s50, 5
	s_lshl_b32 s50, s28, 2
	s_or_b32 s6, s6, s50
	s_ashr_i32 s7, s6, 31
	s_lshl_b64 s[6:7], s[6:7], 15
	s_add_u32 s6, s20, s6
	v_lshlrev_b32_e32 v72, 2, v8
	s_addc_u32 s7, s21, s7
	v_ashrrev_i32_e32 v73, 31, v72
	s_cmp_gt_i32 s8, -1
	v_lshlrev_b32_e32 v68, 4, v8
	v_lshlrev_b64 v[76:77], 2, v[72:73]
	s_cselect_b64 s[14:15], -1, 0
	v_ashrrev_i32_e32 v9, 5, v8
	v_and_b32_e32 v68, 0x1f0, v68
	v_lshl_add_u64 v[82:83], s[6:7], 0, v[76:77]
	s_and_b64 s[6:7], s[14:15], exec
	s_movk_i32 s9, 0x1000
	v_add_u32_e32 v74, 0, v68
	s_cselect_b32 s6, s8, s51
	v_lshl_add_u32 v81, v9, 2, 0
	v_add_u32_e64 v9, s9, 0
	s_waitcnt lgkmcnt(0)
	s_barrier
	ds_read_b128 v[68:71], v74 offset:3584
	s_lshl_b32 s6, s6, 2
	ds_read_b128 v[72:75], v74 offset:3072
	ds_read_b32 v86, v81 offset:2048
	ds_read2_b32 v[78:79], v9 offset1:4
	s_ashr_i32 s7, s6, 31
	s_lshl_b64 s[6:7], s[6:7], 15
	s_add_u32 s6, s0, s6
	s_addc_u32 s7, s1, s7
	v_lshl_add_u64 v[84:85], s[6:7], 0, v[76:77]
	s_waitcnt lgkmcnt(0)
	v_mov_b32_e32 v76, v79
	v_mul_f32_e32 v78, v86, v78
	v_pk_mul_f32 v[86:87], v[2:3], v[76:77] op_sel_hi:[1,0]
	v_pk_mul_f32 v[76:77], v[0:1], v[76:77] op_sel_hi:[1,0]
	s_cmp_lt_i32 s8, 0
	v_pk_fma_f32 v[76:77], v[72:73], v[78:79], v[76:77] op_sel_hi:[1,0,1]
	v_pk_fma_f32 v[78:79], v[74:75], v[78:79], v[86:87] op_sel_hi:[1,0,1]
	global_store_dwordx4 v[82:83], v[76:79], off
	s_cbranch_scc1 .LBB0_607
	global_load_dwordx4 v[0:3], v[84:85], off

; __device__ __forceinline__ float bf2f(bf16 v) { return __uint_as_float(((unsigned)v) << 16); }
; __device__ __forceinline__ float siluf_(float x) { return x * frcp_(1.0f + __expf(-x)); }
; __device__ __forceinline__ float row32_sum(float s) { s += SHFL_XOR(s, 1); s += SHFL_XOR(s, 2); s += SHFL_XOR(s, 4); s += SHFL_XOR(s, 8); s += SHFL_XOR(s, 16); return s; }
; __device__ __forceinline__ void ssd_sample_step(const bf16* proj, const float* conv_w, const float* conv_b, const float* dt_bias, const float* a_log, const float* d_skip, const float* ssm_norm, ...
;     ...
;     float yv = 0.f;
;     if (tid < 256) { const int k = tid >> 6; const float z = bf2f(proj[row * LDP + PC_Z + grp * 256 + tid]);
;         yv = (sy[tid] + d_skip[grp * 4 + k] * sx[tid]) * siluf_(z);
;         float ss = yv * yv; ss = row32_sum(ss); if ((lane & 31) == 0) sred[tid >> 5] = ss; }
.LBB0_669:
	s_or_b64 exec, exec, s[8:9]
	s_waitcnt lgkmcnt(0)
	v_mov_b32_e32 v68, 0
	v_ashrrev_i32_e32 v9, 31, v8
	s_barrier
	s_and_saveexec_b64 s[8:9], s[4:5]
	s_cbranch_execz .LBB0_673
	s_lshl_b32 s14, s28, 9
	s_add_u32 s10, s10, s14
	s_addc_u32 s11, s11, 0
	v_lshl_add_u64 v[68:69], v[8:9], 1, s[10:11]
	v_add_co_u32_e32 v68, vcc, 0x2000, v68
	v_readlane_b32 s10, v255, 32
	s_nop 0
	v_addc_co_u32_e32 v69, vcc, 0, v69, vcc
	global_load_ushort v70, v[68:69], off
	v_ashrrev_i32_e32 v68, 6, v8
	v_add_u32_e32 v68, s50, v68
	v_ashrrev_i32_e32 v69, 31, v68
	v_readlane_b32 s11, v255, 33
	ds_read2st64_b32 v[72:73], v10 offset0:8 offset1:18
	s_waitcnt vmcnt(0) lgkmcnt(0)
	v_lshlrev_b32_e32 v71, 16, v70
	v_lshl_add_u64 v[68:69], v[68:69], 2, s[10:11]
	global_load_dword v68, v[68:69], off
	v_mul_f32_e32 v69, 0xbfb8aa3b, v71
	v_exp_f32_e32 v69, v69
	v_mov_b32_e32 v70, v72
	v_add_f32_e32 v10, 1.0, v69
	v_rcp_f32_e32 v69, v10
	s_waitcnt vmcnt(0)
	v_pk_mul_f32 v[68:69], v[68:69], v[70:71]
	s_nop 0
	v_add_f32_e32 v10, v73, v68
	v_mul_f32_e32 v68, v10, v69
	v_mul_f32_e32 v10, v68, v68
	ds_swizzle_b32 v10, v10 offset:swizzle(SWAP,1)
	s_waitcnt lgkmcnt(0)
	v_fmac_f32_e32 v10, v68, v68
	ds_swizzle_b32 v69, v10 offset:swizzle(SWAP,2)
	s_waitcnt lgkmcnt(0)
	v_add_f32_e32 v10, v10, v69
	ds_swizzle_b32 v69, v10 offset:swizzle(SWAP,4)
	s_waitcnt lgkmcnt(0)
	v_add_f32_e32 v10, v10, v69
	ds_swizzle_b32 v69, v10 offset:swizzle(SWAP,8)
	s_waitcnt lgkmcnt(0)
	v_add_f32_e32 v10, v10, v69
	ds_swizzle_b32 v69, v10 offset:swizzle(SWAP,16)
	s_and_saveexec_b64 s[10:11], s[6:7]
	s_cbranch_execz .LBB0_672
	s_waitcnt lgkmcnt(0)
	v_add_f32_e32 v10, v10, v69
	ds_write_b32 v81, v10 offset:16384

; __device__ __forceinline__ bf16 f2bf(float f) { return (bf16)pk2(f, f); }
; __device__ __forceinline__ void sync_threads() { __syncthreads(); }
; __device__ __forceinline__ void ssd_sample_step(const bf16* proj, const float* conv_w, const float* conv_b, const float* dt_bias, const float* a_log, const float* d_skip, const float* ssm_norm, ...
;     ...
;     sync_threads();
;     if (tid < 256) { float tot = 0.f;
; #pragma unroll
;         for (int r = 0; r < 8; ++r) tot += sred[r];
;         ybuf[row * 2048 + grp * 256 + tid] = f2bf(yv * rsqrtf(tot * (1.f / 256.f) + EPS) * ssm_norm[grp * 256 + tid]); }
.LBB0_673:
	s_or_b64 exec, exec, s[8:9]
	s_waitcnt lgkmcnt(0)
	s_barrier
	s_and_saveexec_b64 s[6:7], s[4:5]
	s_cbranch_execz .LBB0_582
	ds_read_b128 v[70:73], v11 offset:16384
	ds_read_b128 v[74:77], v11 offset:16400
	v_readlane_b32 s4, v255, 57
	v_ashrrev_i32_e32 v81, 31, v80
	v_readlane_b32 s5, v255, 58
	s_waitcnt lgkmcnt(0)
	v_add_f32_e32 v10, 0, v70
	v_add_f32_e32 v10, v10, v71
	v_add_f32_e32 v10, v10, v72
	v_add_f32_e32 v10, v10, v73
	v_add_f32_e32 v10, v10, v74
	v_add_f32_e32 v10, v10, v75
	v_add_f32_e32 v10, v10, v76
	v_add_f32_e32 v10, v10, v77
	v_fmamk_f32 v10, v10, 0x3b800000, v176
	v_cmp_gt_f32_e32 vcc, s33, v10
	v_mul_f32_e32 v69, 0x4b800000, v10
	s_lshl_b64 s[2:3], s[2:3], 12
	v_cndmask_b32_e32 v10, v10, v69, vcc
	v_rsq_f32_e32 v10, v10
	s_nop 0
	v_mul_f32_e32 v69, 0x45800000, v10
	v_cndmask_b32_e32 v10, v10, v69, vcc
	v_mul_f32_e32 v10, v68, v10
	v_lshl_add_u64 v[68:69], v[80:81], 2, s[4:5]
	global_load_dword v68, v[68:69], off
	v_readlane_b32 s4, v255, 49
	s_add_u32 s2, s4, s2
	v_readlane_b32 s4, v255, 50
	s_addc_u32 s3, s4, s3
	s_lshl_b32 s4, s28, 9
	s_add_u32 s2, s2, s4
	s_addc_u32 s3, s3, 0
	v_lshl_add_u64 v[8:9], v[8:9], 1, s[2:3]
	s_waitcnt vmcnt(0)
	v_mul_f32_e32 v10, v68, v10
	v_cvt_pk_bf16_f32 v10, v10, v10
	global_store_short v[8:9], v10, off
	s_branch .LBB0_582

; #define LAS __attribute__((address_space(3)))
; __device__ __forceinline__ void ssd_pass1(const RecurBufs& rb, const float* conv_w, const float* conv_b, const float* dt_bias, const float* a_log, float* conv_out_l, int u, int tid, LAS unsigned char* lds) {
;     const int b = u >> 5, grp = (u >> 2) & 7, seg = u & 3, lane = tid & 63, w = tid >> 6;
;     LAS unsigned char* T = lds + SD_T; LAS float* sDt = (LAS float*)(lds + SD_DT); LAS float* sCum = (LAS float*)(lds + SD_CUM); LAS unsigned char* RH = lds + SD_RH;
;     const int cp = tid & 255, half = tid >> 8, t0c = 2 * cp;
;     const int chx = t0c < 256 ? (grp * 256 + t0c) : (t0c < 384 ? (2048 + grp * 128 + (t0c - 256)) : (3072 + grp * 128 + (t0c - 384)));
;     const int xcol = (t0c & ~63) + 16 * (t0c & 3) + ((t0c & 63) >> 2);
;     const f32x2r w0 = (f32x2r){conv_w[chx], conv_w[chx + 1]}, w1 = (f32x2r){conv_w[4096 + chx], conv_w[4096 + chx + 1]}, w2 = (f32x2r){conv_w[8192 + chx], conv_w[8192 + chx + 1]},
;                  w3 = (f32x2r){conv_w[12288 + chx], conv_w[12288 + chx + 1]}, cb = (f32x2r){conv_b[chx], conv_b[chx + 1]};
;     const size_t rowS = (size_t)b * SEQ + seg * SEGLEN;
;     if (half == 0) {
; #pragma unroll
;         for (int j = 0; j < 3; ++j) { unsigned v = 0u; if (seg > 0) v = *(const unsigned*)(rb.proj + (rowS - 3 + j) * LDP + PC_XBC + chx); *(LAS unsigned*)(RH + j * 1024 + cp * 4) = v; } }
.LBB0_684:
	s_andn2_saveexec_b64 s[4:5], s[4:5]
	v_lshl_or_b32 v10, s3, 8, v0
	s_or_b64 exec, exec, s[4:5]
	v_lshlrev_b64 v[0:1], 2, v[10:11]
	v_lshl_add_u64 v[2:3], s[30:31], 0, v[0:1]
	s_mov_b32 s4, 0xc000
	v_add_u32_e32 v8, 0x1000, v10
	v_mov_b32_e32 v9, v11
	v_add_u32_e32 v100, 0x2000, v10
	v_mov_b32_e32 v101, v11
	v_add_co_u32_e32 v12, vcc, s4, v2
	v_lshl_add_u64 v[4:5], v[8:9], 2, s[30:31]
	v_lshl_add_u64 v[6:7], v[100:101], 2, s[30:31]
	v_addc_co_u32_e32 v13, vcc, 0, v3, vcc
	global_load_dwordx2 v[102:103], v[2:3], off
	global_load_dwordx2 v[104:105], v[4:5], off
	global_load_dwordx2 v[106:107], v[6:7], off
	global_load_dwordx2 v[108:109], v[12:13], off
	v_lshl_add_u64 v[0:1], s[34:35], 0, v[0:1]
	global_load_dwordx2 v[112:113], v[0:1], off
	s_ashr_i32 s58, s2, 5
	s_and_b32 s28, s2, 3
	s_ashr_i32 s59, s58, 31
	s_lshl_b64 s[66:67], s[58:59], 11
	s_lshl_b32 s4, s28, 9
	s_or_b32 s66, s66, s4
	s_movk_i32 s4, 0x100
	v_cmp_gt_u32_e64 s[6:7], s4, v139
	v_lshlrev_b32_e32 v110, 2, v139
	s_and_saveexec_b64 s[4:5], s[6:7]
	s_cbranch_execz .LBB0_695
	s_cmp_lg_u32 s28, 0
	v_add_u32_e32 v0, 0, v110
	s_cselect_b64 s[8:9], -1, 0
	s_cmp_eq_u32 s28, 0
	s_mul_hi_u32 s12, s66, 0x6200
	s_mul_i32 s13, s66, 0x6200
	v_add_u32_e32 v0, 0x18800, v0
	s_cbranch_scc1 .LBB0_692
	s_mul_i32 s10, s67, 0x6200
	s_add_i32 s11, s12, s10
	s_add_u32 s10, s78, s13
	s_addc_u32 s11, s79, s11
	v_lshl_add_u64 v[2:3], v[10:11], 1, s[10:11]
	v_add_co_u32_e32 v4, vcc, 0xffff0a00, v2
	s_nop 1
	v_addc_co_u32_e32 v5, vcc, -1, v3, vcc
	global_load_dword v1, v[4:5], off
	v_add_co_u32_e32 v2, vcc, 0xffff6c00, v2
	s_waitcnt vmcnt(0) lgkmcnt(0)
	ds_write_b32 v0, v1
	v_addc_co_u32_e32 v3, vcc, -1, v3, vcc
	global_load_dword v1, v[2:3], off
	s_cbranch_execnz .LBB0_690

; #define LAS __attribute__((address_space(3)))
; __device__ __forceinline__ void ssd_state_update(f32x4 (&H)[4][4], LAS unsigned char* Xi, int xp, LAS unsigned char* Bi, int bp, const LAS float* sDt, const LAS float* sCum, int w, int lane) {
;     const int g = lane >> 4, k = w >> 1, nh = w & 1;
;     const float tot = sCum[63 * 4 + k]; const float et = __expf(tot);
; #pragma unroll
;     for (int nt = 0; nt < 4; ++nt)
; #pragma unroll
;         for (int pt = 0; pt < 4; ++pt) H[nt][pt] = H[nt][pt] * et;
; #pragma unroll
;     for (int ks = 0; ks < 2; ++ks) {
;         float wg[8];
; #pragma unroll
;         for (int j = 0; j < 8; ++j) wg[j] = __expf(tot - sCum[(32 * ks + 8 * g + j) * 4 + k]) * sDt[(32 * ks + 8 * g + j) * 4 + k];
;         bf16x8 Bx[4];
; #pragma unroll
;         for (int pt = 0; pt < 4; ++pt) Bx[pt] = scale_frag8(frag_tr(Xi, xp, 32 * ks + 8 * g, 32 * ks + 8 * g + 4, 64 * k + 16 * pt, lane), wg);
; #pragma unroll
.LBB0_708:
	s_or_b64 exec, exec, s[50:51]
	s_waitcnt lgkmcnt(0)
	s_barrier
	ds_read_b32 v128, v157 offset:1008
	ds_read_b32 v132, v163
	ds_read_b32 v136, v171
	s_add_i32 s3, s3, 1
	ds_read_b32 v134, v167
	s_waitcnt lgkmcnt(0)
	v_mul_f32_e32 v129, 0x3fb8aa3b, v128
	v_exp_f32_e32 v130, v129
	ds_read_b32 v129, v158
	ds_read_b32 v133, v165
	ds_read_b32 v135, v169
	v_pk_mul_f32 v[98:99], v[98:99], v[130:131] op_sel_hi:[1,0]
	v_pk_mul_f32 v[96:97], v[96:97], v[130:131] op_sel_hi:[1,0]
	v_pk_mul_f32 v[94:95], v[94:95], v[130:131] op_sel_hi:[1,0]
	v_pk_mul_f32 v[92:93], v[92:93], v[130:131] op_sel_hi:[1,0]
	v_pk_mul_f32 v[90:91], v[90:91], v[130:131] op_sel_hi:[1,0]
	v_pk_mul_f32 v[88:89], v[88:89], v[130:131] op_sel_hi:[1,0]
	v_pk_mul_f32 v[86:87], v[86:87], v[130:131] op_sel_hi:[1,0]
	v_pk_mul_f32 v[84:85], v[84:85], v[130:131] op_sel_hi:[1,0]
	v_pk_mul_f32 v[70:71], v[70:71], v[130:131] op_sel_hi:[1,0]
	v_pk_mul_f32 v[68:69], v[68:69], v[130:131] op_sel_hi:[1,0]
	v_pk_mul_f32 v[74:75], v[74:75], v[130:131] op_sel_hi:[1,0]
	v_pk_mul_f32 v[72:73], v[72:73], v[130:131] op_sel_hi:[1,0]
	v_pk_mul_f32 v[78:79], v[78:79], v[130:131] op_sel_hi:[1,0]
	v_pk_mul_f32 v[76:77], v[76:77], v[130:131] op_sel_hi:[1,0]
	v_pk_mul_f32 v[82:83], v[82:83], v[130:131] op_sel_hi:[1,0]
	v_pk_mul_f32 v[80:81], v[80:81], v[130:131] op_sel_hi:[1,0]
	v_pk_mul_f32 v[62:63], v[62:63], v[130:131] op_sel_hi:[1,0]
	v_pk_mul_f32 v[60:61], v[60:61], v[130:131] op_sel_hi:[1,0]
	v_pk_mul_f32 v[66:67], v[66:67], v[130:131] op_sel_hi:[1,0]
	v_pk_mul_f32 v[64:65], v[64:65], v[130:131] op_sel_hi:[1,0]
	v_pk_mul_f32 v[58:59], v[58:59], v[130:131] op_sel_hi:[1,0]
	v_pk_mul_f32 v[56:57], v[56:57], v[130:131] op_sel_hi:[1,0]
	v_pk_mul_f32 v[54:55], v[54:55], v[130:131] op_sel_hi:[1,0]
	v_pk_mul_f32 v[52:53], v[52:53], v[130:131] op_sel_hi:[1,0]
	v_pk_mul_f32 v[50:51], v[50:51], v[130:131] op_sel_hi:[1,0]
	v_pk_mul_f32 v[48:49], v[48:49], v[130:131] op_sel_hi:[1,0]
	v_pk_mul_f32 v[46:47], v[46:47], v[130:131] op_sel_hi:[1,0]
	v_pk_mul_f32 v[44:45], v[44:45], v[130:131] op_sel_hi:[1,0]
	v_pk_mul_f32 v[42:43], v[42:43], v[130:131] op_sel_hi:[1,0]
	v_pk_mul_f32 v[40:41], v[40:41], v[130:131] op_sel_hi:[1,0]
	v_pk_mul_f32 v[38:39], v[38:39], v[130:131] op_sel_hi:[1,0]
	v_pk_mul_f32 v[36:37], v[36:37], v[130:131] op_sel_hi:[1,0]
	ds_read_b32 v130, v159
	ds_read_b32 v131, v161
	s_waitcnt lgkmcnt(0)
	v_sub_f32_e32 v129, v128, v129
	v_mul_f32_e32 v129, 0x3fb8aa3b, v129
	v_exp_f32_e32 v129, v129
	s_nop 0
	v_mul_f32_e32 v129, v130, v129
	ds_read_b32 v130, v160
	s_waitcnt lgkmcnt(0)
	v_sub_f32_e32 v130, v128, v130
	v_mul_f32_e32 v130, 0x3fb8aa3b, v130
	v_exp_f32_e32 v130, v130
	s_nop 0
	v_mul_f32_e32 v130, v131, v130
	ds_read_b32 v131, v162
	s_waitcnt lgkmcnt(0)
	v_sub_f32_e32 v131, v128, v131
	v_mul_f32_e32 v131, 0x3fb8aa3b, v131
	v_exp_f32_e32 v131, v131
	s_nop 0
	v_mul_f32_e32 v131, v132, v131
	ds_read_b32 v132, v164
	s_waitcnt lgkmcnt(0)
	v_sub_f32_e32 v132, v128, v132
	v_mul_f32_e32 v132, 0x3fb8aa3b, v132
	v_exp_f32_e32 v132, v132
	s_nop 0
	v_mul_f32_e32 v132, v133, v132
	ds_read_b32 v133, v166
	s_waitcnt lgkmcnt(0)
	v_sub_f32_e32 v133, v128, v133
	v_mul_f32_e32 v133, 0x3fb8aa3b, v133
	v_exp_f32_e32 v133, v133
	s_nop 0
	v_mul_f32_e32 v133, v134, v133
	ds_read_b32 v134, v168
	s_waitcnt lgkmcnt(0)
	v_sub_f32_e32 v134, v128, v134
	v_mul_f32_e32 v134, 0x3fb8aa3b, v134
	v_exp_f32_e32 v134, v134
	s_nop 0
	v_mul_f32_e32 v134, v135, v134
	ds_read_b32 v135, v170
	s_waitcnt lgkmcnt(0)
	v_sub_f32_e32 v135, v128, v135
	v_mul_f32_e32 v135, 0x3fb8aa3b, v135
	v_exp_f32_e32 v135, v135
	s_nop 0
	v_mul_f32_e32 v226, v136, v135
	ds_read_b32 v135, v172
	ds_read_b32 v136, v173
	ds_read_b64_tr_b16 v[230:231], v219 offset:2112
	ds_read_b64_tr_b16 v[228:229], v219
	ds_read_b64_tr_b16 v[236:237], v219 offset:32
	ds_read_b64_tr_b16 v[238:239], v219 offset:2144
	ds_read_b64_tr_b16 v[242:243], v219 offset:64
	ds_read_b64_tr_b16 v[244:245], v219 offset:2176
	s_waitcnt lgkmcnt(0)
	v_sub_f32_e32 v135, v128, v135
	v_mul_f32_e32 v135, 0x3fb8aa3b, v135
	v_exp_f32_e32 v135, v135
	v_lshlrev_b32_e32 v241, 16, v242
	v_mul_f32_e32 v241, v129, v241
	v_cvt_pk_bf16_f32 v246, v241, v241
	v_and_b32_e32 v241, 0xffff0000, v242
	v_mul_f32_e32 v241, v130, v241
	v_cvt_pk_bf16_f32 v247, v241, v241
	v_lshlrev_b32_e32 v241, 16, v243
	v_mul_f32_e32 v241, v131, v241
	v_cvt_pk_bf16_f32 v248, v241, v241
	v_and_b32_e32 v241, 0xffff0000, v243
	v_mul_f32_e32 v241, v132, v241
	v_cvt_pk_bf16_f32 v249, v241, v241
	v_lshlrev_b32_e32 v241, 16, v244
	v_mul_f32_e32 v241, v133, v241
	v_cvt_pk_bf16_f32 v250, v241, v241
	v_and_b32_e32 v241, 0xffff0000, v244
	v_mul_f32_e32 v241, v134, v241
	v_lshlrev_b32_e32 v137, 16, v229
	v_and_b32_e32 v227, 0xffff0000, v229
	v_and_b32_e32 v229, 0xffff0000, v230
	v_cvt_pk_bf16_f32 v251, v241, v241
	v_lshlrev_b32_e32 v241, 16, v245
	v_mul_f32_e32 v229, v134, v229
	v_mul_f32_e32 v241, v226, v241
	v_mul_f32_e32 v240, v136, v135
	v_lshlrev_b32_e32 v135, 16, v228
	v_and_b32_e32 v136, 0xffff0000, v228
	v_lshlrev_b32_e32 v228, 16, v230
	v_cvt_pk_bf16_f32 v230, v229, v229
	v_lshlrev_b32_e32 v229, 16, v231
	v_cvt_pk_bf16_f32 v252, v241, v241
	v_and_b32_e32 v241, 0xffff0000, v245
	ds_read_b64_tr_b16 v[242:243], v219 offset:96
	ds_read_b64_tr_b16 v[244:245], v219 offset:2208
	v_mul_f32_e32 v229, v226, v229
	v_cvt_pk_bf16_f32 v232, v229, v229
	v_and_b32_e32 v229, 0xffff0000, v231
	v_mul_f32_e32 v229, v240, v229
	v_mul_f32_e32 v241, v240, v241
	v_cvt_pk_bf16_f32 v234, v229, v229
	v_lshlrev_b32_e32 v229, 16, v236
	v_cvt_pk_bf16_f32 v180, v241, v241
	s_waitcnt lgkmcnt(0)
; __device__ __forceinline__ f32x4 mfma16(bf16x8 a, bf16x8 b, f32x4 c) { return __builtin_amdgcn_mfma_f32_16x16x32_bf16(a, b, c, 0, 0, 0); }
; #define SCHED_FENCE() do {} while (0)
; #define SCHED_FENCE() __builtin_amdgcn_sched_barrier(0)
; __device__ __forceinline__ void ssd_state_update(f32x4 (&H)[4][4], LAS unsigned char* Xi, int xp, LAS unsigned char* Bi, int bp, const LAS float* sDt, const LAS float* sCum, int w, int lane) {
;     ...
;     for (int ks = 0; ks < 2; ++ks) {
;         float wg[8];
; #pragma unroll
;         for (int j = 0; j < 8; ++j) wg[j] = __expf(tot - sCum[(32 * ks + 8 * g + j) * 4 + k]) * sDt[(32 * ks + 8 * g + j) * 4 + k];
;         bf16x8 Bx[4];
; #pragma unroll
;         for (int pt = 0; pt < 4; ++pt) Bx[pt] = scale_frag8(frag_tr(Xi, xp, 32 * ks + 8 * g, 32 * ks + 8 * g + 4, 64 * k + 16 * pt, lane), wg);
; #pragma unroll
;         for (int nt = 0; nt < 4; ++nt) { const bf16x8 A = frag_tr(Bi, bp, 32 * ks + 8 * g, 32 * ks + 8 * g + 4, 16 * (4 * nh + nt), lane);
; #pragma unroll
;             for (int pt = 0; pt < 4; ++pt) H[nt][pt] = mfma16(A, Bx[pt], H[nt][pt]);
;             SCHED_FENCE(); }
	v_lshlrev_b32_e32 v241, 16, v242
	v_mul_f32_e32 v135, v129, v135
	v_mul_f32_e32 v229, v129, v229
	v_and_b32_e32 v231, 0xffff0000, v236
	v_mul_f32_e32 v129, v129, v241
	v_and_b32_e32 v241, 0xffff0000, v242
	v_mul_f32_e32 v136, v130, v136
	v_mul_f32_e32 v231, v130, v231
	v_mul_f32_e32 v130, v130, v241
	v_cvt_pk_bf16_f32 v181, v130, v130
	v_lshlrev_b32_e32 v130, 16, v243
	v_mul_f32_e32 v130, v131, v130
	v_cvt_pk_bf16_f32 v182, v130, v130
	v_and_b32_e32 v130, 0xffff0000, v243
	v_mul_f32_e32 v130, v132, v130
	v_cvt_pk_bf16_f32 v154, v130, v130
	v_lshlrev_b32_e32 v130, 16, v244
	v_mul_f32_e32 v130, v133, v130
	v_cvt_pk_bf16_f32 v155, v130, v130
	v_and_b32_e32 v130, 0xffff0000, v244
	v_mul_f32_e32 v130, v134, v130
	v_cvt_pk_bf16_f32 v244, v130, v130
	v_lshlrev_b32_e32 v130, 16, v245
	v_mul_f32_e32 v130, v226, v130
	v_cvt_pk_bf16_f32 v177, v130, v130
	v_and_b32_e32 v130, 0xffff0000, v245
	v_lshlrev_b32_e32 v233, 16, v237
	v_and_b32_e32 v235, 0xffff0000, v237
	v_lshlrev_b32_e32 v236, 16, v238
	v_mul_f32_e32 v130, v240, v130
	v_mul_f32_e32 v137, v131, v137
	v_mul_f32_e32 v227, v132, v227
	v_mul_f32_e32 v228, v133, v228
	v_mul_f32_e32 v233, v131, v233
	v_mul_f32_e32 v235, v132, v235
	v_mul_f32_e32 v236, v133, v236
	v_cvt_pk_bf16_f32 v245, v130, v130
	ds_read_b64_tr_b16 v[130:131], v220 offset:512
	ds_read_b64_tr_b16 v[132:133], v220 offset:4672
	v_and_b32_e32 v237, 0xffff0000, v238
	v_lshlrev_b32_e32 v238, 16, v239
	v_and_b32_e32 v239, 0xffff0000, v239
	v_cvt_pk_bf16_f32 v135, v135, v135
	v_cvt_pk_bf16_f32 v136, v136, v136
	v_cvt_pk_bf16_f32 v137, v137, v137
	v_cvt_pk_bf16_f32 v227, v227, v227
	v_cvt_pk_bf16_f32 v228, v228, v228
	v_cvt_pk_bf16_f32 v229, v229, v229
	v_cvt_pk_bf16_f32 v231, v231, v231
	v_cvt_pk_bf16_f32 v233, v233, v233
	v_mul_f32_e32 v237, v134, v237
	v_mul_f32_e32 v238, v226, v238
	v_mul_f32_e32 v239, v240, v239
	v_cvt_pk_bf16_f32 v235, v235, v235
	v_cvt_pk_bf16_f32 v236, v236, v236
	v_cvt_pk_bf16_f32 v237, v237, v237
	v_cvt_pk_bf16_f32 v238, v238, v238
	v_cvt_pk_bf16_f32 v239, v239, v239
	v_cvt_pk_bf16_f32 v129, v129, v129
	v_perm_b32 v243, v234, v232, s75
	v_perm_b32 v242, v230, v228, s75
	v_perm_b32 v241, v227, v137, s75
	v_perm_b32 v240, v136, v135, s75
	v_perm_b32 v137, v239, v238, s75
	v_perm_b32 v136, v237, v236, s75
	v_perm_b32 v135, v235, v233, s75
	v_perm_b32 v134, v231, v229, s75
	v_perm_b32 v229, v180, v252, s75
	v_perm_b32 v228, v251, v250, s75
	v_perm_b32 v227, v249, v248, s75
	v_perm_b32 v226, v247, v246, s75
	v_perm_b32 v233, v245, v177, s75
	v_perm_b32 v232, v244, v155, s75
	v_perm_b32 v231, v154, v182, s75
	v_perm_b32 v230, v181, v129, s75
	s_waitcnt lgkmcnt(0)
	v_mfma_f32_16x16x32_bf16 v[96:99], v[130:133], v[240:243], v[96:99]
	v_mfma_f32_16x16x32_bf16 v[92:95], v[130:133], v[134:137], v[92:95]
	v_mfma_f32_16x16x32_bf16 v[88:91], v[130:133], v[226:229], v[88:91]
	v_mfma_f32_16x16x32_bf16 v[84:87], v[130:133], v[230:233], v[84:87]
	ds_read_b64_tr_b16 v[130:131], v220 offset:544
	ds_read_b64_tr_b16 v[132:133], v220 offset:4704
	s_waitcnt lgkmcnt(0)
	v_mfma_f32_16x16x32_bf16 v[68:71], v[130:133], v[240:243], v[68:71]
	v_mfma_f32_16x16x32_bf16 v[72:75], v[130:133], v[134:137], v[72:75]
	v_mfma_f32_16x16x32_bf16 v[76:79], v[130:133], v[226:229], v[76:79]
	v_mfma_f32_16x16x32_bf16 v[80:83], v[130:133], v[230:233], v[80:83]
	ds_read_b64_tr_b16 v[130:131], v220 offset:576
	ds_read_b64_tr_b16 v[132:133], v220 offset:4736
	s_waitcnt lgkmcnt(0)
	v_mfma_f32_16x16x32_bf16 v[60:63], v[130:133], v[240:243], v[60:63]
	v_mfma_f32_16x16x32_bf16 v[64:67], v[130:133], v[134:137], v[64:67]
	v_mfma_f32_16x16x32_bf16 v[56:59], v[130:133], v[226:229], v[56:59]
	v_mfma_f32_16x16x32_bf16 v[52:55], v[130:133], v[230:233], v[52:55]
	ds_read_b64_tr_b16 v[130:131], v220 offset:608
	ds_read_b64_tr_b16 v[132:133], v220 offset:4768
	s_waitcnt lgkmcnt(0)
	v_mfma_f32_16x16x32_bf16 v[48:51], v[130:133], v[240:243], v[48:51]
	v_mfma_f32_16x16x32_bf16 v[44:47], v[130:133], v[134:137], v[44:47]
	v_mfma_f32_16x16x32_bf16 v[40:43], v[130:133], v[226:229], v[40:43]
	v_mfma_f32_16x16x32_bf16 v[36:39], v[130:133], v[230:233], v[36:39]
	ds_read_b32 v129, v174
	ds_read_b32 v130, v175
	ds_read_b32 v131, v188
	ds_read_b32 v132, v189
	ds_read_b32 v133, v190
	ds_read_b32 v134, v191
	ds_read_b32 v135, v192
	ds_read_b32 v136, v193
	s_waitcnt lgkmcnt(0)
	v_sub_f32_e32 v129, v128, v129
	v_sub_f32_e32 v131, v128, v131
	v_sub_f32_e32 v133, v128, v133
	v_sub_f32_e32 v135, v128, v135
	v_mul_f32_e32 v129, 0x3fb8aa3b, v129
	v_mul_f32_e32 v131, 0x3fb8aa3b, v131
	v_mul_f32_e32 v133, 0x3fb8aa3b, v133
	v_mul_f32_e32 v135, 0x3fb8aa3b, v135
	v_exp_f32_e32 v129, v129
	v_exp_f32_e32 v131, v131
	v_exp_f32_e32 v133, v133
	v_exp_f32_e32 v135, v135
	v_mul_f32_e32 v129, v130, v129
	v_mul_f32_e32 v154, v132, v131
	v_mul_f32_e32 v155, v134, v133
	v_mul_f32_e32 v177, v136, v135
	ds_read_b32 v130, v194
	ds_read_b32 v131, v195
	ds_read_b32 v132, v196
	ds_read_b32 v133, v197
	ds_read_b32 v134, v198
	ds_read_b32 v135, v199
	ds_read_b32 v136, v200
	ds_read_b32 v137, v201
	s_waitcnt lgkmcnt(0)
	v_sub_f32_e32 v130, v128, v130
	v_sub_f32_e32 v132, v128, v132
	v_sub_f32_e32 v134, v128, v134
	v_sub_f32_e32 v136, v128, v136
	v_mul_f32_e32 v130, 0x3fb8aa3b, v130
	v_mul_f32_e32 v132, 0x3fb8aa3b, v132
	v_mul_f32_e32 v134, 0x3fb8aa3b, v134
	v_mul_f32_e32 v136, 0x3fb8aa3b, v136
	v_exp_f32_e32 v130, v130
	v_exp_f32_e32 v132, v132
	v_exp_f32_e32 v134, v134
	v_exp_f32_e32 v136, v136
	v_mul_f32_e32 v180, v131, v130
	v_mul_f32_e32 v181, v133, v132
	v_mul_f32_e32 v182, v135, v134
	v_mul_f32_e32 v232, v137, v136
	ds_read_b64_tr_b16 v[130:131], v221
	ds_read_b64_tr_b16 v[132:133], v221 offset:2112
	ds_read_b64_tr_b16 v[134:135], v221 offset:32
	ds_read_b64_tr_b16 v[136:137], v221 offset:64
	ds_read_b64_tr_b16 v[226:227], v221 offset:96
	s_waitcnt lgkmcnt(0)
; __device__ __forceinline__ f32x4 mfma16(bf16x8 a, bf16x8 b, f32x4 c) { return __builtin_amdgcn_mfma_f32_16x16x32_bf16(a, b, c, 0, 0, 0); }
; #define SCHED_FENCE() do {} while (0)
; #define SCHED_FENCE() __builtin_amdgcn_sched_barrier(0)
; __device__ __forceinline__ void ssd_state_update(f32x4 (&H)[4][4], LAS unsigned char* Xi, int xp, LAS unsigned char* Bi, int bp, const LAS float* sDt, const LAS float* sCum, int w, int lane) {
;     ...
;     for (int ks = 0; ks < 2; ++ks) {
;         float wg[8];
; #pragma unroll
;         for (int j = 0; j < 8; ++j) wg[j] = __expf(tot - sCum[(32 * ks + 8 * g + j) * 4 + k]) * sDt[(32 * ks + 8 * g + j) * 4 + k];
;         bf16x8 Bx[4];
; #pragma unroll
;         for (int pt = 0; pt < 4; ++pt) Bx[pt] = scale_frag8(frag_tr(Xi, xp, 32 * ks + 8 * g, 32 * ks + 8 * g + 4, 64 * k + 16 * pt, lane), wg);
; #pragma unroll
;         for (int nt = 0; nt < 4; ++nt) { const bf16x8 A = frag_tr(Bi, bp, 32 * ks + 8 * g, 32 * ks + 8 * g + 4, 16 * (4 * nh + nt), lane);
; #pragma unroll
;             for (int pt = 0; pt < 4; ++pt) H[nt][pt] = mfma16(A, Bx[pt], H[nt][pt]);
;             SCHED_FENCE(); }
	v_lshlrev_b32_e32 v228, 16, v130
	v_lshlrev_b32_e32 v237, 16, v132
	v_and_b32_e32 v132, 0xffff0000, v132
	v_mul_f32_e32 v132, v181, v132
	v_cvt_pk_bf16_f32 v238, v132, v132
	v_lshlrev_b32_e32 v132, 16, v133
	v_mul_f32_e32 v132, v182, v132
	v_cvt_pk_bf16_f32 v239, v132, v132
	v_and_b32_e32 v132, 0xffff0000, v133
	v_and_b32_e32 v130, 0xffff0000, v130
	v_mul_f32_e32 v132, v232, v132
	v_mul_f32_e32 v130, v154, v130
	v_cvt_pk_bf16_f32 v240, v132, v132
	v_lshlrev_b32_e32 v132, 16, v134
	v_cvt_pk_bf16_f32 v234, v130, v130
	v_lshlrev_b32_e32 v130, 16, v131
	v_mul_f32_e32 v132, v129, v132
	v_mul_f32_e32 v130, v155, v130
	v_cvt_pk_bf16_f32 v241, v132, v132
	v_and_b32_e32 v132, 0xffff0000, v134
	v_cvt_pk_bf16_f32 v235, v130, v130
	v_and_b32_e32 v130, 0xffff0000, v131
	v_mul_f32_e32 v132, v154, v132
	v_mul_f32_e32 v228, v129, v228
	v_mul_f32_e32 v130, v177, v130
	v_cvt_pk_bf16_f32 v242, v132, v132
	v_lshlrev_b32_e32 v132, 16, v135
	v_cvt_pk_bf16_f32 v233, v228, v228
	v_cvt_pk_bf16_f32 v236, v130, v130
	ds_read_b64_tr_b16 v[130:131], v221 offset:2144
	ds_read_b64_tr_b16 v[228:229], v221 offset:2176
	ds_read_b64_tr_b16 v[230:231], v221 offset:2208
	v_mul_f32_e32 v132, v155, v132
	v_cvt_pk_bf16_f32 v243, v132, v132
	v_and_b32_e32 v132, 0xffff0000, v135
	v_mul_f32_e32 v132, v177, v132
	v_cvt_pk_bf16_f32 v244, v132, v132
	s_waitcnt lgkmcnt(0)
	v_lshlrev_b32_e32 v132, 16, v130
	v_and_b32_e32 v130, 0xffff0000, v130
	v_mul_f32_e32 v130, v181, v130
	v_cvt_pk_bf16_f32 v246, v130, v130
	v_lshlrev_b32_e32 v130, 16, v131
	v_mul_f32_e32 v130, v182, v130
	v_cvt_pk_bf16_f32 v247, v130, v130
	v_and_b32_e32 v130, 0xffff0000, v131
	v_mul_f32_e32 v130, v232, v130
	v_cvt_pk_bf16_f32 v248, v130, v130
	v_lshlrev_b32_e32 v130, 16, v136
	v_mul_f32_e32 v130, v129, v130
	v_cvt_pk_bf16_f32 v249, v130, v130
	v_and_b32_e32 v130, 0xffff0000, v136
	v_mul_f32_e32 v130, v154, v130
	v_cvt_pk_bf16_f32 v250, v130, v130
	v_lshlrev_b32_e32 v130, 16, v137
	v_mul_f32_e32 v130, v155, v130
	v_cvt_pk_bf16_f32 v251, v130, v130
	v_and_b32_e32 v130, 0xffff0000, v137
	v_mul_f32_e32 v130, v177, v130
	v_cvt_pk_bf16_f32 v252, v130, v130
	v_lshlrev_b32_e32 v130, 16, v228
	v_mul_f32_e32 v130, v180, v130
	v_cvt_pk_bf16_f32 v150, v130, v130
	v_and_b32_e32 v130, 0xffff0000, v228
	v_mul_f32_e32 v130, v181, v130
	v_cvt_pk_bf16_f32 v151, v130, v130
	v_lshlrev_b32_e32 v130, 16, v229
	v_mul_f32_e32 v130, v182, v130
	v_cvt_pk_bf16_f32 v152, v130, v130
	v_and_b32_e32 v130, 0xffff0000, v229
	v_mul_f32_e32 v130, v232, v130
	v_cvt_pk_bf16_f32 v153, v130, v130
	v_lshlrev_b32_e32 v130, 16, v226
	v_mul_f32_e32 v129, v129, v130
	v_and_b32_e32 v130, 0xffff0000, v226
	v_mul_f32_e32 v130, v154, v130
	v_cvt_pk_bf16_f32 v154, v130, v130
	v_lshlrev_b32_e32 v130, 16, v227
	v_mul_f32_e32 v130, v155, v130
	v_cvt_pk_bf16_f32 v155, v130, v130
	v_and_b32_e32 v130, 0xffff0000, v227
	v_mul_f32_e32 v130, v177, v130
	v_cvt_pk_bf16_f32 v177, v130, v130
	v_lshlrev_b32_e32 v130, 16, v230
	v_mul_f32_e32 v130, v180, v130
	v_mul_f32_e32 v237, v180, v237
	v_mul_f32_e32 v132, v180, v132
	v_cvt_pk_bf16_f32 v180, v130, v130
	v_and_b32_e32 v130, 0xffff0000, v230
	v_mul_f32_e32 v130, v181, v130
	v_cvt_pk_bf16_f32 v181, v130, v130
	v_lshlrev_b32_e32 v130, 16, v231
	v_cvt_pk_bf16_f32 v245, v132, v132
	v_mul_f32_e32 v134, v182, v130
	ds_read_b64_tr_b16 v[130:131], v222 offset:512
	ds_read_b64_tr_b16 v[132:133], v222 offset:4672
	v_cvt_pk_bf16_f32 v182, v134, v134
	v_and_b32_e32 v134, 0xffff0000, v231
	v_cvt_pk_bf16_f32 v237, v237, v237
	v_mul_f32_e32 v134, v232, v134
	v_cvt_pk_bf16_f32 v129, v129, v129
	v_cvt_pk_bf16_f32 v179, v134, v134
	v_perm_b32 v137, v240, v239, s75
	v_perm_b32 v136, v238, v237, s75
	v_perm_b32 v135, v236, v235, s75
	v_perm_b32 v134, v234, v233, s75
	v_perm_b32 v229, v248, v247, s75
	v_perm_b32 v228, v246, v245, s75
	v_perm_b32 v227, v244, v243, s75
	v_perm_b32 v226, v242, v241, s75
	v_perm_b32 v233, v153, v152, s75
	v_perm_b32 v232, v151, v150, s75
	v_perm_b32 v231, v252, v251, s75
	v_perm_b32 v230, v250, v249, s75
	v_perm_b32 v237, v179, v182, s75
	v_perm_b32 v236, v181, v180, s75
	v_perm_b32 v235, v177, v155, s75
	v_perm_b32 v234, v154, v129, s75
	s_waitcnt lgkmcnt(0)
; #define LAS __attribute__((address_space(3)))
; __device__ __forceinline__ f32x4 mfma16(bf16x8 a, bf16x8 b, f32x4 c) { return __builtin_amdgcn_mfma_f32_16x16x32_bf16(a, b, c, 0, 0, 0); }
; __device__ __forceinline__ void sync_threads() { __syncthreads(); }
; #define SCHED_FENCE() do {} while (0)
; #define LAUNDER_PTR(p) do {} while (0)
; #define LAUNDER_PTR(p) asm volatile("" : "+v"(p))
; #define SCHED_FENCE() __builtin_amdgcn_sched_barrier(0)
; __device__ __forceinline__ void ssd_state_update(f32x4 (&H)[4][4], LAS unsigned char* Xi, int xp, LAS unsigned char* Bi, int bp, const LAS float* sDt, const LAS float* sCum, int w, int lane) {
;     ...
;         for (int nt = 0; nt < 4; ++nt) { const bf16x8 A = frag_tr(Bi, bp, 32 * ks + 8 * g, 32 * ks + 8 * g + 4, 16 * (4 * nh + nt), lane);
; #pragma unroll
;             for (int pt = 0; pt < 4; ++pt) H[nt][pt] = mfma16(A, Bx[pt], H[nt][pt]);
;             SCHED_FENCE(); }
; __device__ __forceinline__ void ssd_pass1(const RecurBufs& rb, const float* conv_w, const float* conv_b, const float* dt_bias, const float* a_log, float* conv_out_l, int u, int tid, LAS unsigned char* lds) {
;     ...
;         {   bf16* gp = rb.xbcc + (row0 + rr) * 4096 + gcol;
;             const LAS unsigned char* src = ch16 < 32 ? (XO + ch16 * 16) : (T + ch16 * 16); const int spitch = ch16 < 32 ? PX : PR;
; #pragma unroll
;             for (int i = 0; i < 8; ++i) { LAUNDER_PTR(gp); *(v4u*)gp = *(const LAS v4u*)(src + (rr + 8 * i) * spitch); gp += 8 * 4096; } }
;         sync_threads();
	v_mfma_f32_16x16x32_bf16 v[96:99], v[130:133], v[134:137], v[96:99]
	v_mfma_f32_16x16x32_bf16 v[92:95], v[130:133], v[226:229], v[92:95]
	v_mfma_f32_16x16x32_bf16 v[88:91], v[130:133], v[230:233], v[88:91]
	v_mfma_f32_16x16x32_bf16 v[84:87], v[130:133], v[234:237], v[84:87]
	ds_read_b64_tr_b16 v[130:131], v222 offset:544
	ds_read_b64_tr_b16 v[132:133], v222 offset:4704
	s_waitcnt lgkmcnt(0)
	v_mfma_f32_16x16x32_bf16 v[68:71], v[130:133], v[134:137], v[68:71]
	v_mfma_f32_16x16x32_bf16 v[72:75], v[130:133], v[226:229], v[72:75]
	v_mfma_f32_16x16x32_bf16 v[76:79], v[130:133], v[230:233], v[76:79]
	v_mfma_f32_16x16x32_bf16 v[80:83], v[130:133], v[234:237], v[80:83]
	ds_read_b64_tr_b16 v[130:131], v222 offset:576
	ds_read_b64_tr_b16 v[132:133], v222 offset:4736
	s_waitcnt lgkmcnt(0)
	v_mfma_f32_16x16x32_bf16 v[60:63], v[130:133], v[134:137], v[60:63]
	v_mfma_f32_16x16x32_bf16 v[64:67], v[130:133], v[226:229], v[64:67]
	v_mfma_f32_16x16x32_bf16 v[56:59], v[130:133], v[230:233], v[56:59]
	v_mfma_f32_16x16x32_bf16 v[52:55], v[130:133], v[234:237], v[52:55]
	ds_read_b64_tr_b16 v[130:131], v222 offset:608
	ds_read_b64_tr_b16 v[132:133], v222 offset:4768
	s_waitcnt lgkmcnt(0)
	v_mfma_f32_16x16x32_bf16 v[48:51], v[130:133], v[134:137], v[48:51]
	v_mfma_f32_16x16x32_bf16 v[44:47], v[130:133], v[226:229], v[44:47]
	v_mfma_f32_16x16x32_bf16 v[40:43], v[130:133], v[230:233], v[40:43]
	v_mfma_f32_16x16x32_bf16 v[36:39], v[130:133], v[234:237], v[36:39]
	v_lshl_add_u64 v[130:131], s[68:69], 0, v[116:117]
	v_lshlrev_b64 v[130:131], 13, v[130:131]
	v_lshl_add_u64 v[134:135], v[126:127], 0, v[130:131]
	v_add_u32_e32 v129, v202, v209
	ds_read_b128 v[130:133], v129
	v_add_u32_e32 v129, v202, v210
	v_add_f32_e32 v140, v140, v128
	s_cmp_eq_u32 s3, 8
	s_waitcnt lgkmcnt(0)
	global_store_dwordx4 v[134:135], v[130:133], off
	v_lshl_add_u64 v[134:135], v[134:135], 0, s[42:43]
	ds_read_b128 v[130:133], v129
	v_add_u32_e32 v129, v202, v211
	s_waitcnt lgkmcnt(0)
	global_store_dwordx4 v[134:135], v[130:133], off
	v_lshl_add_u64 v[134:135], v[134:135], 0, s[42:43]
	ds_read_b128 v[130:133], v129
	v_add_u32_e32 v129, v202, v212
	s_waitcnt lgkmcnt(0)
	global_store_dwordx4 v[134:135], v[130:133], off
	v_lshl_add_u64 v[134:135], v[134:135], 0, s[42:43]
	ds_read_b128 v[130:133], v129
	v_add_u32_e32 v129, v202, v213
	s_waitcnt lgkmcnt(0)
	global_store_dwordx4 v[134:135], v[130:133], off
	v_lshl_add_u64 v[134:135], v[134:135], 0, s[42:43]
	ds_read_b128 v[130:133], v129
	v_add_u32_e32 v129, v202, v214
	s_waitcnt lgkmcnt(0)
	global_store_dwordx4 v[134:135], v[130:133], off
	v_lshl_add_u64 v[134:135], v[134:135], 0, s[42:43]
	ds_read_b128 v[130:133], v129
	v_add_u32_e32 v129, v202, v215
	s_waitcnt lgkmcnt(0)
	global_store_dwordx4 v[134:135], v[130:133], off
	v_lshl_add_u64 v[134:135], v[134:135], 0, s[42:43]
	ds_read_b128 v[130:133], v129
	s_waitcnt lgkmcnt(0)
	global_store_dwordx4 v[134:135], v[130:133], off
	v_lshl_add_u64 v[134:135], v[134:135], 0, s[42:43]
	ds_read_b128 v[130:133], v223
	s_waitcnt lgkmcnt(0)
	global_store_dwordx4 v[134:135], v[130:133], off
	s_waitcnt lgkmcnt(0)
	s_barrier
	s_cbranch_scc1 .LBB0_753

; __device__ __forceinline__ float bf2f(bf16 v) { return __uint_as_float(((unsigned)v) << 16); }
; __device__ __forceinline__ float softplusf_(float x) { return x > 20.f ? x : log1pf(__expf(x)); }
; __device__ __forceinline__ void ssd_pass1(const RecurBufs& rb, const float* conv_w, const float* conv_b, const float* dt_bias, const float* a_log, float* conv_out_l, int u, int tid, LAS unsigned char* lds) {
;     ...
;         if (w < 4) {
;             const int head = grp * 4 + w; const size_t row = row0 + lane;
;             const float dv = softplusf_(bf2f(dtn) + dt_bias[head]);
;             if (ch + 1 < NCH) dtn = rb.proj[(row + RC) * LDP + PC_DT + head];
.LBB0_712:
	s_or_b64 exec, exec, s[72:73]
	v_mov_b32_e32 v129, s69
	s_cmp_eq_u32 s3, 7
	v_or_b32_e32 v128, s68, v111
	s_cbranch_scc1 .LBB0_714
	v_mov_b64_e32 v[132:133], s[78:79]
	v_mad_u64_u32 v[132:133], s[22:23], v128, s77, v[132:133]
	v_mov_b32_e32 v134, v133
	v_mad_u64_u32 v[134:135], s[22:23], v129, s77, v[134:135]
	v_mov_b32_e32 v133, v134
	v_lshl_add_u64 v[132:133], v[118:119], 1, v[132:133]
	v_add_co_u32_e32 v132, vcc, 0x18e000, v132
	s_nop 1
	v_addc_co_u32_e32 v133, vcc, 0, v133, vcc
	global_load_ushort v142, v[132:133], off

; #define LAS __attribute__((address_space(3)))
; #define LAUNDER_PTR(p) do {} while (0)
; #define LAUNDER_PTR(p) asm volatile("" : "+v"(p))
; __device__ __forceinline__ void ssd_pass1(const RecurBufs& rb, const float* conv_w, const float* conv_b, const float* dt_bias, const float* a_log, float* conv_out_l, int u, int tid, LAS unsigned char* lds) {
;     ...
;         for (int i = 0; i < 8; ++i) *(LAS v4u*)(T + (rr + 8 * i) * PR + ch16 * 16) = raw[i];
;         if (ch + 1 < NCH) { const bf16* gp = rb.proj + (row0 + RC + rr) * LDP + PC_XBC + gcol;
; #pragma unroll
;             for (int i = 0; i < 8; ++i) { LAUNDER_PTR(gp); raw[i] = *(const v4u*)gp; gp += 8 * (size_t)LDP; } }
.LBB0_715:
	s_or_b64 exec, exec, s[70:71]
	s_cmp_eq_u32 s3, 7
	s_waitcnt vmcnt(0) lgkmcnt(0)
	ds_write_b128 v218, v[0:3]
	ds_write_b128 v218, v[4:7] offset:8320
	ds_write_b128 v218, v[12:15] offset:16640
	ds_write_b128 v218, v[16:19] offset:24960
	ds_write_b128 v218, v[20:23] offset:33280
	ds_write_b128 v218, v[24:27] offset:41600
	ds_write_b128 v218, v[28:31] offset:49920
	ds_write_b128 v218, v[32:35] offset:58240
	s_cbranch_scc1 .LBB0_717
	v_lshl_add_u64 v[0:1], v[124:125], 0, s[68:69]
	v_mov_b64_e32 v[2:3], s[78:79]
	v_mad_u64_u32 v[2:3], s[22:23], v0, s77, v[2:3]
	v_mov_b32_e32 v0, v3
	v_mad_u64_u32 v[0:1], s[22:23], v1, s77, v[0:1]
	v_mov_b32_e32 v3, v0
	v_lshl_add_u64 v[0:1], v[114:115], 1, v[2:3]
	v_lshl_add_u64 v[4:5], v[0:1], 0, s[92:93]
	global_load_dwordx4 v[0:3], v[4:5], off
	v_lshl_add_u64 v[12:13], v[4:5], 0, s[84:85]
	global_load_dwordx4 v[4:7], v[12:13], off
	v_lshl_add_u64 v[16:17], v[12:13], 0, s[84:85]
	global_load_dwordx4 v[12:15], v[16:17], off
	v_lshl_add_u64 v[20:21], v[16:17], 0, s[84:85]
	global_load_dwordx4 v[16:19], v[20:21], off
	v_lshl_add_u64 v[24:25], v[20:21], 0, s[84:85]
	global_load_dwordx4 v[20:23], v[24:25], off
	v_lshl_add_u64 v[28:29], v[24:25], 0, s[84:85]
	global_load_dwordx4 v[24:27], v[28:29], off
	v_lshl_add_u64 v[32:33], v[28:29], 0, s[84:85]
	global_load_dwordx4 v[28:31], v[32:33], off
	v_lshl_add_u64 v[32:33], v[32:33], 0, s[84:85]
	global_load_dwordx4 v[32:35], v[32:33], off

; __device__ __forceinline__ unsigned xb_ld(unsigned* p)              { return __hip_atomic_load(p, __ATOMIC_RELAXED, __HIP_MEMORY_SCOPE_AGENT); }
; __device__ __forceinline__ void xcd_barrier_complete(unsigned* bar, unsigned x, unsigned& nloc, unsigned& nx) {
;     const unsigned G = gridDim.x * gridDim.y * gridDim.z;
;     unsigned sum, cnt, mine, sp = 0u;
;     for (;;) {
;         sum = 0u; cnt = 0u; mine = 0u;
; #pragma unroll
;         for (unsigned j = 0; j < 16; ++j) { const unsigned c = xb_ld(&bar[XB_XCNT(j)]); sum += c; cnt += (c > 0u) ? 1u : 0u; mine = (j == x) ? c : mine; }
;         if (sum == G) break;
;         __builtin_amdgcn_s_sleep(1);
;         if ((++sp & 255u) == 0u) { if (xb_ld(&bar[XB_TMO])) break; if (sp > XB_SPIN_CAP) { atomicAdd(&bar[XB_TMO], 1u); break; } }
;     }
;     nloc = mine > 0u ? mine : 1u; nx = cnt > 0u ? cnt : 1u;
; }
.LBB0_762:
	v_mov_b64_e32 v[12:13], s[36:37]
	global_load_dword v1, v[12:13], off offset:1024 sc1
	global_load_dword v0, v[12:13], off offset:1280 sc1
	global_load_dword v2, v[12:13], off offset:1536 sc1
	s_or_b64 s[18:19], s[18:19], exec
	s_or_b64 s[16:17], s[16:17], exec
	s_waitcnt vmcnt(0) lgkmcnt(0)
	v_add_u32_e32 v3, v0, v1
	v_add_u32_e32 v4, v3, v2
	global_load_dword v3, v[12:13], off offset:1792 sc1
	s_waitcnt vmcnt(0) lgkmcnt(0)
	v_add_u32_e32 v5, v4, v3
	global_load_dword v4, v[12:13], off offset:2048 sc1
	s_waitcnt vmcnt(0) lgkmcnt(0)
	v_add_u32_e32 v6, v5, v4
	global_load_dword v5, v[12:13], off offset:2304 sc1
	s_waitcnt vmcnt(0) lgkmcnt(0)
	v_add_u32_e32 v7, v6, v5
	global_load_dword v6, v[12:13], off offset:2560 sc1
	s_waitcnt vmcnt(0) lgkmcnt(0)
	v_add_u32_e32 v8, v7, v6
	global_load_dword v7, v[12:13], off offset:2816 sc1
	s_waitcnt vmcnt(0) lgkmcnt(0)
	v_add_u32_e32 v9, v8, v7
	global_load_dword v8, v[12:13], off offset:3072 sc1
	s_waitcnt vmcnt(0) lgkmcnt(0)
	v_add_u32_e32 v10, v9, v8
	global_load_dword v9, v[12:13], off offset:3328 sc1
	s_waitcnt vmcnt(0) lgkmcnt(0)
	v_add_u32_e32 v14, v10, v9
	global_load_dword v10, v[12:13], off offset:3584 sc1
	s_waitcnt vmcnt(0) lgkmcnt(0)
	v_add_u32_e32 v14, v14, v10
	global_load_dword v12, v[12:13], off offset:3840 sc1
	s_waitcnt vmcnt(0) lgkmcnt(0)
	v_add_u32_e32 v16, v14, v12
	v_mov_b64_e32 v[14:15], s[4:5]
	global_load_dword v13, v[14:15], off sc1
	v_mov_b64_e32 v[14:15], s[6:7]
	global_load_dword v14, v[14:15], off sc1
	s_waitcnt vmcnt(0) lgkmcnt(0)
	v_add_u32_e32 v16, v16, v13
	v_add_u32_e32 v18, v16, v14
	v_mov_b64_e32 v[16:17], s[8:9]
	global_load_dword v15, v[16:17], off sc1
	v_mov_b64_e32 v[16:17], s[10:11]
	global_load_dword v16, v[16:17], off sc1
	s_waitcnt vmcnt(0) lgkmcnt(0)
	v_add_u32_e32 v18, v18, v15
	v_add_u32_e32 v17, v18, v16
	v_cmp_ne_u32_e32 vcc, s1, v17
	s_and_saveexec_b64 s[20:21], vcc
	s_cbranch_execz .LBB0_761
	s_and_b32 s24, s30, 0xff
	s_mov_b64 s[22:23], -1
	s_cmp_eq_u32 s24, 0
	s_mov_b64 s[26:27], -1
	s_mov_b64 s[24:25], -1
	s_sleep 1
	s_cbranch_scc1 .LBB0_765
	s_and_saveexec_b64 s[28:29], s[26:27]
	s_cbranch_execz .LBB0_760
	s_branch .LBB0_768
.LBB0_765:
	v_mov_b64_e32 v[18:19], s[36:37]
	global_load_dword v17, v[18:19], off offset:512 sc1
	s_mov_b64 s[26:27], 0
	s_waitcnt vmcnt(0) lgkmcnt(0)
	v_cmp_eq_u32_e32 vcc, 0, v17
	s_and_saveexec_b64 s[28:29], vcc
	s_cmp_lt_u32 s30, 0x40001
	s_cselect_b64 s[26:27], -1, 0
	s_xor_b64 s[24:25], exec, -1
	s_and_b64 s[26:27], s[26:27], exec
	s_or_b64 exec, exec, s[28:29]
	s_and_saveexec_b64 s[28:29], s[26:27]
	s_cbranch_execz .LBB0_760

; __device__ __forceinline__ unsigned xb_ld(unsigned* p)              { return __hip_atomic_load(p, __ATOMIC_RELAXED, __HIP_MEMORY_SCOPE_AGENT); }
; __device__ __forceinline__ unsigned xb_add(unsigned* p, unsigned v) { return __hip_atomic_fetch_add(p, v, __ATOMIC_RELAXED, __HIP_MEMORY_SCOPE_AGENT); }
; #define XB_SPIN(cond, bar) do { unsigned _sp = 0; while (cond) { __builtin_amdgcn_s_sleep(1); \
;     if ((++_sp & 255u) == 0u) { if (xb_ld(&(bar)[XB_TMO])) break; if (_sp > XB_SPIN_CAP) { atomicAdd(&(bar)[XB_TMO], 1u); break; } } } } while (0)
; __device__ __forceinline__ void xcd_barrier(const XcdBarrier& b, int tid) {
;     ...
;         const unsigned old = xb_add(&bar[XB_XSUB(bx_)], 1u);
;         const unsigned gen = old / nloc;
;         if (old + 1u == (gen + 1u) * nloc) {
;             __builtin_amdgcn_fence(__ATOMIC_RELEASE, "agent");
;             asm volatile("s_waitcnt vmcnt(0)" ::: "memory");
;             const unsigned og = xb_add(&bar[XB_TOP], 1u);
;             const unsigned tg = og / nx;
;             if (og + 1u == (tg + 1u) * nx) xb_add(&bar[XB_TOPGEN], 1u);
;             else XB_SPIN(xb_ld(&bar[XB_TOPGEN]) == tg, bar);
;             __builtin_amdgcn_fence(__ATOMIC_ACQUIRE, "agent");
;             xb_add(&bar[XB_XGEN(bx_)], 1u);
;             asm volatile("s_waitcnt vmcnt(0)" ::: "memory");
;         } else {
;             XB_SPIN(xb_ld(&bar[XB_XGEN(bx_)]) == gen, bar);
.LBB0_772:
	s_lshl_b32 s0, s0, 6
	s_add_i32 s64, s0, 0x500
	s_lshl_b64 s[4:5], s[64:65], 2
	s_add_u32 s4, s36, s4
	s_addc_u32 s5, s37, s5
	v_mov_b64_e32 v[4:5], s[4:5]
	v_mov_b32_e32 v1, 1
	flat_atomic_add v3, v[4:5], v1 sc0
	v_cvt_f32_u32_e32 v1, v2
	v_sub_u32_e32 v4, 0, v2
	v_rcp_iflag_f32_e32 v1, v1
	s_nop 0
	v_mul_f32_e32 v1, 0x4f7ffffe, v1
	v_cvt_u32_f32_e32 v1, v1
	v_mul_lo_u32 v4, v4, v1
	v_mul_hi_u32 v4, v1, v4
	v_add_u32_e32 v1, v1, v4
	s_waitcnt vmcnt(0) lgkmcnt(0)
	v_mul_hi_u32 v1, v3, v1
	v_mul_lo_u32 v4, v1, v2
	v_sub_u32_e32 v4, v3, v4
	v_cmp_ge_u32_e32 vcc, v4, v2
	v_add_u32_e32 v5, 1, v1
	s_nop 0
	v_cndmask_b32_e32 v1, v1, v5, vcc
	v_sub_u32_e32 v5, v4, v2
	v_cndmask_b32_e32 v4, v4, v5, vcc
	v_cmp_ge_u32_e32 vcc, v4, v2
	v_add_u32_e32 v4, 1, v1
	s_nop 0
	v_cndmask_b32_e32 v1, v1, v4, vcc
	v_add_u32_e32 v4, 1, v3
	v_mad_u64_u32 v[2:3], s[4:5], v2, v1, v[2:3]
	v_cmp_ne_u32_e32 vcc, v4, v2
	s_and_saveexec_b64 s[4:5], vcc
	s_xor_b64 s[4:5], exec, s[4:5]
	s_cbranch_execz .LBB0_785
	s_add_i32 s64, s0, 0x900
	s_lshl_b64 s[6:7], s[64:65], 2
	s_add_u32 s8, s36, s6
	s_addc_u32 s9, s37, s7
	v_mov_b64_e32 v[2:3], s[8:9]
	global_load_dword v0, v[2:3], off sc1
	s_waitcnt vmcnt(0) lgkmcnt(0)
	v_cmp_eq_u32_e32 vcc, v0, v1
	s_and_saveexec_b64 s[6:7], vcc
	s_cbranch_execz .LBB0_784
	s_mov_b32 s1, 1
	s_mov_b64 s[10:11], 0
	s_branch .LBB0_776

; __device__ __forceinline__ unsigned xb_ld(unsigned* p)              { return __hip_atomic_load(p, __ATOMIC_RELAXED, __HIP_MEMORY_SCOPE_AGENT); }
; #define XB_SPIN(cond, bar) do { unsigned _sp = 0; while (cond) { __builtin_amdgcn_s_sleep(1); \
;     if ((++_sp & 255u) == 0u) { if (xb_ld(&(bar)[XB_TMO])) break; if (_sp > XB_SPIN_CAP) { atomicAdd(&(bar)[XB_TMO], 1u); break; } } } } while (0)
; __device__ __forceinline__ void xcd_barrier(const XcdBarrier& b, int tid) {
;     ...
;             XB_SPIN(xb_ld(&bar[XB_XGEN(bx_)]) == gen, bar);
.LBB0_776:
	s_and_b32 s18, s1, 0xff
	s_mov_b64 s[16:17], -1
	s_cmp_lg_u32 s18, 0
	s_mov_b64 s[18:19], -1
	s_sleep 1
	s_cbranch_scc1 .LBB0_780
	v_mov_b64_e32 v[2:3], s[36:37]
	global_load_dword v0, v[2:3], off offset:512 sc1
	s_mov_b64 s[18:19], 0
	s_mov_b64 s[20:21], -1
	s_waitcnt vmcnt(0) lgkmcnt(0)
	v_cmp_eq_u32_e32 vcc, 0, v0
	s_and_saveexec_b64 s[22:23], vcc
	s_cmp_lt_u32 s1, 0x40001
	s_cselect_b64 s[18:19], -1, 0
	s_xor_b64 s[20:21], exec, -1
	s_and_b64 s[18:19], s[18:19], exec
	s_or_b64 exec, exec, s[22:23]
.LBB0_780:
	s_andn2_b64 s[14:15], s[14:15], exec
	s_and_b64 s[20:21], s[20:21], exec
	s_or_b64 s[14:15], s[14:15], s[20:21]
	s_and_saveexec_b64 s[20:21], s[18:19]
	s_cbranch_execz .LBB0_775
	v_mov_b64_e32 v[2:3], s[8:9]
	global_load_dword v0, v[2:3], off sc1
	s_add_i32 s1, s1, 1
	s_or_b64 s[14:15], s[14:15], exec
	s_waitcnt vmcnt(0) lgkmcnt(0)
	v_cmp_ne_u32_e32 vcc, v0, v1
	s_orn2_b64 s[16:17], vcc, exec
	s_branch .LBB0_775

; __device__ __forceinline__ unsigned xb_ld(unsigned* p)              { return __hip_atomic_load(p, __ATOMIC_RELAXED, __HIP_MEMORY_SCOPE_AGENT); }
; __device__ __forceinline__ unsigned xb_add(unsigned* p, unsigned v) { return __hip_atomic_fetch_add(p, v, __ATOMIC_RELAXED, __HIP_MEMORY_SCOPE_AGENT); }
; #define XB_SPIN(cond, bar) do { unsigned _sp = 0; while (cond) { __builtin_amdgcn_s_sleep(1); \
;     if ((++_sp & 255u) == 0u) { if (xb_ld(&(bar)[XB_TMO])) break; if (_sp > XB_SPIN_CAP) { atomicAdd(&(bar)[XB_TMO], 1u); break; } } } } while (0)
; __device__ __forceinline__ void xcd_barrier(const XcdBarrier& b, int tid) {
;     ...
;         if (old + 1u == (gen + 1u) * nloc) {
;             __builtin_amdgcn_fence(__ATOMIC_RELEASE, "agent");
;             asm volatile("s_waitcnt vmcnt(0)" ::: "memory");
;             const unsigned og = xb_add(&bar[XB_TOP], 1u);
;             const unsigned tg = og / nx;
;             if (og + 1u == (tg + 1u) * nx) xb_add(&bar[XB_TOPGEN], 1u);
;             else XB_SPIN(xb_ld(&bar[XB_TOPGEN]) == tg, bar);
.LBB0_785:
	s_andn2_saveexec_b64 s[4:5], s[4:5]
	s_cbranch_execz .LBB0_801
	v_mov_b32_e32 v1, s36
	v_add_co_u32_e32 v2, vcc, 0x3000, v1
	v_mov_b32_e32 v1, s37
	buffer_wbl2 sc1
	s_waitcnt vmcnt(0)
	v_addc_co_u32_e32 v3, vcc, 0, v1, vcc
	v_mov_b32_e32 v1, 1
	flat_atomic_add v1, v[2:3], v1 offset:1024 sc0
	v_cvt_f32_u32_e32 v2, v0
	v_sub_u32_e32 v3, 0, v0
	s_mov_b64 s[8:9], -1
	v_rcp_iflag_f32_e32 v2, v2
	s_nop 0
	v_mul_f32_e32 v2, 0x4f7ffffe, v2
	v_cvt_u32_f32_e32 v2, v2
	v_mul_lo_u32 v3, v3, v2
	v_mul_hi_u32 v3, v2, v3
	v_add_u32_e32 v2, v2, v3
	s_waitcnt vmcnt(0) lgkmcnt(0)
	v_mul_hi_u32 v2, v1, v2
	v_mul_lo_u32 v3, v2, v0
	v_sub_u32_e32 v3, v1, v3
	v_cmp_ge_u32_e32 vcc, v3, v0
	v_add_u32_e32 v4, 1, v2
	s_nop 0
	v_cndmask_b32_e32 v2, v2, v4, vcc
	v_sub_u32_e32 v4, v3, v0
	v_cndmask_b32_e32 v3, v3, v4, vcc
	v_cmp_ge_u32_e32 vcc, v3, v0
	v_add_u32_e32 v3, 1, v2
	s_nop 0
	v_cndmask_b32_e32 v2, v2, v3, vcc
	v_add_u32_e32 v3, 1, v1
	v_mad_u64_u32 v[0:1], s[4:5], v0, v2, v[0:1]
	s_add_u32 s4, s36, 0x3500
	s_addc_u32 s5, s37, 0
	v_cmp_ne_u32_e32 vcc, v3, v0
	v_mov_b64_e32 v[0:1], s[4:5]
	s_and_saveexec_b64 s[6:7], vcc
	s_cbranch_execz .LBB0_798
	v_mov_b64_e32 v[0:1], s[4:5]
	global_load_dword v0, v[0:1], off sc1
	s_mov_b64 s[12:13], 0
	s_waitcnt vmcnt(0) lgkmcnt(0)
	v_cmp_eq_u32_e32 vcc, v0, v2
	s_and_saveexec_b64 s[10:11], vcc
	s_cbranch_execz .LBB0_797
	s_add_u32 s8, s36, 0x200
	s_addc_u32 s9, s37, 0
	s_mov_b32 s1, 1
	s_branch .LBB0_790

; __device__ __forceinline__ unsigned xb_ld(unsigned* p)              { return __hip_atomic_load(p, __ATOMIC_RELAXED, __HIP_MEMORY_SCOPE_AGENT); }
; #define XB_SPIN(cond, bar) do { unsigned _sp = 0; while (cond) { __builtin_amdgcn_s_sleep(1); \
;     if ((++_sp & 255u) == 0u) { if (xb_ld(&(bar)[XB_TMO])) break; if (_sp > XB_SPIN_CAP) { atomicAdd(&(bar)[XB_TMO], 1u); break; } } } } while (0)
; __device__ __forceinline__ void xcd_barrier(const XcdBarrier& b, int tid) {
;     ...
;             else XB_SPIN(xb_ld(&bar[XB_TOPGEN]) == tg, bar);
.LBB0_792:
	v_mov_b64_e32 v[0:1], s[8:9]
	global_load_dword v0, v[0:1], off sc1
	s_mov_b64 s[20:21], 0
	s_mov_b64 s[18:19], -1
	s_waitcnt vmcnt(0) lgkmcnt(0)
	v_cmp_eq_u32_e32 vcc, 0, v0
	s_and_saveexec_b64 s[22:23], vcc
	s_cmp_lt_u32 s1, 0x40001
	s_cselect_b64 s[20:21], -1, 0
	s_xor_b64 s[18:19], exec, -1
	s_and_b64 s[20:21], s[20:21], exec
	s_or_b64 exec, exec, s[22:23]
	s_and_saveexec_b64 s[22:23], s[20:21]
	s_cbranch_execz .LBB0_789
.LBB0_795:
	v_mov_b64_e32 v[0:1], s[4:5]
	global_load_dword v0, v[0:1], off sc1
	s_add_i32 s1, s1, 1
	s_or_b64 s[18:19], s[18:19], exec
	s_waitcnt vmcnt(0) lgkmcnt(0)
	v_cmp_ne_u32_e32 vcc, v0, v2
	s_orn2_b64 s[16:17], vcc, exec
	s_branch .LBB0_789

; #define LAUNDER_PTR(p) do {} while (0)
; #define LAUNDER_PTR(p) asm volatile("" : "+v"(p))
; __device__ __forceinline__ void hgrn_pass2(const RecurBufs& rb, const float* hgn_l, float* state_out_l, int u, int tid, LAS unsigned char* lds) {
;     ...
;     {
;         f32x4 L[3][8], dcs[3];
; #pragma unroll
;         for (int s = 0; s < 3; ++s) if (s < seg) { const int u2 = u - seg + s;
;             dcs[s] = *(const f32x4*)(rb.dseg + u2 * 128 + 16 * w + 4 * g);
;             const float* sp = rb.sseg + (size_t)u2 * 16384 + tid * 4;
; #pragma unroll
;             for (int et = 0; et < 8; ++et) { LAUNDER_PTR(sp); L[s][et] = *(const f32x4*)sp; sp += 2048; } }
; #pragma unroll
;         for (int s = 0; s < 3; ++s) if (s < seg) {
; #pragma unroll
;             for (int et = 0; et < 8; ++et) S[et] = S[et] * dcs[s] + L[s][et]; } }
.LBB0_804:
	v_mov_b32_e32 v112, v137
	s_and_b32 s8, s69, 3
	v_ashrrev_i32_e32 v123, 6, v112
	s_and_b32 s6, s69, -4
	v_lshrrev_b32_e32 v0, 2, v112
	v_lshlrev_b32_e32 v114, 4, v123
	v_and_b32_e32 v122, 12, v0
	v_lshlrev_b32_e32 v116, 2, v112
	s_cmp_lg_u32 s8, 0
	v_ashrrev_i32_e32 v115, 31, v114
	v_ashrrev_i32_e32 v117, 31, v116
	s_cselect_b64 s[4:5], -1, 0
	s_cmp_eq_u32 s8, 0
	v_lshlrev_b32_e32 v8, 2, v122
	s_cbranch_scc1 .LBB0_846
	s_lshl_b32 s2, s6, 7
	s_ashr_i32 s3, s2, 31
	s_lshl_b64 s[2:3], s[2:3], 2
	s_add_u32 s2, s66, s2
	s_addc_u32 s3, s67, s3
	s_ashr_i32 s7, s6, 31
	v_lshl_add_u64 v[0:1], v[114:115], 2, s[2:3]
	s_lshl_b64 s[2:3], s[6:7], 16
	v_mov_b32_e32 v9, v11
	s_add_u32 s2, s62, s2
	v_lshl_add_u64 v[0:1], v[0:1], 0, v[8:9]
	s_addc_u32 s3, s63, s3
	global_load_dwordx4 v[16:19], v[0:1], off
	v_lshl_add_u64 v[0:1], v[116:117], 2, s[2:3]
	global_load_dwordx4 v[12:15], v[0:1], off
	v_lshl_add_u64 v[4:5], v[0:1], 0, s[44:45]
	global_load_dwordx4 v[0:3], v[4:5], off
	v_lshl_add_u64 v[4:5], v[4:5], 0, s[44:45]
	global_load_dwordx4 v[24:27], v[4:5], off
	v_lshl_add_u64 v[20:21], v[4:5], 0, s[44:45]
	global_load_dwordx4 v[4:7], v[20:21], off
	v_lshl_add_u64 v[20:21], v[20:21], 0, s[44:45]
	global_load_dwordx4 v[44:47], v[20:21], off
	v_lshl_add_u64 v[20:21], v[20:21], 0, s[44:45]
	global_load_dwordx4 v[52:55], v[20:21], off
	v_lshl_add_u64 v[20:21], v[20:21], 0, s[44:45]
	global_load_dwordx4 v[60:63], v[20:21], off
	v_lshl_add_u64 v[20:21], v[20:21], 0, s[44:45]
	global_load_dwordx4 v[108:111], v[20:21], off
	s_waitcnt vmcnt(0) lgkmcnt(0)
	v_pk_mul_f32 v[120:121], v[18:19], 0 op_sel_hi:[1,0]
	v_pk_mul_f32 v[118:119], v[16:17], 0 op_sel_hi:[1,0]
	s_cmp_gt_u32 s8, 1
	s_cselect_b64 s[2:3], -1, 0
	s_cmp_lt_u32 s8, 2
	s_cbranch_scc1 .LBB0_807
.LBB0_806:
	s_or_b32 s10, s6, 1
	s_lshl_b32 s12, s10, 7
	s_ashr_i32 s13, s12, 31
	s_lshl_b64 s[12:13], s[12:13], 2
	s_add_u32 s12, s66, s12
	s_addc_u32 s13, s67, s13
	s_ashr_i32 s11, s10, 31
	s_lshl_b64 s[10:11], s[10:11], 16
	v_lshl_add_u64 v[16:17], v[114:115], 2, s[12:13]
	v_mov_b32_e32 v9, v11
	s_add_u32 s10, s62, s10
	v_lshl_add_u64 v[16:17], v[16:17], 0, v[8:9]
	s_addc_u32 s11, s63, s11
	global_load_dwordx4 v[48:51], v[16:17], off
	v_lshl_add_u64 v[16:17], v[116:117], 2, s[10:11]
	global_load_dwordx4 v[104:107], v[16:17], off
	v_lshl_add_u64 v[16:17], v[16:17], 0, s[44:45]
	global_load_dwordx4 v[100:103], v[16:17], off
	v_lshl_add_u64 v[16:17], v[16:17], 0, s[44:45]
	global_load_dwordx4 v[96:99], v[16:17], off
	v_lshl_add_u64 v[16:17], v[16:17], 0, s[44:45]
	global_load_dwordx4 v[92:95], v[16:17], off
	v_lshl_add_u64 v[16:17], v[16:17], 0, s[44:45]
	global_load_dwordx4 v[88:91], v[16:17], off
	v_lshl_add_u64 v[16:17], v[16:17], 0, s[44:45]
	global_load_dwordx4 v[84:87], v[16:17], off
	v_lshl_add_u64 v[16:17], v[16:17], 0, s[44:45]
	global_load_dwordx4 v[80:83], v[16:17], off
	v_lshl_add_u64 v[16:17], v[16:17], 0, s[44:45]
	global_load_dwordx4 v[76:79], v[16:17], off
.LBB0_807:
	s_cmp_eq_u32 s8, 3
	s_cselect_b64 s[30:31], -1, 0
	s_cmp_lg_u32 s8, 3
	s_cbranch_scc1 .LBB0_810
	s_or_b32 s6, s6, 2
	s_lshl_b32 s10, s6, 7
	s_ashr_i32 s11, s10, 31
	s_lshl_b64 s[10:11], s[10:11], 2
	s_add_u32 s10, s66, s10
	s_addc_u32 s11, s67, s11
	s_ashr_i32 s7, s6, 31
	s_lshl_b64 s[6:7], s[6:7], 16
	s_add_u32 s6, s62, s6
	v_lshl_add_u64 v[16:17], v[114:115], 2, s[10:11]
	v_mov_b32_e32 v9, v11
	s_addc_u32 s7, s63, s7
	v_lshl_add_u64 v[16:17], v[16:17], 0, v[8:9]
	v_lshl_add_u64 v[28:29], v[116:117], 2, s[6:7]
	global_load_dwordx4 v[16:19], v[16:17], off
	global_load_dwordx4 v[20:23], v[28:29], off
	v_lshl_add_u64 v[32:33], v[28:29], 0, s[44:45]
	global_load_dwordx4 v[28:31], v[32:33], off
	v_lshl_add_u64 v[36:37], v[32:33], 0, s[44:45]
	global_load_dwordx4 v[32:35], v[36:37], off
	v_lshl_add_u64 v[36:37], v[36:37], 0, s[44:45]
	global_load_dwordx4 v[40:43], v[36:37], off
	v_lshl_add_u64 v[36:37], v[36:37], 0, s[44:45]
	global_load_dwordx4 v[56:59], v[36:37], off
	v_lshl_add_u64 v[36:37], v[36:37], 0, s[44:45]
	global_load_dwordx4 v[64:67], v[36:37], off
	v_lshl_add_u64 v[36:37], v[36:37], 0, s[44:45]
	global_load_dwordx4 v[68:71], v[36:37], off
	v_lshl_add_u64 v[36:37], v[36:37], 0, s[44:45]
	global_load_dwordx4 v[72:75], v[36:37], off
	s_andn2_b64 vcc, exec, s[4:5]
	s_cbranch_vccz .LBB0_811

; __device__ __forceinline__ void hgrn_pass2(const RecurBufs& rb, const float* hgn_l, float* state_out_l, int u, int tid, LAS unsigned char* lds) {
;     ...
;     const int e0 = 64 * eh + 4 * c;
;     const f32x4 hn = *(const f32x4*)(hgn_l + e0);
;     const float* cvb = rb.cv + ((size_t)((b * 8 + h) * 32 + seg * NCH) * 3) * 128;
;     const int sr = tid >> 4, sc16 = tid & 15;
;     const size_t rowS = (size_t)b * SEQ + seg * SEGLEN;
;     v4u pre[6];
;     {   const bf16* gq = rb.proj + (rowS + sr) * LDP + PC_Q + h * 128 + sc16 * 8;
;         pre[0] = *(const v4u*)gq; pre[1] = *(const v4u*)(gq + 32 * (size_t)LDP); pre[2] = *(const v4u*)(gq + PC_F); pre[3] = *(const v4u*)(gq + 32 * (size_t)LDP + PC_F);
;         pre[4] = *(const v4u*)(gq + PC_I); pre[5] = *(const v4u*)(gq + 32 * (size_t)LDP + PC_I); }
;     float cvn = tid < 384 ? cvb[tid] : 0.f; f32x4 ern = *(const f32x4*)(cvb + 16 * w + 4 * g);
.LBB0_815:
	s_waitcnt vmcnt(0) lgkmcnt(0)
	v_and_b32_e32 v72, 15, v112
	v_ashrrev_i32_e32 v73, 8, v112
	s_ashr_i32 s36, s69, 5
	v_lshlrev_b32_e32 v74, 6, v73
	v_lshlrev_b32_e32 v134, 2, v72
	s_bfe_u32 s3, s69, 0x30002
	v_or_b32_e32 v64, v74, v134
	v_readlane_b32 s4, v255, 53
	s_lshl_b32 s2, s36, 3
	v_ashrrev_i32_e32 v65, 31, v64
	v_readlane_b32 s5, v255, 54
	s_or_b32 s2, s2, s3
	v_ashrrev_i32_e32 v66, 4, v112
	v_lshl_add_u64 v[16:17], v[64:65], 2, s[4:5]
	s_lshl_b32 s4, s2, 5
	s_lshl_b32 s5, s8, 3
	s_or_b32 s4, s4, s5
	s_mul_hi_i32 s5, s4, 0x600
	s_mulk_i32 s4, 0x600
	s_add_u32 s6, s60, s4
	s_addc_u32 s7, s61, s5
	s_ashr_i32 s37, s36, 31
	s_lshl_b64 s[58:59], s[36:37], 11
	s_lshl_b32 s4, s8, 9
	s_or_b32 s4, s58, s4
	s_mov_b32 s5, s59
	v_ashrrev_i32_e32 v67, 31, v66
	v_lshl_add_u64 v[20:21], s[4:5], 0, v[66:67]
	v_mov_b64_e32 v[22:23], s[28:29]
	v_mad_u64_u32 v[22:23], s[4:5], v20, s77, v[22:23]
	v_mad_i32_i24 v23, v21, s77, v23
	s_lshl_b32 s64, s3, 8
	v_lshl_add_u64 v[20:21], v[22:23], 0, s[64:65]
	v_lshlrev_b32_e32 v10, 4, v72
	v_lshl_add_u64 v[48:49], v[20:21], 0, v[10:11]
	v_add_co_u32_e32 v40, vcc, 0xc4000, v48
	global_load_dwordx4 v[16:19], v[16:17], off
	s_nop 0
	v_addc_co_u32_e32 v41, vcc, 0, v49, vcc
	v_add_co_u32_e32 v50, vcc, 0x1000, v48
	global_load_dwordx4 v[20:23], v[48:49], off
	global_load_dwordx4 v[28:31], v[48:49], off offset:2048
	global_load_dwordx4 v[32:35], v[40:41], off
	s_nop 0
	global_load_dwordx4 v[40:43], v[40:41], off offset:2048
	v_addc_co_u32_e32 v51, vcc, 0, v49, vcc
	v_add_co_u32_e32 v56, vcc, 0xc5000, v48
	s_movk_i32 s4, 0x180
	s_nop 0
	v_addc_co_u32_e32 v57, vcc, 0, v49, vcc
	global_load_dwordx4 v[48:51], v[50:51], off
	s_nop 0
	global_load_dwordx4 v[56:59], v[56:57], off
	s_movk_i32 s8, 0x17f
	v_cmp_gt_i32_e64 s[4:5], s4, v112
	v_cmp_lt_i32_e32 vcc, s8, v112
	s_and_saveexec_b64 s[8:9], vcc
	s_xor_b64 s[8:9], exec, s[8:9]
	v_mov_b32_e32 v113, v11
	s_or_saveexec_b64 s[8:9], s[8:9]
	v_mov_b32_e32 v135, 0
	s_xor_b64 exec, exec, s[8:9]
	s_cbranch_execz .LBB0_819
	v_ashrrev_i32_e32 v113, 31, v112
	v_lshl_add_u64 v[68:69], v[112:113], 2, s[6:7]
	global_load_dword v135, v[68:69], off
.LBB0_819:
	s_or_b64 exec, exec, s[8:9]
	v_lshlrev_b64 v[78:79], 2, v[114:115]
	v_lshl_add_u64 v[68:69], s[6:7], 0, v[78:79]
	v_mov_b32_e32 v9, v11
	v_lshl_add_u64 v[8:9], v[68:69], 0, v[8:9]
	global_load_dwordx4 v[68:71], v[8:9], off
	v_and_b32_e32 v67, 3, v123
	v_readlane_b32 s6, v255, 17
	v_and_b32_e32 v85, 12, v116
	v_lshlrev_b32_e32 v80, 4, v67
	v_lshl_add_u32 v9, v112, 2, s6
	v_or_b32_e32 v86, v85, v74
	v_or_b32_e32 v87, v74, v72
	v_lshlrev_b32_e32 v74, 2, v114
	v_readlane_b32 s6, v255, 18
	s_movk_i32 s73, 0x110
	v_or_b32_e32 v81, v80, v72
	v_add_u32_e32 v88, s6, v74
	v_readlane_b32 s6, v255, 19
	s_and_b32 s8, s68, 3
	v_mad_u32_u24 v84, v81, s73, 0
	v_bfe_u32 v81, v112, 2, 2
	v_add3_u32 v138, s6, v74, v134
	v_lshrrev_b32_e32 v74, 1, v112
	s_lshl_b32 s51, s8, 3
	s_mul_i32 s70, s8, 0xc40000
	s_lshl_b32 s71, s8, 20
	s_lshl_b32 s72, s8, 9
	v_and_or_b32 v74, v74, 24, v81
	v_cmp_eq_u32_e64 s[8:9], 0, v67
	v_cmp_ne_u32_e64 s[10:11], 0, v67
	v_cmp_eq_u32_e64 s[20:21], 1, v67
	v_cmp_lt_u32_e64 s[22:23], 1, v67
	v_cmp_eq_u32_e64 s[24:25], 2, v67
	v_cmp_eq_u32_e64 s[26:27], 3, v67
	v_bfe_u32 v67, v112, 2, 4
	s_lshl_b32 s50, s3, 5
	v_mul_lo_u32 v8, v66, s73
	v_mad_u32_u24 v91, v74, s73, 0
	v_mad_u32_u24 v92, v67, s73, 0
	v_mul_lo_u32 v87, v87, s73
	s_lshl_b32 s73, s36, 8
	s_or_b32 s50, s73, s50
	s_or_b32 s50, s50, s51
	s_mul_hi_i32 s51, s50, 0x600
	s_mulk_i32 s50, 0x600
	s_add_u32 s50, s50, 0x4d200600
	s_addc_u32 s51, s51, 0
	v_and_b32_e32 v83, 48, v112
	v_lshl_add_u64 v[112:113], v[112:113], 2, s[50:51]
	v_mov_b32_e32 v81, s51
	s_mul_i32 s51, s36, 0x3100000
	v_mul_u32_u24_e32 v90, 0x110, v74
	v_or_b32_e32 v74, v80, v122
	v_or_b32_e32 v80, s50, v83
	s_mul_hi_i32 s50, s36, 0x3100000
	s_add_u32 s70, s51, s70
	s_addc_u32 s51, s50, 0
	s_or_b32 s50, s70, s64
	v_add_u32_e32 v82, 0, v8
	v_or_b32_e32 v8, v122, v114
	v_or_b32_e32 v89, v85, v114
	v_lshl_add_u64 v[114:115], v[80:81], 0, v[78:79]
	v_mov_b64_e32 v[78:79], s[50:51]
	s_lshl_b64 s[36:37], s[36:37], 22
	v_mad_i64_i32 v[116:117], s[50:51], v66, s77, v[78:79]
	v_mad_u64_u32 v[66:67], s[50:51], v74, s77, v[78:79]
	v_lshlrev_b64 v[64:65], 1, v[64:65]
	s_or_b32 s36, s36, s71
	v_lshlrev_b32_e32 v75, 1, v8
	v_mul_u32_u24_e32 v140, 0x110, v72
	v_lshl_add_u64 v[118:119], v[66:67], 0, v[64:65]
	v_lshl_or_b32 v66, v74, 11, s36
	s_add_u32 s36, s58, s72
	v_lshl_add_u32 v139, v73, 2, s87
	v_add3_u32 v141, 0, v75, v140
	v_or_b32_e32 v73, 2, v122
	v_mov_b32_e32 v75, v11
	v_or_b32_e32 v66, s64, v66
	v_mov_b32_e32 v67, s37
	s_addc_u32 s37, s59, 0
	v_cmp_gt_u32_e64 s[16:17], v73, v72
	v_or_b32_e32 v73, 3, v122
	v_lshl_add_u64 v[120:121], v[66:67], 0, v[64:65]
	v_lshl_add_u64 v[66:67], s[36:37], 0, v[74:75]
	v_cmp_eq_u32_e64 s[6:7], 0, v72
	v_cmp_gt_u32_e64 s[12:13], v122, v72
	v_cmp_lt_u32_e64 s[14:15], v122, v72
	v_cmp_gt_u32_e64 s[18:19], v73, v72
	v_lshl_or_b32 v116, v72, 4, v116
	v_lshlrev_b64 v[72:73], 11, v[66:67]
	v_or_b32_e32 v72, s64, v72
	v_mov_b32_e32 v76, s64
	v_mov_b32_e32 v77, v11
	v_lshl_add_u64 v[72:73], v[72:73], 0, v[64:65]
	s_mov_b64 s[36:37], 0x30500000
	v_lshl_add_u64 v[122:123], v[72:73], 0, s[36:37]
	v_mad_u64_u32 v[72:73], s[36:37], v66, s77, v[76:77]
	v_mad_i32_i24 v73, v67, s77, v73
	v_add_u32_e32 v136, 0, v83
	v_lshl_add_u32 v89, v89, 1, 0
	v_lshlrev_b32_e32 v85, 1, v85
	v_lshlrev_b32_e32 v86, 1, v86
	v_lshlrev_b32_e32 v143, 3, v74
	v_lshl_add_u64 v[64:65], v[72:73], 0, v[64:65]
	s_mov_b64 s[36:37], 0x17601800
	s_mov_b32 s3, 8
	v_add_u32_e32 v142, 0xcc00, v141
	v_or_b32_e32 v144, 8, v143
	v_or_b32_e32 v145, 16, v143
	v_or_b32_e32 v146, 24, v143
	v_lshl_add_u64 v[124:125], v[64:65], 0, s[36:37]
	v_add_u32_e32 v10, v82, v10
	v_add_u32_e32 v147, v84, v83
	v_add_u32_e32 v149, v136, v87
	v_add_u32_e32 v156, v88, v83
	v_add_u32_e32 v157, v89, v90
	v_add_u32_e32 v158, v91, v85
	v_add_u32_e32 v159, v92, v86
	s_branch .LBB0_821
; __device__ __forceinline__ float bf2f(bf16 v) { return __uint_as_float(((unsigned)v) << 16); }
; __device__ __forceinline__ unsigned pk2(float lo, float hi) { unsigned r; asm("v_cvt_pk_bf16_f32 %0, %1, %2" : "=v"(r) : "v"(lo), "v"(hi)); return r; }
; __device__ __forceinline__ float siluf_(float x) { return x * frcp_(1.0f + __expf(-x)); }
; __device__ __forceinline__ void hgrn_pass2(const RecurBufs& rb, const float* hgn_l, float* state_out_l, int u, int tid, LAS unsigned char* lds) {
;     ...
;         for (int r = 0; r < 4; ++r) { const int i = 16 * it + 4 * g + r; const float rstd = rsqrtf((red[i * 2] + red[i * 2 + 1]) * (1.f / 128.f) + EPS);
;             float ov[4];
; #pragma unroll
;             for (int et = 0; et < 4; ++et) { const float og = bf2f((bf16)(ogv[r] >> (16 * et))); ov[et] = o[et][r] * rstd * hn[et] * siluf_(og); }
;             *(unsigned long long*)(rb.ohg + (row0 + i) * 1024 + h * 128 + e0) = (unsigned long long)pk2(ov[0], ov[1]) | ((unsigned long long)pk2(ov[2], ov[3]) << 32); }
.LBB0_820:
	s_or_b64 exec, exec, s[36:37]
	v_add_u32_e32 v84, s87, v143
	s_waitcnt lgkmcnt(0)
	s_barrier
	ds_read_b64 v[84:85], v84
	s_mov_b32 s36, 0x30500000
	s_add_i32 s3, s3, -1
	v_lshl_add_u64 v[112:113], v[112:113], 0, s[46:47]
	v_lshl_add_u64 v[114:115], v[114:115], 0, s[46:47]
	s_waitcnt lgkmcnt(0)
	v_add_f32_e32 v84, v84, v85
	v_fmamk_f32 v84, v84, 0x3c000000, v176
	v_cmp_gt_f32_e32 vcc, s33, v84
	v_mul_f32_e32 v85, 0x4b800000, v84
	v_lshl_add_u64 v[116:117], v[116:117], 0, s[48:49]
	v_cndmask_b32_e32 v84, v84, v85, vcc
	v_rsq_f32_e32 v84, v84
	v_lshl_add_u64 v[118:119], v[118:119], 0, s[48:49]
	v_lshl_add_u64 v[124:125], v[124:125], 0, s[48:49]
	s_cmp_eq_u32 s3, 0
	v_mul_f32_e32 v85, 0x45800000, v84
	v_cndmask_b32_e32 v84, v84, v85, vcc
	s_waitcnt vmcnt(0)
	v_lshlrev_b32_e32 v85, 16, v132
	v_mul_f32_e32 v86, 0xbfb8aa3b, v85
	v_exp_f32_e32 v86, v86
	v_mul_f32_e32 v80, v80, v84
	v_mul_f32_e32 v80, v16, v80
	v_mul_f32_e32 v76, v76, v84
	v_add_f32_e32 v86, 1.0, v86
	v_rcp_f32_e32 v86, v86
	v_mul_f32_e32 v76, v17, v76
	v_mul_f32_e32 v72, v72, v84
	v_mul_f32_e32 v72, v18, v72
	v_mul_f32_e32 v85, v86, v85
	v_mul_f32_e32 v80, v85, v80
	v_and_b32_e32 v85, 0xffff0000, v132
	v_mul_f32_e32 v86, 0xbfb8aa3b, v85
	v_exp_f32_e32 v86, v86
	v_mul_f32_e32 v68, v68, v84
	v_mul_f32_e32 v68, v19, v68
	v_add_f32_e32 v86, 1.0, v86
	v_rcp_f32_e32 v86, v86
	s_nop 0
	v_mul_f32_e32 v85, v86, v85
	v_mul_f32_e32 v76, v85, v76
	v_alignbit_b32 v85, v133, v132, 16
	v_and_b32_e32 v85, 0xffff0000, v85
	v_mul_f32_e32 v86, 0xbfb8aa3b, v85
	v_exp_f32_e32 v86, v86
	s_nop 0
	v_add_f32_e32 v86, 1.0, v86
	v_rcp_f32_e32 v86, v86
	s_nop 0
	v_mul_f32_e32 v85, v86, v85
	v_mul_f32_e32 v72, v85, v72
	v_and_b32_e32 v85, 0xffff0000, v133
	v_mul_f32_e32 v84, 0xbfb8aa3b, v85
	v_exp_f32_e32 v84, v84
	v_lshl_add_u64 v[86:87], s[34:35], 0, v[122:123]
	v_lshl_add_u64 v[122:123], v[122:123], 0, s[56:57]
	v_add_f32_e32 v84, 1.0, v84
	v_rcp_f32_e32 v84, v84
	s_nop 0
	v_mul_f32_e32 v84, v84, v85
	v_mul_f32_e32 v68, v84, v68
	v_cvt_pk_bf16_f32 v84, v80, v76
	v_cvt_pk_bf16_f32 v85, v72, v68
	v_add_u32_e32 v68, s87, v144
	global_store_dwordx2 v[86:87], v[84:85], off
	ds_read_b64 v[84:85], v68
	s_waitcnt lgkmcnt(0)
	v_add_f32_e32 v68, v84, v85
	v_fmamk_f32 v68, v68, 0x3c000000, v176
	v_cmp_gt_f32_e32 vcc, s33, v68
	v_mul_f32_e32 v72, 0x4b800000, v68
	s_nop 0
	v_cndmask_b32_e32 v68, v68, v72, vcc
	v_rsq_f32_e32 v68, v68
	s_nop 0
	v_mul_f32_e32 v72, 0x45800000, v68
	v_cndmask_b32_e32 v68, v68, v72, vcc
	v_lshlrev_b32_e32 v72, 16, v130
	v_mul_f32_e32 v80, 0xbfb8aa3b, v72
	v_exp_f32_e32 v80, v80
	v_mul_f32_e32 v76, v81, v68
	v_mul_f32_e32 v76, v16, v76
	v_mul_f32_e32 v77, v77, v68
	v_add_f32_e32 v80, 1.0, v80
	v_rcp_f32_e32 v80, v80
	v_mul_f32_e32 v77, v17, v77
	v_mul_f32_e32 v73, v73, v68
	v_mul_f32_e32 v73, v18, v73
	v_mul_f32_e32 v72, v80, v72
	v_mul_f32_e32 v72, v72, v76
	v_and_b32_e32 v76, 0xffff0000, v130
	v_mul_f32_e32 v80, 0xbfb8aa3b, v76
	v_exp_f32_e32 v80, v80
	v_mul_f32_e32 v68, v69, v68
	v_mul_f32_e32 v68, v19, v68
	v_add_f32_e32 v80, 1.0, v80
	v_rcp_f32_e32 v80, v80
	s_nop 0
	v_mul_f32_e32 v76, v80, v76
	v_mul_f32_e32 v76, v76, v77
	v_alignbit_b32 v77, v131, v130, 16
	v_and_b32_e32 v77, 0xffff0000, v77
	v_mul_f32_e32 v80, 0xbfb8aa3b, v77
	v_exp_f32_e32 v80, v80
	v_cvt_pk_bf16_f32 v72, v72, v76
	s_nop 0
	v_add_f32_e32 v80, 1.0, v80
	v_rcp_f32_e32 v80, v80
	s_nop 0
	v_mul_f32_e32 v77, v80, v77
	v_mul_f32_e32 v73, v77, v73
	v_and_b32_e32 v77, 0xffff0000, v131
	v_mul_f32_e32 v69, 0xbfb8aa3b, v77
	v_exp_f32_e32 v69, v69
	s_nop 0
	v_add_f32_e32 v69, 1.0, v69
	v_rcp_f32_e32 v69, v69
	s_nop 0
	v_mul_f32_e32 v69, v69, v77
	v_mul_f32_e32 v68, v69, v68
	v_cvt_pk_bf16_f32 v73, v73, v68
	v_lshl_add_u64 v[68:69], s[34:35], 0, v[120:121]
	v_add_co_u32_e32 v76, vcc, s36, v68
	s_mov_b32 s36, 0x30501000
	s_nop 0
	v_addc_co_u32_e32 v77, vcc, 0, v69, vcc
	global_store_dwordx2 v[76:77], v[72:73], off offset:2048
	v_add_u32_e32 v72, s87, v145
	ds_read_b64 v[72:73], v72
	v_lshl_add_u64 v[120:121], v[120:121], 0, s[56:57]
	s_waitcnt lgkmcnt(0)
; __device__ __forceinline__ float bf2f(bf16 v) { return __uint_as_float(((unsigned)v) << 16); }
; __device__ __forceinline__ unsigned pk2(float lo, float hi) { unsigned r; asm("v_cvt_pk_bf16_f32 %0, %1, %2" : "=v"(r) : "v"(lo), "v"(hi)); return r; }
; __device__ __forceinline__ float siluf_(float x) { return x * frcp_(1.0f + __expf(-x)); }
; #define LAS __attribute__((address_space(3)))
; __device__ __forceinline__ void sync_threads() { __syncthreads(); }
; __device__ __forceinline__ void hgrn_pass2(const RecurBufs& rb, const float* hgn_l, float* state_out_l, int u, int tid, LAS unsigned char* lds) {
;     ...
;         const size_t row0 = rowS + ch * RC;
;         *(LAS v4u*)(Qt + sr * PQ + sc16 * 16) = pre[0]; *(LAS v4u*)(Qt + (sr + 32) * PQ + sc16 * 16) = pre[1];
;         *(LAS v4u*)(Kt + sr * PQ + sc16 * 16) = pre[2]; *(LAS v4u*)(Kt + (sr + 32) * PQ + sc16 * 16) = pre[3];
;         *(LAS v4u*)(V + sr * PQ + sc16 * 16) = pre[4]; *(LAS v4u*)(V + (sr + 32) * PQ + sc16 * 16) = pre[5];
;         if (ch + 1 < NCH) { const bf16* gq = rb.proj + (row0 + RC + sr) * LDP + PC_Q + h * 128 + sc16 * 8;
;             pre[0] = *(const v4u*)gq; pre[1] = *(const v4u*)(gq + 32 * (size_t)LDP); pre[2] = *(const v4u*)(gq + PC_F); pre[3] = *(const v4u*)(gq + 32 * (size_t)LDP + PC_F);
;             pre[4] = *(const v4u*)(gq + PC_I); pre[5] = *(const v4u*)(gq + 32 * (size_t)LDP + PC_I); }
;     ...
;         for (int r = 0; r < 4; ++r) { const int i = 16 * it + 4 * g + r; const float rstd = rsqrtf((red[i * 2] + red[i * 2 + 1]) * (1.f / 128.f) + EPS);
;             float ov[4];
; #pragma unroll
;             for (int et = 0; et < 4; ++et) { const float og = bf2f((bf16)(ogv[r] >> (16 * et))); ov[et] = o[et][r] * rstd * hn[et] * siluf_(og); }
;             *(unsigned long long*)(rb.ohg + (row0 + i) * 1024 + h * 128 + e0) = (unsigned long long)pk2(ov[0], ov[1]) | ((unsigned long long)pk2(ov[2], ov[3]) << 32); }
;         sync_threads();
	v_add_f32_e32 v72, v72, v73
	v_fmamk_f32 v72, v72, 0x3c000000, v176
	v_cmp_gt_f32_e32 vcc, s33, v72
	v_mul_f32_e32 v73, 0x4b800000, v72
	s_nop 0
	v_cndmask_b32_e32 v72, v72, v73, vcc
	v_rsq_f32_e32 v72, v72
	s_nop 0
	v_mul_f32_e32 v73, 0x45800000, v72
	v_cndmask_b32_e32 v72, v72, v73, vcc
	v_lshlrev_b32_e32 v73, 16, v128
	v_mul_f32_e32 v77, 0xbfb8aa3b, v73
	v_exp_f32_e32 v77, v77
	v_mul_f32_e32 v76, v82, v72
	v_mul_f32_e32 v76, v16, v76
	v_mul_f32_e32 v74, v74, v72
	v_add_f32_e32 v77, 1.0, v77
	v_rcp_f32_e32 v77, v77
	v_mul_f32_e32 v74, v18, v74
	v_mul_f32_e32 v70, v70, v72
	v_mul_f32_e32 v70, v19, v70
	v_mul_f32_e32 v73, v77, v73
	v_mul_f32_e32 v73, v73, v76
	v_and_b32_e32 v76, 0xffff0000, v128
	v_mul_f32_e32 v77, v78, v72
	v_mul_f32_e32 v78, 0xbfb8aa3b, v76
	v_exp_f32_e32 v78, v78
	v_mul_f32_e32 v77, v17, v77
	v_add_co_u32_e32 v68, vcc, s36, v68
	v_add_f32_e32 v78, 1.0, v78
	v_rcp_f32_e32 v78, v78
	v_addc_co_u32_e32 v69, vcc, 0, v69, vcc
	v_mul_f32_e32 v76, v78, v76
	v_mul_f32_e32 v76, v76, v77
	v_alignbit_b32 v77, v129, v128, 16
	v_and_b32_e32 v77, 0xffff0000, v77
	v_mul_f32_e32 v78, 0xbfb8aa3b, v77
	v_exp_f32_e32 v78, v78
	s_nop 0
	v_add_f32_e32 v78, 1.0, v78
	v_rcp_f32_e32 v78, v78
	s_nop 0
	v_mul_f32_e32 v77, v78, v77
	v_mul_f32_e32 v74, v77, v74
	v_and_b32_e32 v77, 0xffff0000, v129
	v_mul_f32_e32 v72, 0xbfb8aa3b, v77
	v_exp_f32_e32 v72, v72
	s_nop 0
	v_add_f32_e32 v72, 1.0, v72
	v_rcp_f32_e32 v72, v72
	s_nop 0
	v_mul_f32_e32 v72, v72, v77
	v_mul_f32_e32 v70, v72, v70
	v_cvt_pk_bf16_f32 v72, v73, v76
	v_cvt_pk_bf16_f32 v73, v74, v70
	v_add_u32_e32 v70, s87, v146
	global_store_dwordx2 v[68:69], v[72:73], off
	ds_read_b64 v[72:73], v70
	s_waitcnt lgkmcnt(0)
	v_add_f32_e32 v70, v72, v73
	v_fmamk_f32 v70, v70, 0x3c000000, v176
	v_cmp_gt_f32_e32 vcc, s33, v70
	v_mul_f32_e32 v72, 0x4b800000, v70
	s_nop 0
	v_cndmask_b32_e32 v70, v70, v72, vcc
	v_rsq_f32_e32 v70, v70
	s_nop 0
	v_mul_f32_e32 v72, 0x45800000, v70
	v_cndmask_b32_e32 v70, v70, v72, vcc
	v_lshlrev_b32_e32 v72, 16, v126
	v_mul_f32_e32 v74, 0xbfb8aa3b, v72
	v_exp_f32_e32 v74, v74
	v_mul_f32_e32 v73, v83, v70
	v_mul_f32_e32 v73, v16, v73
	v_mul_f32_e32 v75, v75, v70
	v_add_f32_e32 v74, 1.0, v74
	v_rcp_f32_e32 v74, v74
	v_mul_f32_e32 v75, v18, v75
	v_mul_f32_e32 v72, v74, v72
	v_mul_f32_e32 v72, v72, v73
	v_and_b32_e32 v73, 0xffff0000, v126
	v_mul_f32_e32 v76, 0xbfb8aa3b, v73
	v_exp_f32_e32 v76, v76
	v_mul_f32_e32 v74, v79, v70
	v_mul_f32_e32 v74, v17, v74
	v_mul_f32_e32 v70, v71, v70
	v_add_f32_e32 v76, 1.0, v76
	v_rcp_f32_e32 v76, v76
	v_mul_f32_e32 v70, v19, v70
	v_mul_f32_e32 v73, v76, v73
	v_mul_f32_e32 v73, v73, v74
	v_alignbit_b32 v74, v127, v126, 16
	v_and_b32_e32 v74, 0xffff0000, v74
	v_mul_f32_e32 v76, 0xbfb8aa3b, v74
	v_exp_f32_e32 v76, v76
	s_nop 0
	v_add_f32_e32 v76, 1.0, v76
	v_rcp_f32_e32 v76, v76
	s_nop 0
	v_mul_f32_e32 v74, v76, v74
	v_mul_f32_e32 v74, v74, v75
	v_and_b32_e32 v75, 0xffff0000, v127
	v_mul_f32_e32 v71, 0xbfb8aa3b, v75
	v_exp_f32_e32 v71, v71
	s_nop 0
	v_add_f32_e32 v71, 1.0, v71
	v_rcp_f32_e32 v71, v71
	s_nop 0
	v_mul_f32_e32 v71, v71, v75
	v_mul_f32_e32 v71, v71, v70
	v_cvt_pk_bf16_f32 v70, v72, v73
	v_cvt_pk_bf16_f32 v71, v74, v71
	global_store_dwordx2 v[68:69], v[70:71], off offset:2048
	v_mov_b64_e32 v[70:71], v[66:67]
	v_mov_b64_e32 v[68:69], v[64:65]
	s_waitcnt lgkmcnt(0)
	s_barrier
	s_cbranch_scc1 .LBB0_844
.LBB0_821:
	s_cmp_lg_u32 s3, 1
	s_cselect_b64 s[36:37], -1, 0
	s_cmp_eq_u32 s3, 1
	s_waitcnt vmcnt(0) lgkmcnt(0)
	ds_write_b128 v10, v[20:23]
	ds_write_b128 v10, v[32:35] offset:8704
	ds_write_b128 v10, v[28:31] offset:17408
	ds_write_b128 v10, v[40:43] offset:26112
	ds_write_b128 v10, v[48:51] offset:34816
	ds_write_b128 v10, v[56:59] offset:43520
	s_cbranch_scc1 .LBB0_827
	v_lshl_add_u64 v[48:49], s[34:35], 0, v[116:117]
	v_add_co_u32_e32 v28, vcc, 0x17788000, v48
	s_nop 1
	v_addc_co_u32_e32 v29, vcc, 0, v49, vcc
	v_add_co_u32_e32 v40, vcc, 0x1784c000, v48
	s_nop 1
	v_addc_co_u32_e32 v41, vcc, 0, v49, vcc
	v_add_co_u32_e32 v50, vcc, 0x17789000, v48
	global_load_dwordx4 v[20:23], v[28:29], off
	s_nop 0
	global_load_dwordx4 v[28:31], v[28:29], off offset:2048
	s_nop 0
	global_load_dwordx4 v[32:35], v[40:41], off
	s_nop 0
	global_load_dwordx4 v[40:43], v[40:41], off offset:2048
	v_addc_co_u32_e32 v51, vcc, 0, v49, vcc
	v_add_co_u32_e32 v56, vcc, 0x1784d000, v48
	s_nop 1
	v_addc_co_u32_e32 v57, vcc, 0, v49, vcc
	global_load_dwordx4 v[48:51], v[50:51], off
	s_nop 0
	global_load_dwordx4 v[56:59], v[56:57], off
	s_and_saveexec_b64 s[50:51], s[4:5]
	s_cbranch_execnz .LBB0_828

; __device__ __forceinline__ void hgrn_pass2(const RecurBufs& rb, const float* hgn_l, float* state_out_l, int u, int tid, LAS unsigned char* lds) {
;     ...
;             if (ch + 1 < NCH) { if (tid < 384) cvn = cvb[(size_t)(ch + 1) * 384 + tid]; ern = *(const f32x4*)(cvb + (size_t)(ch + 1) * 384 + 16 * w + 4 * g); }
.LBB0_824:
	s_and_saveexec_b64 s[36:37], s[4:5]
	s_cbranch_execz .LBB0_826
	v_lshl_add_u64 v[64:65], s[34:35], 0, v[112:113]
	global_load_dword v135, v[64:65], off
.LBB0_826:
	s_or_b64 exec, exec, s[36:37]
	v_lshl_add_u64 v[64:65], s[34:35], 0, v[114:115]
	global_load_dwordx4 v[64:67], v[64:65], off
	s_branch .LBB0_830

; __device__ __forceinline__ unsigned pk2(float lo, float hi) { unsigned r; asm("v_cvt_pk_bf16_f32 %0, %1, %2" : "=v"(r) : "v"(lo), "v"(hi)); return r; }
; #define LAS __attribute__((address_space(3)))
; __device__ __forceinline__ f32x4 mfma16(bf16x8 a, bf16x8 b, f32x4 c) { return __builtin_amdgcn_mfma_f32_16x16x32_bf16(a, b, c, 0, 0, 0); }
; __device__ __forceinline__ void sync_threads() { __syncthreads(); }
; #define SCHED_FENCE() do {} while (0)
; #define SCHED_FENCE() __builtin_amdgcn_sched_barrier(0)
; __device__ __forceinline__ void hgrn_pass2(const RecurBufs& rb, const float* hgn_l, float* state_out_l, int u, int tid, LAS unsigned char* lds) {
;     ...
;             for (int et = 0; et < 8; ++et) { const f32x4 v = S[et] * er;
;                 *(LAS unsigned long long*)(ST + (16 * et + c) * PQ + (16 * w + 4 * g) * 2) = (unsigned long long)pk2(v[0], v[1]) | ((unsigned long long)pk2(v[2], v[3]) << 32); } }
;         unsigned long long ogv[4];
; #pragma unroll
;         for (int r = 0; r < 4; ++r) ogv[r] = *(const unsigned long long*)(rb.proj + (row0 + 16 * it + 4 * g + r) * LDP + PC_OG + h * 128 + e0);
;         sync_threads();
;         bf16x8 Qfr[4];
; #pragma unroll
;         for (int kd = 0; kd < 4; ++kd) Qfr[kd] = frag_rows(Qt, PQ, 16 * it + c, 32 * kd + 8 * g);
;         unsigned PT[4][2];
; #pragma unroll
;         for (int jt = 0; jt < 4; ++jt) {
;             f32x4 acc = (f32x4){0.f, 0.f, 0.f, 0.f};
;             if (jt <= it) {
; #pragma unroll
;                 for (int kd = 0; kd < 4; ++kd) acc = mfma16(frag_rows(Kt, PQ, 16 * jt + c, 32 * kd + 8 * g), Qfr[kd], acc);
;                 if (jt == it) {
; #pragma unroll
;                     for (int r = 0; r < 4; ++r) acc[r] = (4 * g + r <= c) ? acc[r] : 0.f; }
;             }
;             PT[jt][0] = pk2(acc[0], acc[1]); PT[jt][1] = pk2(acc[2], acc[3]); SCHED_FENCE();
.LBB0_830:
	v_pk_mul_f32 v[74:75], v[68:69], v[12:13]
	v_pk_mul_f32 v[72:73], v[70:71], v[14:15]
	v_cvt_pk_bf16_f32 v74, v74, v75
	s_mov_b32 s36, 0x17607000
	v_cvt_pk_bf16_f32 v75, v72, v73
	ds_write_b64 v141, v[74:75] offset:52224
	v_pk_mul_f32 v[74:75], v[68:69], v[0:1]
	v_pk_mul_f32 v[72:73], v[70:71], v[2:3]
	v_cvt_pk_bf16_f32 v74, v74, v75
	v_add_u32_e32 v92, v136, v140
	v_cvt_pk_bf16_f32 v75, v72, v73
	ds_write_b64 v141, v[74:75] offset:56576
	v_pk_mul_f32 v[74:75], v[68:69], v[24:25]
	v_pk_mul_f32 v[72:73], v[70:71], v[26:27]
	v_cvt_pk_bf16_f32 v74, v74, v75
	s_nop 0
	v_cvt_pk_bf16_f32 v75, v72, v73
	ds_write_b64 v141, v[74:75] offset:60928
	v_pk_mul_f32 v[74:75], v[68:69], v[36:37]
	v_pk_mul_f32 v[72:73], v[70:71], v[38:39]
	v_cvt_pk_bf16_f32 v74, v74, v75
	s_nop 0
	v_cvt_pk_bf16_f32 v75, v72, v73
	ds_write_b64 v141, v[74:75] offset:65280
	v_pk_mul_f32 v[74:75], v[68:69], v[44:45]
	v_pk_mul_f32 v[72:73], v[70:71], v[46:47]
	v_cvt_pk_bf16_f32 v74, v74, v75
	s_nop 0
	v_cvt_pk_bf16_f32 v75, v72, v73
	ds_write_b64 v142, v[74:75] offset:17408
	v_pk_mul_f32 v[74:75], v[68:69], v[4:5]
	v_pk_mul_f32 v[72:73], v[70:71], v[6:7]
	v_cvt_pk_bf16_f32 v74, v74, v75
	s_nop 0
	v_cvt_pk_bf16_f32 v75, v72, v73
	ds_write_b64 v142, v[74:75] offset:21760
	v_pk_mul_f32 v[74:75], v[68:69], v[52:53]
	v_pk_mul_f32 v[68:69], v[68:69], v[60:61]
	v_pk_mul_f32 v[72:73], v[70:71], v[54:55]
	v_pk_mul_f32 v[70:71], v[70:71], v[62:63]
	v_cvt_pk_bf16_f32 v68, v68, v69
	v_cvt_pk_bf16_f32 v74, v74, v75
	v_cvt_pk_bf16_f32 v75, v72, v73
	ds_write_b64 v142, v[74:75] offset:26112
	v_cvt_pk_bf16_f32 v69, v70, v71
	ds_write_b64 v142, v[68:69] offset:30464
	v_lshl_add_u64 v[68:69], s[34:35], 0, v[124:125]
	global_load_dwordx2 v[132:133], v[68:69], off
	v_lshl_add_u64 v[68:69], s[34:35], 0, v[118:119]
	v_add_co_u32_e32 v70, vcc, s36, v68
	s_mov_b32 s36, 0x1760d000
	s_nop 0
	v_addc_co_u32_e32 v71, vcc, 0, v69, vcc
	global_load_dwordx2 v[130:131], v[70:71], off offset:2560
	v_add_co_u32_e32 v70, vcc, s36, v68
	s_mov_b32 s36, 0x17613000
	s_nop 0
	v_addc_co_u32_e32 v71, vcc, 0, v69, vcc
	v_add_co_u32_e32 v68, vcc, s36, v68
	global_load_dwordx2 v[128:129], v[70:71], off offset:3072
	s_nop 0
	v_addc_co_u32_e32 v69, vcc, 0, v69, vcc
	global_load_dwordx2 v[126:127], v[68:69], off offset:3584
	s_waitcnt lgkmcnt(0)
	s_barrier
	ds_read_b128 v[80:83], v147
	ds_read_b128 v[76:79], v147 offset:64
	ds_read_b128 v[72:75], v147 offset:128
	ds_read_b128 v[68:71], v147 offset:192
	ds_read_b128 v[84:87], v92 offset:17408
	ds_read_b128 v[88:91], v92 offset:17472
	s_waitcnt lgkmcnt(0)
	v_mfma_f32_16x16x32_bf16 v[84:87], v[84:87], v[80:83], 0
	v_mfma_f32_16x16x32_bf16 v[84:87], v[88:91], v[76:79], v[84:87]
	ds_read_b128 v[88:91], v92 offset:17536
	s_waitcnt lgkmcnt(0)
	v_mfma_f32_16x16x32_bf16 v[84:87], v[88:91], v[72:75], v[84:87]
	ds_read_b128 v[88:91], v92 offset:17600
	s_waitcnt lgkmcnt(0)
	v_mfma_f32_16x16x32_bf16 v[84:87], v[88:91], v[68:71], v[84:87]
	s_nop 7
	v_cndmask_b32_e64 v88, v84, 0, s[12:13]
	v_cndmask_b32_e64 v89, 0, v85, s[14:15]
	v_cndmask_b32_e64 v90, v86, 0, s[16:17]
	v_cndmask_b32_e64 v91, v87, 0, s[18:19]
	v_cndmask_b32_e64 v86, v86, v90, s[8:9]
	v_cndmask_b32_e64 v87, v87, v91, s[8:9]
	v_cndmask_b32_e64 v84, v84, v88, s[8:9]
	v_cndmask_b32_e64 v85, v85, v89, s[8:9]
	v_cvt_pk_bf16_f32 v84, v84, v85
	v_cvt_pk_bf16_f32 v85, v86, v87
	v_mov_b32_e32 v93, 0
	v_mov_b32_e32 v86, 0
	v_mov_b32_e32 v87, 0
	v_mov_b32_e32 v88, 0
	v_mov_b32_e32 v89, 0
	s_and_saveexec_b64 s[36:37], s[10:11]
	s_cbranch_execz .LBB0_834
	ds_read_b128 v[86:89], v92 offset:21760
	ds_read_b128 v[94:97], v92 offset:21824
	s_waitcnt lgkmcnt(0)
	v_mfma_f32_16x16x32_bf16 v[86:89], v[86:89], v[80:83], 0
	v_mfma_f32_16x16x32_bf16 v[86:89], v[94:97], v[76:79], v[86:89]
	ds_read_b128 v[94:97], v92 offset:21888
	s_waitcnt lgkmcnt(0)
	v_mfma_f32_16x16x32_bf16 v[86:89], v[94:97], v[72:75], v[86:89]
	ds_read_b128 v[94:97], v92 offset:21952
	s_waitcnt lgkmcnt(0)
	v_mfma_f32_16x16x32_bf16 v[86:89], v[94:97], v[68:71], v[86:89]
	s_and_saveexec_b64 s[50:51], s[20:21]
	s_nop 6
	v_cndmask_b32_e64 v86, v86, 0, s[12:13]
	v_cndmask_b32_e64 v87, 0, v87, s[14:15]
	v_cndmask_b32_e64 v88, v88, 0, s[16:17]
	v_cndmask_b32_e64 v89, v89, 0, s[18:19]
	s_or_b64 exec, exec, s[50:51]

; #define LAUNDER_PTR(p) do {} while (0)
; #define LAUNDER_PTR(p) asm volatile("" : "+v"(p))
; __device__ __forceinline__ void ssd_pass2(const RecurBufs& rb, const float* d_skip, const float* ssm_norm, float* state_out_l, int u, int tid, LAS unsigned char* lds) {
;     ...
;     for (int s = 0; s < seg; s += 2) {
;         f32x4 L0[4][4], L1[4][4]; const bool two = s + 1 < seg;
;         const int ua = u - seg + s, ub = two ? ua + 1 : ua;
;         const float dca = __expf(rb.tseg[ua * 4 + k]), dcb = __expf(rb.tseg[ub * 4 + k]);
;         {   const float* hp = rb.hseg + (size_t)ua * 32768 + tid * 4;
; #pragma unroll
;             for (int nt = 0; nt < 4; ++nt)
; #pragma unroll
;                 for (int pt = 0; pt < 4; ++pt) { LAUNDER_PTR(hp); L0[nt][pt] = *(const f32x4*)hp; hp += 2048; } }
;         if (two) { const float* hp = rb.hseg + (size_t)ub * 32768 + tid * 4;
; #pragma unroll
;             for (int nt = 0; nt < 4; ++nt)
; #pragma unroll
;                 for (int pt = 0; pt < 4; ++pt) { LAUNDER_PTR(hp); L1[nt][pt] = *(const f32x4*)hp; hp += 2048; } }
; #pragma unroll
;         for (int nt = 0; nt < 4; ++nt)
; #pragma unroll
;             for (int pt = 0; pt < 4; ++pt) { H[nt][pt] = H[nt][pt] * dca + L0[nt][pt]; if (two) H[nt][pt] = H[nt][pt] * dcb + L1[nt][pt]; } }
.LBB0_850:
	s_and_b32 s1, s0, 3
	v_mov_b32_e32 v138, v137
	s_xor_b32 s6, s1, 3
	s_cmp_eq_u32 s1, 3
	v_ashrrev_i32_e32 v189, 7, v138
	v_lshlrev_b32_e32 v134, 2, v138
	s_cbranch_scc1 .LBB0_855
	s_and_b32 s2, s0, -4
	s_cmp_gt_u32 s6, 1
	s_cselect_b64 vcc, -1, 0
	v_cndmask_b32_e64 v0, 0, 1, vcc
	v_ashrrev_i32_e32 v135, 31, v134
	v_or_b32_e32 v16, s2, v0
	s_ashr_i32 s3, s2, 31
	v_lshl_add_u32 v0, s2, 2, v189
	v_lshl_add_u64 v[8:9], v[134:135], 2, s[26:27]
	s_lshl_b64 s[4:5], s[2:3], 17
	v_ashrrev_i32_e32 v1, 31, v0
	v_lshl_add_u32 v2, v16, 2, v189
	v_lshl_add_u64 v[0:1], v[0:1], 2, s[30:31]
	v_ashrrev_i32_e32 v3, 31, v2
	v_lshl_add_u64 v[4:5], v[8:9], 0, s[4:5]
	v_lshl_add_u64 v[2:3], v[2:3], 2, s[30:31]
	global_load_dword v135, v[0:1], off
	global_load_dword v10, v[2:3], off
	global_load_dwordx4 v[0:3], v[4:5], off
	v_lshl_add_u64 v[12:13], v[4:5], 0, s[44:45]
	global_load_dwordx4 v[4:7], v[12:13], off
	v_lshl_add_u64 v[18:19], v[12:13], 0, s[44:45]
	global_load_dwordx4 v[12:15], v[18:19], off
	v_lshl_add_u64 v[22:23], v[18:19], 0, s[44:45]
	global_load_dwordx4 v[18:21], v[22:23], off
	v_lshl_add_u64 v[26:27], v[22:23], 0, s[44:45]
	global_load_dwordx4 v[22:25], v[26:27], off
	v_lshl_add_u64 v[30:31], v[26:27], 0, s[44:45]
	global_load_dwordx4 v[26:29], v[30:31], off
	v_lshl_add_u64 v[34:35], v[30:31], 0, s[44:45]
	global_load_dwordx4 v[30:33], v[34:35], off
	v_lshl_add_u64 v[38:39], v[34:35], 0, s[44:45]
	global_load_dwordx4 v[34:37], v[38:39], off
	v_lshl_add_u64 v[42:43], v[38:39], 0, s[44:45]
	global_load_dwordx4 v[38:41], v[42:43], off
	v_lshl_add_u64 v[46:47], v[42:43], 0, s[44:45]
	global_load_dwordx4 v[42:45], v[46:47], off
	v_lshl_add_u64 v[50:51], v[46:47], 0, s[44:45]
	global_load_dwordx4 v[46:49], v[50:51], off
	v_lshl_add_u64 v[54:55], v[50:51], 0, s[44:45]
	global_load_dwordx4 v[50:53], v[54:55], off
	v_lshl_add_u64 v[58:59], v[54:55], 0, s[44:45]
	global_load_dwordx4 v[54:57], v[58:59], off
	v_lshl_add_u64 v[62:63], v[58:59], 0, s[44:45]
	global_load_dwordx4 v[58:61], v[62:63], off
	v_lshl_add_u64 v[66:67], v[62:63], 0, s[44:45]
	global_load_dwordx4 v[62:65], v[66:67], off
	v_lshl_add_u64 v[66:67], v[66:67], 0, s[44:45]
	global_load_dwordx4 v[66:69], v[66:67], off
	s_cmp_lt_u32 s6, 2
	s_cbranch_scc1 .LBB0_853
	v_ashrrev_i32_e32 v17, 31, v16
	v_lshlrev_b64 v[16:17], 17, v[16:17]
	v_lshl_add_u64 v[16:17], v[8:9], 0, v[16:17]
	global_load_dwordx4 v[130:133], v[16:17], off
	v_lshl_add_u64 v[16:17], v[16:17], 0, s[44:45]
	global_load_dwordx4 v[126:129], v[16:17], off
	v_lshl_add_u64 v[16:17], v[16:17], 0, s[44:45]
	global_load_dwordx4 v[122:125], v[16:17], off
	v_lshl_add_u64 v[16:17], v[16:17], 0, s[44:45]
	global_load_dwordx4 v[118:121], v[16:17], off
	v_lshl_add_u64 v[16:17], v[16:17], 0, s[44:45]
	global_load_dwordx4 v[114:117], v[16:17], off
	v_lshl_add_u64 v[16:17], v[16:17], 0, s[44:45]
	global_load_dwordx4 v[110:113], v[16:17], off
	v_lshl_add_u64 v[16:17], v[16:17], 0, s[44:45]
	global_load_dwordx4 v[106:109], v[16:17], off
	v_lshl_add_u64 v[16:17], v[16:17], 0, s[44:45]
	global_load_dwordx4 v[102:105], v[16:17], off
	v_lshl_add_u64 v[16:17], v[16:17], 0, s[44:45]
	global_load_dwordx4 v[98:101], v[16:17], off
	v_lshl_add_u64 v[16:17], v[16:17], 0, s[44:45]
	global_load_dwordx4 v[94:97], v[16:17], off
	v_lshl_add_u64 v[16:17], v[16:17], 0, s[44:45]
	global_load_dwordx4 v[90:93], v[16:17], off
	v_lshl_add_u64 v[16:17], v[16:17], 0, s[44:45]
	global_load_dwordx4 v[86:89], v[16:17], off
	v_lshl_add_u64 v[16:17], v[16:17], 0, s[44:45]
	global_load_dwordx4 v[82:85], v[16:17], off
	v_lshl_add_u64 v[16:17], v[16:17], 0, s[44:45]
	global_load_dwordx4 v[78:81], v[16:17], off
	v_lshl_add_u64 v[16:17], v[16:17], 0, s[44:45]
	global_load_dwordx4 v[74:77], v[16:17], off
	v_lshl_add_u64 v[16:17], v[16:17], 0, s[44:45]
	global_load_dwordx4 v[70:73], v[16:17], off
.LBB0_853:
	s_waitcnt vmcnt(0) lgkmcnt(0)
	v_mul_f32_e32 v16, 0x3fb8aa3b, v135
	v_exp_f32_e32 v16, v16
	v_mul_f32_e32 v10, 0x3fb8aa3b, v10
	v_exp_f32_e32 v10, v10
	s_cmp_eq_u32 s1, 0
	v_mul_f32_e32 v136, 0, v16
	v_pk_add_f32 v[0:1], v[0:1], v[136:137] op_sel_hi:[1,0]
	v_pk_add_f32 v[4:5], v[136:137], v[4:5] op_sel_hi:[0,1]
	v_pk_fma_f32 v[16:17], v[10:11], v[0:1], v[130:131] op_sel_hi:[0,1,1]
	v_cndmask_b32_e32 v1, v1, v17, vcc
	v_cndmask_b32_e32 v0, v0, v16, vcc
	v_pk_fma_f32 v[16:17], v[10:11], v[4:5], v[126:127] op_sel_hi:[0,1,1]
	v_pk_add_f32 v[14:15], v[136:137], v[14:15] op_sel_hi:[0,1]
	v_pk_add_f32 v[12:13], v[136:137], v[12:13] op_sel_hi:[0,1]
	v_cndmask_b32_e32 v5, v5, v17, vcc
	v_cndmask_b32_e32 v4, v4, v16, vcc
	v_pk_fma_f32 v[122:123], v[10:11], v[12:13], v[122:123] op_sel_hi:[0,1,1]
	v_pk_fma_f32 v[16:17], v[10:11], v[14:15], v[124:125] op_sel_hi:[0,1,1]
	v_cndmask_b32_e32 v17, v15, v17, vcc
	v_cndmask_b32_e32 v16, v14, v16, vcc
	v_cndmask_b32_e32 v15, v13, v123, vcc
	v_cndmask_b32_e32 v14, v12, v122, vcc
	v_pk_add_f32 v[12:13], v[136:137], v[20:21] op_sel_hi:[0,1]
	v_pk_fma_f32 v[20:21], v[10:11], v[12:13], v[120:121] op_sel_hi:[0,1,1]
	v_cndmask_b32_e32 v21, v13, v21, vcc
	v_cndmask_b32_e32 v20, v12, v20, vcc
	v_pk_add_f32 v[12:13], v[136:137], v[24:25] op_sel_hi:[0,1]
	v_pk_fma_f32 v[24:25], v[10:11], v[12:13], v[116:117] op_sel_hi:[0,1,1]
	v_cndmask_b32_e32 v25, v13, v25, vcc
	v_cndmask_b32_e32 v24, v12, v24, vcc
	v_pk_add_f32 v[12:13], v[136:137], v[28:29] op_sel_hi:[0,1]
	v_pk_fma_f32 v[28:29], v[10:11], v[12:13], v[112:113] op_sel_hi:[0,1,1]
	v_cndmask_b32_e32 v29, v13, v29, vcc
	v_cndmask_b32_e32 v28, v12, v28, vcc
	v_pk_add_f32 v[12:13], v[136:137], v[32:33] op_sel_hi:[0,1]
	v_pk_fma_f32 v[32:33], v[10:11], v[12:13], v[108:109] op_sel_hi:[0,1,1]
; __device__ __forceinline__ void ssd_pass2(const RecurBufs& rb, const float* d_skip, const float* ssm_norm, float* state_out_l, int u, int tid, LAS unsigned char* lds) {
;     ...
;         for (int nt = 0; nt < 4; ++nt)
; #pragma unroll
;             for (int pt = 0; pt < 4; ++pt) { H[nt][pt] = H[nt][pt] * dca + L0[nt][pt]; if (two) H[nt][pt] = H[nt][pt] * dcb + L1[nt][pt]; } }
	v_cndmask_b32_e32 v33, v13, v33, vcc
	v_cndmask_b32_e32 v32, v12, v32, vcc
	v_pk_add_f32 v[12:13], v[136:137], v[36:37] op_sel_hi:[0,1]
	v_pk_fma_f32 v[36:37], v[10:11], v[12:13], v[104:105] op_sel_hi:[0,1,1]
	v_cndmask_b32_e32 v37, v13, v37, vcc
	v_cndmask_b32_e32 v36, v12, v36, vcc
	v_pk_add_f32 v[12:13], v[136:137], v[40:41] op_sel_hi:[0,1]
	v_pk_fma_f32 v[40:41], v[10:11], v[12:13], v[100:101] op_sel_hi:[0,1,1]
	v_cndmask_b32_e32 v41, v13, v41, vcc
	v_cndmask_b32_e32 v40, v12, v40, vcc
	v_pk_add_f32 v[12:13], v[136:137], v[44:45] op_sel_hi:[0,1]
	v_pk_fma_f32 v[44:45], v[10:11], v[12:13], v[96:97] op_sel_hi:[0,1,1]
	v_cndmask_b32_e32 v45, v13, v45, vcc
	v_cndmask_b32_e32 v44, v12, v44, vcc
	v_pk_add_f32 v[12:13], v[136:137], v[48:49] op_sel_hi:[0,1]
	v_pk_fma_f32 v[48:49], v[10:11], v[12:13], v[92:93] op_sel_hi:[0,1,1]
	v_cndmask_b32_e32 v49, v13, v49, vcc
	v_cndmask_b32_e32 v48, v12, v48, vcc
	v_pk_add_f32 v[12:13], v[136:137], v[52:53] op_sel_hi:[0,1]
	v_pk_fma_f32 v[52:53], v[10:11], v[12:13], v[88:89] op_sel_hi:[0,1,1]
	v_cndmask_b32_e32 v53, v13, v53, vcc
	v_cndmask_b32_e32 v52, v12, v52, vcc
	v_pk_add_f32 v[12:13], v[136:137], v[56:57] op_sel_hi:[0,1]
	v_pk_fma_f32 v[56:57], v[10:11], v[12:13], v[84:85] op_sel_hi:[0,1,1]
	v_cndmask_b32_e32 v57, v13, v57, vcc
	v_cndmask_b32_e32 v56, v12, v56, vcc
	v_pk_add_f32 v[12:13], v[136:137], v[60:61] op_sel_hi:[0,1]
	v_pk_fma_f32 v[60:61], v[10:11], v[12:13], v[80:81] op_sel_hi:[0,1,1]
	v_cndmask_b32_e32 v61, v13, v61, vcc
	v_cndmask_b32_e32 v60, v12, v60, vcc
	v_pk_add_f32 v[12:13], v[136:137], v[64:65] op_sel_hi:[0,1]
	v_pk_fma_f32 v[64:65], v[10:11], v[12:13], v[76:77] op_sel_hi:[0,1,1]
	v_pk_add_f32 v[2:3], v[2:3], v[136:137] op_sel_hi:[1,0]
	v_pk_add_f32 v[6:7], v[136:137], v[6:7] op_sel_hi:[0,1]
	v_pk_add_f32 v[18:19], v[136:137], v[18:19] op_sel_hi:[0,1]
	v_pk_add_f32 v[22:23], v[136:137], v[22:23] op_sel_hi:[0,1]
	v_pk_add_f32 v[26:27], v[136:137], v[26:27] op_sel_hi:[0,1]
	v_pk_add_f32 v[30:31], v[136:137], v[30:31] op_sel_hi:[0,1]
	v_pk_add_f32 v[34:35], v[136:137], v[34:35] op_sel_hi:[0,1]
	v_pk_add_f32 v[38:39], v[136:137], v[38:39] op_sel_hi:[0,1]
	v_pk_add_f32 v[42:43], v[136:137], v[42:43] op_sel_hi:[0,1]
	v_pk_add_f32 v[46:47], v[136:137], v[46:47] op_sel_hi:[0,1]
	v_pk_add_f32 v[50:51], v[136:137], v[50:51] op_sel_hi:[0,1]
	v_pk_add_f32 v[54:55], v[136:137], v[54:55] op_sel_hi:[0,1]
	v_pk_add_f32 v[58:59], v[136:137], v[58:59] op_sel_hi:[0,1]
	v_pk_add_f32 v[62:63], v[136:137], v[62:63] op_sel_hi:[0,1]
	v_cndmask_b32_e32 v65, v13, v65, vcc
	v_cndmask_b32_e32 v64, v12, v64, vcc
	v_pk_add_f32 v[12:13], v[136:137], v[68:69] op_sel_hi:[0,1]
	v_pk_add_f32 v[66:67], v[136:137], v[66:67] op_sel_hi:[0,1]
	v_pk_fma_f32 v[130:131], v[10:11], v[2:3], v[132:133] op_sel_hi:[0,1,1]
	v_pk_fma_f32 v[126:127], v[10:11], v[6:7], v[128:129] op_sel_hi:[0,1,1]
	v_pk_fma_f32 v[118:119], v[10:11], v[18:19], v[118:119] op_sel_hi:[0,1,1]
	v_pk_fma_f32 v[114:115], v[10:11], v[22:23], v[114:115] op_sel_hi:[0,1,1]
	v_pk_fma_f32 v[110:111], v[10:11], v[26:27], v[110:111] op_sel_hi:[0,1,1]
	v_pk_fma_f32 v[106:107], v[10:11], v[30:31], v[106:107] op_sel_hi:[0,1,1]
	v_pk_fma_f32 v[102:103], v[10:11], v[34:35], v[102:103] op_sel_hi:[0,1,1]
	v_pk_fma_f32 v[98:99], v[10:11], v[38:39], v[98:99] op_sel_hi:[0,1,1]
	v_pk_fma_f32 v[94:95], v[10:11], v[42:43], v[94:95] op_sel_hi:[0,1,1]
	v_pk_fma_f32 v[90:91], v[10:11], v[46:47], v[90:91] op_sel_hi:[0,1,1]
	v_pk_fma_f32 v[86:87], v[10:11], v[50:51], v[86:87] op_sel_hi:[0,1,1]
	v_pk_fma_f32 v[82:83], v[10:11], v[54:55], v[82:83] op_sel_hi:[0,1,1]
	v_pk_fma_f32 v[78:79], v[10:11], v[58:59], v[78:79] op_sel_hi:[0,1,1]
	v_pk_fma_f32 v[74:75], v[10:11], v[62:63], v[74:75] op_sel_hi:[0,1,1]
	v_pk_fma_f32 v[70:71], v[10:11], v[66:67], v[70:71] op_sel_hi:[0,1,1]
	v_pk_fma_f32 v[68:69], v[10:11], v[12:13], v[72:73] op_sel_hi:[0,1,1]
	v_cndmask_b32_e32 v3, v3, v131, vcc
	v_cndmask_b32_e32 v2, v2, v130, vcc
	v_cndmask_b32_e32 v7, v7, v127, vcc
	v_cndmask_b32_e32 v6, v6, v126, vcc
	v_cndmask_b32_e32 v19, v19, v119, vcc
	v_cndmask_b32_e32 v18, v18, v118, vcc
	v_cndmask_b32_e32 v23, v23, v115, vcc
	v_cndmask_b32_e32 v22, v22, v114, vcc
	v_cndmask_b32_e32 v27, v27, v111, vcc
	v_cndmask_b32_e32 v26, v26, v110, vcc
	v_cndmask_b32_e32 v31, v31, v107, vcc
	v_cndmask_b32_e32 v30, v30, v106, vcc
	v_cndmask_b32_e32 v35, v35, v103, vcc
	v_cndmask_b32_e32 v34, v34, v102, vcc
	v_cndmask_b32_e32 v39, v39, v99, vcc
	v_cndmask_b32_e32 v38, v38, v98, vcc
	v_cndmask_b32_e32 v43, v43, v95, vcc
	v_cndmask_b32_e32 v42, v42, v94, vcc
	v_cndmask_b32_e32 v47, v47, v91, vcc
	v_cndmask_b32_e32 v46, v46, v90, vcc
	v_cndmask_b32_e32 v51, v51, v87, vcc
	v_cndmask_b32_e32 v50, v50, v86, vcc
	v_cndmask_b32_e32 v55, v55, v83, vcc
	v_cndmask_b32_e32 v54, v54, v82, vcc
	v_cndmask_b32_e32 v59, v59, v79, vcc
	v_cndmask_b32_e32 v58, v58, v78, vcc
	v_cndmask_b32_e32 v63, v63, v75, vcc
	v_cndmask_b32_e32 v62, v62, v74, vcc
	v_cndmask_b32_e32 v69, v13, v69, vcc
	v_cndmask_b32_e32 v68, v12, v68, vcc
	v_cndmask_b32_e32 v67, v67, v71, vcc
	v_cndmask_b32_e32 v66, v66, v70, vcc
	s_cbranch_scc0 .LBB0_856
; #define LAUNDER_PTR(p) do {} while (0)
; #define LAUNDER_PTR(p) asm volatile("" : "+v"(p))
; __device__ __forceinline__ void ssd_pass2(const RecurBufs& rb, const float* d_skip, const float* ssm_norm, float* state_out_l, int u, int tid, LAS unsigned char* lds) {
;     ...
;     for (int s = 0; s < seg; s += 2) {
;         f32x4 L0[4][4], L1[4][4]; const bool two = s + 1 < seg;
;         const int ua = u - seg + s, ub = two ? ua + 1 : ua;
;         const float dca = __expf(rb.tseg[ua * 4 + k]), dcb = __expf(rb.tseg[ub * 4 + k]);
;         {   const float* hp = rb.hseg + (size_t)ua * 32768 + tid * 4;
; #pragma unroll
;             for (int nt = 0; nt < 4; ++nt)
; #pragma unroll
;                 for (int pt = 0; pt < 4; ++pt) { LAUNDER_PTR(hp); L0[nt][pt] = *(const f32x4*)hp; hp += 2048; } }
;         if (two) { const float* hp = rb.hseg + (size_t)ub * 32768 + tid * 4;
; #pragma unroll
;             for (int nt = 0; nt < 4; ++nt)
; #pragma unroll
;                 for (int pt = 0; pt < 4; ++pt) { LAUNDER_PTR(hp); L1[nt][pt] = *(const f32x4*)hp; hp += 2048; } }
; #pragma unroll
;         for (int nt = 0; nt < 4; ++nt)
; #pragma unroll
;             for (int pt = 0; pt < 4; ++pt) { H[nt][pt] = H[nt][pt] * dca + L0[nt][pt]; if (two) H[nt][pt] = H[nt][pt] * dcb + L1[nt][pt]; } }
	s_or_b32 s2, s0, 2
	v_lshl_add_u32 v12, s2, 2, v189
	s_ashr_i32 s3, s2, 31
	v_ashrrev_i32_e32 v13, 31, v12
	s_lshl_b64 s[2:3], s[2:3], 17
	v_lshl_add_u64 v[12:13], v[12:13], 2, s[30:31]
	v_lshl_add_u64 v[8:9], v[8:9], 0, s[2:3]
	global_load_dword v10, v[12:13], off
	global_load_dwordx4 v[70:73], v[8:9], off
	v_lshl_add_u64 v[8:9], v[8:9], 0, s[44:45]
	global_load_dwordx4 v[74:77], v[8:9], off
	v_lshl_add_u64 v[8:9], v[8:9], 0, s[44:45]
	global_load_dwordx4 v[78:81], v[8:9], off
	v_lshl_add_u64 v[8:9], v[8:9], 0, s[44:45]
	global_load_dwordx4 v[82:85], v[8:9], off
	v_lshl_add_u64 v[8:9], v[8:9], 0, s[44:45]
	global_load_dwordx4 v[86:89], v[8:9], off
	v_lshl_add_u64 v[8:9], v[8:9], 0, s[44:45]
	global_load_dwordx4 v[90:93], v[8:9], off
	v_lshl_add_u64 v[8:9], v[8:9], 0, s[44:45]
	global_load_dwordx4 v[94:97], v[8:9], off
	v_lshl_add_u64 v[8:9], v[8:9], 0, s[44:45]
	global_load_dwordx4 v[98:101], v[8:9], off
	v_lshl_add_u64 v[8:9], v[8:9], 0, s[44:45]
	global_load_dwordx4 v[102:105], v[8:9], off
	v_lshl_add_u64 v[8:9], v[8:9], 0, s[44:45]
	global_load_dwordx4 v[106:109], v[8:9], off
	v_lshl_add_u64 v[8:9], v[8:9], 0, s[44:45]
	global_load_dwordx4 v[110:113], v[8:9], off
	v_lshl_add_u64 v[8:9], v[8:9], 0, s[44:45]
	global_load_dwordx4 v[114:117], v[8:9], off
	v_lshl_add_u64 v[8:9], v[8:9], 0, s[44:45]
	global_load_dwordx4 v[118:121], v[8:9], off
	v_lshl_add_u64 v[8:9], v[8:9], 0, s[44:45]
	global_load_dwordx4 v[122:125], v[8:9], off
	v_lshl_add_u64 v[8:9], v[8:9], 0, s[44:45]
	global_load_dwordx4 v[126:129], v[8:9], off
	v_lshl_add_u64 v[8:9], v[8:9], 0, s[44:45]
	global_load_dwordx4 v[130:133], v[8:9], off
	s_waitcnt vmcnt(0) lgkmcnt(0)
	v_mul_f32_e32 v8, 0x3fb8aa3b, v10
	v_exp_f32_e32 v8, v8
	s_nop 0
	v_pk_fma_f32 v[4:5], v[4:5], v[8:9], v[74:75] op_sel_hi:[1,0,1]
	v_pk_fma_f32 v[6:7], v[6:7], v[8:9], v[76:77] op_sel_hi:[1,0,1]
	v_pk_fma_f32 v[0:1], v[0:1], v[8:9], v[70:71] op_sel_hi:[1,0,1]
	v_pk_fma_f32 v[14:15], v[14:15], v[8:9], v[78:79] op_sel_hi:[1,0,1]
	v_pk_fma_f32 v[16:17], v[16:17], v[8:9], v[80:81] op_sel_hi:[1,0,1]
	v_pk_fma_f32 v[2:3], v[2:3], v[8:9], v[72:73] op_sel_hi:[1,0,1]
	v_pk_fma_f32 v[18:19], v[18:19], v[8:9], v[82:83] op_sel_hi:[1,0,1]
	v_pk_fma_f32 v[20:21], v[20:21], v[8:9], v[84:85] op_sel_hi:[1,0,1]
	v_pk_fma_f32 v[22:23], v[22:23], v[8:9], v[86:87] op_sel_hi:[1,0,1]
	v_pk_fma_f32 v[24:25], v[24:25], v[8:9], v[88:89] op_sel_hi:[1,0,1]
	v_pk_fma_f32 v[26:27], v[26:27], v[8:9], v[90:91] op_sel_hi:[1,0,1]
	v_pk_fma_f32 v[28:29], v[28:29], v[8:9], v[92:93] op_sel_hi:[1,0,1]
	v_pk_fma_f32 v[30:31], v[30:31], v[8:9], v[94:95] op_sel_hi:[1,0,1]
	v_pk_fma_f32 v[32:33], v[32:33], v[8:9], v[96:97] op_sel_hi:[1,0,1]
	v_pk_fma_f32 v[34:35], v[34:35], v[8:9], v[98:99] op_sel_hi:[1,0,1]
	v_pk_fma_f32 v[36:37], v[36:37], v[8:9], v[100:101] op_sel_hi:[1,0,1]
	v_pk_fma_f32 v[38:39], v[38:39], v[8:9], v[102:103] op_sel_hi:[1,0,1]
	v_pk_fma_f32 v[40:41], v[40:41], v[8:9], v[104:105] op_sel_hi:[1,0,1]
	v_pk_fma_f32 v[42:43], v[42:43], v[8:9], v[106:107] op_sel_hi:[1,0,1]
	v_pk_fma_f32 v[44:45], v[44:45], v[8:9], v[108:109] op_sel_hi:[1,0,1]
	v_pk_fma_f32 v[46:47], v[46:47], v[8:9], v[110:111] op_sel_hi:[1,0,1]
	v_pk_fma_f32 v[48:49], v[48:49], v[8:9], v[112:113] op_sel_hi:[1,0,1]
	v_pk_fma_f32 v[50:51], v[50:51], v[8:9], v[114:115] op_sel_hi:[1,0,1]
	v_pk_fma_f32 v[52:53], v[52:53], v[8:9], v[116:117] op_sel_hi:[1,0,1]
	v_pk_fma_f32 v[54:55], v[54:55], v[8:9], v[118:119] op_sel_hi:[1,0,1]
	v_pk_fma_f32 v[56:57], v[56:57], v[8:9], v[120:121] op_sel_hi:[1,0,1]
	v_pk_fma_f32 v[58:59], v[58:59], v[8:9], v[122:123] op_sel_hi:[1,0,1]
	v_pk_fma_f32 v[60:61], v[60:61], v[8:9], v[124:125] op_sel_hi:[1,0,1]
	v_pk_fma_f32 v[62:63], v[62:63], v[8:9], v[126:127] op_sel_hi:[1,0,1]
	v_pk_fma_f32 v[64:65], v[64:65], v[8:9], v[128:129] op_sel_hi:[1,0,1]
	v_pk_fma_f32 v[66:67], v[66:67], v[8:9], v[130:131] op_sel_hi:[1,0,1]
	v_pk_fma_f32 v[68:69], v[68:69], v[8:9], v[132:133] op_sel_hi:[1,0,1]
	s_branch .LBB0_856

; #define LAS __attribute__((address_space(3)))
; __device__ __forceinline__ f32x4 mfma16(bf16x8 a, bf16x8 b, f32x4 c) { return __builtin_amdgcn_mfma_f32_16x16x32_bf16(a, b, c, 0, 0, 0); }
; #define SCHED_FENCE() do {} while (0)
; #define SCHED_FENCE() __builtin_amdgcn_sched_barrier(0)
; __device__ __forceinline__ void ssd_state_update(f32x4 (&H)[4][4], LAS unsigned char* Xi, int xp, LAS unsigned char* Bi, int bp, const LAS float* sDt, const LAS float* sCum, int w, int lane) {
;     const int g = lane >> 4, k = w >> 1, nh = w & 1;
;     const float tot = sCum[63 * 4 + k]; const float et = __expf(tot);
; #pragma unroll
;     for (int nt = 0; nt < 4; ++nt)
; #pragma unroll
;         for (int pt = 0; pt < 4; ++pt) H[nt][pt] = H[nt][pt] * et;
; #pragma unroll
;     for (int ks = 0; ks < 2; ++ks) {
;         float wg[8];
; #pragma unroll
;         for (int j = 0; j < 8; ++j) wg[j] = __expf(tot - sCum[(32 * ks + 8 * g + j) * 4 + k]) * sDt[(32 * ks + 8 * g + j) * 4 + k];
;         bf16x8 Bx[4];
; #pragma unroll
;         for (int pt = 0; pt < 4; ++pt) Bx[pt] = scale_frag8(frag_tr(Xi, xp, 32 * ks + 8 * g, 32 * ks + 8 * g + 4, 64 * k + 16 * pt, lane), wg);
; #pragma unroll
;         for (int nt = 0; nt < 4; ++nt) { const bf16x8 A = frag_tr(Bi, bp, 32 * ks + 8 * g, 32 * ks + 8 * g + 4, 16 * (4 * nh + nt), lane);
; #pragma unroll
;             for (int pt = 0; pt < 4; ++pt) H[nt][pt] = mfma16(A, Bx[pt], H[nt][pt]);
;             SCHED_FENCE(); }
.LBB0_865:
	ds_read_b32 v10, v131 offset:1008
	v_add_u32_e32 v155, v158, v159
	s_waitcnt lgkmcnt(0)
	v_mul_f32_e32 v12, 0x3fb8aa3b, v10
	v_exp_f32_e32 v102, v12
	s_nop 0
	v_pk_mul_f32 v[84:85], v[36:37], v[102:103] op_sel_hi:[1,0]
	ds_read_b32 v36, v134
	ds_read_b32 v37, v135
	v_pk_mul_f32 v[88:89], v[20:21], v[102:103] op_sel_hi:[1,0]
	v_pk_mul_f32 v[70:71], v[22:23], v[102:103] op_sel_hi:[1,0]
	v_pk_mul_f32 v[22:23], v[40:41], v[102:103] op_sel_hi:[1,0]
	v_pk_mul_f32 v[20:21], v[38:39], v[102:103] op_sel_hi:[1,0]
	ds_read_b32 v38, v138
	ds_read_b32 v40, v142
	s_waitcnt lgkmcnt(0)
	v_sub_f32_e32 v36, v10, v36
	v_mul_f32_e32 v36, 0x3fb8aa3b, v36
	v_exp_f32_e32 v36, v36
	v_pk_mul_f32 v[72:73], v[24:25], v[102:103] op_sel_hi:[1,0]
	v_pk_mul_f32 v[24:25], v[42:43], v[102:103] op_sel_hi:[1,0]
	ds_read_b32 v39, v140
	ds_read_b32 v42, v146
	v_mul_f32_e32 v36, v37, v36
	ds_read_b32 v37, v136
	v_pk_mul_f32 v[78:79], v[30:31], v[102:103] op_sel_hi:[1,0]
	v_pk_mul_f32 v[30:31], v[48:49], v[102:103] op_sel_hi:[1,0]
	v_pk_mul_f32 v[96:97], v[6:7], v[102:103] op_sel_hi:[1,0]
	v_pk_mul_f32 v[6:7], v[60:61], v[102:103] op_sel_hi:[1,0]
	s_waitcnt lgkmcnt(0)
	v_sub_f32_e32 v37, v10, v37
	v_mul_f32_e32 v37, 0x3fb8aa3b, v37
	v_exp_f32_e32 v37, v37
	ds_read_b32 v41, v144
	v_add_u32_e32 v60, v158, v133
	v_pk_mul_f32 v[98:99], v[0:1], v[102:103] op_sel_hi:[1,0]
	v_mul_f32_e32 v37, v38, v37
	ds_read_b32 v38, v139
	v_pk_mul_f32 v[74:75], v[26:27], v[102:103] op_sel_hi:[1,0]
	v_pk_mul_f32 v[82:83], v[34:35], v[102:103] op_sel_hi:[1,0]
	v_pk_mul_f32 v[26:27], v[44:45], v[102:103] op_sel_hi:[1,0]
	ds_read_b32 v43, v149
	s_waitcnt lgkmcnt(0)
	v_sub_f32_e32 v38, v10, v38
	v_mul_f32_e32 v38, 0x3fb8aa3b, v38
	v_exp_f32_e32 v38, v38
	v_pk_mul_f32 v[34:35], v[52:53], v[102:103] op_sel_hi:[1,0]
	v_pk_mul_f32 v[0:1], v[54:55], v[102:103] op_sel_hi:[1,0]
	v_pk_mul_f32 v[76:77], v[28:29], v[102:103] op_sel_hi:[1,0]
	v_mul_f32_e32 v38, v39, v38
	ds_read_b32 v39, v141
	v_pk_mul_f32 v[28:29], v[46:47], v[102:103] op_sel_hi:[1,0]
	v_pk_mul_f32 v[12:13], v[62:63], v[102:103] op_sel_hi:[1,0]
	v_pk_mul_f32 v[94:95], v[4:5], v[102:103] op_sel_hi:[1,0]
	v_pk_mul_f32 v[80:81], v[32:33], v[102:103] op_sel_hi:[1,0]
	s_waitcnt lgkmcnt(0)
	v_sub_f32_e32 v39, v10, v39
	v_mul_f32_e32 v39, 0x3fb8aa3b, v39
	v_exp_f32_e32 v39, v39
	v_pk_mul_f32 v[32:33], v[50:51], v[102:103] op_sel_hi:[1,0]
	v_pk_mul_f32 v[4:5], v[58:59], v[102:103] op_sel_hi:[1,0]
	v_pk_mul_f32 v[100:101], v[2:3], v[102:103] op_sel_hi:[1,0]
	v_mul_f32_e32 v39, v40, v39
	ds_read_b32 v40, v143
	v_pk_mul_f32 v[90:91], v[14:15], v[102:103] op_sel_hi:[1,0]
	v_pk_mul_f32 v[2:3], v[56:57], v[102:103] op_sel_hi:[1,0]
	v_pk_mul_f32 v[14:15], v[64:65], v[102:103] op_sel_hi:[1,0]
	v_pk_mul_f32 v[92:93], v[16:17], v[102:103] op_sel_hi:[1,0]
	s_waitcnt lgkmcnt(0)
	v_sub_f32_e32 v40, v10, v40
	v_mul_f32_e32 v40, 0x3fb8aa3b, v40
	v_exp_f32_e32 v40, v40
	v_pk_mul_f32 v[16:17], v[66:67], v[102:103] op_sel_hi:[1,0]
	v_pk_mul_f32 v[86:87], v[18:19], v[102:103] op_sel_hi:[1,0]
	v_pk_mul_f32 v[18:19], v[68:69], v[102:103] op_sel_hi:[1,0]
	v_mul_f32_e32 v40, v41, v40
	ds_read_b32 v41, v145
	s_waitcnt lgkmcnt(0)
	v_sub_f32_e32 v41, v10, v41
	v_mul_f32_e32 v41, 0x3fb8aa3b, v41
	v_exp_f32_e32 v41, v41
	s_nop 0
	v_mul_f32_e32 v42, v42, v41
	ds_read_b32 v41, v147
	s_waitcnt lgkmcnt(0)
	v_sub_f32_e32 v41, v10, v41
	v_mul_f32_e32 v41, 0x3fb8aa3b, v41
	v_exp_f32_e32 v41, v41
	s_nop 0
	v_mul_f32_e32 v48, v43, v41
	ds_read_b32 v41, v156
	ds_read_b32 v43, v157
	ds_read_b64_tr_b16 v[52:53], v60 offset:4160
	ds_read_b64_tr_b16 v[44:45], v60
	ds_read_b64_tr_b16 v[54:55], v60 offset:32
	ds_read_b64_tr_b16 v[62:63], v60 offset:4192
	s_waitcnt lgkmcnt(0)
	v_sub_f32_e32 v41, v10, v41
	v_mul_f32_e32 v41, 0x3fb8aa3b, v41
	v_exp_f32_e32 v41, v41
	v_and_b32_e32 v47, 0xffff0000, v52
	v_mul_f32_e32 v47, v42, v47
	v_cvt_pk_bf16_f32 v49, v47, v47
	v_lshlrev_b32_e32 v47, 16, v53
	v_mul_f32_e32 v47, v48, v47
	v_mul_f32_e32 v59, v43, v41
	v_cvt_pk_bf16_f32 v51, v47, v47
	v_and_b32_e32 v47, 0xffff0000, v53
	v_mul_f32_e32 v47, v59, v47
	v_lshlrev_b32_e32 v46, 16, v52
	v_cvt_pk_bf16_f32 v53, v47, v47
	v_lshlrev_b32_e32 v47, 16, v54
	v_and_b32_e32 v50, 0xffff0000, v54
	v_lshlrev_b32_e32 v52, 16, v55
	v_and_b32_e32 v54, 0xffff0000, v55
	v_lshlrev_b32_e32 v55, 16, v62
	v_and_b32_e32 v56, 0xffff0000, v62
	v_lshlrev_b32_e32 v57, 16, v63
	v_and_b32_e32 v58, 0xffff0000, v63
	ds_read_b64_tr_b16 v[62:63], v60 offset:64
	ds_read_b64_tr_b16 v[64:65], v60 offset:4224
	v_lshlrev_b32_e32 v41, 16, v44
	v_mul_f32_e32 v41, v36, v41
	v_mul_f32_e32 v47, v36, v47
	s_waitcnt lgkmcnt(0)
	v_lshlrev_b32_e32 v61, 16, v62
	v_mul_f32_e32 v61, v36, v61
	v_cvt_pk_bf16_f32 v66, v61, v61
	v_and_b32_e32 v61, 0xffff0000, v62
	v_mul_f32_e32 v61, v37, v61
	v_cvt_pk_bf16_f32 v67, v61, v61
	v_lshlrev_b32_e32 v61, 16, v63
	v_mul_f32_e32 v61, v38, v61
	v_cvt_pk_bf16_f32 v68, v61, v61
	v_and_b32_e32 v61, 0xffff0000, v63
	v_mul_f32_e32 v61, v39, v61
	v_cvt_pk_bf16_f32 v69, v61, v61
	v_lshlrev_b32_e32 v61, 16, v64
	v_mul_f32_e32 v61, v40, v61
	v_cvt_pk_bf16_f32 v102, v61, v61
	v_and_b32_e32 v61, 0xffff0000, v64
	v_mul_f32_e32 v61, v42, v61
	v_cvt_pk_bf16_f32 v64, v61, v61
	v_lshlrev_b32_e32 v61, 16, v65
	v_mul_f32_e32 v61, v48, v61
	v_cvt_pk_bf16_f32 v126, v61, v61
	v_and_b32_e32 v61, 0xffff0000, v65
	v_mul_f32_e32 v61, v59, v61
	v_cvt_pk_bf16_f32 v65, v61, v61
	ds_read_b64_tr_b16 v[62:63], v60 offset:96
	ds_read_b64_tr_b16 v[60:61], v60 offset:4256
	v_mul_f32_e32 v57, v48, v57
	v_and_b32_e32 v43, 0xffff0000, v44
	v_lshlrev_b32_e32 v44, 16, v45
	s_waitcnt lgkmcnt(0)
; __device__ __forceinline__ f32x4 mfma16(bf16x8 a, bf16x8 b, f32x4 c) { return __builtin_amdgcn_mfma_f32_16x16x32_bf16(a, b, c, 0, 0, 0); }
; #define SCHED_FENCE() do {} while (0)
; #define SCHED_FENCE() __builtin_amdgcn_sched_barrier(0)
; __device__ __forceinline__ void ssd_state_update(f32x4 (&H)[4][4], LAS unsigned char* Xi, int xp, LAS unsigned char* Bi, int bp, const LAS float* sDt, const LAS float* sCum, int w, int lane) {
;     ...
;     for (int ks = 0; ks < 2; ++ks) {
;         float wg[8];
; #pragma unroll
;         for (int j = 0; j < 8; ++j) wg[j] = __expf(tot - sCum[(32 * ks + 8 * g + j) * 4 + k]) * sDt[(32 * ks + 8 * g + j) * 4 + k];
;         bf16x8 Bx[4];
; #pragma unroll
;         for (int pt = 0; pt < 4; ++pt) Bx[pt] = scale_frag8(frag_tr(Xi, xp, 32 * ks + 8 * g, 32 * ks + 8 * g + 4, 64 * k + 16 * pt, lane), wg);
; #pragma unroll
;         for (int nt = 0; nt < 4; ++nt) { const bf16x8 A = frag_tr(Bi, bp, 32 * ks + 8 * g, 32 * ks + 8 * g + 4, 16 * (4 * nh + nt), lane);
; #pragma unroll
;             for (int pt = 0; pt < 4; ++pt) H[nt][pt] = mfma16(A, Bx[pt], H[nt][pt]);
;             SCHED_FENCE(); }
	v_lshlrev_b32_e32 v122, 16, v62
	v_mul_f32_e32 v36, v36, v122
	v_cvt_pk_bf16_f32 v127, v36, v36
	v_and_b32_e32 v36, 0xffff0000, v62
	v_mul_f32_e32 v36, v37, v36
	v_cvt_pk_bf16_f32 v150, v36, v36
	v_lshlrev_b32_e32 v36, 16, v63
	v_mul_f32_e32 v36, v38, v36
	v_cvt_pk_bf16_f32 v151, v36, v36
	v_and_b32_e32 v36, 0xffff0000, v63
	v_mul_f32_e32 v36, v39, v36
	v_cvt_pk_bf16_f32 v152, v36, v36
	v_lshlrev_b32_e32 v36, 16, v60
	v_mul_f32_e32 v36, v40, v36
	v_cvt_pk_bf16_f32 v153, v36, v36
	v_and_b32_e32 v36, 0xffff0000, v60
	v_mul_f32_e32 v36, v42, v36
	v_cvt_pk_bf16_f32 v154, v36, v36
	v_lshlrev_b32_e32 v36, 16, v61
	v_mul_f32_e32 v36, v48, v36
	v_cvt_pk_bf16_f32 v48, v36, v36
	v_and_b32_e32 v36, 0xffff0000, v61
	ds_read_b64_tr_b16 v[60:61], v155 offset:512
	ds_read_b64_tr_b16 v[62:63], v155 offset:4672
	v_and_b32_e32 v45, 0xffff0000, v45
	v_mul_f32_e32 v43, v37, v43
	v_mul_f32_e32 v44, v38, v44
	v_mul_f32_e32 v45, v39, v45
	v_mul_f32_e32 v46, v40, v46
	v_cvt_pk_bf16_f32 v41, v41, v41
	v_cvt_pk_bf16_f32 v43, v43, v43
	v_cvt_pk_bf16_f32 v44, v44, v44
	v_cvt_pk_bf16_f32 v45, v45, v45
	v_cvt_pk_bf16_f32 v46, v46, v46
	v_mul_f32_e32 v50, v37, v50
	v_mul_f32_e32 v52, v38, v52
	v_mul_f32_e32 v54, v39, v54
	v_mul_f32_e32 v55, v40, v55
	v_mul_f32_e32 v56, v42, v56
	v_mul_f32_e32 v58, v59, v58
	v_mul_f32_e32 v36, v59, v36
	v_perm_b32 v125, v53, v51, s75
	v_perm_b32 v124, v49, v46, s75
	v_perm_b32 v123, v45, v44, s75
	v_perm_b32 v122, v43, v41, s75
	v_cvt_pk_bf16_f32 v47, v47, v47
	v_cvt_pk_bf16_f32 v50, v50, v50
	v_cvt_pk_bf16_f32 v52, v52, v52
	v_cvt_pk_bf16_f32 v54, v54, v54
	v_cvt_pk_bf16_f32 v55, v55, v55
	v_cvt_pk_bf16_f32 v56, v56, v56
	v_cvt_pk_bf16_f32 v57, v57, v57
	v_cvt_pk_bf16_f32 v58, v58, v58
	v_cvt_pk_bf16_f32 v59, v36, v36
	s_waitcnt lgkmcnt(0)
	s_nop 0
	v_mfma_f32_16x16x32_bf16 v[36:39], v[60:63], v[122:125], v[98:101]
	v_perm_b32 v233, v59, v48, s75
	v_perm_b32 v232, v154, v153, s75
	v_perm_b32 v231, v152, v151, s75
	v_perm_b32 v101, v58, v57, s75
	v_perm_b32 v100, v56, v55, s75
	v_perm_b32 v99, v54, v52, s75
	v_perm_b32 v98, v50, v47, s75
	v_perm_b32 v230, v150, v127, s75
	s_nop 0
	v_mfma_f32_16x16x32_bf16 v[40:43], v[60:63], v[98:101], v[94:97]
	s_nop 2
	v_perm_b32 v97, v65, v126, s75
	v_perm_b32 v96, v64, v102, s75
	v_perm_b32 v95, v69, v68, s75
	v_perm_b32 v94, v67, v66, s75
	v_mfma_f32_16x16x32_bf16 v[48:51], v[60:63], v[230:233], v[86:89]
	s_nop 0
	v_mfma_f32_16x16x32_bf16 v[44:47], v[60:63], v[94:97], v[90:93]
	ds_read_b64_tr_b16 v[64:65], v155 offset:544
	ds_read_b64_tr_b16 v[66:67], v155 offset:4704
	s_waitcnt lgkmcnt(0)
	v_mfma_f32_16x16x32_bf16 v[52:55], v[64:67], v[122:125], v[70:73]
	v_mfma_f32_16x16x32_bf16 v[56:59], v[64:67], v[98:101], v[74:77]
	v_mfma_f32_16x16x32_bf16 v[60:63], v[64:67], v[94:97], v[78:81]
	v_mfma_f32_16x16x32_bf16 v[64:67], v[64:67], v[230:233], v[82:85]
	s_nop 1
	ds_read_b64_tr_b16 v[80:81], v155 offset:576
	ds_read_b64_tr_b16 v[82:83], v155 offset:4736
	s_waitcnt lgkmcnt(0)
	v_mfma_f32_16x16x32_bf16 v[68:71], v[80:83], v[122:125], v[20:23]
	v_mfma_f32_16x16x32_bf16 v[72:75], v[80:83], v[98:101], v[24:27]
	v_mfma_f32_16x16x32_bf16 v[76:79], v[80:83], v[94:97], v[28:31]
	v_mfma_f32_16x16x32_bf16 v[80:83], v[80:83], v[230:233], v[32:35]
	ds_read_b64_tr_b16 v[20:21], v155 offset:608
	ds_read_b64_tr_b16 v[22:23], v155 offset:4768
	s_waitcnt lgkmcnt(0)
	v_mfma_f32_16x16x32_bf16 v[84:87], v[20:23], v[122:125], v[0:3]
	v_mfma_f32_16x16x32_bf16 v[88:91], v[20:23], v[98:101], v[4:7]
	v_mfma_f32_16x16x32_bf16 v[92:95], v[20:23], v[94:97], v[12:15]
	v_mfma_f32_16x16x32_bf16 v[96:99], v[20:23], v[230:233], v[16:19]
	ds_read_b32 v0, v160
	ds_read_b32 v1, v161
	ds_read_b32 v2, v163
	ds_read_b32 v4, v167
	v_add_u32_e32 v32, v188, v133
	s_waitcnt lgkmcnt(0)
	v_sub_f32_e32 v0, v10, v0
	v_mul_f32_e32 v0, 0x3fb8aa3b, v0
	v_exp_f32_e32 v0, v0
	v_add_u32_e32 v177, v188, v159
	ds_read_b32 v3, v165
	ds_read_b32 v6, v171
	v_mul_f32_e32 v0, v1, v0
	ds_read_b32 v1, v162
	ds_read_b32 v5, v169
	ds_read_b32 v7, v173
	s_waitcnt lgkmcnt(0)
	v_sub_f32_e32 v1, v10, v1
	v_mul_f32_e32 v1, 0x3fb8aa3b, v1
	v_exp_f32_e32 v1, v1
	s_nop 0
	v_mul_f32_e32 v1, v2, v1
	ds_read_b32 v2, v164
	s_waitcnt lgkmcnt(0)
	v_sub_f32_e32 v2, v10, v2
	v_mul_f32_e32 v2, 0x3fb8aa3b, v2
	v_exp_f32_e32 v2, v2
	s_nop 0
	v_mul_f32_e32 v2, v3, v2
	ds_read_b32 v3, v166
	s_waitcnt lgkmcnt(0)
	v_sub_f32_e32 v3, v10, v3
	v_mul_f32_e32 v3, 0x3fb8aa3b, v3
	v_exp_f32_e32 v3, v3
	s_nop 0
	v_mul_f32_e32 v3, v4, v3
	ds_read_b32 v4, v168
	s_waitcnt lgkmcnt(0)
	v_sub_f32_e32 v4, v10, v4
	v_mul_f32_e32 v4, 0x3fb8aa3b, v4
	v_exp_f32_e32 v4, v4
	s_nop 0
	v_mul_f32_e32 v4, v5, v4
	ds_read_b32 v5, v170
	s_waitcnt lgkmcnt(0)
	v_sub_f32_e32 v5, v10, v5
	v_mul_f32_e32 v5, 0x3fb8aa3b, v5
	v_exp_f32_e32 v5, v5
	s_nop 0
	v_mul_f32_e32 v5, v6, v5
	ds_read_b32 v6, v172
	s_waitcnt lgkmcnt(0)
	v_sub_f32_e32 v6, v10, v6
	v_mul_f32_e32 v6, 0x3fb8aa3b, v6
	v_exp_f32_e32 v6, v6
	s_nop 0
	v_mul_f32_e32 v6, v7, v6
	ds_read_b32 v7, v174
	s_waitcnt lgkmcnt(0)
	v_sub_f32_e32 v7, v10, v7
	ds_read_b32 v10, v175
	ds_read_b64_tr_b16 v[20:21], v32 offset:4160
	ds_read_b64_tr_b16 v[12:13], v32
	ds_read_b64_tr_b16 v[22:23], v32 offset:32
	v_mul_f32_e32 v7, 0x3fb8aa3b, v7
	v_exp_f32_e32 v7, v7
	s_waitcnt lgkmcnt(0)
	v_and_b32_e32 v16, 0xffff0000, v20
	v_mul_f32_e32 v16, v5, v16
	ds_read_b64_tr_b16 v[26:27], v32 offset:4192
	v_cvt_pk_bf16_f32 v17, v16, v16
	v_lshlrev_b32_e32 v16, 16, v21
	ds_read_b64_tr_b16 v[28:29], v32 offset:64
	ds_read_b64_tr_b16 v[30:31], v32 offset:4224
	v_mul_f32_e32 v16, v6, v16
	v_mul_f32_e32 v14, v10, v7
	v_cvt_pk_bf16_f32 v19, v16, v16
	v_and_b32_e32 v16, 0xffff0000, v21
	v_mul_f32_e32 v16, v14, v16
	v_lshlrev_b32_e32 v15, 16, v20
	v_cvt_pk_bf16_f32 v21, v16, v16
	v_lshlrev_b32_e32 v16, 16, v22
	v_and_b32_e32 v18, 0xffff0000, v22
	v_lshlrev_b32_e32 v20, 16, v23
	v_and_b32_e32 v22, 0xffff0000, v23
	s_waitcnt lgkmcnt(0)
; #define LAS __attribute__((address_space(3)))
; __device__ __forceinline__ f32x4 mfma16(bf16x8 a, bf16x8 b, f32x4 c) { return __builtin_amdgcn_mfma_f32_16x16x32_bf16(a, b, c, 0, 0, 0); }
; __device__ __forceinline__ void sync_threads() { __syncthreads(); }
; #define SCHED_FENCE() do {} while (0)
; #define SCHED_FENCE() __builtin_amdgcn_sched_barrier(0)
; __device__ __forceinline__ void ssd_state_update(f32x4 (&H)[4][4], LAS unsigned char* Xi, int xp, LAS unsigned char* Bi, int bp, const LAS float* sDt, const LAS float* sCum, int w, int lane) {
;     const int g = lane >> 4, k = w >> 1, nh = w & 1;
;     const float tot = sCum[63 * 4 + k]; const float et = __expf(tot);
; #pragma unroll
;     for (int nt = 0; nt < 4; ++nt)
; #pragma unroll
;         for (int pt = 0; pt < 4; ++pt) H[nt][pt] = H[nt][pt] * et;
; #pragma unroll
;     for (int ks = 0; ks < 2; ++ks) {
;         float wg[8];
; #pragma unroll
;         for (int j = 0; j < 8; ++j) wg[j] = __expf(tot - sCum[(32 * ks + 8 * g + j) * 4 + k]) * sDt[(32 * ks + 8 * g + j) * 4 + k];
;         bf16x8 Bx[4];
; #pragma unroll
;         for (int pt = 0; pt < 4; ++pt) Bx[pt] = scale_frag8(frag_tr(Xi, xp, 32 * ks + 8 * g, 32 * ks + 8 * g + 4, 64 * k + 16 * pt, lane), wg);
; #pragma unroll
;         for (int nt = 0; nt < 4; ++nt) { const bf16x8 A = frag_tr(Bi, bp, 32 * ks + 8 * g, 32 * ks + 8 * g + 4, 16 * (4 * nh + nt), lane);
; #pragma unroll
;             for (int pt = 0; pt < 4; ++pt) H[nt][pt] = mfma16(A, Bx[pt], H[nt][pt]);
;             SCHED_FENCE(); }
;     }
; __device__ __forceinline__ void ssd_pass2(const RecurBufs& rb, const float* d_skip, const float* ssm_norm, float* state_out_l, int u, int tid, LAS unsigned char* lds) {
;     ...
;         sync_threads();
;         {   const f32x4 nw = *(const f32x4*)(ssm_norm + chn0);
;             unsigned long long yy[8];
;             const int itA = hf, itB = 3 - hf;
;             bf16* yb0 = rb.y + (row0 + 16 * itA + 4 * g) * 2048 + chn0;
	v_lshlrev_b32_e32 v23, 16, v26
	v_and_b32_e32 v24, 0xffff0000, v26
	v_lshlrev_b32_e32 v25, 16, v27
	v_and_b32_e32 v26, 0xffff0000, v27
	v_lshlrev_b32_e32 v27, 16, v28
	v_and_b32_e32 v28, 0xffff0000, v28
	v_mul_f32_e32 v28, v1, v28
	v_cvt_pk_bf16_f32 v33, v28, v28
	v_lshlrev_b32_e32 v28, 16, v29
	v_mul_f32_e32 v28, v2, v28
	v_cvt_pk_bf16_f32 v34, v28, v28
	v_and_b32_e32 v28, 0xffff0000, v29
	v_mul_f32_e32 v28, v3, v28
	v_cvt_pk_bf16_f32 v35, v28, v28
	v_lshlrev_b32_e32 v28, 16, v30
	v_mul_f32_e32 v28, v4, v28
	v_cvt_pk_bf16_f32 v100, v28, v28
	v_and_b32_e32 v28, 0xffff0000, v30
	v_mul_f32_e32 v28, v5, v28
	v_cvt_pk_bf16_f32 v101, v28, v28
	v_lshlrev_b32_e32 v28, 16, v31
	v_mul_f32_e32 v28, v6, v28
	v_cvt_pk_bf16_f32 v102, v28, v28
	v_and_b32_e32 v28, 0xffff0000, v31
	v_mul_f32_e32 v28, v14, v28
	v_cvt_pk_bf16_f32 v126, v28, v28
	ds_read_b64_tr_b16 v[28:29], v32 offset:96
	ds_read_b64_tr_b16 v[30:31], v32 offset:4256
	v_lshlrev_b32_e32 v7, 16, v12
	v_mul_f32_e32 v7, v0, v7
	v_mul_f32_e32 v16, v0, v16
	s_waitcnt lgkmcnt(0)
	v_lshlrev_b32_e32 v32, 16, v28
	v_mul_f32_e32 v27, v0, v27
	v_mul_f32_e32 v0, v0, v32
	v_cvt_pk_bf16_f32 v32, v0, v0
	v_and_b32_e32 v0, 0xffff0000, v28
	v_mul_f32_e32 v0, v1, v0
	v_cvt_pk_bf16_f32 v127, v0, v0
	v_lshlrev_b32_e32 v0, 16, v29
	v_mul_f32_e32 v0, v2, v0
	v_cvt_pk_bf16_f32 v150, v0, v0
	v_and_b32_e32 v0, 0xffff0000, v29
	v_mul_f32_e32 v0, v3, v0
	v_cvt_pk_bf16_f32 v151, v0, v0
	v_lshlrev_b32_e32 v0, 16, v30
	v_mul_f32_e32 v0, v4, v0
	v_cvt_pk_bf16_f32 v152, v0, v0
	v_and_b32_e32 v0, 0xffff0000, v30
	v_mul_f32_e32 v0, v5, v0
	v_cvt_pk_bf16_f32 v153, v0, v0
	v_lshlrev_b32_e32 v0, 16, v31
	v_mul_f32_e32 v0, v6, v0
	v_cvt_pk_bf16_f32 v154, v0, v0
	v_and_b32_e32 v0, 0xffff0000, v31
	ds_read_b64_tr_b16 v[28:29], v177 offset:512
	ds_read_b64_tr_b16 v[30:31], v177 offset:4672
	v_and_b32_e32 v10, 0xffff0000, v12
	v_lshlrev_b32_e32 v12, 16, v13
	v_and_b32_e32 v13, 0xffff0000, v13
	v_mul_f32_e32 v10, v1, v10
	v_mul_f32_e32 v12, v2, v12
	v_mul_f32_e32 v13, v3, v13
	v_mul_f32_e32 v15, v4, v15
	v_mul_f32_e32 v18, v1, v18
	v_mul_f32_e32 v20, v2, v20
	v_mul_f32_e32 v22, v3, v22
	v_mul_f32_e32 v23, v4, v23
	v_mul_f32_e32 v24, v5, v24
	v_mul_f32_e32 v25, v6, v25
	v_mul_f32_e32 v26, v14, v26
	v_cvt_pk_bf16_f32 v7, v7, v7
	v_cvt_pk_bf16_f32 v10, v10, v10
	v_cvt_pk_bf16_f32 v12, v12, v12
	v_cvt_pk_bf16_f32 v13, v13, v13
	v_cvt_pk_bf16_f32 v15, v15, v15
	v_cvt_pk_bf16_f32 v16, v16, v16
	v_cvt_pk_bf16_f32 v18, v18, v18
	v_cvt_pk_bf16_f32 v20, v20, v20
	v_cvt_pk_bf16_f32 v22, v22, v22
	v_cvt_pk_bf16_f32 v23, v23, v23
	v_cvt_pk_bf16_f32 v24, v24, v24
	v_cvt_pk_bf16_f32 v25, v25, v25
	v_cvt_pk_bf16_f32 v26, v26, v26
	v_cvt_pk_bf16_f32 v27, v27, v27
	v_mul_f32_e32 v0, v14, v0
	v_cvt_pk_bf16_f32 v155, v0, v0
	v_perm_b32 v125, v21, v19, s75
	v_perm_b32 v124, v17, v15, s75
	v_perm_b32 v123, v13, v12, s75
	v_perm_b32 v122, v10, v7, s75
	v_perm_b32 v233, v26, v25, s75
	v_perm_b32 v232, v24, v23, s75
	v_perm_b32 v231, v22, v20, s75
	v_perm_b32 v230, v18, v16, s75
	v_perm_b32 v237, v126, v102, s75
	v_perm_b32 v236, v101, v100, s75
	v_perm_b32 v235, v35, v34, s75
	v_perm_b32 v234, v33, v27, s75
	v_perm_b32 v241, v155, v154, s75
	v_perm_b32 v240, v153, v152, s75
	v_perm_b32 v239, v151, v150, s75
	v_perm_b32 v238, v127, v32, s75
	s_waitcnt lgkmcnt(0)
	v_mfma_f32_16x16x32_bf16 v[0:3], v[28:31], v[122:125], v[36:39]
	v_mfma_f32_16x16x32_bf16 v[4:7], v[28:31], v[230:233], v[40:43]
	v_mfma_f32_16x16x32_bf16 v[14:17], v[28:31], v[234:237], v[44:47]
	v_mfma_f32_16x16x32_bf16 v[18:21], v[28:31], v[238:241], v[48:51]
	ds_read_b64_tr_b16 v[34:35], v177 offset:544
	ds_read_b64_tr_b16 v[36:37], v177 offset:4704
	s_waitcnt lgkmcnt(0)
	v_mfma_f32_16x16x32_bf16 v[22:25], v[34:37], v[122:125], v[52:55]
	v_mfma_f32_16x16x32_bf16 v[26:29], v[34:37], v[230:233], v[56:59]
	v_mfma_f32_16x16x32_bf16 v[30:33], v[34:37], v[234:237], v[60:63]
	v_mfma_f32_16x16x32_bf16 v[34:37], v[34:37], v[238:241], v[64:67]
	ds_read_b64_tr_b16 v[50:51], v177 offset:576
	ds_read_b64_tr_b16 v[52:53], v177 offset:4736
	s_waitcnt lgkmcnt(0)
	v_mfma_f32_16x16x32_bf16 v[38:41], v[50:53], v[122:125], v[68:71]
	v_mfma_f32_16x16x32_bf16 v[42:45], v[50:53], v[230:233], v[72:75]
	v_mfma_f32_16x16x32_bf16 v[46:49], v[50:53], v[234:237], v[76:79]
	v_mfma_f32_16x16x32_bf16 v[50:53], v[50:53], v[238:241], v[80:83]
	ds_read_b64_tr_b16 v[66:67], v177 offset:608
	ds_read_b64_tr_b16 v[68:69], v177 offset:4768
	s_waitcnt lgkmcnt(0)
	v_mfma_f32_16x16x32_bf16 v[54:57], v[66:69], v[122:125], v[84:87]
	v_mfma_f32_16x16x32_bf16 v[58:61], v[66:69], v[230:233], v[88:91]
	v_mfma_f32_16x16x32_bf16 v[62:65], v[66:69], v[234:237], v[92:95]
	v_mfma_f32_16x16x32_bf16 v[66:69], v[66:69], v[238:241], v[96:99]
	v_mov_b32_e32 v13, s61
	v_or_b32_e32 v12, s60, v112
	v_lshlrev_b64 v[12:13], 12, v[12:13]
	v_lshl_add_u64 v[90:91], v[116:117], 0, v[12:13]
	v_mov_b64_e32 v[12:13], v[90:91]
	s_barrier
; __device__ __forceinline__ unsigned pk2(float lo, float hi) { unsigned r; asm("v_cvt_pk_bf16_f32 %0, %1, %2" : "=v"(r) : "v"(lo), "v"(hi)); return r; }
; #define LAUNDER_PTR(p) do {} while (0)
; #define LAUNDER_PTR(p) asm volatile("" : "+v"(p))
; __device__ __forceinline__ void ssd_pass2(const RecurBufs& rb, const float* d_skip, const float* ssm_norm, float* state_out_l, int u, int tid, LAS unsigned char* lds) {
;     ...
;         {   const f32x4 nw = *(const f32x4*)(ssm_norm + chn0);
;             unsigned long long yy[8];
;             const int itA = hf, itB = 3 - hf;
;             bf16* yb0 = rb.y + (row0 + 16 * itA + 4 * g) * 2048 + chn0;
;             const int jump = (16 * (itB - itA) - 3) * 2048;
;             {   bf16* yp = yb0;
; #pragma unroll
;                 for (int q = 0; q < 8; ++q) { LAUNDER_PTR(yp); yy[q] = *(const unsigned long long*)yp; yp += (q == 3) ? jump : 2048; } }
;             bf16* yp = yb0;
; #pragma unroll
;             for (int q = 0; q < 8; ++q) { const int i = 16 * (q < 4 ? itA : itB) + 4 * g + (q & 3);
;                 const float rstd = rsqrtf(((red[i * 4] + red[i * 4 + 1]) + (red[i * 4 + 2] + red[i * 4 + 3])) * (1.f / 256.f) + EPS);
;                 const unsigned lo = (unsigned)yy[q], hi = (unsigned)(yy[q] >> 32);
;                 const float y0 = __uint_as_float(lo << 16) * rstd * nw[0], y1 = __uint_as_float(lo & 0xffff0000u) * rstd * nw[1], y2 = __uint_as_float(hi << 16) * rstd * nw[2], y3 = __uint_as_float(hi & 0xffff0000u) * rstd * nw[3];
;                 LAUNDER_PTR(yp); *(unsigned long long*)yp = (unsigned long long)pk2(y0, y1) | ((unsigned long long)pk2(y2, y3) << 32); yp += (q == 3) ? jump : 2048; } }
	global_load_dwordx4 v[70:73], v[110:111], off
	global_load_dwordx2 v[92:93], v[12:13], off
	v_lshl_add_u64 v[12:13], v[12:13], 0, s[94:95]
	global_load_dwordx2 v[84:85], v[12:13], off
	v_lshl_add_u64 v[12:13], v[12:13], 0, s[94:95]
	global_load_dwordx2 v[82:83], v[12:13], off
	v_lshl_add_u64 v[12:13], v[12:13], 0, s[94:95]
	global_load_dwordx2 v[80:81], v[12:13], off
	v_lshl_add_u64 v[12:13], v[12:13], 0, v[120:121]
	global_load_dwordx2 v[78:79], v[12:13], off
	v_lshl_add_u64 v[12:13], v[12:13], 0, s[94:95]
	global_load_dwordx2 v[76:77], v[12:13], off
	v_lshl_add_u64 v[12:13], v[12:13], 0, s[94:95]
	global_load_dwordx2 v[74:75], v[12:13], off
	v_lshl_add_u64 v[12:13], v[12:13], 0, s[94:95]
	ds_read_b128 v[86:89], v226
	global_load_dwordx2 v[12:13], v[12:13], off
	s_add_i32 s62, s62, 1
	s_cmp_eq_u32 s62, 8
	s_waitcnt lgkmcnt(0)
	v_mov_b32_e32 v94, v87
	v_mov_b32_e32 v95, v88
	v_mov_b32_e32 v87, v89
	v_pk_add_f32 v[86:87], v[94:95], v[86:87]
	s_waitcnt vmcnt(0)
	v_lshlrev_b32_e32 v88, 16, v93
	v_add_f32_e32 v10, v86, v87
	v_fmamk_f32 v10, v10, 0x3b800000, v176
	v_cmp_gt_f32_e32 vcc, s33, v10
	v_mul_f32_e32 v86, 0x4b800000, v10
	v_and_b32_e32 v87, 0xffff0000, v92
	v_cndmask_b32_e32 v10, v10, v86, vcc
	v_rsq_f32_e32 v10, v10
	v_and_b32_e32 v89, 0xffff0000, v93
	v_mul_f32_e32 v86, 0x45800000, v10
	v_cndmask_b32_e32 v10, v10, v86, vcc
	v_lshlrev_b32_e32 v86, 16, v92
	v_mul_f32_e32 v86, v10, v86
	v_mul_f32_e32 v87, v10, v87
	v_mul_f32_e32 v86, v70, v86
	v_mul_f32_e32 v87, v71, v87
	v_mul_f32_e32 v88, v10, v88
	v_mul_f32_e32 v10, v10, v89
	v_mul_f32_e32 v88, v72, v88
	v_mul_f32_e32 v10, v73, v10
	v_cvt_pk_bf16_f32 v86, v86, v87
	v_cvt_pk_bf16_f32 v87, v88, v10
	global_store_dwordx2 v[90:91], v[86:87], off
	ds_read_b128 v[86:89], v226 offset:16
	v_lshl_add_u64 v[90:91], v[90:91], 0, s[94:95]
	s_waitcnt lgkmcnt(0)
	v_mov_b32_e32 v92, v87
	v_mov_b32_e32 v93, v88
	v_mov_b32_e32 v87, v89
	v_pk_add_f32 v[86:87], v[92:93], v[86:87]
	v_lshl_add_u64 v[88:89], v[90:91], 0, s[94:95]
	v_add_f32_e32 v10, v86, v87
	v_fmamk_f32 v10, v10, 0x3b800000, v176
	v_cmp_gt_f32_e32 vcc, s33, v10
	v_mul_f32_e32 v86, 0x4b800000, v10
	v_lshlrev_b32_e32 v87, 16, v85
	v_cndmask_b32_e32 v10, v10, v86, vcc
	v_rsq_f32_e32 v10, v10
	v_and_b32_e32 v85, 0xffff0000, v85
	v_mul_f32_e32 v86, 0x45800000, v10
	v_cndmask_b32_e32 v10, v10, v86, vcc
	v_lshlrev_b32_e32 v86, 16, v84
	v_and_b32_e32 v84, 0xffff0000, v84
	v_mul_f32_e32 v84, v10, v84
	v_mul_f32_e32 v86, v10, v86
	v_mul_f32_e32 v84, v71, v84
	v_mul_f32_e32 v87, v10, v87
	v_mul_f32_e32 v10, v10, v85
	v_mul_f32_e32 v86, v70, v86
	v_mul_f32_e32 v87, v72, v87
	v_mul_f32_e32 v10, v73, v10
	v_cvt_pk_bf16_f32 v84, v86, v84
	v_cvt_pk_bf16_f32 v85, v87, v10
	global_store_dwordx2 v[90:91], v[84:85], off
	ds_read_b128 v[84:87], v226 offset:32
	s_waitcnt lgkmcnt(0)
	v_mov_b32_e32 v90, v85
	v_mov_b32_e32 v91, v86
	v_mov_b32_e32 v85, v87
	v_pk_add_f32 v[84:85], v[90:91], v[84:85]
	v_lshl_add_u64 v[86:87], v[88:89], 0, s[94:95]
	v_add_f32_e32 v10, v84, v85
	v_fmamk_f32 v10, v10, 0x3b800000, v176
	v_cmp_gt_f32_e32 vcc, s33, v10
	v_mul_f32_e32 v84, 0x4b800000, v10
	v_lshlrev_b32_e32 v85, 16, v83
	v_cndmask_b32_e32 v10, v10, v84, vcc
	v_rsq_f32_e32 v10, v10
	v_and_b32_e32 v83, 0xffff0000, v83
	v_mul_f32_e32 v84, 0x45800000, v10
	v_cndmask_b32_e32 v10, v10, v84, vcc
	v_lshlrev_b32_e32 v84, 16, v82
	v_and_b32_e32 v82, 0xffff0000, v82
	v_mul_f32_e32 v82, v10, v82
	v_mul_f32_e32 v84, v10, v84
	v_mul_f32_e32 v82, v71, v82
	v_mul_f32_e32 v85, v10, v85
	v_mul_f32_e32 v10, v10, v83
	v_mul_f32_e32 v84, v70, v84
	v_mul_f32_e32 v85, v72, v85
	v_mul_f32_e32 v10, v73, v10
	v_cvt_pk_bf16_f32 v82, v84, v82
	v_cvt_pk_bf16_f32 v83, v85, v10
	global_store_dwordx2 v[88:89], v[82:83], off
	ds_read_b128 v[82:85], v226 offset:48
	s_waitcnt lgkmcnt(0)
	v_mov_b32_e32 v88, v83
	v_mov_b32_e32 v89, v84
	v_mov_b32_e32 v83, v85
	v_pk_add_f32 v[82:83], v[88:89], v[82:83]
	v_lshl_add_u64 v[84:85], v[86:87], 0, v[120:121]
	v_add_f32_e32 v10, v82, v83
	v_fmamk_f32 v10, v10, 0x3b800000, v176
	v_cmp_gt_f32_e32 vcc, s33, v10
	v_mul_f32_e32 v82, 0x4b800000, v10
	v_lshlrev_b32_e32 v83, 16, v81
	v_cndmask_b32_e32 v10, v10, v82, vcc
	v_rsq_f32_e32 v10, v10
	v_and_b32_e32 v81, 0xffff0000, v81
	v_mul_f32_e32 v82, 0x45800000, v10
	v_cndmask_b32_e32 v10, v10, v82, vcc
	v_lshlrev_b32_e32 v82, 16, v80
	v_and_b32_e32 v80, 0xffff0000, v80
	v_mul_f32_e32 v80, v10, v80
	v_mul_f32_e32 v82, v10, v82
	v_mul_f32_e32 v80, v71, v80
	v_mul_f32_e32 v83, v10, v83
	v_mul_f32_e32 v10, v10, v81
	v_mul_f32_e32 v82, v70, v82
	v_mul_f32_e32 v83, v72, v83
	v_mul_f32_e32 v10, v73, v10
	v_cvt_pk_bf16_f32 v80, v82, v80
	v_cvt_pk_bf16_f32 v81, v83, v10
	global_store_dwordx2 v[86:87], v[80:81], off
	ds_read_b128 v[80:83], v227
	s_waitcnt lgkmcnt(0)
; __device__ __forceinline__ unsigned pk2(float lo, float hi) { unsigned r; asm("v_cvt_pk_bf16_f32 %0, %1, %2" : "=v"(r) : "v"(lo), "v"(hi)); return r; }
; #define LAUNDER_PTR(p) do {} while (0)
; #define LAUNDER_PTR(p) asm volatile("" : "+v"(p))
; __device__ __forceinline__ void ssd_pass2(const RecurBufs& rb, const float* d_skip, const float* ssm_norm, float* state_out_l, int u, int tid, LAS unsigned char* lds) {
;     ...
;     for (int ch = 0; ch < NCH; ++ch) {
;         const size_t row0 = rowS + ch * RC;
;         {   v4u raw[8];
;             {   const bf16* gp = rb.xbcc + (row0 + rr) * 4096 + gcol;
; #pragma unroll
;                 for (int i = 0; i < 8; ++i) { LAUNDER_PTR(gp); raw[i] = *(const v4u*)gp; gp += 8 * 4096; } }
;             if (tid < 256) { sDt[tid] = rb.dtv[(row0 + (tid >> 2)) * 32 + grp * 4 + (tid & 3)]; sCum[tid] = rb.cum[(row0 + (tid >> 2)) * 32 + grp * 4 + (tid & 3)]; }
;     ...
;             {   bf16* yp = yb0;
; #pragma unroll
;                 for (int q = 0; q < 8; ++q) { LAUNDER_PTR(yp); yy[q] = *(const unsigned long long*)yp; yp += (q == 3) ? jump : 2048; } }
;             bf16* yp = yb0;
; #pragma unroll
;             for (int q = 0; q < 8; ++q) { const int i = 16 * (q < 4 ? itA : itB) + 4 * g + (q & 3);
;                 const float rstd = rsqrtf(((red[i * 4] + red[i * 4 + 1]) + (red[i * 4 + 2] + red[i * 4 + 3])) * (1.f / 256.f) + EPS);
;                 const unsigned lo = (unsigned)yy[q], hi = (unsigned)(yy[q] >> 32);
;                 const float y0 = __uint_as_float(lo << 16) * rstd * nw[0], y1 = __uint_as_float(lo & 0xffff0000u) * rstd * nw[1], y2 = __uint_as_float(hi << 16) * rstd * nw[2], y3 = __uint_as_float(hi & 0xffff0000u) * rstd * nw[3];
;                 LAUNDER_PTR(yp); *(unsigned long long*)yp = (unsigned long long)pk2(y0, y1) | ((unsigned long long)pk2(y2, y3) << 32); yp += (q == 3) ? jump : 2048; } }
	v_mov_b32_e32 v86, v81
	v_mov_b32_e32 v87, v82
	v_mov_b32_e32 v81, v83
	v_pk_add_f32 v[80:81], v[86:87], v[80:81]
	v_lshl_add_u64 v[82:83], v[84:85], 0, s[94:95]
	v_add_f32_e32 v10, v80, v81
	v_fmamk_f32 v10, v10, 0x3b800000, v176
	v_cmp_gt_f32_e32 vcc, s33, v10
	v_mul_f32_e32 v80, 0x4b800000, v10
	v_lshlrev_b32_e32 v81, 16, v79
	v_cndmask_b32_e32 v10, v10, v80, vcc
	v_rsq_f32_e32 v10, v10
	v_and_b32_e32 v79, 0xffff0000, v79
	v_mul_f32_e32 v80, 0x45800000, v10
	v_cndmask_b32_e32 v10, v10, v80, vcc
	v_lshlrev_b32_e32 v80, 16, v78
	v_and_b32_e32 v78, 0xffff0000, v78
	v_mul_f32_e32 v78, v10, v78
	v_mul_f32_e32 v80, v10, v80
	v_mul_f32_e32 v78, v71, v78
	v_mul_f32_e32 v81, v10, v81
	v_mul_f32_e32 v10, v10, v79
	v_mul_f32_e32 v80, v70, v80
	v_mul_f32_e32 v81, v72, v81
	v_mul_f32_e32 v10, v73, v10
	v_cvt_pk_bf16_f32 v78, v80, v78
	v_cvt_pk_bf16_f32 v79, v81, v10
	global_store_dwordx2 v[84:85], v[78:79], off
	ds_read_b128 v[78:81], v227 offset:16
	s_waitcnt lgkmcnt(0)
	v_mov_b32_e32 v84, v79
	v_mov_b32_e32 v85, v80
	v_mov_b32_e32 v79, v81
	v_pk_add_f32 v[78:79], v[84:85], v[78:79]
	v_lshl_add_u64 v[80:81], v[82:83], 0, s[94:95]
	v_add_f32_e32 v10, v78, v79
	v_fmamk_f32 v10, v10, 0x3b800000, v176
	v_cmp_gt_f32_e32 vcc, s33, v10
	v_mul_f32_e32 v78, 0x4b800000, v10
	v_lshlrev_b32_e32 v79, 16, v77
	v_cndmask_b32_e32 v10, v10, v78, vcc
	v_rsq_f32_e32 v10, v10
	v_and_b32_e32 v77, 0xffff0000, v77
	v_mul_f32_e32 v78, 0x45800000, v10
	v_cndmask_b32_e32 v10, v10, v78, vcc
	v_lshlrev_b32_e32 v78, 16, v76
	v_and_b32_e32 v76, 0xffff0000, v76
	v_mul_f32_e32 v76, v10, v76
	v_mul_f32_e32 v78, v10, v78
	v_mul_f32_e32 v76, v71, v76
	v_mul_f32_e32 v79, v10, v79
	v_mul_f32_e32 v10, v10, v77
	v_mul_f32_e32 v78, v70, v78
	v_mul_f32_e32 v79, v72, v79
	v_mul_f32_e32 v10, v73, v10
	v_cvt_pk_bf16_f32 v76, v78, v76
	v_cvt_pk_bf16_f32 v77, v79, v10
	global_store_dwordx2 v[82:83], v[76:77], off
	ds_read_b128 v[76:79], v227 offset:32
	s_waitcnt lgkmcnt(0)
	v_mov_b32_e32 v82, v77
	v_mov_b32_e32 v83, v78
	v_mov_b32_e32 v77, v79
	v_pk_add_f32 v[76:77], v[82:83], v[76:77]
	v_lshl_add_u64 v[78:79], v[80:81], 0, s[94:95]
	v_add_f32_e32 v10, v76, v77
	v_fmamk_f32 v10, v10, 0x3b800000, v176
	v_cmp_gt_f32_e32 vcc, s33, v10
	v_mul_f32_e32 v76, 0x4b800000, v10
	v_lshlrev_b32_e32 v77, 16, v75
	v_cndmask_b32_e32 v10, v10, v76, vcc
	v_rsq_f32_e32 v10, v10
	v_and_b32_e32 v75, 0xffff0000, v75
	v_mul_f32_e32 v76, 0x45800000, v10
	v_cndmask_b32_e32 v10, v10, v76, vcc
	v_lshlrev_b32_e32 v76, 16, v74
	v_and_b32_e32 v74, 0xffff0000, v74
	v_mul_f32_e32 v74, v10, v74
	v_mul_f32_e32 v76, v10, v76
	v_mul_f32_e32 v74, v71, v74
	v_mul_f32_e32 v77, v10, v77
	v_mul_f32_e32 v10, v10, v75
	v_mul_f32_e32 v76, v70, v76
	v_mul_f32_e32 v77, v72, v77
	v_mul_f32_e32 v10, v73, v10
	v_cvt_pk_bf16_f32 v74, v76, v74
	v_cvt_pk_bf16_f32 v75, v77, v10
	global_store_dwordx2 v[80:81], v[74:75], off
	ds_read_b128 v[74:77], v227 offset:48
	s_waitcnt lgkmcnt(0)
	v_mov_b32_e32 v80, v75
	v_mov_b32_e32 v81, v76
	v_mov_b32_e32 v75, v77
	v_pk_add_f32 v[74:75], v[80:81], v[74:75]
	s_nop 0
	v_add_f32_e32 v10, v74, v75
	v_fmamk_f32 v10, v10, 0x3b800000, v176
	v_cmp_gt_f32_e32 vcc, s33, v10
	v_mul_f32_e32 v74, 0x4b800000, v10
	s_nop 0
	v_cndmask_b32_e32 v10, v10, v74, vcc
	v_rsq_f32_e32 v10, v10
	s_nop 0
	v_mul_f32_e32 v74, 0x45800000, v10
	v_cndmask_b32_e32 v10, v10, v74, vcc
	v_lshlrev_b32_e32 v74, 16, v12
	v_and_b32_e32 v12, 0xffff0000, v12
	v_mul_f32_e32 v12, v10, v12
	v_mul_f32_e32 v12, v71, v12
	v_lshlrev_b32_e32 v71, 16, v13
	v_and_b32_e32 v13, 0xffff0000, v13
	v_mul_f32_e32 v74, v10, v74
	v_mul_f32_e32 v71, v10, v71
	v_mul_f32_e32 v10, v10, v13
	v_mul_f32_e32 v70, v70, v74
	v_mul_f32_e32 v71, v72, v71
	v_mul_f32_e32 v10, v73, v10
	v_cvt_pk_bf16_f32 v12, v70, v12
	v_cvt_pk_bf16_f32 v13, v71, v10
	global_store_dwordx2 v[78:79], v[12:13], off
	s_waitcnt lgkmcnt(0)
	s_barrier
	s_cbranch_scc1 .LBB0_848
.LBB0_866:
	s_lshl_b32 s2, s62, 6
	s_add_u32 s60, s36, s2
	s_addc_u32 s61, s37, 0
	v_lshl_add_u64 v[12:13], s[60:61], 0, v[104:105]
	v_lshlrev_b64 v[12:13], 13, v[12:13]
	v_lshl_add_u64 v[12:13], v[114:115], 0, v[12:13]
	global_load_dwordx4 v[70:73], v[12:13], off
	v_lshl_add_u64 v[12:13], v[12:13], 0, s[42:43]
	global_load_dwordx4 v[74:77], v[12:13], off
	v_lshl_add_u64 v[12:13], v[12:13], 0, s[42:43]
	global_load_dwordx4 v[78:81], v[12:13], off
	v_lshl_add_u64 v[12:13], v[12:13], 0, s[42:43]
	global_load_dwordx4 v[82:85], v[12:13], off
	v_lshl_add_u64 v[12:13], v[12:13], 0, s[42:43]
	global_load_dwordx4 v[86:89], v[12:13], off
	v_lshl_add_u64 v[12:13], v[12:13], 0, s[42:43]
	global_load_dwordx4 v[90:93], v[12:13], off
	v_lshl_add_u64 v[12:13], v[12:13], 0, s[42:43]
	global_load_dwordx4 v[94:97], v[12:13], off
	v_lshl_add_u64 v[12:13], v[12:13], 0, s[42:43]
	global_load_dwordx4 v[98:101], v[12:13], off
	s_and_saveexec_b64 s[2:3], s[4:5]
	s_cbranch_execz .LBB0_868
	v_lshl_add_u64 v[12:13], s[60:61], 0, v[106:107]
	v_lshlrev_b64 v[12:13], 7, v[12:13]
	v_lshl_or_b32 v12, v108, 2, v12
	v_lshl_add_u64 v[122:123], s[22:23], 0, v[12:13]
	global_load_dword v10, v[122:123], off
	v_lshl_add_u64 v[12:13], s[24:25], 0, v[12:13]
	s_waitcnt vmcnt(0) lgkmcnt(0)
	ds_write_b32 v128, v10
	global_load_dword v10, v[12:13], off
	s_waitcnt vmcnt(0) lgkmcnt(0)
	ds_write_b32 v129, v10

; __device__ __forceinline__ f32x4 mfma16(bf16x8 a, bf16x8 b, f32x4 c) { return __builtin_amdgcn_mfma_f32_16x16x32_bf16(a, b, c, 0, 0, 0); }
; #define SCHED_FENCE() do {} while (0)
; #define SCHED_FENCE() __builtin_amdgcn_sched_barrier(0)
; __device__ __forceinline__ void ssd_pass2(const RecurBufs& rb, const float* d_skip, const float* ssm_norm, float* state_out_l, int u, int tid, LAS unsigned char* lds) {
;     ...
;         for (int i2 = 0; i2 < 2; ++i2) {
;             const int it = i2 ? 3 - hf : hf;
;             unsigned long long zz[4];
; #pragma unroll
;             for (int r = 0; r < 4; ++r) zz[r] = *(const unsigned long long*)(rb.proj + (row0 + 16 * it + 4 * g + r) * LDP + PC_Z + chn0);
;             f32x4 ya[4];
; #pragma unroll
;             for (int pt = 0; pt < 4; ++pt) ya[pt] = (f32x4){0.f, 0.f, 0.f, 0.f};
; #pragma unroll
;             for (int kn = 0; kn < 4; ++kn) { const bf16x8 Cf = frag_rows(sC, PR, 16 * it + c, 32 * kn + 8 * g);
; #pragma unroll
;                 for (int pt = 0; pt < 4; ++pt) ya[pt] = mfma16(Cf, frag_rows(hS, PQ, 4 * c + pt, 32 * kn + 8 * g), ya[pt]);
;                 SCHED_FENCE(); }
;             {   float ei[4];
; #pragma unroll
;                 for (int r = 0; r < 4; ++r) ei[r] = __expf(sCum[(16 * it + 4 * g + r) * 4 + k]);
; #pragma unroll
;                 for (int pt = 0; pt < 4; ++pt)
; #pragma unroll
;                     for (int r = 0; r < 4; ++r) ya[pt][r] *= ei[r]; }
;             const float cum_i = sCum[(16 * it + c) * 4 + k];
;             unsigned PT[4][2];
; #pragma unroll
;             for (int jt = 0; jt < 4; ++jt) {
;                 f32x4 acc = (f32x4){0.f, 0.f, 0.f, 0.f};
;                 if (jt <= it) {
; #pragma unroll
;                     for (int kn = 0; kn < 4; ++kn) acc = mfma16(frag_rows(sB, PR, 16 * jt + c, 32 * kn + 8 * g), frag_rows(sC, PR, 16 * it + c, 32 * kn + 8 * g), acc);
; #pragma unroll
;                     for (int r = 0; r < 4; ++r) { const int j = 16 * jt + 4 * g + r; const float df = cum_i - sCum[j * 4 + k]; const bool keep = (jt < it) || (4 * g + r <= c);
.LBB0_870:
	v_cndmask_b32_e64 v94, v130, v109, s[16:17]
	v_lshlrev_b32_e32 v70, 4, v94
	v_or_b32_e32 v102, v70, v113
	v_or_b32_e32 v124, s60, v102
	v_mov_b64_e32 v[74:75], s[28:29]
	s_waitcnt lgkmcnt(0)
	v_mad_u64_u32 v[12:13], s[2:3], v124, s77, v[74:75]
	s_mul_i32 s50, s61, 0x6200
	v_add_u32_e32 v13, s50, v13
	v_lshl_add_u64 v[12:13], v[12:13], 0, v[118:119]
	v_or_b32_e32 v10, 1, v102
	v_add_co_u32_e32 v86, vcc, 0x2000, v12
	v_or_b32_e32 v12, s60, v10
	s_nop 0
	v_addc_co_u32_e32 v87, vcc, 0, v13, vcc
	v_mad_u64_u32 v[12:13], s[2:3], v12, s77, v[74:75]
	v_add_u32_e32 v13, s50, v13
	v_lshl_add_u64 v[12:13], v[12:13], 0, v[118:119]
	v_or_b32_e32 v98, 2, v102
	v_add_co_u32_e32 v88, vcc, 0x2000, v12
	v_or_b32_e32 v12, s60, v98
	s_nop 0
	v_addc_co_u32_e32 v89, vcc, 0, v13, vcc
	v_mad_u64_u32 v[12:13], s[2:3], v12, s77, v[74:75]
	v_add_u32_e32 v13, s50, v13
	v_lshl_add_u64 v[12:13], v[12:13], 0, v[118:119]
	v_add_co_u32_e32 v90, vcc, 0x2000, v12
	v_or_b32_e32 v12, 3, v102
	v_or_b32_e32 v76, s60, v12
	v_mad_u64_u32 v[78:79], s[2:3], v76, s77, v[74:75]
	v_add_u32_e32 v79, s50, v79
	v_addc_co_u32_e32 v91, vcc, 0, v13, vcc
	v_or_b32_e32 v13, v70, v9
	v_lshl_add_u64 v[82:83], v[78:79], 0, v[118:119]
	v_mad_u32_u24 v95, v13, s89, v222
	v_add_co_u32_e32 v92, vcc, 0x2000, v82
	ds_read_b128 v[70:73], v95 offset:768
	ds_read_b128 v[74:77], v225
	ds_read_b128 v[78:81], v225 offset:272
	v_addc_co_u32_e32 v93, vcc, 0, v83, vcc
	ds_read_b128 v[82:85], v225 offset:544
	global_load_dwordx2 v[126:127], v[86:87], off
	global_load_dwordx2 v[122:123], v[88:89], off
	global_load_dwordx2 v[100:101], v[90:91], off
	global_load_dwordx2 v[96:97], v[92:93], off
	ds_read_b128 v[86:89], v225 offset:816
	s_waitcnt lgkmcnt(0)
	v_mfma_f32_16x16x32_bf16 v[74:77], v[70:73], v[74:77], 0
	v_mov_b32_e32 v125, s61
	v_mfma_f32_16x16x32_bf16 v[78:81], v[70:73], v[78:81], 0
	v_mfma_f32_16x16x32_bf16 v[82:85], v[70:73], v[82:85], 0
	v_mfma_f32_16x16x32_bf16 v[70:73], v[70:73], v[86:89], 0
	ds_read_b128 v[86:89], v95 offset:832
	ds_read_b128 v[90:93], v225 offset:64
	s_waitcnt lgkmcnt(0)
	v_mfma_f32_16x16x32_bf16 v[74:77], v[86:89], v[90:93], v[74:77]
	ds_read_b128 v[90:93], v225 offset:336
	s_waitcnt lgkmcnt(0)
	v_mfma_f32_16x16x32_bf16 v[78:81], v[86:89], v[90:93], v[78:81]
	ds_read_b128 v[90:93], v225 offset:608
	s_waitcnt lgkmcnt(0)
	v_mfma_f32_16x16x32_bf16 v[82:85], v[86:89], v[90:93], v[82:85]
	ds_read_b128 v[90:93], v225 offset:880
	s_waitcnt lgkmcnt(0)
	v_mfma_f32_16x16x32_bf16 v[70:73], v[86:89], v[90:93], v[70:73]
	ds_read_b128 v[86:89], v95 offset:896
	ds_read_b128 v[90:93], v225 offset:128
	s_waitcnt lgkmcnt(0)
	v_mfma_f32_16x16x32_bf16 v[74:77], v[86:89], v[90:93], v[74:77]
	ds_read_b128 v[90:93], v225 offset:400
	s_waitcnt lgkmcnt(0)
	v_mfma_f32_16x16x32_bf16 v[78:81], v[86:89], v[90:93], v[78:81]
	ds_read_b128 v[90:93], v225 offset:672
	s_waitcnt lgkmcnt(0)
	v_mfma_f32_16x16x32_bf16 v[90:93], v[86:89], v[90:93], v[82:85]
	s_nop 2
	ds_read_b128 v[82:85], v225 offset:944
	s_waitcnt lgkmcnt(0)
	v_mfma_f32_16x16x32_bf16 v[70:73], v[86:89], v[82:85], v[70:73]
	ds_read_b128 v[86:89], v95 offset:960
	ds_read_b128 v[82:85], v225 offset:192
	s_waitcnt lgkmcnt(0)
	v_mfma_f32_16x16x32_bf16 v[82:85], v[86:89], v[82:85], v[74:77]
	s_nop 2
	ds_read_b128 v[74:77], v225 offset:464
	s_waitcnt lgkmcnt(0)
	v_mfma_f32_16x16x32_bf16 v[74:77], v[86:89], v[74:77], v[78:81]
	s_nop 2
	ds_read_b128 v[78:81], v225 offset:736
	s_waitcnt lgkmcnt(0)
	v_mfma_f32_16x16x32_bf16 v[78:81], v[86:89], v[78:81], v[90:93]
	s_nop 2
	ds_read_b128 v[90:93], v225 offset:1008
	s_waitcnt lgkmcnt(0)
	v_mfma_f32_16x16x32_bf16 v[70:73], v[86:89], v[90:93], v[70:73]
	v_lshlrev_b32_e32 v233, 4, v102
	v_add_u32_e32 v86, v131, v233
	v_lshlrev_b32_e32 v232, 4, v10
	ds_read_b32 v234, v86
	v_add_u32_e32 v86, v131, v232
	v_lshlrev_b32_e32 v231, 4, v98
	ds_read_b32 v235, v86
	v_add_u32_e32 v86, v131, v231
	v_lshlrev_b32_e32 v230, 4, v12
	ds_read_b32 v236, v86
	v_add_u32_e32 v86, v131, v230
	ds_read_b32 v237, v86
	v_lshl_add_u32 v86, v13, 4, v131
	ds_read_b32 v238, v86
	ds_read_b128 v[86:89], v228 offset:512
	ds_read_b128 v[90:93], v95 offset:768
	s_waitcnt lgkmcnt(0)
	v_mfma_f32_16x16x32_bf16 v[86:89], v[86:89], v[90:93], 0
	ds_read_b128 v[90:93], v228 offset:576
	ds_read_b128 v[240:243], v95 offset:832
	v_cmp_ne_u32_e32 vcc, 0, v94
	s_or_b64 s[50:51], vcc, s[8:9]
	s_waitcnt lgkmcnt(0)
	v_mfma_f32_16x16x32_bf16 v[86:89], v[90:93], v[240:243], v[86:89]
	ds_read_b128 v[90:93], v228 offset:640
	ds_read_b128 v[240:243], v95 offset:896
	s_waitcnt lgkmcnt(0)
	v_mfma_f32_16x16x32_bf16 v[86:89], v[90:93], v[240:243], v[86:89]
	ds_read_b128 v[90:93], v228 offset:704
	ds_read_b128 v[240:243], v95 offset:960
	s_waitcnt lgkmcnt(0)
	v_mfma_f32_16x16x32_bf16 v[86:89], v[90:93], v[240:243], v[86:89]
	v_mov_b32_e32 v90, 0
	v_mov_b32_e32 v91, 0
	s_and_saveexec_b64 s[2:3], s[50:51]
	s_cbranch_execz .LBB0_872
	ds_read_b32 v91, v189
	s_waitcnt lgkmcnt(0)
	v_sub_f32_e32 v91, v238, v91
	v_min_f32_e32 v91, 0, v91
	v_mul_f32_e32 v91, 0x3fb8aa3b, v91
	v_exp_f32_e32 v91, v91
	s_nop 0
	v_mul_f32_e32 v86, v86, v91
	ds_read_b32 v91, v190
	s_waitcnt lgkmcnt(0)
	v_mul_f32_e32 v91, v91, v86

; __device__ __forceinline__ float bf2f(bf16 v) { return __uint_as_float(((unsigned)v) << 16); }
; __device__ __forceinline__ unsigned pk2(float lo, float hi) { unsigned r; asm("v_cvt_pk_bf16_f32 %0, %1, %2" : "=v"(r) : "v"(lo), "v"(hi)); return r; }
; __device__ __forceinline__ bf16 f2bf(float f) { return (bf16)pk2(f, f); }
; __device__ __forceinline__ float siluf_(float x) { return x * frcp_(1.0f + __expf(-x)); }
; #define LAS __attribute__((address_space(3)))
; #define SHFL_XOR(v, M) swz_xor<M>(v)
; __device__ __forceinline__ void ssd_pass2(const RecurBufs& rb, const float* d_skip, const float* ssm_norm, float* state_out_l, int u, int tid, LAS unsigned char* lds) {
;     ...
;             for (int r = 0; r < 4; ++r) { const int i = 16 * it + 4 * g + r; float s = 0.f; float yv[4];
; #pragma unroll
;                 for (int pt = 0; pt < 4; ++pt) { const float xc = bf2f(*(const LAS bf16*)(T + i * PR + (64 * k + 16 * pt + c) * 2)); const float z = bf2f((bf16)(zz[r] >> (16 * pt)));
;                     const bf16 yb = f2bf((ya[pt][r] + Dk * xc) * siluf_(z)); yv[pt] = bf2f(yb); s += yv[pt] * yv[pt]; }
;                 *(unsigned long long*)(rb.y + (row0 + i) * 2048 + chn0) = (unsigned long long)pk2(yv[0], yv[1]) | ((unsigned long long)pk2(yv[2], yv[3]) << 32);
;                 s += SHFL_XOR(s, 1); s += SHFL_XOR(s, 2); s += SHFL_XOR(s, 4); s += SHFL_XOR(s, 8);
;                 if (c == 0) red[i * 4 + k] = s; }
.LBB0_910:
	s_or_b64 exec, exec, s[16:17]
	v_mad_u32_u24 v86, v102, s89, 0
	v_add_u32_e32 v87, v86, v221
	ds_read_u16 v88, v87
	ds_read_u16 v90, v87 offset:32
	s_waitcnt lgkmcnt(0)
	v_lshlrev_b32_e32 v89, 16, v88
	s_waitcnt vmcnt(0)
	v_lshlrev_b32_e32 v88, 16, v126
	v_mul_f32_e32 v91, 0xbfb8aa3b, v88
	v_exp_f32_e32 v91, v91
	s_nop 0
	v_add_f32_e32 v91, 1.0, v91
	v_rcp_f32_e32 v102, v91
	s_nop 0
	v_pk_mul_f32 v[88:89], v[102:103], v[88:89]
	s_nop 0
	v_add_f32_e32 v82, v82, v89
	v_mul_f32_e32 v82, v88, v82
	v_and_b32_e32 v88, 0xffff0000, v126
	v_lshlrev_b32_e32 v89, 16, v90
	v_mul_f32_e32 v90, 0xbfb8aa3b, v88
	v_exp_f32_e32 v90, v90
	v_cvt_pk_bf16_f32 v82, v82, v82
	s_nop 0
	v_lshlrev_b32_e32 v82, 16, v82
	v_add_f32_e32 v90, 1.0, v90
	v_rcp_f32_e32 v102, v90
	s_nop 0
	v_pk_mul_f32 v[88:89], v[102:103], v[88:89]
	s_nop 0
	v_add_f32_e32 v78, v78, v89
	v_mul_f32_e32 v78, v88, v78
	ds_read_u16 v88, v87 offset:64
	ds_read_u16 v87, v87 offset:96
	v_cvt_pk_bf16_f32 v78, v78, v78
	s_waitcnt lgkmcnt(1)
	v_lshlrev_b32_e32 v89, 16, v88
	v_alignbit_b32 v88, v127, v126, 16
	v_and_b32_e32 v88, 0xffff0000, v88
	v_mul_f32_e32 v90, 0xbfb8aa3b, v88
	v_exp_f32_e32 v90, v90
	v_lshlrev_b32_e32 v78, 16, v78
	v_mul_f32_e32 v92, v78, v78
	v_fmac_f32_e32 v92, v82, v82
	v_add_f32_e32 v90, 1.0, v90
	v_rcp_f32_e32 v102, v90
	v_lshlrev_b64 v[90:91], 12, v[124:125]
	v_lshl_add_u64 v[90:91], v[116:117], 0, v[90:91]
	v_pk_mul_f32 v[88:89], v[102:103], v[88:89]
	s_nop 0
	v_add_f32_e32 v74, v74, v89
	v_mul_f32_e32 v74, v88, v74
	v_and_b32_e32 v88, 0xffff0000, v127
	s_waitcnt lgkmcnt(0)
	v_lshlrev_b32_e32 v89, 16, v87
	v_mul_f32_e32 v87, 0xbfb8aa3b, v88
	v_exp_f32_e32 v87, v87
	v_cvt_pk_bf16_f32 v74, v74, v74
	s_nop 0
	v_lshlrev_b32_e32 v74, 16, v74
	v_add_f32_e32 v87, 1.0, v87
	v_rcp_f32_e32 v102, v87
	v_fmac_f32_e32 v92, v74, v74
	v_pk_mul_f32 v[88:89], v[102:103], v[88:89]
	s_nop 0
	v_add_f32_e32 v70, v70, v89
	v_mul_f32_e32 v70, v88, v70
	v_cvt_pk_bf16_f32 v70, v70, v70
	v_cvt_pk_bf16_f32 v88, v82, v78
	s_nop 0
	v_lshlrev_b32_e32 v70, 16, v70
	v_fmac_f32_e32 v92, v70, v70
	v_cvt_pk_bf16_f32 v89, v74, v70
	ds_swizzle_b32 v70, v92 offset:swizzle(SWAP,1)
	global_store_dwordx2 v[90:91], v[88:89], off
	s_waitcnt lgkmcnt(0)
	v_add_f32_e32 v70, v92, v70
	ds_swizzle_b32 v74, v70 offset:swizzle(SWAP,2)
	s_waitcnt lgkmcnt(0)
	v_add_f32_e32 v70, v70, v74
	ds_swizzle_b32 v74, v70 offset:swizzle(SWAP,4)
	s_waitcnt lgkmcnt(0)
	v_add_f32_e32 v70, v70, v74
	ds_swizzle_b32 v74, v70 offset:swizzle(SWAP,8)
	s_and_saveexec_b64 s[16:17], s[6:7]
	s_cbranch_execz .LBB0_912
	v_add_u32_e32 v78, v132, v233
	s_waitcnt lgkmcnt(0)
	v_add_f32_e32 v70, v70, v74
	ds_write_b32 v78, v70
.LBB0_912:
	s_or_b64 exec, exec, s[16:17]
	v_add_u32_e32 v70, 0x410, v86
	s_waitcnt lgkmcnt(0)
	v_add_u32_e32 v74, v70, v221
	ds_read_u16 v78, v74
	ds_read_u16 v88, v74 offset:32
	v_lshlrev_b32_e32 v86, 16, v122
	v_and_b32_e32 v82, 0xffff0000, v122
	s_waitcnt lgkmcnt(0)
	v_lshlrev_b32_e32 v87, 16, v78
	v_mul_f32_e32 v78, 0xbfb8aa3b, v86
	v_exp_f32_e32 v78, v78
	s_nop 0
	v_add_f32_e32 v78, 1.0, v78
	v_rcp_f32_e32 v102, v78
	s_nop 0
	v_pk_mul_f32 v[86:87], v[102:103], v[86:87]
	s_nop 0
	v_add_f32_e32 v78, v83, v87
	v_mul_f32_e32 v78, v86, v78
	v_cvt_pk_bf16_f32 v78, v78, v78
	v_lshlrev_b32_e32 v83, 16, v88
	v_lshlrev_b32_e32 v86, 16, v78
	v_mul_f32_e32 v78, 0xbfb8aa3b, v82
	v_exp_f32_e32 v78, v78
	s_nop 0
	v_add_f32_e32 v78, 1.0, v78
	v_rcp_f32_e32 v102, v78
	s_nop 0
	v_pk_mul_f32 v[82:83], v[102:103], v[82:83]
	s_nop 0
	v_add_f32_e32 v78, v79, v83
	v_mul_f32_e32 v78, v82, v78
	v_cvt_pk_bf16_f32 v78, v78, v78
	s_nop 0
	v_lshlrev_b32_e32 v82, 16, v78
	ds_read_u16 v78, v74 offset:64
	ds_read_u16 v74, v74 offset:96
	v_mul_f32_e32 v83, v82, v82
	v_fmac_f32_e32 v83, v86, v86
	s_waitcnt lgkmcnt(0)
	v_lshlrev_b32_e32 v79, 16, v78
	v_alignbit_b32 v78, v123, v122, 16
	v_and_b32_e32 v78, 0xffff0000, v78
	v_mul_f32_e32 v87, 0xbfb8aa3b, v78
	v_exp_f32_e32 v87, v87
	s_nop 0
	v_add_f32_e32 v87, 1.0, v87
	v_rcp_f32_e32 v102, v87
	s_nop 0
	v_pk_mul_f32 v[78:79], v[102:103], v[78:79]
	s_nop 0
	v_add_f32_e32 v75, v75, v79
	v_mul_f32_e32 v75, v78, v75
	v_cvt_pk_bf16_f32 v75, v75, v75
	s_nop 0
	v_lshlrev_b32_e32 v78, 16, v75
	v_lshlrev_b32_e32 v75, 16, v74
	v_and_b32_e32 v74, 0xffff0000, v123
	v_mul_f32_e32 v79, 0xbfb8aa3b, v74
	v_exp_f32_e32 v79, v79
	v_fmac_f32_e32 v83, v78, v78
	v_add_f32_e32 v79, 1.0, v79
	v_rcp_f32_e32 v102, v79
	s_nop 0
	v_pk_mul_f32 v[74:75], v[102:103], v[74:75]
	s_nop 0
	v_add_f32_e32 v71, v71, v75
	v_mul_f32_e32 v71, v74, v71
	v_cvt_pk_bf16_f32 v71, v71, v71
	v_cvt_pk_bf16_f32 v74, v86, v82
	s_nop 0
	v_lshlrev_b32_e32 v71, 16, v71
	v_fmac_f32_e32 v83, v71, v71
	v_cvt_pk_bf16_f32 v75, v78, v71
	v_lshl_add_u64 v[78:79], s[60:61], 0, v[10:11]
	ds_swizzle_b32 v10, v83 offset:swizzle(SWAP,1)
	v_lshlrev_b64 v[78:79], 12, v[78:79]
	v_lshl_add_u64 v[78:79], v[116:117], 0, v[78:79]
	global_store_dwordx2 v[78:79], v[74:75], off
	s_waitcnt lgkmcnt(0)
	v_add_f32_e32 v10, v83, v10
	ds_swizzle_b32 v71, v10 offset:swizzle(SWAP,2)
	s_waitcnt lgkmcnt(0)
	v_add_f32_e32 v10, v10, v71
	ds_swizzle_b32 v71, v10 offset:swizzle(SWAP,4)
	s_waitcnt lgkmcnt(0)
	v_add_f32_e32 v10, v10, v71
	ds_swizzle_b32 v71, v10 offset:swizzle(SWAP,8)
	s_and_saveexec_b64 s[16:17], s[6:7]
	s_cbranch_execz .LBB0_914
	v_add_u32_e32 v74, v132, v232
	s_waitcnt lgkmcnt(0)
	v_add_f32_e32 v10, v10, v71
	ds_write_b32 v74, v10
; __device__ __forceinline__ float bf2f(bf16 v) { return __uint_as_float(((unsigned)v) << 16); }
; __device__ __forceinline__ unsigned pk2(float lo, float hi) { unsigned r; asm("v_cvt_pk_bf16_f32 %0, %1, %2" : "=v"(r) : "v"(lo), "v"(hi)); return r; }
; __device__ __forceinline__ bf16 f2bf(float f) { return (bf16)pk2(f, f); }
; __device__ __forceinline__ float siluf_(float x) { return x * frcp_(1.0f + __expf(-x)); }
; #define LAS __attribute__((address_space(3)))
; #define SHFL_XOR(v, M) swz_xor<M>(v)
; __device__ __forceinline__ void ssd_pass2(const RecurBufs& rb, const float* d_skip, const float* ssm_norm, float* state_out_l, int u, int tid, LAS unsigned char* lds) {
;     ...
;             for (int r = 0; r < 4; ++r) { const int i = 16 * it + 4 * g + r; float s = 0.f; float yv[4];
; #pragma unroll
;                 for (int pt = 0; pt < 4; ++pt) { const float xc = bf2f(*(const LAS bf16*)(T + i * PR + (64 * k + 16 * pt + c) * 2)); const float z = bf2f((bf16)(zz[r] >> (16 * pt)));
;                     const bf16 yb = f2bf((ya[pt][r] + Dk * xc) * siluf_(z)); yv[pt] = bf2f(yb); s += yv[pt] * yv[pt]; }
;                 *(unsigned long long*)(rb.y + (row0 + i) * 2048 + chn0) = (unsigned long long)pk2(yv[0], yv[1]) | ((unsigned long long)pk2(yv[2], yv[3]) << 32);
;                 s += SHFL_XOR(s, 1); s += SHFL_XOR(s, 2); s += SHFL_XOR(s, 4); s += SHFL_XOR(s, 8);
;                 if (c == 0) red[i * 4 + k] = s; }
.LBB0_914:
	s_or_b64 exec, exec, s[16:17]
	v_add_u32_e32 v10, 0x410, v70
	v_lshlrev_b32_e32 v70, 16, v100
	v_mul_f32_e32 v75, 0xbfb8aa3b, v70
	v_exp_f32_e32 v75, v75
	v_add_u32_e32 v10, v10, v221
	s_waitcnt lgkmcnt(0)
	ds_read_u16 v71, v10
	ds_read_u16 v74, v10 offset:32
	v_add_f32_e32 v75, 1.0, v75
	v_rcp_f32_e32 v102, v75
	s_waitcnt lgkmcnt(0)
	v_lshlrev_b32_e32 v71, 16, v71
	v_pk_mul_f32 v[70:71], v[102:103], v[70:71]
	s_nop 0
	v_add_f32_e32 v71, v84, v71
	v_mul_f32_e32 v70, v70, v71
	v_cvt_pk_bf16_f32 v70, v70, v70
	v_lshlrev_b32_e32 v71, 16, v74
	v_lshlrev_b32_e32 v75, 16, v70
	v_and_b32_e32 v70, 0xffff0000, v100
	v_mul_f32_e32 v74, 0xbfb8aa3b, v70
	v_exp_f32_e32 v74, v74
	s_nop 0
	v_add_f32_e32 v74, 1.0, v74
	v_rcp_f32_e32 v102, v74
	s_nop 0
	v_pk_mul_f32 v[70:71], v[102:103], v[70:71]
	s_nop 0
	v_add_f32_e32 v71, v80, v71
	v_mul_f32_e32 v70, v70, v71
	v_cvt_pk_bf16_f32 v70, v70, v70
	s_nop 0
	v_lshlrev_b32_e32 v74, 16, v70
	ds_read_u16 v70, v10 offset:64
	v_mul_f32_e32 v78, v74, v74
	v_fmac_f32_e32 v78, v75, v75
	s_waitcnt lgkmcnt(0)
	v_lshlrev_b32_e32 v71, 16, v70
	v_alignbit_b32 v70, v101, v100, 16
	v_and_b32_e32 v70, 0xffff0000, v70
	v_mul_f32_e32 v79, 0xbfb8aa3b, v70
	v_exp_f32_e32 v79, v79
	s_nop 0
	v_add_f32_e32 v79, 1.0, v79
	v_rcp_f32_e32 v102, v79
	s_nop 0
	v_pk_mul_f32 v[70:71], v[102:103], v[70:71]
	s_nop 0
	v_add_f32_e32 v71, v76, v71
	v_mul_f32_e32 v70, v70, v71
	v_cvt_pk_bf16_f32 v70, v70, v70
	s_nop 0
	v_lshlrev_b32_e32 v76, 16, v70
	ds_read_u16 v70, v10 offset:96
	v_fmac_f32_e32 v78, v76, v76
	s_waitcnt lgkmcnt(0)
	v_lshlrev_b32_e32 v71, 16, v70
	v_and_b32_e32 v70, 0xffff0000, v101
	v_mul_f32_e32 v79, 0xbfb8aa3b, v70
	v_exp_f32_e32 v79, v79
	s_nop 0
	v_add_f32_e32 v79, 1.0, v79
	v_rcp_f32_e32 v102, v79
	s_nop 0
	v_pk_mul_f32 v[70:71], v[102:103], v[70:71]
	s_nop 0
	v_add_f32_e32 v71, v72, v71
	v_mul_f32_e32 v70, v70, v71
	v_cvt_pk_bf16_f32 v70, v70, v70
	s_nop 0
	v_lshlrev_b32_e32 v71, 16, v70
	v_cvt_pk_bf16_f32 v70, v75, v74
	v_lshl_add_u64 v[74:75], s[60:61], 0, v[98:99]
	v_lshlrev_b64 v[74:75], 12, v[74:75]
	v_fmac_f32_e32 v78, v71, v71
	v_lshl_add_u64 v[74:75], v[116:117], 0, v[74:75]
	v_cvt_pk_bf16_f32 v71, v76, v71
	global_store_dwordx2 v[74:75], v[70:71], off
	ds_swizzle_b32 v70, v78 offset:swizzle(SWAP,1)
	s_waitcnt lgkmcnt(0)
	v_add_f32_e32 v70, v78, v70
	ds_swizzle_b32 v71, v70 offset:swizzle(SWAP,2)
	s_waitcnt lgkmcnt(0)
	v_add_f32_e32 v70, v70, v71
	ds_swizzle_b32 v71, v70 offset:swizzle(SWAP,4)
	s_waitcnt lgkmcnt(0)
	v_add_f32_e32 v70, v70, v71
	ds_swizzle_b32 v71, v70 offset:swizzle(SWAP,8)
	s_and_saveexec_b64 s[16:17], s[6:7]
	s_cbranch_execz .LBB0_916
	v_add_u32_e32 v72, v132, v231
	s_waitcnt lgkmcnt(0)
	v_add_f32_e32 v70, v70, v71
	ds_write_b32 v72, v70
.LBB0_916:
	s_or_b64 exec, exec, s[16:17]
	v_lshlrev_b32_e32 v70, 16, v96
	v_mul_f32_e32 v74, 0xbfb8aa3b, v70
	v_exp_f32_e32 v74, v74
	s_waitcnt lgkmcnt(0)
	ds_read_u16 v71, v10 offset:1040
	ds_read_u16 v72, v10 offset:1072
	v_lshl_add_u64 v[12:13], s[60:61], 0, v[12:13]
	v_lshlrev_b64 v[12:13], 12, v[12:13]
	v_add_f32_e32 v74, 1.0, v74
	v_rcp_f32_e32 v102, v74
	s_waitcnt lgkmcnt(0)
	v_lshlrev_b32_e32 v71, 16, v71
	v_lshl_add_u64 v[12:13], v[116:117], 0, v[12:13]
	v_pk_mul_f32 v[70:71], v[102:103], v[70:71]
	s_nop 0
	v_add_f32_e32 v71, v85, v71
	v_mul_f32_e32 v70, v70, v71
	v_cvt_pk_bf16_f32 v70, v70, v70
	v_lshlrev_b32_e32 v71, 16, v72
	v_lshlrev_b32_e32 v74, 16, v70
	v_and_b32_e32 v70, 0xffff0000, v96
	v_mul_f32_e32 v72, 0xbfb8aa3b, v70
	v_exp_f32_e32 v72, v72
	s_nop 0
	v_add_f32_e32 v72, 1.0, v72
	v_rcp_f32_e32 v102, v72
	s_nop 0
	v_pk_mul_f32 v[70:71], v[102:103], v[70:71]
	s_nop 0
	v_add_f32_e32 v71, v81, v71
	v_mul_f32_e32 v70, v70, v71
	v_cvt_pk_bf16_f32 v70, v70, v70
	s_nop 0
	v_lshlrev_b32_e32 v72, 16, v70
	ds_read_u16 v70, v10 offset:1104
	ds_read_u16 v10, v10 offset:1136
	v_mul_f32_e32 v75, v72, v72
	v_fmac_f32_e32 v75, v74, v74
	s_waitcnt lgkmcnt(0)
	v_lshlrev_b32_e32 v71, 16, v70
	v_alignbit_b32 v70, v97, v96, 16
	v_and_b32_e32 v70, 0xffff0000, v70
	v_mul_f32_e32 v76, 0xbfb8aa3b, v70
	v_exp_f32_e32 v76, v76
	s_nop 0
	v_add_f32_e32 v76, 1.0, v76
	v_rcp_f32_e32 v102, v76
	s_nop 0
	v_pk_mul_f32 v[70:71], v[102:103], v[70:71]
	s_nop 0
	v_add_f32_e32 v71, v77, v71
	v_mul_f32_e32 v70, v70, v71
	v_cvt_pk_bf16_f32 v70, v70, v70
	v_lshlrev_b32_e32 v71, 16, v10
	v_lshlrev_b32_e32 v76, 16, v70
	v_and_b32_e32 v70, 0xffff0000, v97
	v_mul_f32_e32 v10, 0xbfb8aa3b, v70
	v_exp_f32_e32 v10, v10
	v_fmac_f32_e32 v75, v76, v76
	v_add_f32_e32 v10, 1.0, v10
	v_rcp_f32_e32 v102, v10
	s_nop 0
	v_pk_mul_f32 v[70:71], v[102:103], v[70:71]
	s_nop 0
	v_add_f32_e32 v10, v73, v71
	v_mul_f32_e32 v10, v70, v10
	v_cvt_pk_bf16_f32 v10, v10, v10
	v_cvt_pk_bf16_f32 v70, v74, v72
	s_nop 0
	v_lshlrev_b32_e32 v10, 16, v10
	v_fmac_f32_e32 v75, v10, v10
	v_cvt_pk_bf16_f32 v71, v76, v10
	ds_swizzle_b32 v10, v75 offset:swizzle(SWAP,1)
	global_store_dwordx2 v[12:13], v[70:71], off
	s_waitcnt lgkmcnt(0)
	v_add_f32_e32 v10, v75, v10
	ds_swizzle_b32 v12, v10 offset:swizzle(SWAP,2)
	s_waitcnt lgkmcnt(0)
	v_add_f32_e32 v10, v10, v12
	ds_swizzle_b32 v12, v10 offset:swizzle(SWAP,4)
	s_waitcnt lgkmcnt(0)
	v_add_f32_e32 v10, v10, v12
	ds_swizzle_b32 v12, v10 offset:swizzle(SWAP,8)
	s_and_saveexec_b64 s[16:17], s[6:7]
	s_cbranch_execz .LBB0_869
	v_add_u32_e32 v13, v132, v230
	s_waitcnt lgkmcnt(0)
	v_add_f32_e32 v10, v10, v12
	ds_write_b32 v13, v10
	s_branch .LBB0_869

; __device__ __forceinline__ unsigned xb_ld(unsigned* p)              { return __hip_atomic_load(p, __ATOMIC_RELAXED, __HIP_MEMORY_SCOPE_AGENT); }
; __device__ __forceinline__ void xcd_barrier_complete(unsigned* bar, unsigned x, unsigned& nloc, unsigned& nx) {
;     const unsigned G = gridDim.x * gridDim.y * gridDim.z;
;     unsigned sum, cnt, mine, sp = 0u;
;     for (;;) {
;         sum = 0u; cnt = 0u; mine = 0u;
; #pragma unroll
;         for (unsigned j = 0; j < 16; ++j) { const unsigned c = xb_ld(&bar[XB_XCNT(j)]); sum += c; cnt += (c > 0u) ? 1u : 0u; mine = (j == x) ? c : mine; }
;         if (sum == G) break;
;         __builtin_amdgcn_s_sleep(1);
;         if ((++sp & 255u) == 0u) { if (xb_ld(&bar[XB_TMO])) break; if (sp > XB_SPIN_CAP) { atomicAdd(&bar[XB_TMO], 1u); break; } }
;     }
.LBB0_924:
	v_mov_b64_e32 v[12:13], s[2:3]
	global_load_dword v1, v[12:13], off offset:1024 sc1
	global_load_dword v0, v[12:13], off offset:1280 sc1
	global_load_dword v2, v[12:13], off offset:1536 sc1
	s_or_b64 s[18:19], s[18:19], exec
	s_or_b64 s[16:17], s[16:17], exec
	s_waitcnt vmcnt(0) lgkmcnt(0)
	v_add_u32_e32 v3, v0, v1
	v_add_u32_e32 v4, v3, v2
	global_load_dword v3, v[12:13], off offset:1792 sc1
	s_waitcnt vmcnt(0) lgkmcnt(0)
	v_add_u32_e32 v5, v4, v3
	global_load_dword v4, v[12:13], off offset:2048 sc1
	s_waitcnt vmcnt(0) lgkmcnt(0)
	v_add_u32_e32 v6, v5, v4
	global_load_dword v5, v[12:13], off offset:2304 sc1
	s_waitcnt vmcnt(0) lgkmcnt(0)
	v_add_u32_e32 v7, v6, v5
	global_load_dword v6, v[12:13], off offset:2560 sc1
	s_waitcnt vmcnt(0) lgkmcnt(0)
	v_add_u32_e32 v8, v7, v6
	global_load_dword v7, v[12:13], off offset:2816 sc1
	s_waitcnt vmcnt(0) lgkmcnt(0)
	v_add_u32_e32 v9, v8, v7
	global_load_dword v8, v[12:13], off offset:3072 sc1
	s_waitcnt vmcnt(0) lgkmcnt(0)
	v_add_u32_e32 v10, v9, v8
	global_load_dword v9, v[12:13], off offset:3328 sc1
	s_waitcnt vmcnt(0) lgkmcnt(0)
	v_add_u32_e32 v14, v10, v9
	global_load_dword v10, v[12:13], off offset:3584 sc1
	s_waitcnt vmcnt(0) lgkmcnt(0)
	v_add_u32_e32 v14, v14, v10
	global_load_dword v12, v[12:13], off offset:3840 sc1
	s_waitcnt vmcnt(0) lgkmcnt(0)
	v_add_u32_e32 v16, v14, v12
	v_mov_b64_e32 v[14:15], s[4:5]
	global_load_dword v13, v[14:15], off sc1
	v_mov_b64_e32 v[14:15], s[6:7]
	global_load_dword v14, v[14:15], off sc1
	s_waitcnt vmcnt(0) lgkmcnt(0)
	v_add_u32_e32 v16, v16, v13
	v_add_u32_e32 v18, v16, v14
	v_mov_b64_e32 v[16:17], s[8:9]
	global_load_dword v15, v[16:17], off sc1
	v_mov_b64_e32 v[16:17], s[10:11]
	global_load_dword v16, v[16:17], off sc1
	s_waitcnt vmcnt(0) lgkmcnt(0)
	v_add_u32_e32 v18, v18, v15
	v_add_u32_e32 v17, v18, v16
	v_cmp_ne_u32_e32 vcc, s30, v17
	s_and_saveexec_b64 s[20:21], vcc
	s_cbranch_execz .LBB0_923
	s_and_b32 s24, s31, 0xff
	s_mov_b64 s[22:23], -1
	s_cmp_eq_u32 s24, 0
	s_mov_b64 s[26:27], -1
	s_mov_b64 s[24:25], -1
	s_sleep 1
	s_cbranch_scc1 .LBB0_927
	s_and_saveexec_b64 s[28:29], s[26:27]
	s_cbranch_execz .LBB0_922
	s_branch .LBB0_930
.LBB0_927:
	v_mov_b64_e32 v[18:19], s[2:3]
	global_load_dword v17, v[18:19], off offset:512 sc1
	s_mov_b64 s[26:27], 0
	s_waitcnt vmcnt(0) lgkmcnt(0)
	v_cmp_eq_u32_e32 vcc, 0, v17
	s_and_saveexec_b64 s[28:29], vcc
	s_cmp_lt_u32 s31, 0x40001
	s_cselect_b64 s[26:27], -1, 0
	s_xor_b64 s[24:25], exec, -1
	s_and_b64 s[26:27], s[26:27], exec
	s_or_b64 exec, exec, s[28:29]
	s_and_saveexec_b64 s[28:29], s[26:27]
	s_cbranch_execz .LBB0_922

; __device__ __forceinline__ unsigned xb_ld(unsigned* p)              { return __hip_atomic_load(p, __ATOMIC_RELAXED, __HIP_MEMORY_SCOPE_AGENT); }
; __device__ __forceinline__ unsigned xb_add(unsigned* p, unsigned v) { return __hip_atomic_fetch_add(p, v, __ATOMIC_RELAXED, __HIP_MEMORY_SCOPE_AGENT); }
; #define XB_SPIN(cond, bar) do { unsigned _sp = 0; while (cond) { __builtin_amdgcn_s_sleep(1); \
;     if ((++_sp & 255u) == 0u) { if (xb_ld(&(bar)[XB_TMO])) break; if (_sp > XB_SPIN_CAP) { atomicAdd(&(bar)[XB_TMO], 1u); break; } } } } while (0)
; __device__ __forceinline__ void xcd_barrier(const XcdBarrier& b, int tid) {
;     ...
;         unsigned nloc = b.st[0], nx = b.st[1];
;         if (nloc == 0u) { xcd_barrier_complete(bar, bx_, nloc, nx); b.st[0] = nloc; b.st[1] = nx; }
;         const unsigned old = xb_add(&bar[XB_XSUB(bx_)], 1u);
;         const unsigned gen = old / nloc;
;         if (old + 1u == (gen + 1u) * nloc) {
;             __builtin_amdgcn_fence(__ATOMIC_RELEASE, "agent");
;             asm volatile("s_waitcnt vmcnt(0)" ::: "memory");
;             const unsigned og = xb_add(&bar[XB_TOP], 1u);
;             const unsigned tg = og / nx;
;             if (og + 1u == (tg + 1u) * nx) xb_add(&bar[XB_TOPGEN], 1u);
;             else XB_SPIN(xb_ld(&bar[XB_TOPGEN]) == tg, bar);
;             __builtin_amdgcn_fence(__ATOMIC_ACQUIRE, "agent");
;             xb_add(&bar[XB_XGEN(bx_)], 1u);
;             asm volatile("s_waitcnt vmcnt(0)" ::: "memory");
;         } else {
;             XB_SPIN(xb_ld(&bar[XB_XGEN(bx_)]) == gen, bar);
.LBB0_934:
	s_lshl_b32 s26, s36, 6
	s_add_i32 s64, s26, 0x500
	s_lshl_b64 s[4:5], s[64:65], 2
	s_add_u32 s4, s2, s4
	s_addc_u32 s5, s3, s5
	v_mov_b64_e32 v[4:5], s[4:5]
	v_mov_b32_e32 v1, 1
	flat_atomic_add v3, v[4:5], v1 sc0
	v_cvt_f32_u32_e32 v1, v2
	v_sub_u32_e32 v4, 0, v2
	v_rcp_iflag_f32_e32 v1, v1
	s_nop 0
	v_mul_f32_e32 v1, 0x4f7ffffe, v1
	v_cvt_u32_f32_e32 v1, v1
	v_mul_lo_u32 v4, v4, v1
	v_mul_hi_u32 v4, v1, v4
	v_add_u32_e32 v1, v1, v4
	s_waitcnt vmcnt(0) lgkmcnt(0)
	v_mul_hi_u32 v1, v3, v1
	v_mul_lo_u32 v4, v1, v2
	v_sub_u32_e32 v4, v3, v4
	v_cmp_ge_u32_e32 vcc, v4, v2
	v_add_u32_e32 v5, 1, v1
	s_nop 0
	v_cndmask_b32_e32 v1, v1, v5, vcc
	v_sub_u32_e32 v5, v4, v2
	v_cndmask_b32_e32 v4, v4, v5, vcc
	v_cmp_ge_u32_e32 vcc, v4, v2
	v_add_u32_e32 v4, 1, v1
	s_nop 0
	v_cndmask_b32_e32 v1, v1, v4, vcc
	v_add_u32_e32 v4, 1, v3
	v_mad_u64_u32 v[2:3], s[4:5], v2, v1, v[2:3]
	v_cmp_ne_u32_e32 vcc, v4, v2
	s_and_saveexec_b64 s[4:5], vcc
	s_xor_b64 s[4:5], exec, s[4:5]
	s_cbranch_execz .LBB0_947
	s_add_i32 s64, s26, 0x900
	s_lshl_b64 s[6:7], s[64:65], 2
	s_add_u32 s8, s2, s6
	s_addc_u32 s9, s3, s7
	v_mov_b64_e32 v[2:3], s[8:9]
	global_load_dword v0, v[2:3], off sc1
	s_waitcnt vmcnt(0) lgkmcnt(0)
	v_cmp_eq_u32_e32 vcc, v0, v1
	s_and_saveexec_b64 s[6:7], vcc
	s_cbranch_execz .LBB0_946
	s_mov_b32 s24, 1
	s_mov_b64 s[10:11], 0
	s_branch .LBB0_938

; __device__ __forceinline__ unsigned xb_ld(unsigned* p)              { return __hip_atomic_load(p, __ATOMIC_RELAXED, __HIP_MEMORY_SCOPE_AGENT); }
; #define XB_SPIN(cond, bar) do { unsigned _sp = 0; while (cond) { __builtin_amdgcn_s_sleep(1); \
;     if ((++_sp & 255u) == 0u) { if (xb_ld(&(bar)[XB_TMO])) break; if (_sp > XB_SPIN_CAP) { atomicAdd(&(bar)[XB_TMO], 1u); break; } } } } while (0)
; __device__ __forceinline__ void xcd_barrier(const XcdBarrier& b, int tid) {
;     ...
;             XB_SPIN(xb_ld(&bar[XB_XGEN(bx_)]) == gen, bar);
.LBB0_938:
	s_and_b32 s18, s24, 0xff
	s_mov_b64 s[16:17], -1
	s_cmp_lg_u32 s18, 0
	s_mov_b64 s[18:19], -1
	s_sleep 1
	s_cbranch_scc1 .LBB0_942
	v_mov_b64_e32 v[2:3], s[2:3]
	global_load_dword v0, v[2:3], off offset:512 sc1
	s_mov_b64 s[18:19], 0
	s_mov_b64 s[20:21], -1
	s_waitcnt vmcnt(0) lgkmcnt(0)
	v_cmp_eq_u32_e32 vcc, 0, v0
	s_and_saveexec_b64 s[22:23], vcc
	s_cmp_lt_u32 s24, 0x40001
	s_cselect_b64 s[18:19], -1, 0
	s_xor_b64 s[20:21], exec, -1
	s_and_b64 s[18:19], s[18:19], exec
	s_or_b64 exec, exec, s[22:23]
.LBB0_942:
	s_andn2_b64 s[14:15], s[14:15], exec
	s_and_b64 s[20:21], s[20:21], exec
	s_or_b64 s[14:15], s[14:15], s[20:21]
	s_and_saveexec_b64 s[20:21], s[18:19]
	s_cbranch_execz .LBB0_937
	v_mov_b64_e32 v[2:3], s[8:9]
	global_load_dword v0, v[2:3], off sc1
	s_add_i32 s24, s24, 1
	s_or_b64 s[14:15], s[14:15], exec
	s_waitcnt vmcnt(0) lgkmcnt(0)
	v_cmp_ne_u32_e32 vcc, v0, v1
	s_orn2_b64 s[16:17], vcc, exec
	s_branch .LBB0_937

; __device__ __forceinline__ unsigned xb_ld(unsigned* p)              { return __hip_atomic_load(p, __ATOMIC_RELAXED, __HIP_MEMORY_SCOPE_AGENT); }
; __device__ __forceinline__ unsigned xb_add(unsigned* p, unsigned v) { return __hip_atomic_fetch_add(p, v, __ATOMIC_RELAXED, __HIP_MEMORY_SCOPE_AGENT); }
; #define XB_SPIN(cond, bar) do { unsigned _sp = 0; while (cond) { __builtin_amdgcn_s_sleep(1); \
;     if ((++_sp & 255u) == 0u) { if (xb_ld(&(bar)[XB_TMO])) break; if (_sp > XB_SPIN_CAP) { atomicAdd(&(bar)[XB_TMO], 1u); break; } } } } while (0)
; __device__ __forceinline__ void xcd_barrier(const XcdBarrier& b, int tid) {
;     ...
;         if (old + 1u == (gen + 1u) * nloc) {
;             __builtin_amdgcn_fence(__ATOMIC_RELEASE, "agent");
;             asm volatile("s_waitcnt vmcnt(0)" ::: "memory");
;             const unsigned og = xb_add(&bar[XB_TOP], 1u);
;             const unsigned tg = og / nx;
;             if (og + 1u == (tg + 1u) * nx) xb_add(&bar[XB_TOPGEN], 1u);
;             else XB_SPIN(xb_ld(&bar[XB_TOPGEN]) == tg, bar);
.LBB0_947:
	s_andn2_saveexec_b64 s[4:5], s[4:5]
	s_cbranch_execz .LBB0_963
	v_mov_b32_e32 v1, s2
	v_add_co_u32_e32 v2, vcc, 0x3000, v1
	v_mov_b32_e32 v1, s3
	buffer_wbl2 sc1
	s_waitcnt vmcnt(0)
	v_addc_co_u32_e32 v3, vcc, 0, v1, vcc
	v_mov_b32_e32 v1, 1
	flat_atomic_add v1, v[2:3], v1 offset:1024 sc0
	v_cvt_f32_u32_e32 v2, v0
	v_sub_u32_e32 v3, 0, v0
	s_mov_b64 s[10:11], -1
	v_rcp_iflag_f32_e32 v2, v2
	s_nop 0
	v_mul_f32_e32 v2, 0x4f7ffffe, v2
	v_cvt_u32_f32_e32 v2, v2
	v_mul_lo_u32 v3, v3, v2
	v_mul_hi_u32 v3, v2, v3
	v_add_u32_e32 v2, v2, v3
	s_waitcnt vmcnt(0) lgkmcnt(0)
	v_mul_hi_u32 v2, v1, v2
	v_mul_lo_u32 v3, v2, v0
	v_sub_u32_e32 v3, v1, v3
	v_cmp_ge_u32_e32 vcc, v3, v0
	v_add_u32_e32 v4, 1, v2
	s_nop 0
	v_cndmask_b32_e32 v2, v2, v4, vcc
	v_sub_u32_e32 v4, v3, v0
	v_cndmask_b32_e32 v3, v3, v4, vcc
	v_cmp_ge_u32_e32 vcc, v3, v0
	v_add_u32_e32 v3, 1, v2
	s_nop 0
	v_cndmask_b32_e32 v2, v2, v3, vcc
	v_add_u32_e32 v3, 1, v1
	v_mad_u64_u32 v[0:1], s[6:7], v0, v2, v[0:1]
	s_add_u32 s6, s2, 0x3500
	s_addc_u32 s7, s3, 0
	v_cmp_ne_u32_e32 vcc, v3, v0
	v_mov_b64_e32 v[0:1], s[6:7]
	s_and_saveexec_b64 s[8:9], vcc
	s_cbranch_execz .LBB0_960
	v_mov_b64_e32 v[0:1], s[6:7]
	global_load_dword v0, v[0:1], off sc1
	s_mov_b64 s[14:15], 0
	s_waitcnt vmcnt(0) lgkmcnt(0)
	v_cmp_eq_u32_e32 vcc, v0, v2
	s_and_saveexec_b64 s[12:13], vcc
	s_cbranch_execz .LBB0_959
	s_add_u32 s10, s2, 0x200
	s_addc_u32 s11, s3, 0
	s_mov_b32 s27, 1
	s_branch .LBB0_952

; __device__ __forceinline__ unsigned xb_ld(unsigned* p)              { return __hip_atomic_load(p, __ATOMIC_RELAXED, __HIP_MEMORY_SCOPE_AGENT); }
; #define XB_SPIN(cond, bar) do { unsigned _sp = 0; while (cond) { __builtin_amdgcn_s_sleep(1); \
;     if ((++_sp & 255u) == 0u) { if (xb_ld(&(bar)[XB_TMO])) break; if (_sp > XB_SPIN_CAP) { atomicAdd(&(bar)[XB_TMO], 1u); break; } } } } while (0)
; __device__ __forceinline__ void xcd_barrier(const XcdBarrier& b, int tid) {
;     ...
;             else XB_SPIN(xb_ld(&bar[XB_TOPGEN]) == tg, bar);
.LBB0_954:
	v_mov_b64_e32 v[0:1], s[10:11]
	global_load_dword v0, v[0:1], off sc1
	s_mov_b64 s[22:23], 0
	s_mov_b64 s[20:21], -1
	s_waitcnt vmcnt(0) lgkmcnt(0)
	v_cmp_eq_u32_e32 vcc, 0, v0
	s_and_saveexec_b64 s[24:25], vcc
	s_cmp_lt_u32 s27, 0x40001
	s_cselect_b64 s[22:23], -1, 0
	s_xor_b64 s[20:21], exec, -1
	s_and_b64 s[22:23], s[22:23], exec
	s_or_b64 exec, exec, s[24:25]
	s_and_saveexec_b64 s[24:25], s[22:23]
	s_cbranch_execz .LBB0_951
.LBB0_957:
	v_mov_b64_e32 v[0:1], s[6:7]
	global_load_dword v0, v[0:1], off sc1
	s_add_i32 s27, s27, 1
	s_or_b64 s[20:21], s[20:21], exec
	s_waitcnt vmcnt(0) lgkmcnt(0)
	v_cmp_ne_u32_e32 vcc, v0, v2
	s_orn2_b64 s[18:19], vcc, exec
	s_branch .LBB0_951

; #define LAS __attribute__((address_space(3)))
; __device__ __forceinline__ f32x4 mfma16(bf16x8 a, bf16x8 b, f32x4 c) { return __builtin_amdgcn_mfma_f32_16x16x32_bf16(a, b, c, 0, 0, 0); }
; __device__ __forceinline__ void sync_threads() { __syncthreads(); }
; template <int RT, class Epi>
; __device__ __forceinline__ void skinny_gemm(const bf16* A, size_t lda, const bf16* Bt, int K, int N, const Epi& epi, int wg, int wg_first, int wg_count, int tid, LAS unsigned char* lds) {
;     ...
;     for (int s = me; s < nunit; s += wg_count) {
;         const int n0 = 32 * (s / NRG), r0 = (s % NRG) * (16 * RT);
;         f32x4 acc[RT][2];
; #pragma unroll
;         for (int rt = 0; rt < RT; ++rt) { acc[rt][0] = (f32x4){0.f, 0.f, 0.f, 0.f}; acc[rt][1] = (f32x4){0.f, 0.f, 0.f, 0.f}; }
;         const bf16* ap = A + (size_t)(r0 + c) * lda + (size_t)w * (K / 8) + 8 * g;
;         const bf16* bp = Bt + (size_t)(n0 + c) * K + (size_t)w * (K / 8) + 8 * g;
; #pragma unroll 4
;         for (int ks = 0; ks < ksteps; ++ks) {
;             bf16x8 af[RT], bfr[2];
; #pragma unroll
;             for (int rt = 0; rt < RT; ++rt) af[rt] = *(const bf16x8*)(ap + (size_t)(16 * rt) * lda + 32 * ks);
;             bfr[0] = *(const bf16x8*)(bp + 32 * ks); bfr[1] = *(const bf16x8*)(bp + (size_t)16 * K + 32 * ks);
; #pragma unroll
;             for (int rt = 0; rt < RT; ++rt) { acc[rt][0] = mfma16(af[rt], bfr[0], acc[rt][0]); acc[rt][1] = mfma16(af[rt], bfr[1], acc[rt][1]); }
;         }
;         LAS float* part = (LAS float*)(lds + w * SK_PART);
; #pragma unroll
;         for (int rt = 0; rt < RT; ++rt)
; #pragma unroll
;             for (int nt = 0; nt < 2; ++nt)
; #pragma unroll
;                 for (int r = 0; r < 4; ++r) part[(16 * rt + 4 * g + r) * 32 + 16 * nt + c] = acc[rt][nt][r];
;         sync_threads();
;         if (RT == 8 || tid < 64 * RT) {
;             const int row = tid >> 2, c8 = (tid & 3) * 8;
;             f32x4 v0 = (f32x4){0.f, 0.f, 0.f, 0.f}, v1 = (f32x4){0.f, 0.f, 0.f, 0.f};
; #pragma unroll
;             for (int ww = 0; ww < 8; ++ww) { const LAS float* pp = (const LAS float*)(lds + ww * SK_PART) + row * 32 + c8; v0 = v0 + *(const LAS f32x4*)pp; v1 = v1 + *(const LAS f32x4*)(pp + 4); }
;             epi(r0 + row, n0 + c8, v0, v1);
.LBB0_987:
	s_and_b32 s16, s13, 0x70
	v_or_b32_e32 v0, s16, v26
	s_and_b32 s15, s12, 0x7fffffe0
	v_lshlrev_b32_e32 v10, 11, v0
	v_lshl_add_u64 v[40:41], v[8:9], 0, v[10:11]
	v_or_b32_e32 v10, s15, v26
	v_lshlrev_b64 v[0:1], 11, v[10:11]
	v_lshl_add_u64 v[42:43], v[12:13], 0, v[0:1]
	v_add_co_u32_e32 v44, vcc, 0x8000, v42
	global_load_dwordx4 v[0:3], v[40:41], off
	global_load_dwordx4 v[4:7], v[42:43], off
	v_addc_co_u32_e32 v45, vcc, 0, v43, vcc
	global_load_dwordx4 v[14:17], v[44:45], off
	s_waitcnt vmcnt(0) lgkmcnt(0)
	v_mfma_f32_16x16x32_bf16 v[4:7], v[0:3], v[4:7], 0
	v_mfma_f32_16x16x32_bf16 v[0:3], v[0:3], v[14:17], 0
	global_load_dwordx4 v[14:17], v[40:41], off offset:64
	global_load_dwordx4 v[18:21], v[42:43], off offset:64
	global_load_dwordx4 v[22:25], v[44:45], off offset:64
	s_waitcnt vmcnt(0) lgkmcnt(0)
	v_mfma_f32_16x16x32_bf16 v[4:7], v[14:17], v[18:21], v[4:7]
	v_mfma_f32_16x16x32_bf16 v[0:3], v[14:17], v[22:25], v[0:3]
	global_load_dwordx4 v[14:17], v[40:41], off offset:128
	global_load_dwordx4 v[18:21], v[42:43], off offset:128
	global_load_dwordx4 v[22:25], v[44:45], off offset:128
	s_waitcnt vmcnt(0) lgkmcnt(0)
	v_mfma_f32_16x16x32_bf16 v[4:7], v[14:17], v[18:21], v[4:7]
	v_mfma_f32_16x16x32_bf16 v[0:3], v[14:17], v[22:25], v[0:3]
	global_load_dwordx4 v[14:17], v[40:41], off offset:192
	global_load_dwordx4 v[18:21], v[42:43], off offset:192
	global_load_dwordx4 v[22:25], v[44:45], off offset:192
	s_waitcnt vmcnt(0) lgkmcnt(0)
	v_mfma_f32_16x16x32_bf16 v[4:7], v[14:17], v[18:21], v[4:7]
	v_mfma_f32_16x16x32_bf16 v[0:3], v[14:17], v[22:25], v[0:3]
	s_nop 7
	ds_write2_b32 v38, v4, v0 offset1:16
	ds_write2_b32 v38, v5, v1 offset0:32 offset1:48
	ds_write2_b32 v38, v6, v2 offset0:64 offset1:80
	ds_write2_b32 v38, v7, v3 offset0:96 offset1:112
	s_waitcnt lgkmcnt(0)
	s_barrier
	s_and_saveexec_b64 s[2:3], s[6:7]
	s_cbranch_execz .LBB0_986
	ds_read_b128 v[0:3], v29
	ds_read_b128 v[4:7], v29 offset:16
	v_add_u32_e32 v20, s16, v27
	v_or_b32_e32 v10, s15, v28
	v_lshlrev_b32_e32 v24, 1, v10
	s_waitcnt lgkmcnt(1)
	v_pk_add_f32 v[14:15], v[2:3], 0 op_sel_hi:[1,0]
	v_pk_add_f32 v[16:17], v[0:1], 0 op_sel_hi:[1,0]
	ds_read_b128 v[0:3], v29 offset:16384
	s_waitcnt lgkmcnt(1)
	v_pk_add_f32 v[6:7], v[6:7], 0 op_sel_hi:[1,0]
	v_pk_add_f32 v[4:5], v[4:5], 0 op_sel_hi:[1,0]
	v_mov_b32_e32 v25, v11
	v_ashrrev_i32_e32 v21, 31, v20
	s_waitcnt lgkmcnt(0)
	v_pk_add_f32 v[14:15], v[14:15], v[2:3]
	v_pk_add_f32 v[16:17], v[16:17], v[0:1]
	ds_read_b128 v[0:3], v29 offset:16400
	s_waitcnt lgkmcnt(0)
	v_pk_add_f32 v[6:7], v[6:7], v[2:3]
	v_pk_add_f32 v[4:5], v[4:5], v[0:1]
	ds_read_b128 v[0:3], v29 offset:32768
	s_waitcnt lgkmcnt(0)
	v_pk_add_f32 v[14:15], v[14:15], v[2:3]
	v_pk_add_f32 v[16:17], v[16:17], v[0:1]
	ds_read_b128 v[0:3], v29 offset:32784
	s_waitcnt lgkmcnt(0)
	v_pk_add_f32 v[6:7], v[6:7], v[2:3]
	v_pk_add_f32 v[4:5], v[4:5], v[0:1]
	ds_read_b128 v[0:3], v29 offset:49152
	s_waitcnt lgkmcnt(0)
	v_pk_add_f32 v[14:15], v[14:15], v[2:3]
	v_pk_add_f32 v[16:17], v[16:17], v[0:1]
	ds_read_b128 v[0:3], v29 offset:49168
	s_waitcnt lgkmcnt(0)
	v_pk_add_f32 v[6:7], v[6:7], v[2:3]
	v_pk_add_f32 v[4:5], v[4:5], v[0:1]
	ds_read_b128 v[0:3], v30
	s_waitcnt lgkmcnt(0)
	v_pk_add_f32 v[14:15], v[14:15], v[2:3]
	v_pk_add_f32 v[16:17], v[16:17], v[0:1]
	ds_read_b128 v[0:3], v31
	s_waitcnt lgkmcnt(0)
	v_pk_add_f32 v[6:7], v[6:7], v[2:3]
	v_pk_add_f32 v[4:5], v[4:5], v[0:1]
	ds_read_b128 v[0:3], v32
	s_waitcnt lgkmcnt(0)
	v_pk_add_f32 v[14:15], v[14:15], v[2:3]
	v_pk_add_f32 v[16:17], v[16:17], v[0:1]
	ds_read_b128 v[0:3], v33
	s_waitcnt lgkmcnt(0)
	v_pk_add_f32 v[6:7], v[6:7], v[2:3]
	v_pk_add_f32 v[4:5], v[4:5], v[0:1]
	ds_read_b128 v[0:3], v34
	s_waitcnt lgkmcnt(0)
	v_pk_add_f32 v[14:15], v[14:15], v[2:3]
	v_pk_add_f32 v[18:19], v[16:17], v[0:1]
	ds_read_b128 v[0:3], v35
	s_waitcnt lgkmcnt(0)
	v_pk_add_f32 v[6:7], v[6:7], v[2:3]
	v_pk_add_f32 v[4:5], v[4:5], v[0:1]
	ds_read_b128 v[0:3], v36
	s_waitcnt lgkmcnt(0)
	v_pk_add_f32 v[16:17], v[14:15], v[2:3]
	v_pk_add_f32 v[22:23], v[18:19], v[0:1]
	ds_read_b128 v[0:3], v37
	s_waitcnt lgkmcnt(0)
	v_pk_add_f32 v[18:19], v[4:5], v[0:1]
	v_mov_b64_e32 v[0:1], s[10:11]
	v_mad_i64_i32 v[0:1], s[16:17], v20, s77, v[0:1]
	v_lshl_add_u64 v[0:1], v[0:1], 0, v[24:25]
	v_pk_add_f32 v[14:15], v[6:7], v[2:3]
	global_load_dwordx4 v[0:3], v[0:1], off
	v_lshl_add_u64 v[4:5], v[10:11], 2, s[0:1]
	s_waitcnt vmcnt(0) lgkmcnt(0)
	v_lshlrev_b32_e32 v41, 16, v0
	v_and_b32_e32 v42, 0xffff0000, v0
	v_lshlrev_b32_e32 v43, 16, v1
	v_and_b32_e32 v40, 0xffff0000, v1
	v_lshlrev_b32_e32 v44, 16, v2
	v_and_b32_e32 v45, 0xffff0000, v2
	v_lshlrev_b32_e32 v46, 16, v3
	v_and_b32_e32 v39, 0xffff0000, v3
	global_load_dwordx4 v[0:3], v[4:5], off offset:16
	s_nop 0
	global_load_dwordx4 v[4:7], v[4:5], off
	s_waitcnt vmcnt(1)
	v_add_f32_e32 v0, v0, v44
	v_add_f32_e32 v1, v1, v45
	v_add_f32_e32 v2, v2, v46
	v_mul_f32_e32 v0, 0xbfb8aa3b, v0
	v_mul_f32_e32 v1, 0xbfb8aa3b, v1
	v_mul_f32_e32 v2, 0xbfb8aa3b, v2
	v_exp_f32_e32 v0, v0
	v_exp_f32_e32 v1, v1
	v_exp_f32_e32 v2, v2
	s_waitcnt vmcnt(0)
	v_add_f32_e32 v4, v4, v41
	v_add_f32_e32 v0, 1.0, v0
	v_add_f32_e32 v1, 1.0, v1
	v_add_f32_e32 v2, 1.0, v2
	v_rcp_f32_e32 v0, v0
	v_rcp_f32_e32 v1, v1
	v_rcp_f32_e32 v2, v2
	v_mul_f32_e32 v4, 0xbfb8aa3b, v4
	v_mul_f32_e32 v10, v18, v0
	v_add_f32_e32 v0, v5, v42
	v_mul_f32_e32 v5, v19, v1
	v_add_f32_e32 v1, v6, v43
	v_mul_f32_e32 v6, v14, v2
	v_add_f32_e32 v2, v7, v40
	v_mul_f32_e32 v0, 0xbfb8aa3b, v0
	v_mul_f32_e32 v1, 0xbfb8aa3b, v1
	v_mul_f32_e32 v2, 0xbfb8aa3b, v2
	v_exp_f32_e32 v4, v4
	v_exp_f32_e32 v0, v0
	v_exp_f32_e32 v1, v1
	v_exp_f32_e32 v2, v2
	v_add_f32_e32 v3, v3, v39
	v_mul_f32_e32 v3, 0xbfb8aa3b, v3
	v_exp_f32_e32 v3, v3
	v_add_f32_e32 v4, 1.0, v4
	v_add_f32_e32 v0, 1.0, v0
	v_add_f32_e32 v1, 1.0, v1
	v_add_f32_e32 v2, 1.0, v2
	v_rcp_f32_e32 v4, v4
	v_rcp_f32_e32 v0, v0
	v_rcp_f32_e32 v1, v1
	v_rcp_f32_e32 v2, v2
	v_add_f32_e32 v3, 1.0, v3
	v_rcp_f32_e32 v3, v3
	v_mul_f32_e32 v4, v22, v4
	v_mul_f32_e32 v0, v23, v0
	v_mul_f32_e32 v1, v16, v1
	v_mul_f32_e32 v2, v17, v2
	v_cvt_pk_bf16_f32 v0, v4, v0
	v_cvt_pk_bf16_f32 v1, v1, v2
	v_cvt_pk_bf16_f32 v2, v10, v5
	v_lshlrev_b64 v[4:5], 11, v[20:21]
	v_lshl_add_u64 v[4:5], s[8:9], 0, v[4:5]
	v_mul_f32_e32 v3, v15, v3
	v_lshl_add_u64 v[4:5], v[4:5], 0, v[24:25]
	v_cvt_pk_bf16_f32 v3, v6, v3
	global_store_dwordx4 v[4:5], v[0:3], off
	s_branch .LBB0_986

; #define LAS __attribute__((address_space(3)))
; __device__ __forceinline__ f32x4 mfma16(bf16x8 a, bf16x8 b, f32x4 c) { return __builtin_amdgcn_mfma_f32_16x16x32_bf16(a, b, c, 0, 0, 0); }
; __device__ __forceinline__ void sync_threads() { __syncthreads(); }
; template <int RT, class Epi>
; __device__ __forceinline__ void skinny_gemm(const bf16* A, size_t lda, const bf16* Bt, int K, int N, const Epi& epi, int wg, int wg_first, int wg_count, int tid, LAS unsigned char* lds) {
;     ...
; #pragma unroll 4
;         for (int ks = 0; ks < ksteps; ++ks) {
;             bf16x8 af[RT], bfr[2];
; #pragma unroll
;             for (int rt = 0; rt < RT; ++rt) af[rt] = *(const bf16x8*)(ap + (size_t)(16 * rt) * lda + 32 * ks);
;             bfr[0] = *(const bf16x8*)(bp + 32 * ks); bfr[1] = *(const bf16x8*)(bp + (size_t)16 * K + 32 * ks);
; #pragma unroll
;             for (int rt = 0; rt < RT; ++rt) { acc[rt][0] = mfma16(af[rt], bfr[0], acc[rt][0]); acc[rt][1] = mfma16(af[rt], bfr[1], acc[rt][1]); }
;         }
;         LAS float* part = (LAS float*)(lds + w * SK_PART);
; #pragma unroll
;         for (int rt = 0; rt < RT; ++rt)
; #pragma unroll
;             for (int nt = 0; nt < 2; ++nt)
; #pragma unroll
;                 for (int r = 0; r < 4; ++r) part[(16 * rt + 4 * g + r) * 32 + 16 * nt + c] = acc[rt][nt][r];
;         sync_threads();
.LBB0_1013:
	v_lshl_add_u64 v[18:19], v[14:15], 0, s[8:9]
	v_add_co_u32_e32 v44, vcc, 0x36600000, v18
	v_lshl_add_u64 v[40:41], v[16:17], 0, s[8:9]
	s_nop 0
	v_addc_co_u32_e32 v45, vcc, 0, v19, vcc
	global_load_dwordx4 v[18:21], v[44:45], off
	v_add_co_u32_e32 v46, vcc, 0x6a80000, v40
	s_add_u32 s8, s8, 0x100
	s_nop 0
	v_addc_co_u32_e32 v47, vcc, 0, v41, vcc
	v_add_co_u32_e32 v48, vcc, 0x6a90000, v40
	global_load_dwordx4 v[22:25], v[46:47], off
	s_nop 0
	v_addc_co_u32_e32 v49, vcc, 0, v41, vcc
	global_load_dwordx4 v[40:43], v[48:49], off
	s_addc_u32 s9, s9, 0
	s_cmpk_eq_i32 s8, 0x200
	s_waitcnt vmcnt(0) lgkmcnt(0)
	v_mfma_f32_16x16x32_bf16 v[0:3], v[18:21], v[22:25], v[0:3]
	v_mfma_f32_16x16x32_bf16 v[4:7], v[18:21], v[40:43], v[4:7]
	global_load_dwordx4 v[18:21], v[44:45], off offset:64
	global_load_dwordx4 v[22:25], v[46:47], off offset:64
	global_load_dwordx4 v[40:43], v[48:49], off offset:64
	s_waitcnt vmcnt(0) lgkmcnt(0)
	v_mfma_f32_16x16x32_bf16 v[0:3], v[18:21], v[22:25], v[0:3]
	v_mfma_f32_16x16x32_bf16 v[4:7], v[18:21], v[40:43], v[4:7]
	global_load_dwordx4 v[18:21], v[44:45], off offset:128
	global_load_dwordx4 v[22:25], v[46:47], off offset:128
	global_load_dwordx4 v[40:43], v[48:49], off offset:128
	s_waitcnt vmcnt(0) lgkmcnt(0)
	v_mfma_f32_16x16x32_bf16 v[0:3], v[18:21], v[22:25], v[0:3]
	v_mfma_f32_16x16x32_bf16 v[4:7], v[18:21], v[40:43], v[4:7]
	global_load_dwordx4 v[18:21], v[44:45], off offset:192
	global_load_dwordx4 v[22:25], v[46:47], off offset:192
	global_load_dwordx4 v[40:43], v[48:49], off offset:192
	s_waitcnt vmcnt(0) lgkmcnt(0)
	v_mfma_f32_16x16x32_bf16 v[0:3], v[18:21], v[22:25], v[0:3]
	v_mfma_f32_16x16x32_bf16 v[4:7], v[18:21], v[40:43], v[4:7]
	s_cbranch_scc0 .LBB0_1013
	s_nop 6
	ds_write2_b32 v39, v0, v4 offset1:16
	ds_write2_b32 v39, v1, v5 offset0:32 offset1:48
	ds_write2_b32 v39, v2, v6 offset0:64 offset1:80
	ds_write2_b32 v39, v3, v7 offset0:96 offset1:112
	s_waitcnt lgkmcnt(0)
	s_barrier
	s_and_saveexec_b64 s[8:9], s[6:7]
	s_cbranch_execz .LBB0_1011
; #define LAS __attribute__((address_space(3)))
; template <int RT, class Epi>
; __device__ __forceinline__ void skinny_gemm(const bf16* A, size_t lda, const bf16* Bt, int K, int N, const Epi& epi, int wg, int wg_first, int wg_count, int tid, LAS unsigned char* lds) {
;     ...
;         if (RT == 8 || tid < 64 * RT) {
;             const int row = tid >> 2, c8 = (tid & 3) * 8;
;             f32x4 v0 = (f32x4){0.f, 0.f, 0.f, 0.f}, v1 = (f32x4){0.f, 0.f, 0.f, 0.f};
; #pragma unroll
;             for (int ww = 0; ww < 8; ++ww) { const LAS float* pp = (const LAS float*)(lds + ww * SK_PART) + row * 32 + c8; v0 = v0 + *(const LAS f32x4*)pp; v1 = v1 + *(const LAS f32x4*)(pp + 4); }
;             epi(r0 + row, n0 + c8, v0, v1);
	ds_read_b128 v[0:3], v29
	ds_read_b128 v[4:7], v29 offset:16
	s_lshl_b32 s17, s16, 2
	s_lshl_b32 s18, s16, 4
	s_and_b32 s17, s17, 0x7fffffe0
	s_waitcnt lgkmcnt(1)
	v_pk_add_f32 v[14:15], v[2:3], 0 op_sel_hi:[1,0]
	v_pk_add_f32 v[16:17], v[0:1], 0 op_sel_hi:[1,0]
	ds_read_b128 v[0:3], v29 offset:16384
	s_waitcnt lgkmcnt(1)
	v_pk_add_f32 v[6:7], v[6:7], 0 op_sel_hi:[1,0]
	v_pk_add_f32 v[4:5], v[4:5], 0 op_sel_hi:[1,0]
	s_and_b32 s18, s18, 0x70
	v_add_u32_e32 v24, s18, v27
	s_waitcnt lgkmcnt(0)
	v_pk_add_f32 v[14:15], v[14:15], v[2:3]
	v_pk_add_f32 v[16:17], v[16:17], v[0:1]
	ds_read_b128 v[0:3], v29 offset:16400
	v_or_b32_e32 v10, s17, v28
	v_lshlrev_b32_e32 v22, 1, v10
	v_mov_b32_e32 v23, v11
	v_ashrrev_i32_e32 v25, 31, v24
	s_waitcnt lgkmcnt(0)
	v_pk_add_f32 v[6:7], v[6:7], v[2:3]
	v_pk_add_f32 v[4:5], v[4:5], v[0:1]
	ds_read_b128 v[0:3], v29 offset:32768
	s_waitcnt lgkmcnt(0)
	v_pk_add_f32 v[14:15], v[14:15], v[2:3]
	v_pk_add_f32 v[16:17], v[16:17], v[0:1]
	ds_read_b128 v[0:3], v29 offset:32784
	s_waitcnt lgkmcnt(0)
	v_pk_add_f32 v[6:7], v[6:7], v[2:3]
	v_pk_add_f32 v[4:5], v[4:5], v[0:1]
	ds_read_b128 v[0:3], v29 offset:49152
	s_waitcnt lgkmcnt(0)
	v_pk_add_f32 v[14:15], v[14:15], v[2:3]
	v_pk_add_f32 v[16:17], v[16:17], v[0:1]
	ds_read_b128 v[0:3], v29 offset:49168
	s_waitcnt lgkmcnt(0)
	v_pk_add_f32 v[6:7], v[6:7], v[2:3]
	v_pk_add_f32 v[4:5], v[4:5], v[0:1]
	ds_read_b128 v[0:3], v30
	s_waitcnt lgkmcnt(0)
	v_pk_add_f32 v[14:15], v[14:15], v[2:3]
	v_pk_add_f32 v[16:17], v[16:17], v[0:1]
	ds_read_b128 v[0:3], v31
	s_waitcnt lgkmcnt(0)
	v_pk_add_f32 v[6:7], v[6:7], v[2:3]
	v_pk_add_f32 v[4:5], v[4:5], v[0:1]
	ds_read_b128 v[0:3], v32
	s_waitcnt lgkmcnt(0)
	v_pk_add_f32 v[14:15], v[14:15], v[2:3]
	v_pk_add_f32 v[16:17], v[16:17], v[0:1]
	ds_read_b128 v[0:3], v33
	s_waitcnt lgkmcnt(0)
	v_pk_add_f32 v[6:7], v[6:7], v[2:3]
	v_pk_add_f32 v[4:5], v[4:5], v[0:1]
	ds_read_b128 v[0:3], v34
	s_waitcnt lgkmcnt(0)
	v_pk_add_f32 v[14:15], v[14:15], v[2:3]
	v_pk_add_f32 v[18:19], v[16:17], v[0:1]
	ds_read_b128 v[0:3], v35
	s_waitcnt lgkmcnt(0)
	v_pk_add_f32 v[6:7], v[6:7], v[2:3]
	v_pk_add_f32 v[4:5], v[4:5], v[0:1]
	ds_read_b128 v[0:3], v36
	s_waitcnt lgkmcnt(0)
	v_pk_add_f32 v[16:17], v[14:15], v[2:3]
	v_pk_add_f32 v[20:21], v[18:19], v[0:1]
	ds_read_b128 v[0:3], v37
	s_waitcnt lgkmcnt(0)
	v_pk_add_f32 v[18:19], v[4:5], v[0:1]
	v_mov_b64_e32 v[0:1], s[12:13]
	v_mad_i64_i32 v[0:1], s[18:19], v24, s77, v[0:1]
	v_lshl_add_u64 v[0:1], v[0:1], 0, v[22:23]
	v_pk_add_f32 v[14:15], v[6:7], v[2:3]
	global_load_dwordx4 v[0:3], v[0:1], off
	v_lshl_add_u64 v[4:5], v[10:11], 2, s[0:1]
	v_lshlrev_b64 v[24:25], 11, v[24:25]
	v_lshl_add_u64 v[42:43], s[2:3], 0, v[24:25]
	v_lshl_add_u64 v[42:43], v[42:43], 0, v[22:23]
	s_waitcnt vmcnt(0) lgkmcnt(0)
	v_lshlrev_b32_e32 v50, 16, v0
	v_and_b32_e32 v51, 0xffff0000, v0
	v_lshlrev_b32_e32 v52, 16, v1
	v_and_b32_e32 v45, 0xffff0000, v1
	v_lshlrev_b32_e32 v53, 16, v2
	v_and_b32_e32 v54, 0xffff0000, v2
	v_lshlrev_b32_e32 v55, 16, v3
	v_and_b32_e32 v40, 0xffff0000, v3
	global_load_dwordx4 v[0:3], v[4:5], off offset:16
	s_nop 0
	global_load_dwordx4 v[4:7], v[4:5], off
	s_waitcnt vmcnt(1)
	v_add_f32_e32 v0, v0, v53
	global_load_dwordx4 v[46:49], v[42:43], off
	v_mul_f32_e32 v0, 0xbfb8aa3b, v0
	v_exp_f32_e32 v0, v0
	s_waitcnt vmcnt(0)
	v_add_f32_e32 v4, v4, v50
	v_mul_f32_e32 v4, 0xbfb8aa3b, v4
	v_exp_f32_e32 v4, v4
	v_add_f32_e32 v0, 1.0, v0
	v_rcp_f32_e32 v0, v0
	v_add_f32_e32 v4, 1.0, v4
	v_rcp_f32_e32 v4, v4
	s_waitcnt lgkmcnt(0)
	v_lshlrev_b32_e32 v44, 16, v48
	v_fmac_f32_e32 v44, v18, v0
	v_add_f32_e32 v0, v5, v51
	v_mul_f32_e32 v0, 0xbfb8aa3b, v0
	v_exp_f32_e32 v0, v0
	v_and_b32_e32 v41, 0xffff0000, v46
	v_lshlrev_b32_e32 v10, 16, v46
	v_and_b32_e32 v46, 0xffff0000, v48
	v_add_f32_e32 v0, 1.0, v0
	v_rcp_f32_e32 v0, v0
	v_lshlrev_b32_e32 v42, 16, v47
	v_and_b32_e32 v43, 0xffff0000, v47
	v_lshlrev_b32_e32 v47, 16, v49
	v_fmac_f32_e32 v41, v21, v0
	v_add_f32_e32 v0, v1, v54
	v_mul_f32_e32 v0, 0xbfb8aa3b, v0
	v_exp_f32_e32 v0, v0
	v_fmac_f32_e32 v10, v20, v4
	v_lshl_add_u64 v[4:5], s[10:11], 0, v[24:25]
	v_and_b32_e32 v48, 0xffff0000, v49
	v_add_f32_e32 v0, 1.0, v0
	v_rcp_f32_e32 v0, v0
	v_lshl_add_u64 v[4:5], v[4:5], 0, v[22:23]
	v_fmac_f32_e32 v46, v19, v0
	v_add_f32_e32 v0, v6, v52
	v_mul_f32_e32 v0, 0xbfb8aa3b, v0
	v_exp_f32_e32 v0, v0
	s_nop 0
	v_add_f32_e32 v0, 1.0, v0
	v_rcp_f32_e32 v0, v0
	s_nop 0
	v_fmac_f32_e32 v42, v16, v0
	v_add_f32_e32 v0, v2, v55
	v_mul_f32_e32 v0, 0xbfb8aa3b, v0
	v_exp_f32_e32 v0, v0
	v_cvt_pk_bf16_f32 v2, v44, v46
	s_nop 0
	v_add_f32_e32 v0, 1.0, v0
	v_rcp_f32_e32 v0, v0
	s_nop 0
	v_fmac_f32_e32 v47, v14, v0
	v_add_f32_e32 v0, v7, v45
	v_mul_f32_e32 v0, 0xbfb8aa3b, v0
	v_exp_f32_e32 v0, v0
	s_nop 0
	v_add_f32_e32 v0, 1.0, v0
	v_rcp_f32_e32 v0, v0
	s_nop 0
	v_fmac_f32_e32 v43, v17, v0
	v_add_f32_e32 v0, v3, v40
	v_mul_f32_e32 v0, 0xbfb8aa3b, v0
	v_exp_f32_e32 v0, v0
	v_cvt_pk_bf16_f32 v1, v42, v43
	s_nop 0
	v_add_f32_e32 v0, 1.0, v0
	v_rcp_f32_e32 v0, v0
	s_nop 0
	v_fmac_f32_e32 v48, v15, v0
	v_cvt_pk_bf16_f32 v0, v10, v41
	v_cvt_pk_bf16_f32 v3, v47, v48
	global_store_dwordx4 v[4:5], v[0:3], off
	s_branch .LBB0_1011

; __device__ __forceinline__ unsigned xb_ld(unsigned* p)              { return __hip_atomic_load(p, __ATOMIC_RELAXED, __HIP_MEMORY_SCOPE_AGENT); }
; __device__ __forceinline__ void xcd_barrier_complete(unsigned* bar, unsigned x, unsigned& nloc, unsigned& nx) {
;     const unsigned G = gridDim.x * gridDim.y * gridDim.z;
;     unsigned sum, cnt, mine, sp = 0u;
;     for (;;) {
;         sum = 0u; cnt = 0u; mine = 0u;
; #pragma unroll
;         for (unsigned j = 0; j < 16; ++j) { const unsigned c = xb_ld(&bar[XB_XCNT(j)]); sum += c; cnt += (c > 0u) ? 1u : 0u; mine = (j == x) ? c : mine; }
;         if (sum == G) break;
;         __builtin_amdgcn_s_sleep(1);
;         if ((++sp & 255u) == 0u) { if (xb_ld(&bar[XB_TMO])) break; if (sp > XB_SPIN_CAP) { atomicAdd(&bar[XB_TMO], 1u); break; } }
;     }
.LBB0_1021:
	v_mov_b64_e32 v[12:13], s[2:3]
	global_load_dword v1, v[12:13], off offset:1024 sc1
	global_load_dword v0, v[12:13], off offset:1280 sc1
	global_load_dword v2, v[12:13], off offset:1536 sc1
	s_or_b64 s[20:21], s[20:21], exec
	s_or_b64 s[18:19], s[18:19], exec
	s_waitcnt vmcnt(0) lgkmcnt(0)
	v_add_u32_e32 v3, v0, v1
	v_add_u32_e32 v4, v3, v2
	global_load_dword v3, v[12:13], off offset:1792 sc1
	s_waitcnt vmcnt(0) lgkmcnt(0)
	v_add_u32_e32 v5, v4, v3
	global_load_dword v4, v[12:13], off offset:2048 sc1
	s_waitcnt vmcnt(0) lgkmcnt(0)
	v_add_u32_e32 v6, v5, v4
	global_load_dword v5, v[12:13], off offset:2304 sc1
	s_waitcnt vmcnt(0) lgkmcnt(0)
	v_add_u32_e32 v7, v6, v5
	global_load_dword v6, v[12:13], off offset:2560 sc1
	s_waitcnt vmcnt(0) lgkmcnt(0)
	v_add_u32_e32 v8, v7, v6
	global_load_dword v7, v[12:13], off offset:2816 sc1
	s_waitcnt vmcnt(0) lgkmcnt(0)
	v_add_u32_e32 v9, v8, v7
	global_load_dword v8, v[12:13], off offset:3072 sc1
	s_waitcnt vmcnt(0) lgkmcnt(0)
	v_add_u32_e32 v10, v9, v8
	global_load_dword v9, v[12:13], off offset:3328 sc1
	s_waitcnt vmcnt(0) lgkmcnt(0)
	v_add_u32_e32 v14, v10, v9
	global_load_dword v10, v[12:13], off offset:3584 sc1
	s_waitcnt vmcnt(0) lgkmcnt(0)
	v_add_u32_e32 v14, v14, v10
	global_load_dword v12, v[12:13], off offset:3840 sc1
	s_waitcnt vmcnt(0) lgkmcnt(0)
	v_add_u32_e32 v16, v14, v12
	v_mov_b64_e32 v[14:15], s[6:7]
	global_load_dword v13, v[14:15], off sc1
	v_mov_b64_e32 v[14:15], s[8:9]
	global_load_dword v14, v[14:15], off sc1
	s_waitcnt vmcnt(0) lgkmcnt(0)
	v_add_u32_e32 v16, v16, v13
	v_add_u32_e32 v18, v16, v14
	v_mov_b64_e32 v[16:17], s[10:11]
	global_load_dword v15, v[16:17], off sc1
	v_mov_b64_e32 v[16:17], s[12:13]
	global_load_dword v16, v[16:17], off sc1
	s_waitcnt vmcnt(0) lgkmcnt(0)
	v_add_u32_e32 v18, v18, v15
	v_add_u32_e32 v17, v18, v16
	v_cmp_ne_u32_e32 vcc, s34, v17
	s_and_saveexec_b64 s[22:23], vcc
	s_cbranch_execz .LBB0_1020
	s_and_b32 s26, s35, 0xff
	s_mov_b64 s[24:25], -1
	s_cmp_eq_u32 s26, 0
	s_mov_b64 s[28:29], -1
	s_mov_b64 s[26:27], -1
	s_sleep 1
	s_cbranch_scc1 .LBB0_1024
	s_and_saveexec_b64 s[30:31], s[28:29]
	s_cbranch_execz .LBB0_1019
	s_branch .LBB0_1027
.LBB0_1024:
	v_mov_b64_e32 v[18:19], s[2:3]
	global_load_dword v17, v[18:19], off offset:512 sc1
	s_mov_b64 s[28:29], 0
	s_waitcnt vmcnt(0) lgkmcnt(0)
	v_cmp_eq_u32_e32 vcc, 0, v17
	s_and_saveexec_b64 s[30:31], vcc
	s_cmp_lt_u32 s35, 0x40001
	s_cselect_b64 s[28:29], -1, 0
	s_xor_b64 s[26:27], exec, -1
	s_and_b64 s[28:29], s[28:29], exec
	s_or_b64 exec, exec, s[30:31]
	s_and_saveexec_b64 s[30:31], s[28:29]
	s_cbranch_execz .LBB0_1019

; __device__ __forceinline__ unsigned xb_ld(unsigned* p)              { return __hip_atomic_load(p, __ATOMIC_RELAXED, __HIP_MEMORY_SCOPE_AGENT); }
; __device__ __forceinline__ unsigned xb_add(unsigned* p, unsigned v) { return __hip_atomic_fetch_add(p, v, __ATOMIC_RELAXED, __HIP_MEMORY_SCOPE_AGENT); }
; #define XB_SPIN(cond, bar) do { unsigned _sp = 0; while (cond) { __builtin_amdgcn_s_sleep(1); \
;     if ((++_sp & 255u) == 0u) { if (xb_ld(&(bar)[XB_TMO])) break; if (_sp > XB_SPIN_CAP) { atomicAdd(&(bar)[XB_TMO], 1u); break; } } } } while (0)
; __device__ __forceinline__ void xcd_barrier(const XcdBarrier& b, int tid) {
;     ...
;         unsigned nloc = b.st[0], nx = b.st[1];
;         if (nloc == 0u) { xcd_barrier_complete(bar, bx_, nloc, nx); b.st[0] = nloc; b.st[1] = nx; }
;         const unsigned old = xb_add(&bar[XB_XSUB(bx_)], 1u);
;         const unsigned gen = old / nloc;
;         if (old + 1u == (gen + 1u) * nloc) {
;             __builtin_amdgcn_fence(__ATOMIC_RELEASE, "agent");
;             asm volatile("s_waitcnt vmcnt(0)" ::: "memory");
;             const unsigned og = xb_add(&bar[XB_TOP], 1u);
;             const unsigned tg = og / nx;
;             if (og + 1u == (tg + 1u) * nx) xb_add(&bar[XB_TOPGEN], 1u);
;             else XB_SPIN(xb_ld(&bar[XB_TOPGEN]) == tg, bar);
;             __builtin_amdgcn_fence(__ATOMIC_ACQUIRE, "agent");
;             xb_add(&bar[XB_XGEN(bx_)], 1u);
;             asm volatile("s_waitcnt vmcnt(0)" ::: "memory");
;         } else {
;             XB_SPIN(xb_ld(&bar[XB_XGEN(bx_)]) == gen, bar);
.LBB0_1031:
	s_lshl_b32 s28, s50, 6
	s_add_i32 s64, s28, 0x500
	s_lshl_b64 s[6:7], s[64:65], 2
	s_add_u32 s6, s2, s6
	s_addc_u32 s7, s3, s7
	v_mov_b64_e32 v[4:5], s[6:7]
	v_mov_b32_e32 v1, 1
	flat_atomic_add v3, v[4:5], v1 sc0
	v_cvt_f32_u32_e32 v1, v2
	v_sub_u32_e32 v4, 0, v2
	v_rcp_iflag_f32_e32 v1, v1
	s_nop 0
	v_mul_f32_e32 v1, 0x4f7ffffe, v1
	v_cvt_u32_f32_e32 v1, v1
	v_mul_lo_u32 v4, v4, v1
	v_mul_hi_u32 v4, v1, v4
	v_add_u32_e32 v1, v1, v4
	s_waitcnt vmcnt(0) lgkmcnt(0)
	v_mul_hi_u32 v1, v3, v1
	v_mul_lo_u32 v4, v1, v2
	v_sub_u32_e32 v4, v3, v4
	v_cmp_ge_u32_e32 vcc, v4, v2
	v_add_u32_e32 v5, 1, v1
	s_nop 0
	v_cndmask_b32_e32 v1, v1, v5, vcc
	v_sub_u32_e32 v5, v4, v2
	v_cndmask_b32_e32 v4, v4, v5, vcc
	v_cmp_ge_u32_e32 vcc, v4, v2
	v_add_u32_e32 v4, 1, v1
	s_nop 0
	v_cndmask_b32_e32 v1, v1, v4, vcc
	v_add_u32_e32 v4, 1, v3
	v_mad_u64_u32 v[2:3], s[6:7], v2, v1, v[2:3]
	v_cmp_ne_u32_e32 vcc, v4, v2
	s_and_saveexec_b64 s[6:7], vcc
	s_xor_b64 s[6:7], exec, s[6:7]
	s_cbranch_execz .LBB0_1044
	s_add_i32 s64, s28, 0x900
	s_lshl_b64 s[8:9], s[64:65], 2
	s_add_u32 s10, s2, s8
	s_addc_u32 s11, s3, s9
	v_mov_b64_e32 v[2:3], s[10:11]
	global_load_dword v0, v[2:3], off sc1
	s_waitcnt vmcnt(0) lgkmcnt(0)
	v_cmp_eq_u32_e32 vcc, v0, v1
	s_and_saveexec_b64 s[8:9], vcc
	s_cbranch_execz .LBB0_1043
	s_mov_b32 s26, 1
	s_mov_b64 s[12:13], 0
	s_branch .LBB0_1035

; __device__ __forceinline__ unsigned xb_ld(unsigned* p)              { return __hip_atomic_load(p, __ATOMIC_RELAXED, __HIP_MEMORY_SCOPE_AGENT); }
; #define XB_SPIN(cond, bar) do { unsigned _sp = 0; while (cond) { __builtin_amdgcn_s_sleep(1); \
;     if ((++_sp & 255u) == 0u) { if (xb_ld(&(bar)[XB_TMO])) break; if (_sp > XB_SPIN_CAP) { atomicAdd(&(bar)[XB_TMO], 1u); break; } } } } while (0)
; __device__ __forceinline__ void xcd_barrier(const XcdBarrier& b, int tid) {
;     ...
;             XB_SPIN(xb_ld(&bar[XB_XGEN(bx_)]) == gen, bar);
.LBB0_1035:
	s_and_b32 s20, s26, 0xff
	s_mov_b64 s[18:19], -1
	s_cmp_lg_u32 s20, 0
	s_mov_b64 s[20:21], -1
	s_sleep 1
	s_cbranch_scc1 .LBB0_1039
	v_mov_b64_e32 v[2:3], s[2:3]
	global_load_dword v0, v[2:3], off offset:512 sc1
	s_mov_b64 s[20:21], 0
	s_mov_b64 s[22:23], -1
	s_waitcnt vmcnt(0) lgkmcnt(0)
	v_cmp_eq_u32_e32 vcc, 0, v0
	s_and_saveexec_b64 s[24:25], vcc
	s_cmp_lt_u32 s26, 0x40001
	s_cselect_b64 s[20:21], -1, 0
	s_xor_b64 s[22:23], exec, -1
	s_and_b64 s[20:21], s[20:21], exec
	s_or_b64 exec, exec, s[24:25]
.LBB0_1039:
	s_andn2_b64 s[16:17], s[16:17], exec
	s_and_b64 s[22:23], s[22:23], exec
	s_or_b64 s[16:17], s[16:17], s[22:23]
	s_and_saveexec_b64 s[22:23], s[20:21]
	s_cbranch_execz .LBB0_1034
	v_mov_b64_e32 v[2:3], s[10:11]
	global_load_dword v0, v[2:3], off sc1
	s_add_i32 s26, s26, 1
	s_or_b64 s[16:17], s[16:17], exec
	s_waitcnt vmcnt(0) lgkmcnt(0)
	v_cmp_ne_u32_e32 vcc, v0, v1
	s_orn2_b64 s[18:19], vcc, exec
	s_branch .LBB0_1034

; __device__ __forceinline__ unsigned xb_ld(unsigned* p)              { return __hip_atomic_load(p, __ATOMIC_RELAXED, __HIP_MEMORY_SCOPE_AGENT); }
; __device__ __forceinline__ unsigned xb_add(unsigned* p, unsigned v) { return __hip_atomic_fetch_add(p, v, __ATOMIC_RELAXED, __HIP_MEMORY_SCOPE_AGENT); }
; #define XB_SPIN(cond, bar) do { unsigned _sp = 0; while (cond) { __builtin_amdgcn_s_sleep(1); \
;     if ((++_sp & 255u) == 0u) { if (xb_ld(&(bar)[XB_TMO])) break; if (_sp > XB_SPIN_CAP) { atomicAdd(&(bar)[XB_TMO], 1u); break; } } } } while (0)
; __device__ __forceinline__ void xcd_barrier(const XcdBarrier& b, int tid) {
;     ...
;         if (old + 1u == (gen + 1u) * nloc) {
;             __builtin_amdgcn_fence(__ATOMIC_RELEASE, "agent");
;             asm volatile("s_waitcnt vmcnt(0)" ::: "memory");
;             const unsigned og = xb_add(&bar[XB_TOP], 1u);
;             const unsigned tg = og / nx;
;             if (og + 1u == (tg + 1u) * nx) xb_add(&bar[XB_TOPGEN], 1u);
;             else XB_SPIN(xb_ld(&bar[XB_TOPGEN]) == tg, bar);
.LBB0_1044:
	s_andn2_saveexec_b64 s[6:7], s[6:7]
	s_cbranch_execz .LBB0_1060
	v_mov_b32_e32 v1, s2
	v_add_co_u32_e32 v2, vcc, 0x3000, v1
	v_mov_b32_e32 v1, s3
	buffer_wbl2 sc1
	s_waitcnt vmcnt(0)
	v_addc_co_u32_e32 v3, vcc, 0, v1, vcc
	v_mov_b32_e32 v1, 1
	flat_atomic_add v1, v[2:3], v1 offset:1024 sc0
	v_cvt_f32_u32_e32 v2, v0
	v_sub_u32_e32 v3, 0, v0
	s_mov_b64 s[12:13], -1
	v_rcp_iflag_f32_e32 v2, v2
	s_nop 0
	v_mul_f32_e32 v2, 0x4f7ffffe, v2
	v_cvt_u32_f32_e32 v2, v2
	v_mul_lo_u32 v3, v3, v2
	v_mul_hi_u32 v3, v2, v3
	v_add_u32_e32 v2, v2, v3
	s_waitcnt vmcnt(0) lgkmcnt(0)
	v_mul_hi_u32 v2, v1, v2
	v_mul_lo_u32 v3, v2, v0
	v_sub_u32_e32 v3, v1, v3
	v_cmp_ge_u32_e32 vcc, v3, v0
	v_add_u32_e32 v4, 1, v2
	s_nop 0
	v_cndmask_b32_e32 v2, v2, v4, vcc
	v_sub_u32_e32 v4, v3, v0
	v_cndmask_b32_e32 v3, v3, v4, vcc
	v_cmp_ge_u32_e32 vcc, v3, v0
	v_add_u32_e32 v3, 1, v2
	s_nop 0
	v_cndmask_b32_e32 v2, v2, v3, vcc
	v_add_u32_e32 v3, 1, v1
	v_mad_u64_u32 v[0:1], s[8:9], v0, v2, v[0:1]
	s_add_u32 s8, s2, 0x3500
	s_addc_u32 s9, s3, 0
	v_cmp_ne_u32_e32 vcc, v3, v0
	v_mov_b64_e32 v[0:1], s[8:9]
	s_and_saveexec_b64 s[10:11], vcc
	s_cbranch_execz .LBB0_1057
	v_mov_b64_e32 v[0:1], s[8:9]
	global_load_dword v0, v[0:1], off sc1
	s_mov_b64 s[16:17], 0
	s_waitcnt vmcnt(0) lgkmcnt(0)
	v_cmp_eq_u32_e32 vcc, v0, v2
	s_and_saveexec_b64 s[14:15], vcc
	s_cbranch_execz .LBB0_1056
	s_add_u32 s12, s2, 0x200
	s_addc_u32 s13, s3, 0
	s_mov_b32 s29, 1
	s_branch .LBB0_1049

; __device__ __forceinline__ unsigned xb_ld(unsigned* p)              { return __hip_atomic_load(p, __ATOMIC_RELAXED, __HIP_MEMORY_SCOPE_AGENT); }
; #define XB_SPIN(cond, bar) do { unsigned _sp = 0; while (cond) { __builtin_amdgcn_s_sleep(1); \
;     if ((++_sp & 255u) == 0u) { if (xb_ld(&(bar)[XB_TMO])) break; if (_sp > XB_SPIN_CAP) { atomicAdd(&(bar)[XB_TMO], 1u); break; } } } } while (0)
; __device__ __forceinline__ void xcd_barrier(const XcdBarrier& b, int tid) {
;     ...
;             else XB_SPIN(xb_ld(&bar[XB_TOPGEN]) == tg, bar);
.LBB0_1051:
	v_mov_b64_e32 v[0:1], s[12:13]
	global_load_dword v0, v[0:1], off sc1
	s_mov_b64 s[24:25], 0
	s_mov_b64 s[22:23], -1
	s_waitcnt vmcnt(0) lgkmcnt(0)
	v_cmp_eq_u32_e32 vcc, 0, v0
	s_and_saveexec_b64 s[26:27], vcc
	s_cmp_lt_u32 s29, 0x40001
	s_cselect_b64 s[24:25], -1, 0
	s_xor_b64 s[22:23], exec, -1
	s_and_b64 s[24:25], s[24:25], exec
	s_or_b64 exec, exec, s[26:27]
	s_and_saveexec_b64 s[26:27], s[24:25]
	s_cbranch_execz .LBB0_1048
.LBB0_1054:
	v_mov_b64_e32 v[0:1], s[8:9]
	global_load_dword v0, v[0:1], off sc1
	s_add_i32 s29, s29, 1
	s_or_b64 s[22:23], s[22:23], exec
	s_waitcnt vmcnt(0) lgkmcnt(0)
	v_cmp_ne_u32_e32 vcc, v0, v2
	s_orn2_b64 s[20:21], vcc, exec
	s_branch .LBB0_1048

; #define LAS __attribute__((address_space(3)))
; __device__ __forceinline__ f32x4 mfma16(bf16x8 a, bf16x8 b, f32x4 c) { return __builtin_amdgcn_mfma_f32_16x16x32_bf16(a, b, c, 0, 0, 0); }
; __device__ __forceinline__ void sync_threads() { __syncthreads(); }
; template <int RT, class Epi>
; __device__ __forceinline__ void skinny_gemm(const bf16* A, size_t lda, const bf16* Bt, int K, int N, const Epi& epi, int wg, int wg_first, int wg_count, int tid, LAS unsigned char* lds) {
;     ...
;     for (int s = me; s < nunit; s += wg_count) {
;         const int n0 = 32 * (s / NRG), r0 = (s % NRG) * (16 * RT);
;         f32x4 acc[RT][2];
; #pragma unroll
;         for (int rt = 0; rt < RT; ++rt) { acc[rt][0] = (f32x4){0.f, 0.f, 0.f, 0.f}; acc[rt][1] = (f32x4){0.f, 0.f, 0.f, 0.f}; }
;         const bf16* ap = A + (size_t)(r0 + c) * lda + (size_t)w * (K / 8) + 8 * g;
;         const bf16* bp = Bt + (size_t)(n0 + c) * K + (size_t)w * (K / 8) + 8 * g;
; #pragma unroll 4
;         for (int ks = 0; ks < ksteps; ++ks) {
;             bf16x8 af[RT], bfr[2];
; #pragma unroll
;             for (int rt = 0; rt < RT; ++rt) af[rt] = *(const bf16x8*)(ap + (size_t)(16 * rt) * lda + 32 * ks);
;             bfr[0] = *(const bf16x8*)(bp + 32 * ks); bfr[1] = *(const bf16x8*)(bp + (size_t)16 * K + 32 * ks);
; #pragma unroll
;             for (int rt = 0; rt < RT; ++rt) { acc[rt][0] = mfma16(af[rt], bfr[0], acc[rt][0]); acc[rt][1] = mfma16(af[rt], bfr[1], acc[rt][1]); }
;         }
;         LAS float* part = (LAS float*)(lds + w * SK_PART);
; #pragma unroll
;         for (int rt = 0; rt < RT; ++rt)
; #pragma unroll
;             for (int nt = 0; nt < 2; ++nt)
; #pragma unroll
;                 for (int r = 0; r < 4; ++r) part[(16 * rt + 4 * g + r) * 32 + 16 * nt + c] = acc[rt][nt][r];
;         sync_threads();
;         if (RT == 8 || tid < 64 * RT) {
;             const int row = tid >> 2, c8 = (tid & 3) * 8;
;             f32x4 v0 = (f32x4){0.f, 0.f, 0.f, 0.f}, v1 = (f32x4){0.f, 0.f, 0.f, 0.f};
; #pragma unroll
;             for (int ww = 0; ww < 8; ++ww) { const LAS float* pp = (const LAS float*)(lds + ww * SK_PART) + row * 32 + c8; v0 = v0 + *(const LAS f32x4*)pp; v1 = v1 + *(const LAS f32x4*)(pp + 4); }
;             epi(r0 + row, n0 + c8, v0, v1);
.LBB0_1084:
	s_and_b32 s16, s9, 0x70
	v_or_b32_e32 v4, s16, v20
	s_and_b32 s15, s8, 0x7fffffe0
	v_lshlrev_b32_e32 v10, 11, v4
	v_lshl_add_u64 v[8:9], v[0:1], 0, v[10:11]
	v_or_b32_e32 v10, s15, v20
	v_lshlrev_b64 v[4:5], 11, v[10:11]
	v_lshl_add_u64 v[42:43], v[2:3], 0, v[4:5]
	v_add_co_u32_e32 v44, vcc, 0x8000, v42
	global_load_dwordx4 v[4:7], v[8:9], off
	global_load_dwordx4 v[12:15], v[42:43], off
	v_addc_co_u32_e32 v45, vcc, 0, v43, vcc
	global_load_dwordx4 v[16:19], v[44:45], off
	s_waitcnt vmcnt(0) lgkmcnt(0)
	v_mfma_f32_16x16x32_bf16 v[12:15], v[4:7], v[12:15], 0
	v_mfma_f32_16x16x32_bf16 v[4:7], v[4:7], v[16:19], 0
	global_load_dwordx4 v[16:19], v[8:9], off offset:64
	global_load_dwordx4 v[34:37], v[42:43], off offset:64
	global_load_dwordx4 v[38:41], v[44:45], off offset:64
	s_waitcnt vmcnt(0) lgkmcnt(0)
	v_mfma_f32_16x16x32_bf16 v[12:15], v[16:19], v[34:37], v[12:15]
	v_mfma_f32_16x16x32_bf16 v[4:7], v[16:19], v[38:41], v[4:7]
	global_load_dwordx4 v[16:19], v[8:9], off offset:128
	global_load_dwordx4 v[34:37], v[42:43], off offset:128
	global_load_dwordx4 v[38:41], v[44:45], off offset:128
	s_waitcnt vmcnt(0) lgkmcnt(0)
	v_mfma_f32_16x16x32_bf16 v[12:15], v[16:19], v[34:37], v[12:15]
	v_mfma_f32_16x16x32_bf16 v[4:7], v[16:19], v[38:41], v[4:7]
	global_load_dwordx4 v[16:19], v[8:9], off offset:192
	global_load_dwordx4 v[34:37], v[42:43], off offset:192
	global_load_dwordx4 v[38:41], v[44:45], off offset:192
	s_waitcnt vmcnt(0) lgkmcnt(0)
	v_mfma_f32_16x16x32_bf16 v[12:15], v[16:19], v[34:37], v[12:15]
	v_mfma_f32_16x16x32_bf16 v[4:7], v[16:19], v[38:41], v[4:7]
	s_nop 7
	ds_write2_b32 v32, v12, v4 offset1:16
	ds_write2_b32 v32, v13, v5 offset0:32 offset1:48
	ds_write2_b32 v32, v14, v6 offset0:64 offset1:80
	ds_write2_b32 v32, v15, v7 offset0:96 offset1:112
	s_waitcnt lgkmcnt(0)
	s_barrier
	s_and_saveexec_b64 s[2:3], s[6:7]
	s_cbranch_execz .LBB0_1083
	ds_read_b128 v[4:7], v23
	ds_read_b128 v[12:15], v23 offset:16
	v_or_b32_e32 v10, s15, v22
	s_mov_b32 s15, 0x18000
	s_waitcnt lgkmcnt(1)
	v_pk_add_f32 v[8:9], v[6:7], 0 op_sel_hi:[1,0]
	v_pk_add_f32 v[16:17], v[4:5], 0 op_sel_hi:[1,0]
	ds_read_b128 v[4:7], v23 offset:16384
	s_waitcnt lgkmcnt(1)
	v_pk_add_f32 v[14:15], v[14:15], 0 op_sel_hi:[1,0]
	v_pk_add_f32 v[12:13], v[12:13], 0 op_sel_hi:[1,0]
	s_waitcnt lgkmcnt(0)
	v_pk_add_f32 v[8:9], v[8:9], v[6:7]
	v_pk_add_f32 v[16:17], v[16:17], v[4:5]
	ds_read_b128 v[4:7], v23 offset:16400
	s_waitcnt lgkmcnt(0)
	v_pk_add_f32 v[14:15], v[14:15], v[6:7]
	v_pk_add_f32 v[12:13], v[12:13], v[4:5]
	ds_read_b128 v[4:7], v23 offset:32768
	s_waitcnt lgkmcnt(0)
	v_pk_add_f32 v[8:9], v[8:9], v[6:7]
	v_pk_add_f32 v[16:17], v[16:17], v[4:5]
	ds_read_b128 v[4:7], v23 offset:32784
	s_waitcnt lgkmcnt(0)
	v_pk_add_f32 v[14:15], v[14:15], v[6:7]
	v_pk_add_f32 v[12:13], v[12:13], v[4:5]
	ds_read_b128 v[4:7], v23 offset:49152
	s_waitcnt lgkmcnt(0)
	v_pk_add_f32 v[8:9], v[8:9], v[6:7]
	v_pk_add_f32 v[16:17], v[16:17], v[4:5]
	ds_read_b128 v[4:7], v23 offset:49168
	s_waitcnt lgkmcnt(0)
	v_pk_add_f32 v[14:15], v[14:15], v[6:7]
	v_pk_add_f32 v[12:13], v[12:13], v[4:5]
	ds_read_b128 v[4:7], v24
	s_waitcnt lgkmcnt(0)
	v_pk_add_f32 v[8:9], v[8:9], v[6:7]
	v_pk_add_f32 v[16:17], v[16:17], v[4:5]
	ds_read_b128 v[4:7], v25
	s_waitcnt lgkmcnt(0)
	v_pk_add_f32 v[14:15], v[14:15], v[6:7]
	v_pk_add_f32 v[12:13], v[12:13], v[4:5]
	ds_read_b128 v[4:7], v26
	s_waitcnt lgkmcnt(0)
	v_pk_add_f32 v[8:9], v[8:9], v[6:7]
	v_pk_add_f32 v[16:17], v[16:17], v[4:5]
	ds_read_b128 v[4:7], v27
	s_waitcnt lgkmcnt(0)
	v_pk_add_f32 v[14:15], v[14:15], v[6:7]
	v_pk_add_f32 v[12:13], v[12:13], v[4:5]
	ds_read_b128 v[4:7], v28
	s_waitcnt lgkmcnt(0)
	v_pk_add_f32 v[8:9], v[8:9], v[6:7]
	v_pk_add_f32 v[16:17], v[16:17], v[4:5]
	ds_read_b128 v[4:7], v29
	s_waitcnt lgkmcnt(0)
	v_pk_add_f32 v[18:19], v[14:15], v[6:7]
	v_pk_add_f32 v[12:13], v[12:13], v[4:5]
	ds_read_b128 v[4:7], v30
	s_waitcnt lgkmcnt(0)
	v_pk_add_f32 v[14:15], v[8:9], v[6:7]
	v_pk_add_f32 v[16:17], v[16:17], v[4:5]
	ds_read_b128 v[4:7], v31
	v_add_u32_e32 v8, s16, v21
	v_ashrrev_i32_e32 v9, 31, v8
	s_waitcnt lgkmcnt(0)
	v_pk_add_f32 v[4:5], v[12:13], v[4:5]
	v_mov_b64_e32 v[12:13], s[12:13]
	v_mad_i64_i32 v[12:13], s[16:17], v8, s15, v[12:13]
	v_lshlrev_b64 v[8:9], 11, v[8:9]
	v_lshl_add_u64 v[38:39], v[10:11], 2, v[12:13]
	v_lshl_add_u64 v[8:9], s[10:11], 0, v[8:9]
	v_lshlrev_b32_e32 v10, 1, v10
	v_lshl_add_u64 v[8:9], v[8:9], 0, v[10:11]
	global_load_dwordx4 v[34:37], v[8:9], off
	v_pk_add_f32 v[6:7], v[18:19], v[6:7]
	s_waitcnt vmcnt(0) lgkmcnt(0)
	v_lshlrev_b32_e32 v40, 16, v34
	v_and_b32_e32 v41, 0xffff0000, v34
	v_lshlrev_b32_e32 v42, 16, v35
	v_and_b32_e32 v43, 0xffff0000, v35
	v_lshlrev_b32_e32 v12, 16, v36
	v_and_b32_e32 v13, 0xffff0000, v36
	v_lshlrev_b32_e32 v18, 16, v37
	v_and_b32_e32 v19, 0xffff0000, v37
	global_load_dwordx4 v[34:37], v[38:39], off
	s_waitcnt vmcnt(0) lgkmcnt(0)
	v_pk_fma_f32 v[14:15], v[14:15], v[36:37], v[42:43]
	v_pk_fma_f32 v[16:17], v[16:17], v[34:35], v[40:41]
	global_load_dwordx4 v[34:37], v[38:39], off offset:16
	s_waitcnt vmcnt(0) lgkmcnt(0)
	v_pk_fma_f32 v[18:19], v[6:7], v[36:37], v[18:19]
	v_pk_fma_f32 v[6:7], v[4:5], v[34:35], v[12:13]
	v_cvt_pk_bf16_f32 v4, v16, v17
	v_cvt_pk_bf16_f32 v5, v14, v15
	s_nop 0
	v_cvt_pk_bf16_f32 v6, v6, v7
	v_cvt_pk_bf16_f32 v7, v18, v19
	global_store_dwordx4 v[8:9], v[4:7], off
	s_branch .LBB0_1083

; __device__ __forceinline__ unsigned xb_ld(unsigned* p)              { return __hip_atomic_load(p, __ATOMIC_RELAXED, __HIP_MEMORY_SCOPE_AGENT); }
; __device__ __forceinline__ void xcd_barrier_complete(unsigned* bar, unsigned x, unsigned& nloc, unsigned& nx) {
;     const unsigned G = gridDim.x * gridDim.y * gridDim.z;
;     unsigned sum, cnt, mine, sp = 0u;
;     for (;;) {
;         sum = 0u; cnt = 0u; mine = 0u;
; #pragma unroll
;         for (unsigned j = 0; j < 16; ++j) { const unsigned c = xb_ld(&bar[XB_XCNT(j)]); sum += c; cnt += (c > 0u) ? 1u : 0u; mine = (j == x) ? c : mine; }
;         if (sum == G) break;
;         __builtin_amdgcn_s_sleep(1);
;         if ((++sp & 255u) == 0u) { if (xb_ld(&bar[XB_TMO])) break; if (sp > XB_SPIN_CAP) { atomicAdd(&bar[XB_TMO], 1u); break; } }
;     }
.LBB0_1091:
	v_mov_b64_e32 v[12:13], s[58:59]
	global_load_dword v1, v[12:13], off offset:1024 sc1
	global_load_dword v0, v[12:13], off offset:1280 sc1
	global_load_dword v2, v[12:13], off offset:1536 sc1
	s_or_b64 s[20:21], s[20:21], exec
	s_or_b64 s[18:19], s[18:19], exec
	s_waitcnt vmcnt(0) lgkmcnt(0)
	v_add_u32_e32 v3, v0, v1
	v_add_u32_e32 v4, v3, v2
	global_load_dword v3, v[12:13], off offset:1792 sc1
	s_waitcnt vmcnt(0) lgkmcnt(0)
	v_add_u32_e32 v5, v4, v3
	global_load_dword v4, v[12:13], off offset:2048 sc1
	s_waitcnt vmcnt(0) lgkmcnt(0)
	v_add_u32_e32 v6, v5, v4
	global_load_dword v5, v[12:13], off offset:2304 sc1
	s_waitcnt vmcnt(0) lgkmcnt(0)
	v_add_u32_e32 v7, v6, v5
	global_load_dword v6, v[12:13], off offset:2560 sc1
	s_waitcnt vmcnt(0) lgkmcnt(0)
	v_add_u32_e32 v8, v7, v6
	global_load_dword v7, v[12:13], off offset:2816 sc1
	s_waitcnt vmcnt(0) lgkmcnt(0)
	v_add_u32_e32 v9, v8, v7
	global_load_dword v8, v[12:13], off offset:3072 sc1
	s_waitcnt vmcnt(0) lgkmcnt(0)
	v_add_u32_e32 v10, v9, v8
	global_load_dword v9, v[12:13], off offset:3328 sc1
	s_waitcnt vmcnt(0) lgkmcnt(0)
	v_add_u32_e32 v14, v10, v9
	global_load_dword v10, v[12:13], off offset:3584 sc1
	s_waitcnt vmcnt(0) lgkmcnt(0)
	v_add_u32_e32 v14, v14, v10
	global_load_dword v12, v[12:13], off offset:3840 sc1
	s_waitcnt vmcnt(0) lgkmcnt(0)
	v_add_u32_e32 v16, v14, v12
	v_mov_b64_e32 v[14:15], s[6:7]
	global_load_dword v13, v[14:15], off sc1
	v_mov_b64_e32 v[14:15], s[8:9]
	global_load_dword v14, v[14:15], off sc1
	s_waitcnt vmcnt(0) lgkmcnt(0)
	v_add_u32_e32 v16, v16, v13
	v_add_u32_e32 v18, v16, v14
	v_mov_b64_e32 v[16:17], s[10:11]
	global_load_dword v15, v[16:17], off sc1
	v_mov_b64_e32 v[16:17], s[12:13]
	global_load_dword v16, v[16:17], off sc1
	s_waitcnt vmcnt(0) lgkmcnt(0)
	v_add_u32_e32 v18, v18, v15
	v_add_u32_e32 v17, v18, v16
	v_cmp_ne_u32_e32 vcc, s34, v17
	s_and_saveexec_b64 s[22:23], vcc
	s_cbranch_execz .LBB0_1090
	s_and_b32 s26, s35, 0xff
	s_mov_b64 s[24:25], -1
	s_cmp_eq_u32 s26, 0
	s_mov_b64 s[28:29], -1
	s_mov_b64 s[26:27], -1
	s_sleep 1
	s_cbranch_scc1 .LBB0_1094
	s_and_saveexec_b64 s[30:31], s[28:29]
	s_cbranch_execz .LBB0_1089
	s_branch .LBB0_1097
.LBB0_1094:
	v_mov_b64_e32 v[18:19], s[58:59]
	global_load_dword v17, v[18:19], off offset:512 sc1
	s_mov_b64 s[28:29], 0
	s_waitcnt vmcnt(0) lgkmcnt(0)
	v_cmp_eq_u32_e32 vcc, 0, v17
	s_and_saveexec_b64 s[30:31], vcc
	s_cmp_lt_u32 s35, 0x40001
	s_cselect_b64 s[28:29], -1, 0
	s_xor_b64 s[26:27], exec, -1
	s_and_b64 s[28:29], s[28:29], exec
	s_or_b64 exec, exec, s[30:31]
	s_and_saveexec_b64 s[30:31], s[28:29]
	s_cbranch_execz .LBB0_1089

; __device__ __forceinline__ unsigned xb_ld(unsigned* p)              { return __hip_atomic_load(p, __ATOMIC_RELAXED, __HIP_MEMORY_SCOPE_AGENT); }
; __device__ __forceinline__ unsigned xb_add(unsigned* p, unsigned v) { return __hip_atomic_fetch_add(p, v, __ATOMIC_RELAXED, __HIP_MEMORY_SCOPE_AGENT); }
; #define XB_SPIN(cond, bar) do { unsigned _sp = 0; while (cond) { __builtin_amdgcn_s_sleep(1); \
;     if ((++_sp & 255u) == 0u) { if (xb_ld(&(bar)[XB_TMO])) break; if (_sp > XB_SPIN_CAP) { atomicAdd(&(bar)[XB_TMO], 1u); break; } } } } while (0)
; __device__ __forceinline__ void xcd_barrier(const XcdBarrier& b, int tid) {
;     ...
;         unsigned nloc = b.st[0], nx = b.st[1];
;         if (nloc == 0u) { xcd_barrier_complete(bar, bx_, nloc, nx); b.st[0] = nloc; b.st[1] = nx; }
;         const unsigned old = xb_add(&bar[XB_XSUB(bx_)], 1u);
;         const unsigned gen = old / nloc;
;         if (old + 1u == (gen + 1u) * nloc) {
;             __builtin_amdgcn_fence(__ATOMIC_RELEASE, "agent");
;             asm volatile("s_waitcnt vmcnt(0)" ::: "memory");
;             const unsigned og = xb_add(&bar[XB_TOP], 1u);
;             const unsigned tg = og / nx;
;             if (og + 1u == (tg + 1u) * nx) xb_add(&bar[XB_TOPGEN], 1u);
;             else XB_SPIN(xb_ld(&bar[XB_TOPGEN]) == tg, bar);
;             __builtin_amdgcn_fence(__ATOMIC_ACQUIRE, "agent");
;             xb_add(&bar[XB_XGEN(bx_)], 1u);
;             asm volatile("s_waitcnt vmcnt(0)" ::: "memory");
;         } else {
;             XB_SPIN(xb_ld(&bar[XB_XGEN(bx_)]) == gen, bar);
.LBB0_1101:
	s_lshl_b32 s26, s50, 6
	s_add_i32 s64, s26, 0x500
	s_lshl_b64 s[6:7], s[64:65], 2
	s_add_u32 s6, s58, s6
	s_addc_u32 s7, s59, s7
	v_mov_b64_e32 v[4:5], s[6:7]
	v_mov_b32_e32 v1, 1
	flat_atomic_add v3, v[4:5], v1 sc0
	v_cvt_f32_u32_e32 v1, v2
	v_sub_u32_e32 v4, 0, v2
	v_rcp_iflag_f32_e32 v1, v1
	s_nop 0
	v_mul_f32_e32 v1, 0x4f7ffffe, v1
	v_cvt_u32_f32_e32 v1, v1
	v_mul_lo_u32 v4, v4, v1
	v_mul_hi_u32 v4, v1, v4
	v_add_u32_e32 v1, v1, v4
	s_waitcnt vmcnt(0) lgkmcnt(0)
	v_mul_hi_u32 v1, v3, v1
	v_mul_lo_u32 v4, v1, v2
	v_sub_u32_e32 v4, v3, v4
	v_cmp_ge_u32_e32 vcc, v4, v2
	v_add_u32_e32 v5, 1, v1
	s_nop 0
	v_cndmask_b32_e32 v1, v1, v5, vcc
	v_sub_u32_e32 v5, v4, v2
	v_cndmask_b32_e32 v4, v4, v5, vcc
	v_cmp_ge_u32_e32 vcc, v4, v2
	v_add_u32_e32 v4, 1, v1
	s_nop 0
	v_cndmask_b32_e32 v1, v1, v4, vcc
	v_add_u32_e32 v4, 1, v3
	v_mad_u64_u32 v[2:3], s[6:7], v2, v1, v[2:3]
	v_cmp_ne_u32_e32 vcc, v4, v2
	s_and_saveexec_b64 s[6:7], vcc
	s_xor_b64 s[6:7], exec, s[6:7]
	s_cbranch_execz .LBB0_1114
	s_add_i32 s64, s26, 0x900
	s_lshl_b64 s[8:9], s[64:65], 2
	s_add_u32 s10, s58, s8
	s_addc_u32 s11, s59, s9
	v_mov_b64_e32 v[2:3], s[10:11]
	global_load_dword v0, v[2:3], off sc1
	s_waitcnt vmcnt(0) lgkmcnt(0)
	v_cmp_eq_u32_e32 vcc, v0, v1
	s_and_saveexec_b64 s[8:9], vcc
	s_cbranch_execz .LBB0_1113
	s_mov_b32 s27, 1
	s_mov_b64 s[12:13], 0
	s_branch .LBB0_1105

; __device__ __forceinline__ unsigned xb_ld(unsigned* p)              { return __hip_atomic_load(p, __ATOMIC_RELAXED, __HIP_MEMORY_SCOPE_AGENT); }
; #define XB_SPIN(cond, bar) do { unsigned _sp = 0; while (cond) { __builtin_amdgcn_s_sleep(1); \
;     if ((++_sp & 255u) == 0u) { if (xb_ld(&(bar)[XB_TMO])) break; if (_sp > XB_SPIN_CAP) { atomicAdd(&(bar)[XB_TMO], 1u); break; } } } } while (0)
; __device__ __forceinline__ void xcd_barrier(const XcdBarrier& b, int tid) {
;     ...
;             XB_SPIN(xb_ld(&bar[XB_XGEN(bx_)]) == gen, bar);
.LBB0_1105:
	s_and_b32 s20, s27, 0xff
	s_mov_b64 s[18:19], -1
	s_cmp_lg_u32 s20, 0
	s_mov_b64 s[20:21], -1
	s_sleep 1
	s_cbranch_scc1 .LBB0_1109
	v_mov_b64_e32 v[2:3], s[58:59]
	global_load_dword v0, v[2:3], off offset:512 sc1
	s_mov_b64 s[20:21], 0
	s_mov_b64 s[22:23], -1
	s_waitcnt vmcnt(0) lgkmcnt(0)
	v_cmp_eq_u32_e32 vcc, 0, v0
	s_and_saveexec_b64 s[24:25], vcc
	s_cmp_lt_u32 s27, 0x40001
	s_cselect_b64 s[20:21], -1, 0
	s_xor_b64 s[22:23], exec, -1
	s_and_b64 s[20:21], s[20:21], exec
	s_or_b64 exec, exec, s[24:25]
.LBB0_1109:
	s_andn2_b64 s[16:17], s[16:17], exec
	s_and_b64 s[22:23], s[22:23], exec
	s_or_b64 s[16:17], s[16:17], s[22:23]
	s_and_saveexec_b64 s[22:23], s[20:21]
	s_cbranch_execz .LBB0_1104
	v_mov_b64_e32 v[2:3], s[10:11]
	global_load_dword v0, v[2:3], off sc1
	s_add_i32 s27, s27, 1
	s_or_b64 s[16:17], s[16:17], exec
	s_waitcnt vmcnt(0) lgkmcnt(0)
	v_cmp_ne_u32_e32 vcc, v0, v1
	s_orn2_b64 s[18:19], vcc, exec
	s_branch .LBB0_1104

; __device__ __forceinline__ unsigned xb_ld(unsigned* p)              { return __hip_atomic_load(p, __ATOMIC_RELAXED, __HIP_MEMORY_SCOPE_AGENT); }
; __device__ __forceinline__ unsigned xb_add(unsigned* p, unsigned v) { return __hip_atomic_fetch_add(p, v, __ATOMIC_RELAXED, __HIP_MEMORY_SCOPE_AGENT); }
; #define XB_SPIN(cond, bar) do { unsigned _sp = 0; while (cond) { __builtin_amdgcn_s_sleep(1); \
;     if ((++_sp & 255u) == 0u) { if (xb_ld(&(bar)[XB_TMO])) break; if (_sp > XB_SPIN_CAP) { atomicAdd(&(bar)[XB_TMO], 1u); break; } } } } while (0)
; __device__ __forceinline__ void xcd_barrier(const XcdBarrier& b, int tid) {
;     ...
;         if (old + 1u == (gen + 1u) * nloc) {
;             __builtin_amdgcn_fence(__ATOMIC_RELEASE, "agent");
;             asm volatile("s_waitcnt vmcnt(0)" ::: "memory");
;             const unsigned og = xb_add(&bar[XB_TOP], 1u);
;             const unsigned tg = og / nx;
;             if (og + 1u == (tg + 1u) * nx) xb_add(&bar[XB_TOPGEN], 1u);
;             else XB_SPIN(xb_ld(&bar[XB_TOPGEN]) == tg, bar);
.LBB0_1114:
	s_andn2_saveexec_b64 s[6:7], s[6:7]
	s_cbranch_execz .LBB0_1130
	v_mov_b32_e32 v1, s58
	v_add_co_u32_e32 v2, vcc, 0x3000, v1
	v_mov_b32_e32 v1, s59
	buffer_wbl2 sc1
	s_waitcnt vmcnt(0)
	v_addc_co_u32_e32 v3, vcc, 0, v1, vcc
	v_mov_b32_e32 v1, 1
	flat_atomic_add v1, v[2:3], v1 offset:1024 sc0
	v_cvt_f32_u32_e32 v2, v0
	v_sub_u32_e32 v3, 0, v0
	s_mov_b64 s[10:11], -1
	v_rcp_iflag_f32_e32 v2, v2
	s_nop 0
	v_mul_f32_e32 v2, 0x4f7ffffe, v2
	v_cvt_u32_f32_e32 v2, v2
	v_mul_lo_u32 v3, v3, v2
	v_mul_hi_u32 v3, v2, v3
	v_add_u32_e32 v2, v2, v3
	s_waitcnt vmcnt(0) lgkmcnt(0)
	v_mul_hi_u32 v2, v1, v2
	v_mul_lo_u32 v3, v2, v0
	v_sub_u32_e32 v3, v1, v3
	v_cmp_ge_u32_e32 vcc, v3, v0
	v_add_u32_e32 v4, 1, v2
	s_nop 0
	v_cndmask_b32_e32 v2, v2, v4, vcc
	v_sub_u32_e32 v4, v3, v0
	v_cndmask_b32_e32 v3, v3, v4, vcc
	v_cmp_ge_u32_e32 vcc, v3, v0
	v_add_u32_e32 v3, 1, v2
	s_nop 0
	v_cndmask_b32_e32 v2, v2, v3, vcc
	v_add_u32_e32 v3, 1, v1
	v_mad_u64_u32 v[0:1], s[6:7], v0, v2, v[0:1]
	s_add_u32 s6, s58, 0x3500
	s_addc_u32 s7, s59, 0
	v_cmp_ne_u32_e32 vcc, v3, v0
	v_mov_b64_e32 v[0:1], s[6:7]
	s_and_saveexec_b64 s[8:9], vcc
	s_cbranch_execz .LBB0_1127
	v_mov_b64_e32 v[0:1], s[6:7]
	global_load_dword v0, v[0:1], off sc1
	s_mov_b64 s[14:15], 0
	s_waitcnt vmcnt(0) lgkmcnt(0)
	v_cmp_eq_u32_e32 vcc, v0, v2
	s_and_saveexec_b64 s[12:13], vcc
	s_cbranch_execz .LBB0_1126
	s_add_u32 s10, s58, 0x200
	s_addc_u32 s11, s59, 0
	s_mov_b32 s27, 1
	s_branch .LBB0_1119

; template <int NR> __device__ __forceinline__ void norm_load(unsigned long long (&raw)[NR][4], const bf16* X, int lane) {
; #pragma unroll
;     for (int r = 0; r < NR; ++r) { const unsigned long long* xr = (const unsigned long long*)(X + (size_t)r * D) + lane;
; #pragma unroll
;         for (int j = 0; j < 4; ++j) raw[r][j] = xr[64 * j]; }
; }
; template <int MODE>
; __device__ __forceinline__ void phase_norm(const float* Xp32, const float* Xs32, bf16* X, bf16* H, const float* nw, const float* mod_sh, const float* mod_sc, int gw, int NGW, int lane) {
;     ...
;     for (int b = gw; b < MP / 8; b += NGW) {
;         const int ci = b >> 8; f32x4 mul[4], sh[4];
;         const size_t ro = (size_t)b * 8 * D;
;         const f32x4* shp = (const f32x4*)(mod_sh + (size_t)ci * MODLD) + lane; const f32x4* scp = (const f32x4*)(mod_sc + (size_t)ci * MODLD) + lane;
;         if constexpr (MODE == 1) {
; #pragma unroll
;             for (int j = 0; j < 4; ++j) { sh[j] = shp[64 * j]; mul[j] = w4[j] * (scp[64 * j] + 1.0f); }
;             norm_rows<MODE, 4>(Xp32 + ro, X + ro, H + ro, nullptr, mul, sh, lane);
;             norm_rows<MODE, 4>(Xp32 + ro + 4 * D, X + ro + 4 * D, H + ro + 4 * D, nullptr, mul, sh, lane);
;         } else {
;             unsigned long long raw[8][4]; norm_load<8>(raw, X + ro, lane); asm volatile("" ::: "memory");
; #pragma unroll
;             for (int j = 0; j < 4; ++j) { sh[j] = shp[64 * j]; mul[j] = w4[j] * (scp[64 * j] + 1.0f); }
;             norm_finish<MODE, 8>(raw, H + ro, nullptr, mul, sh, lane);
.LBB0_1132:
	v_add_co_u32_e32 v20, vcc, 0xfbefc200, v38
	s_ashr_i32 s9, s3, 8
	s_nop 0
	v_addc_co_u32_e32 v21, vcc, -1, v39, vcc
	global_load_dwordx2 v[112:113], v[20:21], off
	v_add_co_u32_e32 v20, vcc, 0xfbefc400, v38
	v_mad_i64_i32 v[32:33], s[10:11], s9, v132, v[8:9]
	s_nop 0
	v_addc_co_u32_e32 v21, vcc, -1, v39, vcc
	global_load_dwordx2 v[114:115], v[20:21], off
	v_add_co_u32_e32 v20, vcc, 0xfbefc600, v38
	v_mad_i64_i32 v[52:53], s[10:11], s9, v132, v[36:37]
	s_nop 0
	v_addc_co_u32_e32 v21, vcc, -1, v39, vcc
	global_load_dwordx2 v[116:117], v[20:21], off
	v_add_co_u32_e32 v20, vcc, 0xfbefc800, v38
	s_add_i32 s3, s3, s96
	s_nop 0
	v_addc_co_u32_e32 v21, vcc, -1, v39, vcc
	global_load_dwordx2 v[118:119], v[20:21], off
	v_add_co_u32_e32 v20, vcc, 0xfbefca00, v38
	s_cmpk_gt_i32 s3, 0x7ff
	s_nop 0
	v_addc_co_u32_e32 v21, vcc, -1, v39, vcc
	global_load_dwordx2 v[104:105], v[20:21], off
	v_add_co_u32_e32 v20, vcc, 0xfbefcc00, v38
	s_waitcnt vmcnt(0) lgkmcnt(0)
	v_and_b32_e32 v125, 0xffff0000, v114
	v_addc_co_u32_e32 v21, vcc, -1, v39, vcc
	global_load_dwordx2 v[106:107], v[20:21], off
	v_add_co_u32_e32 v20, vcc, 0xfbefce00, v38
	v_mul_f32_e32 v126, v125, v125
	s_nop 0
	v_addc_co_u32_e32 v21, vcc, -1, v39, vcc
	global_load_dwordx2 v[108:109], v[20:21], off
	v_add_co_u32_e32 v20, vcc, 0xfbefd000, v38
	s_nop 1
	v_addc_co_u32_e32 v21, vcc, -1, v39, vcc
	global_load_dwordx2 v[110:111], v[20:21], off
	v_add_co_u32_e32 v20, vcc, 0xfbefd200, v38
	s_nop 1
	v_addc_co_u32_e32 v21, vcc, -1, v39, vcc
	global_load_dwordx2 v[96:97], v[20:21], off
	v_add_co_u32_e32 v20, vcc, 0xfbefd400, v38
	s_nop 1
	v_addc_co_u32_e32 v21, vcc, -1, v39, vcc
	global_load_dwordx2 v[98:99], v[20:21], off
	v_add_co_u32_e32 v20, vcc, 0xfbefd600, v38
	s_nop 1
	v_addc_co_u32_e32 v21, vcc, -1, v39, vcc
	global_load_dwordx2 v[100:101], v[20:21], off
	v_add_co_u32_e32 v20, vcc, 0xfbefd800, v38
	s_nop 1
	v_addc_co_u32_e32 v21, vcc, -1, v39, vcc
	global_load_dwordx2 v[102:103], v[20:21], off
	v_add_co_u32_e32 v20, vcc, 0xfbefda00, v38
	s_nop 1
	v_addc_co_u32_e32 v21, vcc, -1, v39, vcc
	global_load_dwordx2 v[88:89], v[20:21], off
	v_add_co_u32_e32 v20, vcc, 0xfbefdc00, v38
	s_nop 1
	v_addc_co_u32_e32 v21, vcc, -1, v39, vcc
	global_load_dwordx2 v[90:91], v[20:21], off
	v_add_co_u32_e32 v20, vcc, 0xfbefde00, v38
	s_nop 1
	v_addc_co_u32_e32 v21, vcc, -1, v39, vcc
	global_load_dwordx2 v[92:93], v[20:21], off
	v_add_co_u32_e32 v20, vcc, 0xfbefe000, v38
	s_nop 1
	v_addc_co_u32_e32 v21, vcc, -1, v39, vcc
	global_load_dwordx2 v[94:95], v[20:21], off
	v_add_co_u32_e32 v20, vcc, 0xfbefe200, v38
	s_nop 1
	v_addc_co_u32_e32 v21, vcc, -1, v39, vcc
	global_load_dwordx2 v[80:81], v[20:21], off
	v_add_co_u32_e32 v20, vcc, 0xfbefe400, v38
	s_nop 1
	v_addc_co_u32_e32 v21, vcc, -1, v39, vcc
	global_load_dwordx2 v[82:83], v[20:21], off
	v_add_co_u32_e32 v20, vcc, 0xfbefe600, v38
	s_nop 1
	v_addc_co_u32_e32 v21, vcc, -1, v39, vcc
	global_load_dwordx2 v[84:85], v[20:21], off
	v_add_co_u32_e32 v20, vcc, 0xfbefe800, v38
	s_nop 1
	v_addc_co_u32_e32 v21, vcc, -1, v39, vcc
	global_load_dwordx2 v[86:87], v[20:21], off
	v_add_co_u32_e32 v20, vcc, 0xfbefea00, v38
	s_nop 1
	v_addc_co_u32_e32 v21, vcc, -1, v39, vcc
	global_load_dwordx2 v[72:73], v[20:21], off
	v_add_co_u32_e32 v20, vcc, 0xfbefec00, v38
	s_nop 1
	v_addc_co_u32_e32 v21, vcc, -1, v39, vcc
	global_load_dwordx2 v[74:75], v[20:21], off
	v_add_co_u32_e32 v20, vcc, 0xfbefee00, v38
	s_nop 1
	v_addc_co_u32_e32 v21, vcc, -1, v39, vcc
	global_load_dwordx2 v[76:77], v[20:21], off
	v_add_co_u32_e32 v20, vcc, 0xfbeff000, v38
	s_nop 1
	v_addc_co_u32_e32 v21, vcc, -1, v39, vcc
	global_load_dwordx2 v[78:79], v[20:21], off
	v_add_co_u32_e32 v20, vcc, 0xfbeff200, v38
	s_nop 1
	v_addc_co_u32_e32 v21, vcc, -1, v39, vcc
	global_load_dwordx2 v[64:65], v[20:21], off
	v_add_co_u32_e32 v20, vcc, 0xfbeff400, v38
	s_nop 1
	v_addc_co_u32_e32 v21, vcc, -1, v39, vcc
	global_load_dwordx2 v[66:67], v[20:21], off
	v_add_co_u32_e32 v20, vcc, 0xfbeff600, v38
	s_nop 1
	v_addc_co_u32_e32 v21, vcc, -1, v39, vcc
	global_load_dwordx2 v[68:69], v[20:21], off
	v_add_co_u32_e32 v20, vcc, 0xfbeff800, v38
	s_nop 1
	v_addc_co_u32_e32 v21, vcc, -1, v39, vcc
	global_load_dwordx2 v[70:71], v[20:21], off
	v_add_co_u32_e32 v20, vcc, 0xfbeffa00, v38
	s_nop 1
	v_addc_co_u32_e32 v21, vcc, -1, v39, vcc
	global_load_dwordx2 v[56:57], v[20:21], off
	v_add_co_u32_e32 v20, vcc, 0xfbeffc00, v38
	s_nop 1
	v_addc_co_u32_e32 v21, vcc, -1, v39, vcc
	global_load_dwordx2 v[58:59], v[20:21], off
	v_add_co_u32_e32 v20, vcc, 0xfbeffe00, v38
	s_nop 1
	v_addc_co_u32_e32 v21, vcc, -1, v39, vcc
	global_load_dwordx2 v[60:61], v[20:21], off
	v_add_co_u32_e32 v20, vcc, 0xfbf00000, v38
	s_nop 1
	v_addc_co_u32_e32 v21, vcc, -1, v39, vcc
	global_load_dwordx2 v[62:63], v[20:21], off
	global_load_dwordx4 v[28:31], v[32:33], off
	global_load_dwordx4 v[20:23], v[52:53], off
	s_waitcnt vmcnt(0) lgkmcnt(0)
	v_pk_add_f32 v[22:23], v[22:23], 1.0 op_sel_hi:[1,0]
	v_pk_add_f32 v[20:21], v[20:21], 1.0 op_sel_hi:[1,0]
	v_pk_mul_f32 v[40:41], v[2:3], v[22:23]
	v_pk_mul_f32 v[42:43], v[0:1], v[20:21]
	global_load_dwordx4 v[20:23], v[32:33], off offset:1024
	global_load_dwordx4 v[24:27], v[52:53], off offset:1024
	s_waitcnt vmcnt(0) lgkmcnt(0)
	v_pk_add_f32 v[26:27], v[26:27], 1.0 op_sel_hi:[1,0]
	v_pk_add_f32 v[24:25], v[24:25], 1.0 op_sel_hi:[1,0]
	v_pk_mul_f32 v[44:45], v[6:7], v[26:27]
	v_pk_mul_f32 v[46:47], v[4:5], v[24:25]
	global_load_dwordx4 v[24:27], v[32:33], off offset:2048
	global_load_dwordx4 v[48:51], v[52:53], off offset:2048
	s_waitcnt vmcnt(0) lgkmcnt(0)
; __device__ __forceinline__ unsigned pk2(float lo, float hi) { unsigned r; asm("v_cvt_pk_bf16_f32 %0, %1, %2" : "=v"(r) : "v"(lo), "v"(hi)); return r; }
; __device__ __forceinline__ f32x4 unpack4(unsigned long long w) { const unsigned lo = (unsigned)w, hi = (unsigned)(w >> 32); return (f32x4){__uint_as_float(lo << 16), __uint_as_float(lo & 0xffff0000u), __uint_as_float(hi << 16), __uint_as_float(hi & 0xffff0000u)}; }
; template <int MODE, int NR>
; __device__ __forceinline__ void norm_finish(const unsigned long long (&raw)[NR][4], bf16* H, float* out32, const f32x4 (&mul)[4], const f32x4 (&sh)[4], int lane) {
; #pragma unroll
;     for (int r = 0; r < NR; ++r) { f32x4 v[4]; float s = 0.f;
; #pragma unroll
;         for (int j = 0; j < 4; ++j) { v[j] = unpack4(raw[r][j]); s += (v[j].x * v[j].x + v[j].y * v[j].y) + (v[j].z * v[j].z + v[j].w * v[j].w); }
;         const float rstd = rsqrtf(wave_sum(s) * (1.f / D) + EPS);
;         if constexpr (MODE == 2) { f32x4* o = (f32x4*)(out32 + (size_t)r * D) + lane;
; #pragma unroll
;             for (int j = 0; j < 4; ++j) o[64 * j] = v[j] * rstd * mul[j];
;         } else { unsigned long long* o8 = (unsigned long long*)(H + (size_t)r * D) + lane;
; #pragma unroll
;             for (int j = 0; j < 4; ++j) { const f32x4 y = v[j] * rstd * mul[j] + sh[j]; o8[64 * j] = (unsigned long long)pk2(y.x, y.y) | ((unsigned long long)pk2(y.z, y.w) << 32); } } }
	v_pk_add_f32 v[34:35], v[50:51], 1.0 op_sel_hi:[1,0]
	v_pk_add_f32 v[50:51], v[48:49], 1.0 op_sel_hi:[1,0]
	v_pk_mul_f32 v[48:49], v[14:15], v[34:35]
	global_load_dwordx4 v[32:35], v[32:33], off offset:3072
	s_nop 0
	global_load_dwordx4 v[52:55], v[52:53], off offset:3072
	v_pk_mul_f32 v[50:51], v[12:13], v[50:51]
	s_waitcnt vmcnt(0) lgkmcnt(0)
	v_pk_add_f32 v[54:55], v[54:55], 1.0 op_sel_hi:[1,0]
	v_pk_add_f32 v[122:123], v[52:53], 1.0 op_sel_hi:[1,0]
	v_pk_mul_f32 v[52:53], v[18:19], v[54:55]
	v_pk_mul_f32 v[54:55], v[16:17], v[122:123]
	v_lshlrev_b32_e32 v122, 16, v112
	v_and_b32_e32 v123, 0xffff0000, v112
	v_lshlrev_b32_e32 v112, 16, v113
	v_and_b32_e32 v113, 0xffff0000, v113
	v_mul_f32_e32 v121, v123, v123
	v_mul_f32_e32 v124, v113, v113
	v_fmac_f32_e32 v121, v122, v122
	v_fmac_f32_e32 v124, v112, v112
	v_add_f32_e32 v121, v121, v124
	v_lshlrev_b32_e32 v124, 16, v114
	v_lshlrev_b32_e32 v114, 16, v115
	v_and_b32_e32 v115, 0xffff0000, v115
	v_mul_f32_e32 v127, v115, v115
	v_fmac_f32_e32 v126, v124, v124
	v_fmac_f32_e32 v127, v114, v114
	v_add_f32_e32 v126, v126, v127
	v_add_f32_e32 v121, v121, v126
	v_lshlrev_b32_e32 v126, 16, v116
	v_and_b32_e32 v127, 0xffff0000, v116
	v_lshlrev_b32_e32 v116, 16, v117
	v_and_b32_e32 v117, 0xffff0000, v117
	v_mul_f32_e32 v128, v127, v127
	v_mul_f32_e32 v129, v117, v117
	v_fmac_f32_e32 v128, v126, v126
	v_fmac_f32_e32 v129, v116, v116
	v_add_f32_e32 v128, v128, v129
	v_add_f32_e32 v121, v121, v128
	v_lshlrev_b32_e32 v128, 16, v118
	v_and_b32_e32 v129, 0xffff0000, v118
	v_lshlrev_b32_e32 v118, 16, v119
	v_and_b32_e32 v119, 0xffff0000, v119
	v_mul_f32_e32 v130, v129, v129
	v_mul_f32_e32 v131, v119, v119
	v_fmac_f32_e32 v130, v128, v128
	v_fmac_f32_e32 v131, v118, v118
	v_add_f32_e32 v130, v130, v131
	v_add_f32_e32 v121, v121, v130
	ds_swizzle_b32 v130, v121 offset:swizzle(SWAP,1)
	s_waitcnt lgkmcnt(0)
	v_add_f32_e32 v121, v121, v130
	ds_swizzle_b32 v130, v121 offset:swizzle(SWAP,2)
	s_waitcnt lgkmcnt(0)
	v_add_f32_e32 v121, v121, v130
	ds_swizzle_b32 v130, v121 offset:swizzle(SWAP,4)
	s_waitcnt lgkmcnt(0)
	v_add_f32_e32 v121, v121, v130
	ds_swizzle_b32 v130, v121 offset:swizzle(SWAP,8)
	s_waitcnt lgkmcnt(0)
	v_add_f32_e32 v121, v121, v130
	ds_swizzle_b32 v130, v121 offset:swizzle(SWAP,16)
	s_waitcnt lgkmcnt(0)
	v_add_f32_e32 v121, v121, v130
	v_mov_b32_e32 v130, v121
	s_nop 1
	v_permlane32_swap_b32_e32 v121, v130
	v_add_f32_e32 v121, v121, v130
	v_fmamk_f32 v121, v121, 0x3a800000, v176
	v_cmp_gt_f32_e32 vcc, s33, v121
	v_mul_f32_e32 v130, 0x4b800000, v121
	s_nop 0
	v_cndmask_b32_e32 v121, v121, v130, vcc
	v_rsq_f32_e32 v121, v121
	s_nop 0
	v_mul_f32_e32 v130, 0x45800000, v121
	v_cndmask_b32_e32 v130, v121, v130, vcc
	v_pk_mul_f32 v[122:123], v[122:123], v[130:131] op_sel_hi:[1,0]
	v_pk_mul_f32 v[112:113], v[112:113], v[130:131] op_sel_hi:[1,0]
	v_pk_fma_f32 v[122:123], v[42:43], v[122:123], v[28:29]
	v_pk_fma_f32 v[112:113], v[40:41], v[112:113], v[30:31]
	v_cvt_pk_bf16_f32 v122, v122, v123
	v_pk_mul_f32 v[114:115], v[114:115], v[130:131] op_sel_hi:[1,0]
	v_cvt_pk_bf16_f32 v123, v112, v113
	v_add_co_u32_e32 v112, vcc, s12, v38
	v_pk_fma_f32 v[114:115], v[44:45], v[114:115], v[22:23]
	s_nop 0
	v_addc_co_u32_e32 v113, vcc, -1, v39, vcc
	global_store_dwordx2 v[112:113], v[122:123], off
	v_pk_mul_f32 v[112:113], v[124:125], v[130:131] op_sel_hi:[1,0]
	s_nop 0
	v_pk_fma_f32 v[112:113], v[46:47], v[112:113], v[20:21]
	s_nop 0
	v_cvt_pk_bf16_f32 v112, v112, v113
	v_cvt_pk_bf16_f32 v113, v114, v115
	v_add_co_u32_e32 v114, vcc, s13, v38
	s_nop 1
	v_addc_co_u32_e32 v115, vcc, -1, v39, vcc
	global_store_dwordx2 v[114:115], v[112:113], off
	v_pk_mul_f32 v[112:113], v[126:127], v[130:131] op_sel_hi:[1,0]
	v_pk_mul_f32 v[114:115], v[116:117], v[130:131] op_sel_hi:[1,0]
	v_pk_fma_f32 v[112:113], v[50:51], v[112:113], v[24:25]
	v_pk_fma_f32 v[114:115], v[48:49], v[114:115], v[26:27]
	v_cvt_pk_bf16_f32 v112, v112, v113
	s_nop 0
	v_cvt_pk_bf16_f32 v113, v114, v115
	v_add_co_u32_e32 v114, vcc, s14, v38
	s_nop 1
	v_addc_co_u32_e32 v115, vcc, -1, v39, vcc
	global_store_dwordx2 v[114:115], v[112:113], off
	v_pk_mul_f32 v[112:113], v[128:129], v[130:131] op_sel_hi:[1,0]
	v_pk_mul_f32 v[114:115], v[118:119], v[130:131] op_sel_hi:[1,0]
	v_pk_fma_f32 v[112:113], v[54:55], v[112:113], v[32:33]
	v_pk_fma_f32 v[114:115], v[52:53], v[114:115], v[34:35]
	v_cvt_pk_bf16_f32 v112, v112, v113
	s_nop 0
	v_cvt_pk_bf16_f32 v113, v114, v115
	v_add_co_u32_e32 v114, vcc, s15, v38
	s_nop 1
	v_addc_co_u32_e32 v115, vcc, -1, v39, vcc
	global_store_dwordx2 v[114:115], v[112:113], off
	v_lshlrev_b32_e32 v112, 16, v104
	v_and_b32_e32 v113, 0xffff0000, v104
	v_lshlrev_b32_e32 v104, 16, v105
	v_and_b32_e32 v105, 0xffff0000, v105
	v_mul_f32_e32 v114, v113, v113
	v_mul_f32_e32 v115, v105, v105
	v_fmac_f32_e32 v114, v112, v112
	v_fmac_f32_e32 v115, v104, v104
	v_add_f32_e32 v116, v114, v115
	v_lshlrev_b32_e32 v114, 16, v106
	v_and_b32_e32 v115, 0xffff0000, v106
	v_lshlrev_b32_e32 v106, 16, v107
	v_and_b32_e32 v107, 0xffff0000, v107
	v_mul_f32_e32 v117, v115, v115
	v_mul_f32_e32 v118, v107, v107
	v_fmac_f32_e32 v117, v114, v114
	v_fmac_f32_e32 v118, v106, v106
	v_add_f32_e32 v117, v117, v118
	v_add_f32_e32 v118, v116, v117
	v_lshlrev_b32_e32 v116, 16, v108
	v_and_b32_e32 v117, 0xffff0000, v108
	v_lshlrev_b32_e32 v108, 16, v109
	v_and_b32_e32 v109, 0xffff0000, v109
	v_mul_f32_e32 v119, v117, v117
	v_mul_f32_e32 v121, v109, v109
	v_fmac_f32_e32 v119, v116, v116
	v_fmac_f32_e32 v121, v108, v108
	v_add_f32_e32 v119, v119, v121
	v_add_f32_e32 v121, v118, v119
	v_lshlrev_b32_e32 v118, 16, v110
	v_and_b32_e32 v119, 0xffff0000, v110
	v_lshlrev_b32_e32 v110, 16, v111
	v_and_b32_e32 v111, 0xffff0000, v111
	v_mul_f32_e32 v122, v119, v119
	v_mul_f32_e32 v123, v111, v111
	v_fmac_f32_e32 v122, v118, v118
	v_fmac_f32_e32 v123, v110, v110
	v_add_f32_e32 v122, v122, v123
	v_add_f32_e32 v121, v121, v122
	ds_swizzle_b32 v122, v121 offset:swizzle(SWAP,1)
	s_waitcnt lgkmcnt(0)
; __device__ __forceinline__ unsigned pk2(float lo, float hi) { unsigned r; asm("v_cvt_pk_bf16_f32 %0, %1, %2" : "=v"(r) : "v"(lo), "v"(hi)); return r; }
; __device__ __forceinline__ f32x4 unpack4(unsigned long long w) { const unsigned lo = (unsigned)w, hi = (unsigned)(w >> 32); return (f32x4){__uint_as_float(lo << 16), __uint_as_float(lo & 0xffff0000u), __uint_as_float(hi << 16), __uint_as_float(hi & 0xffff0000u)}; }
; template <int MODE, int NR>
; __device__ __forceinline__ void norm_finish(const unsigned long long (&raw)[NR][4], bf16* H, float* out32, const f32x4 (&mul)[4], const f32x4 (&sh)[4], int lane) {
; #pragma unroll
;     for (int r = 0; r < NR; ++r) { f32x4 v[4]; float s = 0.f;
; #pragma unroll
;         for (int j = 0; j < 4; ++j) { v[j] = unpack4(raw[r][j]); s += (v[j].x * v[j].x + v[j].y * v[j].y) + (v[j].z * v[j].z + v[j].w * v[j].w); }
;         const float rstd = rsqrtf(wave_sum(s) * (1.f / D) + EPS);
;         if constexpr (MODE == 2) { f32x4* o = (f32x4*)(out32 + (size_t)r * D) + lane;
; #pragma unroll
;             for (int j = 0; j < 4; ++j) o[64 * j] = v[j] * rstd * mul[j];
;         } else { unsigned long long* o8 = (unsigned long long*)(H + (size_t)r * D) + lane;
; #pragma unroll
;             for (int j = 0; j < 4; ++j) { const f32x4 y = v[j] * rstd * mul[j] + sh[j]; o8[64 * j] = (unsigned long long)pk2(y.x, y.y) | ((unsigned long long)pk2(y.z, y.w) << 32); } } }
	v_add_f32_e32 v121, v121, v122
	ds_swizzle_b32 v122, v121 offset:swizzle(SWAP,2)
	s_waitcnt lgkmcnt(0)
	v_add_f32_e32 v121, v121, v122
	ds_swizzle_b32 v122, v121 offset:swizzle(SWAP,4)
	s_waitcnt lgkmcnt(0)
	v_add_f32_e32 v121, v121, v122
	ds_swizzle_b32 v122, v121 offset:swizzle(SWAP,8)
	s_waitcnt lgkmcnt(0)
	v_add_f32_e32 v121, v121, v122
	ds_swizzle_b32 v122, v121 offset:swizzle(SWAP,16)
	s_waitcnt lgkmcnt(0)
	v_add_f32_e32 v121, v121, v122
	v_mov_b32_e32 v122, v121
	s_nop 1
	v_permlane32_swap_b32_e32 v121, v122
	v_add_f32_e32 v121, v121, v122
	v_fmamk_f32 v121, v121, 0x3a800000, v176
	v_cmp_gt_f32_e32 vcc, s33, v121
	v_mul_f32_e32 v122, 0x4b800000, v121
	s_nop 0
	v_cndmask_b32_e32 v121, v121, v122, vcc
	v_rsq_f32_e32 v121, v121
	s_nop 0
	v_mul_f32_e32 v122, 0x45800000, v121
	v_cndmask_b32_e32 v122, v121, v122, vcc
	v_pk_mul_f32 v[112:113], v[112:113], v[122:123] op_sel_hi:[1,0]
	v_pk_mul_f32 v[104:105], v[104:105], v[122:123] op_sel_hi:[1,0]
	v_pk_fma_f32 v[112:113], v[42:43], v[112:113], v[28:29]
	v_pk_fma_f32 v[104:105], v[40:41], v[104:105], v[30:31]
	v_cvt_pk_bf16_f32 v112, v112, v113
	v_pk_mul_f32 v[106:107], v[106:107], v[122:123] op_sel_hi:[1,0]
	v_cvt_pk_bf16_f32 v113, v104, v105
	v_add_co_u32_e32 v104, vcc, s16, v38
	v_pk_fma_f32 v[106:107], v[44:45], v[106:107], v[22:23]
	s_nop 0
	v_addc_co_u32_e32 v105, vcc, -1, v39, vcc
	global_store_dwordx2 v[104:105], v[112:113], off
	v_pk_mul_f32 v[104:105], v[114:115], v[122:123] op_sel_hi:[1,0]
	s_nop 0
	v_pk_fma_f32 v[104:105], v[46:47], v[104:105], v[20:21]
	s_nop 0
	v_cvt_pk_bf16_f32 v104, v104, v105
	v_cvt_pk_bf16_f32 v105, v106, v107
	v_add_co_u32_e32 v106, vcc, s17, v38
	s_nop 1
	v_addc_co_u32_e32 v107, vcc, -1, v39, vcc
	global_store_dwordx2 v[106:107], v[104:105], off
	v_pk_mul_f32 v[104:105], v[116:117], v[122:123] op_sel_hi:[1,0]
	v_pk_mul_f32 v[106:107], v[108:109], v[122:123] op_sel_hi:[1,0]
	v_pk_fma_f32 v[104:105], v[50:51], v[104:105], v[24:25]
	v_pk_fma_f32 v[106:107], v[48:49], v[106:107], v[26:27]
	v_cvt_pk_bf16_f32 v104, v104, v105
	s_nop 0
	v_cvt_pk_bf16_f32 v105, v106, v107
	v_add_co_u32_e32 v106, vcc, s18, v38
	s_nop 1
	v_addc_co_u32_e32 v107, vcc, -1, v39, vcc
	global_store_dwordx2 v[106:107], v[104:105], off
	v_pk_mul_f32 v[104:105], v[118:119], v[122:123] op_sel_hi:[1,0]
	v_pk_mul_f32 v[106:107], v[110:111], v[122:123] op_sel_hi:[1,0]
	v_pk_fma_f32 v[104:105], v[54:55], v[104:105], v[32:33]
	v_pk_fma_f32 v[106:107], v[52:53], v[106:107], v[34:35]
	v_cvt_pk_bf16_f32 v104, v104, v105
	s_nop 0
	v_cvt_pk_bf16_f32 v105, v106, v107
	v_add_co_u32_e32 v106, vcc, s19, v38
	s_nop 1
	v_addc_co_u32_e32 v107, vcc, -1, v39, vcc
	global_store_dwordx2 v[106:107], v[104:105], off
	v_lshlrev_b32_e32 v104, 16, v96
	v_and_b32_e32 v105, 0xffff0000, v96
	v_lshlrev_b32_e32 v96, 16, v97
	v_and_b32_e32 v97, 0xffff0000, v97
	v_mul_f32_e32 v106, v105, v105
	v_mul_f32_e32 v107, v97, v97
	v_fmac_f32_e32 v106, v104, v104
	v_fmac_f32_e32 v107, v96, v96
	v_add_f32_e32 v108, v106, v107
	v_lshlrev_b32_e32 v106, 16, v98
	v_and_b32_e32 v107, 0xffff0000, v98
	v_lshlrev_b32_e32 v98, 16, v99
	v_and_b32_e32 v99, 0xffff0000, v99
	v_mul_f32_e32 v109, v107, v107
	v_mul_f32_e32 v110, v99, v99
	v_fmac_f32_e32 v109, v106, v106
	v_fmac_f32_e32 v110, v98, v98
	v_add_f32_e32 v109, v109, v110
	v_add_f32_e32 v110, v108, v109
	v_lshlrev_b32_e32 v108, 16, v100
	v_and_b32_e32 v109, 0xffff0000, v100
	v_lshlrev_b32_e32 v100, 16, v101
	v_and_b32_e32 v101, 0xffff0000, v101
	v_mul_f32_e32 v111, v109, v109
	v_mul_f32_e32 v112, v101, v101
	v_fmac_f32_e32 v111, v108, v108
	v_fmac_f32_e32 v112, v100, v100
	v_add_f32_e32 v111, v111, v112
	v_add_f32_e32 v112, v110, v111
	v_lshlrev_b32_e32 v110, 16, v102
	v_and_b32_e32 v111, 0xffff0000, v102
	v_lshlrev_b32_e32 v102, 16, v103
	v_and_b32_e32 v103, 0xffff0000, v103
	v_mul_f32_e32 v113, v111, v111
	v_mul_f32_e32 v114, v103, v103
	v_fmac_f32_e32 v113, v110, v110
	v_fmac_f32_e32 v114, v102, v102
	v_add_f32_e32 v113, v113, v114
	v_add_f32_e32 v112, v112, v113
	ds_swizzle_b32 v113, v112 offset:swizzle(SWAP,1)
	s_waitcnt lgkmcnt(0)
	v_add_f32_e32 v112, v112, v113
	ds_swizzle_b32 v113, v112 offset:swizzle(SWAP,2)
	s_waitcnt lgkmcnt(0)
	v_add_f32_e32 v112, v112, v113
	ds_swizzle_b32 v113, v112 offset:swizzle(SWAP,4)
	s_waitcnt lgkmcnt(0)
	v_add_f32_e32 v112, v112, v113
	ds_swizzle_b32 v113, v112 offset:swizzle(SWAP,8)
	s_waitcnt lgkmcnt(0)
	v_add_f32_e32 v112, v112, v113
	ds_swizzle_b32 v113, v112 offset:swizzle(SWAP,16)
	s_waitcnt lgkmcnt(0)
; __device__ __forceinline__ unsigned pk2(float lo, float hi) { unsigned r; asm("v_cvt_pk_bf16_f32 %0, %1, %2" : "=v"(r) : "v"(lo), "v"(hi)); return r; }
; __device__ __forceinline__ f32x4 unpack4(unsigned long long w) { const unsigned lo = (unsigned)w, hi = (unsigned)(w >> 32); return (f32x4){__uint_as_float(lo << 16), __uint_as_float(lo & 0xffff0000u), __uint_as_float(hi << 16), __uint_as_float(hi & 0xffff0000u)}; }
; template <int MODE, int NR>
; __device__ __forceinline__ void norm_finish(const unsigned long long (&raw)[NR][4], bf16* H, float* out32, const f32x4 (&mul)[4], const f32x4 (&sh)[4], int lane) {
; #pragma unroll
;     for (int r = 0; r < NR; ++r) { f32x4 v[4]; float s = 0.f;
; #pragma unroll
;         for (int j = 0; j < 4; ++j) { v[j] = unpack4(raw[r][j]); s += (v[j].x * v[j].x + v[j].y * v[j].y) + (v[j].z * v[j].z + v[j].w * v[j].w); }
;         const float rstd = rsqrtf(wave_sum(s) * (1.f / D) + EPS);
;         if constexpr (MODE == 2) { f32x4* o = (f32x4*)(out32 + (size_t)r * D) + lane;
; #pragma unroll
;             for (int j = 0; j < 4; ++j) o[64 * j] = v[j] * rstd * mul[j];
;         } else { unsigned long long* o8 = (unsigned long long*)(H + (size_t)r * D) + lane;
; #pragma unroll
;             for (int j = 0; j < 4; ++j) { const f32x4 y = v[j] * rstd * mul[j] + sh[j]; o8[64 * j] = (unsigned long long)pk2(y.x, y.y) | ((unsigned long long)pk2(y.z, y.w) << 32); } } }
	v_add_f32_e32 v112, v112, v113
	v_mov_b32_e32 v113, v112
	s_nop 1
	v_permlane32_swap_b32_e32 v112, v113
	v_add_f32_e32 v112, v112, v113
	v_fmamk_f32 v112, v112, 0x3a800000, v176
	v_cmp_gt_f32_e32 vcc, s33, v112
	v_mul_f32_e32 v113, 0x4b800000, v112
	s_nop 0
	v_cndmask_b32_e32 v112, v112, v113, vcc
	v_rsq_f32_e32 v112, v112
	s_nop 0
	v_mul_f32_e32 v113, 0x45800000, v112
	v_cndmask_b32_e32 v112, v112, v113, vcc
	v_pk_mul_f32 v[104:105], v[104:105], v[112:113] op_sel_hi:[1,0]
	v_pk_mul_f32 v[96:97], v[96:97], v[112:113] op_sel_hi:[1,0]
	v_pk_fma_f32 v[104:105], v[42:43], v[104:105], v[28:29]
	v_pk_fma_f32 v[96:97], v[40:41], v[96:97], v[30:31]
	v_cvt_pk_bf16_f32 v104, v104, v105
	v_pk_mul_f32 v[98:99], v[98:99], v[112:113] op_sel_hi:[1,0]
	v_cvt_pk_bf16_f32 v105, v96, v97
	v_add_co_u32_e32 v96, vcc, s20, v38
	v_pk_fma_f32 v[98:99], v[44:45], v[98:99], v[22:23]
	s_nop 0
	v_addc_co_u32_e32 v97, vcc, -1, v39, vcc
	global_store_dwordx2 v[96:97], v[104:105], off
	v_pk_mul_f32 v[96:97], v[106:107], v[112:113] op_sel_hi:[1,0]
	s_nop 0
	v_pk_fma_f32 v[96:97], v[46:47], v[96:97], v[20:21]
	s_nop 0
	v_cvt_pk_bf16_f32 v96, v96, v97
	v_cvt_pk_bf16_f32 v97, v98, v99
	v_add_co_u32_e32 v98, vcc, s21, v38
	s_nop 1
	v_addc_co_u32_e32 v99, vcc, -1, v39, vcc
	global_store_dwordx2 v[98:99], v[96:97], off
	v_pk_mul_f32 v[96:97], v[108:109], v[112:113] op_sel_hi:[1,0]
	v_pk_mul_f32 v[98:99], v[100:101], v[112:113] op_sel_hi:[1,0]
	v_pk_fma_f32 v[96:97], v[50:51], v[96:97], v[24:25]
	v_pk_fma_f32 v[98:99], v[48:49], v[98:99], v[26:27]
	v_cvt_pk_bf16_f32 v96, v96, v97
	s_nop 0
	v_cvt_pk_bf16_f32 v97, v98, v99
	v_add_co_u32_e32 v98, vcc, s22, v38
	s_nop 1
	v_addc_co_u32_e32 v99, vcc, -1, v39, vcc
	global_store_dwordx2 v[98:99], v[96:97], off
	v_pk_mul_f32 v[96:97], v[110:111], v[112:113] op_sel_hi:[1,0]
	v_pk_mul_f32 v[98:99], v[102:103], v[112:113] op_sel_hi:[1,0]
	v_pk_fma_f32 v[96:97], v[54:55], v[96:97], v[32:33]
	v_pk_fma_f32 v[98:99], v[52:53], v[98:99], v[34:35]
	v_cvt_pk_bf16_f32 v96, v96, v97
	s_nop 0
	v_cvt_pk_bf16_f32 v97, v98, v99
	v_add_co_u32_e32 v98, vcc, s23, v38
	s_nop 1
	v_addc_co_u32_e32 v99, vcc, -1, v39, vcc
	global_store_dwordx2 v[98:99], v[96:97], off
	v_lshlrev_b32_e32 v96, 16, v88
	v_and_b32_e32 v97, 0xffff0000, v88
	v_lshlrev_b32_e32 v88, 16, v89
	v_and_b32_e32 v89, 0xffff0000, v89
	v_mul_f32_e32 v98, v97, v97
	v_mul_f32_e32 v99, v89, v89
	v_fmac_f32_e32 v98, v96, v96
	v_fmac_f32_e32 v99, v88, v88
	v_add_f32_e32 v100, v98, v99
	v_lshlrev_b32_e32 v98, 16, v90
	v_and_b32_e32 v99, 0xffff0000, v90
	v_lshlrev_b32_e32 v90, 16, v91
	v_and_b32_e32 v91, 0xffff0000, v91
	v_mul_f32_e32 v101, v99, v99
	v_mul_f32_e32 v102, v91, v91
	v_fmac_f32_e32 v101, v98, v98
	v_fmac_f32_e32 v102, v90, v90
	v_add_f32_e32 v101, v101, v102
	v_add_f32_e32 v102, v100, v101
	v_lshlrev_b32_e32 v100, 16, v92
	v_and_b32_e32 v101, 0xffff0000, v92
	v_lshlrev_b32_e32 v92, 16, v93
	v_and_b32_e32 v93, 0xffff0000, v93
	v_mul_f32_e32 v103, v101, v101
	v_mul_f32_e32 v104, v93, v93
	v_fmac_f32_e32 v103, v100, v100
	v_fmac_f32_e32 v104, v92, v92
	v_add_f32_e32 v103, v103, v104
	v_add_f32_e32 v104, v102, v103
	v_lshlrev_b32_e32 v102, 16, v94
	v_and_b32_e32 v103, 0xffff0000, v94
	v_lshlrev_b32_e32 v94, 16, v95
	v_and_b32_e32 v95, 0xffff0000, v95
	v_mul_f32_e32 v105, v103, v103
	v_mul_f32_e32 v106, v95, v95
	v_fmac_f32_e32 v105, v102, v102
	v_fmac_f32_e32 v106, v94, v94
	v_add_f32_e32 v105, v105, v106
	v_add_f32_e32 v104, v104, v105
	ds_swizzle_b32 v105, v104 offset:swizzle(SWAP,1)
	s_waitcnt lgkmcnt(0)
	v_add_f32_e32 v104, v104, v105
	ds_swizzle_b32 v105, v104 offset:swizzle(SWAP,2)
	s_waitcnt lgkmcnt(0)
	v_add_f32_e32 v104, v104, v105
	ds_swizzle_b32 v105, v104 offset:swizzle(SWAP,4)
	s_waitcnt lgkmcnt(0)
	v_add_f32_e32 v104, v104, v105
	ds_swizzle_b32 v105, v104 offset:swizzle(SWAP,8)
	s_waitcnt lgkmcnt(0)
	v_add_f32_e32 v104, v104, v105
	ds_swizzle_b32 v105, v104 offset:swizzle(SWAP,16)
	s_waitcnt lgkmcnt(0)
	v_add_f32_e32 v104, v104, v105
	v_mov_b32_e32 v105, v104
	s_nop 1
	v_permlane32_swap_b32_e32 v104, v105
	v_add_f32_e32 v104, v104, v105
	v_fmamk_f32 v104, v104, 0x3a800000, v176
	v_cmp_gt_f32_e32 vcc, s33, v104
	v_mul_f32_e32 v105, 0x4b800000, v104
	s_nop 0
	v_cndmask_b32_e32 v104, v104, v105, vcc
	v_rsq_f32_e32 v104, v104
	s_nop 0
	v_mul_f32_e32 v105, 0x45800000, v104
	v_cndmask_b32_e32 v104, v104, v105, vcc
	v_pk_mul_f32 v[96:97], v[96:97], v[104:105] op_sel_hi:[1,0]
	v_pk_mul_f32 v[88:89], v[88:89], v[104:105] op_sel_hi:[1,0]
	v_pk_fma_f32 v[96:97], v[42:43], v[96:97], v[28:29]
	v_pk_fma_f32 v[88:89], v[40:41], v[88:89], v[30:31]
	v_cvt_pk_bf16_f32 v96, v96, v97
	v_pk_mul_f32 v[90:91], v[90:91], v[104:105] op_sel_hi:[1,0]
	v_cvt_pk_bf16_f32 v97, v88, v89
	v_add_co_u32_e32 v88, vcc, s24, v38
	v_pk_fma_f32 v[90:91], v[44:45], v[90:91], v[22:23]
	s_nop 0
	v_addc_co_u32_e32 v89, vcc, -1, v39, vcc
	global_store_dwordx2 v[88:89], v[96:97], off
	v_pk_mul_f32 v[88:89], v[98:99], v[104:105] op_sel_hi:[1,0]
	s_nop 0
	v_pk_fma_f32 v[88:89], v[46:47], v[88:89], v[20:21]
	s_nop 0
	v_cvt_pk_bf16_f32 v88, v88, v89
	v_cvt_pk_bf16_f32 v89, v90, v91
	v_add_co_u32_e32 v90, vcc, s25, v38
	s_nop 1
	v_addc_co_u32_e32 v91, vcc, -1, v39, vcc
	global_store_dwordx2 v[90:91], v[88:89], off
	v_pk_mul_f32 v[88:89], v[100:101], v[104:105] op_sel_hi:[1,0]
	v_pk_mul_f32 v[90:91], v[92:93], v[104:105] op_sel_hi:[1,0]
	v_pk_fma_f32 v[88:89], v[50:51], v[88:89], v[24:25]
	v_pk_fma_f32 v[90:91], v[48:49], v[90:91], v[26:27]
	v_cvt_pk_bf16_f32 v88, v88, v89
	s_nop 0
	v_cvt_pk_bf16_f32 v89, v90, v91
	v_add_co_u32_e32 v90, vcc, s26, v38
	s_nop 1
	v_addc_co_u32_e32 v91, vcc, -1, v39, vcc
; __device__ __forceinline__ unsigned pk2(float lo, float hi) { unsigned r; asm("v_cvt_pk_bf16_f32 %0, %1, %2" : "=v"(r) : "v"(lo), "v"(hi)); return r; }
; __device__ __forceinline__ f32x4 unpack4(unsigned long long w) { const unsigned lo = (unsigned)w, hi = (unsigned)(w >> 32); return (f32x4){__uint_as_float(lo << 16), __uint_as_float(lo & 0xffff0000u), __uint_as_float(hi << 16), __uint_as_float(hi & 0xffff0000u)}; }
; template <int MODE, int NR>
; __device__ __forceinline__ void norm_finish(const unsigned long long (&raw)[NR][4], bf16* H, float* out32, const f32x4 (&mul)[4], const f32x4 (&sh)[4], int lane) {
; #pragma unroll
;     for (int r = 0; r < NR; ++r) { f32x4 v[4]; float s = 0.f;
; #pragma unroll
;         for (int j = 0; j < 4; ++j) { v[j] = unpack4(raw[r][j]); s += (v[j].x * v[j].x + v[j].y * v[j].y) + (v[j].z * v[j].z + v[j].w * v[j].w); }
;         const float rstd = rsqrtf(wave_sum(s) * (1.f / D) + EPS);
;         if constexpr (MODE == 2) { f32x4* o = (f32x4*)(out32 + (size_t)r * D) + lane;
; #pragma unroll
;             for (int j = 0; j < 4; ++j) o[64 * j] = v[j] * rstd * mul[j];
;         } else { unsigned long long* o8 = (unsigned long long*)(H + (size_t)r * D) + lane;
; #pragma unroll
;             for (int j = 0; j < 4; ++j) { const f32x4 y = v[j] * rstd * mul[j] + sh[j]; o8[64 * j] = (unsigned long long)pk2(y.x, y.y) | ((unsigned long long)pk2(y.z, y.w) << 32); } } }
	global_store_dwordx2 v[90:91], v[88:89], off
	v_pk_mul_f32 v[88:89], v[102:103], v[104:105] op_sel_hi:[1,0]
	v_pk_mul_f32 v[90:91], v[94:95], v[104:105] op_sel_hi:[1,0]
	v_pk_fma_f32 v[88:89], v[54:55], v[88:89], v[32:33]
	v_pk_fma_f32 v[90:91], v[52:53], v[90:91], v[34:35]
	v_cvt_pk_bf16_f32 v88, v88, v89
	s_nop 0
	v_cvt_pk_bf16_f32 v89, v90, v91
	v_add_co_u32_e32 v90, vcc, s27, v38
	s_nop 1
	v_addc_co_u32_e32 v91, vcc, -1, v39, vcc
	global_store_dwordx2 v[90:91], v[88:89], off
	v_lshlrev_b32_e32 v88, 16, v80
	v_and_b32_e32 v89, 0xffff0000, v80
	v_lshlrev_b32_e32 v80, 16, v81
	v_and_b32_e32 v81, 0xffff0000, v81
	v_mul_f32_e32 v90, v89, v89
	v_mul_f32_e32 v91, v81, v81
	v_fmac_f32_e32 v90, v88, v88
	v_fmac_f32_e32 v91, v80, v80
	v_add_f32_e32 v92, v90, v91
	v_lshlrev_b32_e32 v90, 16, v82
	v_and_b32_e32 v91, 0xffff0000, v82
	v_lshlrev_b32_e32 v82, 16, v83
	v_and_b32_e32 v83, 0xffff0000, v83
	v_mul_f32_e32 v93, v91, v91
	v_mul_f32_e32 v94, v83, v83
	v_fmac_f32_e32 v93, v90, v90
	v_fmac_f32_e32 v94, v82, v82
	v_add_f32_e32 v93, v93, v94
	v_add_f32_e32 v94, v92, v93
	v_lshlrev_b32_e32 v92, 16, v84
	v_and_b32_e32 v93, 0xffff0000, v84
	v_lshlrev_b32_e32 v84, 16, v85
	v_and_b32_e32 v85, 0xffff0000, v85
	v_mul_f32_e32 v95, v93, v93
	v_mul_f32_e32 v96, v85, v85
	v_fmac_f32_e32 v95, v92, v92
	v_fmac_f32_e32 v96, v84, v84
	v_add_f32_e32 v95, v95, v96
	v_add_f32_e32 v96, v94, v95
	v_lshlrev_b32_e32 v94, 16, v86
	v_and_b32_e32 v95, 0xffff0000, v86
	v_lshlrev_b32_e32 v86, 16, v87
	v_and_b32_e32 v87, 0xffff0000, v87
	v_mul_f32_e32 v97, v95, v95
	v_mul_f32_e32 v98, v87, v87
	v_fmac_f32_e32 v97, v94, v94
	v_fmac_f32_e32 v98, v86, v86
	v_add_f32_e32 v97, v97, v98
	v_add_f32_e32 v96, v96, v97
	ds_swizzle_b32 v97, v96 offset:swizzle(SWAP,1)
	s_waitcnt lgkmcnt(0)
	v_add_f32_e32 v96, v96, v97
	ds_swizzle_b32 v97, v96 offset:swizzle(SWAP,2)
	s_waitcnt lgkmcnt(0)
	v_add_f32_e32 v96, v96, v97
	ds_swizzle_b32 v97, v96 offset:swizzle(SWAP,4)
	s_waitcnt lgkmcnt(0)
	v_add_f32_e32 v96, v96, v97
	ds_swizzle_b32 v97, v96 offset:swizzle(SWAP,8)
	s_waitcnt lgkmcnt(0)
	v_add_f32_e32 v96, v96, v97
	ds_swizzle_b32 v97, v96 offset:swizzle(SWAP,16)
	s_waitcnt lgkmcnt(0)
	v_add_f32_e32 v96, v96, v97
	v_mov_b32_e32 v97, v96
	s_nop 1
	v_permlane32_swap_b32_e32 v96, v97
	v_add_f32_e32 v96, v96, v97
	v_fmamk_f32 v96, v96, 0x3a800000, v176
	v_cmp_gt_f32_e32 vcc, s33, v96
	v_mul_f32_e32 v97, 0x4b800000, v96
	s_nop 0
	v_cndmask_b32_e32 v96, v96, v97, vcc
	v_rsq_f32_e32 v96, v96
	s_nop 0
	v_mul_f32_e32 v97, 0x45800000, v96
	v_cndmask_b32_e32 v96, v96, v97, vcc
	v_pk_mul_f32 v[88:89], v[88:89], v[96:97] op_sel_hi:[1,0]
	v_pk_mul_f32 v[80:81], v[80:81], v[96:97] op_sel_hi:[1,0]
	v_pk_fma_f32 v[88:89], v[42:43], v[88:89], v[28:29]
	v_pk_fma_f32 v[80:81], v[40:41], v[80:81], v[30:31]
	v_cvt_pk_bf16_f32 v88, v88, v89
	v_pk_mul_f32 v[82:83], v[82:83], v[96:97] op_sel_hi:[1,0]
	v_cvt_pk_bf16_f32 v89, v80, v81
	v_add_co_u32_e32 v80, vcc, s28, v38
	v_pk_fma_f32 v[82:83], v[44:45], v[82:83], v[22:23]
	s_nop 0
	v_addc_co_u32_e32 v81, vcc, -1, v39, vcc
	global_store_dwordx2 v[80:81], v[88:89], off
	v_pk_mul_f32 v[80:81], v[90:91], v[96:97] op_sel_hi:[1,0]
	s_nop 0
	v_pk_fma_f32 v[80:81], v[46:47], v[80:81], v[20:21]
	s_nop 0
	v_cvt_pk_bf16_f32 v80, v80, v81
	v_cvt_pk_bf16_f32 v81, v82, v83
	v_add_co_u32_e32 v82, vcc, s29, v38
	s_nop 1
	v_addc_co_u32_e32 v83, vcc, -1, v39, vcc
	global_store_dwordx2 v[82:83], v[80:81], off
	v_pk_mul_f32 v[80:81], v[92:93], v[96:97] op_sel_hi:[1,0]
	v_pk_mul_f32 v[82:83], v[84:85], v[96:97] op_sel_hi:[1,0]
	v_pk_fma_f32 v[80:81], v[50:51], v[80:81], v[24:25]
	v_pk_fma_f32 v[82:83], v[48:49], v[82:83], v[26:27]
	v_cvt_pk_bf16_f32 v80, v80, v81
	s_nop 0
	v_cvt_pk_bf16_f32 v81, v82, v83
	v_add_co_u32_e32 v82, vcc, s30, v38
	s_nop 1
	v_addc_co_u32_e32 v83, vcc, -1, v39, vcc
	global_store_dwordx2 v[82:83], v[80:81], off
	v_pk_mul_f32 v[80:81], v[94:95], v[96:97] op_sel_hi:[1,0]
	v_pk_mul_f32 v[82:83], v[86:87], v[96:97] op_sel_hi:[1,0]
	v_pk_fma_f32 v[80:81], v[54:55], v[80:81], v[32:33]
	v_pk_fma_f32 v[82:83], v[52:53], v[82:83], v[34:35]
	v_cvt_pk_bf16_f32 v80, v80, v81
	s_nop 0
	v_cvt_pk_bf16_f32 v81, v82, v83
	v_add_co_u32_e32 v82, vcc, s31, v38
	s_nop 1
	v_addc_co_u32_e32 v83, vcc, -1, v39, vcc
	global_store_dwordx2 v[82:83], v[80:81], off
	v_lshlrev_b32_e32 v80, 16, v72
	v_and_b32_e32 v81, 0xffff0000, v72
	v_lshlrev_b32_e32 v72, 16, v73
	v_and_b32_e32 v73, 0xffff0000, v73
	v_mul_f32_e32 v82, v81, v81
	v_mul_f32_e32 v83, v73, v73
	v_fmac_f32_e32 v82, v80, v80
	v_fmac_f32_e32 v83, v72, v72
	v_add_f32_e32 v84, v82, v83
	v_lshlrev_b32_e32 v82, 16, v74
	v_and_b32_e32 v83, 0xffff0000, v74
	v_lshlrev_b32_e32 v74, 16, v75
	v_and_b32_e32 v75, 0xffff0000, v75
	v_mul_f32_e32 v85, v83, v83
	v_mul_f32_e32 v86, v75, v75
	v_fmac_f32_e32 v85, v82, v82
	v_fmac_f32_e32 v86, v74, v74
	v_add_f32_e32 v85, v85, v86
	v_add_f32_e32 v86, v84, v85
	v_lshlrev_b32_e32 v84, 16, v76
	v_and_b32_e32 v85, 0xffff0000, v76
	v_lshlrev_b32_e32 v76, 16, v77
	v_and_b32_e32 v77, 0xffff0000, v77
	v_mul_f32_e32 v87, v85, v85
	v_mul_f32_e32 v88, v77, v77
	v_fmac_f32_e32 v87, v84, v84
	v_fmac_f32_e32 v88, v76, v76
	v_add_f32_e32 v87, v87, v88
	v_add_f32_e32 v88, v86, v87
	v_lshlrev_b32_e32 v86, 16, v78
	v_and_b32_e32 v87, 0xffff0000, v78
	v_lshlrev_b32_e32 v78, 16, v79
	v_and_b32_e32 v79, 0xffff0000, v79
	v_mul_f32_e32 v89, v87, v87
	v_mul_f32_e32 v90, v79, v79
	v_fmac_f32_e32 v89, v86, v86
	v_fmac_f32_e32 v90, v78, v78
	v_add_f32_e32 v89, v89, v90
	v_add_f32_e32 v88, v88, v89
	ds_swizzle_b32 v89, v88 offset:swizzle(SWAP,1)
	s_waitcnt lgkmcnt(0)
	v_add_f32_e32 v88, v88, v89
	ds_swizzle_b32 v89, v88 offset:swizzle(SWAP,2)
	s_waitcnt lgkmcnt(0)
; __device__ __forceinline__ unsigned pk2(float lo, float hi) { unsigned r; asm("v_cvt_pk_bf16_f32 %0, %1, %2" : "=v"(r) : "v"(lo), "v"(hi)); return r; }
; __device__ __forceinline__ f32x4 unpack4(unsigned long long w) { const unsigned lo = (unsigned)w, hi = (unsigned)(w >> 32); return (f32x4){__uint_as_float(lo << 16), __uint_as_float(lo & 0xffff0000u), __uint_as_float(hi << 16), __uint_as_float(hi & 0xffff0000u)}; }
; template <int MODE, int NR>
; __device__ __forceinline__ void norm_finish(const unsigned long long (&raw)[NR][4], bf16* H, float* out32, const f32x4 (&mul)[4], const f32x4 (&sh)[4], int lane) {
; #pragma unroll
;     for (int r = 0; r < NR; ++r) { f32x4 v[4]; float s = 0.f;
; #pragma unroll
;         for (int j = 0; j < 4; ++j) { v[j] = unpack4(raw[r][j]); s += (v[j].x * v[j].x + v[j].y * v[j].y) + (v[j].z * v[j].z + v[j].w * v[j].w); }
;         const float rstd = rsqrtf(wave_sum(s) * (1.f / D) + EPS);
;         if constexpr (MODE == 2) { f32x4* o = (f32x4*)(out32 + (size_t)r * D) + lane;
; #pragma unroll
;             for (int j = 0; j < 4; ++j) o[64 * j] = v[j] * rstd * mul[j];
;         } else { unsigned long long* o8 = (unsigned long long*)(H + (size_t)r * D) + lane;
; #pragma unroll
;             for (int j = 0; j < 4; ++j) { const f32x4 y = v[j] * rstd * mul[j] + sh[j]; o8[64 * j] = (unsigned long long)pk2(y.x, y.y) | ((unsigned long long)pk2(y.z, y.w) << 32); } } }
; }
	v_add_f32_e32 v88, v88, v89
	ds_swizzle_b32 v89, v88 offset:swizzle(SWAP,4)
	s_waitcnt lgkmcnt(0)
	v_add_f32_e32 v88, v88, v89
	ds_swizzle_b32 v89, v88 offset:swizzle(SWAP,8)
	s_waitcnt lgkmcnt(0)
	v_add_f32_e32 v88, v88, v89
	ds_swizzle_b32 v89, v88 offset:swizzle(SWAP,16)
	s_waitcnt lgkmcnt(0)
	v_add_f32_e32 v88, v88, v89
	v_mov_b32_e32 v89, v88
	s_nop 1
	v_permlane32_swap_b32_e32 v88, v89
	v_add_f32_e32 v88, v88, v89
	v_fmamk_f32 v88, v88, 0x3a800000, v176
	v_cmp_gt_f32_e32 vcc, s33, v88
	v_mul_f32_e32 v89, 0x4b800000, v88
	s_nop 0
	v_cndmask_b32_e32 v88, v88, v89, vcc
	v_rsq_f32_e32 v88, v88
	s_nop 0
	v_mul_f32_e32 v89, 0x45800000, v88
	v_cndmask_b32_e32 v88, v88, v89, vcc
	v_pk_mul_f32 v[80:81], v[80:81], v[88:89] op_sel_hi:[1,0]
	v_pk_mul_f32 v[72:73], v[72:73], v[88:89] op_sel_hi:[1,0]
	v_pk_fma_f32 v[80:81], v[42:43], v[80:81], v[28:29]
	v_pk_fma_f32 v[72:73], v[40:41], v[72:73], v[30:31]
	v_cvt_pk_bf16_f32 v80, v80, v81
	v_pk_mul_f32 v[74:75], v[74:75], v[88:89] op_sel_hi:[1,0]
	v_cvt_pk_bf16_f32 v81, v72, v73
	v_add_co_u32_e32 v72, vcc, s34, v38
	v_pk_fma_f32 v[74:75], v[44:45], v[74:75], v[22:23]
	s_nop 0
	v_addc_co_u32_e32 v73, vcc, -1, v39, vcc
	global_store_dwordx2 v[72:73], v[80:81], off
	v_pk_mul_f32 v[72:73], v[82:83], v[88:89] op_sel_hi:[1,0]
	s_nop 0
	v_pk_fma_f32 v[72:73], v[46:47], v[72:73], v[20:21]
	s_nop 0
	v_cvt_pk_bf16_f32 v72, v72, v73
	v_cvt_pk_bf16_f32 v73, v74, v75
	v_add_co_u32_e32 v74, vcc, s35, v38
	s_nop 1
	v_addc_co_u32_e32 v75, vcc, -1, v39, vcc
	global_store_dwordx2 v[74:75], v[72:73], off
	v_pk_mul_f32 v[72:73], v[84:85], v[88:89] op_sel_hi:[1,0]
	v_pk_mul_f32 v[74:75], v[76:77], v[88:89] op_sel_hi:[1,0]
	v_pk_fma_f32 v[72:73], v[50:51], v[72:73], v[24:25]
	v_pk_fma_f32 v[74:75], v[48:49], v[74:75], v[26:27]
	v_cvt_pk_bf16_f32 v72, v72, v73
	s_nop 0
	v_cvt_pk_bf16_f32 v73, v74, v75
	v_add_co_u32_e32 v74, vcc, s36, v38
	s_nop 1
	v_addc_co_u32_e32 v75, vcc, -1, v39, vcc
	global_store_dwordx2 v[74:75], v[72:73], off
	v_pk_mul_f32 v[72:73], v[86:87], v[88:89] op_sel_hi:[1,0]
	v_pk_mul_f32 v[74:75], v[78:79], v[88:89] op_sel_hi:[1,0]
	v_pk_fma_f32 v[72:73], v[54:55], v[72:73], v[32:33]
	v_pk_fma_f32 v[74:75], v[52:53], v[74:75], v[34:35]
	v_cvt_pk_bf16_f32 v72, v72, v73
	s_nop 0
	v_cvt_pk_bf16_f32 v73, v74, v75
	v_add_co_u32_e32 v74, vcc, s37, v38
	s_nop 1
	v_addc_co_u32_e32 v75, vcc, -1, v39, vcc
	global_store_dwordx2 v[74:75], v[72:73], off
	v_lshlrev_b32_e32 v72, 16, v64
	v_and_b32_e32 v73, 0xffff0000, v64
	v_lshlrev_b32_e32 v64, 16, v65
	v_and_b32_e32 v65, 0xffff0000, v65
	v_mul_f32_e32 v74, v73, v73
	v_mul_f32_e32 v75, v65, v65
	v_fmac_f32_e32 v74, v72, v72
	v_fmac_f32_e32 v75, v64, v64
	v_add_f32_e32 v76, v74, v75
	v_lshlrev_b32_e32 v74, 16, v66
	v_and_b32_e32 v75, 0xffff0000, v66
	v_lshlrev_b32_e32 v66, 16, v67
	v_and_b32_e32 v67, 0xffff0000, v67
	v_mul_f32_e32 v77, v75, v75
	v_mul_f32_e32 v78, v67, v67
	v_fmac_f32_e32 v77, v74, v74
	v_fmac_f32_e32 v78, v66, v66
	v_add_f32_e32 v77, v77, v78
	v_add_f32_e32 v78, v76, v77
	v_lshlrev_b32_e32 v76, 16, v68
	v_and_b32_e32 v77, 0xffff0000, v68
	v_lshlrev_b32_e32 v68, 16, v69
	v_and_b32_e32 v69, 0xffff0000, v69
	v_mul_f32_e32 v79, v77, v77
	v_mul_f32_e32 v80, v69, v69
	v_fmac_f32_e32 v79, v76, v76
	v_fmac_f32_e32 v80, v68, v68
	v_add_f32_e32 v79, v79, v80
	v_add_f32_e32 v80, v78, v79
	v_lshlrev_b32_e32 v78, 16, v70
	v_and_b32_e32 v79, 0xffff0000, v70
	v_lshlrev_b32_e32 v70, 16, v71
	v_and_b32_e32 v71, 0xffff0000, v71
	v_mul_f32_e32 v81, v79, v79
	v_mul_f32_e32 v82, v71, v71
	v_fmac_f32_e32 v81, v78, v78
	v_fmac_f32_e32 v82, v70, v70
	v_add_f32_e32 v81, v81, v82
	v_add_f32_e32 v80, v80, v81
	ds_swizzle_b32 v81, v80 offset:swizzle(SWAP,1)
	s_waitcnt lgkmcnt(0)
	v_add_f32_e32 v80, v80, v81
	ds_swizzle_b32 v81, v80 offset:swizzle(SWAP,2)
	s_waitcnt lgkmcnt(0)
	v_add_f32_e32 v80, v80, v81
	ds_swizzle_b32 v81, v80 offset:swizzle(SWAP,4)
	s_waitcnt lgkmcnt(0)
	v_add_f32_e32 v80, v80, v81
	ds_swizzle_b32 v81, v80 offset:swizzle(SWAP,8)
	s_waitcnt lgkmcnt(0)
	v_add_f32_e32 v80, v80, v81
	ds_swizzle_b32 v81, v80 offset:swizzle(SWAP,16)
	s_waitcnt lgkmcnt(0)
; __device__ __forceinline__ unsigned pk2(float lo, float hi) { unsigned r; asm("v_cvt_pk_bf16_f32 %0, %1, %2" : "=v"(r) : "v"(lo), "v"(hi)); return r; }
; __device__ __forceinline__ f32x4 unpack4(unsigned long long w) { const unsigned lo = (unsigned)w, hi = (unsigned)(w >> 32); return (f32x4){__uint_as_float(lo << 16), __uint_as_float(lo & 0xffff0000u), __uint_as_float(hi << 16), __uint_as_float(hi & 0xffff0000u)}; }
; template <int MODE, int NR>
; __device__ __forceinline__ void norm_finish(const unsigned long long (&raw)[NR][4], bf16* H, float* out32, const f32x4 (&mul)[4], const f32x4 (&sh)[4], int lane) {
; #pragma unroll
;     for (int r = 0; r < NR; ++r) { f32x4 v[4]; float s = 0.f;
; #pragma unroll
;         for (int j = 0; j < 4; ++j) { v[j] = unpack4(raw[r][j]); s += (v[j].x * v[j].x + v[j].y * v[j].y) + (v[j].z * v[j].z + v[j].w * v[j].w); }
;         const float rstd = rsqrtf(wave_sum(s) * (1.f / D) + EPS);
;         if constexpr (MODE == 2) { f32x4* o = (f32x4*)(out32 + (size_t)r * D) + lane;
; #pragma unroll
;             for (int j = 0; j < 4; ++j) o[64 * j] = v[j] * rstd * mul[j];
;         } else { unsigned long long* o8 = (unsigned long long*)(H + (size_t)r * D) + lane;
; #pragma unroll
;             for (int j = 0; j < 4; ++j) { const f32x4 y = v[j] * rstd * mul[j] + sh[j]; o8[64 * j] = (unsigned long long)pk2(y.x, y.y) | ((unsigned long long)pk2(y.z, y.w) << 32); } } }
; }
	v_add_f32_e32 v80, v80, v81
	v_mov_b32_e32 v81, v80
	s_nop 1
	v_permlane32_swap_b32_e32 v80, v81
	v_add_f32_e32 v80, v80, v81
	v_fmamk_f32 v80, v80, 0x3a800000, v176
	v_cmp_gt_f32_e32 vcc, s33, v80
	v_mul_f32_e32 v81, 0x4b800000, v80
	s_nop 0
	v_cndmask_b32_e32 v80, v80, v81, vcc
	v_rsq_f32_e32 v80, v80
	s_nop 0
	v_mul_f32_e32 v81, 0x45800000, v80
	v_cndmask_b32_e32 v80, v80, v81, vcc
	v_pk_mul_f32 v[72:73], v[72:73], v[80:81] op_sel_hi:[1,0]
	v_pk_mul_f32 v[64:65], v[64:65], v[80:81] op_sel_hi:[1,0]
	v_pk_fma_f32 v[72:73], v[42:43], v[72:73], v[28:29]
	v_pk_fma_f32 v[64:65], v[40:41], v[64:65], v[30:31]
	v_cvt_pk_bf16_f32 v72, v72, v73
	v_pk_mul_f32 v[66:67], v[66:67], v[80:81] op_sel_hi:[1,0]
	v_cvt_pk_bf16_f32 v73, v64, v65
	v_add_co_u32_e32 v64, vcc, s50, v38
	v_pk_fma_f32 v[66:67], v[44:45], v[66:67], v[22:23]
	s_nop 0
	v_addc_co_u32_e32 v65, vcc, -1, v39, vcc
	global_store_dwordx2 v[64:65], v[72:73], off
	v_pk_mul_f32 v[64:65], v[74:75], v[80:81] op_sel_hi:[1,0]
	s_nop 0
	v_pk_fma_f32 v[64:65], v[46:47], v[64:65], v[20:21]
	s_nop 0
	v_cvt_pk_bf16_f32 v64, v64, v65
	v_cvt_pk_bf16_f32 v65, v66, v67
	v_add_co_u32_e32 v66, vcc, s58, v38
	s_nop 1
	v_addc_co_u32_e32 v67, vcc, -1, v39, vcc
	global_store_dwordx2 v[66:67], v[64:65], off
	v_pk_mul_f32 v[64:65], v[76:77], v[80:81] op_sel_hi:[1,0]
	v_pk_mul_f32 v[66:67], v[68:69], v[80:81] op_sel_hi:[1,0]
	v_pk_fma_f32 v[64:65], v[50:51], v[64:65], v[24:25]
	v_pk_fma_f32 v[66:67], v[48:49], v[66:67], v[26:27]
	v_cvt_pk_bf16_f32 v64, v64, v65
	s_nop 0
	v_cvt_pk_bf16_f32 v65, v66, v67
	v_add_co_u32_e32 v66, vcc, s59, v38
	s_nop 1
	v_addc_co_u32_e32 v67, vcc, -1, v39, vcc
	global_store_dwordx2 v[66:67], v[64:65], off
	v_pk_mul_f32 v[64:65], v[78:79], v[80:81] op_sel_hi:[1,0]
	v_pk_mul_f32 v[66:67], v[70:71], v[80:81] op_sel_hi:[1,0]
	v_pk_fma_f32 v[64:65], v[54:55], v[64:65], v[32:33]
	v_pk_fma_f32 v[66:67], v[52:53], v[66:67], v[34:35]
	v_cvt_pk_bf16_f32 v64, v64, v65
	s_nop 0
	v_cvt_pk_bf16_f32 v65, v66, v67
	v_add_co_u32_e32 v66, vcc, s62, v38
	s_nop 1
	v_addc_co_u32_e32 v67, vcc, -1, v39, vcc
	global_store_dwordx2 v[66:67], v[64:65], off
	v_lshlrev_b32_e32 v64, 16, v56
	v_and_b32_e32 v65, 0xffff0000, v56
	v_lshlrev_b32_e32 v56, 16, v57
	v_and_b32_e32 v57, 0xffff0000, v57
	v_mul_f32_e32 v66, v65, v65
	v_mul_f32_e32 v67, v57, v57
	v_fmac_f32_e32 v66, v64, v64
	v_fmac_f32_e32 v67, v56, v56
	v_add_f32_e32 v68, v66, v67
	v_lshlrev_b32_e32 v66, 16, v58
	v_and_b32_e32 v67, 0xffff0000, v58
	v_lshlrev_b32_e32 v58, 16, v59
	v_and_b32_e32 v59, 0xffff0000, v59
	v_mul_f32_e32 v69, v67, v67
	v_mul_f32_e32 v70, v59, v59
	v_fmac_f32_e32 v69, v66, v66
	v_fmac_f32_e32 v70, v58, v58
	v_add_f32_e32 v69, v69, v70
	v_add_f32_e32 v70, v68, v69
	v_lshlrev_b32_e32 v68, 16, v60
	v_and_b32_e32 v69, 0xffff0000, v60
	v_lshlrev_b32_e32 v60, 16, v61
	v_and_b32_e32 v61, 0xffff0000, v61
	v_mul_f32_e32 v71, v69, v69
	v_mul_f32_e32 v72, v61, v61
	v_fmac_f32_e32 v71, v68, v68
	v_fmac_f32_e32 v72, v60, v60
	v_add_f32_e32 v71, v71, v72
	v_add_f32_e32 v72, v70, v71
	v_lshlrev_b32_e32 v70, 16, v62
	v_and_b32_e32 v71, 0xffff0000, v62
	v_lshlrev_b32_e32 v62, 16, v63
	v_and_b32_e32 v63, 0xffff0000, v63
	v_mul_f32_e32 v73, v71, v71
	v_mul_f32_e32 v74, v63, v63
	v_fmac_f32_e32 v73, v70, v70
	v_fmac_f32_e32 v74, v62, v62
	v_add_f32_e32 v73, v73, v74
	v_add_f32_e32 v72, v72, v73
	ds_swizzle_b32 v73, v72 offset:swizzle(SWAP,1)
	s_waitcnt lgkmcnt(0)
	v_add_f32_e32 v72, v72, v73
	ds_swizzle_b32 v73, v72 offset:swizzle(SWAP,2)
	s_waitcnt lgkmcnt(0)
	v_add_f32_e32 v72, v72, v73
	ds_swizzle_b32 v73, v72 offset:swizzle(SWAP,4)
	s_waitcnt lgkmcnt(0)
	v_add_f32_e32 v72, v72, v73
	ds_swizzle_b32 v73, v72 offset:swizzle(SWAP,8)
	s_waitcnt lgkmcnt(0)
	v_add_f32_e32 v72, v72, v73
	ds_swizzle_b32 v73, v72 offset:swizzle(SWAP,16)
	s_waitcnt lgkmcnt(0)
	v_add_f32_e32 v72, v72, v73
	v_mov_b32_e32 v73, v72
	s_nop 1
	v_permlane32_swap_b32_e32 v72, v73
	v_add_f32_e32 v72, v72, v73
	v_fmamk_f32 v72, v72, 0x3a800000, v176
	v_cmp_gt_f32_e32 vcc, s33, v72
	v_mul_f32_e32 v73, 0x4b800000, v72
	s_nop 0
	v_cndmask_b32_e32 v72, v72, v73, vcc
	v_rsq_f32_e32 v72, v72
	s_nop 0
	v_mul_f32_e32 v73, 0x45800000, v72
	v_cndmask_b32_e32 v72, v72, v73, vcc
	v_pk_mul_f32 v[64:65], v[64:65], v[72:73] op_sel_hi:[1,0]
	v_pk_mul_f32 v[56:57], v[56:57], v[72:73] op_sel_hi:[1,0]
	v_pk_fma_f32 v[28:29], v[42:43], v[64:65], v[28:29]
	v_pk_fma_f32 v[30:31], v[40:41], v[56:57], v[30:31]
	v_cvt_pk_bf16_f32 v28, v28, v29
	s_nop 0
	v_cvt_pk_bf16_f32 v29, v30, v31
	v_add_co_u32_e32 v30, vcc, s63, v38
	s_nop 1
	v_addc_co_u32_e32 v31, vcc, -1, v39, vcc
	global_store_dwordx2 v[30:31], v[28:29], off
	v_pk_mul_f32 v[28:29], v[66:67], v[72:73] op_sel_hi:[1,0]
	v_pk_mul_f32 v[30:31], v[58:59], v[72:73] op_sel_hi:[1,0]
	v_pk_fma_f32 v[20:21], v[46:47], v[28:29], v[20:21]
	v_pk_fma_f32 v[22:23], v[44:45], v[30:31], v[22:23]
	v_cvt_pk_bf16_f32 v20, v20, v21
	s_nop 0
	v_cvt_pk_bf16_f32 v21, v22, v23
	v_add_co_u32_e32 v22, vcc, s64, v38
	s_nop 1
	v_addc_co_u32_e32 v23, vcc, -1, v39, vcc
	global_store_dwordx2 v[22:23], v[20:21], off
	v_pk_mul_f32 v[20:21], v[68:69], v[72:73] op_sel_hi:[1,0]
	v_pk_mul_f32 v[22:23], v[60:61], v[72:73] op_sel_hi:[1,0]
	v_pk_fma_f32 v[20:21], v[50:51], v[20:21], v[24:25]
	v_pk_fma_f32 v[22:23], v[48:49], v[22:23], v[26:27]
	v_cvt_pk_bf16_f32 v20, v20, v21
	s_nop 0
	v_cvt_pk_bf16_f32 v21, v22, v23
	v_add_co_u32_e32 v22, vcc, s66, v38
	s_nop 1
	v_addc_co_u32_e32 v23, vcc, -1, v39, vcc
	global_store_dwordx2 v[22:23], v[20:21], off
	v_pk_mul_f32 v[20:21], v[70:71], v[72:73] op_sel_hi:[1,0]
	v_pk_mul_f32 v[22:23], v[62:63], v[72:73] op_sel_hi:[1,0]
	v_pk_fma_f32 v[20:21], v[54:55], v[20:21], v[32:33]
	v_pk_fma_f32 v[22:23], v[52:53], v[22:23], v[34:35]
	v_cvt_pk_bf16_f32 v20, v20, v21
	s_nop 0
	v_cvt_pk_bf16_f32 v21, v22, v23
	global_store_dwordx2 v[38:39], v[20:21], off
	v_lshl_add_u64 v[38:39], v[38:39], 0, s[78:79]
	s_cbranch_scc0 .LBB0_1132

; __device__ __forceinline__ unsigned pk2(float lo, float hi) { unsigned r; asm("v_cvt_pk_bf16_f32 %0, %1, %2" : "=v"(r) : "v"(lo), "v"(hi)); return r; }
; template <int MODE, int NR>
; __device__ __forceinline__ void norm_rows(const float* X32, bf16* X, bf16* H, float* out32, const f32x4 (&mul)[4], const f32x4 (&sh)[4], int lane) {
;     ...
;         unsigned long long raw[NR][4];
; #pragma unroll
;         for (int r = 0; r < NR; ++r) { const unsigned long long* xr = (const unsigned long long*)(X + (size_t)r * D) + lane;
; #pragma unroll
;             for (int j = 0; j < 4; ++j) raw[r][j] = xr[64 * j]; }
; #pragma unroll
;         for (int r = 0; r < NR; ++r) { f32x4 v[4]; float s = 0.f;
; #pragma unroll
;             for (int j = 0; j < 4; ++j) { v[j] = unpack4(raw[r][j]); s += (v[j].x * v[j].x + v[j].y * v[j].y) + (v[j].z * v[j].z + v[j].w * v[j].w); }
;             const float rstd = rsqrtf(wave_sum(s) * (1.f / D) + EPS);
;             if constexpr (MODE == 2) { f32x4* o = (f32x4*)(out32 + (size_t)r * D) + lane;
; #pragma unroll
;                 for (int j = 0; j < 4; ++j) o[64 * j] = v[j] * rstd * mul[j];
;             } else { unsigned long long* o8 = (unsigned long long*)(H + (size_t)r * D) + lane;
; #pragma unroll
;                 for (int j = 0; j < 4; ++j) { const f32x4 y = v[j] * rstd * mul[j] + sh[j]; o8[64 * j] = (unsigned long long)pk2(y.x, y.y) | ((unsigned long long)pk2(y.z, y.w) << 32); } } }
; template <int MODE>
; __device__ __forceinline__ void phase_norm(const float* Xp32, const float* Xs32, bf16* X, bf16* H, const float* nw, const float* mod_sh, const float* mod_sc, int gw, int NGW, int lane) {
;     ...
;     for (int sr = gw; sr < MS; sr += NGW) {
;         const int ci = NB + sr; f32x4 mul[4], sh[4];
;         const f32x4* shp = (const f32x4*)(mod_sh + (size_t)ci * MODLD) + lane; const f32x4* scp = (const f32x4*)(mod_sc + (size_t)ci * MODLD) + lane;
; #pragma unroll
;         for (int j = 0; j < 4; ++j) { sh[j] = shp[64 * j]; mul[j] = w4[j] * (scp[64 * j] + 1.0f); }
;         const size_t ro = (size_t)(MP + sr) * D;
;         norm_rows<MODE, 1>(MODE == 1 ? Xs32 + (size_t)sr * D : nullptr, X + ro, H + ro, nullptr, mul, sh, lane);
;     }
.LBB0_1135:
	v_lshl_add_u64 v[26:27], s[6:7], 0, v[20:21]
	v_add_co_u32_e32 v38, vcc, 0x303000, v26
	v_lshl_add_u64 v[54:55], s[6:7], 0, v[8:9]
	s_nop 0
	v_addc_co_u32_e32 v39, vcc, 0, v27, vcc
	v_add_co_u32_e32 v40, vcc, 0x304000, v26
	global_load_dwordx4 v[22:25], v[38:39], off
	s_nop 0
	v_addc_co_u32_e32 v41, vcc, 0, v27, vcc
	global_load_dwordx4 v[26:29], v[40:41], off
	v_add_co_u32_e32 v56, vcc, s9, v54
	s_add_i32 s8, s8, s96
	s_nop 0
	v_addc_co_u32_e32 v57, vcc, 0, v55, vcc
	v_lshl_add_u64 v[8:9], v[8:9], 0, s[2:3]
	v_lshl_add_u64 v[20:21], v[20:21], 0, s[60:61]
	s_cmpk_lt_i32 s8, 0x80
	s_waitcnt vmcnt(0) lgkmcnt(0)
	v_pk_add_f32 v[28:29], v[28:29], 1.0 op_sel_hi:[1,0]
	v_pk_add_f32 v[26:27], v[26:27], 1.0 op_sel_hi:[1,0]
	v_pk_mul_f32 v[42:43], v[2:3], v[28:29]
	v_pk_mul_f32 v[44:45], v[0:1], v[26:27]
	global_load_dwordx4 v[26:29], v[38:39], off offset:1024
	global_load_dwordx4 v[30:33], v[40:41], off offset:1024
	s_waitcnt vmcnt(0) lgkmcnt(0)
	v_pk_add_f32 v[32:33], v[32:33], 1.0 op_sel_hi:[1,0]
	v_pk_add_f32 v[30:31], v[30:31], 1.0 op_sel_hi:[1,0]
	v_pk_mul_f32 v[46:47], v[6:7], v[32:33]
	v_pk_mul_f32 v[48:49], v[4:5], v[30:31]
	global_load_dwordx4 v[30:33], v[38:39], off offset:2048
	global_load_dwordx4 v[34:37], v[40:41], off offset:2048
	s_waitcnt vmcnt(0) lgkmcnt(0)
	v_pk_add_f32 v[36:37], v[36:37], 1.0 op_sel_hi:[1,0]
	v_pk_add_f32 v[34:35], v[34:35], 1.0 op_sel_hi:[1,0]
	v_pk_mul_f32 v[50:51], v[14:15], v[36:37]
	v_pk_mul_f32 v[52:53], v[12:13], v[34:35]
	global_load_dwordx4 v[34:37], v[38:39], off offset:3072
	s_nop 0
	global_load_dwordx4 v[38:41], v[40:41], off offset:3072
	s_nop 0
	global_load_dwordx2 v[58:59], v[56:57], off
	global_load_dwordx2 v[60:61], v[56:57], off offset:512
	global_load_dwordx2 v[62:63], v[56:57], off offset:1024
	s_nop 0
	global_load_dwordx2 v[56:57], v[56:57], off offset:1536
	s_waitcnt vmcnt(0) lgkmcnt(0)
	v_lshlrev_b32_e32 v64, 16, v58
	v_and_b32_e32 v65, 0xffff0000, v58
	v_lshlrev_b32_e32 v58, 16, v59
	v_and_b32_e32 v59, 0xffff0000, v59
	v_mul_f32_e32 v10, v65, v65
	v_mul_f32_e32 v66, v59, v59
	v_fmac_f32_e32 v10, v64, v64
	v_fmac_f32_e32 v66, v58, v58
	v_add_f32_e32 v10, v10, v66
	v_lshlrev_b32_e32 v66, 16, v60
	v_and_b32_e32 v67, 0xffff0000, v60
	v_lshlrev_b32_e32 v60, 16, v61
	v_and_b32_e32 v61, 0xffff0000, v61
	v_mul_f32_e32 v68, v67, v67
	v_mul_f32_e32 v69, v61, v61
	v_fmac_f32_e32 v68, v66, v66
	v_fmac_f32_e32 v69, v60, v60
	v_add_f32_e32 v68, v68, v69
	v_add_f32_e32 v10, v10, v68
	v_lshlrev_b32_e32 v68, 16, v62
	v_and_b32_e32 v69, 0xffff0000, v62
	v_lshlrev_b32_e32 v62, 16, v63
	v_and_b32_e32 v63, 0xffff0000, v63
	v_mul_f32_e32 v70, v69, v69
	v_mul_f32_e32 v71, v63, v63
	v_fmac_f32_e32 v70, v68, v68
	v_fmac_f32_e32 v71, v62, v62
	v_add_f32_e32 v70, v70, v71
	v_add_f32_e32 v10, v10, v70
	v_lshlrev_b32_e32 v70, 16, v56
	v_and_b32_e32 v71, 0xffff0000, v56
	v_lshlrev_b32_e32 v56, 16, v57
	v_and_b32_e32 v57, 0xffff0000, v57
	v_mul_f32_e32 v72, v71, v71
	v_mul_f32_e32 v73, v57, v57
	v_fmac_f32_e32 v72, v70, v70
	v_fmac_f32_e32 v73, v56, v56
	v_add_f32_e32 v72, v72, v73
	v_add_f32_e32 v10, v10, v72
	ds_swizzle_b32 v72, v10 offset:swizzle(SWAP,1)
	v_pk_add_f32 v[38:39], v[38:39], 1.0 op_sel_hi:[1,0]
	v_pk_add_f32 v[40:41], v[40:41], 1.0 op_sel_hi:[1,0]
	v_pk_mul_f32 v[38:39], v[16:17], v[38:39]
	v_pk_mul_f32 v[40:41], v[18:19], v[40:41]
	s_waitcnt lgkmcnt(0)
	v_add_f32_e32 v10, v10, v72
	ds_swizzle_b32 v72, v10 offset:swizzle(SWAP,2)
	s_waitcnt lgkmcnt(0)
	v_add_f32_e32 v10, v10, v72
	ds_swizzle_b32 v72, v10 offset:swizzle(SWAP,4)
	s_waitcnt lgkmcnt(0)
	v_add_f32_e32 v10, v10, v72
	ds_swizzle_b32 v72, v10 offset:swizzle(SWAP,8)
	s_waitcnt lgkmcnt(0)
	v_add_f32_e32 v10, v10, v72
	ds_swizzle_b32 v72, v10 offset:swizzle(SWAP,16)
	s_waitcnt lgkmcnt(0)
	v_add_f32_e32 v10, v10, v72
	v_mov_b32_e32 v72, v10
	s_nop 1
	v_permlane32_swap_b32_e32 v10, v72
	v_add_f32_e32 v10, v10, v72
	v_fmamk_f32 v10, v10, 0x3a800000, v176
	v_cmp_gt_f32_e32 vcc, s33, v10
	v_mul_f32_e32 v72, 0x4b800000, v10
	s_nop 0
	v_cndmask_b32_e32 v10, v10, v72, vcc
	v_rsq_f32_e32 v10, v10
	s_nop 0
	v_mul_f32_e32 v72, 0x45800000, v10
	v_cndmask_b32_e32 v10, v10, v72, vcc
	v_pk_mul_f32 v[64:65], v[64:65], v[10:11] op_sel_hi:[1,0]
	v_pk_mul_f32 v[58:59], v[58:59], v[10:11] op_sel_hi:[1,0]
	v_pk_fma_f32 v[22:23], v[44:45], v[64:65], v[22:23]
	v_pk_fma_f32 v[24:25], v[42:43], v[58:59], v[24:25]
	v_cvt_pk_bf16_f32 v22, v22, v23
	v_pk_mul_f32 v[42:43], v[60:61], v[10:11] op_sel_hi:[1,0]
	v_cvt_pk_bf16_f32 v23, v24, v25
	v_add_co_u32_e32 v24, vcc, s10, v54
	v_pk_fma_f32 v[28:29], v[46:47], v[42:43], v[28:29]
	s_nop 0
	v_addc_co_u32_e32 v25, vcc, 0, v55, vcc
	global_store_dwordx2 v[24:25], v[22:23], off
	v_pk_mul_f32 v[22:23], v[66:67], v[10:11] op_sel_hi:[1,0]
	s_nop 0
	v_pk_fma_f32 v[22:23], v[48:49], v[22:23], v[26:27]
	v_pk_mul_f32 v[26:27], v[62:63], v[10:11] op_sel_hi:[1,0]
	v_cvt_pk_bf16_f32 v22, v22, v23
	v_cvt_pk_bf16_f32 v23, v28, v29
	global_store_dwordx2 v[24:25], v[22:23], off offset:512
	v_pk_mul_f32 v[22:23], v[68:69], v[10:11] op_sel_hi:[1,0]
	v_pk_fma_f32 v[26:27], v[50:51], v[26:27], v[32:33]
	v_pk_fma_f32 v[22:23], v[52:53], v[22:23], v[30:31]
	s_nop 0
	v_cvt_pk_bf16_f32 v22, v22, v23
	v_cvt_pk_bf16_f32 v23, v26, v27
	global_store_dwordx2 v[24:25], v[22:23], off offset:1024
	v_pk_mul_f32 v[22:23], v[70:71], v[10:11] op_sel_hi:[1,0]
	v_pk_mul_f32 v[26:27], v[56:57], v[10:11] op_sel_hi:[1,0]
	v_pk_fma_f32 v[22:23], v[38:39], v[22:23], v[34:35]
	v_pk_fma_f32 v[26:27], v[40:41], v[26:27], v[36:37]
	v_cvt_pk_bf16_f32 v22, v22, v23
	s_nop 0
	v_cvt_pk_bf16_f32 v23, v26, v27
	global_store_dwordx2 v[24:25], v[22:23], off offset:1536
	s_cbranch_scc1 .LBB0_1135

; __device__ __forceinline__ unsigned xb_ld(unsigned* p)              { return __hip_atomic_load(p, __ATOMIC_RELAXED, __HIP_MEMORY_SCOPE_AGENT); }
; __device__ __forceinline__ unsigned xb_add(unsigned* p, unsigned v) { return __hip_atomic_fetch_add(p, v, __ATOMIC_RELAXED, __HIP_MEMORY_SCOPE_AGENT); }
; #define XB_SPIN(cond, bar) do { unsigned _sp = 0; while (cond) { __builtin_amdgcn_s_sleep(1); \
;     if ((++_sp & 255u) == 0u) { if (xb_ld(&(bar)[XB_TMO])) break; if (_sp > XB_SPIN_CAP) { atomicAdd(&(bar)[XB_TMO], 1u); break; } } } } while (0)
; __device__ __forceinline__ void xcd_barrier(const XcdBarrier& b, int tid) {
;     ...
;     if (tid == 0) {
;         unsigned* bar = b.bar; unsigned bx_ = b.x; asm volatile("" : "+s"(bar), "+s"(bx_));
;         __builtin_amdgcn_s_waitcnt(0);
;         unsigned nloc = b.st[0], nx = b.st[1];
;         if (nloc == 0u) { xcd_barrier_complete(bar, bx_, nloc, nx); b.st[0] = nloc; b.st[1] = nx; }
;         const unsigned old = xb_add(&bar[XB_XSUB(bx_)], 1u);
;         const unsigned gen = old / nloc;
;         if (old + 1u == (gen + 1u) * nloc) {
;             __builtin_amdgcn_fence(__ATOMIC_RELEASE, "agent");
;             asm volatile("s_waitcnt vmcnt(0)" ::: "memory");
;             const unsigned og = xb_add(&bar[XB_TOP], 1u);
;             const unsigned tg = og / nx;
;             if (og + 1u == (tg + 1u) * nx) xb_add(&bar[XB_TOPGEN], 1u);
;             else XB_SPIN(xb_ld(&bar[XB_TOPGEN]) == tg, bar);
;             __builtin_amdgcn_fence(__ATOMIC_ACQUIRE, "agent");
;             xb_add(&bar[XB_XGEN(bx_)], 1u);
;             asm volatile("s_waitcnt vmcnt(0)" ::: "memory");
;         } else {
;             XB_SPIN(xb_ld(&bar[XB_XGEN(bx_)]) == gen, bar);
.LBB0_1151:
	s_lshl_b32 s28, s50, 6
	s_add_i32 s64, s28, 0x500
	s_lshl_b64 s[6:7], s[64:65], 2
	s_add_u32 s6, s58, s6
	s_addc_u32 s7, s59, s7
	v_mov_b64_e32 v[4:5], s[6:7]
	v_mov_b32_e32 v1, 1
	flat_atomic_add v3, v[4:5], v1 sc0
	v_cvt_f32_u32_e32 v1, v2
	v_sub_u32_e32 v4, 0, v2
	v_rcp_iflag_f32_e32 v1, v1
	s_nop 0
	v_mul_f32_e32 v1, 0x4f7ffffe, v1
	v_cvt_u32_f32_e32 v1, v1
	v_mul_lo_u32 v4, v4, v1
	v_mul_hi_u32 v4, v1, v4
	v_add_u32_e32 v1, v1, v4
	s_waitcnt vmcnt(0) lgkmcnt(0)
	v_mul_hi_u32 v1, v3, v1
	v_mul_lo_u32 v4, v1, v2
	v_sub_u32_e32 v4, v3, v4
	v_cmp_ge_u32_e32 vcc, v4, v2
	v_add_u32_e32 v5, 1, v1
	s_nop 0
	v_cndmask_b32_e32 v1, v1, v5, vcc
	v_sub_u32_e32 v5, v4, v2
	v_cndmask_b32_e32 v4, v4, v5, vcc
	v_cmp_ge_u32_e32 vcc, v4, v2
	v_add_u32_e32 v4, 1, v1
	s_nop 0
	v_cndmask_b32_e32 v1, v1, v4, vcc
	v_add_u32_e32 v4, 1, v3
	v_mad_u64_u32 v[2:3], s[6:7], v2, v1, v[2:3]
	v_cmp_ne_u32_e32 vcc, v4, v2
	s_and_saveexec_b64 s[6:7], vcc
	s_xor_b64 s[6:7], exec, s[6:7]
	s_cbranch_execz .LBB0_1164
	s_add_i32 s64, s28, 0x900
	s_lshl_b64 s[8:9], s[64:65], 2
	s_add_u32 s10, s58, s8
	s_addc_u32 s11, s59, s9
	v_mov_b64_e32 v[2:3], s[10:11]
	global_load_dword v0, v[2:3], off sc1
	s_waitcnt vmcnt(0) lgkmcnt(0)
	v_cmp_eq_u32_e32 vcc, v0, v1
	s_and_saveexec_b64 s[8:9], vcc
	s_cbranch_execz .LBB0_1163
	s_mov_b32 s26, 1
	s_mov_b64 s[12:13], 0
	s_branch .LBB0_1155

.LBB0_1155:
	s_and_b32 s20, s26, 0xff
	s_mov_b64 s[18:19], -1
	s_cmp_lg_u32 s20, 0
	s_mov_b64 s[20:21], -1
	s_sleep 1
	s_cbranch_scc1 .LBB0_1159
	v_mov_b64_e32 v[2:3], s[58:59]
	global_load_dword v0, v[2:3], off offset:512 sc1
	s_mov_b64 s[20:21], 0
	s_mov_b64 s[22:23], -1
	s_waitcnt vmcnt(0) lgkmcnt(0)
	v_cmp_eq_u32_e32 vcc, 0, v0
	s_and_saveexec_b64 s[24:25], vcc
	s_cmp_lt_u32 s26, 0x40001
	s_cselect_b64 s[20:21], -1, 0
	s_xor_b64 s[22:23], exec, -1
	s_and_b64 s[20:21], s[20:21], exec
	s_or_b64 exec, exec, s[24:25]

; __device__ __forceinline__ unsigned xb_ld(unsigned* p)              { return __hip_atomic_load(p, __ATOMIC_RELAXED, __HIP_MEMORY_SCOPE_AGENT); }
; __device__ __forceinline__ unsigned xb_add(unsigned* p, unsigned v) { return __hip_atomic_fetch_add(p, v, __ATOMIC_RELAXED, __HIP_MEMORY_SCOPE_AGENT); }
; #define XB_SPIN(cond, bar) do { unsigned _sp = 0; while (cond) { __builtin_amdgcn_s_sleep(1); \
;     if ((++_sp & 255u) == 0u) { if (xb_ld(&(bar)[XB_TMO])) break; if (_sp > XB_SPIN_CAP) { atomicAdd(&(bar)[XB_TMO], 1u); break; } } } } while (0)
; __device__ __forceinline__ void xcd_barrier(const XcdBarrier& b, int tid) {
;     ...
;             __builtin_amdgcn_fence(__ATOMIC_RELEASE, "agent");
;             asm volatile("s_waitcnt vmcnt(0)" ::: "memory");
;             const unsigned og = xb_add(&bar[XB_TOP], 1u);
;             const unsigned tg = og / nx;
;             if (og + 1u == (tg + 1u) * nx) xb_add(&bar[XB_TOPGEN], 1u);
;             else XB_SPIN(xb_ld(&bar[XB_TOPGEN]) == tg, bar);
.LBB0_1164:
	s_andn2_saveexec_b64 s[6:7], s[6:7]
	s_cbranch_execz .LBB0_1180
	v_mov_b32_e32 v1, s58
	v_add_co_u32_e32 v2, vcc, 0x3000, v1
	v_mov_b32_e32 v1, s59
	buffer_wbl2 sc1
	s_waitcnt vmcnt(0)
	v_addc_co_u32_e32 v3, vcc, 0, v1, vcc
	v_mov_b32_e32 v1, 1
	flat_atomic_add v1, v[2:3], v1 offset:1024 sc0
	v_cvt_f32_u32_e32 v2, v0
	v_sub_u32_e32 v3, 0, v0
	s_mov_b64 s[12:13], -1
	v_rcp_iflag_f32_e32 v2, v2
	s_nop 0
	v_mul_f32_e32 v2, 0x4f7ffffe, v2
	v_cvt_u32_f32_e32 v2, v2
	v_mul_lo_u32 v3, v3, v2
	v_mul_hi_u32 v3, v2, v3
	v_add_u32_e32 v2, v2, v3
	s_waitcnt vmcnt(0) lgkmcnt(0)
	v_mul_hi_u32 v2, v1, v2
	v_mul_lo_u32 v3, v2, v0
	v_sub_u32_e32 v3, v1, v3
	v_cmp_ge_u32_e32 vcc, v3, v0
	v_add_u32_e32 v4, 1, v2
	s_nop 0
	v_cndmask_b32_e32 v2, v2, v4, vcc
	v_sub_u32_e32 v4, v3, v0
	v_cndmask_b32_e32 v3, v3, v4, vcc
	v_cmp_ge_u32_e32 vcc, v3, v0
	v_add_u32_e32 v3, 1, v2
	s_nop 0
	v_cndmask_b32_e32 v2, v2, v3, vcc
	v_add_u32_e32 v3, 1, v1
	v_mad_u64_u32 v[0:1], s[8:9], v0, v2, v[0:1]
	s_add_u32 s8, s58, 0x3500
	s_addc_u32 s9, s59, 0
	v_cmp_ne_u32_e32 vcc, v3, v0
	v_mov_b64_e32 v[0:1], s[8:9]
	s_and_saveexec_b64 s[10:11], vcc
	s_cbranch_execz .LBB0_1177
	v_mov_b64_e32 v[0:1], s[8:9]
	global_load_dword v0, v[0:1], off sc1
	s_mov_b64 s[16:17], 0
	s_waitcnt vmcnt(0) lgkmcnt(0)
	v_cmp_eq_u32_e32 vcc, v0, v2
	s_and_saveexec_b64 s[14:15], vcc
	s_cbranch_execz .LBB0_1176
	s_add_u32 s12, s58, 0x200
	s_addc_u32 s13, s59, 0
	s_mov_b32 s29, 1
	s_branch .LBB0_1169

; __device__ __forceinline__ unsigned cvt_pk_bf16(float lo, float hi) { unsigned r; asm volatile("v_cvt_pk_bf16_f32 %0, %1, %2" : "=v"(r) : "v"(lo), "v"(hi)); return r; }
;     __device__ __forceinline__ void operator()(const f32x4 (&acc)[2][2][4][2], const Unit& u, int wr, int wc, int fr, int fq) const {
;         const int lane = fr + 16 * fq, r2 = lane >> 2, q2 = lane & 3;
;         const int src4 = (r2 + 16 * q2) << 2;
;         const int row0 = u.pm * BM + wr * 64 + r2; const int col0 = u.pn * BM + wc * 32 + 8 * q2;
; #pragma unroll
;         for (int ai = 0; ai < 2; ++ai)
; #pragma unroll
;             for (int m = 0; m < 4; ++m) { bf16_t* rowp = O + (size_t)(row0 + ai * HALF + m * 16) * ldc + col0;
; #pragma unroll
;                 for (int bj = 0; bj < 2; ++bj) { f32x4 v0 = acc[ai][bj][m][0], v1 = acc[ai][bj][m][1];
;                     if (ACT == 1) {
; #pragma unroll
;                         for (int j = 0; j < 4; ++j) { const float a = fmaxf(v0[j], 0.f), b = fmaxf(v1[j], 0.f); v0[j] = a * a; v1[j] = b * b; } }
;                     u32x4 w; w.x = cvt_pk_bf16(v0[0], v0[1]); w.y = cvt_pk_bf16(v0[2], v0[3]); w.z = cvt_pk_bf16(v1[0], v1[1]); w.w = cvt_pk_bf16(v1[2], v1[3]);
;                     w.x = (unsigned)__builtin_amdgcn_ds_bpermute(src4, (int)w.x); w.y = (unsigned)__builtin_amdgcn_ds_bpermute(src4, (int)w.y);
;                     w.z = (unsigned)__builtin_amdgcn_ds_bpermute(src4, (int)w.z); w.w = (unsigned)__builtin_amdgcn_ds_bpermute(src4, (int)w.w);
;                     *(u32x4*)(rowp + bj * HALF) = w; } }
;     }
.LBB0_1197:
	v_max_f32_e32 v128, v128, v128
	v_max_f32_e32 v129, v129, v129
	v_max_f32_e32 v128, 0, v128
	v_max_f32_e32 v124, v124, v124
	v_max_f32_e32 v129, 0, v129
	v_max_f32_e32 v125, v125, v125
	v_max_f32_e32 v130, v130, v130
	v_max_f32_e32 v131, v131, v131
	v_max_f32_e32 v124, 0, v124
	v_mul_f32_e32 v128, v128, v128
	v_max_f32_e32 v125, 0, v125
	v_mul_f32_e32 v129, v129, v129
	v_max_f32_e32 v130, 0, v130
	v_max_f32_e32 v126, v126, v126
	v_max_f32_e32 v131, 0, v131
	v_max_f32_e32 v127, v127, v127
	v_mul_f32_e32 v124, v124, v124
	v_mul_f32_e32 v125, v125, v125
	v_max_f32_e32 v126, 0, v126
	v_mul_f32_e32 v130, v130, v130
	v_max_f32_e32 v127, 0, v127
	v_mul_f32_e32 v131, v131, v131
	v_cvt_pk_bf16_f32 v128, v128, v129
	v_cvt_pk_bf16_f32 v129, v130, v131
	v_lshl_add_u32 v140, s61, 8, v144
	v_mul_f32_e32 v126, v126, v126
	v_mul_f32_e32 v127, v127, v127
	v_cvt_pk_bf16_f32 v124, v124, v125
	v_cvt_pk_bf16_f32 v125, v126, v127
	ds_bpermute_b32 v128, v143, v128
	ds_bpermute_b32 v129, v143, v129
	ds_bpermute_b32 v130, v143, v124
	ds_bpermute_b32 v131, v143, v125
	v_lshl_or_b32 v156, s60, 8, v145
	v_ashrrev_i32_e32 v141, 31, v140
	v_ashrrev_i32_e32 v157, 31, v156
	v_lshlrev_b64 v[124:125], 13, v[140:141]
	v_max_f32_e32 v120, v120, v120
	v_max_f32_e32 v121, v121, v121
	v_max_f32_e32 v122, v122, v122
	v_max_f32_e32 v119, v119, v119
	v_lshl_add_u64 v[124:125], s[12:13], 0, v[124:125]
	v_lshlrev_b64 v[126:127], 1, v[156:157]
	v_max_f32_e32 v120, 0, v120
	v_max_f32_e32 v116, v116, v116
	v_max_f32_e32 v121, 0, v121
	v_max_f32_e32 v117, v117, v117
	v_max_f32_e32 v122, 0, v122
	v_max_f32_e32 v118, v118, v118
	v_max_f32_e32 v123, v123, v123
	v_max_f32_e32 v119, 0, v119
	v_lshl_add_u64 v[124:125], v[124:125], 0, v[126:127]
	v_max_f32_e32 v116, 0, v116
	v_mul_f32_e32 v120, v120, v120
	v_max_f32_e32 v117, 0, v117
	v_mul_f32_e32 v121, v121, v121
	v_max_f32_e32 v118, 0, v118
	v_mul_f32_e32 v122, v122, v122
	v_max_f32_e32 v123, 0, v123
	v_mul_f32_e32 v119, v119, v119
	s_waitcnt lgkmcnt(0)
	global_store_dwordx4 v[124:125], v[128:131], off
	v_mul_f32_e32 v116, v116, v116
	v_mul_f32_e32 v117, v117, v117
	v_mul_f32_e32 v118, v118, v118
	v_mul_f32_e32 v123, v123, v123
	v_cvt_pk_bf16_f32 v120, v120, v121
	v_cvt_pk_bf16_f32 v121, v122, v123
	v_cvt_pk_bf16_f32 v122, v116, v117
	v_cvt_pk_bf16_f32 v119, v118, v119
	ds_bpermute_b32 v116, v143, v120
	ds_bpermute_b32 v117, v143, v121
	ds_bpermute_b32 v118, v143, v122
	ds_bpermute_b32 v119, v143, v119
	v_max_f32_e32 v112, v112, v112
	v_max_f32_e32 v113, v113, v113
	v_max_f32_e32 v114, v114, v114
	v_max_f32_e32 v111, v111, v111
	v_max_f32_e32 v112, 0, v112
	v_max_f32_e32 v108, v108, v108
	v_max_f32_e32 v113, 0, v113
	v_max_f32_e32 v109, v109, v109
	v_max_f32_e32 v114, 0, v114
	v_max_f32_e32 v110, v110, v110
	v_max_f32_e32 v115, v115, v115
	v_max_f32_e32 v111, 0, v111
	v_max_f32_e32 v108, 0, v108
	v_mul_f32_e32 v112, v112, v112
	v_max_f32_e32 v109, 0, v109
	v_mul_f32_e32 v113, v113, v113
	v_max_f32_e32 v110, 0, v110
	v_mul_f32_e32 v114, v114, v114
	v_max_f32_e32 v115, 0, v115
	v_mul_f32_e32 v111, v111, v111
	s_waitcnt lgkmcnt(0)
	global_store_dwordx4 v[124:125], v[116:119], off offset:256
	v_mul_f32_e32 v108, v108, v108
	v_mul_f32_e32 v109, v109, v109
	v_mul_f32_e32 v110, v110, v110
	v_mul_f32_e32 v115, v115, v115
	v_cvt_pk_bf16_f32 v112, v112, v113
	v_cvt_pk_bf16_f32 v113, v114, v115
	v_cvt_pk_bf16_f32 v114, v108, v109
	v_cvt_pk_bf16_f32 v111, v110, v111
	v_or_b32_e32 v116, 16, v140
	ds_bpermute_b32 v108, v143, v112
	ds_bpermute_b32 v109, v143, v113
	ds_bpermute_b32 v110, v143, v114
	ds_bpermute_b32 v111, v143, v111
	v_ashrrev_i32_e32 v117, 31, v116
	v_lshlrev_b64 v[112:113], 13, v[116:117]
	v_max_f32_e32 v104, v104, v104
	v_max_f32_e32 v105, v105, v105
	v_max_f32_e32 v106, v106, v106
	v_max_f32_e32 v103, v103, v103
	v_lshl_add_u64 v[112:113], s[12:13], 0, v[112:113]
	v_max_f32_e32 v104, 0, v104
	v_max_f32_e32 v100, v100, v100
	v_max_f32_e32 v105, 0, v105
	v_max_f32_e32 v101, v101, v101
	v_max_f32_e32 v106, 0, v106
	v_max_f32_e32 v102, v102, v102
	v_max_f32_e32 v107, v107, v107
	v_max_f32_e32 v103, 0, v103
	v_lshl_add_u64 v[112:113], v[112:113], 0, v[126:127]
	v_max_f32_e32 v100, 0, v100
	v_mul_f32_e32 v104, v104, v104
	v_max_f32_e32 v101, 0, v101
	v_mul_f32_e32 v105, v105, v105
	v_max_f32_e32 v102, 0, v102
	v_mul_f32_e32 v106, v106, v106
	v_max_f32_e32 v107, 0, v107
	v_mul_f32_e32 v103, v103, v103
	s_waitcnt lgkmcnt(0)
	global_store_dwordx4 v[112:113], v[108:111], off
	v_mul_f32_e32 v100, v100, v100
	v_mul_f32_e32 v101, v101, v101
	v_mul_f32_e32 v102, v102, v102
	v_mul_f32_e32 v107, v107, v107
	v_cvt_pk_bf16_f32 v104, v104, v105
	v_cvt_pk_bf16_f32 v105, v106, v107
	v_cvt_pk_bf16_f32 v106, v100, v101
	v_cvt_pk_bf16_f32 v103, v102, v103
	ds_bpermute_b32 v100, v143, v104
	ds_bpermute_b32 v101, v143, v105
	ds_bpermute_b32 v102, v143, v106
	ds_bpermute_b32 v103, v143, v103
	v_max_f32_e32 v96, v96, v96
	v_max_f32_e32 v97, v97, v97
	v_max_f32_e32 v98, v98, v98
	v_max_f32_e32 v95, v95, v95
	v_max_f32_e32 v96, 0, v96
	v_max_f32_e32 v92, v92, v92
	v_max_f32_e32 v97, 0, v97
	v_max_f32_e32 v93, v93, v93
	v_max_f32_e32 v98, 0, v98
	v_max_f32_e32 v94, v94, v94
	v_max_f32_e32 v99, v99, v99
	v_max_f32_e32 v95, 0, v95
	v_max_f32_e32 v92, 0, v92
	v_mul_f32_e32 v96, v96, v96
	v_max_f32_e32 v93, 0, v93
	v_mul_f32_e32 v97, v97, v97
	v_max_f32_e32 v94, 0, v94
	v_mul_f32_e32 v98, v98, v98
	v_max_f32_e32 v99, 0, v99
	v_mul_f32_e32 v95, v95, v95
	s_waitcnt lgkmcnt(0)
; __device__ __forceinline__ unsigned cvt_pk_bf16(float lo, float hi) { unsigned r; asm volatile("v_cvt_pk_bf16_f32 %0, %1, %2" : "=v"(r) : "v"(lo), "v"(hi)); return r; }
;     __device__ __forceinline__ void operator()(const f32x4 (&acc)[2][2][4][2], const Unit& u, int wr, int wc, int fr, int fq) const {
;         const int lane = fr + 16 * fq, r2 = lane >> 2, q2 = lane & 3;
;         const int src4 = (r2 + 16 * q2) << 2;
;         const int row0 = u.pm * BM + wr * 64 + r2; const int col0 = u.pn * BM + wc * 32 + 8 * q2;
; #pragma unroll
;         for (int ai = 0; ai < 2; ++ai)
; #pragma unroll
;             for (int m = 0; m < 4; ++m) { bf16_t* rowp = O + (size_t)(row0 + ai * HALF + m * 16) * ldc + col0;
; #pragma unroll
;                 for (int bj = 0; bj < 2; ++bj) { f32x4 v0 = acc[ai][bj][m][0], v1 = acc[ai][bj][m][1];
;                     if (ACT == 1) {
; #pragma unroll
;                         for (int j = 0; j < 4; ++j) { const float a = fmaxf(v0[j], 0.f), b = fmaxf(v1[j], 0.f); v0[j] = a * a; v1[j] = b * b; } }
;                     u32x4 w; w.x = cvt_pk_bf16(v0[0], v0[1]); w.y = cvt_pk_bf16(v0[2], v0[3]); w.z = cvt_pk_bf16(v1[0], v1[1]); w.w = cvt_pk_bf16(v1[2], v1[3]);
;                     w.x = (unsigned)__builtin_amdgcn_ds_bpermute(src4, (int)w.x); w.y = (unsigned)__builtin_amdgcn_ds_bpermute(src4, (int)w.y);
;                     w.z = (unsigned)__builtin_amdgcn_ds_bpermute(src4, (int)w.z); w.w = (unsigned)__builtin_amdgcn_ds_bpermute(src4, (int)w.w);
;                     *(u32x4*)(rowp + bj * HALF) = w; } }
;     }
	global_store_dwordx4 v[112:113], v[100:103], off offset:256
	v_mul_f32_e32 v92, v92, v92
	v_mul_f32_e32 v93, v93, v93
	v_mul_f32_e32 v94, v94, v94
	v_mul_f32_e32 v99, v99, v99
	v_cvt_pk_bf16_f32 v96, v96, v97
	v_cvt_pk_bf16_f32 v97, v98, v99
	v_cvt_pk_bf16_f32 v98, v92, v93
	v_cvt_pk_bf16_f32 v95, v94, v95
	v_or_b32_e32 v100, 32, v140
	ds_bpermute_b32 v92, v143, v96
	ds_bpermute_b32 v93, v143, v97
	ds_bpermute_b32 v94, v143, v98
	ds_bpermute_b32 v95, v143, v95
	v_ashrrev_i32_e32 v101, 31, v100
	v_lshlrev_b64 v[96:97], 13, v[100:101]
	v_max_f32_e32 v88, v88, v88
	v_max_f32_e32 v89, v89, v89
	v_max_f32_e32 v90, v90, v90
	v_max_f32_e32 v87, v87, v87
	v_lshl_add_u64 v[96:97], s[12:13], 0, v[96:97]
	v_max_f32_e32 v88, 0, v88
	v_max_f32_e32 v84, v84, v84
	v_max_f32_e32 v89, 0, v89
	v_max_f32_e32 v85, v85, v85
	v_max_f32_e32 v90, 0, v90
	v_max_f32_e32 v86, v86, v86
	v_max_f32_e32 v91, v91, v91
	v_max_f32_e32 v87, 0, v87
	v_lshl_add_u64 v[96:97], v[96:97], 0, v[126:127]
	v_max_f32_e32 v84, 0, v84
	v_mul_f32_e32 v88, v88, v88
	v_max_f32_e32 v85, 0, v85
	v_mul_f32_e32 v89, v89, v89
	v_max_f32_e32 v86, 0, v86
	v_mul_f32_e32 v90, v90, v90
	v_max_f32_e32 v91, 0, v91
	v_mul_f32_e32 v87, v87, v87
	s_waitcnt lgkmcnt(0)
	global_store_dwordx4 v[96:97], v[92:95], off
	v_mul_f32_e32 v84, v84, v84
	v_mul_f32_e32 v85, v85, v85
	v_mul_f32_e32 v86, v86, v86
	v_mul_f32_e32 v91, v91, v91
	v_cvt_pk_bf16_f32 v88, v88, v89
	v_cvt_pk_bf16_f32 v89, v90, v91
	v_cvt_pk_bf16_f32 v90, v84, v85
	v_cvt_pk_bf16_f32 v87, v86, v87
	ds_bpermute_b32 v84, v143, v88
	ds_bpermute_b32 v85, v143, v89
	ds_bpermute_b32 v86, v143, v90
	ds_bpermute_b32 v87, v143, v87
	v_max_f32_e32 v80, v80, v80
	v_max_f32_e32 v81, v81, v81
	v_max_f32_e32 v82, v82, v82
	v_max_f32_e32 v79, v79, v79
	v_max_f32_e32 v80, 0, v80
	v_max_f32_e32 v76, v76, v76
	v_max_f32_e32 v81, 0, v81
	v_max_f32_e32 v77, v77, v77
	v_max_f32_e32 v82, 0, v82
	v_max_f32_e32 v78, v78, v78
	v_max_f32_e32 v83, v83, v83
	v_max_f32_e32 v79, 0, v79
	v_max_f32_e32 v76, 0, v76
	v_mul_f32_e32 v80, v80, v80
	v_max_f32_e32 v77, 0, v77
	v_mul_f32_e32 v81, v81, v81
	v_max_f32_e32 v78, 0, v78
	v_mul_f32_e32 v82, v82, v82
	v_max_f32_e32 v83, 0, v83
	v_mul_f32_e32 v79, v79, v79
	s_waitcnt lgkmcnt(0)
	global_store_dwordx4 v[96:97], v[84:87], off offset:256
	v_mul_f32_e32 v76, v76, v76
	v_mul_f32_e32 v77, v77, v77
	v_mul_f32_e32 v78, v78, v78
	v_mul_f32_e32 v83, v83, v83
	v_cvt_pk_bf16_f32 v80, v80, v81
	v_cvt_pk_bf16_f32 v81, v82, v83
	v_cvt_pk_bf16_f32 v82, v76, v77
	v_cvt_pk_bf16_f32 v79, v78, v79
	v_or_b32_e32 v84, 48, v140
	ds_bpermute_b32 v76, v143, v80
	ds_bpermute_b32 v77, v143, v81
	ds_bpermute_b32 v78, v143, v82
	ds_bpermute_b32 v79, v143, v79
	v_ashrrev_i32_e32 v85, 31, v84
	v_lshlrev_b64 v[80:81], 13, v[84:85]
	v_max_f32_e32 v72, v72, v72
	v_max_f32_e32 v73, v73, v73
	v_max_f32_e32 v74, v74, v74
	v_max_f32_e32 v71, v71, v71
	v_lshl_add_u64 v[80:81], s[12:13], 0, v[80:81]
	v_max_f32_e32 v72, 0, v72
	v_max_f32_e32 v68, v68, v68
	v_max_f32_e32 v73, 0, v73
	v_max_f32_e32 v69, v69, v69
	v_max_f32_e32 v74, 0, v74
	v_max_f32_e32 v70, v70, v70
	v_max_f32_e32 v75, v75, v75
	v_max_f32_e32 v71, 0, v71
	v_lshl_add_u64 v[80:81], v[80:81], 0, v[126:127]
	v_max_f32_e32 v68, 0, v68
	v_mul_f32_e32 v72, v72, v72
	v_max_f32_e32 v69, 0, v69
	v_mul_f32_e32 v73, v73, v73
	v_max_f32_e32 v70, 0, v70
	v_mul_f32_e32 v74, v74, v74
	v_max_f32_e32 v75, 0, v75
	v_mul_f32_e32 v71, v71, v71
	s_waitcnt lgkmcnt(0)
	global_store_dwordx4 v[80:81], v[76:79], off
	v_mul_f32_e32 v68, v68, v68
	v_mul_f32_e32 v69, v69, v69
	v_mul_f32_e32 v70, v70, v70
	v_mul_f32_e32 v75, v75, v75
	v_cvt_pk_bf16_f32 v72, v72, v73
	v_cvt_pk_bf16_f32 v73, v74, v75
	v_cvt_pk_bf16_f32 v74, v68, v69
	v_cvt_pk_bf16_f32 v71, v70, v71
	ds_bpermute_b32 v68, v143, v72
	ds_bpermute_b32 v69, v143, v73
	ds_bpermute_b32 v70, v143, v74
	ds_bpermute_b32 v71, v143, v71
	v_max_f32_e32 v64, v64, v64
	v_max_f32_e32 v65, v65, v65
	v_max_f32_e32 v66, v66, v66
	v_max_f32_e32 v63, v63, v63
	v_max_f32_e32 v64, 0, v64
	v_max_f32_e32 v60, v60, v60
	v_max_f32_e32 v65, 0, v65
	v_max_f32_e32 v61, v61, v61
	v_max_f32_e32 v66, 0, v66
	v_max_f32_e32 v62, v62, v62
	v_max_f32_e32 v67, v67, v67
	v_max_f32_e32 v63, 0, v63
	v_max_f32_e32 v60, 0, v60
	v_mul_f32_e32 v64, v64, v64
	v_max_f32_e32 v61, 0, v61
	v_mul_f32_e32 v65, v65, v65
	v_max_f32_e32 v62, 0, v62
	v_mul_f32_e32 v66, v66, v66
	v_max_f32_e32 v67, 0, v67
	v_mul_f32_e32 v63, v63, v63
	s_waitcnt lgkmcnt(0)
	global_store_dwordx4 v[80:81], v[68:71], off offset:256
	v_mul_f32_e32 v60, v60, v60
	v_mul_f32_e32 v61, v61, v61
	v_mul_f32_e32 v62, v62, v62
	v_mul_f32_e32 v67, v67, v67
	v_cvt_pk_bf16_f32 v64, v64, v65
	v_cvt_pk_bf16_f32 v65, v66, v67
	v_cvt_pk_bf16_f32 v66, v60, v61
	v_cvt_pk_bf16_f32 v63, v62, v63
	ds_bpermute_b32 v60, v143, v64
	ds_bpermute_b32 v61, v143, v65
	ds_bpermute_b32 v62, v143, v66
	ds_bpermute_b32 v63, v143, v63
	s_mov_b32 s17, 0x100000
	v_max_f32_e32 v56, v56, v56
	v_max_f32_e32 v57, v57, v57
	v_max_f32_e32 v58, v58, v58
	v_max_f32_e32 v55, v55, v55
	v_add_co_u32_e32 v64, vcc, s17, v124
	v_max_f32_e32 v56, 0, v56
	v_max_f32_e32 v52, v52, v52
	v_max_f32_e32 v57, 0, v57
	v_max_f32_e32 v53, v53, v53
	v_max_f32_e32 v58, 0, v58
	v_max_f32_e32 v54, v54, v54
	v_max_f32_e32 v59, v59, v59
	v_max_f32_e32 v55, 0, v55
	v_addc_co_u32_e32 v65, vcc, 0, v125, vcc
	v_max_f32_e32 v52, 0, v52
	v_mul_f32_e32 v56, v56, v56
	v_max_f32_e32 v53, 0, v53
	v_mul_f32_e32 v57, v57, v57
	v_max_f32_e32 v54, 0, v54
	v_mul_f32_e32 v58, v58, v58
	v_max_f32_e32 v59, 0, v59
	v_mul_f32_e32 v55, v55, v55
	s_waitcnt lgkmcnt(0)
; __device__ __forceinline__ unsigned cvt_pk_bf16(float lo, float hi) { unsigned r; asm volatile("v_cvt_pk_bf16_f32 %0, %1, %2" : "=v"(r) : "v"(lo), "v"(hi)); return r; }
;     __device__ __forceinline__ void operator()(const f32x4 (&acc)[2][2][4][2], const Unit& u, int wr, int wc, int fr, int fq) const {
;         const int lane = fr + 16 * fq, r2 = lane >> 2, q2 = lane & 3;
;         const int src4 = (r2 + 16 * q2) << 2;
;         const int row0 = u.pm * BM + wr * 64 + r2; const int col0 = u.pn * BM + wc * 32 + 8 * q2;
; #pragma unroll
;         for (int ai = 0; ai < 2; ++ai)
; #pragma unroll
;             for (int m = 0; m < 4; ++m) { bf16_t* rowp = O + (size_t)(row0 + ai * HALF + m * 16) * ldc + col0;
; #pragma unroll
;                 for (int bj = 0; bj < 2; ++bj) { f32x4 v0 = acc[ai][bj][m][0], v1 = acc[ai][bj][m][1];
;                     if (ACT == 1) {
; #pragma unroll
;                         for (int j = 0; j < 4; ++j) { const float a = fmaxf(v0[j], 0.f), b = fmaxf(v1[j], 0.f); v0[j] = a * a; v1[j] = b * b; } }
;                     u32x4 w; w.x = cvt_pk_bf16(v0[0], v0[1]); w.y = cvt_pk_bf16(v0[2], v0[3]); w.z = cvt_pk_bf16(v1[0], v1[1]); w.w = cvt_pk_bf16(v1[2], v1[3]);
;                     w.x = (unsigned)__builtin_amdgcn_ds_bpermute(src4, (int)w.x); w.y = (unsigned)__builtin_amdgcn_ds_bpermute(src4, (int)w.y);
;                     w.z = (unsigned)__builtin_amdgcn_ds_bpermute(src4, (int)w.z); w.w = (unsigned)__builtin_amdgcn_ds_bpermute(src4, (int)w.w);
;                     *(u32x4*)(rowp + bj * HALF) = w; } }
;     }
	global_store_dwordx4 v[64:65], v[60:63], off
	v_mul_f32_e32 v52, v52, v52
	v_mul_f32_e32 v53, v53, v53
	v_mul_f32_e32 v54, v54, v54
	v_mul_f32_e32 v59, v59, v59
	v_cvt_pk_bf16_f32 v56, v56, v57
	v_cvt_pk_bf16_f32 v57, v58, v59
	v_cvt_pk_bf16_f32 v58, v52, v53
	v_cvt_pk_bf16_f32 v55, v54, v55
	ds_bpermute_b32 v52, v143, v56
	ds_bpermute_b32 v53, v143, v57
	ds_bpermute_b32 v54, v143, v58
	ds_bpermute_b32 v55, v143, v55
	v_max_f32_e32 v48, v48, v48
	v_max_f32_e32 v49, v49, v49
	v_max_f32_e32 v50, v50, v50
	v_max_f32_e32 v47, v47, v47
	s_mov_b64 s[24:25], 0x100000
	v_max_f32_e32 v48, 0, v48
	v_max_f32_e32 v44, v44, v44
	v_max_f32_e32 v49, 0, v49
	v_max_f32_e32 v45, v45, v45
	v_max_f32_e32 v50, 0, v50
	v_max_f32_e32 v46, v46, v46
	v_max_f32_e32 v51, v51, v51
	v_max_f32_e32 v47, 0, v47
	v_lshl_add_u64 v[56:57], v[124:125], 0, s[24:25]
	v_max_f32_e32 v44, 0, v44
	v_mul_f32_e32 v48, v48, v48
	v_max_f32_e32 v45, 0, v45
	v_mul_f32_e32 v49, v49, v49
	v_max_f32_e32 v46, 0, v46
	v_mul_f32_e32 v50, v50, v50
	v_max_f32_e32 v51, 0, v51
	v_mul_f32_e32 v47, v47, v47
	s_waitcnt lgkmcnt(0)
	global_store_dwordx4 v[56:57], v[52:55], off offset:256
	v_mul_f32_e32 v44, v44, v44
	v_mul_f32_e32 v45, v45, v45
	v_mul_f32_e32 v46, v46, v46
	v_mul_f32_e32 v51, v51, v51
	v_cvt_pk_bf16_f32 v48, v48, v49
	v_cvt_pk_bf16_f32 v49, v50, v51
	v_cvt_pk_bf16_f32 v50, v44, v45
	v_cvt_pk_bf16_f32 v47, v46, v47
	ds_bpermute_b32 v44, v143, v48
	ds_bpermute_b32 v45, v143, v49
	ds_bpermute_b32 v46, v143, v50
	ds_bpermute_b32 v47, v143, v47
	s_mov_b32 s17, 0x120000
	v_max_f32_e32 v40, v40, v40
	v_max_f32_e32 v41, v41, v41
	v_max_f32_e32 v42, v42, v42
	v_max_f32_e32 v39, v39, v39
	v_add_co_u32_e32 v48, vcc, s17, v124
	v_max_f32_e32 v40, 0, v40
	v_max_f32_e32 v36, v36, v36
	v_max_f32_e32 v41, 0, v41
	v_max_f32_e32 v37, v37, v37
	v_max_f32_e32 v42, 0, v42
	v_max_f32_e32 v38, v38, v38
	v_max_f32_e32 v43, v43, v43
	v_max_f32_e32 v39, 0, v39
	v_addc_co_u32_e32 v49, vcc, 0, v125, vcc
	v_max_f32_e32 v36, 0, v36
	v_mul_f32_e32 v40, v40, v40
	v_max_f32_e32 v37, 0, v37
	v_mul_f32_e32 v41, v41, v41
	v_max_f32_e32 v38, 0, v38
	v_mul_f32_e32 v42, v42, v42
	v_max_f32_e32 v43, 0, v43
	v_mul_f32_e32 v39, v39, v39
	s_waitcnt lgkmcnt(0)
	global_store_dwordx4 v[48:49], v[44:47], off
	v_mul_f32_e32 v36, v36, v36
	v_mul_f32_e32 v37, v37, v37
	v_mul_f32_e32 v38, v38, v38
	v_mul_f32_e32 v43, v43, v43
	v_cvt_pk_bf16_f32 v40, v40, v41
	v_cvt_pk_bf16_f32 v41, v42, v43
	v_cvt_pk_bf16_f32 v42, v36, v37
	v_cvt_pk_bf16_f32 v39, v38, v39
	ds_bpermute_b32 v36, v143, v40
	ds_bpermute_b32 v37, v143, v41
	ds_bpermute_b32 v38, v143, v42
	ds_bpermute_b32 v39, v143, v39
	v_max_f32_e32 v32, v32, v32
	v_max_f32_e32 v33, v33, v33
	v_max_f32_e32 v34, v34, v34
	v_max_f32_e32 v31, v31, v31
	s_mov_b64 s[24:25], 0x120000
	v_max_f32_e32 v32, 0, v32
	v_max_f32_e32 v28, v28, v28
	v_max_f32_e32 v33, 0, v33
	v_max_f32_e32 v29, v29, v29
	v_max_f32_e32 v34, 0, v34
	v_max_f32_e32 v30, v30, v30
	v_max_f32_e32 v35, v35, v35
	v_max_f32_e32 v31, 0, v31
	v_lshl_add_u64 v[40:41], v[124:125], 0, s[24:25]
	v_max_f32_e32 v28, 0, v28
	v_mul_f32_e32 v32, v32, v32
	v_max_f32_e32 v29, 0, v29
	v_mul_f32_e32 v33, v33, v33
	v_max_f32_e32 v30, 0, v30
	v_mul_f32_e32 v34, v34, v34
	v_max_f32_e32 v35, 0, v35
	v_mul_f32_e32 v31, v31, v31
	s_waitcnt lgkmcnt(0)
; __device__ __forceinline__ unsigned cvt_pk_bf16(float lo, float hi) { unsigned r; asm volatile("v_cvt_pk_bf16_f32 %0, %1, %2" : "=v"(r) : "v"(lo), "v"(hi)); return r; }
;     __device__ __forceinline__ void operator()(const f32x4 (&acc)[2][2][4][2], const Unit& u, int wr, int wc, int fr, int fq) const {
;         const int lane = fr + 16 * fq, r2 = lane >> 2, q2 = lane & 3;
;         const int src4 = (r2 + 16 * q2) << 2;
;         const int row0 = u.pm * BM + wr * 64 + r2; const int col0 = u.pn * BM + wc * 32 + 8 * q2;
; #pragma unroll
;         for (int ai = 0; ai < 2; ++ai)
; #pragma unroll
;             for (int m = 0; m < 4; ++m) { bf16_t* rowp = O + (size_t)(row0 + ai * HALF + m * 16) * ldc + col0;
; #pragma unroll
;                 for (int bj = 0; bj < 2; ++bj) { f32x4 v0 = acc[ai][bj][m][0], v1 = acc[ai][bj][m][1];
;                     if (ACT == 1) {
; #pragma unroll
;                         for (int j = 0; j < 4; ++j) { const float a = fmaxf(v0[j], 0.f), b = fmaxf(v1[j], 0.f); v0[j] = a * a; v1[j] = b * b; } }
;                     u32x4 w; w.x = cvt_pk_bf16(v0[0], v0[1]); w.y = cvt_pk_bf16(v0[2], v0[3]); w.z = cvt_pk_bf16(v1[0], v1[1]); w.w = cvt_pk_bf16(v1[2], v1[3]);
;                     w.x = (unsigned)__builtin_amdgcn_ds_bpermute(src4, (int)w.x); w.y = (unsigned)__builtin_amdgcn_ds_bpermute(src4, (int)w.y);
;                     w.z = (unsigned)__builtin_amdgcn_ds_bpermute(src4, (int)w.z); w.w = (unsigned)__builtin_amdgcn_ds_bpermute(src4, (int)w.w);
;                     *(u32x4*)(rowp + bj * HALF) = w; } }
;     }
	global_store_dwordx4 v[40:41], v[36:39], off offset:256
	v_mul_f32_e32 v28, v28, v28
	v_mul_f32_e32 v29, v29, v29
	v_mul_f32_e32 v30, v30, v30
	v_mul_f32_e32 v35, v35, v35
	v_cvt_pk_bf16_f32 v32, v32, v33
	v_cvt_pk_bf16_f32 v33, v34, v35
	v_cvt_pk_bf16_f32 v34, v28, v29
	v_cvt_pk_bf16_f32 v31, v30, v31
	ds_bpermute_b32 v28, v143, v32
	ds_bpermute_b32 v29, v143, v33
	ds_bpermute_b32 v30, v143, v34
	ds_bpermute_b32 v31, v143, v31
	s_mov_b32 s17, 0x140000
	v_max_f32_e32 v24, v24, v24
	v_max_f32_e32 v25, v25, v25
	v_max_f32_e32 v26, v26, v26
	v_max_f32_e32 v23, v23, v23
	v_add_co_u32_e32 v32, vcc, s17, v124
	v_max_f32_e32 v24, 0, v24
	v_max_f32_e32 v20, v20, v20
	v_max_f32_e32 v25, 0, v25
	v_max_f32_e32 v21, v21, v21
	v_max_f32_e32 v26, 0, v26
	v_max_f32_e32 v22, v22, v22
	v_max_f32_e32 v27, v27, v27
	v_max_f32_e32 v23, 0, v23
	v_addc_co_u32_e32 v33, vcc, 0, v125, vcc
	v_max_f32_e32 v20, 0, v20
	v_mul_f32_e32 v24, v24, v24
	v_max_f32_e32 v21, 0, v21
	v_mul_f32_e32 v25, v25, v25
	v_max_f32_e32 v22, 0, v22
	v_mul_f32_e32 v26, v26, v26
	v_max_f32_e32 v27, 0, v27
	v_mul_f32_e32 v23, v23, v23
	s_waitcnt lgkmcnt(0)
	global_store_dwordx4 v[32:33], v[28:31], off
	v_mul_f32_e32 v20, v20, v20
	v_mul_f32_e32 v21, v21, v21
	v_mul_f32_e32 v22, v22, v22
	v_mul_f32_e32 v27, v27, v27
	v_cvt_pk_bf16_f32 v24, v24, v25
	v_cvt_pk_bf16_f32 v25, v26, v27
	v_cvt_pk_bf16_f32 v26, v20, v21
	v_cvt_pk_bf16_f32 v23, v22, v23
	ds_bpermute_b32 v20, v143, v24
	ds_bpermute_b32 v21, v143, v25
	ds_bpermute_b32 v22, v143, v26
	ds_bpermute_b32 v23, v143, v23
	v_max_f32_e32 v16, v16, v16
	v_max_f32_e32 v17, v17, v17
	v_max_f32_e32 v18, v18, v18
	v_max_f32_e32 v15, v15, v15
	s_mov_b64 s[24:25], 0x140000
	v_max_f32_e32 v16, 0, v16
	v_max_f32_e32 v12, v12, v12
	v_max_f32_e32 v17, 0, v17
	v_max_f32_e32 v13, v13, v13
	v_max_f32_e32 v18, 0, v18
	v_max_f32_e32 v14, v14, v14
	v_max_f32_e32 v19, v19, v19
	v_max_f32_e32 v15, 0, v15
	v_lshl_add_u64 v[24:25], v[124:125], 0, s[24:25]
	v_max_f32_e32 v12, 0, v12
	v_mul_f32_e32 v16, v16, v16
	v_max_f32_e32 v13, 0, v13
	v_mul_f32_e32 v17, v17, v17
	v_max_f32_e32 v14, 0, v14
	v_mul_f32_e32 v18, v18, v18
	v_max_f32_e32 v19, 0, v19
	v_mul_f32_e32 v15, v15, v15
	s_waitcnt lgkmcnt(0)
	global_store_dwordx4 v[24:25], v[20:23], off offset:256
	v_mul_f32_e32 v12, v12, v12
	v_mul_f32_e32 v13, v13, v13
	v_mul_f32_e32 v14, v14, v14
	v_mul_f32_e32 v19, v19, v19
	v_cvt_pk_bf16_f32 v16, v16, v17
	v_cvt_pk_bf16_f32 v17, v18, v19
	v_cvt_pk_bf16_f32 v18, v12, v13
	v_cvt_pk_bf16_f32 v15, v14, v15
	ds_bpermute_b32 v12, v143, v16
	ds_bpermute_b32 v13, v143, v17
	ds_bpermute_b32 v14, v143, v18
	ds_bpermute_b32 v15, v143, v15
	s_mov_b32 s17, 0x160000
	v_max_f32_e32 v4, v4, v4
	v_max_f32_e32 v5, v5, v5
	v_max_f32_e32 v6, v6, v6
	v_max_f32_e32 v3, v3, v3
	v_add_co_u32_e32 v16, vcc, s17, v124
	v_max_f32_e32 v4, 0, v4
	v_max_f32_e32 v0, v0, v0
	v_max_f32_e32 v5, 0, v5
	v_max_f32_e32 v1, v1, v1
	v_max_f32_e32 v6, 0, v6
	v_max_f32_e32 v2, v2, v2
	v_max_f32_e32 v7, v7, v7
	v_max_f32_e32 v3, 0, v3
	v_addc_co_u32_e32 v17, vcc, 0, v125, vcc
	v_max_f32_e32 v0, 0, v0
	v_mul_f32_e32 v4, v4, v4
	v_max_f32_e32 v1, 0, v1
	v_mul_f32_e32 v5, v5, v5
	v_max_f32_e32 v2, 0, v2
	v_mul_f32_e32 v6, v6, v6
	v_max_f32_e32 v7, 0, v7
	v_mul_f32_e32 v3, v3, v3
	s_waitcnt lgkmcnt(0)
	global_store_dwordx4 v[16:17], v[12:15], off
	v_mul_f32_e32 v0, v0, v0
	v_mul_f32_e32 v1, v1, v1
	v_mul_f32_e32 v2, v2, v2
	v_mul_f32_e32 v7, v7, v7
	v_cvt_pk_bf16_f32 v4, v4, v5
	v_cvt_pk_bf16_f32 v5, v6, v7
	v_cvt_pk_bf16_f32 v6, v0, v1
	v_cvt_pk_bf16_f32 v3, v2, v3
	ds_bpermute_b32 v0, v143, v4
	ds_bpermute_b32 v1, v143, v5
	ds_bpermute_b32 v2, v143, v6
	ds_bpermute_b32 v3, v143, v3
	s_mov_b64 s[24:25], 0x160000
	v_lshl_add_u64 v[4:5], v[124:125], 0, s[24:25]
	s_andn2_b64 vcc, exec, s[6:7]
	s_mov_b64 s[6:7], -1
	s_waitcnt lgkmcnt(0)
	global_store_dwordx4 v[4:5], v[0:3], off offset:256
	s_cbranch_vccnz .LBB0_1186
	s_andn2_b64 vcc, exec, s[10:11]
	s_cbranch_vccnz .LBB0_1185
	s_barrier
	s_branch .LBB0_1185

; #define LAS __attribute__((address_space(3)))
; __device__ __forceinline__ f32x4 mfma16(bf16x8 a, bf16x8 b, f32x4 c) { return __builtin_amdgcn_mfma_f32_16x16x32_bf16(a, b, c, 0, 0, 0); }
; __device__ __forceinline__ void sync_threads() { __syncthreads(); }
; template <int RT, class Epi>
; __device__ __forceinline__ void skinny_gemm(const bf16* A, size_t lda, const bf16* Bt, int K, int N, const Epi& epi, int wg, int wg_first, int wg_count, int tid, LAS unsigned char* lds) {
;     ...
;     for (int s = me; s < nunit; s += wg_count) {
;         const int n0 = 32 * (s / NRG), r0 = (s % NRG) * (16 * RT);
;         f32x4 acc[RT][2];
; #pragma unroll
;         for (int rt = 0; rt < RT; ++rt) { acc[rt][0] = (f32x4){0.f, 0.f, 0.f, 0.f}; acc[rt][1] = (f32x4){0.f, 0.f, 0.f, 0.f}; }
;         const bf16* ap = A + (size_t)(r0 + c) * lda + (size_t)w * (K / 8) + 8 * g;
;         const bf16* bp = Bt + (size_t)(n0 + c) * K + (size_t)w * (K / 8) + 8 * g;
; #pragma unroll 4
;         for (int ks = 0; ks < ksteps; ++ks) {
;             bf16x8 af[RT], bfr[2];
; #pragma unroll
;             for (int rt = 0; rt < RT; ++rt) af[rt] = *(const bf16x8*)(ap + (size_t)(16 * rt) * lda + 32 * ks);
;             bfr[0] = *(const bf16x8*)(bp + 32 * ks); bfr[1] = *(const bf16x8*)(bp + (size_t)16 * K + 32 * ks);
; #pragma unroll
;             for (int rt = 0; rt < RT; ++rt) { acc[rt][0] = mfma16(af[rt], bfr[0], acc[rt][0]); acc[rt][1] = mfma16(af[rt], bfr[1], acc[rt][1]); }
;         }
;         LAS float* part = (LAS float*)(lds + w * SK_PART);
; #pragma unroll
;         for (int rt = 0; rt < RT; ++rt)
; #pragma unroll
;             for (int nt = 0; nt < 2; ++nt)
; #pragma unroll
;                 for (int r = 0; r < 4; ++r) part[(16 * rt + 4 * g + r) * 32 + 16 * nt + c] = acc[rt][nt][r];
;         sync_threads();
.LBB0_1204:
	s_and_b32 s14, s9, 64
	v_or_b32_e32 v4, s14, v18
	v_lshlrev_b32_e32 v10, 11, v4
	v_lshl_add_u64 v[6:7], v[0:1], 0, v[10:11]
	v_add_co_u32_e32 v8, vcc, 0x8000, v6
	s_mov_b32 s2, 0x10000
	s_nop 0
	v_addc_co_u32_e32 v9, vcc, 0, v7, vcc
	s_and_b32 s13, s8, 0x7fffffe0
	v_add_co_u32_e32 v12, vcc, s2, v6
	v_or_b32_e32 v10, s13, v18
	s_nop 0
	v_addc_co_u32_e32 v13, vcc, 0, v7, vcc
	s_mov_b32 s2, 0x18000
	v_lshlrev_b64 v[4:5], 11, v[10:11]
	global_load_dwordx4 v[32:35], v[6:7], off
	global_load_dwordx4 v[36:39], v[8:9], off
	global_load_dwordx4 v[40:43], v[12:13], off
	v_add_co_u32_e32 v14, vcc, s2, v6
	v_lshl_add_u64 v[4:5], v[2:3], 0, v[4:5]
	s_nop 0
	v_addc_co_u32_e32 v15, vcc, 0, v7, vcc
	s_mov_b32 s2, 0x8000
	v_add_co_u32_e32 v16, vcc, s2, v4
	global_load_dwordx4 v[44:47], v[14:15], off
	global_load_dwordx4 v[48:51], v[4:5], off
	v_addc_co_u32_e32 v17, vcc, 0, v5, vcc
	global_load_dwordx4 v[52:55], v[16:17], off
	s_waitcnt vmcnt(0) lgkmcnt(0)
	v_mfma_f32_16x16x32_bf16 v[56:59], v[32:35], v[48:51], 0
	v_mfma_f32_16x16x32_bf16 v[32:35], v[32:35], v[52:55], 0
	v_mfma_f32_16x16x32_bf16 v[60:63], v[36:39], v[48:51], 0
	v_mfma_f32_16x16x32_bf16 v[36:39], v[36:39], v[52:55], 0
	v_mfma_f32_16x16x32_bf16 v[64:67], v[40:43], v[48:51], 0
	v_mfma_f32_16x16x32_bf16 v[40:43], v[40:43], v[52:55], 0
	v_mfma_f32_16x16x32_bf16 v[48:51], v[44:47], v[48:51], 0
	v_mfma_f32_16x16x32_bf16 v[44:47], v[44:47], v[52:55], 0
	global_load_dwordx4 v[52:55], v[6:7], off offset:64
	global_load_dwordx4 v[68:71], v[8:9], off offset:64
	global_load_dwordx4 v[72:75], v[12:13], off offset:64
	global_load_dwordx4 v[76:79], v[14:15], off offset:64
	global_load_dwordx4 v[80:83], v[4:5], off offset:64
	global_load_dwordx4 v[84:87], v[16:17], off offset:64
	s_waitcnt vmcnt(0) lgkmcnt(0)
	v_mfma_f32_16x16x32_bf16 v[56:59], v[52:55], v[80:83], v[56:59]
	v_mfma_f32_16x16x32_bf16 v[32:35], v[52:55], v[84:87], v[32:35]
	v_mfma_f32_16x16x32_bf16 v[52:55], v[68:71], v[80:83], v[60:63]
	v_mfma_f32_16x16x32_bf16 v[36:39], v[68:71], v[84:87], v[36:39]
	v_mfma_f32_16x16x32_bf16 v[60:63], v[72:75], v[80:83], v[64:67]
	v_mfma_f32_16x16x32_bf16 v[40:43], v[72:75], v[84:87], v[40:43]
	v_mfma_f32_16x16x32_bf16 v[48:51], v[76:79], v[80:83], v[48:51]
	v_mfma_f32_16x16x32_bf16 v[44:47], v[76:79], v[84:87], v[44:47]
	global_load_dwordx4 v[64:67], v[6:7], off offset:128
	global_load_dwordx4 v[68:71], v[8:9], off offset:128
	global_load_dwordx4 v[72:75], v[12:13], off offset:128
	global_load_dwordx4 v[76:79], v[14:15], off offset:128
	global_load_dwordx4 v[80:83], v[4:5], off offset:128
	global_load_dwordx4 v[84:87], v[16:17], off offset:128
	s_waitcnt vmcnt(0) lgkmcnt(0)
	v_mfma_f32_16x16x32_bf16 v[56:59], v[64:67], v[80:83], v[56:59]
	v_mfma_f32_16x16x32_bf16 v[32:35], v[64:67], v[84:87], v[32:35]
	v_mfma_f32_16x16x32_bf16 v[52:55], v[68:71], v[80:83], v[52:55]
	v_mfma_f32_16x16x32_bf16 v[36:39], v[68:71], v[84:87], v[36:39]
	v_mfma_f32_16x16x32_bf16 v[60:63], v[72:75], v[80:83], v[60:63]
	v_mfma_f32_16x16x32_bf16 v[40:43], v[72:75], v[84:87], v[40:43]
	v_mfma_f32_16x16x32_bf16 v[48:51], v[76:79], v[80:83], v[48:51]
	v_mfma_f32_16x16x32_bf16 v[44:47], v[76:79], v[84:87], v[44:47]
	global_load_dwordx4 v[64:67], v[6:7], off offset:192
	s_nop 0
	global_load_dwordx4 v[6:9], v[8:9], off offset:192
	s_nop 0
	global_load_dwordx4 v[68:71], v[12:13], off offset:192
	s_nop 0
	global_load_dwordx4 v[12:15], v[14:15], off offset:192
	s_nop 0
	global_load_dwordx4 v[72:75], v[4:5], off offset:192
	global_load_dwordx4 v[76:79], v[16:17], off offset:192
	s_waitcnt vmcnt(0) lgkmcnt(0)
	v_mfma_f32_16x16x32_bf16 v[56:59], v[64:67], v[72:75], v[56:59]
	v_mfma_f32_16x16x32_bf16 v[32:35], v[64:67], v[76:79], v[32:35]
	s_nop 7
	ds_write2_b32 v30, v56, v32 offset1:16
	ds_write2_b32 v30, v57, v33 offset0:32 offset1:48
	ds_write2_b32 v30, v58, v34 offset0:64 offset1:80
	ds_write2_b32 v30, v59, v35 offset0:96 offset1:112
	v_mfma_f32_16x16x32_bf16 v[52:55], v[6:9], v[72:75], v[52:55]
	v_mfma_f32_16x16x32_bf16 v[4:7], v[6:9], v[76:79], v[36:39]
	v_add_u32_e32 v8, 0x800, v30
	s_nop 6
	ds_write2_b32 v8, v52, v4 offset1:16
	ds_write2_b32 v8, v53, v5 offset0:32 offset1:48
	ds_write2_b32 v8, v54, v6 offset0:64 offset1:80
	ds_write2_b32 v8, v55, v7 offset0:96 offset1:112
	v_mfma_f32_16x16x32_bf16 v[36:39], v[68:71], v[72:75], v[60:63]
	v_add_u32_e32 v4, 0x1000, v30
	v_mfma_f32_16x16x32_bf16 v[40:43], v[68:71], v[76:79], v[40:43]
	s_nop 7
	ds_write2_b32 v4, v36, v40 offset1:16
	ds_write2_b32 v4, v37, v41 offset0:32 offset1:48
	ds_write2_b32 v4, v38, v42 offset0:64 offset1:80
	ds_write2_b32 v4, v39, v43 offset0:96 offset1:112
	v_mfma_f32_16x16x32_bf16 v[48:51], v[12:15], v[72:75], v[48:51]
	v_add_u32_e32 v4, 0x1800, v30
	v_mfma_f32_16x16x32_bf16 v[12:15], v[12:15], v[76:79], v[44:47]
	s_nop 7
	ds_write2_b32 v4, v48, v12 offset1:16
	ds_write2_b32 v4, v49, v13 offset0:32 offset1:48
	ds_write2_b32 v4, v50, v14 offset0:64 offset1:80
	ds_write2_b32 v4, v51, v15 offset0:96 offset1:112
	s_waitcnt lgkmcnt(0)
	s_barrier
; #define LAS __attribute__((address_space(3)))
; __device__ __forceinline__ void sync_threads() { __syncthreads(); }
; template <int RT, class Epi>
; __device__ __forceinline__ void skinny_gemm(const bf16* A, size_t lda, const bf16* Bt, int K, int N, const Epi& epi, int wg, int wg_first, int wg_count, int tid, LAS unsigned char* lds) {
;     ...
;         if (RT == 8 || tid < 64 * RT) {
;             const int row = tid >> 2, c8 = (tid & 3) * 8;
;             f32x4 v0 = (f32x4){0.f, 0.f, 0.f, 0.f}, v1 = (f32x4){0.f, 0.f, 0.f, 0.f};
; #pragma unroll
;             for (int ww = 0; ww < 8; ++ww) { const LAS float* pp = (const LAS float*)(lds + ww * SK_PART) + row * 32 + c8; v0 = v0 + *(const LAS f32x4*)pp; v1 = v1 + *(const LAS f32x4*)(pp + 4); }
;             epi(r0 + row, n0 + c8, v0, v1);
;         }
;         sync_threads();
;     }
; }
	s_and_saveexec_b64 s[2:3], s[6:7]
	s_cbranch_execz .LBB0_1203
	ds_read_b128 v[4:7], v21
	ds_read_b128 v[12:15], v21 offset:16
	v_or_b32_e32 v10, s13, v20
	v_lshlrev_b32_e32 v10, 1, v10
	s_waitcnt lgkmcnt(1)
	v_pk_add_f32 v[8:9], v[6:7], 0 op_sel_hi:[1,0]
	v_pk_add_f32 v[16:17], v[4:5], 0 op_sel_hi:[1,0]
	ds_read_b128 v[4:7], v21 offset:16384
	s_waitcnt lgkmcnt(1)
	v_pk_add_f32 v[14:15], v[14:15], 0 op_sel_hi:[1,0]
	v_pk_add_f32 v[12:13], v[12:13], 0 op_sel_hi:[1,0]
	s_waitcnt lgkmcnt(0)
	v_pk_add_f32 v[8:9], v[8:9], v[6:7]
	v_pk_add_f32 v[16:17], v[16:17], v[4:5]
	ds_read_b128 v[4:7], v21 offset:16400
	s_waitcnt lgkmcnt(0)
	v_pk_add_f32 v[14:15], v[14:15], v[6:7]
	v_pk_add_f32 v[12:13], v[12:13], v[4:5]
	ds_read_b128 v[4:7], v21 offset:32768
	s_waitcnt lgkmcnt(0)
	v_pk_add_f32 v[8:9], v[8:9], v[6:7]
	v_pk_add_f32 v[16:17], v[16:17], v[4:5]
	ds_read_b128 v[4:7], v21 offset:32784
	s_waitcnt lgkmcnt(0)
	v_pk_add_f32 v[14:15], v[14:15], v[6:7]
	v_pk_add_f32 v[12:13], v[12:13], v[4:5]
	ds_read_b128 v[4:7], v21 offset:49152
	s_waitcnt lgkmcnt(0)
	v_pk_add_f32 v[8:9], v[8:9], v[6:7]
	v_pk_add_f32 v[16:17], v[16:17], v[4:5]
	ds_read_b128 v[4:7], v21 offset:49168
	s_waitcnt lgkmcnt(0)
	v_pk_add_f32 v[14:15], v[14:15], v[6:7]
	v_pk_add_f32 v[12:13], v[12:13], v[4:5]
	ds_read_b128 v[4:7], v22
	s_waitcnt lgkmcnt(0)
	v_pk_add_f32 v[8:9], v[8:9], v[6:7]
	v_pk_add_f32 v[16:17], v[16:17], v[4:5]
	ds_read_b128 v[4:7], v23
	s_waitcnt lgkmcnt(0)
	v_pk_add_f32 v[14:15], v[14:15], v[6:7]
	v_pk_add_f32 v[12:13], v[12:13], v[4:5]
	ds_read_b128 v[4:7], v24
	s_waitcnt lgkmcnt(0)
	v_pk_add_f32 v[8:9], v[8:9], v[6:7]
	v_pk_add_f32 v[16:17], v[16:17], v[4:5]
	ds_read_b128 v[4:7], v25
	s_waitcnt lgkmcnt(0)
	v_pk_add_f32 v[14:15], v[14:15], v[6:7]
	v_pk_add_f32 v[12:13], v[12:13], v[4:5]
	ds_read_b128 v[4:7], v26
	s_waitcnt lgkmcnt(0)
	v_pk_add_f32 v[8:9], v[8:9], v[6:7]
	v_pk_add_f32 v[16:17], v[16:17], v[4:5]
	ds_read_b128 v[4:7], v27
	s_waitcnt lgkmcnt(0)
	v_pk_add_f32 v[14:15], v[14:15], v[6:7]
	v_pk_add_f32 v[12:13], v[12:13], v[4:5]
	ds_read_b128 v[4:7], v28
	s_waitcnt lgkmcnt(0)
	v_pk_add_f32 v[8:9], v[8:9], v[6:7]
	v_pk_add_f32 v[16:17], v[16:17], v[4:5]
	ds_read_b128 v[4:7], v29
	s_waitcnt lgkmcnt(0)
	v_pk_add_f32 v[4:5], v[12:13], v[4:5]
	s_nop 0
	v_max_f32_e32 v4, 0, v4
	v_pk_add_f32 v[6:7], v[14:15], v[6:7]
	v_max_f32_e32 v13, 0, v16
	v_mul_f32_e32 v14, v4, v4
	v_max_f32_e32 v4, 0, v17
	v_add_u32_e32 v12, s14, v19
	v_mul_f32_e32 v13, v13, v13
	v_max_f32_e32 v5, 0, v5
	v_mul_f32_e32 v4, v4, v4
	v_max_f32_e32 v6, 0, v6
	v_max_f32_e32 v7, 0, v7
	v_mul_f32_e32 v15, v5, v5
	v_max_f32_e32 v5, 0, v8
	v_mul_f32_e32 v8, v6, v6
	v_mul_f32_e32 v7, v7, v7
	v_cvt_pk_bf16_f32 v4, v13, v4
	v_ashrrev_i32_e32 v13, 31, v12
	v_max_f32_e32 v6, 0, v9
	v_cvt_pk_bf16_f32 v7, v8, v7
	v_lshlrev_b64 v[8:9], 13, v[12:13]
	v_lshl_add_u64 v[8:9], s[10:11], 0, v[8:9]
	v_mul_f32_e32 v5, v5, v5
	v_mul_f32_e32 v6, v6, v6
	v_lshl_add_u64 v[8:9], v[8:9], 0, v[10:11]
	v_cvt_pk_bf16_f32 v5, v5, v6
	v_cvt_pk_bf16_f32 v6, v14, v15
	global_store_dwordx4 v[8:9], v[4:7], off
	s_branch .LBB0_1203

; #define LAS __attribute__((address_space(3)))
; __device__ __forceinline__ f32x4 mfma16(bf16x8 a, bf16x8 b, f32x4 c) { return __builtin_amdgcn_mfma_f32_16x16x32_bf16(a, b, c, 0, 0, 0); }
; __device__ __forceinline__ void sync_threads() { __syncthreads(); }
; template <int RT, class Epi>
; __device__ __forceinline__ void skinny_gemm(const bf16* A, size_t lda, const bf16* Bt, int K, int N, const Epi& epi, int wg, int wg_first, int wg_count, int tid, LAS unsigned char* lds) {
;     ...
; #pragma unroll 4
;         for (int ks = 0; ks < ksteps; ++ks) {
;             bf16x8 af[RT], bfr[2];
; #pragma unroll
;             for (int rt = 0; rt < RT; ++rt) af[rt] = *(const bf16x8*)(ap + (size_t)(16 * rt) * lda + 32 * ks);
;             bfr[0] = *(const bf16x8*)(bp + 32 * ks); bfr[1] = *(const bf16x8*)(bp + (size_t)16 * K + 32 * ks);
; #pragma unroll
;             for (int rt = 0; rt < RT; ++rt) { acc[rt][0] = mfma16(af[rt], bfr[0], acc[rt][0]); acc[rt][1] = mfma16(af[rt], bfr[1], acc[rt][1]); }
;         }
;         LAS float* part = (LAS float*)(lds + w * SK_PART);
; #pragma unroll
;         for (int rt = 0; rt < RT; ++rt)
; #pragma unroll
;             for (int nt = 0; nt < 2; ++nt)
; #pragma unroll
;                 for (int r = 0; r < 4; ++r) part[(16 * rt + 4 * g + r) * 32 + 16 * nt + c] = acc[rt][nt][r];
;         sync_threads();
;         if (RT == 8 || tid < 64 * RT) {
;             const int row = tid >> 2, c8 = (tid & 3) * 8;
;             f32x4 v0 = (f32x4){0.f, 0.f, 0.f, 0.f}, v1 = (f32x4){0.f, 0.f, 0.f, 0.f};
; #pragma unroll
;             for (int ww = 0; ww < 8; ++ww) { const LAS float* pp = (const LAS float*)(lds + ww * SK_PART) + row * 32 + c8; v0 = v0 + *(const LAS f32x4*)pp; v1 = v1 + *(const LAS f32x4*)(pp + 4); }
;             epi(r0 + row, n0 + c8, v0, v1);
;         }
;         sync_threads();
;     }
; }
.LBB0_1275:
	v_lshl_add_u64 v[18:19], v[14:15], 0, s[2:3]
	v_add_co_u32_e32 v18, vcc, 0x44900000, v18
	v_lshl_add_u64 v[42:43], v[16:17], 0, s[2:3]
	s_nop 0
	v_addc_co_u32_e32 v19, vcc, 0, v19, vcc
	global_load_dwordx4 v[34:37], v[18:19], off
	v_add_co_u32_e32 v46, vcc, 0x7880000, v42
	s_add_u32 s2, s2, 0x100
	s_nop 0
	v_addc_co_u32_e32 v47, vcc, 0, v43, vcc
	v_add_co_u32_e32 v48, vcc, 0x78a0000, v42
	global_load_dwordx4 v[38:41], v[46:47], off
	s_nop 0
	v_addc_co_u32_e32 v49, vcc, 0, v43, vcc
	global_load_dwordx4 v[42:45], v[48:49], off
	s_addc_u32 s3, s3, 0
	s_cmpk_eq_i32 s2, 0x400
	s_waitcnt vmcnt(0) lgkmcnt(0)
	v_mfma_f32_16x16x32_bf16 v[0:3], v[34:37], v[38:41], v[0:3]
	v_mfma_f32_16x16x32_bf16 v[4:7], v[34:37], v[42:45], v[4:7]
	global_load_dwordx4 v[34:37], v[18:19], off offset:64
	global_load_dwordx4 v[38:41], v[46:47], off offset:64
	global_load_dwordx4 v[42:45], v[48:49], off offset:64
	s_waitcnt vmcnt(0) lgkmcnt(0)
	v_mfma_f32_16x16x32_bf16 v[0:3], v[34:37], v[38:41], v[0:3]
	v_mfma_f32_16x16x32_bf16 v[4:7], v[34:37], v[42:45], v[4:7]
	global_load_dwordx4 v[34:37], v[18:19], off offset:128
	global_load_dwordx4 v[38:41], v[46:47], off offset:128
	global_load_dwordx4 v[42:45], v[48:49], off offset:128
	s_waitcnt vmcnt(0) lgkmcnt(0)
	v_mfma_f32_16x16x32_bf16 v[0:3], v[34:37], v[38:41], v[0:3]
	v_mfma_f32_16x16x32_bf16 v[4:7], v[34:37], v[42:45], v[4:7]
	global_load_dwordx4 v[34:37], v[18:19], off offset:192
	global_load_dwordx4 v[38:41], v[46:47], off offset:192
	global_load_dwordx4 v[42:45], v[48:49], off offset:192
	s_waitcnt vmcnt(0) lgkmcnt(0)
	v_mfma_f32_16x16x32_bf16 v[0:3], v[34:37], v[38:41], v[0:3]
	v_mfma_f32_16x16x32_bf16 v[4:7], v[34:37], v[42:45], v[4:7]
	s_cbranch_scc0 .LBB0_1275
	s_nop 6
	ds_write2_b32 v33, v0, v4 offset1:16
	ds_write2_b32 v33, v1, v5 offset0:32 offset1:48
	ds_write2_b32 v33, v2, v6 offset0:64 offset1:80
	ds_write2_b32 v33, v3, v7 offset0:96 offset1:112
	s_waitcnt lgkmcnt(0)
	s_barrier
	s_and_saveexec_b64 s[2:3], s[0:1]
	s_cbranch_execz .LBB0_1273
	ds_read_b128 v[0:3], v23
	ds_read_b128 v[4:7], v23 offset:16
	s_lshl_b32 s12, s10, 4
	s_lshl_b32 s11, s10, 2
	s_and_b32 s12, s12, 0x70
	s_waitcnt lgkmcnt(1)
	v_pk_add_f32 v[14:15], v[2:3], 0 op_sel_hi:[1,0]
	v_pk_add_f32 v[16:17], v[0:1], 0 op_sel_hi:[1,0]
	ds_read_b128 v[0:3], v23 offset:16384
	s_waitcnt lgkmcnt(1)
	v_pk_add_f32 v[6:7], v[6:7], 0 op_sel_hi:[1,0]
	v_pk_add_f32 v[4:5], v[4:5], 0 op_sel_hi:[1,0]
	s_and_b32 s11, s11, 0x7fffffe0
	v_or_b32_e32 v10, s11, v22
	s_waitcnt lgkmcnt(0)
	v_pk_add_f32 v[14:15], v[14:15], v[2:3]
	v_pk_add_f32 v[16:17], v[16:17], v[0:1]
	ds_read_b128 v[0:3], v23 offset:16400
	s_mov_b32 s11, 0x18000
	s_waitcnt lgkmcnt(0)
	v_pk_add_f32 v[6:7], v[6:7], v[2:3]
	v_pk_add_f32 v[4:5], v[4:5], v[0:1]
	ds_read_b128 v[0:3], v23 offset:32768
	s_waitcnt lgkmcnt(0)
	v_pk_add_f32 v[14:15], v[14:15], v[2:3]
	v_pk_add_f32 v[16:17], v[16:17], v[0:1]
	ds_read_b128 v[0:3], v23 offset:32784
	s_waitcnt lgkmcnt(0)
	v_pk_add_f32 v[6:7], v[6:7], v[2:3]
	v_pk_add_f32 v[4:5], v[4:5], v[0:1]
	ds_read_b128 v[0:3], v23 offset:49152
	s_waitcnt lgkmcnt(0)
	v_pk_add_f32 v[14:15], v[14:15], v[2:3]
	v_pk_add_f32 v[16:17], v[16:17], v[0:1]
	ds_read_b128 v[0:3], v23 offset:49168
	s_waitcnt lgkmcnt(0)
	v_pk_add_f32 v[6:7], v[6:7], v[2:3]
	v_pk_add_f32 v[4:5], v[4:5], v[0:1]
	ds_read_b128 v[0:3], v24
	s_waitcnt lgkmcnt(0)
	v_pk_add_f32 v[14:15], v[14:15], v[2:3]
	v_pk_add_f32 v[16:17], v[16:17], v[0:1]
	ds_read_b128 v[0:3], v25
	s_waitcnt lgkmcnt(0)
	v_pk_add_f32 v[6:7], v[6:7], v[2:3]
	v_pk_add_f32 v[4:5], v[4:5], v[0:1]
	ds_read_b128 v[0:3], v26
	s_waitcnt lgkmcnt(0)
	v_pk_add_f32 v[14:15], v[14:15], v[2:3]
	v_pk_add_f32 v[16:17], v[16:17], v[0:1]
	ds_read_b128 v[0:3], v27
	s_waitcnt lgkmcnt(0)
	v_pk_add_f32 v[6:7], v[6:7], v[2:3]
	v_pk_add_f32 v[4:5], v[4:5], v[0:1]
	ds_read_b128 v[0:3], v28
	s_waitcnt lgkmcnt(0)
	v_pk_add_f32 v[14:15], v[14:15], v[2:3]
	v_pk_add_f32 v[16:17], v[16:17], v[0:1]
	ds_read_b128 v[0:3], v29
	s_waitcnt lgkmcnt(0)
	v_pk_add_f32 v[6:7], v[6:7], v[2:3]
	v_pk_add_f32 v[4:5], v[4:5], v[0:1]
	ds_read_b128 v[0:3], v30
	s_waitcnt lgkmcnt(0)
	v_pk_add_f32 v[14:15], v[14:15], v[2:3]
	v_pk_add_f32 v[16:17], v[16:17], v[0:1]
	ds_read_b128 v[0:3], v31
	s_waitcnt lgkmcnt(0)
	v_pk_add_f32 v[0:1], v[4:5], v[0:1]
	v_add_u32_e32 v4, s12, v21
	v_pk_add_f32 v[2:3], v[6:7], v[2:3]
	v_ashrrev_i32_e32 v5, 31, v4
	v_mov_b64_e32 v[6:7], s[6:7]
	v_mad_i64_i32 v[6:7], s[12:13], v4, s11, v[6:7]
	v_lshlrev_b64 v[4:5], 11, v[4:5]
	v_lshl_add_u64 v[38:39], v[10:11], 2, v[6:7]
	v_lshl_add_u64 v[4:5], s[4:5], 0, v[4:5]
	v_lshlrev_b32_e32 v10, 1, v10
	v_lshl_add_u64 v[4:5], v[4:5], 0, v[10:11]
	global_load_dwordx4 v[34:37], v[4:5], off
	s_waitcnt vmcnt(0) lgkmcnt(0)
	v_lshlrev_b32_e32 v40, 16, v34
	v_and_b32_e32 v41, 0xffff0000, v34
	v_lshlrev_b32_e32 v42, 16, v35
	v_and_b32_e32 v43, 0xffff0000, v35
	v_lshlrev_b32_e32 v6, 16, v36
	v_and_b32_e32 v7, 0xffff0000, v36
	v_lshlrev_b32_e32 v18, 16, v37
	v_and_b32_e32 v19, 0xffff0000, v37
	global_load_dwordx4 v[34:37], v[38:39], off
	s_waitcnt vmcnt(0) lgkmcnt(0)
	v_pk_fma_f32 v[14:15], v[14:15], v[36:37], v[42:43]
	v_pk_fma_f32 v[16:17], v[16:17], v[34:35], v[40:41]
	global_load_dwordx4 v[34:37], v[38:39], off offset:16
	s_waitcnt vmcnt(0) lgkmcnt(0)
	v_pk_fma_f32 v[18:19], v[2:3], v[36:37], v[18:19]
	v_pk_fma_f32 v[2:3], v[0:1], v[34:35], v[6:7]
	v_cvt_pk_bf16_f32 v0, v16, v17
	v_cvt_pk_bf16_f32 v1, v14, v15
	s_nop 0
	v_cvt_pk_bf16_f32 v2, v2, v3
	v_cvt_pk_bf16_f32 v3, v18, v19
	global_store_dwordx4 v[4:5], v[0:3], off
	s_branch .LBB0_1273

; __device__ __forceinline__ unsigned xb_ld(unsigned* p)              { return __hip_atomic_load(p, __ATOMIC_RELAXED, __HIP_MEMORY_SCOPE_AGENT); }
; __device__ __forceinline__ unsigned xb_add(unsigned* p, unsigned v) { return __hip_atomic_fetch_add(p, v, __ATOMIC_RELAXED, __HIP_MEMORY_SCOPE_AGENT); }
; #define XB_SPIN(cond, bar) do { unsigned _sp = 0; while (cond) { __builtin_amdgcn_s_sleep(1); \
;     if ((++_sp & 255u) == 0u) { if (xb_ld(&(bar)[XB_TMO])) break; if (_sp > XB_SPIN_CAP) { atomicAdd(&(bar)[XB_TMO], 1u); break; } } } } while (0)
; __device__ __forceinline__ void xcd_barrier(const XcdBarrier& b, int tid) {
;     ...
;     if (tid == 0) {
;         unsigned* bar = b.bar; unsigned bx_ = b.x; asm volatile("" : "+s"(bar), "+s"(bx_));
;         __builtin_amdgcn_s_waitcnt(0);
;         unsigned nloc = b.st[0], nx = b.st[1];
;         if (nloc == 0u) { xcd_barrier_complete(bar, bx_, nloc, nx); b.st[0] = nloc; b.st[1] = nx; }
;         const unsigned old = xb_add(&bar[XB_XSUB(bx_)], 1u);
;         const unsigned gen = old / nloc;
;         if (old + 1u == (gen + 1u) * nloc) {
;             __builtin_amdgcn_fence(__ATOMIC_RELEASE, "agent");
;             asm volatile("s_waitcnt vmcnt(0)" ::: "memory");
;             const unsigned og = xb_add(&bar[XB_TOP], 1u);
;             const unsigned tg = og / nx;
;             if (og + 1u == (tg + 1u) * nx) xb_add(&bar[XB_TOPGEN], 1u);
;             else XB_SPIN(xb_ld(&bar[XB_TOPGEN]) == tg, bar);
;             __builtin_amdgcn_fence(__ATOMIC_ACQUIRE, "agent");
;             xb_add(&bar[XB_XGEN(bx_)], 1u);
;             asm volatile("s_waitcnt vmcnt(0)" ::: "memory");
;         } else {
;             XB_SPIN(xb_ld(&bar[XB_XGEN(bx_)]) == gen, bar);
.LBB0_1293:
	s_lshl_b32 s22, s36, 6
	s_add_i32 s64, s22, 0x500
	s_lshl_b64 s[0:1], s[64:65], 2
	s_add_u32 s0, s34, s0
	s_addc_u32 s1, s35, s1
	v_mov_b64_e32 v[4:5], s[0:1]
	v_mov_b32_e32 v1, 1
	flat_atomic_add v3, v[4:5], v1 sc0
	v_cvt_f32_u32_e32 v1, v2
	v_sub_u32_e32 v4, 0, v2
	v_rcp_iflag_f32_e32 v1, v1
	s_nop 0
	v_mul_f32_e32 v1, 0x4f7ffffe, v1
	v_cvt_u32_f32_e32 v1, v1
	v_mul_lo_u32 v4, v4, v1
	v_mul_hi_u32 v4, v1, v4
	v_add_u32_e32 v1, v1, v4
	s_waitcnt vmcnt(0) lgkmcnt(0)
	v_mul_hi_u32 v1, v3, v1
	v_mul_lo_u32 v4, v1, v2
	v_sub_u32_e32 v4, v3, v4
	v_cmp_ge_u32_e32 vcc, v4, v2
	v_add_u32_e32 v5, 1, v1
	s_nop 0
	v_cndmask_b32_e32 v1, v1, v5, vcc
	v_sub_u32_e32 v5, v4, v2
	v_cndmask_b32_e32 v4, v4, v5, vcc
	v_cmp_ge_u32_e32 vcc, v4, v2
	v_add_u32_e32 v4, 1, v1
	s_nop 0
	v_cndmask_b32_e32 v1, v1, v4, vcc
	v_add_u32_e32 v4, 1, v3
	v_mad_u64_u32 v[2:3], s[0:1], v2, v1, v[2:3]
	v_cmp_ne_u32_e32 vcc, v4, v2
	s_and_saveexec_b64 s[0:1], vcc
	s_xor_b64 s[0:1], exec, s[0:1]
	s_cbranch_execz .LBB0_1306
	s_add_i32 s64, s22, 0x900
	s_lshl_b64 s[4:5], s[64:65], 2
	s_add_u32 s6, s34, s4
	s_addc_u32 s7, s35, s5
	v_mov_b64_e32 v[2:3], s[6:7]
	global_load_dword v0, v[2:3], off sc1
	s_waitcnt vmcnt(0) lgkmcnt(0)
	v_cmp_eq_u32_e32 vcc, v0, v1
	s_and_saveexec_b64 s[4:5], vcc
	s_cbranch_execz .LBB0_1305
	s_mov_b32 s23, 1
	s_mov_b64 s[8:9], 0
	s_branch .LBB0_1297

; __device__ __forceinline__ unsigned xb_ld(unsigned* p)              { return __hip_atomic_load(p, __ATOMIC_RELAXED, __HIP_MEMORY_SCOPE_AGENT); }
; __device__ __forceinline__ unsigned xb_add(unsigned* p, unsigned v) { return __hip_atomic_fetch_add(p, v, __ATOMIC_RELAXED, __HIP_MEMORY_SCOPE_AGENT); }
; #define XB_SPIN(cond, bar) do { unsigned _sp = 0; while (cond) { __builtin_amdgcn_s_sleep(1); \
;     if ((++_sp & 255u) == 0u) { if (xb_ld(&(bar)[XB_TMO])) break; if (_sp > XB_SPIN_CAP) { atomicAdd(&(bar)[XB_TMO], 1u); break; } } } } while (0)
; __device__ __forceinline__ void xcd_barrier(const XcdBarrier& b, int tid) {
;     ...
;             __builtin_amdgcn_fence(__ATOMIC_RELEASE, "agent");
;             asm volatile("s_waitcnt vmcnt(0)" ::: "memory");
;             const unsigned og = xb_add(&bar[XB_TOP], 1u);
;             const unsigned tg = og / nx;
;             if (og + 1u == (tg + 1u) * nx) xb_add(&bar[XB_TOPGEN], 1u);
;             else XB_SPIN(xb_ld(&bar[XB_TOPGEN]) == tg, bar);
.LBB0_1307:
	v_mov_b32_e32 v1, s34
	v_add_co_u32_e32 v2, vcc, 0x3000, v1
	v_mov_b32_e32 v1, s35
	buffer_wbl2 sc1
	s_waitcnt vmcnt(0)
	v_addc_co_u32_e32 v3, vcc, 0, v1, vcc
	v_mov_b32_e32 v1, 1
	flat_atomic_add v1, v[2:3], v1 offset:1024 sc0
	v_cvt_f32_u32_e32 v2, v0
	v_sub_u32_e32 v3, 0, v0
	s_mov_b64 s[6:7], -1
	v_rcp_iflag_f32_e32 v2, v2
	s_nop 0
	v_mul_f32_e32 v2, 0x4f7ffffe, v2
	v_cvt_u32_f32_e32 v2, v2
	v_mul_lo_u32 v3, v3, v2
	v_mul_hi_u32 v3, v2, v3
	v_add_u32_e32 v2, v2, v3
	s_waitcnt vmcnt(0) lgkmcnt(0)
	v_mul_hi_u32 v2, v1, v2
	v_mul_lo_u32 v3, v2, v0
	v_sub_u32_e32 v3, v1, v3
	v_cmp_ge_u32_e32 vcc, v3, v0
	v_add_u32_e32 v4, 1, v2
	s_nop 0
	v_cndmask_b32_e32 v2, v2, v4, vcc
	v_sub_u32_e32 v4, v3, v0
	v_cndmask_b32_e32 v3, v3, v4, vcc
	v_cmp_ge_u32_e32 vcc, v3, v0
	v_add_u32_e32 v3, 1, v2
	s_nop 0
	v_cndmask_b32_e32 v2, v2, v3, vcc
	v_add_u32_e32 v3, 1, v1
	v_mad_u64_u32 v[0:1], s[0:1], v0, v2, v[0:1]
	s_add_u32 s0, s34, 0x3500
	s_addc_u32 s1, s35, 0
	v_cmp_ne_u32_e32 vcc, v3, v0
	v_mov_b64_e32 v[0:1], s[0:1]
	s_and_saveexec_b64 s[4:5], vcc
	s_cbranch_execz .LBB0_1319
	v_mov_b64_e32 v[0:1], s[0:1]
	global_load_dword v0, v[0:1], off sc1
	s_mov_b64 s[10:11], 0
	s_waitcnt vmcnt(0) lgkmcnt(0)
	v_cmp_eq_u32_e32 vcc, v0, v2
	s_and_saveexec_b64 s[8:9], vcc
	s_cbranch_execz .LBB0_1318
	s_add_u32 s6, s34, 0x200
	s_addc_u32 s7, s35, 0
	s_mov_b32 s23, 1
	s_branch .LBB0_1311

; __device__ __forceinline__ unsigned xb_ld(unsigned* p)              { return __hip_atomic_load(p, __ATOMIC_RELAXED, __HIP_MEMORY_SCOPE_AGENT); }
; #define XB_SPIN(cond, bar) do { unsigned _sp = 0; while (cond) { __builtin_amdgcn_s_sleep(1); \
;     if ((++_sp & 255u) == 0u) { if (xb_ld(&(bar)[XB_TMO])) break; if (_sp > XB_SPIN_CAP) { atomicAdd(&(bar)[XB_TMO], 1u); break; } } } } while (0)
; __device__ __forceinline__ void xcd_barrier(const XcdBarrier& b, int tid) {
;     ...
;             else XB_SPIN(xb_ld(&bar[XB_TOPGEN]) == tg, bar);
.LBB0_1313:
	v_mov_b64_e32 v[0:1], s[6:7]
	global_load_dword v0, v[0:1], off sc1
	s_mov_b64 s[18:19], 0
	s_mov_b64 s[16:17], -1
	s_waitcnt vmcnt(0) lgkmcnt(0)
	v_cmp_eq_u32_e32 vcc, 0, v0
	s_and_saveexec_b64 s[20:21], vcc
	s_cmp_lt_u32 s23, 0x40001
	s_cselect_b64 s[18:19], -1, 0
	s_xor_b64 s[16:17], exec, -1
	s_and_b64 s[18:19], s[18:19], exec
	s_or_b64 exec, exec, s[20:21]
	s_and_saveexec_b64 s[20:21], s[18:19]
	s_cbranch_execz .LBB0_1310
.LBB0_1316:
	v_mov_b64_e32 v[0:1], s[0:1]
	global_load_dword v0, v[0:1], off sc1
	s_add_i32 s23, s23, 1
	s_or_b64 s[16:17], s[16:17], exec
	s_waitcnt vmcnt(0) lgkmcnt(0)
	v_cmp_ne_u32_e32 vcc, v0, v2
	s_orn2_b64 s[14:15], vcc, exec
	s_branch .LBB0_1310

; __device__ __forceinline__ f32x4 unpack4(unsigned long long w) { const unsigned lo = (unsigned)w, hi = (unsigned)(w >> 32); return (f32x4){__uint_as_float(lo << 16), __uint_as_float(lo & 0xffff0000u), __uint_as_float(hi << 16), __uint_as_float(hi & 0xffff0000u)}; }
; template <int MODE, int NR>
; __device__ __forceinline__ void norm_rows(const float* X32, bf16* X, bf16* H, float* out32, const f32x4 (&mul)[4], const f32x4 (&sh)[4], int lane) {
;     ...
;         unsigned long long raw[NR][4];
; #pragma unroll
;         for (int r = 0; r < NR; ++r) { const unsigned long long* xr = (const unsigned long long*)(X + (size_t)r * D) + lane;
; #pragma unroll
;             for (int j = 0; j < 4; ++j) raw[r][j] = xr[64 * j]; }
; #pragma unroll
;         for (int r = 0; r < NR; ++r) { f32x4 v[4]; float s = 0.f;
; #pragma unroll
;             for (int j = 0; j < 4; ++j) { v[j] = unpack4(raw[r][j]); s += (v[j].x * v[j].x + v[j].y * v[j].y) + (v[j].z * v[j].z + v[j].w * v[j].w); }
;             const float rstd = rsqrtf(wave_sum(s) * (1.f / D) + EPS);
;             if constexpr (MODE == 2) { f32x4* o = (f32x4*)(out32 + (size_t)r * D) + lane;
; #pragma unroll
;                 for (int j = 0; j < 4; ++j) o[64 * j] = v[j] * rstd * mul[j];
; __device__ __forceinline__ void phase_final(const bf16* X, float* out, const float* nw, int gw, int NGW, int lane) {
;     ...
;     for (int b = gw; b < MP / 8; b += NGW) { const size_t ro = (size_t)b * 8 * D; norm_rows<2, 8>(nullptr, (bf16*)X + ro, nullptr, out + ro, w4, w4, lane); }
.LBB0_1323:
	v_add_co_u32_e32 v34, vcc, 0xffffc200, v22
	v_add_co_u32_e64 v28, s[0:1], s5, v20
	s_nop 0
	v_addc_co_u32_e32 v35, vcc, -1, v23, vcc
	v_add_co_u32_e32 v42, vcc, 0xffffc400, v22
	v_addc_co_u32_e64 v29, s[0:1], 0, v21, s[0:1]
	s_nop 0
	v_addc_co_u32_e32 v43, vcc, -1, v23, vcc
	v_add_co_u32_e32 v44, vcc, 0xffffc600, v22
	global_load_dwordx2 v[46:47], v[34:35], off
	global_load_dwordx2 v[48:49], v[42:43], off
	v_addc_co_u32_e32 v45, vcc, -1, v23, vcc
	v_add_co_u32_e32 v34, vcc, 0xffffc800, v22
	v_add_co_u32_e64 v26, s[0:1], s6, v20
	s_nop 0
	v_addc_co_u32_e32 v35, vcc, -1, v23, vcc
	v_add_co_u32_e32 v42, vcc, 0xffffca00, v22
	global_load_dwordx2 v[50:51], v[44:45], off
	global_load_dwordx2 v[56:57], v[34:35], off
	v_addc_co_u32_e32 v43, vcc, -1, v23, vcc
	v_add_co_u32_e32 v34, vcc, 0xffffcc00, v22
	v_addc_co_u32_e64 v27, s[0:1], 0, v21, s[0:1]
	s_nop 0
	v_addc_co_u32_e32 v35, vcc, -1, v23, vcc
	v_add_co_u32_e32 v44, vcc, 0xffffce00, v22
	global_load_dwordx2 v[58:59], v[42:43], off
	global_load_dwordx2 v[64:65], v[34:35], off
	v_addc_co_u32_e32 v45, vcc, -1, v23, vcc
	v_add_co_u32_e32 v34, vcc, 0xffffd000, v22
	v_add_co_u32_e64 v32, s[0:1], s7, v20
	s_nop 0
	v_addc_co_u32_e32 v35, vcc, -1, v23, vcc
	v_add_co_u32_e32 v42, vcc, 0xffffd200, v22
	global_load_dwordx2 v[66:67], v[44:45], off
	global_load_dwordx2 v[72:73], v[34:35], off
	v_addc_co_u32_e32 v43, vcc, -1, v23, vcc
	v_add_co_u32_e32 v34, vcc, 0xffffd400, v22
	v_addc_co_u32_e64 v33, s[0:1], 0, v21, s[0:1]
	s_nop 0
	v_addc_co_u32_e32 v35, vcc, -1, v23, vcc
	v_add_co_u32_e32 v44, vcc, 0xffffd600, v22
	global_load_dwordx2 v[74:75], v[42:43], off
	global_load_dwordx2 v[76:77], v[34:35], off
	v_addc_co_u32_e32 v45, vcc, -1, v23, vcc
	v_add_co_u32_e32 v34, vcc, 0xffffd800, v22
	v_add_co_u32_e64 v30, s[0:1], s8, v20
	s_nop 0
	v_addc_co_u32_e32 v35, vcc, -1, v23, vcc
	v_add_co_u32_e32 v42, vcc, 0xffffda00, v22
	global_load_dwordx2 v[78:79], v[44:45], off
	global_load_dwordx2 v[84:85], v[34:35], off
	v_addc_co_u32_e32 v43, vcc, -1, v23, vcc
	v_add_co_u32_e32 v34, vcc, 0xffffdc00, v22
	v_addc_co_u32_e64 v31, s[0:1], 0, v21, s[0:1]
	s_nop 0
	v_addc_co_u32_e32 v35, vcc, -1, v23, vcc
	v_add_co_u32_e32 v44, vcc, 0xffffde00, v22
	global_load_dwordx2 v[88:89], v[42:43], off
	global_load_dwordx2 v[96:97], v[34:35], off
	v_addc_co_u32_e32 v45, vcc, -1, v23, vcc
	v_add_co_u32_e32 v34, vcc, 0xffffe000, v22
	v_add_co_u32_e64 v38, s[0:1], s9, v20
	s_nop 0
	v_addc_co_u32_e32 v35, vcc, -1, v23, vcc
	v_add_co_u32_e32 v42, vcc, 0xffffe200, v22
	global_load_dwordx2 v[100:101], v[44:45], off
	global_load_dwordx2 v[108:109], v[34:35], off
	v_addc_co_u32_e32 v43, vcc, -1, v23, vcc
	v_add_co_u32_e32 v34, vcc, 0xffffe400, v22
	v_addc_co_u32_e64 v39, s[0:1], 0, v21, s[0:1]
	s_nop 0
	v_addc_co_u32_e32 v35, vcc, -1, v23, vcc
	v_add_co_u32_e32 v44, vcc, 0xffffe600, v22
	global_load_dwordx2 v[120:121], v[42:43], off
	global_load_dwordx2 v[128:129], v[34:35], off
	v_addc_co_u32_e32 v45, vcc, -1, v23, vcc
	v_add_co_u32_e32 v34, vcc, 0xffffe800, v22
	s_waitcnt vmcnt(0) lgkmcnt(0)
	v_and_b32_e32 v53, 0xffff0000, v50
	v_addc_co_u32_e32 v35, vcc, -1, v23, vcc
	v_add_co_u32_e32 v42, vcc, 0xffffea00, v22
	global_load_dwordx2 v[132:133], v[44:45], off
	global_load_dwordx2 v[112:113], v[34:35], off
	v_addc_co_u32_e32 v43, vcc, -1, v23, vcc
	v_add_co_u32_e32 v34, vcc, 0xffffec00, v22
	v_and_b32_e32 v55, 0xffff0000, v51
	s_nop 0
	v_addc_co_u32_e32 v35, vcc, -1, v23, vcc
	v_add_co_u32_e32 v44, vcc, 0xffffee00, v22
	global_load_dwordx2 v[126:127], v[42:43], off
	global_load_dwordx2 v[130:131], v[34:35], off
	v_addc_co_u32_e32 v45, vcc, -1, v23, vcc
	v_add_co_u32_e32 v34, vcc, 0xfffff000, v22
	v_lshlrev_b32_e32 v52, 16, v50
	s_nop 0
	v_addc_co_u32_e32 v35, vcc, -1, v23, vcc
	v_add_co_u32_e32 v42, vcc, 0xfffff200, v22
	global_load_dwordx2 v[138:139], v[44:45], off
	global_load_dwordx2 v[118:119], v[34:35], off
	v_addc_co_u32_e32 v43, vcc, -1, v23, vcc
	v_add_co_u32_e32 v34, vcc, 0xfffff400, v22
	v_lshlrev_b32_e32 v54, 16, v51
	s_nop 0
	v_addc_co_u32_e32 v35, vcc, -1, v23, vcc
	v_add_co_u32_e32 v44, vcc, 0xfffff600, v22
	global_load_dwordx2 v[124:125], v[42:43], off
	global_load_dwordx2 v[134:135], v[34:35], off
	v_addc_co_u32_e32 v45, vcc, -1, v23, vcc
	v_add_co_u32_e32 v34, vcc, 0xfffff800, v22
	v_mul_f32_e32 v50, v55, v55
	s_nop 0
	v_addc_co_u32_e32 v35, vcc, -1, v23, vcc
	v_add_co_u32_e32 v42, vcc, 0xfffffa00, v22
	global_load_dwordx2 v[144:145], v[44:45], off
	global_load_dwordx2 v[154:155], v[34:35], off
	v_addc_co_u32_e32 v43, vcc, -1, v23, vcc
	v_add_co_u32_e32 v34, vcc, 0xfffffc00, v22
	global_load_dwordx2 v[160:161], v[42:43], off
	s_nop 0
	v_addc_co_u32_e32 v35, vcc, -1, v23, vcc
	v_add_co_u32_e32 v42, vcc, 0xfffffe00, v22
	v_and_b32_e32 v45, 0xffff0000, v48
	s_nop 0
	v_addc_co_u32_e32 v43, vcc, -1, v23, vcc
	global_load_dwordx2 v[156:157], v[34:35], off
	global_load_dwordx2 v[146:147], v[42:43], off
	global_load_dwordx2 v[140:141], v[22:23], off
	v_and_b32_e32 v35, 0xffff0000, v46
	v_and_b32_e32 v43, 0xffff0000, v47
	v_lshlrev_b32_e32 v34, 16, v46
	v_lshlrev_b32_e32 v42, 16, v47
	v_mul_f32_e32 v17, v35, v35
	v_mul_f32_e32 v19, v43, v43
	v_and_b32_e32 v47, 0xffff0000, v49
	v_lshlrev_b32_e32 v44, 16, v48
	v_lshlrev_b32_e32 v46, 16, v49
	v_fmac_f32_e32 v17, v34, v34
	v_fmac_f32_e32 v19, v42, v42
	v_mul_f32_e32 v48, v45, v45
	v_mul_f32_e32 v49, v47, v47
	v_add_f32_e32 v17, v17, v19
	v_fmac_f32_e32 v48, v44, v44
	v_fmac_f32_e32 v49, v46, v46
	v_mul_f32_e32 v19, v53, v53
	v_and_b32_e32 v61, 0xffff0000, v56
	v_and_b32_e32 v63, 0xffff0000, v57
	v_lshlrev_b32_e32 v60, 16, v56
	v_lshlrev_b32_e32 v62, 16, v57
; __device__ __forceinline__ f32x4 unpack4(unsigned long long w) { const unsigned lo = (unsigned)w, hi = (unsigned)(w >> 32); return (f32x4){__uint_as_float(lo << 16), __uint_as_float(lo & 0xffff0000u), __uint_as_float(hi << 16), __uint_as_float(hi & 0xffff0000u)}; }
; template <int MODE, int NR>
; __device__ __forceinline__ void norm_rows(const float* X32, bf16* X, bf16* H, float* out32, const f32x4 (&mul)[4], const f32x4 (&sh)[4], int lane) {
;     ...
;         for (int r = 0; r < NR; ++r) { f32x4 v[4]; float s = 0.f;
; #pragma unroll
;             for (int j = 0; j < 4; ++j) { v[j] = unpack4(raw[r][j]); s += (v[j].x * v[j].x + v[j].y * v[j].y) + (v[j].z * v[j].z + v[j].w * v[j].w); }
;             const float rstd = rsqrtf(wave_sum(s) * (1.f / D) + EPS);
	v_add_f32_e32 v48, v48, v49
	v_fmac_f32_e32 v19, v52, v52
	v_fmac_f32_e32 v50, v54, v54
	v_mul_f32_e32 v49, v61, v61
	v_mul_f32_e32 v51, v63, v63
	v_and_b32_e32 v69, 0xffff0000, v58
	v_and_b32_e32 v71, 0xffff0000, v59
	v_add_f32_e32 v17, v17, v48
	v_add_f32_e32 v19, v19, v50
	v_fmac_f32_e32 v49, v60, v60
	v_fmac_f32_e32 v51, v62, v62
	v_and_b32_e32 v81, 0xffff0000, v64
	v_and_b32_e32 v83, 0xffff0000, v65
	v_lshlrev_b32_e32 v68, 16, v58
	v_lshlrev_b32_e32 v70, 16, v59
	v_mul_f32_e32 v48, v69, v69
	v_mul_f32_e32 v50, v71, v71
	v_lshlrev_b32_e32 v80, 16, v64
	v_lshlrev_b32_e32 v82, 16, v65
	v_add_f32_e32 v17, v17, v19
	v_add_f32_e32 v19, v49, v51
	v_mul_f32_e32 v49, v81, v81
	v_mul_f32_e32 v51, v83, v83
	v_and_b32_e32 v93, 0xffff0000, v66
	v_and_b32_e32 v95, 0xffff0000, v67
	v_fmac_f32_e32 v48, v68, v68
	v_fmac_f32_e32 v50, v70, v70
	v_lshlrev_b32_e32 v92, 16, v66
	v_lshlrev_b32_e32 v94, 16, v67
	v_add_f32_e32 v17, v17, v19
	v_fmac_f32_e32 v49, v80, v80
	v_fmac_f32_e32 v51, v82, v82
	v_mul_f32_e32 v56, v93, v93
	v_mul_f32_e32 v57, v95, v95
	v_and_b32_e32 v105, 0xffff0000, v72
	v_and_b32_e32 v107, 0xffff0000, v73
	v_add_f32_e32 v19, v48, v50
	v_lshlrev_b32_e32 v104, 16, v72
	v_lshlrev_b32_e32 v106, 16, v73
	ds_swizzle_b32 v72, v17 offset:swizzle(SWAP,1)
	v_add_f32_e32 v58, v49, v51
	v_fmac_f32_e32 v56, v92, v92
	v_fmac_f32_e32 v57, v94, v94
	v_mul_f32_e32 v64, v105, v105
	v_mul_f32_e32 v65, v107, v107
	v_and_b32_e32 v49, 0xffff0000, v74
	v_and_b32_e32 v51, 0xffff0000, v75
	v_lshlrev_b32_e32 v48, 16, v74
	v_lshlrev_b32_e32 v50, 16, v75
	v_add_f32_e32 v19, v19, v58
	v_add_f32_e32 v66, v56, v57
	v_fmac_f32_e32 v64, v104, v104
	v_fmac_f32_e32 v65, v106, v106
	v_mul_f32_e32 v73, v49, v49
	v_mul_f32_e32 v74, v51, v51
	v_and_b32_e32 v57, 0xffff0000, v76
	v_and_b32_e32 v59, 0xffff0000, v77
	v_lshlrev_b32_e32 v56, 16, v76
	v_lshlrev_b32_e32 v58, 16, v77
	v_add_f32_e32 v19, v19, v66
	v_add_f32_e32 v75, v64, v65
	v_fmac_f32_e32 v73, v48, v48
	v_fmac_f32_e32 v74, v50, v50
	v_mul_f32_e32 v86, v57, v57
	v_mul_f32_e32 v87, v59, v59
	v_and_b32_e32 v65, 0xffff0000, v78
	v_and_b32_e32 v67, 0xffff0000, v79
	v_lshlrev_b32_e32 v64, 16, v78
	v_lshlrev_b32_e32 v66, 16, v79
	v_add_f32_e32 v19, v19, v75
	v_add_f32_e32 v73, v73, v74
	v_fmac_f32_e32 v86, v56, v56
	v_fmac_f32_e32 v87, v58, v58
	v_mul_f32_e32 v74, v65, v65
	v_mul_f32_e32 v75, v67, v67
	v_and_b32_e32 v77, 0xffff0000, v84
	v_and_b32_e32 v79, 0xffff0000, v85
	v_lshlrev_b32_e32 v76, 16, v84
	v_lshlrev_b32_e32 v78, 16, v85
	ds_swizzle_b32 v84, v19 offset:swizzle(SWAP,1)
	v_add_f32_e32 v85, v86, v87
	v_fmac_f32_e32 v74, v64, v64
	v_fmac_f32_e32 v75, v66, v66
	v_mul_f32_e32 v110, v77, v77
	v_mul_f32_e32 v111, v79, v79
	v_and_b32_e32 v87, 0xffff0000, v88
	v_and_b32_e32 v91, 0xffff0000, v89
	s_waitcnt lgkmcnt(0)
	v_add_f32_e32 v17, v17, v72
	v_add_f32_e32 v72, v73, v85
	v_add_f32_e32 v73, v74, v75
	v_fmac_f32_e32 v110, v76, v76
	v_fmac_f32_e32 v111, v78, v78
	v_and_b32_e32 v99, 0xffff0000, v96
	v_and_b32_e32 v103, 0xffff0000, v97
	v_lshlrev_b32_e32 v86, 16, v88
	v_lshlrev_b32_e32 v90, 16, v89
	v_mul_f32_e32 v74, v87, v87
	v_mul_f32_e32 v75, v91, v91
	v_lshlrev_b32_e32 v98, 16, v96
	v_lshlrev_b32_e32 v102, 16, v97
	ds_swizzle_b32 v136, v17 offset:swizzle(SWAP,2)
	v_add_f32_e32 v72, v72, v73
	v_add_f32_e32 v73, v110, v111
	v_mul_f32_e32 v85, v99, v99
	v_mul_f32_e32 v88, v103, v103
	v_and_b32_e32 v111, 0xffff0000, v100
	v_and_b32_e32 v115, 0xffff0000, v101
	v_fmac_f32_e32 v74, v86, v86
	v_fmac_f32_e32 v75, v90, v90
	v_lshlrev_b32_e32 v110, 16, v100
	v_lshlrev_b32_e32 v114, 16, v101
	v_add_f32_e32 v137, v72, v73
	v_fmac_f32_e32 v85, v98, v98
	v_fmac_f32_e32 v88, v102, v102
	v_mul_f32_e32 v96, v111, v111
	v_mul_f32_e32 v97, v115, v115
	v_and_b32_e32 v117, 0xffff0000, v108
	v_and_b32_e32 v123, 0xffff0000, v109
	v_add_f32_e32 v89, v74, v75
	v_lshlrev_b32_e32 v116, 16, v108
	v_lshlrev_b32_e32 v122, 16, v109
	ds_swizzle_b32 v142, v137 offset:swizzle(SWAP,1)
	v_add_f32_e32 v85, v85, v88
	v_fmac_f32_e32 v96, v110, v110
	v_fmac_f32_e32 v97, v114, v114
	v_mul_f32_e32 v100, v117, v117
	v_mul_f32_e32 v101, v123, v123
	v_and_b32_e32 v73, 0xffff0000, v120
	v_and_b32_e32 v75, 0xffff0000, v121
	v_lshlrev_b32_e32 v72, 16, v120
	v_lshlrev_b32_e32 v74, 16, v121
	v_add_f32_e32 v19, v19, v84
	v_add_f32_e32 v108, v89, v85
	v_add_f32_e32 v96, v96, v97
	v_fmac_f32_e32 v100, v116, v116
	v_fmac_f32_e32 v101, v122, v122
	v_mul_f32_e32 v109, v73, v73
	v_mul_f32_e32 v120, v75, v75
	v_and_b32_e32 v85, 0xffff0000, v128
	v_and_b32_e32 v89, 0xffff0000, v129
	v_lshlrev_b32_e32 v84, 16, v128
	v_lshlrev_b32_e32 v88, 16, v129
	ds_swizzle_b32 v143, v19 offset:swizzle(SWAP,2)
	v_add_f32_e32 v108, v108, v96
	v_add_f32_e32 v121, v100, v101
	v_fmac_f32_e32 v109, v72, v72
	v_fmac_f32_e32 v120, v74, v74
	v_mul_f32_e32 v128, v85, v85
	v_mul_f32_e32 v129, v89, v89
	s_waitcnt vmcnt(0)
	v_and_b32_e32 v97, 0xffff0000, v132
	v_and_b32_e32 v101, 0xffff0000, v133
	v_lshlrev_b32_e32 v96, 16, v132
	v_lshlrev_b32_e32 v100, 16, v133
	s_waitcnt lgkmcnt(2)
	v_add_f32_e32 v17, v17, v136
	v_add_f32_e32 v152, v108, v121
	v_add_f32_e32 v132, v109, v120
	v_fmac_f32_e32 v128, v84, v84
	v_fmac_f32_e32 v129, v88, v88
	v_mul_f32_e32 v133, v97, v97
	v_mul_f32_e32 v136, v101, v101
	v_lshlrev_b32_e32 v108, 16, v112
	v_and_b32_e32 v109, 0xffff0000, v112
	v_lshlrev_b32_e32 v112, 16, v113
	v_and_b32_e32 v113, 0xffff0000, v113
	ds_swizzle_b32 v153, v17 offset:swizzle(SWAP,4)
	ds_swizzle_b32 v158, v152 offset:swizzle(SWAP,1)
	v_add_f32_e32 v128, v128, v129
	v_fmac_f32_e32 v133, v96, v96
	v_fmac_f32_e32 v136, v100, v100
	v_mul_f32_e32 v148, v109, v109
	v_mul_f32_e32 v149, v113, v113
	v_lshlrev_b32_e32 v120, 16, v126
	v_and_b32_e32 v121, 0xffff0000, v126
	v_lshlrev_b32_e32 v126, 16, v127
	v_and_b32_e32 v127, 0xffff0000, v127
	s_waitcnt lgkmcnt(3)
; __device__ __forceinline__ f32x4 unpack4(unsigned long long w) { const unsigned lo = (unsigned)w, hi = (unsigned)(w >> 32); return (f32x4){__uint_as_float(lo << 16), __uint_as_float(lo & 0xffff0000u), __uint_as_float(hi << 16), __uint_as_float(hi & 0xffff0000u)}; }
; template <int MODE, int NR>
; __device__ __forceinline__ void norm_rows(const float* X32, bf16* X, bf16* H, float* out32, const f32x4 (&mul)[4], const f32x4 (&sh)[4], int lane) {
;     ...
;         for (int r = 0; r < NR; ++r) { f32x4 v[4]; float s = 0.f;
; #pragma unroll
;             for (int j = 0; j < 4; ++j) { v[j] = unpack4(raw[r][j]); s += (v[j].x * v[j].x + v[j].y * v[j].y) + (v[j].z * v[j].z + v[j].w * v[j].w); }
;             const float rstd = rsqrtf(wave_sum(s) * (1.f / D) + EPS);
	v_add_f32_e32 v159, v137, v142
	v_add_f32_e32 v137, v132, v128
	v_add_f32_e32 v136, v133, v136
	v_fmac_f32_e32 v148, v108, v108
	v_fmac_f32_e32 v149, v112, v112
	v_mul_f32_e32 v142, v121, v121
	v_mul_f32_e32 v150, v127, v127
	v_and_b32_e32 v129, 0xffff0000, v130
	v_and_b32_e32 v133, 0xffff0000, v131
	v_lshlrev_b32_e32 v128, 16, v130
	v_lshlrev_b32_e32 v132, 16, v131
	ds_swizzle_b32 v162, v159 offset:swizzle(SWAP,2)
	v_add_f32_e32 v130, v137, v136
	v_add_f32_e32 v131, v148, v149
	v_fmac_f32_e32 v142, v120, v120
	v_fmac_f32_e32 v150, v126, v126
	v_mul_f32_e32 v163, v129, v129
	v_mul_f32_e32 v164, v133, v133
	v_lshlrev_b32_e32 v136, 16, v138
	v_and_b32_e32 v137, 0xffff0000, v138
	v_lshlrev_b32_e32 v138, 16, v139
	v_and_b32_e32 v139, 0xffff0000, v139
	s_waitcnt lgkmcnt(3)
	v_add_f32_e32 v19, v19, v143
	v_add_f32_e32 v165, v130, v131
	v_add_f32_e32 v130, v142, v150
	v_fmac_f32_e32 v163, v128, v128
	v_fmac_f32_e32 v164, v132, v132
	v_mul_f32_e32 v131, v137, v137
	v_mul_f32_e32 v142, v139, v139
	v_and_b32_e32 v149, 0xffff0000, v118
	v_and_b32_e32 v151, 0xffff0000, v119
	v_lshlrev_b32_e32 v148, 16, v118
	v_lshlrev_b32_e32 v150, 16, v119
	ds_swizzle_b32 v166, v19 offset:swizzle(SWAP,4)
	ds_swizzle_b32 v167, v165 offset:swizzle(SWAP,1)
	v_add_f32_e32 v143, v163, v164
	v_fmac_f32_e32 v131, v136, v136
	v_fmac_f32_e32 v142, v138, v138
	v_mul_f32_e32 v163, v149, v149
	v_mul_f32_e32 v164, v151, v151
	v_lshlrev_b32_e32 v118, 16, v124
	v_and_b32_e32 v119, 0xffff0000, v124
	v_lshlrev_b32_e32 v124, 16, v125
	v_and_b32_e32 v125, 0xffff0000, v125
	s_waitcnt lgkmcnt(4)
	v_add_f32_e32 v17, v17, v153
	s_waitcnt lgkmcnt(3)
	v_add_f32_e32 v168, v152, v158
	v_add_f32_e32 v143, v130, v143
	v_add_f32_e32 v142, v131, v142
	v_fmac_f32_e32 v163, v148, v148
	v_fmac_f32_e32 v164, v150, v150
	v_mul_f32_e32 v152, v119, v119
	v_mul_f32_e32 v153, v125, v125
	v_lshlrev_b32_e32 v130, 16, v134
	v_and_b32_e32 v131, 0xffff0000, v134
	v_lshlrev_b32_e32 v134, 16, v135
	v_and_b32_e32 v135, 0xffff0000, v135
	ds_swizzle_b32 v169, v17 offset:swizzle(SWAP,8)
	ds_swizzle_b32 v170, v168 offset:swizzle(SWAP,2)
	v_add_f32_e32 v158, v143, v142
	v_add_f32_e32 v163, v163, v164
	v_fmac_f32_e32 v152, v118, v118
	v_fmac_f32_e32 v153, v124, v124
	v_mul_f32_e32 v164, v131, v131
	v_mul_f32_e32 v171, v135, v135
	v_lshlrev_b32_e32 v142, 16, v144
	v_and_b32_e32 v143, 0xffff0000, v144
	v_lshlrev_b32_e32 v144, 16, v145
	v_and_b32_e32 v145, 0xffff0000, v145
	s_waitcnt lgkmcnt(4)
	v_add_f32_e32 v172, v159, v162
	v_add_f32_e32 v173, v158, v163
	v_add_f32_e32 v162, v152, v153
	v_fmac_f32_e32 v164, v130, v130
	v_fmac_f32_e32 v171, v134, v134
	v_mul_f32_e32 v163, v143, v143
	v_mul_f32_e32 v174, v145, v145
	v_lshlrev_b32_e32 v152, 16, v154
	v_and_b32_e32 v153, 0xffff0000, v154
	v_lshlrev_b32_e32 v154, 16, v155
	v_and_b32_e32 v155, 0xffff0000, v155
	v_add_f32_e32 v164, v164, v171
	v_fmac_f32_e32 v163, v142, v142
	v_fmac_f32_e32 v174, v144, v144
	v_mul_f32_e32 v171, v153, v153
	v_mul_f32_e32 v177, v155, v155
	v_lshlrev_b32_e32 v158, 16, v160
	v_and_b32_e32 v159, 0xffff0000, v160
	v_lshlrev_b32_e32 v160, 16, v161
	v_and_b32_e32 v161, 0xffff0000, v161
	ds_swizzle_b32 v175, v172 offset:swizzle(SWAP,4)
	ds_swizzle_b32 v176, v173 offset:swizzle(SWAP,1)
	s_waitcnt lgkmcnt(5)
	v_add_f32_e32 v19, v19, v166
	s_waitcnt lgkmcnt(4)
	v_add_f32_e32 v178, v165, v167
	v_add_f32_e32 v164, v162, v164
	v_add_f32_e32 v165, v163, v174
	v_fmac_f32_e32 v171, v152, v152
	v_fmac_f32_e32 v177, v154, v154
	v_mul_f32_e32 v174, v159, v159
	v_mul_f32_e32 v179, v161, v161
	v_lshlrev_b32_e32 v162, 16, v156
	v_and_b32_e32 v163, 0xffff0000, v156
	v_lshlrev_b32_e32 v156, 16, v157
	v_and_b32_e32 v157, 0xffff0000, v157
	ds_swizzle_b32 v180, v19 offset:swizzle(SWAP,8)
	ds_swizzle_b32 v181, v178 offset:swizzle(SWAP,2)
	v_add_f32_e32 v182, v164, v165
	v_add_f32_e32 v171, v171, v177
	v_fmac_f32_e32 v174, v158, v158
	v_fmac_f32_e32 v179, v160, v160
	v_mul_f32_e32 v177, v163, v163
	v_mul_f32_e32 v183, v157, v157
	v_lshlrev_b32_e32 v164, 16, v146
	v_and_b32_e32 v165, 0xffff0000, v146
	v_lshlrev_b32_e32 v146, 16, v147
	v_and_b32_e32 v147, 0xffff0000, v147
	v_lshlrev_b32_e32 v166, 16, v140
	v_and_b32_e32 v167, 0xffff0000, v140
	v_lshlrev_b32_e32 v140, 16, v141
	v_and_b32_e32 v141, 0xffff0000, v141
	s_waitcnt lgkmcnt(5)
	v_add_f32_e32 v17, v17, v169
	s_waitcnt lgkmcnt(4)
	v_add_f32_e32 v168, v168, v170
	v_add_f32_e32 v170, v182, v171
	v_add_f32_e32 v169, v174, v179
	v_fmac_f32_e32 v177, v162, v162
	v_fmac_f32_e32 v183, v156, v156
	v_mul_f32_e32 v171, v165, v165
	v_mul_f32_e32 v174, v147, v147
	v_mul_f32_e32 v179, v167, v167
	v_mul_f32_e32 v182, v141, v141
	v_add_f32_e32 v177, v177, v183
	v_fmac_f32_e32 v171, v164, v164
	v_fmac_f32_e32 v174, v146, v146
	ds_swizzle_b32 v184, v17 offset:swizzle(SWAP,16)
	ds_swizzle_b32 v185, v168 offset:swizzle(SWAP,4)
	v_fmac_f32_e32 v179, v166, v166
	v_fmac_f32_e32 v182, v140, v140
	v_add_f32_e32 v169, v169, v177
	v_add_f32_e32 v171, v171, v174
	ds_swizzle_b32 v186, v170 offset:swizzle(SWAP,1)
	s_waitcnt lgkmcnt(6)
	v_add_f32_e32 v172, v172, v175
	s_waitcnt lgkmcnt(5)
	v_add_f32_e32 v173, v173, v176
	v_add_f32_e32 v174, v179, v182
	v_add_f32_e32 v169, v169, v171
	ds_swizzle_b32 v175, v172 offset:swizzle(SWAP,8)
	ds_swizzle_b32 v176, v173 offset:swizzle(SWAP,2)
	s_waitcnt lgkmcnt(6)
	v_add_f32_e32 v19, v19, v180
	s_waitcnt lgkmcnt(5)
	v_add_f32_e32 v177, v178, v181
	v_add_f32_e32 v174, v169, v174
	ds_swizzle_b32 v178, v19 offset:swizzle(SWAP,16)
	ds_swizzle_b32 v179, v177 offset:swizzle(SWAP,4)
	ds_swizzle_b32 v180, v174 offset:swizzle(SWAP,1)
	s_waitcnt lgkmcnt(7)
	v_add_f32_e32 v169, v17, v184
	s_waitcnt lgkmcnt(6)
; __device__ __forceinline__ f32x4 unpack4(unsigned long long w) { const unsigned lo = (unsigned)w, hi = (unsigned)(w >> 32); return (f32x4){__uint_as_float(lo << 16), __uint_as_float(lo & 0xffff0000u), __uint_as_float(hi << 16), __uint_as_float(hi & 0xffff0000u)}; }
; template <int MODE, int NR>
; __device__ __forceinline__ void norm_rows(const float* X32, bf16* X, bf16* H, float* out32, const f32x4 (&mul)[4], const f32x4 (&sh)[4], int lane) {
;     ...
;         for (int r = 0; r < NR; ++r) { f32x4 v[4]; float s = 0.f;
; #pragma unroll
;             for (int j = 0; j < 4; ++j) { v[j] = unpack4(raw[r][j]); s += (v[j].x * v[j].x + v[j].y * v[j].y) + (v[j].z * v[j].z + v[j].w * v[j].w); }
;             const float rstd = rsqrtf(wave_sum(s) * (1.f / D) + EPS);
;             if constexpr (MODE == 2) { f32x4* o = (f32x4*)(out32 + (size_t)r * D) + lane;
; #pragma unroll
;                 for (int j = 0; j < 4; ++j) o[64 * j] = v[j] * rstd * mul[j];
	v_add_f32_e32 v17, v168, v185
	s_waitcnt lgkmcnt(5)
	v_add_f32_e32 v181, v170, v186
	ds_swizzle_b32 v182, v17 offset:swizzle(SWAP,8)
	ds_swizzle_b32 v183, v181 offset:swizzle(SWAP,2)
	s_waitcnt lgkmcnt(6)
	v_add_f32_e32 v172, v172, v175
	s_waitcnt lgkmcnt(5)
	v_add_f32_e32 v173, v173, v176
	ds_swizzle_b32 v175, v172 offset:swizzle(SWAP,16)
	ds_swizzle_b32 v176, v173 offset:swizzle(SWAP,4)
	s_waitcnt lgkmcnt(6)
	v_add_f32_e32 v168, v19, v178
	s_waitcnt lgkmcnt(5)
	v_add_f32_e32 v19, v177, v179
	s_waitcnt lgkmcnt(4)
	v_add_f32_e32 v174, v174, v180
	v_mov_b32_e32 v171, v169
	v_mov_b32_e32 v170, v168
	ds_swizzle_b32 v177, v19 offset:swizzle(SWAP,8)
	ds_swizzle_b32 v178, v174 offset:swizzle(SWAP,2)
	v_permlane32_swap_b32_e32 v169, v171
	v_permlane32_swap_b32_e32 v168, v170
	v_add_co_u32_e64 v36, s[0:1], s10, v20
	s_waitcnt lgkmcnt(5)
	v_add_f32_e32 v17, v17, v182
	v_pk_add_f32 v[168:169], v[168:169], v[170:171]
	v_addc_co_u32_e64 v37, s[0:1], 0, v21, s[0:1]
	s_waitcnt lgkmcnt(4)
	v_add_f32_e32 v179, v181, v183
	ds_swizzle_b32 v170, v17 offset:swizzle(SWAP,16)
	v_pk_fma_f32 v[168:169], v[168:169], s[4:5], v[24:25] op_sel_hi:[1,0,0]
	v_add_co_u32_e64 v40, s[0:1], s11, v20
	ds_swizzle_b32 v180, v179 offset:swizzle(SWAP,4)
	s_waitcnt lgkmcnt(5)
	v_add_f32_e32 v171, v172, v175
	s_waitcnt lgkmcnt(4)
	v_add_f32_e32 v175, v173, v176
	v_mul_f32_e32 v176, 0x4b800000, v168
	v_cmp_gt_f32_e32 vcc, s3, v168
	v_addc_co_u32_e64 v41, s[0:1], 0, v21, s[0:1]
	ds_swizzle_b32 v181, v175 offset:swizzle(SWAP,8)
	v_cndmask_b32_e32 v168, v168, v176, vcc
	s_waitcnt lgkmcnt(4)
	v_add_f32_e32 v19, v19, v177
	s_waitcnt lgkmcnt(3)
	v_add_f32_e32 v176, v174, v178
	v_mul_f32_e32 v172, 0x4b800000, v169
	v_cmp_gt_f32_e64 s[0:1], s3, v169
	ds_swizzle_b32 v178, v19 offset:swizzle(SWAP,16)
	ds_swizzle_b32 v182, v176 offset:swizzle(SWAP,4)
	v_cndmask_b32_e64 v169, v169, v172, s[0:1]
	v_rsq_f32_e32 v174, v169
	v_rsq_f32_e32 v177, v168
	s_waitcnt lgkmcnt(4)
	v_add_f32_e32 v170, v17, v170
	v_mov_b32_e32 v173, v171
	s_waitcnt lgkmcnt(3)
	v_add_f32_e32 v17, v179, v180
	v_mov_b32_e32 v172, v170
	v_permlane32_swap_b32_e32 v171, v173
	ds_swizzle_b32 v198, v17 offset:swizzle(SWAP,8)
	v_permlane32_swap_b32_e32 v170, v172
	s_waitcnt lgkmcnt(3)
	v_add_f32_e32 v200, v175, v181
	v_pk_add_f32 v[168:169], v[170:171], v[172:173]
	ds_swizzle_b32 v201, v200 offset:swizzle(SWAP,16)
	s_waitcnt lgkmcnt(3)
	v_add_f32_e32 v173, v19, v178
	s_waitcnt lgkmcnt(2)
	v_add_f32_e32 v19, v176, v182
	v_mul_f32_e32 v175, 0x45800000, v174
	v_mul_f32_e32 v179, 0x45800000, v177
	ds_swizzle_b32 v203, v19 offset:swizzle(SWAP,8)
	v_cndmask_b32_e64 v170, v174, v175, s[0:1]
	v_cndmask_b32_e32 v172, v177, v179, vcc
	v_pk_fma_f32 v[174:175], v[168:169], s[4:5], v[24:25] op_sel_hi:[1,0,0]
	v_pk_mul_f32 v[34:35], v[34:35], v[170:171] op_sel_hi:[1,0]
	v_pk_mul_f32 v[42:43], v[42:43], v[170:171] op_sel_hi:[1,0]
	v_pk_mul_f32 v[182:183], v[68:69], v[172:173] op_sel_hi:[1,0]
	v_pk_mul_f32 v[184:185], v[70:71], v[172:173] op_sel_hi:[1,0]
	v_pk_mul_f32 v[186:187], v[80:81], v[172:173] op_sel_hi:[1,0]
	v_pk_mul_f32 v[188:189], v[82:83], v[172:173] op_sel_hi:[1,0]
	v_pk_mul_f32 v[190:191], v[92:93], v[172:173] op_sel_hi:[1,0]
	v_pk_mul_f32 v[192:193], v[94:95], v[172:173] op_sel_hi:[1,0]
	v_pk_mul_f32 v[194:195], v[104:105], v[172:173] op_sel_hi:[1,0]
	v_pk_mul_f32 v[196:197], v[106:107], v[172:173] op_sel_hi:[1,0]
	v_mul_f32_e32 v172, 0x4b800000, v175
	v_mul_f32_e32 v202, 0x4b800000, v174
	v_cmp_gt_f32_e32 vcc, s3, v174
	v_cmp_gt_f32_e64 s[0:1], s3, v175
	v_pk_mul_f32 v[168:169], v[44:45], v[170:171] op_sel_hi:[1,0]
	v_pk_mul_f32 v[46:47], v[46:47], v[170:171] op_sel_hi:[1,0]
	v_pk_mul_f32 v[176:177], v[52:53], v[170:171] op_sel_hi:[1,0]
	v_pk_mul_f32 v[178:179], v[54:55], v[170:171] op_sel_hi:[1,0]
	v_pk_mul_f32 v[180:181], v[60:61], v[170:171] op_sel_hi:[1,0]
	v_pk_mul_f32 v[170:171], v[62:63], v[170:171] op_sel_hi:[1,0]
	v_pk_mul_f32 v[44:45], v[2:3], v[42:43]
	v_pk_mul_f32 v[42:43], v[0:1], v[34:35]
	v_cndmask_b32_e64 v34, v175, v172, s[0:1]
	v_cndmask_b32_e32 v35, v174, v202, vcc
	s_waitcnt lgkmcnt(2)
	v_add_f32_e32 v17, v17, v198
	v_pk_mul_f32 v[54:55], v[6:7], v[46:47]
	v_pk_mul_f32 v[52:53], v[4:5], v[168:169]
	v_pk_mul_f32 v[62:63], v[10:11], v[178:179]
	v_pk_mul_f32 v[60:61], v[8:9], v[176:177]
	v_pk_mul_f32 v[70:71], v[14:15], v[170:171]
	v_pk_mul_f32 v[68:69], v[12:13], v[180:181]
	v_pk_mul_f32 v[82:83], v[2:3], v[184:185]
	v_pk_mul_f32 v[80:81], v[0:1], v[182:183]
	v_pk_mul_f32 v[94:95], v[6:7], v[188:189]
	v_pk_mul_f32 v[92:93], v[4:5], v[186:187]
	v_pk_mul_f32 v[106:107], v[10:11], v[192:193]
	v_pk_mul_f32 v[104:105], v[8:9], v[190:191]
	v_pk_mul_f32 v[170:171], v[14:15], v[196:197]
	v_pk_mul_f32 v[168:169], v[12:13], v[194:195]
	global_store_dwordx4 v[20:21], v[42:45], off
	global_store_dwordx4 v[20:21], v[52:55], off offset:1024
	global_store_dwordx4 v[20:21], v[60:63], off offset:2048
	global_store_dwordx4 v[20:21], v[68:71], off offset:3072
	global_store_dwordx4 v[26:27], v[80:83], off offset:-4096
	global_store_dwordx4 v[28:29], v[92:95], off offset:1024
	global_store_dwordx4 v[28:29], v[104:107], off offset:2048
	global_store_dwordx4 v[28:29], v[168:171], off offset:3072
	v_rsq_f32_e32 v34, v34
	v_rsq_f32_e32 v35, v35
	ds_swizzle_b32 v43, v17 offset:swizzle(SWAP,16)
	s_waitcnt lgkmcnt(2)
	v_add_f32_e32 v172, v200, v201
	v_mov_b32_e32 v199, v173
	v_mov_b32_e32 v198, v172
	s_waitcnt lgkmcnt(1)
; __device__ __forceinline__ f32x4 unpack4(unsigned long long w) { const unsigned lo = (unsigned)w, hi = (unsigned)(w >> 32); return (f32x4){__uint_as_float(lo << 16), __uint_as_float(lo & 0xffff0000u), __uint_as_float(hi << 16), __uint_as_float(hi & 0xffff0000u)}; }
; template <int MODE, int NR>
; __device__ __forceinline__ void norm_rows(const float* X32, bf16* X, bf16* H, float* out32, const f32x4 (&mul)[4], const f32x4 (&sh)[4], int lane) {
;     ...
;         for (int r = 0; r < NR; ++r) { f32x4 v[4]; float s = 0.f;
; #pragma unroll
;             for (int j = 0; j < 4; ++j) { v[j] = unpack4(raw[r][j]); s += (v[j].x * v[j].x + v[j].y * v[j].y) + (v[j].z * v[j].z + v[j].w * v[j].w); }
;             const float rstd = rsqrtf(wave_sum(s) * (1.f / D) + EPS);
;             if constexpr (MODE == 2) { f32x4* o = (f32x4*)(out32 + (size_t)r * D) + lane;
; #pragma unroll
;                 for (int j = 0; j < 4; ++j) o[64 * j] = v[j] * rstd * mul[j];
	v_add_f32_e32 v19, v19, v203
	v_permlane32_swap_b32_e32 v173, v199
	v_permlane32_swap_b32_e32 v172, v198
	ds_swizzle_b32 v80, v19 offset:swizzle(SWAP,16)
	v_pk_add_f32 v[28:29], v[172:173], v[198:199]
	v_mul_f32_e32 v42, 0x45800000, v34
	v_mul_f32_e32 v44, 0x45800000, v35
	v_pk_fma_f32 v[28:29], v[28:29], s[4:5], v[24:25] op_sel_hi:[1,0,0]
	v_cndmask_b32_e64 v34, v34, v42, s[0:1]
	v_cndmask_b32_e32 v42, v35, v44, vcc
	s_waitcnt lgkmcnt(1)
	v_add_f32_e32 v35, v17, v43
	v_mul_f32_e32 v17, 0x4b800000, v29
	v_cmp_gt_f32_e64 s[0:1], s3, v29
	v_pk_mul_f32 v[46:47], v[48:49], v[34:35] op_sel_hi:[1,0]
	v_pk_mul_f32 v[44:45], v[50:51], v[34:35] op_sel_hi:[1,0]
	v_pk_mul_f32 v[50:51], v[56:57], v[34:35] op_sel_hi:[1,0]
	v_pk_mul_f32 v[48:49], v[58:59], v[34:35] op_sel_hi:[1,0]
	v_pk_mul_f32 v[54:55], v[64:65], v[34:35] op_sel_hi:[1,0]
	v_pk_mul_f32 v[52:53], v[66:67], v[34:35] op_sel_hi:[1,0]
	v_pk_mul_f32 v[58:59], v[76:77], v[34:35] op_sel_hi:[1,0]
	v_pk_mul_f32 v[56:57], v[78:79], v[34:35] op_sel_hi:[1,0]
	v_mul_f32_e32 v34, 0x4b800000, v28
	v_cmp_gt_f32_e32 vcc, s3, v28
	v_cndmask_b32_e64 v17, v29, v17, s[0:1]
	v_rsq_f32_e32 v17, v17
	v_cndmask_b32_e32 v28, v28, v34, vcc
	s_waitcnt lgkmcnt(0)
; template <int MODE, int NR>
; __device__ __forceinline__ void norm_rows(const float* X32, bf16* X, bf16* H, float* out32, const f32x4 (&mul)[4], const f32x4 (&sh)[4], int lane) {
;     ...
;             if constexpr (MODE == 2) { f32x4* o = (f32x4*)(out32 + (size_t)r * D) + lane;
; #pragma unroll
;                 for (int j = 0; j < 4; ++j) o[64 * j] = v[j] * rstd * mul[j];
; __device__ __forceinline__ void phase_final(const bf16* X, float* out, const float* nw, int gw, int NGW, int lane) {
;     ...
;     for (int b = gw; b < MP / 8; b += NGW) { const size_t ro = (size_t)b * 8 * D; norm_rows<2, 8>(nullptr, (bf16*)X + ro, nullptr, out + ro, w4, w4, lane); }
	v_add_f32_e32 v34, v19, v80
	v_mov_b32_e32 v81, v35
	v_rsq_f32_e32 v29, v28
	v_mov_b32_e32 v80, v34
	v_pk_mul_f32 v[62:63], v[86:87], v[42:43] op_sel_hi:[1,0]
	v_pk_mul_f32 v[60:61], v[90:91], v[42:43] op_sel_hi:[1,0]
	v_pk_mul_f32 v[66:67], v[98:99], v[42:43] op_sel_hi:[1,0]
	v_pk_mul_f32 v[64:65], v[102:103], v[42:43] op_sel_hi:[1,0]
	v_pk_mul_f32 v[70:71], v[110:111], v[42:43] op_sel_hi:[1,0]
	v_pk_mul_f32 v[68:69], v[114:115], v[42:43] op_sel_hi:[1,0]
	v_pk_mul_f32 v[76:77], v[116:117], v[42:43] op_sel_hi:[1,0]
	v_pk_mul_f32 v[78:79], v[122:123], v[42:43] op_sel_hi:[1,0]
	v_pk_mul_f32 v[44:45], v[2:3], v[44:45]
	v_pk_mul_f32 v[42:43], v[0:1], v[46:47]
	v_permlane32_swap_b32_e32 v35, v81
	v_permlane32_swap_b32_e32 v34, v80
	v_pk_mul_f32 v[48:49], v[6:7], v[48:49]
	v_pk_mul_f32 v[46:47], v[4:5], v[50:51]
	v_pk_mul_f32 v[52:53], v[10:11], v[52:53]
	v_pk_mul_f32 v[50:51], v[8:9], v[54:55]
	v_pk_mul_f32 v[56:57], v[14:15], v[56:57]
	v_pk_mul_f32 v[54:55], v[12:13], v[58:59]
	v_pk_mul_f32 v[60:61], v[2:3], v[60:61]
	v_pk_mul_f32 v[58:59], v[0:1], v[62:63]
	v_pk_mul_f32 v[64:65], v[6:7], v[64:65]
	v_pk_mul_f32 v[62:63], v[4:5], v[66:67]
	v_pk_mul_f32 v[68:69], v[10:11], v[68:69]
	v_pk_mul_f32 v[66:67], v[8:9], v[70:71]
	v_pk_mul_f32 v[78:79], v[14:15], v[78:79]
	v_pk_mul_f32 v[76:77], v[12:13], v[76:77]
	global_store_dwordx4 v[26:27], v[42:45], off
	global_store_dwordx4 v[26:27], v[46:49], off offset:1024
	global_store_dwordx4 v[26:27], v[50:53], off offset:2048
	global_store_dwordx4 v[26:27], v[54:57], off offset:3072
	global_store_dwordx4 v[30:31], v[58:61], off offset:-4096
	global_store_dwordx4 v[32:33], v[62:65], off offset:1024
	global_store_dwordx4 v[32:33], v[66:69], off offset:2048
	global_store_dwordx4 v[32:33], v[76:79], off offset:3072
	v_pk_add_f32 v[26:27], v[34:35], v[80:81]
	v_mul_f32_e32 v19, 0x45800000, v17
	v_pk_fma_f32 v[66:67], v[26:27], s[4:5], v[24:25] op_sel_hi:[1,0,0]
	v_mul_f32_e32 v32, 0x45800000, v29
	v_cndmask_b32_e64 v28, v17, v19, s[0:1]
	v_mul_f32_e32 v17, 0x4b800000, v67
	v_cmp_gt_f32_e64 s[0:1], s3, v67
	v_cndmask_b32_e32 v32, v29, v32, vcc
	v_mul_f32_e32 v19, 0x4b800000, v66
	v_cmp_gt_f32_e32 vcc, s3, v66
	v_cndmask_b32_e64 v17, v67, v17, s[0:1]
	v_rsq_f32_e32 v17, v17
	v_cndmask_b32_e32 v19, v66, v19, vcc
	v_rsq_f32_e32 v19, v19
	v_pk_mul_f32 v[26:27], v[72:73], v[28:29] op_sel_hi:[1,0]
	v_pk_mul_f32 v[34:35], v[74:75], v[28:29] op_sel_hi:[1,0]
	v_pk_mul_f32 v[42:43], v[84:85], v[28:29] op_sel_hi:[1,0]
	v_pk_mul_f32 v[44:45], v[88:89], v[28:29] op_sel_hi:[1,0]
	v_pk_mul_f32 v[46:47], v[96:97], v[28:29] op_sel_hi:[1,0]
	v_pk_mul_f32 v[48:49], v[100:101], v[28:29] op_sel_hi:[1,0]
	v_pk_mul_f32 v[50:51], v[108:109], v[28:29] op_sel_hi:[1,0]
	v_pk_mul_f32 v[52:53], v[112:113], v[28:29] op_sel_hi:[1,0]
	v_pk_mul_f32 v[54:55], v[120:121], v[32:33] op_sel_hi:[1,0]
	v_pk_mul_f32 v[56:57], v[126:127], v[32:33] op_sel_hi:[1,0]
	v_pk_mul_f32 v[58:59], v[128:129], v[32:33] op_sel_hi:[1,0]
	v_pk_mul_f32 v[60:61], v[132:133], v[32:33] op_sel_hi:[1,0]
	v_pk_mul_f32 v[28:29], v[2:3], v[34:35]
	v_pk_mul_f32 v[26:27], v[0:1], v[26:27]
	v_pk_mul_f32 v[62:63], v[136:137], v[32:33] op_sel_hi:[1,0]
	v_pk_mul_f32 v[64:65], v[138:139], v[32:33] op_sel_hi:[1,0]
	v_pk_mul_f32 v[68:69], v[148:149], v[32:33] op_sel_hi:[1,0]
	v_pk_mul_f32 v[70:71], v[150:151], v[32:33] op_sel_hi:[1,0]
	v_pk_mul_f32 v[34:35], v[6:7], v[44:45]
	v_pk_mul_f32 v[32:33], v[4:5], v[42:43]
	v_pk_mul_f32 v[44:45], v[10:11], v[48:49]
	v_pk_mul_f32 v[42:43], v[8:9], v[46:47]
	v_pk_mul_f32 v[48:49], v[14:15], v[52:53]
	v_pk_mul_f32 v[46:47], v[12:13], v[50:51]
	v_pk_mul_f32 v[52:53], v[2:3], v[56:57]
	v_pk_mul_f32 v[50:51], v[0:1], v[54:55]
	v_pk_mul_f32 v[56:57], v[6:7], v[60:61]
	v_pk_mul_f32 v[54:55], v[4:5], v[58:59]
	global_store_dwordx4 v[30:31], v[26:29], off
	global_store_dwordx4 v[30:31], v[32:35], off offset:1024
	global_store_dwordx4 v[30:31], v[42:45], off offset:2048
	global_store_dwordx4 v[30:31], v[46:49], off offset:3072
	global_store_dwordx4 v[36:37], v[50:53], off offset:-4096
	global_store_dwordx4 v[38:39], v[54:57], off offset:1024
	v_mul_f32_e32 v26, 0x45800000, v17
	v_mul_f32_e32 v27, 0x45800000, v19
	v_cndmask_b32_e64 v26, v17, v26, s[0:1]
	s_add_i32 s12, s12, s96
	v_pk_mul_f32 v[60:61], v[10:11], v[64:65]
	v_pk_mul_f32 v[58:59], v[8:9], v[62:63]
	v_pk_mul_f32 v[64:65], v[14:15], v[70:71]
	v_pk_mul_f32 v[62:63], v[12:13], v[68:69]
	v_cndmask_b32_e32 v28, v19, v27, vcc
	v_pk_mul_f32 v[30:31], v[118:119], v[26:27] op_sel_hi:[1,0]
	v_pk_mul_f32 v[32:33], v[124:125], v[26:27] op_sel_hi:[1,0]
	s_cmpk_gt_i32 s12, 0x7ff
	v_lshl_add_u64 v[22:23], v[22:23], 0, s[78:79]
	v_lshl_add_u64 v[20:21], v[20:21], 0, s[16:17]
	global_store_dwordx4 v[38:39], v[58:61], off offset:2048
	global_store_dwordx4 v[38:39], v[62:65], off offset:3072
	v_pk_mul_f32 v[34:35], v[130:131], v[26:27] op_sel_hi:[1,0]
	v_pk_mul_f32 v[38:39], v[134:135], v[26:27] op_sel_hi:[1,0]
	v_pk_mul_f32 v[42:43], v[142:143], v[26:27] op_sel_hi:[1,0]
	v_pk_mul_f32 v[44:45], v[144:145], v[26:27] op_sel_hi:[1,0]
	v_pk_mul_f32 v[46:47], v[152:153], v[26:27] op_sel_hi:[1,0]
	v_pk_mul_f32 v[48:49], v[154:155], v[26:27] op_sel_hi:[1,0]
	v_pk_mul_f32 v[50:51], v[158:159], v[28:29] op_sel_hi:[1,0]
	v_pk_mul_f32 v[52:53], v[160:161], v[28:29] op_sel_hi:[1,0]
	v_pk_mul_f32 v[54:55], v[162:163], v[28:29] op_sel_hi:[1,0]
	v_pk_mul_f32 v[56:57], v[156:157], v[28:29] op_sel_hi:[1,0]
	v_pk_mul_f32 v[58:59], v[164:165], v[28:29] op_sel_hi:[1,0]
	v_pk_mul_f32 v[60:61], v[146:147], v[28:29] op_sel_hi:[1,0]
	v_pk_mul_f32 v[62:63], v[166:167], v[28:29] op_sel_hi:[1,0]
	v_pk_mul_f32 v[64:65], v[140:141], v[28:29] op_sel_hi:[1,0]
	v_pk_mul_f32 v[28:29], v[2:3], v[32:33]
	v_pk_mul_f32 v[26:27], v[0:1], v[30:31]
	v_pk_mul_f32 v[32:33], v[6:7], v[38:39]
	v_pk_mul_f32 v[30:31], v[4:5], v[34:35]
	v_pk_mul_f32 v[44:45], v[10:11], v[44:45]
	v_pk_mul_f32 v[42:43], v[8:9], v[42:43]
	v_pk_mul_f32 v[48:49], v[14:15], v[48:49]
	v_pk_mul_f32 v[46:47], v[12:13], v[46:47]
	v_pk_mul_f32 v[52:53], v[2:3], v[52:53]
	v_pk_mul_f32 v[50:51], v[0:1], v[50:51]
	v_pk_mul_f32 v[56:57], v[6:7], v[56:57]
	v_pk_mul_f32 v[54:55], v[4:5], v[54:55]
	v_pk_mul_f32 v[60:61], v[10:11], v[60:61]
	v_pk_mul_f32 v[58:59], v[8:9], v[58:59]
	v_pk_mul_f32 v[64:65], v[14:15], v[64:65]
	v_pk_mul_f32 v[62:63], v[12:13], v[62:63]
	global_store_dwordx4 v[36:37], v[26:29], off
	global_store_dwordx4 v[36:37], v[30:33], off offset:1024
	global_store_dwordx4 v[36:37], v[42:45], off offset:2048
	global_store_dwordx4 v[36:37], v[46:49], off offset:3072
	global_store_dwordx4 v[40:41], v[50:53], off
	global_store_dwordx4 v[40:41], v[54:57], off offset:1024
	global_store_dwordx4 v[40:41], v[58:61], off offset:2048
	global_store_dwordx4 v[40:41], v[62:65], off offset:3072
	s_cbranch_scc0 .LBB0_1323

; __device__ __forceinline__ f32x4 unpack4(unsigned long long w) { const unsigned lo = (unsigned)w, hi = (unsigned)(w >> 32); return (f32x4){__uint_as_float(lo << 16), __uint_as_float(lo & 0xffff0000u), __uint_as_float(hi << 16), __uint_as_float(hi & 0xffff0000u)}; }
; template <int MODE, int NR>
; __device__ __forceinline__ void norm_rows(const float* X32, bf16* X, bf16* H, float* out32, const f32x4 (&mul)[4], const f32x4 (&sh)[4], int lane) {
;     ...
;         unsigned long long raw[NR][4];
; #pragma unroll
;         for (int r = 0; r < NR; ++r) { const unsigned long long* xr = (const unsigned long long*)(X + (size_t)r * D) + lane;
; #pragma unroll
;             for (int j = 0; j < 4; ++j) raw[r][j] = xr[64 * j]; }
; #pragma unroll
;         for (int r = 0; r < NR; ++r) { f32x4 v[4]; float s = 0.f;
; #pragma unroll
;             for (int j = 0; j < 4; ++j) { v[j] = unpack4(raw[r][j]); s += (v[j].x * v[j].x + v[j].y * v[j].y) + (v[j].z * v[j].z + v[j].w * v[j].w); }
;             const float rstd = rsqrtf(wave_sum(s) * (1.f / D) + EPS);
;             if constexpr (MODE == 2) { f32x4* o = (f32x4*)(out32 + (size_t)r * D) + lane;
; #pragma unroll
;                 for (int j = 0; j < 4; ++j) o[64 * j] = v[j] * rstd * mul[j];
; __device__ __forceinline__ void phase_final(const bf16* X, float* out, const float* nw, int gw, int NGW, int lane) {
;     ...
;     for (int sr = gw; sr < MS; sr += NGW) { const size_t ro = (size_t)(MP + sr) * D; norm_rows<2, 1>(nullptr, (bf16*)X + ro, nullptr, out + ro, w4, w4, lane); }
.LBB0_1326:
	global_load_dwordx2 v[22:23], v[20:21], off
	global_load_dwordx2 v[24:25], v[20:21], off offset:512
	global_load_dwordx2 v[26:27], v[20:21], off offset:1024
	global_load_dwordx2 v[28:29], v[20:21], off offset:1536
	s_add_i32 s2, s2, s96
	v_lshl_add_u64 v[20:21], v[20:21], 0, s[4:5]
	s_cmpk_lt_i32 s2, 0x80
	s_waitcnt vmcnt(0) lgkmcnt(0)
	v_lshlrev_b32_e32 v30, 16, v22
	v_and_b32_e32 v31, 0xffff0000, v22
	v_lshlrev_b32_e32 v22, 16, v23
	v_and_b32_e32 v23, 0xffff0000, v23
	v_lshlrev_b32_e32 v32, 16, v24
	v_and_b32_e32 v33, 0xffff0000, v24
	v_lshlrev_b32_e32 v24, 16, v25
	v_and_b32_e32 v25, 0xffff0000, v25
	v_lshlrev_b32_e32 v34, 16, v26
	v_and_b32_e32 v35, 0xffff0000, v26
	v_lshlrev_b32_e32 v26, 16, v27
	v_and_b32_e32 v27, 0xffff0000, v27
	v_mul_f32_e32 v19, v31, v31
	v_mul_f32_e32 v38, v23, v23
	v_mul_f32_e32 v39, v33, v33
	v_mul_f32_e32 v40, v25, v25
	v_lshlrev_b32_e32 v36, 16, v28
	v_and_b32_e32 v37, 0xffff0000, v28
	v_lshlrev_b32_e32 v28, 16, v29
	v_and_b32_e32 v29, 0xffff0000, v29
	v_mul_f32_e32 v41, v35, v35
	v_mul_f32_e32 v42, v27, v27
	v_fmac_f32_e32 v19, v30, v30
	v_fmac_f32_e32 v38, v22, v22
	v_fmac_f32_e32 v39, v32, v32
	v_fmac_f32_e32 v40, v24, v24
	v_mul_f32_e32 v43, v37, v37
	v_mul_f32_e32 v44, v29, v29
	v_fmac_f32_e32 v41, v34, v34
	v_fmac_f32_e32 v42, v26, v26
	v_add_f32_e32 v19, v19, v38
	v_add_f32_e32 v38, v39, v40
	v_fmac_f32_e32 v43, v36, v36
	v_fmac_f32_e32 v44, v28, v28
	v_add_f32_e32 v39, v41, v42
	v_add_f32_e32 v19, v19, v38
	v_add_f32_e32 v40, v43, v44
	v_add_f32_e32 v19, v19, v39
	v_add_f32_e32 v19, v19, v40
	ds_swizzle_b32 v38, v19 offset:swizzle(SWAP,1)
	s_waitcnt lgkmcnt(0)
	v_add_f32_e32 v19, v19, v38
	ds_swizzle_b32 v38, v19 offset:swizzle(SWAP,2)
	s_waitcnt lgkmcnt(0)
	v_add_f32_e32 v19, v19, v38
	ds_swizzle_b32 v38, v19 offset:swizzle(SWAP,4)
	s_waitcnt lgkmcnt(0)
	v_add_f32_e32 v19, v19, v38
	ds_swizzle_b32 v38, v19 offset:swizzle(SWAP,8)
	s_waitcnt lgkmcnt(0)
	v_add_f32_e32 v19, v19, v38
	ds_swizzle_b32 v38, v19 offset:swizzle(SWAP,16)
	s_waitcnt lgkmcnt(0)
	v_add_f32_e32 v19, v19, v38
	v_mov_b32_e32 v38, v19
	s_nop 1
	v_permlane32_swap_b32_e32 v19, v38
	v_add_f32_e32 v19, v19, v38
	v_fmamk_f32 v19, v19, 0x3a800000, v18
	v_mul_f32_e32 v38, 0x4b800000, v19
	v_cmp_gt_f32_e32 vcc, s0, v19
	s_nop 1
	v_cndmask_b32_e32 v19, v19, v38, vcc
	v_rsq_f32_e32 v19, v19
	s_nop 0
	v_mul_f32_e32 v38, 0x45800000, v19
	v_cndmask_b32_e32 v38, v19, v38, vcc
	v_pk_mul_f32 v[30:31], v[30:31], v[38:39] op_sel_hi:[1,0]
	v_pk_mul_f32 v[22:23], v[22:23], v[38:39] op_sel_hi:[1,0]
	v_pk_mul_f32 v[32:33], v[32:33], v[38:39] op_sel_hi:[1,0]
	v_pk_mul_f32 v[40:41], v[24:25], v[38:39] op_sel_hi:[1,0]
	v_pk_mul_f32 v[34:35], v[34:35], v[38:39] op_sel_hi:[1,0]
	v_pk_mul_f32 v[42:43], v[26:27], v[38:39] op_sel_hi:[1,0]
	v_pk_mul_f32 v[44:45], v[36:37], v[38:39] op_sel_hi:[1,0]
	v_pk_mul_f32 v[36:37], v[28:29], v[38:39] op_sel_hi:[1,0]
	v_pk_mul_f32 v[24:25], v[2:3], v[22:23]
	v_pk_mul_f32 v[22:23], v[0:1], v[30:31]
	v_pk_mul_f32 v[28:29], v[6:7], v[40:41]
	v_pk_mul_f32 v[26:27], v[4:5], v[32:33]
	v_pk_mul_f32 v[32:33], v[10:11], v[42:43]
	v_pk_mul_f32 v[30:31], v[8:9], v[34:35]
	v_pk_mul_f32 v[36:37], v[14:15], v[36:37]
	v_pk_mul_f32 v[34:35], v[12:13], v[44:45]
	global_store_dwordx4 v[16:17], v[22:25], off offset:-3072
	global_store_dwordx4 v[16:17], v[26:29], off offset:-2048
	global_store_dwordx4 v[16:17], v[30:33], off offset:-1024
	global_store_dwordx4 v[16:17], v[34:37], off
	v_lshl_add_u64 v[16:17], v[16:17], 0, s[6:7]
	s_cbranch_scc1 .LBB0_1326
